# align barrier of the leading wave half moved from before to after its tile epilogue (14 GEMM instances)
# baseline (speedup 1.0000x reference)
; #define PG8_STAGE(bufoff, gbase, voff) do { _Pragma("unroll") for (int _i = 0; _i < 2; ++_i) \
;         __builtin_amdgcn_global_load_lds((const unsigned*)((const char*)(gbase) + (voff)[_i]), (PG8_LAS unsigned*)(lds + (bufoff) + ldsw + _i * 8192), 16, 0, 0); } while (0)
; #define PG8_LDA(dst, b, h) do { _Pragma("unroll") for (int m = 0; m < 4; ++m) _Pragma("unroll") for (int k = 0; k < 2; ++k) dst[m][k] = *(const PG8_LAS bf16x8*)(lds + PG8_SA(b, h) + aoff + m * 2048 + k * 1024); } while (0)
; #define PG8_LDB(dst, b, h) do { _Pragma("unroll") for (int n = 0; n < 2; ++n) _Pragma("unroll") for (int k = 0; k < 2; ++k) dst[n][k] = *(const PG8_LAS bf16x8*)(lds + PG8_SB(b, h) + boff + n * 2048 + k * 1024); } while (0)
; #define PG8_WAIT_V(n) asm volatile("s_waitcnt vmcnt(" #n ")" ::: "memory")
; #define PG8_WAIT_L(n) asm volatile("s_waitcnt lgkmcnt(" #n ")" ::: "memory")
; #define PG8_BAR __builtin_amdgcn_s_barrier()
; #define PG8_SCHED __builtin_amdgcn_sched_barrier(0)
; template <class Epi, class Sched, bool ALIGN_EPI = false, bool SP2 = false>
; __device__ __forceinline__ void gemm_phase(PG8_LAS unsigned char* lds, const Gemm g, const Sched& S, const Epi& E) {
;     ...
;         const bool has_next = S.next(ui + 1, nxt);
;         const char* nA = has_next ? (const char*)g.A + (size_t)nxt.pm * tstep : cA; const char* nB = has_next ? (const char*)g.Bt + (size_t)nxt.pn * tstep : cB;
;         for (int t = 0; t < nt; t += 2) {
;             const bool last = (t == nt - 2);
;             const char* a1 = cA + (size_t)(t + 1) * kstep;
;             const char* a2 = last ? nA : cA + (size_t)(t + 2) * kstep; const char* b2 = last ? nB : cB + (size_t)(t + 2) * kstep;
;             const char* a3 = a2 + kstep; const char* b3 = b2 + kstep;
;             if (last && has_next) S.a_ready(nxt);
;             if constexpr (SP2) {
;             PG8_LDB(B0, 0, 0); PG8_LDB(B1, 0, 1); PG8_SCHED; PG8_LDA(At, 0, 0); PG8_STAGE(PG8_SA(1, 1), a1 + hstep, voffA);
;             PG8_WAIT_V(8); PG8_WAIT_L(0); PG8_BAR; PG8_MMA(0, 0, At, B0); PG8_MMA(0, 1, At, B1); PG8_BAR; PG8_SCHED;
;             PG8_LDA(At, 0, 1); PG8_STAGE(PG8_SB(0, 0), b2, voffB); PG8_STAGE(PG8_SB(0, 1), b2 + hstep, voffB); PG8_STAGE(PG8_SA(0, 0), a2, voffA);
;             PG8_WAIT_V(8); PG8_WAIT_L(0); PG8_BAR; PG8_MMA(1, 0, At, B0); PG8_MMA(1, 1, At, B1); PG8_BAR; PG8_SCHED;
.LBB0_190:
	s_ashr_i32 s27, s26, 31
	s_lshl_b64 s[14:15], s[26:27], 19
	s_add_u32 s28, s22, s14
	s_addc_u32 s29, s23, s15
	s_and_b64 s[14:15], s[0:1], exec
	s_cselect_b32 s27, s29, s49
	s_cselect_b32 s67, s28, s48
	s_ashr_i32 s25, s24, 31
	s_lshl_b64 s[14:15], s[24:25], 19
	s_add_u32 s40, s94, s14
	s_addc_u32 s41, s96, s15
	s_and_b64 s[14:15], s[0:1], exec
	s_cselect_b32 s25, s41, s51
	s_cselect_b32 s86, s40, s50
	s_add_u32 s48, s48, 0x40080
	s_addc_u32 s49, s49, 0
	s_add_u32 s87, s50, 0x100
	s_addc_u32 s88, s51, 0
	s_mov_b32 s89, -2
	ds_read_b128 v[144:147], v155
	ds_read_b128 v[148:151], v155 offset:1024
	ds_read_b128 v[160:163], v155 offset:2048
	ds_read_b128 v[168:171], v155 offset:3072
	ds_read_b128 v[172:175], v156
	ds_read_b128 v[176:179], v156 offset:1024
	ds_read_b128 v[182:185], v156 offset:2048
	ds_read_b128 v[186:189], v156 offset:3072
	s_add_u32 s3, s48, 0xfffc0080
	s_addc_u32 s14, s49, -1
	s_cmp_eq_u32 s89, 12
	s_cselect_b32 s55, s27, s14
	s_cselect_b32 s54, s67, s3
	s_cselect_b32 s51, s25, s88
	s_cselect_b32 s50, s86, s87
	v_lshl_add_u64 v[164:165], s[48:49], 0, v[136:137]
	s_add_i32 m0, s45, 0xc000
	ds_read_b128 v[190:193], v157
	ds_read_b128 v[194:197], v157 offset:1024
	ds_read_b128 v[198:201], v157 offset:2048
	ds_read_b128 v[208:211], v157 offset:3072
	ds_read_b128 v[212:215], v157 offset:4096
	ds_read_b128 v[216:219], v157 offset:5120
	ds_read_b128 v[220:223], v157 offset:6144
	ds_read_b128 v[224:227], v157 offset:7168
	global_load_lds_dwordx4 v[164:165], off
	v_lshl_add_u64 v[164:165], s[48:49], 0, v[138:139]
	s_add_i32 m0, s45, 0xe000
	s_nop 0
	global_load_lds_dwordx4 v[164:165], off
	s_waitcnt vmcnt(8)
	s_waitcnt lgkmcnt(0)
	s_barrier
	s_setprio 1
	s_waitcnt lgkmcnt(0)
	v_mfma_f32_16x16x32_bf16 v[124:127], v[144:147], v[190:193], 0
	v_mfma_f32_16x16x32_bf16 v[120:123], v[160:163], v[190:193], 0
	v_mfma_f32_16x16x32_bf16 v[108:111], v[144:147], v[198:201], 0
	v_mfma_f32_16x16x32_bf16 v[104:107], v[160:163], v[198:201], 0
	v_mfma_f32_16x16x32_bf16 v[92:95], v[144:147], v[212:215], 0
	v_mfma_f32_16x16x32_bf16 v[88:91], v[160:163], v[212:215], 0
	v_mfma_f32_16x16x32_bf16 v[76:79], v[144:147], v[220:223], 0
	v_mfma_f32_16x16x32_bf16 v[72:75], v[160:163], v[220:223], 0
	v_mfma_f32_16x16x32_bf16 v[124:127], v[148:151], v[194:197], v[124:127]
	v_mfma_f32_16x16x32_bf16 v[120:123], v[168:171], v[194:197], v[120:123]
	v_mfma_f32_16x16x32_bf16 v[108:111], v[148:151], v[208:211], v[108:111]
	v_mfma_f32_16x16x32_bf16 v[104:107], v[168:171], v[208:211], v[104:107]
	v_mfma_f32_16x16x32_bf16 v[92:95], v[148:151], v[216:219], v[92:95]
	v_mfma_f32_16x16x32_bf16 v[88:91], v[168:171], v[216:219], v[88:91]
	v_mfma_f32_16x16x32_bf16 v[76:79], v[148:151], v[224:227], v[76:79]
	v_mfma_f32_16x16x32_bf16 v[72:75], v[168:171], v[224:227], v[72:75]
	s_setprio 0
	s_setprio 1
	v_mfma_f32_16x16x32_bf16 v[116:119], v[172:175], v[190:193], 0
	v_mfma_f32_16x16x32_bf16 v[112:115], v[182:185], v[190:193], 0
	v_mfma_f32_16x16x32_bf16 v[100:103], v[172:175], v[198:201], 0
	v_mfma_f32_16x16x32_bf16 v[96:99], v[182:185], v[198:201], 0
	v_mfma_f32_16x16x32_bf16 v[84:87], v[172:175], v[212:215], 0
	v_mfma_f32_16x16x32_bf16 v[80:83], v[182:185], v[212:215], 0
	v_mfma_f32_16x16x32_bf16 v[68:71], v[172:175], v[220:223], 0
	v_mfma_f32_16x16x32_bf16 v[64:67], v[182:185], v[220:223], 0
	v_mfma_f32_16x16x32_bf16 v[116:119], v[176:179], v[194:197], v[116:119]
	v_mfma_f32_16x16x32_bf16 v[112:115], v[186:189], v[194:197], v[112:115]
	v_mfma_f32_16x16x32_bf16 v[100:103], v[176:179], v[208:211], v[100:103]
	v_mfma_f32_16x16x32_bf16 v[96:99], v[186:189], v[208:211], v[96:99]
	v_mfma_f32_16x16x32_bf16 v[84:87], v[176:179], v[216:219], v[84:87]
	v_mfma_f32_16x16x32_bf16 v[80:83], v[186:189], v[216:219], v[80:83]
	v_mfma_f32_16x16x32_bf16 v[68:71], v[176:179], v[224:227], v[68:71]
	v_mfma_f32_16x16x32_bf16 v[64:67], v[186:189], v[224:227], v[64:67]
	s_setprio 0
	s_barrier
	s_add_i32 s3, s63, s43
	v_lshl_add_u64 v[164:165], s[50:51], 0, v[132:133]
	s_mov_b32 m0, s3
	ds_read_b128 v[190:193], v157 offset:16384
	ds_read_b128 v[194:197], v157 offset:17408
	ds_read_b128 v[198:201], v157 offset:18432
	ds_read_b128 v[208:211], v157 offset:19456
	ds_read_b128 v[212:215], v157 offset:20480
	ds_read_b128 v[216:219], v157 offset:21504
	ds_read_b128 v[220:223], v157 offset:22528
	ds_read_b128 v[224:227], v157 offset:23552
	global_load_lds_dwordx4 v[164:165], off
	s_add_i32 m0, s3, 0x2000
	s_add_u32 s14, s50, 0x40000
	v_lshl_add_u64 v[202:203], s[50:51], 0, v[128:129]
	s_addc_u32 s15, s51, 0
	s_add_i32 s3, s64, s43
	global_load_lds_dwordx4 v[202:203], off
	v_lshl_add_u64 v[228:229], s[14:15], 0, v[132:133]
	s_mov_b32 m0, s3
	global_load_lds_dwordx4 v[228:229], off
	v_lshl_add_u64 v[228:229], s[14:15], 0, v[128:129]
	s_add_i32 m0, s3, 0x2000
	s_nop 0
	global_load_lds_dwordx4 v[228:229], off
	s_waitcnt vmcnt(6)
	s_waitcnt lgkmcnt(0)
	s_barrier
; #define PG8_STAGE(bufoff, gbase, voff) do { _Pragma("unroll") for (int _i = 0; _i < 2; ++_i) \
;         __builtin_amdgcn_global_load_lds((const unsigned*)((const char*)(gbase) + (voff)[_i]), (PG8_LAS unsigned*)(lds + (bufoff) + ldsw + _i * 8192), 16, 0, 0); } while (0)
; #define PG8_LDA(dst, b, h) do { _Pragma("unroll") for (int m = 0; m < 4; ++m) _Pragma("unroll") for (int k = 0; k < 2; ++k) dst[m][k] = *(const PG8_LAS bf16x8*)(lds + PG8_SA(b, h) + aoff + m * 2048 + k * 1024); } while (0)
; #define PG8_LDB(dst, b, h) do { _Pragma("unroll") for (int n = 0; n < 2; ++n) _Pragma("unroll") for (int k = 0; k < 2; ++k) dst[n][k] = *(const PG8_LAS bf16x8*)(lds + PG8_SB(b, h) + boff + n * 2048 + k * 1024); } while (0)
; #define PG8_MMA(ai, bj, At, Bt) do { __builtin_amdgcn_s_setprio(1); _Pragma("unroll") for (int m = 0; m < 4; ++m) _Pragma("unroll") for (int n = 0; n < 2; ++n) _Pragma("unroll") for (int k = 0; k < 2; ++k) \
;         acc[ai][bj][m][n] = __builtin_amdgcn_mfma_f32_16x16x32_bf16(Bt[n][k], At[m][k], acc[ai][bj][m][n], 0, 0, 0); __builtin_amdgcn_s_setprio(0); } while (0)
; #define PG8_WAIT_V(n) asm volatile("s_waitcnt vmcnt(" #n ")" ::: "memory")
; #define PG8_WAIT_L(n) asm volatile("s_waitcnt lgkmcnt(" #n ")" ::: "memory")
; #define PG8_BAR __builtin_amdgcn_s_barrier()
; #define PG8_SCHED __builtin_amdgcn_sched_barrier(0)
; template <class Epi, class Sched, bool ALIGN_EPI = false, bool SP2 = false>
; __device__ __forceinline__ void gemm_phase(PG8_LAS unsigned char* lds, const Gemm g, const Sched& S, const Epi& E) {
;     ...
;             PG8_LDA(At, 0, 1); PG8_STAGE(PG8_SB(0, 0), b2, voffB); PG8_STAGE(PG8_SB(0, 1), b2 + hstep, voffB); PG8_STAGE(PG8_SA(0, 0), a2, voffA);
;             PG8_WAIT_V(8); PG8_WAIT_L(0); PG8_BAR; PG8_MMA(1, 0, At, B0); PG8_MMA(1, 1, At, B1); PG8_BAR; PG8_SCHED;
;             PG8_LDB(B0, 1, 0); PG8_LDB(B1, 1, 1); PG8_SCHED; PG8_LDA(At, 1, 0); PG8_STAGE(PG8_SA(0, 1), a2 + hstep, voffA);
;             PG8_WAIT_V(8); PG8_WAIT_L(0); PG8_BAR; PG8_MMA(0, 0, At, B0); PG8_MMA(0, 1, At, B1); PG8_BAR; PG8_SCHED;
	s_setprio 1
	s_waitcnt lgkmcnt(0)
	v_mfma_f32_16x16x32_bf16 v[60:63], v[144:147], v[190:193], 0
	v_mfma_f32_16x16x32_bf16 v[56:59], v[160:163], v[190:193], 0
	v_mfma_f32_16x16x32_bf16 v[44:47], v[144:147], v[198:201], 0
	v_mfma_f32_16x16x32_bf16 v[40:43], v[160:163], v[198:201], 0
	v_mfma_f32_16x16x32_bf16 v[28:31], v[144:147], v[212:215], 0
	v_mfma_f32_16x16x32_bf16 v[24:27], v[160:163], v[212:215], 0
	v_mfma_f32_16x16x32_bf16 v[12:15], v[144:147], v[220:223], 0
	v_mfma_f32_16x16x32_bf16 v[8:11], v[160:163], v[220:223], 0
	v_mfma_f32_16x16x32_bf16 v[60:63], v[148:151], v[194:197], v[60:63]
	v_mfma_f32_16x16x32_bf16 v[56:59], v[168:171], v[194:197], v[56:59]
	v_mfma_f32_16x16x32_bf16 v[44:47], v[148:151], v[208:211], v[44:47]
	v_mfma_f32_16x16x32_bf16 v[40:43], v[168:171], v[208:211], v[40:43]
	v_mfma_f32_16x16x32_bf16 v[28:31], v[148:151], v[216:219], v[28:31]
	v_mfma_f32_16x16x32_bf16 v[24:27], v[168:171], v[216:219], v[24:27]
	v_lshl_add_u64 v[228:229], s[54:55], 0, v[134:135]
	s_mov_b32 m0, s45
	s_nop 0
	global_load_lds_dwordx4 v[228:229], off
	v_mfma_f32_16x16x32_bf16 v[12:15], v[148:151], v[224:227], v[12:15]
	v_mfma_f32_16x16x32_bf16 v[8:11], v[168:171], v[224:227], v[8:11]
	s_setprio 0
	s_setprio 1
	v_mfma_f32_16x16x32_bf16 v[52:55], v[172:175], v[190:193], 0
	v_mfma_f32_16x16x32_bf16 v[48:51], v[182:185], v[190:193], 0
	v_mfma_f32_16x16x32_bf16 v[36:39], v[172:175], v[198:201], 0
	v_mfma_f32_16x16x32_bf16 v[32:35], v[182:185], v[198:201], 0
	v_mfma_f32_16x16x32_bf16 v[20:23], v[172:175], v[212:215], 0
	v_mfma_f32_16x16x32_bf16 v[16:19], v[182:185], v[212:215], 0
	v_mfma_f32_16x16x32_bf16 v[4:7], v[172:175], v[220:223], 0
	v_mfma_f32_16x16x32_bf16 v[0:3], v[182:185], v[220:223], 0
	v_mfma_f32_16x16x32_bf16 v[52:55], v[176:179], v[194:197], v[52:55]
	v_mfma_f32_16x16x32_bf16 v[48:51], v[186:189], v[194:197], v[48:51]
	v_mfma_f32_16x16x32_bf16 v[36:39], v[176:179], v[208:211], v[36:39]
	v_mfma_f32_16x16x32_bf16 v[32:35], v[186:189], v[208:211], v[32:35]
	v_mfma_f32_16x16x32_bf16 v[20:23], v[176:179], v[216:219], v[20:23]
	v_mfma_f32_16x16x32_bf16 v[16:19], v[186:189], v[216:219], v[16:19]
	v_lshl_add_u64 v[230:231], s[54:55], 0, v[130:131]
	s_mov_b32 m0, s57
	s_nop 0
	global_load_lds_dwordx4 v[230:231], off
	v_mfma_f32_16x16x32_bf16 v[4:7], v[176:179], v[224:227], v[4:7]
	v_mfma_f32_16x16x32_bf16 v[0:3], v[186:189], v[224:227], v[0:3]
	s_setprio 0
	s_barrier
	s_add_i32 s3, 0, 0x18000
	v_add_u32_e32 v159, s3, v153
	s_add_i32 s33, 0, 0x1c000
	ds_read_b128 v[144:147], v159
	ds_read_b128 v[148:151], v159 offset:1024
	ds_read_b128 v[160:163], v159 offset:2048
	ds_read_b128 v[168:171], v159 offset:3072
	v_add_u32_e32 v159, s33, v153
	ds_read_b128 v[172:175], v159
	ds_read_b128 v[176:179], v159 offset:1024
	ds_read_b128 v[182:185], v159 offset:2048
	ds_read_b128 v[186:189], v159 offset:3072
	s_add_u32 s14, s54, 0x40000
	s_addc_u32 s15, s55, 0
	s_mov_b32 m0, s58
	v_lshl_add_u64 v[232:233], s[14:15], 0, v[134:135]
	ds_read_b128 v[190:193], v157 offset:32768
	ds_read_b128 v[194:197], v157 offset:33792
	ds_read_b128 v[198:201], v157 offset:34816
	ds_read_b128 v[208:211], v157 offset:35840
	ds_read_b128 v[212:215], v157 offset:36864
	ds_read_b128 v[216:219], v157 offset:37888
	ds_read_b128 v[220:223], v157 offset:38912
	ds_read_b128 v[224:227], v157 offset:39936
	global_load_lds_dwordx4 v[232:233], off
	v_lshl_add_u64 v[232:233], s[14:15], 0, v[130:131]
	s_mov_b32 m0, s59
	s_nop 0
	global_load_lds_dwordx4 v[232:233], off
	s_waitcnt vmcnt(8)
	s_waitcnt lgkmcnt(0)
	s_barrier
	s_setprio 1
	s_waitcnt lgkmcnt(0)
	v_mfma_f32_16x16x32_bf16 v[124:127], v[144:147], v[190:193], v[124:127]
	v_mfma_f32_16x16x32_bf16 v[120:123], v[160:163], v[190:193], v[120:123]
	v_mfma_f32_16x16x32_bf16 v[108:111], v[144:147], v[198:201], v[108:111]
	v_mfma_f32_16x16x32_bf16 v[104:107], v[160:163], v[198:201], v[104:107]
	v_mfma_f32_16x16x32_bf16 v[92:95], v[144:147], v[212:215], v[92:95]
	v_mfma_f32_16x16x32_bf16 v[88:91], v[160:163], v[212:215], v[88:91]
	v_mfma_f32_16x16x32_bf16 v[76:79], v[144:147], v[220:223], v[76:79]
	v_mfma_f32_16x16x32_bf16 v[72:75], v[160:163], v[220:223], v[72:75]
	v_mfma_f32_16x16x32_bf16 v[124:127], v[148:151], v[194:197], v[124:127]
	v_mfma_f32_16x16x32_bf16 v[120:123], v[168:171], v[194:197], v[120:123]
	v_mfma_f32_16x16x32_bf16 v[108:111], v[148:151], v[208:211], v[108:111]
	v_mfma_f32_16x16x32_bf16 v[104:107], v[168:171], v[208:211], v[104:107]
	v_mfma_f32_16x16x32_bf16 v[92:95], v[148:151], v[216:219], v[92:95]
	v_mfma_f32_16x16x32_bf16 v[88:91], v[168:171], v[216:219], v[88:91]
	v_mfma_f32_16x16x32_bf16 v[76:79], v[148:151], v[224:227], v[76:79]
	v_mfma_f32_16x16x32_bf16 v[72:75], v[168:171], v[224:227], v[72:75]
	s_setprio 0
	s_setprio 1
	v_mfma_f32_16x16x32_bf16 v[116:119], v[172:175], v[190:193], v[116:119]
	v_mfma_f32_16x16x32_bf16 v[112:115], v[182:185], v[190:193], v[112:115]
	v_mfma_f32_16x16x32_bf16 v[100:103], v[172:175], v[198:201], v[100:103]
	v_mfma_f32_16x16x32_bf16 v[96:99], v[182:185], v[198:201], v[96:99]
	v_mfma_f32_16x16x32_bf16 v[84:87], v[172:175], v[212:215], v[84:87]
	v_mfma_f32_16x16x32_bf16 v[80:83], v[182:185], v[212:215], v[80:83]
	v_mfma_f32_16x16x32_bf16 v[68:71], v[172:175], v[220:223], v[68:71]
	v_mfma_f32_16x16x32_bf16 v[64:67], v[182:185], v[220:223], v[64:67]
	v_mfma_f32_16x16x32_bf16 v[116:119], v[176:179], v[194:197], v[116:119]
	v_mfma_f32_16x16x32_bf16 v[112:115], v[186:189], v[194:197], v[112:115]
	v_mfma_f32_16x16x32_bf16 v[100:103], v[176:179], v[208:211], v[100:103]
	v_mfma_f32_16x16x32_bf16 v[96:99], v[186:189], v[208:211], v[96:99]
	v_mfma_f32_16x16x32_bf16 v[84:87], v[176:179], v[216:219], v[84:87]
	v_mfma_f32_16x16x32_bf16 v[80:83], v[186:189], v[216:219], v[80:83]
	v_mfma_f32_16x16x32_bf16 v[68:71], v[176:179], v[224:227], v[68:71]
	v_mfma_f32_16x16x32_bf16 v[64:67], v[186:189], v[224:227], v[64:67]
	s_setprio 0
	s_barrier
; #define PG8_STAGE(bufoff, gbase, voff) do { _Pragma("unroll") for (int _i = 0; _i < 2; ++_i) \
;         __builtin_amdgcn_global_load_lds((const unsigned*)((const char*)(gbase) + (voff)[_i]), (PG8_LAS unsigned*)(lds + (bufoff) + ldsw + _i * 8192), 16, 0, 0); } while (0)
; #define PG8_LDA(dst, b, h) do { _Pragma("unroll") for (int m = 0; m < 4; ++m) _Pragma("unroll") for (int k = 0; k < 2; ++k) dst[m][k] = *(const PG8_LAS bf16x8*)(lds + PG8_SA(b, h) + aoff + m * 2048 + k * 1024); } while (0)
; #define PG8_LDB(dst, b, h) do { _Pragma("unroll") for (int n = 0; n < 2; ++n) _Pragma("unroll") for (int k = 0; k < 2; ++k) dst[n][k] = *(const PG8_LAS bf16x8*)(lds + PG8_SB(b, h) + boff + n * 2048 + k * 1024); } while (0)
; #define PG8_MMA(ai, bj, At, Bt) do { __builtin_amdgcn_s_setprio(1); _Pragma("unroll") for (int m = 0; m < 4; ++m) _Pragma("unroll") for (int n = 0; n < 2; ++n) _Pragma("unroll") for (int k = 0; k < 2; ++k) \
;         acc[ai][bj][m][n] = __builtin_amdgcn_mfma_f32_16x16x32_bf16(Bt[n][k], At[m][k], acc[ai][bj][m][n], 0, 0, 0); __builtin_amdgcn_s_setprio(0); } while (0)
; #define PG8_WAIT_V(n) asm volatile("s_waitcnt vmcnt(" #n ")" ::: "memory")
; #define PG8_WAIT_L(n) asm volatile("s_waitcnt lgkmcnt(" #n ")" ::: "memory")
; #define PG8_BAR __builtin_amdgcn_s_barrier()
; #define PG8_SCHED __builtin_amdgcn_sched_barrier(0)
; template <class Epi, class Sched, bool ALIGN_EPI = false, bool SP2 = false>
; __device__ __forceinline__ void gemm_phase(PG8_LAS unsigned char* lds, const Gemm g, const Sched& S, const Epi& E) {
;     ...
;             PG8_LDB(B0, 0, 0); PG8_LDB(B1, 0, 1); PG8_SCHED; PG8_LDA(At, 0, 0); PG8_STAGE(PG8_SA(1, 1), a1 + hstep, voffA);
;             PG8_WAIT_V(8); PG8_WAIT_L(0); PG8_BAR; PG8_MMA(0, 0, At, B0); PG8_MMA(0, 1, At, B1); PG8_BAR; PG8_SCHED;
;     ...
;             PG8_LDA(At, 1, 1); PG8_STAGE(PG8_SB(1, 0), b3, voffB); PG8_STAGE(PG8_SB(1, 1), b3 + hstep, voffB); PG8_STAGE(PG8_SA(1, 0), a3, voffA);
;             PG8_WAIT_V(8); PG8_WAIT_L(0); PG8_BAR; PG8_MMA(1, 0, At, B0); PG8_MMA(1, 1, At, B1); PG8_BAR; PG8_SCHED;
	s_add_i32 s3, s3, s43
	v_lshl_add_u64 v[164:165], v[164:165], 0, s[10:11]
	s_mov_b32 m0, s3
	ds_read_b128 v[190:193], v157 offset:49152
	ds_read_b128 v[194:197], v157 offset:50176
	ds_read_b128 v[198:201], v157 offset:51200
	ds_read_b128 v[208:211], v157 offset:52224
	ds_read_b128 v[212:215], v157 offset:53248
	ds_read_b128 v[216:219], v157 offset:54272
	ds_read_b128 v[220:223], v157 offset:55296
	ds_read_b128 v[224:227], v157 offset:56320
	global_load_lds_dwordx4 v[164:165], off
	s_add_i32 m0, s3, 0x2000
	s_add_u32 s14, s50, 0x40080
	v_lshl_add_u64 v[164:165], v[202:203], 0, s[10:11]
	s_addc_u32 s15, s51, 0
	s_add_i32 s3, s33, s43
	global_load_lds_dwordx4 v[164:165], off
	v_lshl_add_u64 v[164:165], s[14:15], 0, v[132:133]
	s_mov_b32 m0, s3
	s_nop 0
	global_load_lds_dwordx4 v[164:165], off
	v_lshl_add_u64 v[164:165], s[14:15], 0, v[128:129]
	s_add_i32 m0, s3, 0x2000
	s_nop 0
	global_load_lds_dwordx4 v[164:165], off
	s_waitcnt vmcnt(6)
	s_waitcnt lgkmcnt(0)
	s_barrier
	s_setprio 1
	s_waitcnt lgkmcnt(0)
	v_mfma_f32_16x16x32_bf16 v[60:63], v[144:147], v[190:193], v[60:63]
	v_mfma_f32_16x16x32_bf16 v[56:59], v[160:163], v[190:193], v[56:59]
	v_mfma_f32_16x16x32_bf16 v[44:47], v[144:147], v[198:201], v[44:47]
	v_mfma_f32_16x16x32_bf16 v[40:43], v[160:163], v[198:201], v[40:43]
	v_mfma_f32_16x16x32_bf16 v[28:31], v[144:147], v[212:215], v[28:31]
	v_mfma_f32_16x16x32_bf16 v[24:27], v[160:163], v[212:215], v[24:27]
	v_mfma_f32_16x16x32_bf16 v[12:15], v[144:147], v[220:223], v[12:15]
	v_mfma_f32_16x16x32_bf16 v[8:11], v[160:163], v[220:223], v[8:11]
	v_mfma_f32_16x16x32_bf16 v[60:63], v[148:151], v[194:197], v[60:63]
	v_mfma_f32_16x16x32_bf16 v[56:59], v[168:171], v[194:197], v[56:59]
	v_mfma_f32_16x16x32_bf16 v[44:47], v[148:151], v[208:211], v[44:47]
	v_mfma_f32_16x16x32_bf16 v[40:43], v[168:171], v[208:211], v[40:43]
	v_mfma_f32_16x16x32_bf16 v[28:31], v[148:151], v[216:219], v[28:31]
	v_mfma_f32_16x16x32_bf16 v[24:27], v[168:171], v[216:219], v[24:27]
	v_lshl_add_u64 v[164:165], v[228:229], 0, s[10:11]
	s_mov_b32 m0, s61
	s_nop 0
	global_load_lds_dwordx4 v[164:165], off
	v_mfma_f32_16x16x32_bf16 v[12:15], v[148:151], v[224:227], v[12:15]
	v_mfma_f32_16x16x32_bf16 v[8:11], v[168:171], v[224:227], v[8:11]
	s_setprio 0
	s_setprio 1
	v_mfma_f32_16x16x32_bf16 v[52:55], v[172:175], v[190:193], v[52:55]
	v_mfma_f32_16x16x32_bf16 v[48:51], v[182:185], v[190:193], v[48:51]
	v_mfma_f32_16x16x32_bf16 v[36:39], v[172:175], v[198:201], v[36:39]
	v_mfma_f32_16x16x32_bf16 v[32:35], v[182:185], v[198:201], v[32:35]
	v_mfma_f32_16x16x32_bf16 v[20:23], v[172:175], v[212:215], v[20:23]
	v_mfma_f32_16x16x32_bf16 v[16:19], v[182:185], v[212:215], v[16:19]
	v_mfma_f32_16x16x32_bf16 v[4:7], v[172:175], v[220:223], v[4:7]
	v_mfma_f32_16x16x32_bf16 v[0:3], v[182:185], v[220:223], v[0:3]
	v_mfma_f32_16x16x32_bf16 v[52:55], v[176:179], v[194:197], v[52:55]
	v_mfma_f32_16x16x32_bf16 v[48:51], v[186:189], v[194:197], v[48:51]
	v_mfma_f32_16x16x32_bf16 v[36:39], v[176:179], v[208:211], v[36:39]
	v_mfma_f32_16x16x32_bf16 v[32:35], v[186:189], v[208:211], v[32:35]
	v_mfma_f32_16x16x32_bf16 v[20:23], v[176:179], v[216:219], v[20:23]
	v_mfma_f32_16x16x32_bf16 v[16:19], v[186:189], v[216:219], v[16:19]
	v_lshl_add_u64 v[164:165], v[230:231], 0, s[10:11]
	s_mov_b32 m0, s62
	s_nop 0
	global_load_lds_dwordx4 v[164:165], off
	v_mfma_f32_16x16x32_bf16 v[4:7], v[176:179], v[224:227], v[4:7]
	v_mfma_f32_16x16x32_bf16 v[0:3], v[186:189], v[224:227], v[0:3]
	s_setprio 0
	s_barrier
	s_add_i32 s89, s89, 2
	s_add_u32 s48, s48, 0x100
	s_addc_u32 s49, s49, 0
	s_add_u32 s87, s87, 0x100
	s_addc_u32 s88, s88, 0
.LBB0_191:
	ds_read_b128 v[144:147], v155
	ds_read_b128 v[148:151], v155 offset:1024
	ds_read_b128 v[160:163], v155 offset:2048
	ds_read_b128 v[168:171], v155 offset:3072
	ds_read_b128 v[172:175], v156
	ds_read_b128 v[176:179], v156 offset:1024
	ds_read_b128 v[182:185], v156 offset:2048
	ds_read_b128 v[186:189], v156 offset:3072
	s_add_u32 s3, s48, 0xfffc0080
	s_addc_u32 s14, s49, -1
	s_cmp_eq_u32 s89, 12
	s_cselect_b32 s55, s27, s14
	s_cselect_b32 s54, s67, s3
	s_cselect_b32 s51, s25, s88
	s_cselect_b32 s50, s86, s87
	v_lshl_add_u64 v[164:165], s[48:49], 0, v[136:137]
	s_add_i32 m0, s45, 0xc000
	ds_read_b128 v[190:193], v157
	ds_read_b128 v[194:197], v157 offset:1024
	ds_read_b128 v[198:201], v157 offset:2048
	ds_read_b128 v[208:211], v157 offset:3072
	ds_read_b128 v[212:215], v157 offset:4096
	ds_read_b128 v[216:219], v157 offset:5120
	ds_read_b128 v[220:223], v157 offset:6144
	ds_read_b128 v[224:227], v157 offset:7168
	global_load_lds_dwordx4 v[164:165], off
	v_lshl_add_u64 v[164:165], s[48:49], 0, v[138:139]
	s_add_i32 m0, s45, 0xe000
	s_nop 0
	global_load_lds_dwordx4 v[164:165], off
	s_waitcnt vmcnt(8)
	s_waitcnt lgkmcnt(0)
	s_barrier
; #define PG8_STAGE(bufoff, gbase, voff) do { _Pragma("unroll") for (int _i = 0; _i < 2; ++_i) \
;         __builtin_amdgcn_global_load_lds((const unsigned*)((const char*)(gbase) + (voff)[_i]), (PG8_LAS unsigned*)(lds + (bufoff) + ldsw + _i * 8192), 16, 0, 0); } while (0)
; #define PG8_LDA(dst, b, h) do { _Pragma("unroll") for (int m = 0; m < 4; ++m) _Pragma("unroll") for (int k = 0; k < 2; ++k) dst[m][k] = *(const PG8_LAS bf16x8*)(lds + PG8_SA(b, h) + aoff + m * 2048 + k * 1024); } while (0)
; #define PG8_MMA(ai, bj, At, Bt) do { __builtin_amdgcn_s_setprio(1); _Pragma("unroll") for (int m = 0; m < 4; ++m) _Pragma("unroll") for (int n = 0; n < 2; ++n) _Pragma("unroll") for (int k = 0; k < 2; ++k) \
;         acc[ai][bj][m][n] = __builtin_amdgcn_mfma_f32_16x16x32_bf16(Bt[n][k], At[m][k], acc[ai][bj][m][n], 0, 0, 0); __builtin_amdgcn_s_setprio(0); } while (0)
; #define PG8_WAIT_V(n) asm volatile("s_waitcnt vmcnt(" #n ")" ::: "memory")
; #define PG8_WAIT_L(n) asm volatile("s_waitcnt lgkmcnt(" #n ")" ::: "memory")
; #define PG8_BAR __builtin_amdgcn_s_barrier()
; #define PG8_SCHED __builtin_amdgcn_sched_barrier(0)
; template <class Epi, class Sched, bool ALIGN_EPI = false, bool SP2 = false>
; __device__ __forceinline__ void gemm_phase(PG8_LAS unsigned char* lds, const Gemm g, const Sched& S, const Epi& E) {
;     ...
;             PG8_WAIT_V(8); PG8_WAIT_L(0); PG8_BAR; PG8_MMA(0, 0, At, B0); PG8_MMA(0, 1, At, B1); PG8_BAR; PG8_SCHED;
;             PG8_LDA(At, 0, 1); PG8_STAGE(PG8_SB(0, 0), b2, voffB); PG8_STAGE(PG8_SB(0, 1), b2 + hstep, voffB); PG8_STAGE(PG8_SA(0, 0), a2, voffA);
;             PG8_WAIT_V(8); PG8_WAIT_L(0); PG8_BAR; PG8_MMA(1, 0, At, B0); PG8_MMA(1, 1, At, B1); PG8_BAR; PG8_SCHED;
	s_setprio 1
	s_waitcnt lgkmcnt(0)
	v_mfma_f32_16x16x32_bf16 v[124:127], v[144:147], v[190:193], v[124:127]
	v_mfma_f32_16x16x32_bf16 v[120:123], v[160:163], v[190:193], v[120:123]
	v_mfma_f32_16x16x32_bf16 v[108:111], v[144:147], v[198:201], v[108:111]
	v_mfma_f32_16x16x32_bf16 v[104:107], v[160:163], v[198:201], v[104:107]
	v_mfma_f32_16x16x32_bf16 v[92:95], v[144:147], v[212:215], v[92:95]
	v_mfma_f32_16x16x32_bf16 v[88:91], v[160:163], v[212:215], v[88:91]
	v_mfma_f32_16x16x32_bf16 v[76:79], v[144:147], v[220:223], v[76:79]
	v_mfma_f32_16x16x32_bf16 v[72:75], v[160:163], v[220:223], v[72:75]
	v_mfma_f32_16x16x32_bf16 v[124:127], v[148:151], v[194:197], v[124:127]
	v_mfma_f32_16x16x32_bf16 v[120:123], v[168:171], v[194:197], v[120:123]
	v_mfma_f32_16x16x32_bf16 v[108:111], v[148:151], v[208:211], v[108:111]
	v_mfma_f32_16x16x32_bf16 v[104:107], v[168:171], v[208:211], v[104:107]
	v_mfma_f32_16x16x32_bf16 v[92:95], v[148:151], v[216:219], v[92:95]
	v_mfma_f32_16x16x32_bf16 v[88:91], v[168:171], v[216:219], v[88:91]
	v_mfma_f32_16x16x32_bf16 v[76:79], v[148:151], v[224:227], v[76:79]
	v_mfma_f32_16x16x32_bf16 v[72:75], v[168:171], v[224:227], v[72:75]
	s_setprio 0
	s_setprio 1
	v_mfma_f32_16x16x32_bf16 v[116:119], v[172:175], v[190:193], v[116:119]
	v_mfma_f32_16x16x32_bf16 v[112:115], v[182:185], v[190:193], v[112:115]
	v_mfma_f32_16x16x32_bf16 v[100:103], v[172:175], v[198:201], v[100:103]
	v_mfma_f32_16x16x32_bf16 v[96:99], v[182:185], v[198:201], v[96:99]
	v_mfma_f32_16x16x32_bf16 v[84:87], v[172:175], v[212:215], v[84:87]
	v_mfma_f32_16x16x32_bf16 v[80:83], v[182:185], v[212:215], v[80:83]
	v_mfma_f32_16x16x32_bf16 v[68:71], v[172:175], v[220:223], v[68:71]
	v_mfma_f32_16x16x32_bf16 v[64:67], v[182:185], v[220:223], v[64:67]
	v_mfma_f32_16x16x32_bf16 v[116:119], v[176:179], v[194:197], v[116:119]
	v_mfma_f32_16x16x32_bf16 v[112:115], v[186:189], v[194:197], v[112:115]
	v_mfma_f32_16x16x32_bf16 v[100:103], v[176:179], v[208:211], v[100:103]
	v_mfma_f32_16x16x32_bf16 v[96:99], v[186:189], v[208:211], v[96:99]
	v_mfma_f32_16x16x32_bf16 v[84:87], v[176:179], v[216:219], v[84:87]
	v_mfma_f32_16x16x32_bf16 v[80:83], v[186:189], v[216:219], v[80:83]
	v_mfma_f32_16x16x32_bf16 v[68:71], v[176:179], v[224:227], v[68:71]
	v_mfma_f32_16x16x32_bf16 v[64:67], v[186:189], v[224:227], v[64:67]
	s_setprio 0
	s_barrier
	s_add_i32 s3, s63, s43
	v_lshl_add_u64 v[164:165], s[50:51], 0, v[132:133]
	s_mov_b32 m0, s3
	ds_read_b128 v[190:193], v157 offset:16384
	ds_read_b128 v[194:197], v157 offset:17408
	ds_read_b128 v[198:201], v157 offset:18432
	ds_read_b128 v[208:211], v157 offset:19456
	ds_read_b128 v[212:215], v157 offset:20480
	ds_read_b128 v[216:219], v157 offset:21504
	ds_read_b128 v[220:223], v157 offset:22528
	ds_read_b128 v[224:227], v157 offset:23552
	global_load_lds_dwordx4 v[164:165], off
	s_add_i32 m0, s3, 0x2000
	s_add_u32 s14, s50, 0x40000
	v_lshl_add_u64 v[202:203], s[50:51], 0, v[128:129]
	s_addc_u32 s15, s51, 0
	s_add_i32 s3, s64, s43
	global_load_lds_dwordx4 v[202:203], off
	v_lshl_add_u64 v[228:229], s[14:15], 0, v[132:133]
	s_mov_b32 m0, s3
	global_load_lds_dwordx4 v[228:229], off
	v_lshl_add_u64 v[228:229], s[14:15], 0, v[128:129]
	s_add_i32 m0, s3, 0x2000
	s_nop 0
	global_load_lds_dwordx4 v[228:229], off
	s_waitcnt vmcnt(6)
	s_waitcnt lgkmcnt(0)
	s_barrier
	s_setprio 1
	s_waitcnt lgkmcnt(0)
	v_mfma_f32_16x16x32_bf16 v[60:63], v[144:147], v[190:193], v[60:63]
	v_mfma_f32_16x16x32_bf16 v[56:59], v[160:163], v[190:193], v[56:59]
	v_mfma_f32_16x16x32_bf16 v[44:47], v[144:147], v[198:201], v[44:47]
	v_mfma_f32_16x16x32_bf16 v[40:43], v[160:163], v[198:201], v[40:43]
	v_mfma_f32_16x16x32_bf16 v[28:31], v[144:147], v[212:215], v[28:31]
	v_mfma_f32_16x16x32_bf16 v[24:27], v[160:163], v[212:215], v[24:27]
	v_mfma_f32_16x16x32_bf16 v[12:15], v[144:147], v[220:223], v[12:15]
	v_mfma_f32_16x16x32_bf16 v[8:11], v[160:163], v[220:223], v[8:11]
	v_mfma_f32_16x16x32_bf16 v[60:63], v[148:151], v[194:197], v[60:63]
	v_mfma_f32_16x16x32_bf16 v[56:59], v[168:171], v[194:197], v[56:59]
	v_mfma_f32_16x16x32_bf16 v[44:47], v[148:151], v[208:211], v[44:47]
	v_mfma_f32_16x16x32_bf16 v[40:43], v[168:171], v[208:211], v[40:43]
	v_mfma_f32_16x16x32_bf16 v[28:31], v[148:151], v[216:219], v[28:31]
	v_mfma_f32_16x16x32_bf16 v[24:27], v[168:171], v[216:219], v[24:27]
	v_lshl_add_u64 v[228:229], s[54:55], 0, v[134:135]
	s_mov_b32 m0, s45
	s_nop 0
	global_load_lds_dwordx4 v[228:229], off
	v_mfma_f32_16x16x32_bf16 v[12:15], v[148:151], v[224:227], v[12:15]
	v_mfma_f32_16x16x32_bf16 v[8:11], v[168:171], v[224:227], v[8:11]
	s_setprio 0
	s_setprio 1
	v_mfma_f32_16x16x32_bf16 v[52:55], v[172:175], v[190:193], v[52:55]
	v_mfma_f32_16x16x32_bf16 v[48:51], v[182:185], v[190:193], v[48:51]
	v_mfma_f32_16x16x32_bf16 v[36:39], v[172:175], v[198:201], v[36:39]
	v_mfma_f32_16x16x32_bf16 v[32:35], v[182:185], v[198:201], v[32:35]
	v_mfma_f32_16x16x32_bf16 v[20:23], v[172:175], v[212:215], v[20:23]
	v_mfma_f32_16x16x32_bf16 v[16:19], v[182:185], v[212:215], v[16:19]
	v_mfma_f32_16x16x32_bf16 v[4:7], v[172:175], v[220:223], v[4:7]
	v_mfma_f32_16x16x32_bf16 v[0:3], v[182:185], v[220:223], v[0:3]
	v_mfma_f32_16x16x32_bf16 v[52:55], v[176:179], v[194:197], v[52:55]
	v_mfma_f32_16x16x32_bf16 v[48:51], v[186:189], v[194:197], v[48:51]
	v_mfma_f32_16x16x32_bf16 v[36:39], v[176:179], v[208:211], v[36:39]
	v_mfma_f32_16x16x32_bf16 v[32:35], v[186:189], v[208:211], v[32:35]
	v_mfma_f32_16x16x32_bf16 v[20:23], v[176:179], v[216:219], v[20:23]
	v_mfma_f32_16x16x32_bf16 v[16:19], v[186:189], v[216:219], v[16:19]
	v_lshl_add_u64 v[230:231], s[54:55], 0, v[130:131]
	s_mov_b32 m0, s57
	s_nop 0
	global_load_lds_dwordx4 v[230:231], off
	v_mfma_f32_16x16x32_bf16 v[4:7], v[176:179], v[224:227], v[4:7]
	v_mfma_f32_16x16x32_bf16 v[0:3], v[186:189], v[224:227], v[0:3]
	s_setprio 0
	s_barrier
; #define PG8_STAGE(bufoff, gbase, voff) do { _Pragma("unroll") for (int _i = 0; _i < 2; ++_i) \
;         __builtin_amdgcn_global_load_lds((const unsigned*)((const char*)(gbase) + (voff)[_i]), (PG8_LAS unsigned*)(lds + (bufoff) + ldsw + _i * 8192), 16, 0, 0); } while (0)
; #define PG8_LDA(dst, b, h) do { _Pragma("unroll") for (int m = 0; m < 4; ++m) _Pragma("unroll") for (int k = 0; k < 2; ++k) dst[m][k] = *(const PG8_LAS bf16x8*)(lds + PG8_SA(b, h) + aoff + m * 2048 + k * 1024); } while (0)
; #define PG8_LDB(dst, b, h) do { _Pragma("unroll") for (int n = 0; n < 2; ++n) _Pragma("unroll") for (int k = 0; k < 2; ++k) dst[n][k] = *(const PG8_LAS bf16x8*)(lds + PG8_SB(b, h) + boff + n * 2048 + k * 1024); } while (0)
; #define PG8_MMA(ai, bj, At, Bt) do { __builtin_amdgcn_s_setprio(1); _Pragma("unroll") for (int m = 0; m < 4; ++m) _Pragma("unroll") for (int n = 0; n < 2; ++n) _Pragma("unroll") for (int k = 0; k < 2; ++k) \
;         acc[ai][bj][m][n] = __builtin_amdgcn_mfma_f32_16x16x32_bf16(Bt[n][k], At[m][k], acc[ai][bj][m][n], 0, 0, 0); __builtin_amdgcn_s_setprio(0); } while (0)
; #define PG8_WAIT_V(n) asm volatile("s_waitcnt vmcnt(" #n ")" ::: "memory")
; #define PG8_WAIT_L(n) asm volatile("s_waitcnt lgkmcnt(" #n ")" ::: "memory")
; #define PG8_BAR __builtin_amdgcn_s_barrier()
; #define PG8_SCHED __builtin_amdgcn_sched_barrier(0)
; template <class Epi, class Sched, bool ALIGN_EPI = false, bool SP2 = false>
; __device__ __forceinline__ void gemm_phase(PG8_LAS unsigned char* lds, const Gemm g, const Sched& S, const Epi& E) {
;     ...
;             PG8_LDB(B0, 1, 0); PG8_LDB(B1, 1, 1); PG8_SCHED; PG8_LDA(At, 1, 0); PG8_STAGE(PG8_SA(0, 1), a2 + hstep, voffA);
;             PG8_WAIT_V(8); PG8_WAIT_L(0); PG8_BAR; PG8_MMA(0, 0, At, B0); PG8_MMA(0, 1, At, B1); PG8_BAR; PG8_SCHED;
;             PG8_LDA(At, 1, 1); PG8_STAGE(PG8_SB(1, 0), b3, voffB); PG8_STAGE(PG8_SB(1, 1), b3 + hstep, voffB); PG8_STAGE(PG8_SA(1, 0), a3, voffA);
	s_add_i32 s3, 0, 0x18000
	v_add_u32_e32 v159, s3, v153
	s_add_i32 s33, 0, 0x1c000
	ds_read_b128 v[144:147], v159
	ds_read_b128 v[148:151], v159 offset:1024
	ds_read_b128 v[160:163], v159 offset:2048
	ds_read_b128 v[168:171], v159 offset:3072
	v_add_u32_e32 v159, s33, v153
	ds_read_b128 v[172:175], v159
	ds_read_b128 v[176:179], v159 offset:1024
	ds_read_b128 v[182:185], v159 offset:2048
	ds_read_b128 v[186:189], v159 offset:3072
	s_add_u32 s14, s54, 0x40000
	s_addc_u32 s15, s55, 0
	s_mov_b32 m0, s58
	v_lshl_add_u64 v[232:233], s[14:15], 0, v[134:135]
	ds_read_b128 v[190:193], v157 offset:32768
	ds_read_b128 v[194:197], v157 offset:33792
	ds_read_b128 v[198:201], v157 offset:34816
	ds_read_b128 v[208:211], v157 offset:35840
	ds_read_b128 v[212:215], v157 offset:36864
	ds_read_b128 v[216:219], v157 offset:37888
	ds_read_b128 v[220:223], v157 offset:38912
	ds_read_b128 v[224:227], v157 offset:39936
	global_load_lds_dwordx4 v[232:233], off
	v_lshl_add_u64 v[232:233], s[14:15], 0, v[130:131]
	s_mov_b32 m0, s59
	s_nop 0
	global_load_lds_dwordx4 v[232:233], off
	s_waitcnt vmcnt(8)
	s_waitcnt lgkmcnt(0)
	s_barrier
	s_setprio 1
	s_waitcnt lgkmcnt(0)
	v_mfma_f32_16x16x32_bf16 v[124:127], v[144:147], v[190:193], v[124:127]
	v_mfma_f32_16x16x32_bf16 v[120:123], v[160:163], v[190:193], v[120:123]
	v_mfma_f32_16x16x32_bf16 v[108:111], v[144:147], v[198:201], v[108:111]
	v_mfma_f32_16x16x32_bf16 v[104:107], v[160:163], v[198:201], v[104:107]
	v_mfma_f32_16x16x32_bf16 v[92:95], v[144:147], v[212:215], v[92:95]
	v_mfma_f32_16x16x32_bf16 v[88:91], v[160:163], v[212:215], v[88:91]
	v_mfma_f32_16x16x32_bf16 v[76:79], v[144:147], v[220:223], v[76:79]
	v_mfma_f32_16x16x32_bf16 v[72:75], v[160:163], v[220:223], v[72:75]
	v_mfma_f32_16x16x32_bf16 v[124:127], v[148:151], v[194:197], v[124:127]
	v_mfma_f32_16x16x32_bf16 v[120:123], v[168:171], v[194:197], v[120:123]
	v_mfma_f32_16x16x32_bf16 v[108:111], v[148:151], v[208:211], v[108:111]
	v_mfma_f32_16x16x32_bf16 v[104:107], v[168:171], v[208:211], v[104:107]
	v_mfma_f32_16x16x32_bf16 v[92:95], v[148:151], v[216:219], v[92:95]
	v_mfma_f32_16x16x32_bf16 v[88:91], v[168:171], v[216:219], v[88:91]
	v_mfma_f32_16x16x32_bf16 v[76:79], v[148:151], v[224:227], v[76:79]
	v_mfma_f32_16x16x32_bf16 v[72:75], v[168:171], v[224:227], v[72:75]
	s_setprio 0
	s_setprio 1
	v_mfma_f32_16x16x32_bf16 v[116:119], v[172:175], v[190:193], v[116:119]
	v_mfma_f32_16x16x32_bf16 v[112:115], v[182:185], v[190:193], v[112:115]
	v_mfma_f32_16x16x32_bf16 v[100:103], v[172:175], v[198:201], v[100:103]
	v_mfma_f32_16x16x32_bf16 v[96:99], v[182:185], v[198:201], v[96:99]
	v_mfma_f32_16x16x32_bf16 v[84:87], v[172:175], v[212:215], v[84:87]
	v_mfma_f32_16x16x32_bf16 v[80:83], v[182:185], v[212:215], v[80:83]
	v_mfma_f32_16x16x32_bf16 v[68:71], v[172:175], v[220:223], v[68:71]
	v_mfma_f32_16x16x32_bf16 v[64:67], v[182:185], v[220:223], v[64:67]
	v_mfma_f32_16x16x32_bf16 v[116:119], v[176:179], v[194:197], v[116:119]
	v_mfma_f32_16x16x32_bf16 v[112:115], v[186:189], v[194:197], v[112:115]
	v_mfma_f32_16x16x32_bf16 v[100:103], v[176:179], v[208:211], v[100:103]
	v_mfma_f32_16x16x32_bf16 v[96:99], v[186:189], v[208:211], v[96:99]
	v_mfma_f32_16x16x32_bf16 v[84:87], v[176:179], v[216:219], v[84:87]
	v_mfma_f32_16x16x32_bf16 v[80:83], v[186:189], v[216:219], v[80:83]
	v_mfma_f32_16x16x32_bf16 v[68:71], v[176:179], v[224:227], v[68:71]
	v_mfma_f32_16x16x32_bf16 v[64:67], v[186:189], v[224:227], v[64:67]
	s_setprio 0
	s_barrier
	s_add_i32 s3, s3, s43
	v_lshl_add_u64 v[164:165], v[164:165], 0, s[10:11]
	s_mov_b32 m0, s3
	ds_read_b128 v[190:193], v157 offset:49152
	ds_read_b128 v[194:197], v157 offset:50176
	ds_read_b128 v[198:201], v157 offset:51200
	ds_read_b128 v[208:211], v157 offset:52224
	ds_read_b128 v[212:215], v157 offset:53248
	ds_read_b128 v[216:219], v157 offset:54272
	ds_read_b128 v[220:223], v157 offset:55296
	ds_read_b128 v[224:227], v157 offset:56320
	global_load_lds_dwordx4 v[164:165], off
	s_add_i32 m0, s3, 0x2000
	s_add_u32 s14, s50, 0x40080
	v_lshl_add_u64 v[164:165], v[202:203], 0, s[10:11]
	s_addc_u32 s15, s51, 0
	s_add_i32 s3, s33, s43
	global_load_lds_dwordx4 v[164:165], off
	v_lshl_add_u64 v[164:165], s[14:15], 0, v[132:133]
	s_mov_b32 m0, s3
	s_nop 0
	global_load_lds_dwordx4 v[164:165], off
	v_lshl_add_u64 v[164:165], s[14:15], 0, v[128:129]
	s_add_i32 m0, s3, 0x2000
	s_nop 0
	global_load_lds_dwordx4 v[164:165], off
	s_waitcnt vmcnt(6)
	s_waitcnt lgkmcnt(0)
	s_barrier
; __device__ __forceinline__ unsigned cvtpk(float lo, float hi) { f32x2v_ v = {lo, hi}; bf16x2v_ b = __builtin_convertvector(v, bf16x2v_); return __builtin_bit_cast(unsigned, b); }
; #define PG8_STAGE(bufoff, gbase, voff) do { _Pragma("unroll") for (int _i = 0; _i < 2; ++_i) \
;         __builtin_amdgcn_global_load_lds((const unsigned*)((const char*)(gbase) + (voff)[_i]), (PG8_LAS unsigned*)(lds + (bufoff) + ldsw + _i * 8192), 16, 0, 0); } while (0)
; #define PG8_LDA(dst, b, h) do { _Pragma("unroll") for (int m = 0; m < 4; ++m) _Pragma("unroll") for (int k = 0; k < 2; ++k) dst[m][k] = *(const PG8_LAS bf16x8*)(lds + PG8_SA(b, h) + aoff + m * 2048 + k * 1024); } while (0)
; #define PG8_WAIT_V(n) asm volatile("s_waitcnt vmcnt(" #n ")" ::: "memory")
; #define PG8_WAIT_L(n) asm volatile("s_waitcnt lgkmcnt(" #n ")" ::: "memory")
;     __device__ __forceinline__ void operator()(const f32x4 (&acc)[2][2][4][2], const Unit& u, int wr, int wc, int fr, int fq) const {
;         const int row0 = u.pm * BM + wr * 64 + fr, col0 = u.pn * HALF + wc * 32 + 8 * fq;
; #pragma unroll
;         for (int ai = 0; ai < 2; ++ai)
; #pragma unroll
;             for (int m = 0; m < 4; ++m) { const int row = row0 + ai * HALF + m * 16; const float rs = row_rs(ss, row);
;                 float hv[8];
; #pragma unroll
;                 for (int n = 0; n < 2; ++n)
; #pragma unroll
;                     for (int i = 0; i < 4; ++i) { const float g = acc[ai][0][m][n][i] * rs, uu = acc[ai][1][m][n][i] * rs;
;                         hv[n * 4 + i] = g * __builtin_amdgcn_rcpf(1.0f + __expf(-g)) * uu; }
;                 u32x4 w; w.x = cvtpk(hv[0], hv[1]); w.y = cvtpk(hv[2], hv[3]); w.z = cvtpk(hv[4], hv[5]); w.w = cvtpk(hv[6], hv[7]);
;                 *(u32x4*)(H + (size_t)row * ldh + col0) = w; }
; template <class Epi, class Sched, bool ALIGN_EPI = false, bool SP2 = false>
; __device__ __forceinline__ void gemm_phase(PG8_LAS unsigned char* lds, const Gemm g, const Sched& S, const Epi& E) {
;     ...
;             PG8_WAIT_V(8); PG8_WAIT_L(0); PG8_BAR; PG8_MMA(0, 0, At, B0); PG8_MMA(0, 1, At, B1); PG8_BAR; PG8_SCHED;
;             PG8_LDA(At, 1, 1); PG8_STAGE(PG8_SB(1, 0), b3, voffB); PG8_STAGE(PG8_SB(1, 1), b3 + hstep, voffB); PG8_STAGE(PG8_SA(1, 0), a3, voffA);
;             PG8_WAIT_V(8); PG8_WAIT_L(0); PG8_BAR; PG8_MMA(1, 0, At, B0); PG8_MMA(1, 1, At, B1); PG8_BAR; PG8_SCHED;
	s_setprio 1
	s_waitcnt lgkmcnt(0)
	v_mfma_f32_16x16x32_bf16 v[60:63], v[144:147], v[190:193], v[60:63]
	v_mfma_f32_16x16x32_bf16 v[56:59], v[160:163], v[190:193], v[56:59]
	v_mfma_f32_16x16x32_bf16 v[44:47], v[144:147], v[198:201], v[44:47]
	v_mfma_f32_16x16x32_bf16 v[40:43], v[160:163], v[198:201], v[40:43]
	v_mfma_f32_16x16x32_bf16 v[28:31], v[144:147], v[212:215], v[28:31]
	v_mfma_f32_16x16x32_bf16 v[24:27], v[160:163], v[212:215], v[24:27]
	v_mfma_f32_16x16x32_bf16 v[12:15], v[144:147], v[220:223], v[12:15]
	v_mfma_f32_16x16x32_bf16 v[8:11], v[160:163], v[220:223], v[8:11]
	v_mfma_f32_16x16x32_bf16 v[60:63], v[148:151], v[194:197], v[60:63]
	v_mfma_f32_16x16x32_bf16 v[56:59], v[168:171], v[194:197], v[56:59]
	v_mfma_f32_16x16x32_bf16 v[44:47], v[148:151], v[208:211], v[44:47]
	v_mfma_f32_16x16x32_bf16 v[40:43], v[168:171], v[208:211], v[40:43]
	v_mfma_f32_16x16x32_bf16 v[28:31], v[148:151], v[216:219], v[28:31]
	v_mfma_f32_16x16x32_bf16 v[24:27], v[168:171], v[216:219], v[24:27]
	v_lshl_add_u64 v[164:165], v[228:229], 0, s[10:11]
	s_mov_b32 m0, s61
	s_nop 0
	global_load_lds_dwordx4 v[164:165], off
	v_mfma_f32_16x16x32_bf16 v[12:15], v[148:151], v[224:227], v[12:15]
	v_mfma_f32_16x16x32_bf16 v[8:11], v[168:171], v[224:227], v[8:11]
	s_setprio 0
	s_setprio 1
	v_mfma_f32_16x16x32_bf16 v[52:55], v[172:175], v[190:193], v[52:55]
	v_mfma_f32_16x16x32_bf16 v[48:51], v[182:185], v[190:193], v[48:51]
	v_mfma_f32_16x16x32_bf16 v[36:39], v[172:175], v[198:201], v[36:39]
	v_mfma_f32_16x16x32_bf16 v[32:35], v[182:185], v[198:201], v[32:35]
	v_mfma_f32_16x16x32_bf16 v[20:23], v[172:175], v[212:215], v[20:23]
	v_mfma_f32_16x16x32_bf16 v[16:19], v[182:185], v[212:215], v[16:19]
	v_mfma_f32_16x16x32_bf16 v[4:7], v[172:175], v[220:223], v[4:7]
	v_mfma_f32_16x16x32_bf16 v[0:3], v[182:185], v[220:223], v[0:3]
	v_mfma_f32_16x16x32_bf16 v[52:55], v[176:179], v[194:197], v[52:55]
	v_mfma_f32_16x16x32_bf16 v[48:51], v[186:189], v[194:197], v[48:51]
	v_mfma_f32_16x16x32_bf16 v[36:39], v[176:179], v[208:211], v[36:39]
	v_mfma_f32_16x16x32_bf16 v[32:35], v[186:189], v[208:211], v[32:35]
	v_mfma_f32_16x16x32_bf16 v[20:23], v[176:179], v[216:219], v[20:23]
	v_mfma_f32_16x16x32_bf16 v[16:19], v[186:189], v[216:219], v[16:19]
	v_lshl_add_u64 v[164:165], v[230:231], 0, s[10:11]
	s_mov_b32 m0, s62
	s_nop 0
	global_load_lds_dwordx4 v[164:165], off
	v_mfma_f32_16x16x32_bf16 v[4:7], v[176:179], v[224:227], v[4:7]
	v_mfma_f32_16x16x32_bf16 v[0:3], v[186:189], v[224:227], v[0:3]
	s_setprio 0
	s_barrier
	s_add_i32 s89, s89, 2
	s_add_u32 s48, s48, 0x100
	s_addc_u32 s49, s49, 0
	s_add_u32 s87, s87, 0x100
	s_addc_u32 s88, s88, 0
	s_cmp_gt_u32 s89, 13
	s_cbranch_scc0 .LBB0_191
	v_lshl_add_u32 v144, s44, 8, v152
	v_ashrrev_i32_e32 v145, 31, v144
	v_lshl_add_u64 v[150:151], v[144:145], 3, s[6:7]
	global_load_dwordx2 v[182:183], v[150:151], off
	global_load_dwordx2 v[184:185], v[150:151], off offset:128
	global_load_dwordx2 v[186:187], v[150:151], off offset:256
	global_load_dwordx2 v[188:189], v[150:151], off offset:384
	global_load_dwordx2 v[190:191], v[150:151], off offset:1024
	global_load_dwordx2 v[192:193], v[150:151], off offset:1152
	global_load_dwordx2 v[194:195], v[150:151], off offset:1280
	global_load_dwordx2 v[196:197], v[150:151], off offset:1408
	s_and_b64 vcc, exec, s[16:17]
	s_cbranch_vccz .LBB0_194
.LBB0_194:
	v_lshl_or_b32 v160, s66, 7, v154
	v_ashrrev_i32_e32 v161, 31, v160
	v_or_b32_e32 v164, 16, v144
	v_ashrrev_i32_e32 v165, 31, v164
	v_lshl_add_u64 v[168:169], v[164:165], 3, s[6:7]
	v_mov_b64_e32 v[146:147], s[20:21]
	v_mad_i64_i32 v[162:163], s[14:15], v144, s65, v[146:147]
	s_andn2_b64 vcc, exec, s[0:1]
	s_mov_b64 s[0:1], -1
	s_waitcnt vmcnt(7)
	v_cvt_f32_u32_e32 v159, v183
	v_cvt_f32_u32_e32 v145, v182
	v_lshlrev_b64 v[148:149], 1, v[160:161]
	v_lshl_add_u64 v[162:163], v[162:163], 0, v[148:149]
	v_fmamk_f32 v145, v145, 0x2f800000, v159
	v_fmamk_f32 v145, v145, 0x3a800000, v158
	v_rsq_f32_e32 v160, v145
	s_nop 0
	v_mul_f32_e32 v182, 0xbfb8aa3b, v160
	v_mul_f32_e32 v183, v160, v160
	v_pk_mul_f32 v[160:161], v[124:125], v[182:183] op_sel_hi:[1,0]
	v_pk_mul_f32 v[170:171], v[126:127], v[182:183] op_sel_hi:[1,0]
	v_pk_mul_f32 v[172:173], v[120:121], v[182:183] op_sel_hi:[1,0]
	v_pk_mul_f32 v[174:175], v[122:123], v[182:183] op_sel_hi:[1,0]
	v_pk_mul_f32 v[116:117], v[116:117], v[124:125]
	v_pk_mul_f32 v[118:119], v[118:119], v[126:127]
	v_pk_mul_f32 v[120:121], v[112:113], v[120:121]
	v_pk_mul_f32 v[122:123], v[114:115], v[122:123]
	v_exp_f32_e32 v160, v160
	v_exp_f32_e32 v161, v161
	v_exp_f32_e32 v170, v170
	v_exp_f32_e32 v171, v171
	v_exp_f32_e32 v172, v172
	v_exp_f32_e32 v173, v173
	v_exp_f32_e32 v174, v174
	v_exp_f32_e32 v175, v175
	v_pk_mul_f32 v[116:117], v[116:117], v[182:183] op_sel:[0,1] op_sel_hi:[1,1]
	v_pk_mul_f32 v[118:119], v[118:119], v[182:183] op_sel:[0,1] op_sel_hi:[1,1]
	v_pk_mul_f32 v[120:121], v[120:121], v[182:183] op_sel:[0,1] op_sel_hi:[1,1]
	v_pk_mul_f32 v[122:123], v[122:123], v[182:183] op_sel:[0,1] op_sel_hi:[1,1]
	v_pk_add_f32 v[160:161], v[160:161], 1.0 op_sel_hi:[1,0]
	v_pk_add_f32 v[170:171], v[170:171], 1.0 op_sel_hi:[1,0]
	v_pk_add_f32 v[172:173], v[172:173], 1.0 op_sel_hi:[1,0]
	v_pk_add_f32 v[174:175], v[174:175], 1.0 op_sel_hi:[1,0]
	v_rcp_f32_e32 v160, v160
	v_rcp_f32_e32 v161, v161
	v_rcp_f32_e32 v170, v170
	v_rcp_f32_e32 v171, v171
	v_rcp_f32_e32 v172, v172
	v_rcp_f32_e32 v173, v173
	v_rcp_f32_e32 v174, v174
	v_rcp_f32_e32 v175, v175
	v_pk_mul_f32 v[116:117], v[116:117], v[160:161]
	v_pk_mul_f32 v[118:119], v[118:119], v[170:171]
	v_pk_mul_f32 v[120:121], v[120:121], v[172:173]
	v_pk_mul_f32 v[122:123], v[122:123], v[174:175]
	v_cvt_pk_bf16_f32 v112, v116, v117
	v_cvt_pk_bf16_f32 v113, v118, v119
	v_cvt_pk_bf16_f32 v114, v120, v121
	v_cvt_pk_bf16_f32 v115, v122, v123
	global_store_dwordx4 v[162:163], v[112:115], off
	s_nop 0
	s_nop 0
	v_or_b32_e32 v114, 32, v144
	s_waitcnt vmcnt(7)
; __device__ __forceinline__ unsigned cvtpk(float lo, float hi) { f32x2v_ v = {lo, hi}; bf16x2v_ b = __builtin_convertvector(v, bf16x2v_); return __builtin_bit_cast(unsigned, b); }
;     __device__ __forceinline__ void operator()(const f32x4 (&acc)[2][2][4][2], const Unit& u, int wr, int wc, int fr, int fq) const {
;     ...
;             for (int m = 0; m < 4; ++m) { const int row = row0 + ai * HALF + m * 16; const float rs = row_rs(ss, row);
;                 float hv[8];
; #pragma unroll
;                 for (int n = 0; n < 2; ++n)
; #pragma unroll
;                     for (int i = 0; i < 4; ++i) { const float g = acc[ai][0][m][n][i] * rs, uu = acc[ai][1][m][n][i] * rs;
;                         hv[n * 4 + i] = g * __builtin_amdgcn_rcpf(1.0f + __expf(-g)) * uu; }
;                 u32x4 w; w.x = cvtpk(hv[0], hv[1]); w.y = cvtpk(hv[2], hv[3]); w.z = cvtpk(hv[4], hv[5]); w.w = cvtpk(hv[6], hv[7]);
;                 *(u32x4*)(H + (size_t)row * ldh + col0) = w; }
	v_cvt_f32_u32_e32 v116, v185
	v_cvt_f32_u32_e32 v115, v184
	v_mad_i64_i32 v[112:113], s[14:15], v164, s65, v[146:147]
	v_fmamk_f32 v115, v115, 0x2f800000, v116
	v_fmamk_f32 v115, v115, 0x3a800000, v158
	v_rsq_f32_e32 v116, v115
	v_ashrrev_i32_e32 v115, 31, v114
	v_lshl_add_u64 v[118:119], v[114:115], 3, s[6:7]
	v_lshl_add_u64 v[112:113], v[112:113], 0, v[148:149]
	v_mul_f32_e32 v184, 0xbfb8aa3b, v116
	v_mul_f32_e32 v185, v116, v116
	v_pk_mul_f32 v[116:117], v[108:109], v[184:185] op_sel_hi:[1,0]
	v_pk_mul_f32 v[120:121], v[110:111], v[184:185] op_sel_hi:[1,0]
	v_pk_mul_f32 v[122:123], v[104:105], v[184:185] op_sel_hi:[1,0]
	v_pk_mul_f32 v[124:125], v[106:107], v[184:185] op_sel_hi:[1,0]
	v_pk_mul_f32 v[100:101], v[100:101], v[108:109]
	v_pk_mul_f32 v[102:103], v[102:103], v[110:111]
	v_pk_mul_f32 v[104:105], v[96:97], v[104:105]
	v_pk_mul_f32 v[106:107], v[98:99], v[106:107]
	v_exp_f32_e32 v116, v116
	v_exp_f32_e32 v117, v117
	v_exp_f32_e32 v120, v120
	v_exp_f32_e32 v121, v121
	v_exp_f32_e32 v122, v122
	v_exp_f32_e32 v123, v123
	v_exp_f32_e32 v124, v124
	v_exp_f32_e32 v125, v125
	v_pk_mul_f32 v[100:101], v[100:101], v[184:185] op_sel:[0,1] op_sel_hi:[1,1]
	v_pk_mul_f32 v[102:103], v[102:103], v[184:185] op_sel:[0,1] op_sel_hi:[1,1]
	v_pk_mul_f32 v[104:105], v[104:105], v[184:185] op_sel:[0,1] op_sel_hi:[1,1]
	v_pk_mul_f32 v[106:107], v[106:107], v[184:185] op_sel:[0,1] op_sel_hi:[1,1]
	v_pk_add_f32 v[116:117], v[116:117], 1.0 op_sel_hi:[1,0]
	v_pk_add_f32 v[120:121], v[120:121], 1.0 op_sel_hi:[1,0]
	v_pk_add_f32 v[122:123], v[122:123], 1.0 op_sel_hi:[1,0]
	v_pk_add_f32 v[124:125], v[124:125], 1.0 op_sel_hi:[1,0]
	v_rcp_f32_e32 v116, v116
	v_rcp_f32_e32 v117, v117
	v_rcp_f32_e32 v120, v120
	v_rcp_f32_e32 v121, v121
	v_rcp_f32_e32 v122, v122
	v_rcp_f32_e32 v123, v123
	v_rcp_f32_e32 v124, v124
	v_rcp_f32_e32 v125, v125
	v_pk_mul_f32 v[100:101], v[100:101], v[116:117]
	v_pk_mul_f32 v[102:103], v[102:103], v[120:121]
	v_pk_mul_f32 v[104:105], v[104:105], v[122:123]
	v_pk_mul_f32 v[106:107], v[106:107], v[124:125]
	v_cvt_pk_bf16_f32 v96, v100, v101
	v_cvt_pk_bf16_f32 v97, v102, v103
	v_cvt_pk_bf16_f32 v98, v104, v105
	v_cvt_pk_bf16_f32 v99, v106, v107
	global_store_dwordx4 v[112:113], v[96:99], off
	s_nop 0
	s_nop 0
	v_or_b32_e32 v98, 48, v144
	s_waitcnt vmcnt(7)
	v_cvt_f32_u32_e32 v100, v187
	v_cvt_f32_u32_e32 v99, v186
	v_mad_i64_i32 v[96:97], s[14:15], v114, s65, v[146:147]
	v_fmamk_f32 v99, v99, 0x2f800000, v100
	v_fmamk_f32 v99, v99, 0x3a800000, v158
	v_rsq_f32_e32 v100, v99
	v_ashrrev_i32_e32 v99, 31, v98
	v_lshl_add_u64 v[102:103], v[98:99], 3, s[6:7]
	v_lshl_add_u64 v[96:97], v[96:97], 0, v[148:149]
	v_mul_f32_e32 v186, 0xbfb8aa3b, v100
	v_mul_f32_e32 v187, v100, v100
	v_pk_mul_f32 v[100:101], v[92:93], v[186:187] op_sel_hi:[1,0]
	v_pk_mul_f32 v[104:105], v[94:95], v[186:187] op_sel_hi:[1,0]
	v_pk_mul_f32 v[106:107], v[88:89], v[186:187] op_sel_hi:[1,0]
	v_pk_mul_f32 v[108:109], v[90:91], v[186:187] op_sel_hi:[1,0]
	v_pk_mul_f32 v[84:85], v[84:85], v[92:93]
	v_pk_mul_f32 v[86:87], v[86:87], v[94:95]
	v_pk_mul_f32 v[88:89], v[80:81], v[88:89]
	v_pk_mul_f32 v[90:91], v[82:83], v[90:91]
	v_exp_f32_e32 v100, v100
	v_exp_f32_e32 v101, v101
	v_exp_f32_e32 v104, v104
	v_exp_f32_e32 v105, v105
	v_exp_f32_e32 v106, v106
	v_exp_f32_e32 v107, v107
	v_exp_f32_e32 v108, v108
	v_exp_f32_e32 v109, v109
	v_pk_mul_f32 v[84:85], v[84:85], v[186:187] op_sel:[0,1] op_sel_hi:[1,1]
	v_pk_mul_f32 v[86:87], v[86:87], v[186:187] op_sel:[0,1] op_sel_hi:[1,1]
	v_pk_mul_f32 v[88:89], v[88:89], v[186:187] op_sel:[0,1] op_sel_hi:[1,1]
	v_pk_mul_f32 v[90:91], v[90:91], v[186:187] op_sel:[0,1] op_sel_hi:[1,1]
	v_pk_add_f32 v[100:101], v[100:101], 1.0 op_sel_hi:[1,0]
	v_pk_add_f32 v[104:105], v[104:105], 1.0 op_sel_hi:[1,0]
	v_pk_add_f32 v[106:107], v[106:107], 1.0 op_sel_hi:[1,0]
	v_pk_add_f32 v[108:109], v[108:109], 1.0 op_sel_hi:[1,0]
	v_rcp_f32_e32 v100, v100
	v_rcp_f32_e32 v101, v101
	v_rcp_f32_e32 v104, v104
	v_rcp_f32_e32 v105, v105
	v_rcp_f32_e32 v106, v106
	v_rcp_f32_e32 v107, v107
	v_rcp_f32_e32 v108, v108
	v_rcp_f32_e32 v109, v109
	v_pk_mul_f32 v[84:85], v[84:85], v[100:101]
	v_pk_mul_f32 v[86:87], v[86:87], v[104:105]
	v_pk_mul_f32 v[88:89], v[88:89], v[106:107]
	v_pk_mul_f32 v[90:91], v[90:91], v[108:109]
	v_cvt_pk_bf16_f32 v80, v84, v85
	v_cvt_pk_bf16_f32 v81, v86, v87
	v_cvt_pk_bf16_f32 v82, v88, v89
	v_cvt_pk_bf16_f32 v83, v90, v91
	global_store_dwordx4 v[96:97], v[80:83], off
	s_nop 0
	s_waitcnt vmcnt(7)
	v_cvt_f32_u32_e32 v80, v189
	v_cvt_f32_u32_e32 v81, v188
	v_mad_i64_i32 v[82:83], s[14:15], v98, s65, v[146:147]
	v_fmamk_f32 v80, v81, 0x2f800000, v80
	v_fmamk_f32 v80, v80, 0x3a800000, v158
	v_rsq_f32_e32 v80, v80
	v_lshl_add_u64 v[82:83], v[82:83], 0, v[148:149]
	v_mul_f32_e32 v188, 0xbfb8aa3b, v80
	v_mul_f32_e32 v189, v80, v80
	v_pk_mul_f32 v[80:81], v[76:77], v[188:189] op_sel_hi:[1,0]
	v_pk_mul_f32 v[84:85], v[78:79], v[188:189] op_sel_hi:[1,0]
	v_pk_mul_f32 v[86:87], v[72:73], v[188:189] op_sel_hi:[1,0]
	v_pk_mul_f32 v[88:89], v[74:75], v[188:189] op_sel_hi:[1,0]
	v_pk_mul_f32 v[68:69], v[68:69], v[76:77]
	v_pk_mul_f32 v[70:71], v[70:71], v[78:79]
	v_pk_mul_f32 v[72:73], v[64:65], v[72:73]
	v_pk_mul_f32 v[74:75], v[66:67], v[74:75]
	v_exp_f32_e32 v80, v80
	v_exp_f32_e32 v81, v81
	v_exp_f32_e32 v84, v84
	v_exp_f32_e32 v85, v85
	v_exp_f32_e32 v86, v86
	v_exp_f32_e32 v87, v87
	v_exp_f32_e32 v88, v88
	v_exp_f32_e32 v89, v89
	v_pk_mul_f32 v[68:69], v[68:69], v[188:189] op_sel:[0,1] op_sel_hi:[1,1]
	v_pk_mul_f32 v[70:71], v[70:71], v[188:189] op_sel:[0,1] op_sel_hi:[1,1]
	v_pk_mul_f32 v[72:73], v[72:73], v[188:189] op_sel:[0,1] op_sel_hi:[1,1]
	v_pk_mul_f32 v[74:75], v[74:75], v[188:189] op_sel:[0,1] op_sel_hi:[1,1]
	v_pk_add_f32 v[80:81], v[80:81], 1.0 op_sel_hi:[1,0]
	v_pk_add_f32 v[84:85], v[84:85], 1.0 op_sel_hi:[1,0]
	v_pk_add_f32 v[86:87], v[86:87], 1.0 op_sel_hi:[1,0]
	v_pk_add_f32 v[88:89], v[88:89], 1.0 op_sel_hi:[1,0]
	v_rcp_f32_e32 v80, v80
	v_rcp_f32_e32 v81, v81
	v_rcp_f32_e32 v84, v84
	v_rcp_f32_e32 v85, v85
	v_rcp_f32_e32 v86, v86
	v_rcp_f32_e32 v87, v87
	v_rcp_f32_e32 v88, v88
	v_rcp_f32_e32 v89, v89
	v_pk_mul_f32 v[68:69], v[68:69], v[80:81]
	v_pk_mul_f32 v[70:71], v[70:71], v[84:85]
	v_pk_mul_f32 v[72:73], v[72:73], v[86:87]
	v_pk_mul_f32 v[74:75], v[74:75], v[88:89]
	v_cvt_pk_bf16_f32 v64, v68, v69
	v_cvt_pk_bf16_f32 v65, v70, v71
	v_cvt_pk_bf16_f32 v66, v72, v73
	v_cvt_pk_bf16_f32 v67, v74, v75
	global_store_dwordx4 v[82:83], v[64:67], off
	s_nop 0
	s_waitcnt vmcnt(7)
; __device__ __forceinline__ unsigned cvtpk(float lo, float hi) { f32x2v_ v = {lo, hi}; bf16x2v_ b = __builtin_convertvector(v, bf16x2v_); return __builtin_bit_cast(unsigned, b); }
;     __device__ __forceinline__ void operator()(const f32x4 (&acc)[2][2][4][2], const Unit& u, int wr, int wc, int fr, int fq) const {
;     ...
;             for (int m = 0; m < 4; ++m) { const int row = row0 + ai * HALF + m * 16; const float rs = row_rs(ss, row);
;                 float hv[8];
; #pragma unroll
;                 for (int n = 0; n < 2; ++n)
; #pragma unroll
;                     for (int i = 0; i < 4; ++i) { const float g = acc[ai][0][m][n][i] * rs, uu = acc[ai][1][m][n][i] * rs;
;                         hv[n * 4 + i] = g * __builtin_amdgcn_rcpf(1.0f + __expf(-g)) * uu; }
;                 u32x4 w; w.x = cvtpk(hv[0], hv[1]); w.y = cvtpk(hv[2], hv[3]); w.z = cvtpk(hv[4], hv[5]); w.w = cvtpk(hv[6], hv[7]);
;                 *(u32x4*)(H + (size_t)row * ldh + col0) = w; }
	v_cvt_f32_u32_e32 v64, v191
	v_cvt_f32_u32_e32 v66, v190
	v_add_u32_e32 v65, 0x80, v144
	v_fmamk_f32 v64, v66, 0x2f800000, v64
	v_fmamk_f32 v64, v64, 0x3a800000, v158
	v_rsq_f32_e32 v64, v64
	v_mad_i64_i32 v[66:67], s[14:15], v65, s65, v[146:147]
	v_lshl_add_u64 v[66:67], v[66:67], 0, v[148:149]
	v_mul_f32_e32 v190, 0xbfb8aa3b, v64
	v_mul_f32_e32 v191, v64, v64
	v_pk_mul_f32 v[64:65], v[60:61], v[190:191] op_sel_hi:[1,0]
	v_pk_mul_f32 v[68:69], v[62:63], v[190:191] op_sel_hi:[1,0]
	v_pk_mul_f32 v[70:71], v[56:57], v[190:191] op_sel_hi:[1,0]
	v_pk_mul_f32 v[72:73], v[58:59], v[190:191] op_sel_hi:[1,0]
	v_pk_mul_f32 v[52:53], v[52:53], v[60:61]
	v_pk_mul_f32 v[54:55], v[54:55], v[62:63]
	v_pk_mul_f32 v[56:57], v[48:49], v[56:57]
	v_pk_mul_f32 v[58:59], v[50:51], v[58:59]
	v_exp_f32_e32 v64, v64
	v_exp_f32_e32 v65, v65
	v_exp_f32_e32 v68, v68
	v_exp_f32_e32 v69, v69
	v_exp_f32_e32 v70, v70
	v_exp_f32_e32 v71, v71
	v_exp_f32_e32 v72, v72
	v_exp_f32_e32 v73, v73
	v_pk_mul_f32 v[52:53], v[52:53], v[190:191] op_sel:[0,1] op_sel_hi:[1,1]
	v_pk_mul_f32 v[54:55], v[54:55], v[190:191] op_sel:[0,1] op_sel_hi:[1,1]
	v_pk_mul_f32 v[56:57], v[56:57], v[190:191] op_sel:[0,1] op_sel_hi:[1,1]
	v_pk_mul_f32 v[58:59], v[58:59], v[190:191] op_sel:[0,1] op_sel_hi:[1,1]
	v_pk_add_f32 v[64:65], v[64:65], 1.0 op_sel_hi:[1,0]
	v_pk_add_f32 v[68:69], v[68:69], 1.0 op_sel_hi:[1,0]
	v_pk_add_f32 v[70:71], v[70:71], 1.0 op_sel_hi:[1,0]
	v_pk_add_f32 v[72:73], v[72:73], 1.0 op_sel_hi:[1,0]
	v_rcp_f32_e32 v64, v64
	v_rcp_f32_e32 v65, v65
	v_rcp_f32_e32 v68, v68
	v_rcp_f32_e32 v69, v69
	v_rcp_f32_e32 v70, v70
	v_rcp_f32_e32 v71, v71
	v_rcp_f32_e32 v72, v72
	v_rcp_f32_e32 v73, v73
	v_pk_mul_f32 v[52:53], v[52:53], v[64:65]
	v_pk_mul_f32 v[54:55], v[54:55], v[68:69]
	v_pk_mul_f32 v[56:57], v[56:57], v[70:71]
	v_pk_mul_f32 v[58:59], v[58:59], v[72:73]
	v_cvt_pk_bf16_f32 v48, v52, v53
	v_cvt_pk_bf16_f32 v49, v54, v55
	v_cvt_pk_bf16_f32 v50, v56, v57
	v_cvt_pk_bf16_f32 v51, v58, v59
	global_store_dwordx4 v[66:67], v[48:51], off
	s_nop 0
	s_waitcnt vmcnt(7)
	v_cvt_f32_u32_e32 v48, v193
	v_cvt_f32_u32_e32 v50, v192
	v_add_u32_e32 v49, 0x90, v144
	v_fmamk_f32 v48, v50, 0x2f800000, v48
	v_fmamk_f32 v48, v48, 0x3a800000, v158
	v_rsq_f32_e32 v48, v48
	v_mad_i64_i32 v[50:51], s[14:15], v49, s65, v[146:147]
	v_lshl_add_u64 v[50:51], v[50:51], 0, v[148:149]
	v_mul_f32_e32 v192, 0xbfb8aa3b, v48
	v_mul_f32_e32 v193, v48, v48
	v_pk_mul_f32 v[48:49], v[44:45], v[192:193] op_sel_hi:[1,0]
	v_pk_mul_f32 v[52:53], v[46:47], v[192:193] op_sel_hi:[1,0]
	v_pk_mul_f32 v[54:55], v[40:41], v[192:193] op_sel_hi:[1,0]
	v_pk_mul_f32 v[56:57], v[42:43], v[192:193] op_sel_hi:[1,0]
	v_pk_mul_f32 v[36:37], v[36:37], v[44:45]
	v_pk_mul_f32 v[38:39], v[38:39], v[46:47]
	v_pk_mul_f32 v[40:41], v[32:33], v[40:41]
	v_pk_mul_f32 v[42:43], v[34:35], v[42:43]
	v_exp_f32_e32 v48, v48
	v_exp_f32_e32 v49, v49
	v_exp_f32_e32 v52, v52
	v_exp_f32_e32 v53, v53
	v_exp_f32_e32 v54, v54
	v_exp_f32_e32 v55, v55
	v_exp_f32_e32 v56, v56
	v_exp_f32_e32 v57, v57
	v_pk_mul_f32 v[36:37], v[36:37], v[192:193] op_sel:[0,1] op_sel_hi:[1,1]
	v_pk_mul_f32 v[38:39], v[38:39], v[192:193] op_sel:[0,1] op_sel_hi:[1,1]
	v_pk_mul_f32 v[40:41], v[40:41], v[192:193] op_sel:[0,1] op_sel_hi:[1,1]
	v_pk_mul_f32 v[42:43], v[42:43], v[192:193] op_sel:[0,1] op_sel_hi:[1,1]
	v_pk_add_f32 v[48:49], v[48:49], 1.0 op_sel_hi:[1,0]
	v_pk_add_f32 v[52:53], v[52:53], 1.0 op_sel_hi:[1,0]
	v_pk_add_f32 v[54:55], v[54:55], 1.0 op_sel_hi:[1,0]
	v_pk_add_f32 v[56:57], v[56:57], 1.0 op_sel_hi:[1,0]
	v_rcp_f32_e32 v48, v48
	v_rcp_f32_e32 v49, v49
	v_rcp_f32_e32 v52, v52
	v_rcp_f32_e32 v53, v53
	v_rcp_f32_e32 v54, v54
	v_rcp_f32_e32 v55, v55
	v_rcp_f32_e32 v56, v56
	v_rcp_f32_e32 v57, v57
	v_pk_mul_f32 v[36:37], v[36:37], v[48:49]
	v_pk_mul_f32 v[38:39], v[38:39], v[52:53]
	v_pk_mul_f32 v[40:41], v[40:41], v[54:55]
	v_pk_mul_f32 v[42:43], v[42:43], v[56:57]
	v_cvt_pk_bf16_f32 v32, v36, v37
	v_cvt_pk_bf16_f32 v33, v38, v39
	v_cvt_pk_bf16_f32 v34, v40, v41
	v_cvt_pk_bf16_f32 v35, v42, v43
	global_store_dwordx4 v[50:51], v[32:35], off
	s_nop 0
	s_waitcnt vmcnt(7)
; __device__ __forceinline__ unsigned cvtpk(float lo, float hi) { f32x2v_ v = {lo, hi}; bf16x2v_ b = __builtin_convertvector(v, bf16x2v_); return __builtin_bit_cast(unsigned, b); }
; #define PG8_BAR __builtin_amdgcn_s_barrier()
;     __device__ __forceinline__ void operator()(const f32x4 (&acc)[2][2][4][2], const Unit& u, int wr, int wc, int fr, int fq) const {
;     ...
;             for (int m = 0; m < 4; ++m) { const int row = row0 + ai * HALF + m * 16; const float rs = row_rs(ss, row);
;                 float hv[8];
; #pragma unroll
;                 for (int n = 0; n < 2; ++n)
; #pragma unroll
;                     for (int i = 0; i < 4; ++i) { const float g = acc[ai][0][m][n][i] * rs, uu = acc[ai][1][m][n][i] * rs;
;                         hv[n * 4 + i] = g * __builtin_amdgcn_rcpf(1.0f + __expf(-g)) * uu; }
;                 u32x4 w; w.x = cvtpk(hv[0], hv[1]); w.y = cvtpk(hv[2], hv[3]); w.z = cvtpk(hv[4], hv[5]); w.w = cvtpk(hv[6], hv[7]);
;                 *(u32x4*)(H + (size_t)row * ldh + col0) = w; }
; template <class Epi, class Sched, bool ALIGN_EPI = false, bool SP2 = false>
; __device__ __forceinline__ void gemm_phase(PG8_LAS unsigned char* lds, const Gemm g, const Sched& S, const Epi& E) {
;     ...
;         if constexpr (ALIGN_EPI) { if (wr == 0) PG8_BAR; }
;         if constexpr (!Epi::AFTER_DRAIN) { E(acc, cur, wr, wc, fr, fq); S.done(cur); }
;         if (!has_next) break;
; #pragma unroll
;         for (int a = 0; a < 2; ++a)
; #pragma unroll
;             for (int b = 0; b < 2; ++b)
; #pragma unroll
;                 for (int m = 0; m < 4; ++m)
; #pragma unroll
;                     for (int n = 0; n < 2; ++n) acc[a][b][m][n] = (f32x4){0.f, 0.f, 0.f, 0.f};
;         cur = nxt; cA = nA; cB = nB; ++ui;
;         if constexpr (ALIGN_EPI) { if (wr == 1) PG8_BAR; }
	v_cvt_f32_u32_e32 v32, v195
	v_cvt_f32_u32_e32 v34, v194
	v_add_u32_e32 v33, 0xa0, v144
	v_fmamk_f32 v32, v34, 0x2f800000, v32
	v_fmamk_f32 v32, v32, 0x3a800000, v158
	v_rsq_f32_e32 v32, v32
	v_mad_i64_i32 v[34:35], s[14:15], v33, s65, v[146:147]
	v_lshl_add_u64 v[34:35], v[34:35], 0, v[148:149]
	v_mul_f32_e32 v194, 0xbfb8aa3b, v32
	v_mul_f32_e32 v195, v32, v32
	v_pk_mul_f32 v[32:33], v[28:29], v[194:195] op_sel_hi:[1,0]
	v_pk_mul_f32 v[36:37], v[30:31], v[194:195] op_sel_hi:[1,0]
	v_pk_mul_f32 v[38:39], v[24:25], v[194:195] op_sel_hi:[1,0]
	v_pk_mul_f32 v[40:41], v[26:27], v[194:195] op_sel_hi:[1,0]
	v_pk_mul_f32 v[20:21], v[20:21], v[28:29]
	v_pk_mul_f32 v[22:23], v[22:23], v[30:31]
	v_pk_mul_f32 v[24:25], v[16:17], v[24:25]
	v_pk_mul_f32 v[26:27], v[18:19], v[26:27]
	v_exp_f32_e32 v32, v32
	v_exp_f32_e32 v33, v33
	v_exp_f32_e32 v36, v36
	v_exp_f32_e32 v37, v37
	v_exp_f32_e32 v38, v38
	v_exp_f32_e32 v39, v39
	v_exp_f32_e32 v40, v40
	v_exp_f32_e32 v41, v41
	v_pk_mul_f32 v[20:21], v[20:21], v[194:195] op_sel:[0,1] op_sel_hi:[1,1]
	v_pk_mul_f32 v[22:23], v[22:23], v[194:195] op_sel:[0,1] op_sel_hi:[1,1]
	v_pk_mul_f32 v[24:25], v[24:25], v[194:195] op_sel:[0,1] op_sel_hi:[1,1]
	v_pk_mul_f32 v[26:27], v[26:27], v[194:195] op_sel:[0,1] op_sel_hi:[1,1]
	v_pk_add_f32 v[32:33], v[32:33], 1.0 op_sel_hi:[1,0]
	v_pk_add_f32 v[36:37], v[36:37], 1.0 op_sel_hi:[1,0]
	v_pk_add_f32 v[38:39], v[38:39], 1.0 op_sel_hi:[1,0]
	v_pk_add_f32 v[40:41], v[40:41], 1.0 op_sel_hi:[1,0]
	v_rcp_f32_e32 v32, v32
	v_rcp_f32_e32 v33, v33
	v_rcp_f32_e32 v36, v36
	v_rcp_f32_e32 v37, v37
	v_rcp_f32_e32 v38, v38
	v_rcp_f32_e32 v39, v39
	v_rcp_f32_e32 v40, v40
	v_rcp_f32_e32 v41, v41
	v_pk_mul_f32 v[20:21], v[20:21], v[32:33]
	v_pk_mul_f32 v[22:23], v[22:23], v[36:37]
	v_pk_mul_f32 v[24:25], v[24:25], v[38:39]
	v_pk_mul_f32 v[26:27], v[26:27], v[40:41]
	v_cvt_pk_bf16_f32 v16, v20, v21
	v_cvt_pk_bf16_f32 v17, v22, v23
	v_cvt_pk_bf16_f32 v18, v24, v25
	v_cvt_pk_bf16_f32 v19, v26, v27
	global_store_dwordx4 v[34:35], v[16:19], off
	s_nop 0
	s_waitcnt vmcnt(7)
	v_cvt_f32_u32_e32 v16, v197
	v_cvt_f32_u32_e32 v18, v196
	v_add_u32_e32 v17, 0xb0, v144
	v_fmamk_f32 v16, v18, 0x2f800000, v16
	v_fmamk_f32 v16, v16, 0x3a800000, v158
	v_rsq_f32_e32 v16, v16
	v_mad_i64_i32 v[18:19], s[14:15], v17, s65, v[146:147]
	v_lshl_add_u64 v[18:19], v[18:19], 0, v[148:149]
	v_mul_f32_e32 v196, 0xbfb8aa3b, v16
	v_mul_f32_e32 v197, v16, v16
	v_pk_mul_f32 v[16:17], v[12:13], v[196:197] op_sel_hi:[1,0]
	v_pk_mul_f32 v[20:21], v[14:15], v[196:197] op_sel_hi:[1,0]
	v_pk_mul_f32 v[22:23], v[8:9], v[196:197] op_sel_hi:[1,0]
	v_pk_mul_f32 v[24:25], v[10:11], v[196:197] op_sel_hi:[1,0]
	v_pk_mul_f32 v[4:5], v[4:5], v[12:13]
	v_pk_mul_f32 v[6:7], v[6:7], v[14:15]
	v_pk_mul_f32 v[8:9], v[0:1], v[8:9]
	v_pk_mul_f32 v[10:11], v[2:3], v[10:11]
	v_exp_f32_e32 v16, v16
	v_exp_f32_e32 v17, v17
	v_exp_f32_e32 v20, v20
	v_exp_f32_e32 v21, v21
	v_exp_f32_e32 v22, v22
	v_exp_f32_e32 v23, v23
	v_exp_f32_e32 v24, v24
	v_exp_f32_e32 v25, v25
	v_pk_mul_f32 v[4:5], v[4:5], v[196:197] op_sel:[0,1] op_sel_hi:[1,1]
	v_pk_mul_f32 v[6:7], v[6:7], v[196:197] op_sel:[0,1] op_sel_hi:[1,1]
	v_pk_mul_f32 v[8:9], v[8:9], v[196:197] op_sel:[0,1] op_sel_hi:[1,1]
	v_pk_mul_f32 v[10:11], v[10:11], v[196:197] op_sel:[0,1] op_sel_hi:[1,1]
	v_pk_add_f32 v[16:17], v[16:17], 1.0 op_sel_hi:[1,0]
	v_pk_add_f32 v[20:21], v[20:21], 1.0 op_sel_hi:[1,0]
	v_pk_add_f32 v[22:23], v[22:23], 1.0 op_sel_hi:[1,0]
	v_pk_add_f32 v[24:25], v[24:25], 1.0 op_sel_hi:[1,0]
	v_rcp_f32_e32 v16, v16
	v_rcp_f32_e32 v17, v17
	v_rcp_f32_e32 v20, v20
	v_rcp_f32_e32 v21, v21
	v_rcp_f32_e32 v22, v22
	v_rcp_f32_e32 v23, v23
	v_rcp_f32_e32 v24, v24
	v_rcp_f32_e32 v25, v25
	v_pk_mul_f32 v[4:5], v[4:5], v[16:17]
	v_pk_mul_f32 v[6:7], v[6:7], v[20:21]
	v_pk_mul_f32 v[8:9], v[8:9], v[22:23]
	v_pk_mul_f32 v[10:11], v[10:11], v[24:25]
	v_cvt_pk_bf16_f32 v0, v4, v5
	v_cvt_pk_bf16_f32 v1, v6, v7
	v_cvt_pk_bf16_f32 v2, v8, v9
	v_cvt_pk_bf16_f32 v3, v10, v11
	global_store_dwordx4 v[18:19], v[0:3], off
	s_cmp_eq_u64 s[16:17], 0
	s_cbranch_scc1 .Lxpost_0
	s_barrier
.Lxpost_0:
	s_cbranch_vccnz .LBB0_187
	s_andn2_b64 vcc, exec, s[8:9]
	s_cbranch_vccnz .LBB0_186
	s_barrier
	s_branch .LBB0_186

; #define PG8_STAGE(bufoff, gbase, voff) do { _Pragma("unroll") for (int _i = 0; _i < 2; ++_i) \
;         __builtin_amdgcn_global_load_lds((const unsigned*)((const char*)(gbase) + (voff)[_i]), (PG8_LAS unsigned*)(lds + (bufoff) + ldsw + _i * 8192), 16, 0, 0); } while (0)
; #define PG8_LDA(dst, b, h) do { _Pragma("unroll") for (int m = 0; m < 4; ++m) _Pragma("unroll") for (int k = 0; k < 2; ++k) dst[m][k] = *(const PG8_LAS bf16x8*)(lds + PG8_SA(b, h) + aoff + m * 2048 + k * 1024); } while (0)
; #define PG8_LDB(dst, b, h) do { _Pragma("unroll") for (int n = 0; n < 2; ++n) _Pragma("unroll") for (int k = 0; k < 2; ++k) dst[n][k] = *(const PG8_LAS bf16x8*)(lds + PG8_SB(b, h) + boff + n * 2048 + k * 1024); } while (0)
; #define PG8_WAIT_V(n) asm volatile("s_waitcnt vmcnt(" #n ")" ::: "memory")
; #define PG8_WAIT_L(n) asm volatile("s_waitcnt lgkmcnt(" #n ")" ::: "memory")
; #define PG8_BAR __builtin_amdgcn_s_barrier()
; #define PG8_SCHED __builtin_amdgcn_sched_barrier(0)
; template <class Epi, class Sched, bool ALIGN_EPI = false, bool SP2 = false>
; __device__ __forceinline__ void gemm_phase(PG8_LAS unsigned char* lds, const Gemm g, const Sched& S, const Epi& E) {
;     ...
;         const bool has_next = S.next(ui + 1, nxt);
;         const char* nA = has_next ? (const char*)g.A + (size_t)nxt.pm * tstep : cA; const char* nB = has_next ? (const char*)g.Bt + (size_t)nxt.pn * tstep : cB;
;         for (int t = 0; t < nt; t += 2) {
;             const bool last = (t == nt - 2);
;             const char* a1 = cA + (size_t)(t + 1) * kstep;
;             const char* a2 = last ? nA : cA + (size_t)(t + 2) * kstep; const char* b2 = last ? nB : cB + (size_t)(t + 2) * kstep;
;             const char* a3 = a2 + kstep; const char* b3 = b2 + kstep;
;             if (last && has_next) S.a_ready(nxt);
;             if constexpr (SP2) {
;             PG8_LDB(B0, 0, 0); PG8_LDB(B1, 0, 1); PG8_SCHED; PG8_LDA(At, 0, 0); PG8_STAGE(PG8_SA(1, 1), a1 + hstep, voffA);
;             PG8_WAIT_V(8); PG8_WAIT_L(0); PG8_BAR; PG8_MMA(0, 0, At, B0); PG8_MMA(0, 1, At, B1); PG8_BAR; PG8_SCHED;
;             PG8_LDA(At, 0, 1); PG8_STAGE(PG8_SB(0, 0), b2, voffB); PG8_STAGE(PG8_SB(0, 1), b2 + hstep, voffB); PG8_STAGE(PG8_SA(0, 0), a2, voffA);
;             PG8_WAIT_V(8); PG8_WAIT_L(0); PG8_BAR; PG8_MMA(1, 0, At, B0); PG8_MMA(1, 1, At, B1); PG8_BAR; PG8_SCHED;
.LBB0_458:
	s_ashr_i32 s49, s48, 31
	s_lshl_b64 s[14:15], s[48:49], 19
	s_add_u32 s50, s34, s14
	s_addc_u32 s51, s43, s15
	s_and_b64 s[14:15], s[40:41], exec
	s_cselect_b32 s49, s51, s59
	s_cselect_b32 s55, s50, s58
	s_ashr_i32 s45, s44, 31
	s_lshl_b64 s[14:15], s[44:45], 19
	v_readlane_b32 s3, v250, 13
	s_add_u32 s52, s3, s14
	v_readlane_b32 s3, v250, 14
	s_addc_u32 s53, s3, s15
	s_and_b64 s[14:15], s[40:41], exec
	s_cselect_b32 s45, s53, s61
	s_cselect_b32 s57, s52, s60
	s_add_u32 s58, s58, 0x40080
	s_addc_u32 s59, s59, 0
	s_add_u32 s96, s60, 0x100
	s_addc_u32 s97, s61, 0
	s_mov_b32 vcc_lo, -2
	ds_read_b128 v[170:173], v165
	ds_read_b128 v[174:177], v165 offset:1024
	ds_read_b128 v[182:185], v165 offset:2048
	ds_read_b128 v[186:189], v165 offset:3072
	ds_read_b128 v[190:193], v168
	ds_read_b128 v[194:197], v168 offset:1024
	ds_read_b128 v[198:201], v168 offset:2048
	ds_read_b128 v[208:211], v168 offset:3072
	s_add_u32 s3, s58, 0xfffc0080
	s_addc_u32 s14, s59, -1
	s_cmp_eq_u32 vcc_lo, 12
	s_cselect_b32 s63, s49, s14
	s_cselect_b32 s62, s55, s3
	s_cselect_b32 s61, s45, s97
	s_cselect_b32 s60, s57, s96
	v_lshl_add_u64 v[178:179], s[58:59], 0, v[160:161]
	s_add_i32 m0, s85, 0xc000
	ds_read_b128 v[212:215], v164
	ds_read_b128 v[216:219], v164 offset:1024
	ds_read_b128 v[220:223], v164 offset:2048
	ds_read_b128 v[224:227], v164 offset:3072
	ds_read_b128 v[228:231], v164 offset:4096
	ds_read_b128 v[232:235], v164 offset:5120
	ds_read_b128 v[236:239], v164 offset:6144
	ds_read_b128 v[240:243], v164 offset:7168
	global_load_lds_dwordx4 v[178:179], off
	v_lshl_add_u64 v[178:179], s[58:59], 0, v[162:163]
	s_add_i32 m0, s85, 0xe000
	s_nop 0
	global_load_lds_dwordx4 v[178:179], off
	s_waitcnt vmcnt(8)
	s_waitcnt lgkmcnt(0)
	s_barrier
	s_setprio 1
	s_waitcnt lgkmcnt(0)
	v_mfma_f32_16x16x32_bf16 v[124:127], v[170:173], v[212:215], 0
	v_mfma_f32_16x16x32_bf16 v[120:123], v[182:185], v[212:215], 0
	v_mfma_f32_16x16x32_bf16 v[116:119], v[170:173], v[220:223], 0
	v_mfma_f32_16x16x32_bf16 v[112:115], v[182:185], v[220:223], 0
	v_mfma_f32_16x16x32_bf16 v[108:111], v[170:173], v[228:231], 0
	v_mfma_f32_16x16x32_bf16 v[104:107], v[182:185], v[228:231], 0
	v_mfma_f32_16x16x32_bf16 v[100:103], v[170:173], v[236:239], 0
	v_mfma_f32_16x16x32_bf16 v[96:99], v[182:185], v[236:239], 0
	v_mfma_f32_16x16x32_bf16 v[124:127], v[174:177], v[216:219], v[124:127]
	v_mfma_f32_16x16x32_bf16 v[120:123], v[186:189], v[216:219], v[120:123]
	v_mfma_f32_16x16x32_bf16 v[116:119], v[174:177], v[224:227], v[116:119]
	v_mfma_f32_16x16x32_bf16 v[112:115], v[186:189], v[224:227], v[112:115]
	v_mfma_f32_16x16x32_bf16 v[108:111], v[174:177], v[232:235], v[108:111]
	v_mfma_f32_16x16x32_bf16 v[104:107], v[186:189], v[232:235], v[104:107]
	v_mfma_f32_16x16x32_bf16 v[100:103], v[174:177], v[240:243], v[100:103]
	v_mfma_f32_16x16x32_bf16 v[96:99], v[186:189], v[240:243], v[96:99]
	s_setprio 0
	s_setprio 1
	v_mfma_f32_16x16x32_bf16 v[60:63], v[190:193], v[212:215], 0
	v_mfma_f32_16x16x32_bf16 v[56:59], v[198:201], v[212:215], 0
	v_mfma_f32_16x16x32_bf16 v[52:55], v[190:193], v[220:223], 0
	v_mfma_f32_16x16x32_bf16 v[48:51], v[198:201], v[220:223], 0
	v_mfma_f32_16x16x32_bf16 v[44:47], v[190:193], v[228:231], 0
	v_mfma_f32_16x16x32_bf16 v[40:43], v[198:201], v[228:231], 0
	v_mfma_f32_16x16x32_bf16 v[36:39], v[190:193], v[236:239], 0
	v_mfma_f32_16x16x32_bf16 v[32:35], v[198:201], v[236:239], 0
	v_mfma_f32_16x16x32_bf16 v[60:63], v[194:197], v[216:219], v[60:63]
	v_mfma_f32_16x16x32_bf16 v[56:59], v[208:211], v[216:219], v[56:59]
	v_mfma_f32_16x16x32_bf16 v[52:55], v[194:197], v[224:227], v[52:55]
	v_mfma_f32_16x16x32_bf16 v[48:51], v[208:211], v[224:227], v[48:51]
	v_mfma_f32_16x16x32_bf16 v[44:47], v[194:197], v[232:235], v[44:47]
	v_mfma_f32_16x16x32_bf16 v[40:43], v[208:211], v[232:235], v[40:43]
	v_mfma_f32_16x16x32_bf16 v[36:39], v[194:197], v[240:243], v[36:39]
	v_mfma_f32_16x16x32_bf16 v[32:35], v[208:211], v[240:243], v[32:35]
	s_setprio 0
	s_barrier
	s_add_i32 s3, s94, s84
	v_lshl_add_u64 v[178:179], s[60:61], 0, v[130:131]
	s_mov_b32 m0, s3
	ds_read_b128 v[212:215], v164 offset:16384
	ds_read_b128 v[216:219], v164 offset:17408
	ds_read_b128 v[220:223], v164 offset:18432
	ds_read_b128 v[224:227], v164 offset:19456
	ds_read_b128 v[228:231], v164 offset:20480
	ds_read_b128 v[232:235], v164 offset:21504
	ds_read_b128 v[236:239], v164 offset:22528
	ds_read_b128 v[240:243], v164 offset:23552
	global_load_lds_dwordx4 v[178:179], off
	s_add_i32 m0, s3, 0x2000
	s_add_u32 s14, s60, 0x40000
	v_lshl_add_u64 v[202:203], s[60:61], 0, v[134:135]
	s_addc_u32 s15, s61, 0
	s_add_i32 s3, s95, s84
	global_load_lds_dwordx4 v[202:203], off
	v_lshl_add_u64 v[244:245], s[14:15], 0, v[130:131]
	s_mov_b32 m0, s3
	global_load_lds_dwordx4 v[244:245], off
	v_lshl_add_u64 v[244:245], s[14:15], 0, v[134:135]
	s_add_i32 m0, s3, 0x2000
	s_nop 0
	global_load_lds_dwordx4 v[244:245], off
	s_waitcnt vmcnt(6)
	s_waitcnt lgkmcnt(0)
	s_barrier
; #define PG8_STAGE(bufoff, gbase, voff) do { _Pragma("unroll") for (int _i = 0; _i < 2; ++_i) \
;         __builtin_amdgcn_global_load_lds((const unsigned*)((const char*)(gbase) + (voff)[_i]), (PG8_LAS unsigned*)(lds + (bufoff) + ldsw + _i * 8192), 16, 0, 0); } while (0)
; #define PG8_LDA(dst, b, h) do { _Pragma("unroll") for (int m = 0; m < 4; ++m) _Pragma("unroll") for (int k = 0; k < 2; ++k) dst[m][k] = *(const PG8_LAS bf16x8*)(lds + PG8_SA(b, h) + aoff + m * 2048 + k * 1024); } while (0)
; #define PG8_LDB(dst, b, h) do { _Pragma("unroll") for (int n = 0; n < 2; ++n) _Pragma("unroll") for (int k = 0; k < 2; ++k) dst[n][k] = *(const PG8_LAS bf16x8*)(lds + PG8_SB(b, h) + boff + n * 2048 + k * 1024); } while (0)
; #define PG8_MMA(ai, bj, At, Bt) do { __builtin_amdgcn_s_setprio(1); _Pragma("unroll") for (int m = 0; m < 4; ++m) _Pragma("unroll") for (int n = 0; n < 2; ++n) _Pragma("unroll") for (int k = 0; k < 2; ++k) \
;         acc[ai][bj][m][n] = __builtin_amdgcn_mfma_f32_16x16x32_bf16(Bt[n][k], At[m][k], acc[ai][bj][m][n], 0, 0, 0); __builtin_amdgcn_s_setprio(0); } while (0)
; #define PG8_WAIT_V(n) asm volatile("s_waitcnt vmcnt(" #n ")" ::: "memory")
; #define PG8_WAIT_L(n) asm volatile("s_waitcnt lgkmcnt(" #n ")" ::: "memory")
; #define PG8_BAR __builtin_amdgcn_s_barrier()
; #define PG8_SCHED __builtin_amdgcn_sched_barrier(0)
; template <class Epi, class Sched, bool ALIGN_EPI = false, bool SP2 = false>
; __device__ __forceinline__ void gemm_phase(PG8_LAS unsigned char* lds, const Gemm g, const Sched& S, const Epi& E) {
;     ...
;             PG8_LDA(At, 0, 1); PG8_STAGE(PG8_SB(0, 0), b2, voffB); PG8_STAGE(PG8_SB(0, 1), b2 + hstep, voffB); PG8_STAGE(PG8_SA(0, 0), a2, voffA);
;             PG8_WAIT_V(8); PG8_WAIT_L(0); PG8_BAR; PG8_MMA(1, 0, At, B0); PG8_MMA(1, 1, At, B1); PG8_BAR; PG8_SCHED;
;             PG8_LDB(B0, 1, 0); PG8_LDB(B1, 1, 1); PG8_SCHED; PG8_LDA(At, 1, 0); PG8_STAGE(PG8_SA(0, 1), a2 + hstep, voffA);
;             PG8_WAIT_V(8); PG8_WAIT_L(0); PG8_BAR; PG8_MMA(0, 0, At, B0); PG8_MMA(0, 1, At, B1); PG8_BAR; PG8_SCHED;
	s_setprio 1
	s_waitcnt lgkmcnt(0)
	v_mfma_f32_16x16x32_bf16 v[92:95], v[170:173], v[212:215], 0
	v_mfma_f32_16x16x32_bf16 v[88:91], v[182:185], v[212:215], 0
	v_mfma_f32_16x16x32_bf16 v[84:87], v[170:173], v[220:223], 0
	v_mfma_f32_16x16x32_bf16 v[80:83], v[182:185], v[220:223], 0
	v_mfma_f32_16x16x32_bf16 v[76:79], v[170:173], v[228:231], 0
	v_mfma_f32_16x16x32_bf16 v[72:75], v[182:185], v[228:231], 0
	v_mfma_f32_16x16x32_bf16 v[68:71], v[170:173], v[236:239], 0
	v_mfma_f32_16x16x32_bf16 v[64:67], v[182:185], v[236:239], 0
	v_mfma_f32_16x16x32_bf16 v[92:95], v[174:177], v[216:219], v[92:95]
	v_mfma_f32_16x16x32_bf16 v[88:91], v[186:189], v[216:219], v[88:91]
	v_mfma_f32_16x16x32_bf16 v[84:87], v[174:177], v[224:227], v[84:87]
	v_mfma_f32_16x16x32_bf16 v[80:83], v[186:189], v[224:227], v[80:83]
	v_mfma_f32_16x16x32_bf16 v[76:79], v[174:177], v[232:235], v[76:79]
	v_mfma_f32_16x16x32_bf16 v[72:75], v[186:189], v[232:235], v[72:75]
	v_lshl_add_u64 v[244:245], s[62:63], 0, v[128:129]
	s_mov_b32 m0, s85
	s_nop 0
	global_load_lds_dwordx4 v[244:245], off
	v_mfma_f32_16x16x32_bf16 v[68:71], v[174:177], v[240:243], v[68:71]
	v_mfma_f32_16x16x32_bf16 v[64:67], v[186:189], v[240:243], v[64:67]
	s_setprio 0
	s_setprio 1
	v_mfma_f32_16x16x32_bf16 v[28:31], v[190:193], v[212:215], 0
	v_mfma_f32_16x16x32_bf16 v[24:27], v[198:201], v[212:215], 0
	v_mfma_f32_16x16x32_bf16 v[20:23], v[190:193], v[220:223], 0
	v_mfma_f32_16x16x32_bf16 v[16:19], v[198:201], v[220:223], 0
	v_mfma_f32_16x16x32_bf16 v[12:15], v[190:193], v[228:231], 0
	v_mfma_f32_16x16x32_bf16 v[8:11], v[198:201], v[228:231], 0
	v_mfma_f32_16x16x32_bf16 v[4:7], v[190:193], v[236:239], 0
	v_mfma_f32_16x16x32_bf16 v[0:3], v[198:201], v[236:239], 0
	v_mfma_f32_16x16x32_bf16 v[28:31], v[194:197], v[216:219], v[28:31]
	v_mfma_f32_16x16x32_bf16 v[24:27], v[208:211], v[216:219], v[24:27]
	v_mfma_f32_16x16x32_bf16 v[20:23], v[194:197], v[224:227], v[20:23]
	v_mfma_f32_16x16x32_bf16 v[16:19], v[208:211], v[224:227], v[16:19]
	v_mfma_f32_16x16x32_bf16 v[12:15], v[194:197], v[232:235], v[12:15]
	v_mfma_f32_16x16x32_bf16 v[8:11], v[208:211], v[232:235], v[8:11]
	v_lshl_add_u64 v[246:247], s[62:63], 0, v[132:133]
	s_mov_b32 m0, s86
	s_nop 0
	global_load_lds_dwordx4 v[246:247], off
	v_mfma_f32_16x16x32_bf16 v[4:7], v[194:197], v[240:243], v[4:7]
	v_mfma_f32_16x16x32_bf16 v[0:3], v[208:211], v[240:243], v[0:3]
	s_setprio 0
	s_barrier
	s_add_i32 s3, 0, 0x18000
	v_add_u32_e32 v136, s3, v141
	s_add_i32 s33, 0, 0x1c000
	ds_read_b128 v[170:173], v136
	ds_read_b128 v[174:177], v136 offset:1024
	ds_read_b128 v[182:185], v136 offset:2048
	ds_read_b128 v[186:189], v136 offset:3072
	v_add_u32_e32 v136, s33, v141
	ds_read_b128 v[190:193], v136
	ds_read_b128 v[194:197], v136 offset:1024
	ds_read_b128 v[198:201], v136 offset:2048
	ds_read_b128 v[208:211], v136 offset:3072
	s_add_u32 s14, s62, 0x40000
	s_addc_u32 s15, s63, 0
	s_mov_b32 m0, s87
	v_lshl_add_u64 v[248:249], s[14:15], 0, v[128:129]
	ds_read_b128 v[212:215], v164 offset:32768
	ds_read_b128 v[216:219], v164 offset:33792
	ds_read_b128 v[220:223], v164 offset:34816
	ds_read_b128 v[224:227], v164 offset:35840
	ds_read_b128 v[228:231], v164 offset:36864
	ds_read_b128 v[232:235], v164 offset:37888
	ds_read_b128 v[236:239], v164 offset:38912
	ds_read_b128 v[240:243], v164 offset:39936
	global_load_lds_dwordx4 v[248:249], off
	v_lshl_add_u64 v[248:249], s[14:15], 0, v[132:133]
	s_mov_b32 m0, s88
	s_nop 0
	global_load_lds_dwordx4 v[248:249], off
	s_waitcnt vmcnt(8)
	s_waitcnt lgkmcnt(0)
	s_barrier
	s_setprio 1
	s_waitcnt lgkmcnt(0)
	v_mfma_f32_16x16x32_bf16 v[124:127], v[170:173], v[212:215], v[124:127]
	v_mfma_f32_16x16x32_bf16 v[120:123], v[182:185], v[212:215], v[120:123]
	v_mfma_f32_16x16x32_bf16 v[116:119], v[170:173], v[220:223], v[116:119]
	v_mfma_f32_16x16x32_bf16 v[112:115], v[182:185], v[220:223], v[112:115]
	v_mfma_f32_16x16x32_bf16 v[108:111], v[170:173], v[228:231], v[108:111]
	v_mfma_f32_16x16x32_bf16 v[104:107], v[182:185], v[228:231], v[104:107]
	v_mfma_f32_16x16x32_bf16 v[100:103], v[170:173], v[236:239], v[100:103]
	v_mfma_f32_16x16x32_bf16 v[96:99], v[182:185], v[236:239], v[96:99]
	v_mfma_f32_16x16x32_bf16 v[124:127], v[174:177], v[216:219], v[124:127]
	v_mfma_f32_16x16x32_bf16 v[120:123], v[186:189], v[216:219], v[120:123]
	v_mfma_f32_16x16x32_bf16 v[116:119], v[174:177], v[224:227], v[116:119]
	v_mfma_f32_16x16x32_bf16 v[112:115], v[186:189], v[224:227], v[112:115]
	v_mfma_f32_16x16x32_bf16 v[108:111], v[174:177], v[232:235], v[108:111]
	v_mfma_f32_16x16x32_bf16 v[104:107], v[186:189], v[232:235], v[104:107]
	v_mfma_f32_16x16x32_bf16 v[100:103], v[174:177], v[240:243], v[100:103]
	v_mfma_f32_16x16x32_bf16 v[96:99], v[186:189], v[240:243], v[96:99]
	s_setprio 0
	s_setprio 1
	v_mfma_f32_16x16x32_bf16 v[60:63], v[190:193], v[212:215], v[60:63]
	v_mfma_f32_16x16x32_bf16 v[56:59], v[198:201], v[212:215], v[56:59]
	v_mfma_f32_16x16x32_bf16 v[52:55], v[190:193], v[220:223], v[52:55]
	v_mfma_f32_16x16x32_bf16 v[48:51], v[198:201], v[220:223], v[48:51]
	v_mfma_f32_16x16x32_bf16 v[44:47], v[190:193], v[228:231], v[44:47]
	v_mfma_f32_16x16x32_bf16 v[40:43], v[198:201], v[228:231], v[40:43]
	v_mfma_f32_16x16x32_bf16 v[36:39], v[190:193], v[236:239], v[36:39]
	v_mfma_f32_16x16x32_bf16 v[32:35], v[198:201], v[236:239], v[32:35]
	v_mfma_f32_16x16x32_bf16 v[60:63], v[194:197], v[216:219], v[60:63]
	v_mfma_f32_16x16x32_bf16 v[56:59], v[208:211], v[216:219], v[56:59]
	v_mfma_f32_16x16x32_bf16 v[52:55], v[194:197], v[224:227], v[52:55]
	v_mfma_f32_16x16x32_bf16 v[48:51], v[208:211], v[224:227], v[48:51]
	v_mfma_f32_16x16x32_bf16 v[44:47], v[194:197], v[232:235], v[44:47]
	v_mfma_f32_16x16x32_bf16 v[40:43], v[208:211], v[232:235], v[40:43]
	v_mfma_f32_16x16x32_bf16 v[36:39], v[194:197], v[240:243], v[36:39]
	v_mfma_f32_16x16x32_bf16 v[32:35], v[208:211], v[240:243], v[32:35]
	s_setprio 0
	s_barrier
; #define PG8_STAGE(bufoff, gbase, voff) do { _Pragma("unroll") for (int _i = 0; _i < 2; ++_i) \
;         __builtin_amdgcn_global_load_lds((const unsigned*)((const char*)(gbase) + (voff)[_i]), (PG8_LAS unsigned*)(lds + (bufoff) + ldsw + _i * 8192), 16, 0, 0); } while (0)
; #define PG8_LDA(dst, b, h) do { _Pragma("unroll") for (int m = 0; m < 4; ++m) _Pragma("unroll") for (int k = 0; k < 2; ++k) dst[m][k] = *(const PG8_LAS bf16x8*)(lds + PG8_SA(b, h) + aoff + m * 2048 + k * 1024); } while (0)
; #define PG8_LDB(dst, b, h) do { _Pragma("unroll") for (int n = 0; n < 2; ++n) _Pragma("unroll") for (int k = 0; k < 2; ++k) dst[n][k] = *(const PG8_LAS bf16x8*)(lds + PG8_SB(b, h) + boff + n * 2048 + k * 1024); } while (0)
; #define PG8_MMA(ai, bj, At, Bt) do { __builtin_amdgcn_s_setprio(1); _Pragma("unroll") for (int m = 0; m < 4; ++m) _Pragma("unroll") for (int n = 0; n < 2; ++n) _Pragma("unroll") for (int k = 0; k < 2; ++k) \
;         acc[ai][bj][m][n] = __builtin_amdgcn_mfma_f32_16x16x32_bf16(Bt[n][k], At[m][k], acc[ai][bj][m][n], 0, 0, 0); __builtin_amdgcn_s_setprio(0); } while (0)
; #define PG8_WAIT_V(n) asm volatile("s_waitcnt vmcnt(" #n ")" ::: "memory")
; #define PG8_WAIT_L(n) asm volatile("s_waitcnt lgkmcnt(" #n ")" ::: "memory")
; #define PG8_BAR __builtin_amdgcn_s_barrier()
; #define PG8_SCHED __builtin_amdgcn_sched_barrier(0)
; template <class Epi, class Sched, bool ALIGN_EPI = false, bool SP2 = false>
; __device__ __forceinline__ void gemm_phase(PG8_LAS unsigned char* lds, const Gemm g, const Sched& S, const Epi& E) {
;     ...
;             PG8_LDB(B0, 0, 0); PG8_LDB(B1, 0, 1); PG8_SCHED; PG8_LDA(At, 0, 0); PG8_STAGE(PG8_SA(1, 1), a1 + hstep, voffA);
;             PG8_WAIT_V(8); PG8_WAIT_L(0); PG8_BAR; PG8_MMA(0, 0, At, B0); PG8_MMA(0, 1, At, B1); PG8_BAR; PG8_SCHED;
;     ...
;             PG8_LDA(At, 1, 1); PG8_STAGE(PG8_SB(1, 0), b3, voffB); PG8_STAGE(PG8_SB(1, 1), b3 + hstep, voffB); PG8_STAGE(PG8_SA(1, 0), a3, voffA);
;             PG8_WAIT_V(8); PG8_WAIT_L(0); PG8_BAR; PG8_MMA(1, 0, At, B0); PG8_MMA(1, 1, At, B1); PG8_BAR; PG8_SCHED;
	s_add_i32 s3, s3, s84
	v_lshl_add_u64 v[178:179], v[178:179], 0, s[8:9]
	s_mov_b32 m0, s3
	ds_read_b128 v[212:215], v164 offset:49152
	ds_read_b128 v[216:219], v164 offset:50176
	ds_read_b128 v[220:223], v164 offset:51200
	ds_read_b128 v[224:227], v164 offset:52224
	ds_read_b128 v[228:231], v164 offset:53248
	ds_read_b128 v[232:235], v164 offset:54272
	ds_read_b128 v[236:239], v164 offset:55296
	ds_read_b128 v[240:243], v164 offset:56320
	global_load_lds_dwordx4 v[178:179], off
	s_add_i32 m0, s3, 0x2000
	s_add_u32 s14, s60, 0x40080
	v_lshl_add_u64 v[178:179], v[202:203], 0, s[8:9]
	s_addc_u32 s15, s61, 0
	s_add_i32 s3, s33, s84
	global_load_lds_dwordx4 v[178:179], off
	v_lshl_add_u64 v[178:179], s[14:15], 0, v[130:131]
	s_mov_b32 m0, s3
	s_nop 0
	global_load_lds_dwordx4 v[178:179], off
	v_lshl_add_u64 v[178:179], s[14:15], 0, v[134:135]
	s_add_i32 m0, s3, 0x2000
	s_nop 0
	global_load_lds_dwordx4 v[178:179], off
	s_waitcnt vmcnt(6)
	s_waitcnt lgkmcnt(0)
	s_barrier
	s_setprio 1
	s_waitcnt lgkmcnt(0)
	v_mfma_f32_16x16x32_bf16 v[92:95], v[170:173], v[212:215], v[92:95]
	v_mfma_f32_16x16x32_bf16 v[88:91], v[182:185], v[212:215], v[88:91]
	v_mfma_f32_16x16x32_bf16 v[84:87], v[170:173], v[220:223], v[84:87]
	v_mfma_f32_16x16x32_bf16 v[80:83], v[182:185], v[220:223], v[80:83]
	v_mfma_f32_16x16x32_bf16 v[76:79], v[170:173], v[228:231], v[76:79]
	v_mfma_f32_16x16x32_bf16 v[72:75], v[182:185], v[228:231], v[72:75]
	v_mfma_f32_16x16x32_bf16 v[68:71], v[170:173], v[236:239], v[68:71]
	v_mfma_f32_16x16x32_bf16 v[64:67], v[182:185], v[236:239], v[64:67]
	v_mfma_f32_16x16x32_bf16 v[92:95], v[174:177], v[216:219], v[92:95]
	v_mfma_f32_16x16x32_bf16 v[88:91], v[186:189], v[216:219], v[88:91]
	v_mfma_f32_16x16x32_bf16 v[84:87], v[174:177], v[224:227], v[84:87]
	v_mfma_f32_16x16x32_bf16 v[80:83], v[186:189], v[224:227], v[80:83]
	v_mfma_f32_16x16x32_bf16 v[76:79], v[174:177], v[232:235], v[76:79]
	v_mfma_f32_16x16x32_bf16 v[72:75], v[186:189], v[232:235], v[72:75]
	v_lshl_add_u64 v[178:179], v[244:245], 0, s[8:9]
	s_mov_b32 m0, s90
	s_nop 0
	global_load_lds_dwordx4 v[178:179], off
	v_mfma_f32_16x16x32_bf16 v[68:71], v[174:177], v[240:243], v[68:71]
	v_mfma_f32_16x16x32_bf16 v[64:67], v[186:189], v[240:243], v[64:67]
	s_setprio 0
	s_setprio 1
	v_mfma_f32_16x16x32_bf16 v[28:31], v[190:193], v[212:215], v[28:31]
	v_mfma_f32_16x16x32_bf16 v[24:27], v[198:201], v[212:215], v[24:27]
	v_mfma_f32_16x16x32_bf16 v[20:23], v[190:193], v[220:223], v[20:23]
	v_mfma_f32_16x16x32_bf16 v[16:19], v[198:201], v[220:223], v[16:19]
	v_mfma_f32_16x16x32_bf16 v[12:15], v[190:193], v[228:231], v[12:15]
	v_mfma_f32_16x16x32_bf16 v[8:11], v[198:201], v[228:231], v[8:11]
	v_mfma_f32_16x16x32_bf16 v[4:7], v[190:193], v[236:239], v[4:7]
	v_mfma_f32_16x16x32_bf16 v[0:3], v[198:201], v[236:239], v[0:3]
	v_mfma_f32_16x16x32_bf16 v[28:31], v[194:197], v[216:219], v[28:31]
	v_mfma_f32_16x16x32_bf16 v[24:27], v[208:211], v[216:219], v[24:27]
	v_mfma_f32_16x16x32_bf16 v[20:23], v[194:197], v[224:227], v[20:23]
	v_mfma_f32_16x16x32_bf16 v[16:19], v[208:211], v[224:227], v[16:19]
	v_mfma_f32_16x16x32_bf16 v[12:15], v[194:197], v[232:235], v[12:15]
	v_mfma_f32_16x16x32_bf16 v[8:11], v[208:211], v[232:235], v[8:11]
	v_lshl_add_u64 v[178:179], v[246:247], 0, s[8:9]
	s_mov_b32 m0, s91
	s_nop 0
	global_load_lds_dwordx4 v[178:179], off
	v_mfma_f32_16x16x32_bf16 v[4:7], v[194:197], v[240:243], v[4:7]
	v_mfma_f32_16x16x32_bf16 v[0:3], v[208:211], v[240:243], v[0:3]
	s_setprio 0
	s_barrier
	s_add_i32 vcc_lo, vcc_lo, 2
	s_add_u32 s58, s58, 0x100
	s_addc_u32 s59, s59, 0
	s_add_u32 s96, s96, 0x100
	s_addc_u32 s97, s97, 0
.LBB0_459:
	ds_read_b128 v[170:173], v165
	ds_read_b128 v[174:177], v165 offset:1024
	ds_read_b128 v[182:185], v165 offset:2048
	ds_read_b128 v[186:189], v165 offset:3072
	ds_read_b128 v[190:193], v168
	ds_read_b128 v[194:197], v168 offset:1024
	ds_read_b128 v[198:201], v168 offset:2048
	ds_read_b128 v[208:211], v168 offset:3072
	s_add_u32 s3, s58, 0xfffc0080
	s_addc_u32 s14, s59, -1
	s_cmp_eq_u32 vcc_lo, 12
	s_cselect_b32 s63, s49, s14
	s_cselect_b32 s62, s55, s3
	s_cselect_b32 s61, s45, s97
	s_cselect_b32 s60, s57, s96
	v_lshl_add_u64 v[178:179], s[58:59], 0, v[160:161]
	s_add_i32 m0, s85, 0xc000
	ds_read_b128 v[212:215], v164
	ds_read_b128 v[216:219], v164 offset:1024
	ds_read_b128 v[220:223], v164 offset:2048
	ds_read_b128 v[224:227], v164 offset:3072
	ds_read_b128 v[228:231], v164 offset:4096
	ds_read_b128 v[232:235], v164 offset:5120
	ds_read_b128 v[236:239], v164 offset:6144
	ds_read_b128 v[240:243], v164 offset:7168
	global_load_lds_dwordx4 v[178:179], off
	v_lshl_add_u64 v[178:179], s[58:59], 0, v[162:163]
	s_add_i32 m0, s85, 0xe000
	s_nop 0
	global_load_lds_dwordx4 v[178:179], off
	s_waitcnt vmcnt(8)
	s_waitcnt lgkmcnt(0)
	s_barrier
; #define PG8_STAGE(bufoff, gbase, voff) do { _Pragma("unroll") for (int _i = 0; _i < 2; ++_i) \
;         __builtin_amdgcn_global_load_lds((const unsigned*)((const char*)(gbase) + (voff)[_i]), (PG8_LAS unsigned*)(lds + (bufoff) + ldsw + _i * 8192), 16, 0, 0); } while (0)
; #define PG8_LDA(dst, b, h) do { _Pragma("unroll") for (int m = 0; m < 4; ++m) _Pragma("unroll") for (int k = 0; k < 2; ++k) dst[m][k] = *(const PG8_LAS bf16x8*)(lds + PG8_SA(b, h) + aoff + m * 2048 + k * 1024); } while (0)
; #define PG8_MMA(ai, bj, At, Bt) do { __builtin_amdgcn_s_setprio(1); _Pragma("unroll") for (int m = 0; m < 4; ++m) _Pragma("unroll") for (int n = 0; n < 2; ++n) _Pragma("unroll") for (int k = 0; k < 2; ++k) \
;         acc[ai][bj][m][n] = __builtin_amdgcn_mfma_f32_16x16x32_bf16(Bt[n][k], At[m][k], acc[ai][bj][m][n], 0, 0, 0); __builtin_amdgcn_s_setprio(0); } while (0)
; #define PG8_WAIT_V(n) asm volatile("s_waitcnt vmcnt(" #n ")" ::: "memory")
; #define PG8_WAIT_L(n) asm volatile("s_waitcnt lgkmcnt(" #n ")" ::: "memory")
; #define PG8_BAR __builtin_amdgcn_s_barrier()
; #define PG8_SCHED __builtin_amdgcn_sched_barrier(0)
; template <class Epi, class Sched, bool ALIGN_EPI = false, bool SP2 = false>
; __device__ __forceinline__ void gemm_phase(PG8_LAS unsigned char* lds, const Gemm g, const Sched& S, const Epi& E) {
;     ...
;             PG8_WAIT_V(8); PG8_WAIT_L(0); PG8_BAR; PG8_MMA(0, 0, At, B0); PG8_MMA(0, 1, At, B1); PG8_BAR; PG8_SCHED;
;             PG8_LDA(At, 0, 1); PG8_STAGE(PG8_SB(0, 0), b2, voffB); PG8_STAGE(PG8_SB(0, 1), b2 + hstep, voffB); PG8_STAGE(PG8_SA(0, 0), a2, voffA);
;             PG8_WAIT_V(8); PG8_WAIT_L(0); PG8_BAR; PG8_MMA(1, 0, At, B0); PG8_MMA(1, 1, At, B1); PG8_BAR; PG8_SCHED;
	s_setprio 1
	s_waitcnt lgkmcnt(0)
	v_mfma_f32_16x16x32_bf16 v[124:127], v[170:173], v[212:215], v[124:127]
	v_mfma_f32_16x16x32_bf16 v[120:123], v[182:185], v[212:215], v[120:123]
	v_mfma_f32_16x16x32_bf16 v[116:119], v[170:173], v[220:223], v[116:119]
	v_mfma_f32_16x16x32_bf16 v[112:115], v[182:185], v[220:223], v[112:115]
	v_mfma_f32_16x16x32_bf16 v[108:111], v[170:173], v[228:231], v[108:111]
	v_mfma_f32_16x16x32_bf16 v[104:107], v[182:185], v[228:231], v[104:107]
	v_mfma_f32_16x16x32_bf16 v[100:103], v[170:173], v[236:239], v[100:103]
	v_mfma_f32_16x16x32_bf16 v[96:99], v[182:185], v[236:239], v[96:99]
	v_mfma_f32_16x16x32_bf16 v[124:127], v[174:177], v[216:219], v[124:127]
	v_mfma_f32_16x16x32_bf16 v[120:123], v[186:189], v[216:219], v[120:123]
	v_mfma_f32_16x16x32_bf16 v[116:119], v[174:177], v[224:227], v[116:119]
	v_mfma_f32_16x16x32_bf16 v[112:115], v[186:189], v[224:227], v[112:115]
	v_mfma_f32_16x16x32_bf16 v[108:111], v[174:177], v[232:235], v[108:111]
	v_mfma_f32_16x16x32_bf16 v[104:107], v[186:189], v[232:235], v[104:107]
	v_mfma_f32_16x16x32_bf16 v[100:103], v[174:177], v[240:243], v[100:103]
	v_mfma_f32_16x16x32_bf16 v[96:99], v[186:189], v[240:243], v[96:99]
	s_setprio 0
	s_setprio 1
	v_mfma_f32_16x16x32_bf16 v[60:63], v[190:193], v[212:215], v[60:63]
	v_mfma_f32_16x16x32_bf16 v[56:59], v[198:201], v[212:215], v[56:59]
	v_mfma_f32_16x16x32_bf16 v[52:55], v[190:193], v[220:223], v[52:55]
	v_mfma_f32_16x16x32_bf16 v[48:51], v[198:201], v[220:223], v[48:51]
	v_mfma_f32_16x16x32_bf16 v[44:47], v[190:193], v[228:231], v[44:47]
	v_mfma_f32_16x16x32_bf16 v[40:43], v[198:201], v[228:231], v[40:43]
	v_mfma_f32_16x16x32_bf16 v[36:39], v[190:193], v[236:239], v[36:39]
	v_mfma_f32_16x16x32_bf16 v[32:35], v[198:201], v[236:239], v[32:35]
	v_mfma_f32_16x16x32_bf16 v[60:63], v[194:197], v[216:219], v[60:63]
	v_mfma_f32_16x16x32_bf16 v[56:59], v[208:211], v[216:219], v[56:59]
	v_mfma_f32_16x16x32_bf16 v[52:55], v[194:197], v[224:227], v[52:55]
	v_mfma_f32_16x16x32_bf16 v[48:51], v[208:211], v[224:227], v[48:51]
	v_mfma_f32_16x16x32_bf16 v[44:47], v[194:197], v[232:235], v[44:47]
	v_mfma_f32_16x16x32_bf16 v[40:43], v[208:211], v[232:235], v[40:43]
	v_mfma_f32_16x16x32_bf16 v[36:39], v[194:197], v[240:243], v[36:39]
	v_mfma_f32_16x16x32_bf16 v[32:35], v[208:211], v[240:243], v[32:35]
	s_setprio 0
	s_barrier
	s_add_i32 s3, s94, s84
	v_lshl_add_u64 v[178:179], s[60:61], 0, v[130:131]
	s_mov_b32 m0, s3
	ds_read_b128 v[212:215], v164 offset:16384
	ds_read_b128 v[216:219], v164 offset:17408
	ds_read_b128 v[220:223], v164 offset:18432
	ds_read_b128 v[224:227], v164 offset:19456
	ds_read_b128 v[228:231], v164 offset:20480
	ds_read_b128 v[232:235], v164 offset:21504
	ds_read_b128 v[236:239], v164 offset:22528
	ds_read_b128 v[240:243], v164 offset:23552
	global_load_lds_dwordx4 v[178:179], off
	s_add_i32 m0, s3, 0x2000
	s_add_u32 s14, s60, 0x40000
	v_lshl_add_u64 v[202:203], s[60:61], 0, v[134:135]
	s_addc_u32 s15, s61, 0
	s_add_i32 s3, s95, s84
	global_load_lds_dwordx4 v[202:203], off
	v_lshl_add_u64 v[244:245], s[14:15], 0, v[130:131]
	s_mov_b32 m0, s3
	global_load_lds_dwordx4 v[244:245], off
	v_lshl_add_u64 v[244:245], s[14:15], 0, v[134:135]
	s_add_i32 m0, s3, 0x2000
	s_nop 0
	global_load_lds_dwordx4 v[244:245], off
	s_waitcnt vmcnt(6)
	s_waitcnt lgkmcnt(0)
	s_barrier
	s_setprio 1
	s_waitcnt lgkmcnt(0)
	v_mfma_f32_16x16x32_bf16 v[92:95], v[170:173], v[212:215], v[92:95]
	v_mfma_f32_16x16x32_bf16 v[88:91], v[182:185], v[212:215], v[88:91]
	v_mfma_f32_16x16x32_bf16 v[84:87], v[170:173], v[220:223], v[84:87]
	v_mfma_f32_16x16x32_bf16 v[80:83], v[182:185], v[220:223], v[80:83]
	v_mfma_f32_16x16x32_bf16 v[76:79], v[170:173], v[228:231], v[76:79]
	v_mfma_f32_16x16x32_bf16 v[72:75], v[182:185], v[228:231], v[72:75]
	v_mfma_f32_16x16x32_bf16 v[68:71], v[170:173], v[236:239], v[68:71]
	v_mfma_f32_16x16x32_bf16 v[64:67], v[182:185], v[236:239], v[64:67]
	v_mfma_f32_16x16x32_bf16 v[92:95], v[174:177], v[216:219], v[92:95]
	v_mfma_f32_16x16x32_bf16 v[88:91], v[186:189], v[216:219], v[88:91]
	v_mfma_f32_16x16x32_bf16 v[84:87], v[174:177], v[224:227], v[84:87]
	v_mfma_f32_16x16x32_bf16 v[80:83], v[186:189], v[224:227], v[80:83]
	v_mfma_f32_16x16x32_bf16 v[76:79], v[174:177], v[232:235], v[76:79]
	v_mfma_f32_16x16x32_bf16 v[72:75], v[186:189], v[232:235], v[72:75]
	v_lshl_add_u64 v[244:245], s[62:63], 0, v[128:129]
	s_mov_b32 m0, s85
	s_nop 0
	global_load_lds_dwordx4 v[244:245], off
	v_mfma_f32_16x16x32_bf16 v[68:71], v[174:177], v[240:243], v[68:71]
	v_mfma_f32_16x16x32_bf16 v[64:67], v[186:189], v[240:243], v[64:67]
	s_setprio 0
	s_setprio 1
	v_mfma_f32_16x16x32_bf16 v[28:31], v[190:193], v[212:215], v[28:31]
	v_mfma_f32_16x16x32_bf16 v[24:27], v[198:201], v[212:215], v[24:27]
	v_mfma_f32_16x16x32_bf16 v[20:23], v[190:193], v[220:223], v[20:23]
	v_mfma_f32_16x16x32_bf16 v[16:19], v[198:201], v[220:223], v[16:19]
	v_mfma_f32_16x16x32_bf16 v[12:15], v[190:193], v[228:231], v[12:15]
	v_mfma_f32_16x16x32_bf16 v[8:11], v[198:201], v[228:231], v[8:11]
	v_mfma_f32_16x16x32_bf16 v[4:7], v[190:193], v[236:239], v[4:7]
	v_mfma_f32_16x16x32_bf16 v[0:3], v[198:201], v[236:239], v[0:3]
	v_mfma_f32_16x16x32_bf16 v[28:31], v[194:197], v[216:219], v[28:31]
	v_mfma_f32_16x16x32_bf16 v[24:27], v[208:211], v[216:219], v[24:27]
	v_mfma_f32_16x16x32_bf16 v[20:23], v[194:197], v[224:227], v[20:23]
	v_mfma_f32_16x16x32_bf16 v[16:19], v[208:211], v[224:227], v[16:19]
	v_mfma_f32_16x16x32_bf16 v[12:15], v[194:197], v[232:235], v[12:15]
	v_mfma_f32_16x16x32_bf16 v[8:11], v[208:211], v[232:235], v[8:11]
	v_lshl_add_u64 v[246:247], s[62:63], 0, v[132:133]
	s_mov_b32 m0, s86
	s_nop 0
	global_load_lds_dwordx4 v[246:247], off
	v_mfma_f32_16x16x32_bf16 v[4:7], v[194:197], v[240:243], v[4:7]
	v_mfma_f32_16x16x32_bf16 v[0:3], v[208:211], v[240:243], v[0:3]
	s_setprio 0
	s_barrier
; #define PG8_STAGE(bufoff, gbase, voff) do { _Pragma("unroll") for (int _i = 0; _i < 2; ++_i) \
;         __builtin_amdgcn_global_load_lds((const unsigned*)((const char*)(gbase) + (voff)[_i]), (PG8_LAS unsigned*)(lds + (bufoff) + ldsw + _i * 8192), 16, 0, 0); } while (0)
; #define PG8_LDA(dst, b, h) do { _Pragma("unroll") for (int m = 0; m < 4; ++m) _Pragma("unroll") for (int k = 0; k < 2; ++k) dst[m][k] = *(const PG8_LAS bf16x8*)(lds + PG8_SA(b, h) + aoff + m * 2048 + k * 1024); } while (0)
; #define PG8_LDB(dst, b, h) do { _Pragma("unroll") for (int n = 0; n < 2; ++n) _Pragma("unroll") for (int k = 0; k < 2; ++k) dst[n][k] = *(const PG8_LAS bf16x8*)(lds + PG8_SB(b, h) + boff + n * 2048 + k * 1024); } while (0)
; #define PG8_MMA(ai, bj, At, Bt) do { __builtin_amdgcn_s_setprio(1); _Pragma("unroll") for (int m = 0; m < 4; ++m) _Pragma("unroll") for (int n = 0; n < 2; ++n) _Pragma("unroll") for (int k = 0; k < 2; ++k) \
;         acc[ai][bj][m][n] = __builtin_amdgcn_mfma_f32_16x16x32_bf16(Bt[n][k], At[m][k], acc[ai][bj][m][n], 0, 0, 0); __builtin_amdgcn_s_setprio(0); } while (0)
; #define PG8_WAIT_V(n) asm volatile("s_waitcnt vmcnt(" #n ")" ::: "memory")
; #define PG8_WAIT_L(n) asm volatile("s_waitcnt lgkmcnt(" #n ")" ::: "memory")
; #define PG8_BAR __builtin_amdgcn_s_barrier()
; #define PG8_SCHED __builtin_amdgcn_sched_barrier(0)
; template <class Epi, class Sched, bool ALIGN_EPI = false, bool SP2 = false>
; __device__ __forceinline__ void gemm_phase(PG8_LAS unsigned char* lds, const Gemm g, const Sched& S, const Epi& E) {
;     ...
;             PG8_LDB(B0, 1, 0); PG8_LDB(B1, 1, 1); PG8_SCHED; PG8_LDA(At, 1, 0); PG8_STAGE(PG8_SA(0, 1), a2 + hstep, voffA);
;             PG8_WAIT_V(8); PG8_WAIT_L(0); PG8_BAR; PG8_MMA(0, 0, At, B0); PG8_MMA(0, 1, At, B1); PG8_BAR; PG8_SCHED;
;             PG8_LDA(At, 1, 1); PG8_STAGE(PG8_SB(1, 0), b3, voffB); PG8_STAGE(PG8_SB(1, 1), b3 + hstep, voffB); PG8_STAGE(PG8_SA(1, 0), a3, voffA);
	s_add_i32 s3, 0, 0x18000
	v_add_u32_e32 v136, s3, v141
	s_add_i32 s33, 0, 0x1c000
	ds_read_b128 v[170:173], v136
	ds_read_b128 v[174:177], v136 offset:1024
	ds_read_b128 v[182:185], v136 offset:2048
	ds_read_b128 v[186:189], v136 offset:3072
	v_add_u32_e32 v136, s33, v141
	ds_read_b128 v[190:193], v136
	ds_read_b128 v[194:197], v136 offset:1024
	ds_read_b128 v[198:201], v136 offset:2048
	ds_read_b128 v[208:211], v136 offset:3072
	s_add_u32 s14, s62, 0x40000
	s_addc_u32 s15, s63, 0
	s_mov_b32 m0, s87
	v_lshl_add_u64 v[248:249], s[14:15], 0, v[128:129]
	ds_read_b128 v[212:215], v164 offset:32768
	ds_read_b128 v[216:219], v164 offset:33792
	ds_read_b128 v[220:223], v164 offset:34816
	ds_read_b128 v[224:227], v164 offset:35840
	ds_read_b128 v[228:231], v164 offset:36864
	ds_read_b128 v[232:235], v164 offset:37888
	ds_read_b128 v[236:239], v164 offset:38912
	ds_read_b128 v[240:243], v164 offset:39936
	global_load_lds_dwordx4 v[248:249], off
	v_lshl_add_u64 v[248:249], s[14:15], 0, v[132:133]
	s_mov_b32 m0, s88
	s_nop 0
	global_load_lds_dwordx4 v[248:249], off
	s_waitcnt vmcnt(8)
	s_waitcnt lgkmcnt(0)
	s_barrier
	s_setprio 1
	s_waitcnt lgkmcnt(0)
	v_mfma_f32_16x16x32_bf16 v[124:127], v[170:173], v[212:215], v[124:127]
	v_mfma_f32_16x16x32_bf16 v[120:123], v[182:185], v[212:215], v[120:123]
	v_mfma_f32_16x16x32_bf16 v[116:119], v[170:173], v[220:223], v[116:119]
	v_mfma_f32_16x16x32_bf16 v[112:115], v[182:185], v[220:223], v[112:115]
	v_mfma_f32_16x16x32_bf16 v[108:111], v[170:173], v[228:231], v[108:111]
	v_mfma_f32_16x16x32_bf16 v[104:107], v[182:185], v[228:231], v[104:107]
	v_mfma_f32_16x16x32_bf16 v[100:103], v[170:173], v[236:239], v[100:103]
	v_mfma_f32_16x16x32_bf16 v[96:99], v[182:185], v[236:239], v[96:99]
	v_mfma_f32_16x16x32_bf16 v[124:127], v[174:177], v[216:219], v[124:127]
	v_mfma_f32_16x16x32_bf16 v[120:123], v[186:189], v[216:219], v[120:123]
	v_mfma_f32_16x16x32_bf16 v[116:119], v[174:177], v[224:227], v[116:119]
	v_mfma_f32_16x16x32_bf16 v[112:115], v[186:189], v[224:227], v[112:115]
	v_mfma_f32_16x16x32_bf16 v[108:111], v[174:177], v[232:235], v[108:111]
	v_mfma_f32_16x16x32_bf16 v[104:107], v[186:189], v[232:235], v[104:107]
	v_mfma_f32_16x16x32_bf16 v[100:103], v[174:177], v[240:243], v[100:103]
	v_mfma_f32_16x16x32_bf16 v[96:99], v[186:189], v[240:243], v[96:99]
	s_setprio 0
	s_setprio 1
	v_mfma_f32_16x16x32_bf16 v[60:63], v[190:193], v[212:215], v[60:63]
	v_mfma_f32_16x16x32_bf16 v[56:59], v[198:201], v[212:215], v[56:59]
	v_mfma_f32_16x16x32_bf16 v[52:55], v[190:193], v[220:223], v[52:55]
	v_mfma_f32_16x16x32_bf16 v[48:51], v[198:201], v[220:223], v[48:51]
	v_mfma_f32_16x16x32_bf16 v[44:47], v[190:193], v[228:231], v[44:47]
	v_mfma_f32_16x16x32_bf16 v[40:43], v[198:201], v[228:231], v[40:43]
	v_mfma_f32_16x16x32_bf16 v[36:39], v[190:193], v[236:239], v[36:39]
	v_mfma_f32_16x16x32_bf16 v[32:35], v[198:201], v[236:239], v[32:35]
	v_mfma_f32_16x16x32_bf16 v[60:63], v[194:197], v[216:219], v[60:63]
	v_mfma_f32_16x16x32_bf16 v[56:59], v[208:211], v[216:219], v[56:59]
	v_mfma_f32_16x16x32_bf16 v[52:55], v[194:197], v[224:227], v[52:55]
	v_mfma_f32_16x16x32_bf16 v[48:51], v[208:211], v[224:227], v[48:51]
	v_mfma_f32_16x16x32_bf16 v[44:47], v[194:197], v[232:235], v[44:47]
	v_mfma_f32_16x16x32_bf16 v[40:43], v[208:211], v[232:235], v[40:43]
	v_mfma_f32_16x16x32_bf16 v[36:39], v[194:197], v[240:243], v[36:39]
	v_mfma_f32_16x16x32_bf16 v[32:35], v[208:211], v[240:243], v[32:35]
	s_setprio 0
	s_barrier
	s_add_i32 s3, s3, s84
	v_lshl_add_u64 v[178:179], v[178:179], 0, s[8:9]
	s_mov_b32 m0, s3
	ds_read_b128 v[212:215], v164 offset:49152
	ds_read_b128 v[216:219], v164 offset:50176
	ds_read_b128 v[220:223], v164 offset:51200
	ds_read_b128 v[224:227], v164 offset:52224
	ds_read_b128 v[228:231], v164 offset:53248
	ds_read_b128 v[232:235], v164 offset:54272
	ds_read_b128 v[236:239], v164 offset:55296
	ds_read_b128 v[240:243], v164 offset:56320
	global_load_lds_dwordx4 v[178:179], off
	s_add_i32 m0, s3, 0x2000
	s_add_u32 s14, s60, 0x40080
	v_lshl_add_u64 v[178:179], v[202:203], 0, s[8:9]
	s_addc_u32 s15, s61, 0
	s_add_i32 s3, s33, s84
	global_load_lds_dwordx4 v[178:179], off
	v_lshl_add_u64 v[178:179], s[14:15], 0, v[130:131]
	s_mov_b32 m0, s3
	s_nop 0
	global_load_lds_dwordx4 v[178:179], off
	v_lshl_add_u64 v[178:179], s[14:15], 0, v[134:135]
	s_add_i32 m0, s3, 0x2000
	s_nop 0
	global_load_lds_dwordx4 v[178:179], off
	s_waitcnt vmcnt(6)
	s_waitcnt lgkmcnt(0)
	s_barrier
; __device__ __forceinline__ unsigned cvtpk(float lo, float hi) { f32x2v_ v = {lo, hi}; bf16x2v_ b = __builtin_convertvector(v, bf16x2v_); return __builtin_bit_cast(unsigned, b); }
; #define PG8_MMA(ai, bj, At, Bt) do { __builtin_amdgcn_s_setprio(1); _Pragma("unroll") for (int m = 0; m < 4; ++m) _Pragma("unroll") for (int n = 0; n < 2; ++n) _Pragma("unroll") for (int k = 0; k < 2; ++k) \
;         acc[ai][bj][m][n] = __builtin_amdgcn_mfma_f32_16x16x32_bf16(Bt[n][k], At[m][k], acc[ai][bj][m][n], 0, 0, 0); __builtin_amdgcn_s_setprio(0); } while (0)
; #define PG8_WAIT_V(n) asm volatile("s_waitcnt vmcnt(" #n ")" ::: "memory")
; #define PG8_WAIT_L(n) asm volatile("s_waitcnt lgkmcnt(" #n ")" ::: "memory")
; #define PG8_BAR __builtin_amdgcn_s_barrier()
; #define PG8_SCHED __builtin_amdgcn_sched_barrier(0)
;     __device__ __forceinline__ void operator()(const f32x4 (&acc)[2][2][4][2], const Unit& u, int wr, int wc, int fr, int fq) const {
;         const int row0 = u.pm * BM + wr * 64 + fr; const int DH = 1 << dh_shift;
; #pragma unroll
;         for (int bj = 0; bj < 2; ++bj) {
;             const int cbase = u.pn * BM + bj * HALF, c0 = cbase + wc * 32 + 8 * fq;
;             if (cbase < kbeg) {
; #pragma unroll
;                 for (int ai = 0; ai < 2; ++ai)
; #pragma unroll
;                     for (int m = 0; m < 4; ++m) { const int row = row0 + ai * HALF + m * 16; const float rs = ss ? row_rs(ss, row) : 1.0f;
;                         const f32x4 v0 = acc[ai][bj][m][0] * rs, v1 = acc[ai][bj][m][1] * rs;
;                         u32x4 w; w.x = cvtpk(v0[0], v0[1]); w.y = cvtpk(v0[2], v0[3]); w.z = cvtpk(v1[0], v1[1]); w.w = cvtpk(v1[2], v1[3]);
;                         *(u32x4*)(O + (size_t)row * ldc + c0) = w; }
;             } else if (cbase < vbeg) {
; template <class Epi, class Sched, bool ALIGN_EPI = false, bool SP2 = false>
; __device__ __forceinline__ void gemm_phase(PG8_LAS unsigned char* lds, const Gemm g, const Sched& S, const Epi& E) {
;     ...
;             PG8_WAIT_V(8); PG8_WAIT_L(0); PG8_BAR; PG8_MMA(1, 0, At, B0); PG8_MMA(1, 1, At, B1); PG8_BAR; PG8_SCHED;
	s_setprio 1
	s_waitcnt lgkmcnt(0)
	v_mfma_f32_16x16x32_bf16 v[92:95], v[170:173], v[212:215], v[92:95]
	v_mfma_f32_16x16x32_bf16 v[88:91], v[182:185], v[212:215], v[88:91]
	v_mfma_f32_16x16x32_bf16 v[84:87], v[170:173], v[220:223], v[84:87]
	v_mfma_f32_16x16x32_bf16 v[80:83], v[182:185], v[220:223], v[80:83]
	v_mfma_f32_16x16x32_bf16 v[76:79], v[170:173], v[228:231], v[76:79]
	v_mfma_f32_16x16x32_bf16 v[72:75], v[182:185], v[228:231], v[72:75]
	v_mfma_f32_16x16x32_bf16 v[68:71], v[170:173], v[236:239], v[68:71]
	v_mfma_f32_16x16x32_bf16 v[64:67], v[182:185], v[236:239], v[64:67]
	v_mfma_f32_16x16x32_bf16 v[92:95], v[174:177], v[216:219], v[92:95]
	v_mfma_f32_16x16x32_bf16 v[88:91], v[186:189], v[216:219], v[88:91]
	v_mfma_f32_16x16x32_bf16 v[84:87], v[174:177], v[224:227], v[84:87]
	v_mfma_f32_16x16x32_bf16 v[80:83], v[186:189], v[224:227], v[80:83]
	v_mfma_f32_16x16x32_bf16 v[76:79], v[174:177], v[232:235], v[76:79]
	v_mfma_f32_16x16x32_bf16 v[72:75], v[186:189], v[232:235], v[72:75]
	v_lshl_add_u64 v[178:179], v[244:245], 0, s[8:9]
	s_mov_b32 m0, s90
	s_nop 0
	global_load_lds_dwordx4 v[178:179], off
	v_mfma_f32_16x16x32_bf16 v[68:71], v[174:177], v[240:243], v[68:71]
	v_mfma_f32_16x16x32_bf16 v[64:67], v[186:189], v[240:243], v[64:67]
	s_setprio 0
	s_setprio 1
	v_mfma_f32_16x16x32_bf16 v[28:31], v[190:193], v[212:215], v[28:31]
	v_mfma_f32_16x16x32_bf16 v[24:27], v[198:201], v[212:215], v[24:27]
	v_mfma_f32_16x16x32_bf16 v[20:23], v[190:193], v[220:223], v[20:23]
	v_mfma_f32_16x16x32_bf16 v[16:19], v[198:201], v[220:223], v[16:19]
	v_mfma_f32_16x16x32_bf16 v[12:15], v[190:193], v[228:231], v[12:15]
	v_mfma_f32_16x16x32_bf16 v[8:11], v[198:201], v[228:231], v[8:11]
	v_mfma_f32_16x16x32_bf16 v[4:7], v[190:193], v[236:239], v[4:7]
	v_mfma_f32_16x16x32_bf16 v[0:3], v[198:201], v[236:239], v[0:3]
	v_mfma_f32_16x16x32_bf16 v[28:31], v[194:197], v[216:219], v[28:31]
	v_mfma_f32_16x16x32_bf16 v[24:27], v[208:211], v[216:219], v[24:27]
	v_mfma_f32_16x16x32_bf16 v[20:23], v[194:197], v[224:227], v[20:23]
	v_mfma_f32_16x16x32_bf16 v[16:19], v[208:211], v[224:227], v[16:19]
	v_mfma_f32_16x16x32_bf16 v[12:15], v[194:197], v[232:235], v[12:15]
	v_mfma_f32_16x16x32_bf16 v[8:11], v[208:211], v[232:235], v[8:11]
	v_lshl_add_u64 v[178:179], v[246:247], 0, s[8:9]
	s_mov_b32 m0, s91
	s_nop 0
	global_load_lds_dwordx4 v[178:179], off
	v_mfma_f32_16x16x32_bf16 v[4:7], v[194:197], v[240:243], v[4:7]
	v_mfma_f32_16x16x32_bf16 v[0:3], v[208:211], v[240:243], v[0:3]
	s_setprio 0
	s_barrier
	s_add_i32 vcc_lo, vcc_lo, 2
	s_add_u32 s58, s58, 0x100
	s_addc_u32 s59, s59, 0
	s_add_u32 s96, s96, 0x100
	s_addc_u32 s97, s97, 0
	s_cmp_gt_u32 vcc_lo, 13
	s_cbranch_scc0 .LBB0_459
	s_and_b64 vcc, exec, s[10:11]
	s_cbranch_vccz .LBB0_462
.LBB0_462:
	s_lshl_b32 s14, s54, 8
	s_cmp_gt_i32 s54, -1
	s_cselect_b64 s[54:55], -1, 0
	v_lshl_add_u32 v169, s56, 8, v139
	s_and_b64 vcc, exec, s[54:55]
	s_cbranch_vccz .LBB0_467
	s_mov_b64 s[56:57], -1
	s_cmpk_gt_u32 s14, 0x1ff
	v_cvt_pk_bf16_f32 v124, v124, v125
	v_cvt_pk_bf16_f32 v125, v126, v127
	v_cvt_pk_bf16_f32 v126, v120, v121
	v_cvt_pk_bf16_f32 v127, v122, v123
	v_cvt_pk_bf16_f32 v116, v116, v117
	v_cvt_pk_bf16_f32 v117, v118, v119
	v_cvt_pk_bf16_f32 v118, v112, v113
	v_cvt_pk_bf16_f32 v119, v114, v115
	v_cvt_pk_bf16_f32 v108, v108, v109
	v_cvt_pk_bf16_f32 v109, v110, v111
	v_cvt_pk_bf16_f32 v110, v104, v105
	v_cvt_pk_bf16_f32 v111, v106, v107
	v_cvt_pk_bf16_f32 v100, v100, v101
	v_cvt_pk_bf16_f32 v101, v102, v103
	v_cvt_pk_bf16_f32 v102, v96, v97
	v_cvt_pk_bf16_f32 v103, v98, v99
	v_cvt_pk_bf16_f32 v92, v92, v93
	v_cvt_pk_bf16_f32 v93, v94, v95
	v_cvt_pk_bf16_f32 v94, v88, v89
	v_cvt_pk_bf16_f32 v95, v90, v91
	v_cvt_pk_bf16_f32 v84, v84, v85
	v_cvt_pk_bf16_f32 v85, v86, v87
	v_cvt_pk_bf16_f32 v86, v80, v81
	v_cvt_pk_bf16_f32 v87, v82, v83
	v_cvt_pk_bf16_f32 v76, v76, v77
	v_cvt_pk_bf16_f32 v77, v78, v79
	v_cvt_pk_bf16_f32 v78, v72, v73
	v_cvt_pk_bf16_f32 v79, v74, v75
	v_cvt_pk_bf16_f32 v68, v68, v69
	v_cvt_pk_bf16_f32 v69, v70, v71
	v_cvt_pk_bf16_f32 v70, v64, v65
	v_cvt_pk_bf16_f32 v71, v66, v67
	s_cbranch_scc0 .LBB0_465
; __device__ __forceinline__ unsigned cvtpk(float lo, float hi) { f32x2v_ v = {lo, hi}; bf16x2v_ b = __builtin_convertvector(v, bf16x2v_); return __builtin_bit_cast(unsigned, b); }
;     __device__ __forceinline__ void operator()(const f32x4 (&acc)[2][2][4][2], const Unit& u, int wr, int wc, int fr, int fq) const {
;     ...
;             } else {
;                 const int c = c0 - vbeg, head = c >> dh_shift, d = c & (DH - 1);
; #pragma unroll
;                 for (int ai = 0; ai < 2; ++ai)
; #pragma unroll
;                     for (int m = 0; m < 4; ++m) { const int row = row0 + ai * HALF + m * 16; const float rs = ss ? row_rs(ss, row) : 1.0f;
;                         const f32x4 v0 = acc[ai][bj][m][0] * rs, v1 = acc[ai][bj][m][1] * rs;
;                         const int b = row >> S_shift, pos = row & ((1 << S_shift) - 1);
;                         const size_t tile = ((size_t)(b * kvh + head) << (S_shift - 5)) + (pos >> 5);
;                         bf16_t* vp = VP + tile * (size_t)(32 * DH) + ((((pos & 31) >> 3) << dh_shift) + d) * 8 + (pos & 7);
;                         const unsigned w0 = cvtpk(v0[0], v0[1]), w1 = cvtpk(v0[2], v0[3]), w2 = cvtpk(v1[0], v1[1]), w3 = cvtpk(v1[2], v1[3]);
;                         vp[0] = (bf16_t)(w0 & 0xffffu); vp[8] = (bf16_t)(w0 >> 16); vp[16] = (bf16_t)(w1 & 0xffffu); vp[24] = (bf16_t)(w1 >> 16);
;                         vp[32] = (bf16_t)(w2 & 0xffffu); vp[40] = (bf16_t)(w2 >> 16); vp[48] = (bf16_t)(w3 & 0xffffu); vp[56] = (bf16_t)(w3 >> 16); }
	s_add_i32 s3, s14, 0xfffffe00
	v_ashrrev_i32_e32 v64, 6, v169
	s_ashr_i32 s3, s3, 7
	v_and_b32_e32 v64, -4, v64
	v_add_u32_e32 v64, s3, v64
	v_ashrrev_i32_e32 v65, 31, v64
	v_lshlrev_b64 v[64:65], 16, v[64:65]
	v_lshl_add_u64 v[66:67], v[144:145], 0, v[64:65]
	global_store_short v[66:67], v124, off
	global_store_short_d16_hi v[66:67], v124, off offset:16
	global_store_short v[66:67], v125, off offset:32
	global_store_short_d16_hi v[66:67], v125, off offset:48
	global_store_short v[66:67], v126, off offset:64
	global_store_short_d16_hi v[66:67], v126, off offset:80
	global_store_short v[66:67], v127, off offset:96
	global_store_short_d16_hi v[66:67], v127, off offset:112
	v_lshl_add_u64 v[66:67], v[146:147], 0, v[64:65]
	global_store_short v[66:67], v116, off
	global_store_short_d16_hi v[66:67], v116, off offset:16
	global_store_short v[66:67], v117, off offset:32
	global_store_short_d16_hi v[66:67], v117, off offset:48
	global_store_short v[66:67], v118, off offset:64
	global_store_short_d16_hi v[66:67], v118, off offset:80
	global_store_short v[66:67], v119, off offset:96
	global_store_short_d16_hi v[66:67], v119, off offset:112
	v_lshl_add_u64 v[66:67], v[148:149], 0, v[64:65]
	global_store_short v[66:67], v108, off
	global_store_short_d16_hi v[66:67], v108, off offset:16
	global_store_short v[66:67], v109, off offset:32
	global_store_short_d16_hi v[66:67], v109, off offset:48
	global_store_short v[66:67], v110, off offset:64
	global_store_short_d16_hi v[66:67], v110, off offset:80
	global_store_short v[66:67], v111, off offset:96
	global_store_short_d16_hi v[66:67], v111, off offset:112
	v_lshl_add_u64 v[64:65], v[150:151], 0, v[64:65]
	v_add_u32_e32 v66, 0x80, v169
	global_store_short v[64:65], v100, off
	global_store_short_d16_hi v[64:65], v100, off offset:16
	global_store_short v[64:65], v101, off offset:32
	global_store_short_d16_hi v[64:65], v101, off offset:48
	global_store_short v[64:65], v102, off offset:64
	global_store_short_d16_hi v[64:65], v102, off offset:80
	global_store_short v[64:65], v103, off offset:96
	global_store_short_d16_hi v[64:65], v103, off offset:112
	v_ashrrev_i32_e32 v64, 6, v66
	v_and_b32_e32 v64, -4, v64
	v_add_u32_e32 v64, s3, v64
	v_ashrrev_i32_e32 v65, 31, v64
	v_lshlrev_b64 v[64:65], 16, v[64:65]
	v_lshlrev_b32_e32 v66, 8, v66
	v_lshl_add_u64 v[64:65], s[6:7], 0, v[64:65]
	v_and_b32_e32 v136, 0xc000, v66
	v_lshl_add_u64 v[64:65], v[64:65], 0, v[136:137]
	v_lshlrev_b32_e32 v136, 1, v140
	v_lshl_add_u64 v[64:65], v[64:65], 0, v[136:137]
	v_lshlrev_b32_e32 v66, 1, v142
	v_mov_b32_e32 v67, v137
	v_lshl_add_u64 v[64:65], v[64:65], 0, v[66:67]
	v_add_u32_e32 v74, 0x90, v169
	global_store_short v[64:65], v92, off
	global_store_short_d16_hi v[64:65], v92, off offset:16
	global_store_short v[64:65], v93, off offset:32
	global_store_short_d16_hi v[64:65], v93, off offset:48
	global_store_short v[64:65], v94, off offset:64
	global_store_short_d16_hi v[64:65], v94, off offset:80
	global_store_short v[64:65], v95, off offset:96
	global_store_short_d16_hi v[64:65], v95, off offset:112
	v_ashrrev_i32_e32 v64, 6, v74
	v_and_b32_e32 v64, -4, v64
	v_add_u32_e32 v64, s3, v64
	v_ashrrev_i32_e32 v65, 31, v64
	v_lshlrev_b64 v[64:65], 16, v[64:65]
	v_lshlrev_b32_e32 v72, 8, v74
	v_lshl_add_u64 v[64:65], s[6:7], 0, v[64:65]
	v_and_b32_e32 v72, 0xc000, v72
	v_mov_b32_e32 v73, v137
	v_lshl_add_u64 v[64:65], v[64:65], 0, v[72:73]
	v_lshlrev_b32_e32 v72, 4, v74
	v_and_or_b32 v72, v72, s93, v138
	v_lshlrev_b32_e32 v72, 4, v72
	v_lshl_add_u64 v[64:65], v[64:65], 0, v[72:73]
	v_lshl_add_u64 v[64:65], v[64:65], 0, v[66:67]
	v_add_u32_e32 v72, 0xa0, v169
	global_store_short v[64:65], v84, off
	global_store_short_d16_hi v[64:65], v84, off offset:16
	global_store_short v[64:65], v85, off offset:32
	global_store_short_d16_hi v[64:65], v85, off offset:48
	global_store_short v[64:65], v86, off offset:64
	global_store_short_d16_hi v[64:65], v86, off offset:80
	global_store_short v[64:65], v87, off offset:96
	global_store_short_d16_hi v[64:65], v87, off offset:112
	v_ashrrev_i32_e32 v64, 6, v72
	v_and_b32_e32 v64, -4, v64
	v_add_u32_e32 v64, s3, v64
	v_ashrrev_i32_e32 v65, 31, v64
	v_lshlrev_b64 v[64:65], 16, v[64:65]
	v_lshlrev_b32_e32 v72, 8, v72
	v_lshl_add_u64 v[64:65], s[6:7], 0, v[64:65]
	v_and_b32_e32 v72, 0xe000, v72
	v_lshl_add_u64 v[64:65], v[64:65], 0, v[72:73]
	v_lshl_add_u64 v[64:65], v[64:65], 0, v[136:137]
	v_lshl_add_u64 v[64:65], v[64:65], 0, v[66:67]
	v_add_u32_e32 v72, 0xb0, v169
	global_store_short v[64:65], v76, off
	global_store_short_d16_hi v[64:65], v76, off offset:16
	global_store_short v[64:65], v77, off offset:32
	global_store_short_d16_hi v[64:65], v77, off offset:48
	global_store_short v[64:65], v78, off offset:64
	global_store_short_d16_hi v[64:65], v78, off offset:80
	global_store_short v[64:65], v79, off offset:96
	global_store_short_d16_hi v[64:65], v79, off offset:112
	v_ashrrev_i32_e32 v64, 6, v72
	v_and_b32_e32 v64, -4, v64
	v_add_u32_e32 v64, s3, v64
	v_ashrrev_i32_e32 v65, 31, v64
	v_lshlrev_b64 v[64:65], 16, v[64:65]
	v_lshlrev_b32_e32 v73, 8, v72
	v_lshlrev_b32_e32 v72, 4, v72
	v_lshl_add_u64 v[64:65], s[6:7], 0, v[64:65]
	v_and_b32_e32 v136, 0xe000, v73
	v_and_or_b32 v72, v72, s93, v138
	v_lshl_add_u64 v[64:65], v[64:65], 0, v[136:137]
	v_lshlrev_b32_e32 v136, 4, v72
	v_lshl_add_u64 v[64:65], v[64:65], 0, v[136:137]
	v_lshl_add_u64 v[64:65], v[64:65], 0, v[66:67]
	global_store_short v[64:65], v68, off
	global_store_short_d16_hi v[64:65], v68, off offset:16
	global_store_short v[64:65], v69, off offset:32
	global_store_short_d16_hi v[64:65], v69, off offset:48
	global_store_short v[64:65], v70, off offset:64
	global_store_short_d16_hi v[64:65], v70, off offset:80
	global_store_short v[64:65], v71, off offset:96
	global_store_short_d16_hi v[64:65], v71, off offset:112
	s_mov_b64 s[56:57], 0

; #define PG8_BAR __builtin_amdgcn_s_barrier()
; template <class Epi, class Sched, bool ALIGN_EPI = false, bool SP2 = false>
; __device__ __forceinline__ void gemm_phase(PG8_LAS unsigned char* lds, const Gemm g, const Sched& S, const Epi& E) {
;     ...
;         if constexpr (ALIGN_EPI) { if (wr == 0) PG8_BAR; }
;         if constexpr (!Epi::AFTER_DRAIN) { E(acc, cur, wr, wc, fr, fq); S.done(cur); }
;         if (!has_next) break;
; #pragma unroll
;         for (int a = 0; a < 2; ++a)
; #pragma unroll
;             for (int b = 0; b < 2; ++b)
; #pragma unroll
;                 for (int m = 0; m < 4; ++m)
; #pragma unroll
;                     for (int n = 0; n < 2; ++n) acc[a][b][m][n] = (f32x4){0.f, 0.f, 0.f, 0.f};
;         cur = nxt; cA = nA; cB = nB; ++ui;
;         if constexpr (ALIGN_EPI) { if (wr == 1) PG8_BAR; }
.LBB0_472:
	s_andn2_b64 vcc, exec, s[40:41]
	s_mov_b64 s[40:41], -1
	s_cmp_eq_u64 s[10:11], 0
	s_cbranch_scc1 .Lxpost_1
	s_barrier
.Lxpost_1:
	s_cbranch_vccnz .LBB0_451
	s_andn2_b64 vcc, exec, s[0:1]
	s_cbranch_vccnz .LBB0_450
	s_barrier
	s_branch .LBB0_450

; #define PG8_STAGE(bufoff, gbase, voff) do { _Pragma("unroll") for (int _i = 0; _i < 2; ++_i) \
;         __builtin_amdgcn_global_load_lds((const unsigned*)((const char*)(gbase) + (voff)[_i]), (PG8_LAS unsigned*)(lds + (bufoff) + ldsw + _i * 8192), 16, 0, 0); } while (0)
; #define PG8_LDA(dst, b, h) do { _Pragma("unroll") for (int m = 0; m < 4; ++m) _Pragma("unroll") for (int k = 0; k < 2; ++k) dst[m][k] = *(const PG8_LAS bf16x8*)(lds + PG8_SA(b, h) + aoff + m * 2048 + k * 1024); } while (0)
; #define PG8_LDB(dst, b, h) do { _Pragma("unroll") for (int n = 0; n < 2; ++n) _Pragma("unroll") for (int k = 0; k < 2; ++k) dst[n][k] = *(const PG8_LAS bf16x8*)(lds + PG8_SB(b, h) + boff + n * 2048 + k * 1024); } while (0)
; #define PG8_WAIT_V(n) asm volatile("s_waitcnt vmcnt(" #n ")" ::: "memory")
; #define PG8_WAIT_L(n) asm volatile("s_waitcnt lgkmcnt(" #n ")" ::: "memory")
; #define PG8_BAR __builtin_amdgcn_s_barrier()
; #define PG8_SCHED __builtin_amdgcn_sched_barrier(0)
; template <class Epi, class Sched, bool ALIGN_EPI = false, bool SP2 = false>
; __device__ __forceinline__ void gemm_phase(PG8_LAS unsigned char* lds, const Gemm g, const Sched& S, const Epi& E) {
;     ...
;         const bool has_next = S.next(ui + 1, nxt);
;         const char* nA = has_next ? (const char*)g.A + (size_t)nxt.pm * tstep : cA; const char* nB = has_next ? (const char*)g.Bt + (size_t)nxt.pn * tstep : cB;
;         for (int t = 0; t < nt; t += 2) {
;             const bool last = (t == nt - 2);
;             const char* a1 = cA + (size_t)(t + 1) * kstep;
;             const char* a2 = last ? nA : cA + (size_t)(t + 2) * kstep; const char* b2 = last ? nB : cB + (size_t)(t + 2) * kstep;
;             const char* a3 = a2 + kstep; const char* b3 = b2 + kstep;
;             if (last && has_next) S.a_ready(nxt);
;             if constexpr (SP2) {
;             PG8_LDB(B0, 0, 0); PG8_LDB(B1, 0, 1); PG8_SCHED; PG8_LDA(At, 0, 0); PG8_STAGE(PG8_SA(1, 1), a1 + hstep, voffA);
;             PG8_WAIT_V(8); PG8_WAIT_L(0); PG8_BAR; PG8_MMA(0, 0, At, B0); PG8_MMA(0, 1, At, B1); PG8_BAR; PG8_SCHED;
;             PG8_LDA(At, 0, 1); PG8_STAGE(PG8_SB(0, 0), b2, voffB); PG8_STAGE(PG8_SB(0, 1), b2 + hstep, voffB); PG8_STAGE(PG8_SA(0, 0), a2, voffA);
;             PG8_WAIT_V(8); PG8_WAIT_L(0); PG8_BAR; PG8_MMA(1, 0, At, B0); PG8_MMA(1, 1, At, B1); PG8_BAR; PG8_SCHED;
.LBB0_649:
	s_ashr_i32 s51, s50, 31
	s_lshl_b64 s[14:15], s[50:51], 19
	s_add_u32 s52, s40, s14
	s_addc_u32 s53, s41, s15
	s_and_b64 s[14:15], s[8:9], exec
	s_cselect_b32 s51, s53, s61
	s_cselect_b32 s57, s52, s60
	s_ashr_i32 s49, s48, 31
	s_lshl_b64 s[14:15], s[48:49], 19
	s_add_u32 s54, s82, s14
	s_addc_u32 s55, s83, s15
	s_and_b64 s[14:15], s[8:9], exec
	s_cselect_b32 s49, s55, s63
	s_cselect_b32 s89, s54, s62
	s_add_u32 s60, s60, 0x40080
	s_addc_u32 s61, s61, 0
	s_add_u32 s90, s62, 0x100
	s_addc_u32 s91, s63, 0
	s_mov_b32 s92, -2
	s_waitcnt lgkmcnt(0)
	s_waitcnt vmcnt(0)
	ds_read_b128 v[148:151], v155
	ds_read_b128 v[160:163], v155 offset:1024
	ds_read_b128 v[164:167], v155 offset:2048
	ds_read_b128 v[168:171], v155 offset:3072
	ds_read_b128 v[172:175], v156
	ds_read_b128 v[176:179], v156 offset:1024
	ds_read_b128 v[182:185], v156 offset:2048
	ds_read_b128 v[186:189], v156 offset:3072
	s_add_u32 s3, s60, 0xfffc0080
	s_addc_u32 s14, s61, -1
	s_cmp_eq_u32 s92, 12
	s_cselect_b32 s65, s51, s14
	s_cselect_b32 s64, s57, s3
	s_cselect_b32 s63, s49, s91
	s_cselect_b32 s62, s89, s90
	v_lshl_add_u64 v[202:203], s[60:61], 0, v[140:141]
	s_add_i32 m0, s43, 0xc000
	ds_read_b128 v[190:193], v157
	ds_read_b128 v[194:197], v157 offset:1024
	ds_read_b128 v[198:201], v157 offset:2048
	ds_read_b128 v[208:211], v157 offset:3072
	ds_read_b128 v[212:215], v157 offset:4096
	ds_read_b128 v[216:219], v157 offset:5120
	ds_read_b128 v[220:223], v157 offset:6144
	ds_read_b128 v[224:227], v157 offset:7168
	global_load_lds_dwordx4 v[202:203], off
	v_lshl_add_u64 v[202:203], s[60:61], 0, v[142:143]
	s_add_i32 m0, s43, 0xe000
	s_nop 0
	global_load_lds_dwordx4 v[202:203], off
	s_waitcnt vmcnt(8)
	s_waitcnt lgkmcnt(0)
	s_barrier
	s_setprio 1
	s_waitcnt lgkmcnt(0)
	v_mfma_f32_16x16x32_bf16 v[124:127], v[148:151], v[190:193], 0
	v_mfma_f32_16x16x32_bf16 v[120:123], v[164:167], v[190:193], 0
	v_mfma_f32_16x16x32_bf16 v[108:111], v[148:151], v[198:201], 0
	v_mfma_f32_16x16x32_bf16 v[104:107], v[164:167], v[198:201], 0
	v_mfma_f32_16x16x32_bf16 v[92:95], v[148:151], v[212:215], 0
	v_mfma_f32_16x16x32_bf16 v[88:91], v[164:167], v[212:215], 0
	v_mfma_f32_16x16x32_bf16 v[76:79], v[148:151], v[220:223], 0
	v_mfma_f32_16x16x32_bf16 v[72:75], v[164:167], v[220:223], 0
	v_mfma_f32_16x16x32_bf16 v[124:127], v[160:163], v[194:197], v[124:127]
	v_mfma_f32_16x16x32_bf16 v[120:123], v[168:171], v[194:197], v[120:123]
	v_mfma_f32_16x16x32_bf16 v[108:111], v[160:163], v[208:211], v[108:111]
	v_mfma_f32_16x16x32_bf16 v[104:107], v[168:171], v[208:211], v[104:107]
	v_mfma_f32_16x16x32_bf16 v[92:95], v[160:163], v[216:219], v[92:95]
	v_mfma_f32_16x16x32_bf16 v[88:91], v[168:171], v[216:219], v[88:91]
	v_mfma_f32_16x16x32_bf16 v[76:79], v[160:163], v[224:227], v[76:79]
	v_mfma_f32_16x16x32_bf16 v[72:75], v[168:171], v[224:227], v[72:75]
	s_setprio 0
	s_setprio 1
	v_mfma_f32_16x16x32_bf16 v[116:119], v[172:175], v[190:193], 0
	v_mfma_f32_16x16x32_bf16 v[112:115], v[182:185], v[190:193], 0
	v_mfma_f32_16x16x32_bf16 v[100:103], v[172:175], v[198:201], 0
	v_mfma_f32_16x16x32_bf16 v[96:99], v[182:185], v[198:201], 0
	v_mfma_f32_16x16x32_bf16 v[84:87], v[172:175], v[212:215], 0
	v_mfma_f32_16x16x32_bf16 v[80:83], v[182:185], v[212:215], 0
	v_mfma_f32_16x16x32_bf16 v[68:71], v[172:175], v[220:223], 0
	v_mfma_f32_16x16x32_bf16 v[64:67], v[182:185], v[220:223], 0
	v_mfma_f32_16x16x32_bf16 v[116:119], v[176:179], v[194:197], v[116:119]
	v_mfma_f32_16x16x32_bf16 v[112:115], v[186:189], v[194:197], v[112:115]
	v_mfma_f32_16x16x32_bf16 v[100:103], v[176:179], v[208:211], v[100:103]
	v_mfma_f32_16x16x32_bf16 v[96:99], v[186:189], v[208:211], v[96:99]
	v_mfma_f32_16x16x32_bf16 v[84:87], v[176:179], v[216:219], v[84:87]
	v_mfma_f32_16x16x32_bf16 v[80:83], v[186:189], v[216:219], v[80:83]
	v_mfma_f32_16x16x32_bf16 v[68:71], v[176:179], v[224:227], v[68:71]
	v_mfma_f32_16x16x32_bf16 v[64:67], v[186:189], v[224:227], v[64:67]
	s_setprio 0
	s_barrier
	s_add_i32 s3, s85, s34
	v_lshl_add_u64 v[202:203], s[62:63], 0, v[134:135]
	s_mov_b32 m0, s3
	ds_read_b128 v[190:193], v157 offset:16384
	ds_read_b128 v[194:197], v157 offset:17408
	ds_read_b128 v[198:201], v157 offset:18432
	ds_read_b128 v[208:211], v157 offset:19456
	ds_read_b128 v[212:215], v157 offset:20480
	ds_read_b128 v[216:219], v157 offset:21504
	ds_read_b128 v[220:223], v157 offset:22528
	ds_read_b128 v[224:227], v157 offset:23552
	global_load_lds_dwordx4 v[202:203], off
	s_add_i32 m0, s3, 0x2000
	s_add_u32 s14, s62, 0x40000
	v_lshl_add_u64 v[228:229], s[62:63], 0, v[138:139]
	s_addc_u32 s15, s63, 0
	s_add_i32 s3, s86, s34
	global_load_lds_dwordx4 v[228:229], off
	v_lshl_add_u64 v[230:231], s[14:15], 0, v[134:135]
	s_mov_b32 m0, s3
	global_load_lds_dwordx4 v[230:231], off
	v_lshl_add_u64 v[230:231], s[14:15], 0, v[138:139]
	s_add_i32 m0, s3, 0x2000
	s_nop 0
	global_load_lds_dwordx4 v[230:231], off
	s_waitcnt vmcnt(6)
	s_waitcnt lgkmcnt(0)
	s_barrier
; #define PG8_STAGE(bufoff, gbase, voff) do { _Pragma("unroll") for (int _i = 0; _i < 2; ++_i) \
;         __builtin_amdgcn_global_load_lds((const unsigned*)((const char*)(gbase) + (voff)[_i]), (PG8_LAS unsigned*)(lds + (bufoff) + ldsw + _i * 8192), 16, 0, 0); } while (0)
; #define PG8_LDA(dst, b, h) do { _Pragma("unroll") for (int m = 0; m < 4; ++m) _Pragma("unroll") for (int k = 0; k < 2; ++k) dst[m][k] = *(const PG8_LAS bf16x8*)(lds + PG8_SA(b, h) + aoff + m * 2048 + k * 1024); } while (0)
; #define PG8_LDB(dst, b, h) do { _Pragma("unroll") for (int n = 0; n < 2; ++n) _Pragma("unroll") for (int k = 0; k < 2; ++k) dst[n][k] = *(const PG8_LAS bf16x8*)(lds + PG8_SB(b, h) + boff + n * 2048 + k * 1024); } while (0)
; #define PG8_MMA(ai, bj, At, Bt) do { __builtin_amdgcn_s_setprio(1); _Pragma("unroll") for (int m = 0; m < 4; ++m) _Pragma("unroll") for (int n = 0; n < 2; ++n) _Pragma("unroll") for (int k = 0; k < 2; ++k) \
;         acc[ai][bj][m][n] = __builtin_amdgcn_mfma_f32_16x16x32_bf16(Bt[n][k], At[m][k], acc[ai][bj][m][n], 0, 0, 0); __builtin_amdgcn_s_setprio(0); } while (0)
; #define PG8_WAIT_V(n) asm volatile("s_waitcnt vmcnt(" #n ")" ::: "memory")
; #define PG8_WAIT_L(n) asm volatile("s_waitcnt lgkmcnt(" #n ")" ::: "memory")
; #define PG8_BAR __builtin_amdgcn_s_barrier()
; #define PG8_SCHED __builtin_amdgcn_sched_barrier(0)
; template <class Epi, class Sched, bool ALIGN_EPI = false, bool SP2 = false>
; __device__ __forceinline__ void gemm_phase(PG8_LAS unsigned char* lds, const Gemm g, const Sched& S, const Epi& E) {
;     ...
;             PG8_LDA(At, 0, 1); PG8_STAGE(PG8_SB(0, 0), b2, voffB); PG8_STAGE(PG8_SB(0, 1), b2 + hstep, voffB); PG8_STAGE(PG8_SA(0, 0), a2, voffA);
;             PG8_WAIT_V(8); PG8_WAIT_L(0); PG8_BAR; PG8_MMA(1, 0, At, B0); PG8_MMA(1, 1, At, B1); PG8_BAR; PG8_SCHED;
;             PG8_LDB(B0, 1, 0); PG8_LDB(B1, 1, 1); PG8_SCHED; PG8_LDA(At, 1, 0); PG8_STAGE(PG8_SA(0, 1), a2 + hstep, voffA);
;             PG8_WAIT_V(8); PG8_WAIT_L(0); PG8_BAR; PG8_MMA(0, 0, At, B0); PG8_MMA(0, 1, At, B1); PG8_BAR; PG8_SCHED;
	s_setprio 1
	s_waitcnt lgkmcnt(0)
	v_mfma_f32_16x16x32_bf16 v[60:63], v[148:151], v[190:193], 0
	v_mfma_f32_16x16x32_bf16 v[56:59], v[164:167], v[190:193], 0
	v_mfma_f32_16x16x32_bf16 v[44:47], v[148:151], v[198:201], 0
	v_mfma_f32_16x16x32_bf16 v[40:43], v[164:167], v[198:201], 0
	v_mfma_f32_16x16x32_bf16 v[28:31], v[148:151], v[212:215], 0
	v_mfma_f32_16x16x32_bf16 v[24:27], v[164:167], v[212:215], 0
	v_mfma_f32_16x16x32_bf16 v[12:15], v[148:151], v[220:223], 0
	v_mfma_f32_16x16x32_bf16 v[8:11], v[164:167], v[220:223], 0
	v_mfma_f32_16x16x32_bf16 v[60:63], v[160:163], v[194:197], v[60:63]
	v_mfma_f32_16x16x32_bf16 v[56:59], v[168:171], v[194:197], v[56:59]
	v_mfma_f32_16x16x32_bf16 v[44:47], v[160:163], v[208:211], v[44:47]
	v_mfma_f32_16x16x32_bf16 v[40:43], v[168:171], v[208:211], v[40:43]
	v_mfma_f32_16x16x32_bf16 v[28:31], v[160:163], v[216:219], v[28:31]
	v_mfma_f32_16x16x32_bf16 v[24:27], v[168:171], v[216:219], v[24:27]
	v_lshl_add_u64 v[230:231], s[64:65], 0, v[132:133]
	s_mov_b32 m0, s43
	s_nop 0
	global_load_lds_dwordx4 v[230:231], off
	v_mfma_f32_16x16x32_bf16 v[12:15], v[160:163], v[224:227], v[12:15]
	v_mfma_f32_16x16x32_bf16 v[8:11], v[168:171], v[224:227], v[8:11]
	s_setprio 0
	s_setprio 1
	v_mfma_f32_16x16x32_bf16 v[52:55], v[172:175], v[190:193], 0
	v_mfma_f32_16x16x32_bf16 v[48:51], v[182:185], v[190:193], 0
	v_mfma_f32_16x16x32_bf16 v[36:39], v[172:175], v[198:201], 0
	v_mfma_f32_16x16x32_bf16 v[32:35], v[182:185], v[198:201], 0
	v_mfma_f32_16x16x32_bf16 v[20:23], v[172:175], v[212:215], 0
	v_mfma_f32_16x16x32_bf16 v[16:19], v[182:185], v[212:215], 0
	v_mfma_f32_16x16x32_bf16 v[4:7], v[172:175], v[220:223], 0
	v_mfma_f32_16x16x32_bf16 v[0:3], v[182:185], v[220:223], 0
	v_mfma_f32_16x16x32_bf16 v[52:55], v[176:179], v[194:197], v[52:55]
	v_mfma_f32_16x16x32_bf16 v[48:51], v[186:189], v[194:197], v[48:51]
	v_mfma_f32_16x16x32_bf16 v[36:39], v[176:179], v[208:211], v[36:39]
	v_mfma_f32_16x16x32_bf16 v[32:35], v[186:189], v[208:211], v[32:35]
	v_mfma_f32_16x16x32_bf16 v[20:23], v[176:179], v[216:219], v[20:23]
	v_mfma_f32_16x16x32_bf16 v[16:19], v[186:189], v[216:219], v[16:19]
	v_lshl_add_u64 v[232:233], s[64:65], 0, v[136:137]
	s_mov_b32 m0, s59
	s_nop 0
	global_load_lds_dwordx4 v[232:233], off
	v_mfma_f32_16x16x32_bf16 v[4:7], v[176:179], v[224:227], v[4:7]
	v_mfma_f32_16x16x32_bf16 v[0:3], v[186:189], v[224:227], v[0:3]
	s_setprio 0
	s_barrier
	s_add_i32 s3, 0, 0x18000
	v_add_u32_e32 v159, s3, v131
	s_add_i32 s33, 0, 0x1c000
	ds_read_b128 v[148:151], v159
	ds_read_b128 v[160:163], v159 offset:1024
	ds_read_b128 v[164:167], v159 offset:2048
	ds_read_b128 v[168:171], v159 offset:3072
	v_add_u32_e32 v159, s33, v131
	ds_read_b128 v[172:175], v159
	ds_read_b128 v[176:179], v159 offset:1024
	ds_read_b128 v[182:185], v159 offset:2048
	ds_read_b128 v[186:189], v159 offset:3072
	s_add_u32 s14, s64, 0x40000
	s_addc_u32 s15, s65, 0
	s_mov_b32 m0, s66
	v_lshl_add_u64 v[234:235], s[14:15], 0, v[132:133]
	ds_read_b128 v[190:193], v157 offset:32768
	ds_read_b128 v[194:197], v157 offset:33792
	ds_read_b128 v[198:201], v157 offset:34816
	ds_read_b128 v[208:211], v157 offset:35840
	ds_read_b128 v[212:215], v157 offset:36864
	ds_read_b128 v[216:219], v157 offset:37888
	ds_read_b128 v[220:223], v157 offset:38912
	ds_read_b128 v[224:227], v157 offset:39936
	global_load_lds_dwordx4 v[234:235], off
	v_lshl_add_u64 v[234:235], s[14:15], 0, v[136:137]
	s_mov_b32 m0, s67
	s_nop 0
	global_load_lds_dwordx4 v[234:235], off
	s_waitcnt vmcnt(8)
	s_waitcnt lgkmcnt(0)
	s_barrier
	s_setprio 1
	s_waitcnt lgkmcnt(0)
	v_mfma_f32_16x16x32_bf16 v[124:127], v[148:151], v[190:193], v[124:127]
	v_mfma_f32_16x16x32_bf16 v[120:123], v[164:167], v[190:193], v[120:123]
	v_mfma_f32_16x16x32_bf16 v[108:111], v[148:151], v[198:201], v[108:111]
	v_mfma_f32_16x16x32_bf16 v[104:107], v[164:167], v[198:201], v[104:107]
	v_mfma_f32_16x16x32_bf16 v[92:95], v[148:151], v[212:215], v[92:95]
	v_mfma_f32_16x16x32_bf16 v[88:91], v[164:167], v[212:215], v[88:91]
	v_mfma_f32_16x16x32_bf16 v[76:79], v[148:151], v[220:223], v[76:79]
	v_mfma_f32_16x16x32_bf16 v[72:75], v[164:167], v[220:223], v[72:75]
	v_mfma_f32_16x16x32_bf16 v[124:127], v[160:163], v[194:197], v[124:127]
	v_mfma_f32_16x16x32_bf16 v[120:123], v[168:171], v[194:197], v[120:123]
	v_mfma_f32_16x16x32_bf16 v[108:111], v[160:163], v[208:211], v[108:111]
	v_mfma_f32_16x16x32_bf16 v[104:107], v[168:171], v[208:211], v[104:107]
	v_mfma_f32_16x16x32_bf16 v[92:95], v[160:163], v[216:219], v[92:95]
	v_mfma_f32_16x16x32_bf16 v[88:91], v[168:171], v[216:219], v[88:91]
	v_mfma_f32_16x16x32_bf16 v[76:79], v[160:163], v[224:227], v[76:79]
	v_mfma_f32_16x16x32_bf16 v[72:75], v[168:171], v[224:227], v[72:75]
	s_setprio 0
	s_setprio 1
	v_mfma_f32_16x16x32_bf16 v[116:119], v[172:175], v[190:193], v[116:119]
	v_mfma_f32_16x16x32_bf16 v[112:115], v[182:185], v[190:193], v[112:115]
	v_mfma_f32_16x16x32_bf16 v[100:103], v[172:175], v[198:201], v[100:103]
	v_mfma_f32_16x16x32_bf16 v[96:99], v[182:185], v[198:201], v[96:99]
	v_mfma_f32_16x16x32_bf16 v[84:87], v[172:175], v[212:215], v[84:87]
	v_mfma_f32_16x16x32_bf16 v[80:83], v[182:185], v[212:215], v[80:83]
	v_mfma_f32_16x16x32_bf16 v[68:71], v[172:175], v[220:223], v[68:71]
	v_mfma_f32_16x16x32_bf16 v[64:67], v[182:185], v[220:223], v[64:67]
	v_mfma_f32_16x16x32_bf16 v[116:119], v[176:179], v[194:197], v[116:119]
	v_mfma_f32_16x16x32_bf16 v[112:115], v[186:189], v[194:197], v[112:115]
	v_mfma_f32_16x16x32_bf16 v[100:103], v[176:179], v[208:211], v[100:103]
	v_mfma_f32_16x16x32_bf16 v[96:99], v[186:189], v[208:211], v[96:99]
	v_mfma_f32_16x16x32_bf16 v[84:87], v[176:179], v[216:219], v[84:87]
	v_mfma_f32_16x16x32_bf16 v[80:83], v[186:189], v[216:219], v[80:83]
	v_mfma_f32_16x16x32_bf16 v[68:71], v[176:179], v[224:227], v[68:71]
	v_mfma_f32_16x16x32_bf16 v[64:67], v[186:189], v[224:227], v[64:67]
	s_setprio 0
	s_barrier
; #define PG8_STAGE(bufoff, gbase, voff) do { _Pragma("unroll") for (int _i = 0; _i < 2; ++_i) \
;         __builtin_amdgcn_global_load_lds((const unsigned*)((const char*)(gbase) + (voff)[_i]), (PG8_LAS unsigned*)(lds + (bufoff) + ldsw + _i * 8192), 16, 0, 0); } while (0)
; #define PG8_LDA(dst, b, h) do { _Pragma("unroll") for (int m = 0; m < 4; ++m) _Pragma("unroll") for (int k = 0; k < 2; ++k) dst[m][k] = *(const PG8_LAS bf16x8*)(lds + PG8_SA(b, h) + aoff + m * 2048 + k * 1024); } while (0)
; #define PG8_LDB(dst, b, h) do { _Pragma("unroll") for (int n = 0; n < 2; ++n) _Pragma("unroll") for (int k = 0; k < 2; ++k) dst[n][k] = *(const PG8_LAS bf16x8*)(lds + PG8_SB(b, h) + boff + n * 2048 + k * 1024); } while (0)
; #define PG8_BAR __builtin_amdgcn_s_barrier()
; template <class Epi, class Sched, bool ALIGN_EPI = false, bool SP2 = false>
; __device__ __forceinline__ void gemm_phase(PG8_LAS unsigned char* lds, const Gemm g, const Sched& S, const Epi& E) {
;     ...
;             const bool last = (t == nt - 2);
;             const char* a1 = cA + (size_t)(t + 1) * kstep;
;             const char* a2 = last ? nA : cA + (size_t)(t + 2) * kstep; const char* b2 = last ? nB : cB + (size_t)(t + 2) * kstep;
;             const char* a3 = a2 + kstep; const char* b3 = b2 + kstep;
;             if (last && has_next) S.a_ready(nxt);
;             if constexpr (SP2) {
;             PG8_LDB(B0, 0, 0); PG8_LDB(B1, 0, 1); PG8_SCHED; PG8_LDA(At, 0, 0); PG8_STAGE(PG8_SA(1, 1), a1 + hstep, voffA);
;             PG8_WAIT_V(8); PG8_WAIT_L(0); PG8_BAR; PG8_MMA(0, 0, At, B0); PG8_MMA(0, 1, At, B1); PG8_BAR; PG8_SCHED;
;             PG8_LDA(At, 0, 1); PG8_STAGE(PG8_SB(0, 0), b2, voffB); PG8_STAGE(PG8_SB(0, 1), b2 + hstep, voffB); PG8_STAGE(PG8_SA(0, 0), a2, voffA);
;             PG8_WAIT_V(8); PG8_WAIT_L(0); PG8_BAR; PG8_MMA(1, 0, At, B0); PG8_MMA(1, 1, At, B1); PG8_BAR; PG8_SCHED;
;             PG8_LDB(B0, 1, 0); PG8_LDB(B1, 1, 1); PG8_SCHED; PG8_LDA(At, 1, 0); PG8_STAGE(PG8_SA(0, 1), a2 + hstep, voffA);
;             PG8_WAIT_V(8); PG8_WAIT_L(0); PG8_BAR; PG8_MMA(0, 0, At, B0); PG8_MMA(0, 1, At, B1); PG8_BAR; PG8_SCHED;
;             PG8_LDA(At, 1, 1); PG8_STAGE(PG8_SB(1, 0), b3, voffB); PG8_STAGE(PG8_SB(1, 1), b3 + hstep, voffB); PG8_STAGE(PG8_SA(1, 0), a3, voffA);
;             PG8_WAIT_V(8); PG8_WAIT_L(0); PG8_BAR; PG8_MMA(1, 0, At, B0); PG8_MMA(1, 1, At, B1); PG8_BAR; PG8_SCHED;
	s_add_i32 s3, s3, s34
	v_lshl_add_u64 v[202:203], v[202:203], 0, s[38:39]
	s_mov_b32 m0, s3
	ds_read_b128 v[190:193], v157 offset:49152
	ds_read_b128 v[194:197], v157 offset:50176
	ds_read_b128 v[198:201], v157 offset:51200
	ds_read_b128 v[208:211], v157 offset:52224
	ds_read_b128 v[212:215], v157 offset:53248
	ds_read_b128 v[216:219], v157 offset:54272
	ds_read_b128 v[220:223], v157 offset:55296
	ds_read_b128 v[224:227], v157 offset:56320
	global_load_lds_dwordx4 v[202:203], off
	s_add_i32 m0, s3, 0x2000
	s_add_u32 s14, s62, 0x40080
	v_lshl_add_u64 v[202:203], v[228:229], 0, s[38:39]
	s_addc_u32 s15, s63, 0
	s_add_i32 s3, s33, s34
	global_load_lds_dwordx4 v[202:203], off
	v_lshl_add_u64 v[202:203], s[14:15], 0, v[134:135]
	s_mov_b32 m0, s3
	s_nop 0
	global_load_lds_dwordx4 v[202:203], off
	v_lshl_add_u64 v[202:203], s[14:15], 0, v[138:139]
	s_add_i32 m0, s3, 0x2000
	s_nop 0
	global_load_lds_dwordx4 v[202:203], off
	s_waitcnt vmcnt(6)
	s_waitcnt lgkmcnt(0)
	s_barrier
	s_setprio 1
	s_waitcnt lgkmcnt(0)
	v_mfma_f32_16x16x32_bf16 v[60:63], v[148:151], v[190:193], v[60:63]
	v_mfma_f32_16x16x32_bf16 v[56:59], v[164:167], v[190:193], v[56:59]
	v_mfma_f32_16x16x32_bf16 v[44:47], v[148:151], v[198:201], v[44:47]
	v_mfma_f32_16x16x32_bf16 v[40:43], v[164:167], v[198:201], v[40:43]
	v_mfma_f32_16x16x32_bf16 v[28:31], v[148:151], v[212:215], v[28:31]
	v_mfma_f32_16x16x32_bf16 v[24:27], v[164:167], v[212:215], v[24:27]
	v_mfma_f32_16x16x32_bf16 v[12:15], v[148:151], v[220:223], v[12:15]
	v_mfma_f32_16x16x32_bf16 v[8:11], v[164:167], v[220:223], v[8:11]
	v_mfma_f32_16x16x32_bf16 v[60:63], v[160:163], v[194:197], v[60:63]
	v_mfma_f32_16x16x32_bf16 v[56:59], v[168:171], v[194:197], v[56:59]
	v_mfma_f32_16x16x32_bf16 v[44:47], v[160:163], v[208:211], v[44:47]
	v_mfma_f32_16x16x32_bf16 v[40:43], v[168:171], v[208:211], v[40:43]
	v_mfma_f32_16x16x32_bf16 v[28:31], v[160:163], v[216:219], v[28:31]
	v_mfma_f32_16x16x32_bf16 v[24:27], v[168:171], v[216:219], v[24:27]
	v_lshl_add_u64 v[202:203], v[230:231], 0, s[38:39]
	s_mov_b32 m0, s75
	s_nop 0
	global_load_lds_dwordx4 v[202:203], off
	v_mfma_f32_16x16x32_bf16 v[12:15], v[160:163], v[224:227], v[12:15]
	v_mfma_f32_16x16x32_bf16 v[8:11], v[168:171], v[224:227], v[8:11]
	s_setprio 0
	s_setprio 1
	v_mfma_f32_16x16x32_bf16 v[52:55], v[172:175], v[190:193], v[52:55]
	v_mfma_f32_16x16x32_bf16 v[48:51], v[182:185], v[190:193], v[48:51]
	v_mfma_f32_16x16x32_bf16 v[36:39], v[172:175], v[198:201], v[36:39]
	v_mfma_f32_16x16x32_bf16 v[32:35], v[182:185], v[198:201], v[32:35]
	v_mfma_f32_16x16x32_bf16 v[20:23], v[172:175], v[212:215], v[20:23]
	v_mfma_f32_16x16x32_bf16 v[16:19], v[182:185], v[212:215], v[16:19]
	v_mfma_f32_16x16x32_bf16 v[4:7], v[172:175], v[220:223], v[4:7]
	v_mfma_f32_16x16x32_bf16 v[0:3], v[182:185], v[220:223], v[0:3]
	v_mfma_f32_16x16x32_bf16 v[52:55], v[176:179], v[194:197], v[52:55]
	v_mfma_f32_16x16x32_bf16 v[48:51], v[186:189], v[194:197], v[48:51]
	v_mfma_f32_16x16x32_bf16 v[36:39], v[176:179], v[208:211], v[36:39]
	v_mfma_f32_16x16x32_bf16 v[32:35], v[186:189], v[208:211], v[32:35]
	v_mfma_f32_16x16x32_bf16 v[20:23], v[176:179], v[216:219], v[20:23]
	v_mfma_f32_16x16x32_bf16 v[16:19], v[186:189], v[216:219], v[16:19]
	v_lshl_add_u64 v[202:203], v[232:233], 0, s[38:39]
	s_mov_b32 m0, s84
	s_nop 0
	global_load_lds_dwordx4 v[202:203], off
	v_mfma_f32_16x16x32_bf16 v[4:7], v[176:179], v[224:227], v[4:7]
	v_mfma_f32_16x16x32_bf16 v[0:3], v[186:189], v[224:227], v[0:3]
	s_setprio 0
	s_barrier
	s_add_i32 s92, s92, 2
	s_add_u32 s60, s60, 0x100
	s_addc_u32 s61, s61, 0
	s_add_u32 s90, s90, 0x100
	s_addc_u32 s91, s91, 0
.LBB0_650:
	ds_read_b128 v[148:151], v155
	ds_read_b128 v[160:163], v155 offset:1024
	ds_read_b128 v[164:167], v155 offset:2048
	ds_read_b128 v[168:171], v155 offset:3072
	ds_read_b128 v[172:175], v156
	ds_read_b128 v[176:179], v156 offset:1024
	ds_read_b128 v[182:185], v156 offset:2048
	ds_read_b128 v[186:189], v156 offset:3072
	s_add_u32 s3, s60, 0xfffc0080
	s_addc_u32 s14, s61, -1
	s_cmp_eq_u32 s92, 12
	s_cselect_b32 s65, s51, s14
	s_cselect_b32 s64, s57, s3
	s_cselect_b32 s63, s49, s91
	s_cselect_b32 s62, s89, s90
	v_lshl_add_u64 v[202:203], s[60:61], 0, v[140:141]
	s_add_i32 m0, s43, 0xc000
	ds_read_b128 v[190:193], v157
	ds_read_b128 v[194:197], v157 offset:1024
	ds_read_b128 v[198:201], v157 offset:2048
	ds_read_b128 v[208:211], v157 offset:3072
	ds_read_b128 v[212:215], v157 offset:4096
	ds_read_b128 v[216:219], v157 offset:5120
	ds_read_b128 v[220:223], v157 offset:6144
	ds_read_b128 v[224:227], v157 offset:7168
	global_load_lds_dwordx4 v[202:203], off
	v_lshl_add_u64 v[202:203], s[60:61], 0, v[142:143]
	s_add_i32 m0, s43, 0xe000
	s_nop 0
	global_load_lds_dwordx4 v[202:203], off
	s_waitcnt vmcnt(8)
	s_waitcnt lgkmcnt(0)
	s_barrier
; #define PG8_STAGE(bufoff, gbase, voff) do { _Pragma("unroll") for (int _i = 0; _i < 2; ++_i) \
;         __builtin_amdgcn_global_load_lds((const unsigned*)((const char*)(gbase) + (voff)[_i]), (PG8_LAS unsigned*)(lds + (bufoff) + ldsw + _i * 8192), 16, 0, 0); } while (0)
; #define PG8_LDA(dst, b, h) do { _Pragma("unroll") for (int m = 0; m < 4; ++m) _Pragma("unroll") for (int k = 0; k < 2; ++k) dst[m][k] = *(const PG8_LAS bf16x8*)(lds + PG8_SA(b, h) + aoff + m * 2048 + k * 1024); } while (0)
; #define PG8_MMA(ai, bj, At, Bt) do { __builtin_amdgcn_s_setprio(1); _Pragma("unroll") for (int m = 0; m < 4; ++m) _Pragma("unroll") for (int n = 0; n < 2; ++n) _Pragma("unroll") for (int k = 0; k < 2; ++k) \
;         acc[ai][bj][m][n] = __builtin_amdgcn_mfma_f32_16x16x32_bf16(Bt[n][k], At[m][k], acc[ai][bj][m][n], 0, 0, 0); __builtin_amdgcn_s_setprio(0); } while (0)
; #define PG8_WAIT_V(n) asm volatile("s_waitcnt vmcnt(" #n ")" ::: "memory")
; #define PG8_WAIT_L(n) asm volatile("s_waitcnt lgkmcnt(" #n ")" ::: "memory")
; #define PG8_BAR __builtin_amdgcn_s_barrier()
; #define PG8_SCHED __builtin_amdgcn_sched_barrier(0)
; template <class Epi, class Sched, bool ALIGN_EPI = false, bool SP2 = false>
; __device__ __forceinline__ void gemm_phase(PG8_LAS unsigned char* lds, const Gemm g, const Sched& S, const Epi& E) {
;     ...
;             PG8_WAIT_V(8); PG8_WAIT_L(0); PG8_BAR; PG8_MMA(0, 0, At, B0); PG8_MMA(0, 1, At, B1); PG8_BAR; PG8_SCHED;
;             PG8_LDA(At, 0, 1); PG8_STAGE(PG8_SB(0, 0), b2, voffB); PG8_STAGE(PG8_SB(0, 1), b2 + hstep, voffB); PG8_STAGE(PG8_SA(0, 0), a2, voffA);
;             PG8_WAIT_V(8); PG8_WAIT_L(0); PG8_BAR; PG8_MMA(1, 0, At, B0); PG8_MMA(1, 1, At, B1); PG8_BAR; PG8_SCHED;
	s_setprio 1
	s_waitcnt lgkmcnt(0)
	v_mfma_f32_16x16x32_bf16 v[124:127], v[148:151], v[190:193], v[124:127]
	v_mfma_f32_16x16x32_bf16 v[120:123], v[164:167], v[190:193], v[120:123]
	v_mfma_f32_16x16x32_bf16 v[108:111], v[148:151], v[198:201], v[108:111]
	v_mfma_f32_16x16x32_bf16 v[104:107], v[164:167], v[198:201], v[104:107]
	v_mfma_f32_16x16x32_bf16 v[92:95], v[148:151], v[212:215], v[92:95]
	v_mfma_f32_16x16x32_bf16 v[88:91], v[164:167], v[212:215], v[88:91]
	v_mfma_f32_16x16x32_bf16 v[76:79], v[148:151], v[220:223], v[76:79]
	v_mfma_f32_16x16x32_bf16 v[72:75], v[164:167], v[220:223], v[72:75]
	v_mfma_f32_16x16x32_bf16 v[124:127], v[160:163], v[194:197], v[124:127]
	v_mfma_f32_16x16x32_bf16 v[120:123], v[168:171], v[194:197], v[120:123]
	v_mfma_f32_16x16x32_bf16 v[108:111], v[160:163], v[208:211], v[108:111]
	v_mfma_f32_16x16x32_bf16 v[104:107], v[168:171], v[208:211], v[104:107]
	v_mfma_f32_16x16x32_bf16 v[92:95], v[160:163], v[216:219], v[92:95]
	v_mfma_f32_16x16x32_bf16 v[88:91], v[168:171], v[216:219], v[88:91]
	v_mfma_f32_16x16x32_bf16 v[76:79], v[160:163], v[224:227], v[76:79]
	v_mfma_f32_16x16x32_bf16 v[72:75], v[168:171], v[224:227], v[72:75]
	s_setprio 0
	s_setprio 1
	v_mfma_f32_16x16x32_bf16 v[116:119], v[172:175], v[190:193], v[116:119]
	v_mfma_f32_16x16x32_bf16 v[112:115], v[182:185], v[190:193], v[112:115]
	v_mfma_f32_16x16x32_bf16 v[100:103], v[172:175], v[198:201], v[100:103]
	v_mfma_f32_16x16x32_bf16 v[96:99], v[182:185], v[198:201], v[96:99]
	v_mfma_f32_16x16x32_bf16 v[84:87], v[172:175], v[212:215], v[84:87]
	v_mfma_f32_16x16x32_bf16 v[80:83], v[182:185], v[212:215], v[80:83]
	v_mfma_f32_16x16x32_bf16 v[68:71], v[172:175], v[220:223], v[68:71]
	v_mfma_f32_16x16x32_bf16 v[64:67], v[182:185], v[220:223], v[64:67]
	v_mfma_f32_16x16x32_bf16 v[116:119], v[176:179], v[194:197], v[116:119]
	v_mfma_f32_16x16x32_bf16 v[112:115], v[186:189], v[194:197], v[112:115]
	v_mfma_f32_16x16x32_bf16 v[100:103], v[176:179], v[208:211], v[100:103]
	v_mfma_f32_16x16x32_bf16 v[96:99], v[186:189], v[208:211], v[96:99]
	v_mfma_f32_16x16x32_bf16 v[84:87], v[176:179], v[216:219], v[84:87]
	v_mfma_f32_16x16x32_bf16 v[80:83], v[186:189], v[216:219], v[80:83]
	v_mfma_f32_16x16x32_bf16 v[68:71], v[176:179], v[224:227], v[68:71]
	v_mfma_f32_16x16x32_bf16 v[64:67], v[186:189], v[224:227], v[64:67]
	s_setprio 0
	s_barrier
	s_add_i32 s3, s85, s34
	v_lshl_add_u64 v[202:203], s[62:63], 0, v[134:135]
	s_mov_b32 m0, s3
	ds_read_b128 v[190:193], v157 offset:16384
	ds_read_b128 v[194:197], v157 offset:17408
	ds_read_b128 v[198:201], v157 offset:18432
	ds_read_b128 v[208:211], v157 offset:19456
	ds_read_b128 v[212:215], v157 offset:20480
	ds_read_b128 v[216:219], v157 offset:21504
	ds_read_b128 v[220:223], v157 offset:22528
	ds_read_b128 v[224:227], v157 offset:23552
	global_load_lds_dwordx4 v[202:203], off
	s_add_i32 m0, s3, 0x2000
	s_add_u32 s14, s62, 0x40000
	v_lshl_add_u64 v[228:229], s[62:63], 0, v[138:139]
	s_addc_u32 s15, s63, 0
	s_add_i32 s3, s86, s34
	global_load_lds_dwordx4 v[228:229], off
	v_lshl_add_u64 v[230:231], s[14:15], 0, v[134:135]
	s_mov_b32 m0, s3
	global_load_lds_dwordx4 v[230:231], off
	v_lshl_add_u64 v[230:231], s[14:15], 0, v[138:139]
	s_add_i32 m0, s3, 0x2000
	s_nop 0
	global_load_lds_dwordx4 v[230:231], off
	s_waitcnt vmcnt(6)
	s_waitcnt lgkmcnt(0)
	s_barrier
	s_setprio 1
	s_waitcnt lgkmcnt(0)
	v_mfma_f32_16x16x32_bf16 v[60:63], v[148:151], v[190:193], v[60:63]
	v_mfma_f32_16x16x32_bf16 v[56:59], v[164:167], v[190:193], v[56:59]
	v_mfma_f32_16x16x32_bf16 v[44:47], v[148:151], v[198:201], v[44:47]
	v_mfma_f32_16x16x32_bf16 v[40:43], v[164:167], v[198:201], v[40:43]
	v_mfma_f32_16x16x32_bf16 v[28:31], v[148:151], v[212:215], v[28:31]
	v_mfma_f32_16x16x32_bf16 v[24:27], v[164:167], v[212:215], v[24:27]
	v_mfma_f32_16x16x32_bf16 v[12:15], v[148:151], v[220:223], v[12:15]
	v_mfma_f32_16x16x32_bf16 v[8:11], v[164:167], v[220:223], v[8:11]
	v_mfma_f32_16x16x32_bf16 v[60:63], v[160:163], v[194:197], v[60:63]
	v_mfma_f32_16x16x32_bf16 v[56:59], v[168:171], v[194:197], v[56:59]
	v_mfma_f32_16x16x32_bf16 v[44:47], v[160:163], v[208:211], v[44:47]
	v_mfma_f32_16x16x32_bf16 v[40:43], v[168:171], v[208:211], v[40:43]
	v_mfma_f32_16x16x32_bf16 v[28:31], v[160:163], v[216:219], v[28:31]
	v_mfma_f32_16x16x32_bf16 v[24:27], v[168:171], v[216:219], v[24:27]
	v_lshl_add_u64 v[230:231], s[64:65], 0, v[132:133]
	s_mov_b32 m0, s43
	s_nop 0
	global_load_lds_dwordx4 v[230:231], off
	v_mfma_f32_16x16x32_bf16 v[12:15], v[160:163], v[224:227], v[12:15]
	v_mfma_f32_16x16x32_bf16 v[8:11], v[168:171], v[224:227], v[8:11]
	s_setprio 0
	s_setprio 1
	v_mfma_f32_16x16x32_bf16 v[52:55], v[172:175], v[190:193], v[52:55]
	v_mfma_f32_16x16x32_bf16 v[48:51], v[182:185], v[190:193], v[48:51]
	v_mfma_f32_16x16x32_bf16 v[36:39], v[172:175], v[198:201], v[36:39]
	v_mfma_f32_16x16x32_bf16 v[32:35], v[182:185], v[198:201], v[32:35]
	v_mfma_f32_16x16x32_bf16 v[20:23], v[172:175], v[212:215], v[20:23]
	v_mfma_f32_16x16x32_bf16 v[16:19], v[182:185], v[212:215], v[16:19]
	v_mfma_f32_16x16x32_bf16 v[4:7], v[172:175], v[220:223], v[4:7]
	v_mfma_f32_16x16x32_bf16 v[0:3], v[182:185], v[220:223], v[0:3]
	v_mfma_f32_16x16x32_bf16 v[52:55], v[176:179], v[194:197], v[52:55]
	v_mfma_f32_16x16x32_bf16 v[48:51], v[186:189], v[194:197], v[48:51]
	v_mfma_f32_16x16x32_bf16 v[36:39], v[176:179], v[208:211], v[36:39]
	v_mfma_f32_16x16x32_bf16 v[32:35], v[186:189], v[208:211], v[32:35]
	v_mfma_f32_16x16x32_bf16 v[20:23], v[176:179], v[216:219], v[20:23]
	v_mfma_f32_16x16x32_bf16 v[16:19], v[186:189], v[216:219], v[16:19]
	v_lshl_add_u64 v[232:233], s[64:65], 0, v[136:137]
	s_mov_b32 m0, s59
	s_nop 0
	global_load_lds_dwordx4 v[232:233], off
	v_mfma_f32_16x16x32_bf16 v[4:7], v[176:179], v[224:227], v[4:7]
	v_mfma_f32_16x16x32_bf16 v[0:3], v[186:189], v[224:227], v[0:3]
	s_setprio 0
	s_barrier
; #define PG8_STAGE(bufoff, gbase, voff) do { _Pragma("unroll") for (int _i = 0; _i < 2; ++_i) \
;         __builtin_amdgcn_global_load_lds((const unsigned*)((const char*)(gbase) + (voff)[_i]), (PG8_LAS unsigned*)(lds + (bufoff) + ldsw + _i * 8192), 16, 0, 0); } while (0)
; #define PG8_LDA(dst, b, h) do { _Pragma("unroll") for (int m = 0; m < 4; ++m) _Pragma("unroll") for (int k = 0; k < 2; ++k) dst[m][k] = *(const PG8_LAS bf16x8*)(lds + PG8_SA(b, h) + aoff + m * 2048 + k * 1024); } while (0)
; #define PG8_LDB(dst, b, h) do { _Pragma("unroll") for (int n = 0; n < 2; ++n) _Pragma("unroll") for (int k = 0; k < 2; ++k) dst[n][k] = *(const PG8_LAS bf16x8*)(lds + PG8_SB(b, h) + boff + n * 2048 + k * 1024); } while (0)
; #define PG8_MMA(ai, bj, At, Bt) do { __builtin_amdgcn_s_setprio(1); _Pragma("unroll") for (int m = 0; m < 4; ++m) _Pragma("unroll") for (int n = 0; n < 2; ++n) _Pragma("unroll") for (int k = 0; k < 2; ++k) \
;         acc[ai][bj][m][n] = __builtin_amdgcn_mfma_f32_16x16x32_bf16(Bt[n][k], At[m][k], acc[ai][bj][m][n], 0, 0, 0); __builtin_amdgcn_s_setprio(0); } while (0)
; #define PG8_WAIT_V(n) asm volatile("s_waitcnt vmcnt(" #n ")" ::: "memory")
; #define PG8_WAIT_L(n) asm volatile("s_waitcnt lgkmcnt(" #n ")" ::: "memory")
; #define PG8_BAR __builtin_amdgcn_s_barrier()
; #define PG8_SCHED __builtin_amdgcn_sched_barrier(0)
; template <class Epi, class Sched, bool ALIGN_EPI = false, bool SP2 = false>
; __device__ __forceinline__ void gemm_phase(PG8_LAS unsigned char* lds, const Gemm g, const Sched& S, const Epi& E) {
;     ...
;             PG8_LDB(B0, 1, 0); PG8_LDB(B1, 1, 1); PG8_SCHED; PG8_LDA(At, 1, 0); PG8_STAGE(PG8_SA(0, 1), a2 + hstep, voffA);
;             PG8_WAIT_V(8); PG8_WAIT_L(0); PG8_BAR; PG8_MMA(0, 0, At, B0); PG8_MMA(0, 1, At, B1); PG8_BAR; PG8_SCHED;
;             PG8_LDA(At, 1, 1); PG8_STAGE(PG8_SB(1, 0), b3, voffB); PG8_STAGE(PG8_SB(1, 1), b3 + hstep, voffB); PG8_STAGE(PG8_SA(1, 0), a3, voffA);
;             PG8_WAIT_V(8); PG8_WAIT_L(0); PG8_BAR; PG8_MMA(1, 0, At, B0); PG8_MMA(1, 1, At, B1); PG8_BAR; PG8_SCHED;
	s_add_i32 s3, 0, 0x18000
	v_add_u32_e32 v159, s3, v131
	s_add_i32 s33, 0, 0x1c000
	ds_read_b128 v[148:151], v159
	ds_read_b128 v[160:163], v159 offset:1024
	ds_read_b128 v[164:167], v159 offset:2048
	ds_read_b128 v[168:171], v159 offset:3072
	v_add_u32_e32 v159, s33, v131
	ds_read_b128 v[172:175], v159
	ds_read_b128 v[176:179], v159 offset:1024
	ds_read_b128 v[182:185], v159 offset:2048
	ds_read_b128 v[186:189], v159 offset:3072
	s_add_u32 s14, s64, 0x40000
	s_addc_u32 s15, s65, 0
	s_mov_b32 m0, s66
	v_lshl_add_u64 v[234:235], s[14:15], 0, v[132:133]
	ds_read_b128 v[190:193], v157 offset:32768
	ds_read_b128 v[194:197], v157 offset:33792
	ds_read_b128 v[198:201], v157 offset:34816
	ds_read_b128 v[208:211], v157 offset:35840
	ds_read_b128 v[212:215], v157 offset:36864
	ds_read_b128 v[216:219], v157 offset:37888
	ds_read_b128 v[220:223], v157 offset:38912
	ds_read_b128 v[224:227], v157 offset:39936
	global_load_lds_dwordx4 v[234:235], off
	v_lshl_add_u64 v[234:235], s[14:15], 0, v[136:137]
	s_mov_b32 m0, s67
	s_nop 0
	global_load_lds_dwordx4 v[234:235], off
	s_waitcnt vmcnt(8)
	s_waitcnt lgkmcnt(0)
	s_barrier
	s_setprio 1
	s_waitcnt lgkmcnt(0)
	v_mfma_f32_16x16x32_bf16 v[124:127], v[148:151], v[190:193], v[124:127]
	v_mfma_f32_16x16x32_bf16 v[120:123], v[164:167], v[190:193], v[120:123]
	v_mfma_f32_16x16x32_bf16 v[108:111], v[148:151], v[198:201], v[108:111]
	v_mfma_f32_16x16x32_bf16 v[104:107], v[164:167], v[198:201], v[104:107]
	v_mfma_f32_16x16x32_bf16 v[92:95], v[148:151], v[212:215], v[92:95]
	v_mfma_f32_16x16x32_bf16 v[88:91], v[164:167], v[212:215], v[88:91]
	v_mfma_f32_16x16x32_bf16 v[76:79], v[148:151], v[220:223], v[76:79]
	v_mfma_f32_16x16x32_bf16 v[72:75], v[164:167], v[220:223], v[72:75]
	v_mfma_f32_16x16x32_bf16 v[124:127], v[160:163], v[194:197], v[124:127]
	v_mfma_f32_16x16x32_bf16 v[120:123], v[168:171], v[194:197], v[120:123]
	v_mfma_f32_16x16x32_bf16 v[108:111], v[160:163], v[208:211], v[108:111]
	v_mfma_f32_16x16x32_bf16 v[104:107], v[168:171], v[208:211], v[104:107]
	v_mfma_f32_16x16x32_bf16 v[92:95], v[160:163], v[216:219], v[92:95]
	v_mfma_f32_16x16x32_bf16 v[88:91], v[168:171], v[216:219], v[88:91]
	v_mfma_f32_16x16x32_bf16 v[76:79], v[160:163], v[224:227], v[76:79]
	v_mfma_f32_16x16x32_bf16 v[72:75], v[168:171], v[224:227], v[72:75]
	s_setprio 0
	s_setprio 1
	v_mfma_f32_16x16x32_bf16 v[116:119], v[172:175], v[190:193], v[116:119]
	v_mfma_f32_16x16x32_bf16 v[112:115], v[182:185], v[190:193], v[112:115]
	v_mfma_f32_16x16x32_bf16 v[100:103], v[172:175], v[198:201], v[100:103]
	v_mfma_f32_16x16x32_bf16 v[96:99], v[182:185], v[198:201], v[96:99]
	v_mfma_f32_16x16x32_bf16 v[84:87], v[172:175], v[212:215], v[84:87]
	v_mfma_f32_16x16x32_bf16 v[80:83], v[182:185], v[212:215], v[80:83]
	v_mfma_f32_16x16x32_bf16 v[68:71], v[172:175], v[220:223], v[68:71]
	v_mfma_f32_16x16x32_bf16 v[64:67], v[182:185], v[220:223], v[64:67]
	v_mfma_f32_16x16x32_bf16 v[116:119], v[176:179], v[194:197], v[116:119]
	v_mfma_f32_16x16x32_bf16 v[112:115], v[186:189], v[194:197], v[112:115]
	v_mfma_f32_16x16x32_bf16 v[100:103], v[176:179], v[208:211], v[100:103]
	v_mfma_f32_16x16x32_bf16 v[96:99], v[186:189], v[208:211], v[96:99]
	v_mfma_f32_16x16x32_bf16 v[84:87], v[176:179], v[216:219], v[84:87]
	v_mfma_f32_16x16x32_bf16 v[80:83], v[186:189], v[216:219], v[80:83]
	v_mfma_f32_16x16x32_bf16 v[68:71], v[176:179], v[224:227], v[68:71]
	v_mfma_f32_16x16x32_bf16 v[64:67], v[186:189], v[224:227], v[64:67]
	s_setprio 0
	s_barrier
	s_add_i32 s3, s3, s34
	v_lshl_add_u64 v[202:203], v[202:203], 0, s[38:39]
	s_mov_b32 m0, s3
	ds_read_b128 v[190:193], v157 offset:49152
	ds_read_b128 v[194:197], v157 offset:50176
	ds_read_b128 v[198:201], v157 offset:51200
	ds_read_b128 v[208:211], v157 offset:52224
	ds_read_b128 v[212:215], v157 offset:53248
	ds_read_b128 v[216:219], v157 offset:54272
	ds_read_b128 v[220:223], v157 offset:55296
	ds_read_b128 v[224:227], v157 offset:56320
	global_load_lds_dwordx4 v[202:203], off
	s_add_i32 m0, s3, 0x2000
	s_add_u32 s14, s62, 0x40080
	v_lshl_add_u64 v[202:203], v[228:229], 0, s[38:39]
	s_addc_u32 s15, s63, 0
	s_add_i32 s3, s33, s34
	global_load_lds_dwordx4 v[202:203], off
	v_lshl_add_u64 v[202:203], s[14:15], 0, v[134:135]
	s_mov_b32 m0, s3
	s_nop 0
	global_load_lds_dwordx4 v[202:203], off
	v_lshl_add_u64 v[202:203], s[14:15], 0, v[138:139]
	s_add_i32 m0, s3, 0x2000
	s_nop 0
	global_load_lds_dwordx4 v[202:203], off
	s_waitcnt vmcnt(6)
	s_waitcnt lgkmcnt(0)
	s_barrier
; #define PG8_BAR __builtin_amdgcn_s_barrier()
;     __device__ __forceinline__ void operator()(const f32x4 (&acc)[2][2][4][2], const Unit& u, int wr, int wc, int fr, int fq) const {
;         const int row0 = u.pm * BM + wr * 64 + fr, col0 = u.pn * BM + wc * 32 + 8 * fq;
; #pragma unroll
;         for (int ai = 0; ai < 2; ++ai)
; #pragma unroll
;             for (int m = 0; m < 4; ++m) { const int row = row0 + ai * HALF + m * 16; const size_t off = (size_t)row * 1024 + col0; float s = 0.f;
; #pragma unroll
;                 for (int bj = 0; bj < 2; ++bj) { f32x4 a0, a1;
;                     if (xin32) { const float* p = xin32 + off + bj * HALF; a0 = *(const f32x4*)p; a1 = *(const f32x4*)(p + 4); }
; template <class Epi, class Sched, bool ALIGN_EPI = false, bool SP2 = false>
; __device__ __forceinline__ void gemm_phase(PG8_LAS unsigned char* lds, const Gemm g, const Sched& S, const Epi& E) {
;     ...
;             PG8_WAIT_V(8); PG8_WAIT_L(0); PG8_BAR; PG8_MMA(1, 0, At, B0); PG8_MMA(1, 1, At, B1); PG8_BAR; PG8_SCHED;
;             } else {
;             PG8_LDB(B0, 0, 0); PG8_SCHED; PG8_LDA(At, 0, 0); PG8_STAGE(PG8_SA(1, 1), a1 + hstep, voffA);
;             PG8_WAIT_L(8); PG8_BAR; PG8_WAIT_L(0); PG8_MMA(0, 0, At, B0); PG8_BAR; PG8_SCHED;
;             PG8_LDB(B1, 0, 1); PG8_STAGE(PG8_SB(0, 0), b2, voffB);
;             PG8_BAR; PG8_WAIT_L(0); PG8_MMA(0, 1, At, B1); PG8_BAR;
;             PG8_LDA(At, 0, 1); PG8_STAGE(PG8_SA(0, 0), a2, voffA);
;             PG8_BAR; PG8_WAIT_L(0); PG8_MMA(1, 0, At, B0); PG8_BAR; PG8_SCHED;
;             PG8_STAGE(PG8_SB(0, 1), b2 + hstep, voffB);
;             PG8_WAIT_V(6); PG8_BAR; PG8_MMA(1, 1, At, B1); PG8_BAR;
;             PG8_LDB(B0, 1, 0); PG8_SCHED; PG8_LDA(At, 1, 0); PG8_STAGE(PG8_SA(0, 1), a2 + hstep, voffA);
;             PG8_WAIT_L(8); PG8_BAR; PG8_WAIT_L(0); PG8_MMA(0, 0, At, B0); PG8_BAR; PG8_SCHED;
;             PG8_LDB(B1, 1, 1); PG8_STAGE(PG8_SB(1, 0), b3, voffB);
;             PG8_BAR; PG8_WAIT_L(0); PG8_MMA(0, 1, At, B1); PG8_BAR;
;             PG8_LDA(At, 1, 1); PG8_STAGE(PG8_SA(1, 0), a3, voffA);
;             PG8_BAR; PG8_WAIT_L(0); PG8_MMA(1, 0, At, B0); PG8_BAR; PG8_SCHED;
;             PG8_STAGE(PG8_SB(1, 1), b3 + hstep, voffB);
;             PG8_WAIT_V(6); PG8_BAR; PG8_MMA(1, 1, At, B1); PG8_BAR;
;             }
;         }
;         if constexpr (ALIGN_EPI) { if (wr == 0) PG8_BAR; }
	s_setprio 1
	s_waitcnt lgkmcnt(0)
	v_mfma_f32_16x16x32_bf16 v[60:63], v[148:151], v[190:193], v[60:63]
	v_mfma_f32_16x16x32_bf16 v[56:59], v[164:167], v[190:193], v[56:59]
	v_mfma_f32_16x16x32_bf16 v[44:47], v[148:151], v[198:201], v[44:47]
	v_mfma_f32_16x16x32_bf16 v[40:43], v[164:167], v[198:201], v[40:43]
	v_mfma_f32_16x16x32_bf16 v[28:31], v[148:151], v[212:215], v[28:31]
	v_mfma_f32_16x16x32_bf16 v[24:27], v[164:167], v[212:215], v[24:27]
	v_mfma_f32_16x16x32_bf16 v[12:15], v[148:151], v[220:223], v[12:15]
	v_mfma_f32_16x16x32_bf16 v[8:11], v[164:167], v[220:223], v[8:11]
	v_mfma_f32_16x16x32_bf16 v[60:63], v[160:163], v[194:197], v[60:63]
	v_mfma_f32_16x16x32_bf16 v[56:59], v[168:171], v[194:197], v[56:59]
	v_mfma_f32_16x16x32_bf16 v[44:47], v[160:163], v[208:211], v[44:47]
	v_mfma_f32_16x16x32_bf16 v[40:43], v[168:171], v[208:211], v[40:43]
	v_mfma_f32_16x16x32_bf16 v[28:31], v[160:163], v[216:219], v[28:31]
	v_mfma_f32_16x16x32_bf16 v[24:27], v[168:171], v[216:219], v[24:27]
	v_lshl_add_u64 v[202:203], v[230:231], 0, s[38:39]
	s_mov_b32 m0, s75
	s_nop 0
	global_load_lds_dwordx4 v[202:203], off
	v_mfma_f32_16x16x32_bf16 v[12:15], v[160:163], v[224:227], v[12:15]
	v_mfma_f32_16x16x32_bf16 v[8:11], v[168:171], v[224:227], v[8:11]
	s_setprio 0
	s_setprio 1
	v_mfma_f32_16x16x32_bf16 v[52:55], v[172:175], v[190:193], v[52:55]
	v_mfma_f32_16x16x32_bf16 v[48:51], v[182:185], v[190:193], v[48:51]
	v_mfma_f32_16x16x32_bf16 v[36:39], v[172:175], v[198:201], v[36:39]
	v_mfma_f32_16x16x32_bf16 v[32:35], v[182:185], v[198:201], v[32:35]
	v_mfma_f32_16x16x32_bf16 v[20:23], v[172:175], v[212:215], v[20:23]
	v_mfma_f32_16x16x32_bf16 v[16:19], v[182:185], v[212:215], v[16:19]
	v_mfma_f32_16x16x32_bf16 v[4:7], v[172:175], v[220:223], v[4:7]
	v_mfma_f32_16x16x32_bf16 v[0:3], v[182:185], v[220:223], v[0:3]
	v_mfma_f32_16x16x32_bf16 v[52:55], v[176:179], v[194:197], v[52:55]
	v_mfma_f32_16x16x32_bf16 v[48:51], v[186:189], v[194:197], v[48:51]
	v_mfma_f32_16x16x32_bf16 v[36:39], v[176:179], v[208:211], v[36:39]
	v_mfma_f32_16x16x32_bf16 v[32:35], v[186:189], v[208:211], v[32:35]
	v_mfma_f32_16x16x32_bf16 v[20:23], v[176:179], v[216:219], v[20:23]
	v_mfma_f32_16x16x32_bf16 v[16:19], v[186:189], v[216:219], v[16:19]
	v_lshl_add_u64 v[202:203], v[232:233], 0, s[38:39]
	s_mov_b32 m0, s84
	s_nop 0
	global_load_lds_dwordx4 v[202:203], off
	v_mfma_f32_16x16x32_bf16 v[4:7], v[176:179], v[224:227], v[4:7]
	v_mfma_f32_16x16x32_bf16 v[0:3], v[186:189], v[224:227], v[0:3]
	s_setprio 0
	s_barrier
	s_add_i32 s92, s92, 2
	s_add_u32 s60, s60, 0x100
	s_addc_u32 s61, s61, 0
	s_add_u32 s90, s90, 0x100
	s_addc_u32 s91, s91, 0
	s_cmp_gt_u32 s92, 13
	s_cbranch_scc0 .LBB0_650
	s_and_b64 vcc, exec, s[44:45]
	s_cbranch_vccz .LBB0_653
.LBB0_653:
	v_lshl_add_u32 v150, s58, 8, v129
	v_ashrrev_i32_e32 v151, 31, v150
	v_lshl_or_b32 v148, s56, 8, v154
	v_lshlrev_b64 v[160:161], 11, v[150:151]
	v_ashrrev_i32_e32 v149, 31, v148
	v_lshl_add_u64 v[160:161], s[22:23], 0, v[160:161]
	v_lshl_add_u64 v[170:171], v[148:149], 1, v[160:161]
	global_load_dwordx4 v[162:165], v[170:171], off
	global_load_dwordx4 v[166:169], v[170:171], off offset:256
	v_and_b32_e32 v160, 64, v158
	v_xor_b32_e32 v159, 16, v158
	v_add_u32_e32 v160, 64, v160
	v_xor_b32_e32 v161, 32, v158
	v_cmp_lt_i32_e32 vcc, v159, v160
	s_waitcnt vmcnt(0)
	v_lshlrev_b32_e32 v172, 16, v162
	v_cndmask_b32_e32 v159, v158, v159, vcc
	v_cmp_lt_i32_e32 vcc, v161, v160
	v_and_b32_e32 v173, 0xffff0000, v162
	v_lshlrev_b32_e32 v162, 16, v163
	v_and_b32_e32 v163, 0xffff0000, v163
	v_lshlrev_b32_e32 v176, 16, v166
	v_and_b32_e32 v177, 0xffff0000, v166
	v_lshlrev_b32_e32 v166, 16, v167
	v_and_b32_e32 v167, 0xffff0000, v167
	v_cndmask_b32_e32 v161, v158, v161, vcc
	v_lshlrev_b32_e32 v174, 16, v164
	v_and_b32_e32 v175, 0xffff0000, v164
	v_lshlrev_b32_e32 v164, 16, v165
	v_and_b32_e32 v165, 0xffff0000, v165
	v_lshlrev_b32_e32 v178, 16, v168
	v_and_b32_e32 v179, 0xffff0000, v168
	v_lshlrev_b32_e32 v168, 16, v169
	v_and_b32_e32 v169, 0xffff0000, v169
	v_pk_add_f32 v[126:127], v[126:127], v[162:163]
	v_pk_add_f32 v[124:125], v[124:125], v[172:173]
	v_pk_add_f32 v[118:119], v[118:119], v[166:167]
	v_pk_add_f32 v[116:117], v[116:117], v[176:177]
	v_lshlrev_b32_e32 v160, 2, v159
	v_lshlrev_b32_e32 v159, 2, v161
	v_pk_add_f32 v[122:123], v[122:123], v[164:165]
	v_pk_add_f32 v[120:121], v[120:121], v[174:175]
	v_pk_add_f32 v[162:163], v[114:115], v[168:169]
	v_pk_add_f32 v[164:165], v[112:113], v[178:179]
	v_mul_f32_e32 v114, v125, v125
	v_mul_f32_e32 v115, v127, v127
	v_mul_f32_e32 v161, v117, v117
	v_mul_f32_e32 v166, v119, v119
	v_cvt_pk_bf16_f32 v112, v124, v125
	v_mul_f32_e32 v125, v121, v121
	v_mul_f32_e32 v167, v165, v165
	v_fmac_f32_e32 v114, v124, v124
	v_fmac_f32_e32 v115, v126, v126
	v_fmac_f32_e32 v161, v116, v116
	v_fmac_f32_e32 v166, v118, v118
	v_cvt_pk_bf16_f32 v113, v126, v127
	v_mul_f32_e32 v127, v123, v123
	v_mul_f32_e32 v168, v163, v163
	v_fmac_f32_e32 v125, v120, v120
	v_fmac_f32_e32 v167, v164, v164
	v_add_f32_e32 v114, v114, v115
	v_add_f32_e32 v115, v161, v166
	v_fmac_f32_e32 v127, v122, v122
	v_fmac_f32_e32 v168, v162, v162
	v_add_f32_e32 v114, v125, v114
	v_add_f32_e32 v115, v167, v115
	v_add_f32_e32 v114, v127, v114
	v_add_f32_e32 v115, v168, v115
	v_add_f32_e32 v124, v114, v115
	ds_bpermute_b32 v125, v160, v124
	v_cvt_pk_bf16_f32 v114, v120, v121
	v_cvt_pk_bf16_f32 v115, v122, v123
	global_store_dwordx4 v[170:171], v[112:115], off
	s_waitcnt lgkmcnt(0)
	s_nop 0
	v_add_f32_e32 v112, v124, v125
	ds_bpermute_b32 v113, v159, v112
	v_cvt_pk_bf16_f32 v114, v116, v117
	v_cvt_pk_bf16_f32 v115, v118, v119
	v_cvt_pk_bf16_f32 v116, v164, v165
	v_cvt_pk_bf16_f32 v117, v162, v163
	global_store_dwordx4 v[170:171], v[114:117], off offset:256
	s_and_saveexec_b64 s[56:57], s[6:7]
	s_cbranch_execz .LBB0_655
	s_waitcnt lgkmcnt(0)
	v_add_f32_e32 v112, v112, v113
	v_mul_f32_e32 v112, 0x4f800000, v112
	v_trunc_f32_e32 v112, v112
	v_mul_f32_e64 v113, |v112|, s87
	v_floor_f32_e32 v113, v113
	v_fma_f32 v114, v113, s88, |v112|
	v_cvt_u32_f32_e32 v114, v114
	v_cvt_u32_f32_e32 v113, v113
	v_ashrrev_i32_e32 v115, 31, v112
	v_xor_b32_e32 v112, v114, v115
	v_xor_b32_e32 v113, v113, v115
	v_sub_co_u32_e32 v112, vcc, v112, v115
	s_nop 1
	v_subb_co_u32_e32 v113, vcc, v113, v115, vcc
	v_lshl_add_u64 v[114:115], v[150:151], 3, s[10:11]
	global_atomic_add_x2 v[114:115], v[112:113], off

; #define PG8_BAR __builtin_amdgcn_s_barrier()
; template <class Epi, class Sched, bool ALIGN_EPI = false, bool SP2 = false>
; __device__ __forceinline__ void gemm_phase(PG8_LAS unsigned char* lds, const Gemm g, const Sched& S, const Epi& E) {
;     ...
;         if constexpr (ALIGN_EPI) { if (wr == 0) PG8_BAR; }
;         if constexpr (!Epi::AFTER_DRAIN) { E(acc, cur, wr, wc, fr, fq); S.done(cur); }
;         if (!has_next) break;
; #pragma unroll
;         for (int a = 0; a < 2; ++a)
; #pragma unroll
;             for (int b = 0; b < 2; ++b)
; #pragma unroll
;                 for (int m = 0; m < 4; ++m)
; #pragma unroll
;                     for (int n = 0; n < 2; ++n) acc[a][b][m][n] = (f32x4){0.f, 0.f, 0.f, 0.f};
;         cur = nxt; cA = nA; cB = nB; ++ui;
;         if constexpr (ALIGN_EPI) { if (wr == 1) PG8_BAR; }
.LBB0_669:
	s_or_b64 exec, exec, s[56:57]
	s_andn2_b64 vcc, exec, s[8:9]
	s_mov_b64 s[8:9], -1
	s_cmp_eq_u64 s[44:45], 0
	s_cbranch_scc1 .Lxpost_2
	s_barrier
.Lxpost_2:
	s_cbranch_vccnz .LBB0_642
	s_andn2_b64 vcc, exec, s[36:37]
	s_cbranch_vccnz .LBB0_641
	s_barrier
	s_branch .LBB0_641

; #define PG8_STAGE(bufoff, gbase, voff) do { _Pragma("unroll") for (int _i = 0; _i < 2; ++_i) \
;         __builtin_amdgcn_global_load_lds((const unsigned*)((const char*)(gbase) + (voff)[_i]), (PG8_LAS unsigned*)(lds + (bufoff) + ldsw + _i * 8192), 16, 0, 0); } while (0)
; #define PG8_LDA(dst, b, h) do { _Pragma("unroll") for (int m = 0; m < 4; ++m) _Pragma("unroll") for (int k = 0; k < 2; ++k) dst[m][k] = *(const PG8_LAS bf16x8*)(lds + PG8_SA(b, h) + aoff + m * 2048 + k * 1024); } while (0)
; #define PG8_LDB(dst, b, h) do { _Pragma("unroll") for (int n = 0; n < 2; ++n) _Pragma("unroll") for (int k = 0; k < 2; ++k) dst[n][k] = *(const PG8_LAS bf16x8*)(lds + PG8_SB(b, h) + boff + n * 2048 + k * 1024); } while (0)
; #define PG8_MMA(ai, bj, At, Bt) do { __builtin_amdgcn_s_setprio(1); _Pragma("unroll") for (int m = 0; m < 4; ++m) _Pragma("unroll") for (int n = 0; n < 2; ++n) _Pragma("unroll") for (int k = 0; k < 2; ++k) \
;         acc[ai][bj][m][n] = __builtin_amdgcn_mfma_f32_16x16x32_bf16(Bt[n][k], At[m][k], acc[ai][bj][m][n], 0, 0, 0); __builtin_amdgcn_s_setprio(0); } while (0)
; #define PG8_BAR __builtin_amdgcn_s_barrier()
; template <class Epi, class Sched, bool ALIGN_EPI = false, bool SP2 = false>
; __device__ __forceinline__ void gemm_phase(PG8_LAS unsigned char* lds, const Gemm g, const Sched& S, const Epi& E) {
;     ...
;         const bool has_next = S.next(ui + 1, nxt);
;         const char* nA = has_next ? (const char*)g.A + (size_t)nxt.pm * tstep : cA; const char* nB = has_next ? (const char*)g.Bt + (size_t)nxt.pn * tstep : cB;
;         for (int t = 0; t < nt; t += 2) {
;             const bool last = (t == nt - 2);
;             const char* a1 = cA + (size_t)(t + 1) * kstep;
;             const char* a2 = last ? nA : cA + (size_t)(t + 2) * kstep; const char* b2 = last ? nB : cB + (size_t)(t + 2) * kstep;
;             const char* a3 = a2 + kstep; const char* b3 = b2 + kstep;
;             if (last && has_next) S.a_ready(nxt);
;             if constexpr (SP2) {
;             PG8_LDB(B0, 0, 0); PG8_LDB(B1, 0, 1); PG8_SCHED; PG8_LDA(At, 0, 0); PG8_STAGE(PG8_SA(1, 1), a1 + hstep, voffA);
;             PG8_WAIT_V(8); PG8_WAIT_L(0); PG8_BAR; PG8_MMA(0, 0, At, B0); PG8_MMA(0, 1, At, B1); PG8_BAR; PG8_SCHED;
;             PG8_LDA(At, 0, 1); PG8_STAGE(PG8_SB(0, 0), b2, voffB); PG8_STAGE(PG8_SB(0, 1), b2 + hstep, voffB); PG8_STAGE(PG8_SA(0, 0), a2, voffA);
.LBB0_737:
	s_ashr_i32 s51, s50, 31
	s_lshl_b64 s[14:15], s[50:51], 19
	s_add_u32 s52, s22, s14
	s_addc_u32 s53, s23, s15
	s_and_b64 s[14:15], s[8:9], exec
	s_cselect_b32 s51, s53, s57
	s_cselect_b32 s82, s52, s56
	s_ashr_i32 s49, s48, 31
	s_lshl_b64 s[14:15], s[48:49], 19
	v_readlane_b32 s3, v250, 15
	s_add_u32 s54, s3, s14
	v_readlane_b32 s3, v250, 16
	s_addc_u32 s55, s3, s15
	s_and_b64 s[14:15], s[8:9], exec
	s_cselect_b32 s49, s55, s59
	s_cselect_b32 s83, s54, s58
	s_add_u32 s56, s56, 0x40080
	s_addc_u32 s57, s57, 0
	s_add_u32 s84, s58, 0x100
	s_addc_u32 s85, s59, 0
	s_mov_b32 s86, -2
	s_waitcnt vmcnt(0)
	ds_read_b128 v[148:151], v155
	ds_read_b128 v[160:163], v155 offset:1024
	ds_read_b128 v[164:167], v155 offset:2048
	ds_read_b128 v[168:171], v155 offset:3072
	ds_read_b128 v[172:175], v156
	ds_read_b128 v[176:179], v156 offset:1024
	ds_read_b128 v[182:185], v156 offset:2048
	ds_read_b128 v[186:189], v156 offset:3072
	s_add_u32 s3, s56, 0xfffc0080
	s_addc_u32 s14, s57, -1
	s_cmp_eq_u32 s86, 12
	s_cselect_b32 s61, s51, s14
	s_cselect_b32 s60, s82, s3
	s_cselect_b32 s59, s49, s85
	s_cselect_b32 s58, s83, s84
	v_lshl_add_u64 v[202:203], s[56:57], 0, v[140:141]
	s_add_i32 m0, s43, 0xc000
	ds_read_b128 v[190:193], v157
	ds_read_b128 v[194:197], v157 offset:1024
	ds_read_b128 v[198:201], v157 offset:2048
	ds_read_b128 v[208:211], v157 offset:3072
	ds_read_b128 v[212:215], v157 offset:4096
	ds_read_b128 v[216:219], v157 offset:5120
	ds_read_b128 v[220:223], v157 offset:6144
	ds_read_b128 v[224:227], v157 offset:7168
	global_load_lds_dwordx4 v[202:203], off
	v_lshl_add_u64 v[202:203], s[56:57], 0, v[142:143]
	s_add_i32 m0, s43, 0xe000
	s_nop 0
	global_load_lds_dwordx4 v[202:203], off
	s_waitcnt vmcnt(8)
	s_waitcnt lgkmcnt(0)
	s_barrier
	s_setprio 1
	s_waitcnt lgkmcnt(0)
	v_mfma_f32_16x16x32_bf16 v[124:127], v[148:151], v[190:193], 0
	v_mfma_f32_16x16x32_bf16 v[120:123], v[164:167], v[190:193], 0
	v_mfma_f32_16x16x32_bf16 v[108:111], v[148:151], v[198:201], 0
	v_mfma_f32_16x16x32_bf16 v[104:107], v[164:167], v[198:201], 0
	v_mfma_f32_16x16x32_bf16 v[92:95], v[148:151], v[212:215], 0
	v_mfma_f32_16x16x32_bf16 v[88:91], v[164:167], v[212:215], 0
	v_mfma_f32_16x16x32_bf16 v[76:79], v[148:151], v[220:223], 0
	v_mfma_f32_16x16x32_bf16 v[72:75], v[164:167], v[220:223], 0
	v_mfma_f32_16x16x32_bf16 v[124:127], v[160:163], v[194:197], v[124:127]
	v_mfma_f32_16x16x32_bf16 v[120:123], v[168:171], v[194:197], v[120:123]
	v_mfma_f32_16x16x32_bf16 v[108:111], v[160:163], v[208:211], v[108:111]
	v_mfma_f32_16x16x32_bf16 v[104:107], v[168:171], v[208:211], v[104:107]
	v_mfma_f32_16x16x32_bf16 v[92:95], v[160:163], v[216:219], v[92:95]
	v_mfma_f32_16x16x32_bf16 v[88:91], v[168:171], v[216:219], v[88:91]
	v_mfma_f32_16x16x32_bf16 v[76:79], v[160:163], v[224:227], v[76:79]
	v_mfma_f32_16x16x32_bf16 v[72:75], v[168:171], v[224:227], v[72:75]
	s_setprio 0
	s_setprio 1
	v_mfma_f32_16x16x32_bf16 v[116:119], v[172:175], v[190:193], 0
	v_mfma_f32_16x16x32_bf16 v[112:115], v[182:185], v[190:193], 0
	v_mfma_f32_16x16x32_bf16 v[100:103], v[172:175], v[198:201], 0
	v_mfma_f32_16x16x32_bf16 v[96:99], v[182:185], v[198:201], 0
	v_mfma_f32_16x16x32_bf16 v[84:87], v[172:175], v[212:215], 0
	v_mfma_f32_16x16x32_bf16 v[80:83], v[182:185], v[212:215], 0
	v_mfma_f32_16x16x32_bf16 v[68:71], v[172:175], v[220:223], 0
	v_mfma_f32_16x16x32_bf16 v[64:67], v[182:185], v[220:223], 0
	v_mfma_f32_16x16x32_bf16 v[116:119], v[176:179], v[194:197], v[116:119]
	v_mfma_f32_16x16x32_bf16 v[112:115], v[186:189], v[194:197], v[112:115]
	v_mfma_f32_16x16x32_bf16 v[100:103], v[176:179], v[208:211], v[100:103]
	v_mfma_f32_16x16x32_bf16 v[96:99], v[186:189], v[208:211], v[96:99]
	v_mfma_f32_16x16x32_bf16 v[84:87], v[176:179], v[216:219], v[84:87]
	v_mfma_f32_16x16x32_bf16 v[80:83], v[186:189], v[216:219], v[80:83]
	v_mfma_f32_16x16x32_bf16 v[68:71], v[176:179], v[224:227], v[68:71]
	v_mfma_f32_16x16x32_bf16 v[64:67], v[186:189], v[224:227], v[64:67]
	s_setprio 0
	s_barrier
	s_add_i32 s3, s74, s34
	v_lshl_add_u64 v[202:203], s[58:59], 0, v[136:137]
	s_mov_b32 m0, s3
	ds_read_b128 v[190:193], v157 offset:16384
	ds_read_b128 v[194:197], v157 offset:17408
	ds_read_b128 v[198:201], v157 offset:18432
	ds_read_b128 v[208:211], v157 offset:19456
	ds_read_b128 v[212:215], v157 offset:20480
	ds_read_b128 v[216:219], v157 offset:21504
	ds_read_b128 v[220:223], v157 offset:22528
	ds_read_b128 v[224:227], v157 offset:23552
	global_load_lds_dwordx4 v[202:203], off
	s_add_i32 m0, s3, 0x2000
	s_add_u32 s14, s58, 0x40000
	v_lshl_add_u64 v[228:229], s[58:59], 0, v[132:133]
	s_addc_u32 s15, s59, 0
	s_add_i32 s3, s75, s34
	global_load_lds_dwordx4 v[228:229], off
	v_lshl_add_u64 v[230:231], s[14:15], 0, v[136:137]
	s_mov_b32 m0, s3
	global_load_lds_dwordx4 v[230:231], off
	v_lshl_add_u64 v[230:231], s[14:15], 0, v[132:133]
	s_add_i32 m0, s3, 0x2000
	s_nop 0
	global_load_lds_dwordx4 v[230:231], off
	s_waitcnt vmcnt(6)
	s_waitcnt lgkmcnt(0)
	s_barrier
; #define PG8_STAGE(bufoff, gbase, voff) do { _Pragma("unroll") for (int _i = 0; _i < 2; ++_i) \
;         __builtin_amdgcn_global_load_lds((const unsigned*)((const char*)(gbase) + (voff)[_i]), (PG8_LAS unsigned*)(lds + (bufoff) + ldsw + _i * 8192), 16, 0, 0); } while (0)
; #define PG8_LDA(dst, b, h) do { _Pragma("unroll") for (int m = 0; m < 4; ++m) _Pragma("unroll") for (int k = 0; k < 2; ++k) dst[m][k] = *(const PG8_LAS bf16x8*)(lds + PG8_SA(b, h) + aoff + m * 2048 + k * 1024); } while (0)
; #define PG8_LDB(dst, b, h) do { _Pragma("unroll") for (int n = 0; n < 2; ++n) _Pragma("unroll") for (int k = 0; k < 2; ++k) dst[n][k] = *(const PG8_LAS bf16x8*)(lds + PG8_SB(b, h) + boff + n * 2048 + k * 1024); } while (0)
; #define PG8_MMA(ai, bj, At, Bt) do { __builtin_amdgcn_s_setprio(1); _Pragma("unroll") for (int m = 0; m < 4; ++m) _Pragma("unroll") for (int n = 0; n < 2; ++n) _Pragma("unroll") for (int k = 0; k < 2; ++k) \
;         acc[ai][bj][m][n] = __builtin_amdgcn_mfma_f32_16x16x32_bf16(Bt[n][k], At[m][k], acc[ai][bj][m][n], 0, 0, 0); __builtin_amdgcn_s_setprio(0); } while (0)
; #define PG8_WAIT_V(n) asm volatile("s_waitcnt vmcnt(" #n ")" ::: "memory")
; #define PG8_WAIT_L(n) asm volatile("s_waitcnt lgkmcnt(" #n ")" ::: "memory")
; #define PG8_BAR __builtin_amdgcn_s_barrier()
; #define PG8_SCHED __builtin_amdgcn_sched_barrier(0)
; template <class Epi, class Sched, bool ALIGN_EPI = false, bool SP2 = false>
; __device__ __forceinline__ void gemm_phase(PG8_LAS unsigned char* lds, const Gemm g, const Sched& S, const Epi& E) {
;     ...
;             PG8_LDA(At, 0, 1); PG8_STAGE(PG8_SB(0, 0), b2, voffB); PG8_STAGE(PG8_SB(0, 1), b2 + hstep, voffB); PG8_STAGE(PG8_SA(0, 0), a2, voffA);
;             PG8_WAIT_V(8); PG8_WAIT_L(0); PG8_BAR; PG8_MMA(1, 0, At, B0); PG8_MMA(1, 1, At, B1); PG8_BAR; PG8_SCHED;
;             PG8_LDB(B0, 1, 0); PG8_LDB(B1, 1, 1); PG8_SCHED; PG8_LDA(At, 1, 0); PG8_STAGE(PG8_SA(0, 1), a2 + hstep, voffA);
;             PG8_WAIT_V(8); PG8_WAIT_L(0); PG8_BAR; PG8_MMA(0, 0, At, B0); PG8_MMA(0, 1, At, B1); PG8_BAR; PG8_SCHED;
	s_setprio 1
	s_waitcnt lgkmcnt(0)
	v_mfma_f32_16x16x32_bf16 v[60:63], v[148:151], v[190:193], 0
	v_mfma_f32_16x16x32_bf16 v[56:59], v[164:167], v[190:193], 0
	v_mfma_f32_16x16x32_bf16 v[44:47], v[148:151], v[198:201], 0
	v_mfma_f32_16x16x32_bf16 v[40:43], v[164:167], v[198:201], 0
	v_mfma_f32_16x16x32_bf16 v[28:31], v[148:151], v[212:215], 0
	v_mfma_f32_16x16x32_bf16 v[24:27], v[164:167], v[212:215], 0
	v_mfma_f32_16x16x32_bf16 v[12:15], v[148:151], v[220:223], 0
	v_mfma_f32_16x16x32_bf16 v[8:11], v[164:167], v[220:223], 0
	v_mfma_f32_16x16x32_bf16 v[60:63], v[160:163], v[194:197], v[60:63]
	v_mfma_f32_16x16x32_bf16 v[56:59], v[168:171], v[194:197], v[56:59]
	v_mfma_f32_16x16x32_bf16 v[44:47], v[160:163], v[208:211], v[44:47]
	v_mfma_f32_16x16x32_bf16 v[40:43], v[168:171], v[208:211], v[40:43]
	v_mfma_f32_16x16x32_bf16 v[28:31], v[160:163], v[216:219], v[28:31]
	v_mfma_f32_16x16x32_bf16 v[24:27], v[168:171], v[216:219], v[24:27]
	v_lshl_add_u64 v[230:231], s[60:61], 0, v[138:139]
	s_mov_b32 m0, s43
	s_nop 0
	global_load_lds_dwordx4 v[230:231], off
	v_mfma_f32_16x16x32_bf16 v[12:15], v[160:163], v[224:227], v[12:15]
	v_mfma_f32_16x16x32_bf16 v[8:11], v[168:171], v[224:227], v[8:11]
	s_setprio 0
	s_setprio 1
	v_mfma_f32_16x16x32_bf16 v[52:55], v[172:175], v[190:193], 0
	v_mfma_f32_16x16x32_bf16 v[48:51], v[182:185], v[190:193], 0
	v_mfma_f32_16x16x32_bf16 v[36:39], v[172:175], v[198:201], 0
	v_mfma_f32_16x16x32_bf16 v[32:35], v[182:185], v[198:201], 0
	v_mfma_f32_16x16x32_bf16 v[20:23], v[172:175], v[212:215], 0
	v_mfma_f32_16x16x32_bf16 v[16:19], v[182:185], v[212:215], 0
	v_mfma_f32_16x16x32_bf16 v[4:7], v[172:175], v[220:223], 0
	v_mfma_f32_16x16x32_bf16 v[0:3], v[182:185], v[220:223], 0
	v_mfma_f32_16x16x32_bf16 v[52:55], v[176:179], v[194:197], v[52:55]
	v_mfma_f32_16x16x32_bf16 v[48:51], v[186:189], v[194:197], v[48:51]
	v_mfma_f32_16x16x32_bf16 v[36:39], v[176:179], v[208:211], v[36:39]
	v_mfma_f32_16x16x32_bf16 v[32:35], v[186:189], v[208:211], v[32:35]
	v_mfma_f32_16x16x32_bf16 v[20:23], v[176:179], v[216:219], v[20:23]
	v_mfma_f32_16x16x32_bf16 v[16:19], v[186:189], v[216:219], v[16:19]
	v_lshl_add_u64 v[232:233], s[60:61], 0, v[134:135]
	s_mov_b32 m0, s62
	s_nop 0
	global_load_lds_dwordx4 v[232:233], off
	v_mfma_f32_16x16x32_bf16 v[4:7], v[176:179], v[224:227], v[4:7]
	v_mfma_f32_16x16x32_bf16 v[0:3], v[186:189], v[224:227], v[0:3]
	s_setprio 0
	s_barrier
	s_add_i32 s3, 0, 0x18000
	v_add_u32_e32 v159, s3, v131
	s_add_i32 s33, 0, 0x1c000
	ds_read_b128 v[148:151], v159
	ds_read_b128 v[160:163], v159 offset:1024
	ds_read_b128 v[164:167], v159 offset:2048
	ds_read_b128 v[168:171], v159 offset:3072
	v_add_u32_e32 v159, s33, v131
	ds_read_b128 v[172:175], v159
	ds_read_b128 v[176:179], v159 offset:1024
	ds_read_b128 v[182:185], v159 offset:2048
	ds_read_b128 v[186:189], v159 offset:3072
	s_add_u32 s14, s60, 0x40000
	s_addc_u32 s15, s61, 0
	s_mov_b32 m0, s63
	v_lshl_add_u64 v[234:235], s[14:15], 0, v[138:139]
	ds_read_b128 v[190:193], v157 offset:32768
	ds_read_b128 v[194:197], v157 offset:33792
	ds_read_b128 v[198:201], v157 offset:34816
	ds_read_b128 v[208:211], v157 offset:35840
	ds_read_b128 v[212:215], v157 offset:36864
	ds_read_b128 v[216:219], v157 offset:37888
	ds_read_b128 v[220:223], v157 offset:38912
	ds_read_b128 v[224:227], v157 offset:39936
	global_load_lds_dwordx4 v[234:235], off
	v_lshl_add_u64 v[234:235], s[14:15], 0, v[134:135]
	s_mov_b32 m0, s64
	s_nop 0
	global_load_lds_dwordx4 v[234:235], off
	s_waitcnt vmcnt(8)
	s_waitcnt lgkmcnt(0)
	s_barrier
	s_setprio 1
	s_waitcnt lgkmcnt(0)
	v_mfma_f32_16x16x32_bf16 v[124:127], v[148:151], v[190:193], v[124:127]
	v_mfma_f32_16x16x32_bf16 v[120:123], v[164:167], v[190:193], v[120:123]
	v_mfma_f32_16x16x32_bf16 v[108:111], v[148:151], v[198:201], v[108:111]
	v_mfma_f32_16x16x32_bf16 v[104:107], v[164:167], v[198:201], v[104:107]
	v_mfma_f32_16x16x32_bf16 v[92:95], v[148:151], v[212:215], v[92:95]
	v_mfma_f32_16x16x32_bf16 v[88:91], v[164:167], v[212:215], v[88:91]
	v_mfma_f32_16x16x32_bf16 v[76:79], v[148:151], v[220:223], v[76:79]
	v_mfma_f32_16x16x32_bf16 v[72:75], v[164:167], v[220:223], v[72:75]
	v_mfma_f32_16x16x32_bf16 v[124:127], v[160:163], v[194:197], v[124:127]
	v_mfma_f32_16x16x32_bf16 v[120:123], v[168:171], v[194:197], v[120:123]
	v_mfma_f32_16x16x32_bf16 v[108:111], v[160:163], v[208:211], v[108:111]
	v_mfma_f32_16x16x32_bf16 v[104:107], v[168:171], v[208:211], v[104:107]
	v_mfma_f32_16x16x32_bf16 v[92:95], v[160:163], v[216:219], v[92:95]
	v_mfma_f32_16x16x32_bf16 v[88:91], v[168:171], v[216:219], v[88:91]
	v_mfma_f32_16x16x32_bf16 v[76:79], v[160:163], v[224:227], v[76:79]
	v_mfma_f32_16x16x32_bf16 v[72:75], v[168:171], v[224:227], v[72:75]
	s_setprio 0
	s_setprio 1
	v_mfma_f32_16x16x32_bf16 v[116:119], v[172:175], v[190:193], v[116:119]
	v_mfma_f32_16x16x32_bf16 v[112:115], v[182:185], v[190:193], v[112:115]
	v_mfma_f32_16x16x32_bf16 v[100:103], v[172:175], v[198:201], v[100:103]
	v_mfma_f32_16x16x32_bf16 v[96:99], v[182:185], v[198:201], v[96:99]
	v_mfma_f32_16x16x32_bf16 v[84:87], v[172:175], v[212:215], v[84:87]
	v_mfma_f32_16x16x32_bf16 v[80:83], v[182:185], v[212:215], v[80:83]
	v_mfma_f32_16x16x32_bf16 v[68:71], v[172:175], v[220:223], v[68:71]
	v_mfma_f32_16x16x32_bf16 v[64:67], v[182:185], v[220:223], v[64:67]
	v_mfma_f32_16x16x32_bf16 v[116:119], v[176:179], v[194:197], v[116:119]
	v_mfma_f32_16x16x32_bf16 v[112:115], v[186:189], v[194:197], v[112:115]
	v_mfma_f32_16x16x32_bf16 v[100:103], v[176:179], v[208:211], v[100:103]
	v_mfma_f32_16x16x32_bf16 v[96:99], v[186:189], v[208:211], v[96:99]
	v_mfma_f32_16x16x32_bf16 v[84:87], v[176:179], v[216:219], v[84:87]
	v_mfma_f32_16x16x32_bf16 v[80:83], v[186:189], v[216:219], v[80:83]
	v_mfma_f32_16x16x32_bf16 v[68:71], v[176:179], v[224:227], v[68:71]
	v_mfma_f32_16x16x32_bf16 v[64:67], v[186:189], v[224:227], v[64:67]
	s_setprio 0
	s_barrier
; #define PG8_STAGE(bufoff, gbase, voff) do { _Pragma("unroll") for (int _i = 0; _i < 2; ++_i) \
;         __builtin_amdgcn_global_load_lds((const unsigned*)((const char*)(gbase) + (voff)[_i]), (PG8_LAS unsigned*)(lds + (bufoff) + ldsw + _i * 8192), 16, 0, 0); } while (0)
; #define PG8_LDA(dst, b, h) do { _Pragma("unroll") for (int m = 0; m < 4; ++m) _Pragma("unroll") for (int k = 0; k < 2; ++k) dst[m][k] = *(const PG8_LAS bf16x8*)(lds + PG8_SA(b, h) + aoff + m * 2048 + k * 1024); } while (0)
; #define PG8_LDB(dst, b, h) do { _Pragma("unroll") for (int n = 0; n < 2; ++n) _Pragma("unroll") for (int k = 0; k < 2; ++k) dst[n][k] = *(const PG8_LAS bf16x8*)(lds + PG8_SB(b, h) + boff + n * 2048 + k * 1024); } while (0)
; #define PG8_MMA(ai, bj, At, Bt) do { __builtin_amdgcn_s_setprio(1); _Pragma("unroll") for (int m = 0; m < 4; ++m) _Pragma("unroll") for (int n = 0; n < 2; ++n) _Pragma("unroll") for (int k = 0; k < 2; ++k) \
;         acc[ai][bj][m][n] = __builtin_amdgcn_mfma_f32_16x16x32_bf16(Bt[n][k], At[m][k], acc[ai][bj][m][n], 0, 0, 0); __builtin_amdgcn_s_setprio(0); } while (0)
; #define PG8_WAIT_V(n) asm volatile("s_waitcnt vmcnt(" #n ")" ::: "memory")
; template <class Epi, class Sched, bool ALIGN_EPI = false, bool SP2 = false>
; __device__ __forceinline__ void gemm_phase(PG8_LAS unsigned char* lds, const Gemm g, const Sched& S, const Epi& E) {
;     ...
;             PG8_LDB(B0, 0, 0); PG8_LDB(B1, 0, 1); PG8_SCHED; PG8_LDA(At, 0, 0); PG8_STAGE(PG8_SA(1, 1), a1 + hstep, voffA);
;             PG8_WAIT_V(8); PG8_WAIT_L(0); PG8_BAR; PG8_MMA(0, 0, At, B0); PG8_MMA(0, 1, At, B1); PG8_BAR; PG8_SCHED;
;             PG8_LDA(At, 0, 1); PG8_STAGE(PG8_SB(0, 0), b2, voffB); PG8_STAGE(PG8_SB(0, 1), b2 + hstep, voffB); PG8_STAGE(PG8_SA(0, 0), a2, voffA);
;             PG8_WAIT_V(8); PG8_WAIT_L(0); PG8_BAR; PG8_MMA(1, 0, At, B0); PG8_MMA(1, 1, At, B1); PG8_BAR; PG8_SCHED;
;             PG8_LDB(B0, 1, 0); PG8_LDB(B1, 1, 1); PG8_SCHED; PG8_LDA(At, 1, 0); PG8_STAGE(PG8_SA(0, 1), a2 + hstep, voffA);
;             PG8_WAIT_V(8); PG8_WAIT_L(0); PG8_BAR; PG8_MMA(0, 0, At, B0); PG8_MMA(0, 1, At, B1); PG8_BAR; PG8_SCHED;
;             PG8_LDA(At, 1, 1); PG8_STAGE(PG8_SB(1, 0), b3, voffB); PG8_STAGE(PG8_SB(1, 1), b3 + hstep, voffB); PG8_STAGE(PG8_SA(1, 0), a3, voffA);
;             PG8_WAIT_V(8); PG8_WAIT_L(0); PG8_BAR; PG8_MMA(1, 0, At, B0); PG8_MMA(1, 1, At, B1); PG8_BAR; PG8_SCHED;
	s_add_i32 s3, s3, s34
	v_lshl_add_u64 v[202:203], v[202:203], 0, s[38:39]
	s_mov_b32 m0, s3
	ds_read_b128 v[190:193], v157 offset:49152
	ds_read_b128 v[194:197], v157 offset:50176
	ds_read_b128 v[198:201], v157 offset:51200
	ds_read_b128 v[208:211], v157 offset:52224
	ds_read_b128 v[212:215], v157 offset:53248
	ds_read_b128 v[216:219], v157 offset:54272
	ds_read_b128 v[220:223], v157 offset:55296
	ds_read_b128 v[224:227], v157 offset:56320
	global_load_lds_dwordx4 v[202:203], off
	s_add_i32 m0, s3, 0x2000
	s_add_u32 s14, s58, 0x40080
	v_lshl_add_u64 v[202:203], v[228:229], 0, s[38:39]
	s_addc_u32 s15, s59, 0
	s_add_i32 s3, s33, s34
	global_load_lds_dwordx4 v[202:203], off
	v_lshl_add_u64 v[202:203], s[14:15], 0, v[136:137]
	s_mov_b32 m0, s3
	s_nop 0
	global_load_lds_dwordx4 v[202:203], off
	v_lshl_add_u64 v[202:203], s[14:15], 0, v[132:133]
	s_add_i32 m0, s3, 0x2000
	s_nop 0
	global_load_lds_dwordx4 v[202:203], off
	s_waitcnt vmcnt(6)
	s_waitcnt lgkmcnt(0)
	s_barrier
	s_setprio 1
	s_waitcnt lgkmcnt(0)
	v_mfma_f32_16x16x32_bf16 v[60:63], v[148:151], v[190:193], v[60:63]
	v_mfma_f32_16x16x32_bf16 v[56:59], v[164:167], v[190:193], v[56:59]
	v_mfma_f32_16x16x32_bf16 v[44:47], v[148:151], v[198:201], v[44:47]
	v_mfma_f32_16x16x32_bf16 v[40:43], v[164:167], v[198:201], v[40:43]
	v_mfma_f32_16x16x32_bf16 v[28:31], v[148:151], v[212:215], v[28:31]
	v_mfma_f32_16x16x32_bf16 v[24:27], v[164:167], v[212:215], v[24:27]
	v_mfma_f32_16x16x32_bf16 v[12:15], v[148:151], v[220:223], v[12:15]
	v_mfma_f32_16x16x32_bf16 v[8:11], v[164:167], v[220:223], v[8:11]
	v_mfma_f32_16x16x32_bf16 v[60:63], v[160:163], v[194:197], v[60:63]
	v_mfma_f32_16x16x32_bf16 v[56:59], v[168:171], v[194:197], v[56:59]
	v_mfma_f32_16x16x32_bf16 v[44:47], v[160:163], v[208:211], v[44:47]
	v_mfma_f32_16x16x32_bf16 v[40:43], v[168:171], v[208:211], v[40:43]
	v_mfma_f32_16x16x32_bf16 v[28:31], v[160:163], v[216:219], v[28:31]
	v_mfma_f32_16x16x32_bf16 v[24:27], v[168:171], v[216:219], v[24:27]
	v_lshl_add_u64 v[202:203], v[230:231], 0, s[38:39]
	s_mov_b32 m0, s66
	s_nop 0
	global_load_lds_dwordx4 v[202:203], off
	v_mfma_f32_16x16x32_bf16 v[12:15], v[160:163], v[224:227], v[12:15]
	v_mfma_f32_16x16x32_bf16 v[8:11], v[168:171], v[224:227], v[8:11]
	s_setprio 0
	s_setprio 1
	v_mfma_f32_16x16x32_bf16 v[52:55], v[172:175], v[190:193], v[52:55]
	v_mfma_f32_16x16x32_bf16 v[48:51], v[182:185], v[190:193], v[48:51]
	v_mfma_f32_16x16x32_bf16 v[36:39], v[172:175], v[198:201], v[36:39]
	v_mfma_f32_16x16x32_bf16 v[32:35], v[182:185], v[198:201], v[32:35]
	v_mfma_f32_16x16x32_bf16 v[20:23], v[172:175], v[212:215], v[20:23]
	v_mfma_f32_16x16x32_bf16 v[16:19], v[182:185], v[212:215], v[16:19]
	v_mfma_f32_16x16x32_bf16 v[4:7], v[172:175], v[220:223], v[4:7]
	v_mfma_f32_16x16x32_bf16 v[0:3], v[182:185], v[220:223], v[0:3]
	v_mfma_f32_16x16x32_bf16 v[52:55], v[176:179], v[194:197], v[52:55]
	v_mfma_f32_16x16x32_bf16 v[48:51], v[186:189], v[194:197], v[48:51]
	v_mfma_f32_16x16x32_bf16 v[36:39], v[176:179], v[208:211], v[36:39]
	v_mfma_f32_16x16x32_bf16 v[32:35], v[186:189], v[208:211], v[32:35]
	v_mfma_f32_16x16x32_bf16 v[20:23], v[176:179], v[216:219], v[20:23]
	v_mfma_f32_16x16x32_bf16 v[16:19], v[186:189], v[216:219], v[16:19]
	v_lshl_add_u64 v[202:203], v[232:233], 0, s[38:39]
	s_mov_b32 m0, s67
	s_nop 0
	global_load_lds_dwordx4 v[202:203], off
	v_mfma_f32_16x16x32_bf16 v[4:7], v[176:179], v[224:227], v[4:7]
	v_mfma_f32_16x16x32_bf16 v[0:3], v[186:189], v[224:227], v[0:3]
	s_setprio 0
	s_barrier
	s_add_i32 s86, s86, 2
	s_add_u32 s56, s56, 0x100
	s_addc_u32 s57, s57, 0
	s_add_u32 s84, s84, 0x100
	s_addc_u32 s85, s85, 0
.LBB0_738:
	ds_read_b128 v[148:151], v155
	ds_read_b128 v[160:163], v155 offset:1024
	ds_read_b128 v[164:167], v155 offset:2048
	ds_read_b128 v[168:171], v155 offset:3072
	ds_read_b128 v[172:175], v156
	ds_read_b128 v[176:179], v156 offset:1024
	ds_read_b128 v[182:185], v156 offset:2048
	ds_read_b128 v[186:189], v156 offset:3072
	s_add_u32 s3, s56, 0xfffc0080
	s_addc_u32 s14, s57, -1
	s_cmp_eq_u32 s86, 12
	s_cselect_b32 s61, s51, s14
	s_cselect_b32 s60, s82, s3
	s_cselect_b32 s59, s49, s85
	s_cselect_b32 s58, s83, s84
	v_lshl_add_u64 v[202:203], s[56:57], 0, v[140:141]
	s_add_i32 m0, s43, 0xc000
	ds_read_b128 v[190:193], v157
	ds_read_b128 v[194:197], v157 offset:1024
	ds_read_b128 v[198:201], v157 offset:2048
	ds_read_b128 v[208:211], v157 offset:3072
	ds_read_b128 v[212:215], v157 offset:4096
	ds_read_b128 v[216:219], v157 offset:5120
	ds_read_b128 v[220:223], v157 offset:6144
	ds_read_b128 v[224:227], v157 offset:7168
	global_load_lds_dwordx4 v[202:203], off
	v_lshl_add_u64 v[202:203], s[56:57], 0, v[142:143]
	s_add_i32 m0, s43, 0xe000
	s_nop 0
	global_load_lds_dwordx4 v[202:203], off
	s_waitcnt vmcnt(8)
	s_waitcnt lgkmcnt(0)
	s_barrier
; #define PG8_STAGE(bufoff, gbase, voff) do { _Pragma("unroll") for (int _i = 0; _i < 2; ++_i) \
;         __builtin_amdgcn_global_load_lds((const unsigned*)((const char*)(gbase) + (voff)[_i]), (PG8_LAS unsigned*)(lds + (bufoff) + ldsw + _i * 8192), 16, 0, 0); } while (0)
; #define PG8_LDA(dst, b, h) do { _Pragma("unroll") for (int m = 0; m < 4; ++m) _Pragma("unroll") for (int k = 0; k < 2; ++k) dst[m][k] = *(const PG8_LAS bf16x8*)(lds + PG8_SA(b, h) + aoff + m * 2048 + k * 1024); } while (0)
; #define PG8_LDB(dst, b, h) do { _Pragma("unroll") for (int n = 0; n < 2; ++n) _Pragma("unroll") for (int k = 0; k < 2; ++k) dst[n][k] = *(const PG8_LAS bf16x8*)(lds + PG8_SB(b, h) + boff + n * 2048 + k * 1024); } while (0)
; #define PG8_MMA(ai, bj, At, Bt) do { __builtin_amdgcn_s_setprio(1); _Pragma("unroll") for (int m = 0; m < 4; ++m) _Pragma("unroll") for (int n = 0; n < 2; ++n) _Pragma("unroll") for (int k = 0; k < 2; ++k) \
;         acc[ai][bj][m][n] = __builtin_amdgcn_mfma_f32_16x16x32_bf16(Bt[n][k], At[m][k], acc[ai][bj][m][n], 0, 0, 0); __builtin_amdgcn_s_setprio(0); } while (0)
; #define PG8_WAIT_V(n) asm volatile("s_waitcnt vmcnt(" #n ")" ::: "memory")
; #define PG8_WAIT_L(n) asm volatile("s_waitcnt lgkmcnt(" #n ")" ::: "memory")
; #define PG8_BAR __builtin_amdgcn_s_barrier()
; #define PG8_SCHED __builtin_amdgcn_sched_barrier(0)
; template <class Epi, class Sched, bool ALIGN_EPI = false, bool SP2 = false>
; __device__ __forceinline__ void gemm_phase(PG8_LAS unsigned char* lds, const Gemm g, const Sched& S, const Epi& E) {
;     ...
;             PG8_WAIT_V(8); PG8_WAIT_L(0); PG8_BAR; PG8_MMA(0, 0, At, B0); PG8_MMA(0, 1, At, B1); PG8_BAR; PG8_SCHED;
;             PG8_LDA(At, 0, 1); PG8_STAGE(PG8_SB(0, 0), b2, voffB); PG8_STAGE(PG8_SB(0, 1), b2 + hstep, voffB); PG8_STAGE(PG8_SA(0, 0), a2, voffA);
;             PG8_WAIT_V(8); PG8_WAIT_L(0); PG8_BAR; PG8_MMA(1, 0, At, B0); PG8_MMA(1, 1, At, B1); PG8_BAR; PG8_SCHED;
;             PG8_LDB(B0, 1, 0); PG8_LDB(B1, 1, 1); PG8_SCHED; PG8_LDA(At, 1, 0); PG8_STAGE(PG8_SA(0, 1), a2 + hstep, voffA);
;             PG8_WAIT_V(8); PG8_WAIT_L(0); PG8_BAR; PG8_MMA(0, 0, At, B0); PG8_MMA(0, 1, At, B1); PG8_BAR; PG8_SCHED;
	s_setprio 1
	s_waitcnt lgkmcnt(0)
	v_mfma_f32_16x16x32_bf16 v[124:127], v[148:151], v[190:193], v[124:127]
	v_mfma_f32_16x16x32_bf16 v[120:123], v[164:167], v[190:193], v[120:123]
	v_mfma_f32_16x16x32_bf16 v[108:111], v[148:151], v[198:201], v[108:111]
	v_mfma_f32_16x16x32_bf16 v[104:107], v[164:167], v[198:201], v[104:107]
	v_mfma_f32_16x16x32_bf16 v[92:95], v[148:151], v[212:215], v[92:95]
	v_mfma_f32_16x16x32_bf16 v[88:91], v[164:167], v[212:215], v[88:91]
	v_mfma_f32_16x16x32_bf16 v[76:79], v[148:151], v[220:223], v[76:79]
	v_mfma_f32_16x16x32_bf16 v[72:75], v[164:167], v[220:223], v[72:75]
	v_mfma_f32_16x16x32_bf16 v[124:127], v[160:163], v[194:197], v[124:127]
	v_mfma_f32_16x16x32_bf16 v[120:123], v[168:171], v[194:197], v[120:123]
	v_mfma_f32_16x16x32_bf16 v[108:111], v[160:163], v[208:211], v[108:111]
	v_mfma_f32_16x16x32_bf16 v[104:107], v[168:171], v[208:211], v[104:107]
	v_mfma_f32_16x16x32_bf16 v[92:95], v[160:163], v[216:219], v[92:95]
	v_mfma_f32_16x16x32_bf16 v[88:91], v[168:171], v[216:219], v[88:91]
	v_mfma_f32_16x16x32_bf16 v[76:79], v[160:163], v[224:227], v[76:79]
	v_mfma_f32_16x16x32_bf16 v[72:75], v[168:171], v[224:227], v[72:75]
	s_setprio 0
	s_setprio 1
	v_mfma_f32_16x16x32_bf16 v[116:119], v[172:175], v[190:193], v[116:119]
	v_mfma_f32_16x16x32_bf16 v[112:115], v[182:185], v[190:193], v[112:115]
	v_mfma_f32_16x16x32_bf16 v[100:103], v[172:175], v[198:201], v[100:103]
	v_mfma_f32_16x16x32_bf16 v[96:99], v[182:185], v[198:201], v[96:99]
	v_mfma_f32_16x16x32_bf16 v[84:87], v[172:175], v[212:215], v[84:87]
	v_mfma_f32_16x16x32_bf16 v[80:83], v[182:185], v[212:215], v[80:83]
	v_mfma_f32_16x16x32_bf16 v[68:71], v[172:175], v[220:223], v[68:71]
	v_mfma_f32_16x16x32_bf16 v[64:67], v[182:185], v[220:223], v[64:67]
	v_mfma_f32_16x16x32_bf16 v[116:119], v[176:179], v[194:197], v[116:119]
	v_mfma_f32_16x16x32_bf16 v[112:115], v[186:189], v[194:197], v[112:115]
	v_mfma_f32_16x16x32_bf16 v[100:103], v[176:179], v[208:211], v[100:103]
	v_mfma_f32_16x16x32_bf16 v[96:99], v[186:189], v[208:211], v[96:99]
	v_mfma_f32_16x16x32_bf16 v[84:87], v[176:179], v[216:219], v[84:87]
	v_mfma_f32_16x16x32_bf16 v[80:83], v[186:189], v[216:219], v[80:83]
	v_mfma_f32_16x16x32_bf16 v[68:71], v[176:179], v[224:227], v[68:71]
	v_mfma_f32_16x16x32_bf16 v[64:67], v[186:189], v[224:227], v[64:67]
	s_setprio 0
	s_barrier
	s_add_i32 s3, s74, s34
	v_lshl_add_u64 v[202:203], s[58:59], 0, v[136:137]
	s_mov_b32 m0, s3
	ds_read_b128 v[190:193], v157 offset:16384
	ds_read_b128 v[194:197], v157 offset:17408
	ds_read_b128 v[198:201], v157 offset:18432
	ds_read_b128 v[208:211], v157 offset:19456
	ds_read_b128 v[212:215], v157 offset:20480
	ds_read_b128 v[216:219], v157 offset:21504
	ds_read_b128 v[220:223], v157 offset:22528
	ds_read_b128 v[224:227], v157 offset:23552
	global_load_lds_dwordx4 v[202:203], off
	s_add_i32 m0, s3, 0x2000
	s_add_u32 s14, s58, 0x40000
	v_lshl_add_u64 v[228:229], s[58:59], 0, v[132:133]
	s_addc_u32 s15, s59, 0
	s_add_i32 s3, s75, s34
	global_load_lds_dwordx4 v[228:229], off
	v_lshl_add_u64 v[230:231], s[14:15], 0, v[136:137]
	s_mov_b32 m0, s3
	global_load_lds_dwordx4 v[230:231], off
	v_lshl_add_u64 v[230:231], s[14:15], 0, v[132:133]
	s_add_i32 m0, s3, 0x2000
	s_nop 0
	global_load_lds_dwordx4 v[230:231], off
	s_waitcnt vmcnt(6)
	s_waitcnt lgkmcnt(0)
	s_barrier
	s_setprio 1
	s_waitcnt lgkmcnt(0)
	v_mfma_f32_16x16x32_bf16 v[60:63], v[148:151], v[190:193], v[60:63]
	v_mfma_f32_16x16x32_bf16 v[56:59], v[164:167], v[190:193], v[56:59]
	v_mfma_f32_16x16x32_bf16 v[44:47], v[148:151], v[198:201], v[44:47]
	v_mfma_f32_16x16x32_bf16 v[40:43], v[164:167], v[198:201], v[40:43]
	v_mfma_f32_16x16x32_bf16 v[28:31], v[148:151], v[212:215], v[28:31]
	v_mfma_f32_16x16x32_bf16 v[24:27], v[164:167], v[212:215], v[24:27]
	v_mfma_f32_16x16x32_bf16 v[12:15], v[148:151], v[220:223], v[12:15]
	v_mfma_f32_16x16x32_bf16 v[8:11], v[164:167], v[220:223], v[8:11]
	v_mfma_f32_16x16x32_bf16 v[60:63], v[160:163], v[194:197], v[60:63]
	v_mfma_f32_16x16x32_bf16 v[56:59], v[168:171], v[194:197], v[56:59]
	v_mfma_f32_16x16x32_bf16 v[44:47], v[160:163], v[208:211], v[44:47]
	v_mfma_f32_16x16x32_bf16 v[40:43], v[168:171], v[208:211], v[40:43]
	v_mfma_f32_16x16x32_bf16 v[28:31], v[160:163], v[216:219], v[28:31]
	v_mfma_f32_16x16x32_bf16 v[24:27], v[168:171], v[216:219], v[24:27]
	v_lshl_add_u64 v[230:231], s[60:61], 0, v[138:139]
	s_mov_b32 m0, s43
	s_nop 0
	global_load_lds_dwordx4 v[230:231], off
	v_mfma_f32_16x16x32_bf16 v[12:15], v[160:163], v[224:227], v[12:15]
	v_mfma_f32_16x16x32_bf16 v[8:11], v[168:171], v[224:227], v[8:11]
	s_setprio 0
	s_setprio 1
	v_mfma_f32_16x16x32_bf16 v[52:55], v[172:175], v[190:193], v[52:55]
	v_mfma_f32_16x16x32_bf16 v[48:51], v[182:185], v[190:193], v[48:51]
	v_mfma_f32_16x16x32_bf16 v[36:39], v[172:175], v[198:201], v[36:39]
	v_mfma_f32_16x16x32_bf16 v[32:35], v[182:185], v[198:201], v[32:35]
	v_mfma_f32_16x16x32_bf16 v[20:23], v[172:175], v[212:215], v[20:23]
	v_mfma_f32_16x16x32_bf16 v[16:19], v[182:185], v[212:215], v[16:19]
	v_mfma_f32_16x16x32_bf16 v[4:7], v[172:175], v[220:223], v[4:7]
	v_mfma_f32_16x16x32_bf16 v[0:3], v[182:185], v[220:223], v[0:3]
	v_mfma_f32_16x16x32_bf16 v[52:55], v[176:179], v[194:197], v[52:55]
	v_mfma_f32_16x16x32_bf16 v[48:51], v[186:189], v[194:197], v[48:51]
	v_mfma_f32_16x16x32_bf16 v[36:39], v[176:179], v[208:211], v[36:39]
	v_mfma_f32_16x16x32_bf16 v[32:35], v[186:189], v[208:211], v[32:35]
	v_mfma_f32_16x16x32_bf16 v[20:23], v[176:179], v[216:219], v[20:23]
	v_mfma_f32_16x16x32_bf16 v[16:19], v[186:189], v[216:219], v[16:19]
	v_lshl_add_u64 v[232:233], s[60:61], 0, v[134:135]
	s_mov_b32 m0, s62
	s_nop 0
	global_load_lds_dwordx4 v[232:233], off
	v_mfma_f32_16x16x32_bf16 v[4:7], v[176:179], v[224:227], v[4:7]
	v_mfma_f32_16x16x32_bf16 v[0:3], v[186:189], v[224:227], v[0:3]
	s_setprio 0
	s_barrier
; #define PG8_STAGE(bufoff, gbase, voff) do { _Pragma("unroll") for (int _i = 0; _i < 2; ++_i) \
;         __builtin_amdgcn_global_load_lds((const unsigned*)((const char*)(gbase) + (voff)[_i]), (PG8_LAS unsigned*)(lds + (bufoff) + ldsw + _i * 8192), 16, 0, 0); } while (0)
; #define PG8_LDA(dst, b, h) do { _Pragma("unroll") for (int m = 0; m < 4; ++m) _Pragma("unroll") for (int k = 0; k < 2; ++k) dst[m][k] = *(const PG8_LAS bf16x8*)(lds + PG8_SA(b, h) + aoff + m * 2048 + k * 1024); } while (0)
; #define PG8_LDB(dst, b, h) do { _Pragma("unroll") for (int n = 0; n < 2; ++n) _Pragma("unroll") for (int k = 0; k < 2; ++k) dst[n][k] = *(const PG8_LAS bf16x8*)(lds + PG8_SB(b, h) + boff + n * 2048 + k * 1024); } while (0)
; #define PG8_MMA(ai, bj, At, Bt) do { __builtin_amdgcn_s_setprio(1); _Pragma("unroll") for (int m = 0; m < 4; ++m) _Pragma("unroll") for (int n = 0; n < 2; ++n) _Pragma("unroll") for (int k = 0; k < 2; ++k) \
;         acc[ai][bj][m][n] = __builtin_amdgcn_mfma_f32_16x16x32_bf16(Bt[n][k], At[m][k], acc[ai][bj][m][n], 0, 0, 0); __builtin_amdgcn_s_setprio(0); } while (0)
; #define PG8_WAIT_V(n) asm volatile("s_waitcnt vmcnt(" #n ")" ::: "memory")
; #define PG8_WAIT_L(n) asm volatile("s_waitcnt lgkmcnt(" #n ")" ::: "memory")
; #define PG8_BAR __builtin_amdgcn_s_barrier()
; #define PG8_SCHED __builtin_amdgcn_sched_barrier(0)
; template <class Epi, class Sched, bool ALIGN_EPI = false, bool SP2 = false>
; __device__ __forceinline__ void gemm_phase(PG8_LAS unsigned char* lds, const Gemm g, const Sched& S, const Epi& E) {
;     ...
;             PG8_LDB(B0, 1, 0); PG8_LDB(B1, 1, 1); PG8_SCHED; PG8_LDA(At, 1, 0); PG8_STAGE(PG8_SA(0, 1), a2 + hstep, voffA);
;             PG8_WAIT_V(8); PG8_WAIT_L(0); PG8_BAR; PG8_MMA(0, 0, At, B0); PG8_MMA(0, 1, At, B1); PG8_BAR; PG8_SCHED;
;             PG8_LDA(At, 1, 1); PG8_STAGE(PG8_SB(1, 0), b3, voffB); PG8_STAGE(PG8_SB(1, 1), b3 + hstep, voffB); PG8_STAGE(PG8_SA(1, 0), a3, voffA);
;             PG8_WAIT_V(8); PG8_WAIT_L(0); PG8_BAR; PG8_MMA(1, 0, At, B0); PG8_MMA(1, 1, At, B1); PG8_BAR; PG8_SCHED;
	s_add_i32 s3, 0, 0x18000
	v_add_u32_e32 v159, s3, v131
	s_add_i32 s33, 0, 0x1c000
	ds_read_b128 v[148:151], v159
	ds_read_b128 v[160:163], v159 offset:1024
	ds_read_b128 v[164:167], v159 offset:2048
	ds_read_b128 v[168:171], v159 offset:3072
	v_add_u32_e32 v159, s33, v131
	ds_read_b128 v[172:175], v159
	ds_read_b128 v[176:179], v159 offset:1024
	ds_read_b128 v[182:185], v159 offset:2048
	ds_read_b128 v[186:189], v159 offset:3072
	s_add_u32 s14, s60, 0x40000
	s_addc_u32 s15, s61, 0
	s_mov_b32 m0, s63
	v_lshl_add_u64 v[234:235], s[14:15], 0, v[138:139]
	ds_read_b128 v[190:193], v157 offset:32768
	ds_read_b128 v[194:197], v157 offset:33792
	ds_read_b128 v[198:201], v157 offset:34816
	ds_read_b128 v[208:211], v157 offset:35840
	ds_read_b128 v[212:215], v157 offset:36864
	ds_read_b128 v[216:219], v157 offset:37888
	ds_read_b128 v[220:223], v157 offset:38912
	ds_read_b128 v[224:227], v157 offset:39936
	global_load_lds_dwordx4 v[234:235], off
	v_lshl_add_u64 v[234:235], s[14:15], 0, v[134:135]
	s_mov_b32 m0, s64
	s_nop 0
	global_load_lds_dwordx4 v[234:235], off
	s_waitcnt vmcnt(8)
	s_waitcnt lgkmcnt(0)
	s_barrier
	s_setprio 1
	s_waitcnt lgkmcnt(0)
	v_mfma_f32_16x16x32_bf16 v[124:127], v[148:151], v[190:193], v[124:127]
	v_mfma_f32_16x16x32_bf16 v[120:123], v[164:167], v[190:193], v[120:123]
	v_mfma_f32_16x16x32_bf16 v[108:111], v[148:151], v[198:201], v[108:111]
	v_mfma_f32_16x16x32_bf16 v[104:107], v[164:167], v[198:201], v[104:107]
	v_mfma_f32_16x16x32_bf16 v[92:95], v[148:151], v[212:215], v[92:95]
	v_mfma_f32_16x16x32_bf16 v[88:91], v[164:167], v[212:215], v[88:91]
	v_mfma_f32_16x16x32_bf16 v[76:79], v[148:151], v[220:223], v[76:79]
	v_mfma_f32_16x16x32_bf16 v[72:75], v[164:167], v[220:223], v[72:75]
	v_mfma_f32_16x16x32_bf16 v[124:127], v[160:163], v[194:197], v[124:127]
	v_mfma_f32_16x16x32_bf16 v[120:123], v[168:171], v[194:197], v[120:123]
	v_mfma_f32_16x16x32_bf16 v[108:111], v[160:163], v[208:211], v[108:111]
	v_mfma_f32_16x16x32_bf16 v[104:107], v[168:171], v[208:211], v[104:107]
	v_mfma_f32_16x16x32_bf16 v[92:95], v[160:163], v[216:219], v[92:95]
	v_mfma_f32_16x16x32_bf16 v[88:91], v[168:171], v[216:219], v[88:91]
	v_mfma_f32_16x16x32_bf16 v[76:79], v[160:163], v[224:227], v[76:79]
	v_mfma_f32_16x16x32_bf16 v[72:75], v[168:171], v[224:227], v[72:75]
	s_setprio 0
	s_setprio 1
	v_mfma_f32_16x16x32_bf16 v[116:119], v[172:175], v[190:193], v[116:119]
	v_mfma_f32_16x16x32_bf16 v[112:115], v[182:185], v[190:193], v[112:115]
	v_mfma_f32_16x16x32_bf16 v[100:103], v[172:175], v[198:201], v[100:103]
	v_mfma_f32_16x16x32_bf16 v[96:99], v[182:185], v[198:201], v[96:99]
	v_mfma_f32_16x16x32_bf16 v[84:87], v[172:175], v[212:215], v[84:87]
	v_mfma_f32_16x16x32_bf16 v[80:83], v[182:185], v[212:215], v[80:83]
	v_mfma_f32_16x16x32_bf16 v[68:71], v[172:175], v[220:223], v[68:71]
	v_mfma_f32_16x16x32_bf16 v[64:67], v[182:185], v[220:223], v[64:67]
	v_mfma_f32_16x16x32_bf16 v[116:119], v[176:179], v[194:197], v[116:119]
	v_mfma_f32_16x16x32_bf16 v[112:115], v[186:189], v[194:197], v[112:115]
	v_mfma_f32_16x16x32_bf16 v[100:103], v[176:179], v[208:211], v[100:103]
	v_mfma_f32_16x16x32_bf16 v[96:99], v[186:189], v[208:211], v[96:99]
	v_mfma_f32_16x16x32_bf16 v[84:87], v[176:179], v[216:219], v[84:87]
	v_mfma_f32_16x16x32_bf16 v[80:83], v[186:189], v[216:219], v[80:83]
	v_mfma_f32_16x16x32_bf16 v[68:71], v[176:179], v[224:227], v[68:71]
	v_mfma_f32_16x16x32_bf16 v[64:67], v[186:189], v[224:227], v[64:67]
	s_setprio 0
	s_barrier
	s_add_i32 s3, s3, s34
	v_lshl_add_u64 v[202:203], v[202:203], 0, s[38:39]
	s_mov_b32 m0, s3
	ds_read_b128 v[190:193], v157 offset:49152
	ds_read_b128 v[194:197], v157 offset:50176
	ds_read_b128 v[198:201], v157 offset:51200
	ds_read_b128 v[208:211], v157 offset:52224
	ds_read_b128 v[212:215], v157 offset:53248
	ds_read_b128 v[216:219], v157 offset:54272
	ds_read_b128 v[220:223], v157 offset:55296
	ds_read_b128 v[224:227], v157 offset:56320
	global_load_lds_dwordx4 v[202:203], off
	s_add_i32 m0, s3, 0x2000
	s_add_u32 s14, s58, 0x40080
	v_lshl_add_u64 v[202:203], v[228:229], 0, s[38:39]
	s_addc_u32 s15, s59, 0
	s_add_i32 s3, s33, s34
	global_load_lds_dwordx4 v[202:203], off
	v_lshl_add_u64 v[202:203], s[14:15], 0, v[136:137]
	s_mov_b32 m0, s3
	s_nop 0
	global_load_lds_dwordx4 v[202:203], off
	v_lshl_add_u64 v[202:203], s[14:15], 0, v[132:133]
	s_add_i32 m0, s3, 0x2000
	s_nop 0
	global_load_lds_dwordx4 v[202:203], off
	s_waitcnt vmcnt(6)
	s_waitcnt lgkmcnt(0)
	s_barrier
;     __device__ __forceinline__ void operator()(const f32x4 (&acc)[2][2][4][2], const Unit& u, int wr, int wc, int fr, int fq) const {
;         const int row0 = u.pm * BM + wr * 64 + fr, col0 = u.pn * BM + wc * 32 + 8 * fq;
; #pragma unroll
;         for (int ai = 0; ai < 2; ++ai)
; #pragma unroll
;             for (int m = 0; m < 4; ++m) { const int row = row0 + ai * HALF + m * 16; const float rs = ss ? row_rs(ss, row) : 1.0f;
; #pragma unroll
;                 for (int bj = 0; bj < 2; ++bj) { const f32x4 v0 = acc[ai][bj][m][0] * rs, v1 = acc[ai][bj][m][1] * rs;
;                     u32x4 w; w.x = cvtpk(v0[0], v0[1]); w.y = cvtpk(v0[2], v0[3]); w.z = cvtpk(v1[0], v1[1]); w.w = cvtpk(v1[2], v1[3]);
; template <class Epi, class Sched, bool ALIGN_EPI = false, bool SP2 = false>
; __device__ __forceinline__ void gemm_phase(PG8_LAS unsigned char* lds, const Gemm g, const Sched& S, const Epi& E) {
;     ...
;             PG8_WAIT_V(8); PG8_WAIT_L(0); PG8_BAR; PG8_MMA(1, 0, At, B0); PG8_MMA(1, 1, At, B1); PG8_BAR; PG8_SCHED;
;             } else {
;             PG8_LDB(B0, 0, 0); PG8_SCHED; PG8_LDA(At, 0, 0); PG8_STAGE(PG8_SA(1, 1), a1 + hstep, voffA);
;             PG8_WAIT_L(8); PG8_BAR; PG8_WAIT_L(0); PG8_MMA(0, 0, At, B0); PG8_BAR; PG8_SCHED;
;             PG8_LDB(B1, 0, 1); PG8_STAGE(PG8_SB(0, 0), b2, voffB);
;             PG8_BAR; PG8_WAIT_L(0); PG8_MMA(0, 1, At, B1); PG8_BAR;
;             PG8_LDA(At, 0, 1); PG8_STAGE(PG8_SA(0, 0), a2, voffA);
;             PG8_BAR; PG8_WAIT_L(0); PG8_MMA(1, 0, At, B0); PG8_BAR; PG8_SCHED;
;             PG8_STAGE(PG8_SB(0, 1), b2 + hstep, voffB);
;             PG8_WAIT_V(6); PG8_BAR; PG8_MMA(1, 1, At, B1); PG8_BAR;
;             PG8_LDB(B0, 1, 0); PG8_SCHED; PG8_LDA(At, 1, 0); PG8_STAGE(PG8_SA(0, 1), a2 + hstep, voffA);
;             PG8_WAIT_L(8); PG8_BAR; PG8_WAIT_L(0); PG8_MMA(0, 0, At, B0); PG8_BAR; PG8_SCHED;
;             PG8_LDB(B1, 1, 1); PG8_STAGE(PG8_SB(1, 0), b3, voffB);
;             PG8_BAR; PG8_WAIT_L(0); PG8_MMA(0, 1, At, B1); PG8_BAR;
;             PG8_LDA(At, 1, 1); PG8_STAGE(PG8_SA(1, 0), a3, voffA);
;             PG8_BAR; PG8_WAIT_L(0); PG8_MMA(1, 0, At, B0); PG8_BAR; PG8_SCHED;
;             PG8_STAGE(PG8_SB(1, 1), b3 + hstep, voffB);
;             PG8_WAIT_V(6); PG8_BAR; PG8_MMA(1, 1, At, B1); PG8_BAR;
;             }
;         }
;         if constexpr (ALIGN_EPI) { if (wr == 0) PG8_BAR; }
	s_setprio 1
	s_waitcnt lgkmcnt(0)
	v_mfma_f32_16x16x32_bf16 v[60:63], v[148:151], v[190:193], v[60:63]
	v_mfma_f32_16x16x32_bf16 v[56:59], v[164:167], v[190:193], v[56:59]
	v_mfma_f32_16x16x32_bf16 v[44:47], v[148:151], v[198:201], v[44:47]
	v_mfma_f32_16x16x32_bf16 v[40:43], v[164:167], v[198:201], v[40:43]
	v_mfma_f32_16x16x32_bf16 v[28:31], v[148:151], v[212:215], v[28:31]
	v_mfma_f32_16x16x32_bf16 v[24:27], v[164:167], v[212:215], v[24:27]
	v_mfma_f32_16x16x32_bf16 v[12:15], v[148:151], v[220:223], v[12:15]
	v_mfma_f32_16x16x32_bf16 v[8:11], v[164:167], v[220:223], v[8:11]
	v_mfma_f32_16x16x32_bf16 v[60:63], v[160:163], v[194:197], v[60:63]
	v_mfma_f32_16x16x32_bf16 v[56:59], v[168:171], v[194:197], v[56:59]
	v_mfma_f32_16x16x32_bf16 v[44:47], v[160:163], v[208:211], v[44:47]
	v_mfma_f32_16x16x32_bf16 v[40:43], v[168:171], v[208:211], v[40:43]
	v_mfma_f32_16x16x32_bf16 v[28:31], v[160:163], v[216:219], v[28:31]
	v_mfma_f32_16x16x32_bf16 v[24:27], v[168:171], v[216:219], v[24:27]
	v_lshl_add_u64 v[202:203], v[230:231], 0, s[38:39]
	s_mov_b32 m0, s66
	s_nop 0
	global_load_lds_dwordx4 v[202:203], off
	v_mfma_f32_16x16x32_bf16 v[12:15], v[160:163], v[224:227], v[12:15]
	v_mfma_f32_16x16x32_bf16 v[8:11], v[168:171], v[224:227], v[8:11]
	s_setprio 0
	s_setprio 1
	v_mfma_f32_16x16x32_bf16 v[52:55], v[172:175], v[190:193], v[52:55]
	v_mfma_f32_16x16x32_bf16 v[48:51], v[182:185], v[190:193], v[48:51]
	v_mfma_f32_16x16x32_bf16 v[36:39], v[172:175], v[198:201], v[36:39]
	v_mfma_f32_16x16x32_bf16 v[32:35], v[182:185], v[198:201], v[32:35]
	v_mfma_f32_16x16x32_bf16 v[20:23], v[172:175], v[212:215], v[20:23]
	v_mfma_f32_16x16x32_bf16 v[16:19], v[182:185], v[212:215], v[16:19]
	v_mfma_f32_16x16x32_bf16 v[4:7], v[172:175], v[220:223], v[4:7]
	v_mfma_f32_16x16x32_bf16 v[0:3], v[182:185], v[220:223], v[0:3]
	v_mfma_f32_16x16x32_bf16 v[52:55], v[176:179], v[194:197], v[52:55]
	v_mfma_f32_16x16x32_bf16 v[48:51], v[186:189], v[194:197], v[48:51]
	v_mfma_f32_16x16x32_bf16 v[36:39], v[176:179], v[208:211], v[36:39]
	v_mfma_f32_16x16x32_bf16 v[32:35], v[186:189], v[208:211], v[32:35]
	v_mfma_f32_16x16x32_bf16 v[20:23], v[176:179], v[216:219], v[20:23]
	v_mfma_f32_16x16x32_bf16 v[16:19], v[186:189], v[216:219], v[16:19]
	v_lshl_add_u64 v[202:203], v[232:233], 0, s[38:39]
	s_mov_b32 m0, s67
	s_nop 0
	global_load_lds_dwordx4 v[202:203], off
	v_mfma_f32_16x16x32_bf16 v[4:7], v[176:179], v[224:227], v[4:7]
	v_mfma_f32_16x16x32_bf16 v[0:3], v[186:189], v[224:227], v[0:3]
	s_setprio 0
	s_barrier
	s_add_i32 s86, s86, 2
	s_add_u32 s56, s56, 0x100
	s_addc_u32 s57, s57, 0
	s_add_u32 s84, s84, 0x100
	s_addc_u32 s85, s85, 0
	s_cmp_gt_u32 s86, 13
	s_cbranch_scc0 .LBB0_738
	s_and_b64 vcc, exec, s[44:45]
	s_cbranch_vccz .LBB0_741
.LBB0_741:
	v_lshl_add_u32 v160, s0, 8, v129
	v_ashrrev_i32_e32 v161, 31, v160
	v_lshl_add_u64 v[150:151], v[160:161], 3, s[10:11]
	global_load_dwordx2 v[148:149], v[150:151], off
	v_lshl_or_b32 v162, s1, 8, v154
	v_ashrrev_i32_e32 v163, 31, v162
	v_lshlrev_b64 v[166:167], 10, v[160:161]
	v_or_b32_e32 v164, 16, v160
	v_lshlrev_b64 v[162:163], 1, v[162:163]
	v_ashrrev_i32_e32 v165, 31, v164
	s_mov_b32 s3, 0x20000
	s_mov_b64 s[0:1], 0x20000
	s_waitcnt vmcnt(0)
	v_ffbh_u32_e32 v159, v149
	v_min_u32_e32 v159, 32, v159
	v_lshlrev_b64 v[148:149], v159, v[148:149]
	v_min_u32_e32 v148, 1, v148
	v_or_b32_e32 v148, v149, v148
	v_cvt_f32_u32_e32 v148, v148
	v_sub_u32_e32 v149, 32, v159
	v_ldexp_f32 v148, v148, v149
	v_mul_f32_e32 v148, 0x2f800000, v148
	v_fmamk_f32 v148, v148, 0x3a800000, v158
	v_rsq_f32_e32 v168, v148
	v_lshl_add_u64 v[148:149], s[20:21], 0, v[166:167]
	v_lshl_add_u64 v[148:149], v[148:149], 0, v[162:163]
	v_lshl_add_u64 v[166:167], v[164:165], 3, s[10:11]
	v_pk_mul_f32 v[126:127], v[126:127], v[168:169] op_sel_hi:[1,0]
	v_pk_mul_f32 v[124:125], v[124:125], v[168:169] op_sel_hi:[1,0]
	v_pk_mul_f32 v[122:123], v[122:123], v[168:169] op_sel_hi:[1,0]
	v_pk_mul_f32 v[120:121], v[120:121], v[168:169] op_sel_hi:[1,0]
	v_pk_mul_f32 v[118:119], v[118:119], v[168:169] op_sel_hi:[1,0]
	v_pk_mul_f32 v[116:117], v[116:117], v[168:169] op_sel_hi:[1,0]
	v_pk_mul_f32 v[170:171], v[114:115], v[168:169] op_sel_hi:[1,0]
	v_pk_mul_f32 v[168:169], v[112:113], v[168:169] op_sel_hi:[1,0]
	v_cvt_pk_bf16_f32 v112, v124, v125
	v_cvt_pk_bf16_f32 v113, v126, v127
	v_cvt_pk_bf16_f32 v114, v120, v121
	v_cvt_pk_bf16_f32 v115, v122, v123
	v_cvt_pk_bf16_f32 v116, v116, v117
	v_cvt_pk_bf16_f32 v117, v118, v119
	v_cvt_pk_bf16_f32 v118, v168, v169
	v_cvt_pk_bf16_f32 v119, v170, v171
	global_store_dwordx4 v[148:149], v[112:115], off
	global_store_dwordx4 v[148:149], v[116:119], off offset:256
	global_load_dwordx2 v[112:113], v[166:167], off
	v_or_b32_e32 v114, 32, v160
	s_waitcnt vmcnt(0)
	v_ffbh_u32_e32 v115, v113
	v_min_u32_e32 v116, 32, v115
	v_lshlrev_b64 v[112:113], v116, v[112:113]
	v_min_u32_e32 v112, 1, v112
	v_or_b32_e32 v112, v113, v112
	v_cvt_f32_u32_e32 v117, v112
	v_sub_u32_e32 v116, 32, v116
	v_lshlrev_b64 v[112:113], 10, v[164:165]
	v_lshl_add_u64 v[112:113], s[20:21], 0, v[112:113]
	v_ldexp_f32 v116, v117, v116
	v_mul_f32_e32 v116, 0x2f800000, v116
	v_fmamk_f32 v116, v116, 0x3a800000, v158
	v_rsq_f32_e32 v116, v116
	v_ashrrev_i32_e32 v115, 31, v114
	v_lshl_add_u64 v[112:113], v[112:113], 0, v[162:163]
	v_lshl_add_u64 v[118:119], v[114:115], 3, s[10:11]
	v_pk_mul_f32 v[110:111], v[110:111], v[116:117] op_sel_hi:[1,0]
	v_pk_mul_f32 v[108:109], v[108:109], v[116:117] op_sel_hi:[1,0]
	v_pk_mul_f32 v[106:107], v[106:107], v[116:117] op_sel_hi:[1,0]
	v_pk_mul_f32 v[104:105], v[104:105], v[116:117] op_sel_hi:[1,0]
	v_pk_mul_f32 v[102:103], v[102:103], v[116:117] op_sel_hi:[1,0]
	v_pk_mul_f32 v[100:101], v[100:101], v[116:117] op_sel_hi:[1,0]
	v_pk_mul_f32 v[120:121], v[98:99], v[116:117] op_sel_hi:[1,0]
	v_pk_mul_f32 v[116:117], v[96:97], v[116:117] op_sel_hi:[1,0]
	v_cvt_pk_bf16_f32 v96, v108, v109
	v_cvt_pk_bf16_f32 v97, v110, v111
	v_cvt_pk_bf16_f32 v98, v104, v105
	v_cvt_pk_bf16_f32 v99, v106, v107
	v_cvt_pk_bf16_f32 v100, v100, v101
	v_cvt_pk_bf16_f32 v101, v102, v103
	v_cvt_pk_bf16_f32 v102, v116, v117
	v_cvt_pk_bf16_f32 v103, v120, v121
	global_store_dwordx4 v[112:113], v[96:99], off
	global_store_dwordx4 v[112:113], v[100:103], off offset:256
	global_load_dwordx2 v[96:97], v[118:119], off
	v_or_b32_e32 v98, 48, v160
	s_waitcnt vmcnt(0)
; __device__ __forceinline__ unsigned cvtpk(float lo, float hi) { f32x2v_ v = {lo, hi}; bf16x2v_ b = __builtin_convertvector(v, bf16x2v_); return __builtin_bit_cast(unsigned, b); }
; __device__ __forceinline__ float row_rs(const float* ssp, int row) { const unsigned long long v = ((const unsigned long long*)ssp)[row];
;     return __builtin_amdgcn_rsqf((float)v * (1.0f / 4294967296.0f) * (1.0f / 1024.0f) + RMS_EPS); }
;     __device__ __forceinline__ void operator()(const f32x4 (&acc)[2][2][4][2], const Unit& u, int wr, int wc, int fr, int fq) const {
;         const int row0 = u.pm * BM + wr * 64 + fr, col0 = u.pn * BM + wc * 32 + 8 * fq;
; #pragma unroll
;         for (int ai = 0; ai < 2; ++ai)
; #pragma unroll
;             for (int m = 0; m < 4; ++m) { const int row = row0 + ai * HALF + m * 16; const float rs = ss ? row_rs(ss, row) : 1.0f;
; #pragma unroll
;                 for (int bj = 0; bj < 2; ++bj) { const f32x4 v0 = acc[ai][bj][m][0] * rs, v1 = acc[ai][bj][m][1] * rs;
;                     u32x4 w; w.x = cvtpk(v0[0], v0[1]); w.y = cvtpk(v0[2], v0[3]); w.z = cvtpk(v1[0], v1[1]); w.w = cvtpk(v1[2], v1[3]);
;                     *(u32x4*)(O + (size_t)row * ldc + col0 + bj * HALF) = w; } }
	v_ffbh_u32_e32 v99, v97
	v_min_u32_e32 v100, 32, v99
	v_lshlrev_b64 v[96:97], v100, v[96:97]
	v_min_u32_e32 v96, 1, v96
	v_or_b32_e32 v96, v97, v96
	v_cvt_f32_u32_e32 v101, v96
	v_sub_u32_e32 v100, 32, v100
	v_lshlrev_b64 v[96:97], 10, v[114:115]
	v_lshl_add_u64 v[96:97], s[20:21], 0, v[96:97]
	v_ldexp_f32 v100, v101, v100
	v_mul_f32_e32 v100, 0x2f800000, v100
	v_fmamk_f32 v100, v100, 0x3a800000, v158
	v_rsq_f32_e32 v100, v100
	v_ashrrev_i32_e32 v99, 31, v98
	v_lshl_add_u64 v[96:97], v[96:97], 0, v[162:163]
	v_lshl_add_u64 v[102:103], v[98:99], 3, s[10:11]
	v_pk_mul_f32 v[94:95], v[94:95], v[100:101] op_sel_hi:[1,0]
	v_pk_mul_f32 v[92:93], v[92:93], v[100:101] op_sel_hi:[1,0]
	v_pk_mul_f32 v[90:91], v[90:91], v[100:101] op_sel_hi:[1,0]
	v_pk_mul_f32 v[88:89], v[88:89], v[100:101] op_sel_hi:[1,0]
	v_pk_mul_f32 v[86:87], v[86:87], v[100:101] op_sel_hi:[1,0]
	v_pk_mul_f32 v[84:85], v[84:85], v[100:101] op_sel_hi:[1,0]
	v_pk_mul_f32 v[104:105], v[82:83], v[100:101] op_sel_hi:[1,0]
	v_pk_mul_f32 v[100:101], v[80:81], v[100:101] op_sel_hi:[1,0]
	v_cvt_pk_bf16_f32 v80, v92, v93
	v_cvt_pk_bf16_f32 v81, v94, v95
	v_cvt_pk_bf16_f32 v82, v88, v89
	v_cvt_pk_bf16_f32 v83, v90, v91
	v_cvt_pk_bf16_f32 v84, v84, v85
	v_cvt_pk_bf16_f32 v85, v86, v87
	v_cvt_pk_bf16_f32 v86, v100, v101
	v_cvt_pk_bf16_f32 v87, v104, v105
	global_store_dwordx4 v[96:97], v[80:83], off
	global_store_dwordx4 v[96:97], v[84:87], off offset:256
	global_load_dwordx2 v[80:81], v[102:103], off
	s_waitcnt vmcnt(0)
	v_ffbh_u32_e32 v82, v81
	v_min_u32_e32 v82, 32, v82
	v_lshlrev_b64 v[80:81], v82, v[80:81]
	v_min_u32_e32 v80, 1, v80
	v_or_b32_e32 v80, v81, v80
	v_cvt_f32_u32_e32 v80, v80
	v_sub_u32_e32 v81, 32, v82
	v_lshlrev_b64 v[82:83], 10, v[98:99]
	v_lshl_add_u64 v[82:83], s[20:21], 0, v[82:83]
	v_ldexp_f32 v80, v80, v81
	v_mul_f32_e32 v80, 0x2f800000, v80
	v_fmamk_f32 v80, v80, 0x3a800000, v158
	v_rsq_f32_e32 v80, v80
	v_lshl_add_u64 v[82:83], v[82:83], 0, v[162:163]
	v_pk_mul_f32 v[78:79], v[78:79], v[80:81] op_sel_hi:[1,0]
	v_pk_mul_f32 v[76:77], v[76:77], v[80:81] op_sel_hi:[1,0]
	v_pk_mul_f32 v[74:75], v[74:75], v[80:81] op_sel_hi:[1,0]
	v_pk_mul_f32 v[72:73], v[72:73], v[80:81] op_sel_hi:[1,0]
	v_pk_mul_f32 v[70:71], v[70:71], v[80:81] op_sel_hi:[1,0]
	v_pk_mul_f32 v[68:69], v[68:69], v[80:81] op_sel_hi:[1,0]
	v_pk_mul_f32 v[84:85], v[66:67], v[80:81] op_sel_hi:[1,0]
	v_pk_mul_f32 v[80:81], v[64:65], v[80:81] op_sel_hi:[1,0]
	v_cvt_pk_bf16_f32 v64, v76, v77
	v_cvt_pk_bf16_f32 v65, v78, v79
	v_cvt_pk_bf16_f32 v66, v72, v73
	v_cvt_pk_bf16_f32 v67, v74, v75
	v_cvt_pk_bf16_f32 v68, v68, v69
	v_cvt_pk_bf16_f32 v69, v70, v71
	v_cvt_pk_bf16_f32 v70, v80, v81
	v_cvt_pk_bf16_f32 v71, v84, v85
	global_store_dwordx4 v[82:83], v[64:67], off
	global_store_dwordx4 v[82:83], v[68:71], off offset:256
	global_load_dwordx2 v[64:65], v[150:151], off offset:1024
	s_waitcnt vmcnt(0)
	v_ffbh_u32_e32 v66, v65
	v_min_u32_e32 v66, 32, v66
	v_lshlrev_b64 v[64:65], v66, v[64:65]
	v_min_u32_e32 v64, 1, v64
	v_or_b32_e32 v64, v65, v64
	v_cvt_f32_u32_e32 v67, v64
	v_sub_u32_e32 v66, 32, v66
	v_add_co_u32_e32 v68, vcc, s3, v148
	v_ldexp_f32 v66, v67, v66
	v_mul_f32_e32 v66, 0x2f800000, v66
	v_fmamk_f32 v66, v66, 0x3a800000, v158
	v_rsq_f32_e32 v66, v66
	v_addc_co_u32_e32 v69, vcc, 0, v149, vcc
	v_lshl_add_u64 v[64:65], v[148:149], 0, s[0:1]
	v_pk_mul_f32 v[62:63], v[62:63], v[66:67] op_sel_hi:[1,0]
	v_pk_mul_f32 v[60:61], v[60:61], v[66:67] op_sel_hi:[1,0]
	v_pk_mul_f32 v[58:59], v[58:59], v[66:67] op_sel_hi:[1,0]
	v_pk_mul_f32 v[56:57], v[56:57], v[66:67] op_sel_hi:[1,0]
	v_pk_mul_f32 v[54:55], v[54:55], v[66:67] op_sel_hi:[1,0]
	v_pk_mul_f32 v[52:53], v[52:53], v[66:67] op_sel_hi:[1,0]
	v_pk_mul_f32 v[70:71], v[50:51], v[66:67] op_sel_hi:[1,0]
	v_pk_mul_f32 v[66:67], v[48:49], v[66:67] op_sel_hi:[1,0]
	v_cvt_pk_bf16_f32 v48, v60, v61
	v_cvt_pk_bf16_f32 v49, v62, v63
	v_cvt_pk_bf16_f32 v50, v56, v57
	v_cvt_pk_bf16_f32 v51, v58, v59
	v_cvt_pk_bf16_f32 v52, v52, v53
	v_cvt_pk_bf16_f32 v53, v54, v55
	v_cvt_pk_bf16_f32 v54, v66, v67
	v_cvt_pk_bf16_f32 v55, v70, v71
	global_store_dwordx4 v[68:69], v[48:51], off
	global_store_dwordx4 v[64:65], v[52:55], off offset:256
	global_load_dwordx2 v[48:49], v[150:151], off offset:1152
	s_mov_b32 s3, 0x24000
	v_add_co_u32_e32 v52, vcc, s3, v148
	s_mov_b64 s[0:1], 0x24000
	s_nop 0
	v_addc_co_u32_e32 v53, vcc, 0, v149, vcc
	s_mov_b32 s3, 0x28000
	s_waitcnt vmcnt(0)
; __device__ __forceinline__ unsigned cvtpk(float lo, float hi) { f32x2v_ v = {lo, hi}; bf16x2v_ b = __builtin_convertvector(v, bf16x2v_); return __builtin_bit_cast(unsigned, b); }
; #define PG8_BAR __builtin_amdgcn_s_barrier()
;     __device__ __forceinline__ void operator()(const f32x4 (&acc)[2][2][4][2], const Unit& u, int wr, int wc, int fr, int fq) const {
;         const int row0 = u.pm * BM + wr * 64 + fr, col0 = u.pn * BM + wc * 32 + 8 * fq;
; #pragma unroll
;         for (int ai = 0; ai < 2; ++ai)
; #pragma unroll
;             for (int m = 0; m < 4; ++m) { const int row = row0 + ai * HALF + m * 16; const float rs = ss ? row_rs(ss, row) : 1.0f;
; #pragma unroll
;                 for (int bj = 0; bj < 2; ++bj) { const f32x4 v0 = acc[ai][bj][m][0] * rs, v1 = acc[ai][bj][m][1] * rs;
;                     u32x4 w; w.x = cvtpk(v0[0], v0[1]); w.y = cvtpk(v0[2], v0[3]); w.z = cvtpk(v1[0], v1[1]); w.w = cvtpk(v1[2], v1[3]);
;                     *(u32x4*)(O + (size_t)row * ldc + col0 + bj * HALF) = w; } }
; template <class Epi, class Sched, bool ALIGN_EPI = false, bool SP2 = false>
; __device__ __forceinline__ void gemm_phase(PG8_LAS unsigned char* lds, const Gemm g, const Sched& S, const Epi& E) {
;     ...
;         if constexpr (ALIGN_EPI) { if (wr == 0) PG8_BAR; }
;         if constexpr (!Epi::AFTER_DRAIN) { E(acc, cur, wr, wc, fr, fq); S.done(cur); }
	v_ffbh_u32_e32 v50, v49
	v_min_u32_e32 v50, 32, v50
	v_lshlrev_b64 v[48:49], v50, v[48:49]
	v_min_u32_e32 v48, 1, v48
	v_or_b32_e32 v48, v49, v48
	v_cvt_f32_u32_e32 v51, v48
	v_sub_u32_e32 v50, 32, v50
	v_lshl_add_u64 v[48:49], v[148:149], 0, s[0:1]
	s_mov_b64 s[0:1], 0x28000
	v_ldexp_f32 v50, v51, v50
	v_mul_f32_e32 v50, 0x2f800000, v50
	v_fmamk_f32 v50, v50, 0x3a800000, v158
	v_rsq_f32_e32 v50, v50
	s_nop 0
	v_pk_mul_f32 v[46:47], v[46:47], v[50:51] op_sel_hi:[1,0]
	v_pk_mul_f32 v[44:45], v[44:45], v[50:51] op_sel_hi:[1,0]
	v_pk_mul_f32 v[42:43], v[42:43], v[50:51] op_sel_hi:[1,0]
	v_pk_mul_f32 v[40:41], v[40:41], v[50:51] op_sel_hi:[1,0]
	v_pk_mul_f32 v[38:39], v[38:39], v[50:51] op_sel_hi:[1,0]
	v_pk_mul_f32 v[36:37], v[36:37], v[50:51] op_sel_hi:[1,0]
	v_pk_mul_f32 v[54:55], v[34:35], v[50:51] op_sel_hi:[1,0]
	v_pk_mul_f32 v[50:51], v[32:33], v[50:51] op_sel_hi:[1,0]
	v_cvt_pk_bf16_f32 v32, v44, v45
	v_cvt_pk_bf16_f32 v33, v46, v47
	v_cvt_pk_bf16_f32 v34, v40, v41
	v_cvt_pk_bf16_f32 v35, v42, v43
	v_cvt_pk_bf16_f32 v36, v36, v37
	v_cvt_pk_bf16_f32 v37, v38, v39
	v_cvt_pk_bf16_f32 v38, v50, v51
	v_cvt_pk_bf16_f32 v39, v54, v55
	global_store_dwordx4 v[52:53], v[32:35], off
	global_store_dwordx4 v[48:49], v[36:39], off offset:256
	global_load_dwordx2 v[32:33], v[150:151], off offset:1280
	s_waitcnt vmcnt(0)
	v_ffbh_u32_e32 v34, v33
	v_min_u32_e32 v34, 32, v34
	v_lshlrev_b64 v[32:33], v34, v[32:33]
	v_min_u32_e32 v32, 1, v32
	v_or_b32_e32 v32, v33, v32
	v_cvt_f32_u32_e32 v35, v32
	v_sub_u32_e32 v34, 32, v34
	v_add_co_u32_e32 v36, vcc, s3, v148
	v_ldexp_f32 v34, v35, v34
	v_mul_f32_e32 v34, 0x2f800000, v34
	v_fmamk_f32 v34, v34, 0x3a800000, v158
	v_rsq_f32_e32 v34, v34
	v_addc_co_u32_e32 v37, vcc, 0, v149, vcc
	v_lshl_add_u64 v[32:33], v[148:149], 0, s[0:1]
	v_pk_mul_f32 v[30:31], v[30:31], v[34:35] op_sel_hi:[1,0]
	v_pk_mul_f32 v[28:29], v[28:29], v[34:35] op_sel_hi:[1,0]
	v_pk_mul_f32 v[26:27], v[26:27], v[34:35] op_sel_hi:[1,0]
	v_pk_mul_f32 v[24:25], v[24:25], v[34:35] op_sel_hi:[1,0]
	v_pk_mul_f32 v[22:23], v[22:23], v[34:35] op_sel_hi:[1,0]
	v_pk_mul_f32 v[20:21], v[20:21], v[34:35] op_sel_hi:[1,0]
	v_pk_mul_f32 v[38:39], v[18:19], v[34:35] op_sel_hi:[1,0]
	v_pk_mul_f32 v[34:35], v[16:17], v[34:35] op_sel_hi:[1,0]
	v_cvt_pk_bf16_f32 v16, v28, v29
	v_cvt_pk_bf16_f32 v17, v30, v31
	v_cvt_pk_bf16_f32 v18, v24, v25
	v_cvt_pk_bf16_f32 v19, v26, v27
	v_cvt_pk_bf16_f32 v20, v20, v21
	v_cvt_pk_bf16_f32 v21, v22, v23
	v_cvt_pk_bf16_f32 v22, v34, v35
	v_cvt_pk_bf16_f32 v23, v38, v39
	global_store_dwordx4 v[36:37], v[16:19], off
	global_store_dwordx4 v[32:33], v[20:23], off offset:256
	global_load_dwordx2 v[16:17], v[150:151], off offset:1408
	s_mov_b64 s[0:1], 0x2c000
	s_mov_b32 s3, 0x2c000
	s_andn2_b64 vcc, exec, s[8:9]
	s_waitcnt vmcnt(0)
	v_ffbh_u32_e32 v18, v17
	v_min_u32_e32 v18, 32, v18
	v_lshlrev_b64 v[16:17], v18, v[16:17]
	v_min_u32_e32 v16, 1, v16
	v_or_b32_e32 v16, v17, v16
	v_cvt_f32_u32_e32 v19, v16
	v_sub_u32_e32 v18, 32, v18
	v_lshl_add_u64 v[16:17], v[148:149], 0, s[0:1]
	v_add_co_u32_e64 v20, s[0:1], s3, v148
	v_ldexp_f32 v18, v19, v18
	v_mul_f32_e32 v18, 0x2f800000, v18
	v_fmamk_f32 v18, v18, 0x3a800000, v158
	v_rsq_f32_e32 v18, v18
	v_addc_co_u32_e64 v21, s[0:1], 0, v149, s[0:1]
	s_mov_b64 s[0:1], -1
	v_pk_mul_f32 v[14:15], v[14:15], v[18:19] op_sel_hi:[1,0]
	v_pk_mul_f32 v[12:13], v[12:13], v[18:19] op_sel_hi:[1,0]
	v_pk_mul_f32 v[10:11], v[10:11], v[18:19] op_sel_hi:[1,0]
	v_pk_mul_f32 v[8:9], v[8:9], v[18:19] op_sel_hi:[1,0]
	v_pk_mul_f32 v[6:7], v[6:7], v[18:19] op_sel_hi:[1,0]
	v_pk_mul_f32 v[4:5], v[4:5], v[18:19] op_sel_hi:[1,0]
	v_pk_mul_f32 v[22:23], v[2:3], v[18:19] op_sel_hi:[1,0]
	v_pk_mul_f32 v[18:19], v[0:1], v[18:19] op_sel_hi:[1,0]
	v_cvt_pk_bf16_f32 v0, v12, v13
	v_cvt_pk_bf16_f32 v1, v14, v15
	v_cvt_pk_bf16_f32 v2, v8, v9
	v_cvt_pk_bf16_f32 v3, v10, v11
	v_cvt_pk_bf16_f32 v4, v4, v5
	v_cvt_pk_bf16_f32 v5, v6, v7
	v_cvt_pk_bf16_f32 v6, v18, v19
	v_cvt_pk_bf16_f32 v7, v22, v23
	global_store_dwordx4 v[20:21], v[0:3], off
	global_store_dwordx4 v[16:17], v[4:7], off offset:256
	s_cmp_eq_u64 s[44:45], 0
	s_cbranch_scc1 .Lxpost_3
	s_barrier

; #define PG8_STAGE(bufoff, gbase, voff) do { _Pragma("unroll") for (int _i = 0; _i < 2; ++_i) \
;         __builtin_amdgcn_global_load_lds((const unsigned*)((const char*)(gbase) + (voff)[_i]), (PG8_LAS unsigned*)(lds + (bufoff) + ldsw + _i * 8192), 16, 0, 0); } while (0)
; #define PG8_LDA(dst, b, h) do { _Pragma("unroll") for (int m = 0; m < 4; ++m) _Pragma("unroll") for (int k = 0; k < 2; ++k) dst[m][k] = *(const PG8_LAS bf16x8*)(lds + PG8_SA(b, h) + aoff + m * 2048 + k * 1024); } while (0)
; #define PG8_LDB(dst, b, h) do { _Pragma("unroll") for (int n = 0; n < 2; ++n) _Pragma("unroll") for (int k = 0; k < 2; ++k) dst[n][k] = *(const PG8_LAS bf16x8*)(lds + PG8_SB(b, h) + boff + n * 2048 + k * 1024); } while (0)
; #define PG8_MMA(ai, bj, At, Bt) do { __builtin_amdgcn_s_setprio(1); _Pragma("unroll") for (int m = 0; m < 4; ++m) _Pragma("unroll") for (int n = 0; n < 2; ++n) _Pragma("unroll") for (int k = 0; k < 2; ++k) \
;         acc[ai][bj][m][n] = __builtin_amdgcn_mfma_f32_16x16x32_bf16(Bt[n][k], At[m][k], acc[ai][bj][m][n], 0, 0, 0); __builtin_amdgcn_s_setprio(0); } while (0)
; #define PG8_BAR __builtin_amdgcn_s_barrier()
; template <class Epi, class Sched, bool ALIGN_EPI = false, bool SP2 = false>
; __device__ __forceinline__ void gemm_phase(PG8_LAS unsigned char* lds, const Gemm g, const Sched& S, const Epi& E) {
;     ...
;         const bool has_next = S.next(ui + 1, nxt);
;         const char* nA = has_next ? (const char*)g.A + (size_t)nxt.pm * tstep : cA; const char* nB = has_next ? (const char*)g.Bt + (size_t)nxt.pn * tstep : cB;
;         for (int t = 0; t < nt; t += 2) {
;             const bool last = (t == nt - 2);
;             const char* a1 = cA + (size_t)(t + 1) * kstep;
;             const char* a2 = last ? nA : cA + (size_t)(t + 2) * kstep; const char* b2 = last ? nB : cB + (size_t)(t + 2) * kstep;
;             const char* a3 = a2 + kstep; const char* b3 = b2 + kstep;
;             if (last && has_next) S.a_ready(nxt);
;             if constexpr (SP2) {
;             PG8_LDB(B0, 0, 0); PG8_LDB(B1, 0, 1); PG8_SCHED; PG8_LDA(At, 0, 0); PG8_STAGE(PG8_SA(1, 1), a1 + hstep, voffA);
;             PG8_WAIT_V(8); PG8_WAIT_L(0); PG8_BAR; PG8_MMA(0, 0, At, B0); PG8_MMA(0, 1, At, B1); PG8_BAR; PG8_SCHED;
;             PG8_LDA(At, 0, 1); PG8_STAGE(PG8_SB(0, 0), b2, voffB); PG8_STAGE(PG8_SB(0, 1), b2 + hstep, voffB); PG8_STAGE(PG8_SA(0, 0), a2, voffA);
.LBB0_872:
	s_ashr_i32 s49, s48, 31
	s_lshl_b64 s[50:51], s[48:49], 18
	s_add_u32 s50, s92, s50
	s_addc_u32 s51, s93, s51
	s_and_b64 s[52:53], s[10:11], exec
	s_cselect_b32 s49, s51, s59
	s_cselect_b32 s55, s50, s58
	s_ashr_i32 s45, s44, 31
	s_lshl_b64 s[52:53], s[44:45], 18
	s_add_u32 s52, s76, s52
	s_addc_u32 s53, s77, s53
	s_and_b64 s[62:63], s[10:11], exec
	s_cselect_b32 s45, s53, s61
	s_cselect_b32 s84, s52, s60
	s_add_u32 s58, s58, 0x20080
	s_addc_u32 s59, s59, 0
	s_add_u32 s85, s60, 0x100
	s_addc_u32 s86, s61, 0
	s_mov_b32 s87, -2
	s_waitcnt lgkmcnt(0)
	ds_read_b128 v[144:147], v151
	ds_read_b128 v[156:159], v151 offset:1024
	ds_read_b128 v[160:163], v151 offset:2048
	ds_read_b128 v[164:167], v151 offset:3072
	ds_read_b128 v[168:171], v152
	ds_read_b128 v[172:175], v152 offset:1024
	ds_read_b128 v[176:179], v152 offset:2048
	ds_read_b128 v[182:185], v152 offset:3072
	s_add_u32 s3, s58, 0xfffe0080
	s_addc_u32 s33, s59, -1
	s_cmp_eq_u32 s87, 4
	s_cselect_b32 s63, s49, s33
	s_cselect_b32 s62, s55, s3
	s_cselect_b32 s61, s45, s86
	s_cselect_b32 s60, s84, s85
	v_lshl_add_u64 v[202:203], s[58:59], 0, v[136:137]
	s_add_i32 m0, s15, 0xc000
	ds_read_b128 v[186:189], v153
	ds_read_b128 v[190:193], v153 offset:1024
	ds_read_b128 v[194:197], v153 offset:2048
	ds_read_b128 v[198:201], v153 offset:3072
	ds_read_b128 v[208:211], v153 offset:4096
	ds_read_b128 v[212:215], v153 offset:5120
	ds_read_b128 v[216:219], v153 offset:6144
	ds_read_b128 v[220:223], v153 offset:7168
	global_load_lds_dwordx4 v[202:203], off
	v_lshl_add_u64 v[202:203], s[58:59], 0, v[138:139]
	s_add_i32 m0, s15, 0xe000
	s_nop 0
	global_load_lds_dwordx4 v[202:203], off
	s_waitcnt vmcnt(8)
	s_waitcnt lgkmcnt(0)
	s_barrier
	s_setprio 1
	s_waitcnt lgkmcnt(0)
	v_mfma_f32_16x16x32_bf16 v[124:127], v[144:147], v[186:189], 0
	v_mfma_f32_16x16x32_bf16 v[120:123], v[160:163], v[186:189], 0
	v_mfma_f32_16x16x32_bf16 v[108:111], v[144:147], v[194:197], 0
	v_mfma_f32_16x16x32_bf16 v[104:107], v[160:163], v[194:197], 0
	v_mfma_f32_16x16x32_bf16 v[92:95], v[144:147], v[208:211], 0
	v_mfma_f32_16x16x32_bf16 v[88:91], v[160:163], v[208:211], 0
	v_mfma_f32_16x16x32_bf16 v[76:79], v[144:147], v[216:219], 0
	v_mfma_f32_16x16x32_bf16 v[72:75], v[160:163], v[216:219], 0
	v_mfma_f32_16x16x32_bf16 v[124:127], v[156:159], v[190:193], v[124:127]
	v_mfma_f32_16x16x32_bf16 v[120:123], v[164:167], v[190:193], v[120:123]
	v_mfma_f32_16x16x32_bf16 v[108:111], v[156:159], v[198:201], v[108:111]
	v_mfma_f32_16x16x32_bf16 v[104:107], v[164:167], v[198:201], v[104:107]
	v_mfma_f32_16x16x32_bf16 v[92:95], v[156:159], v[212:215], v[92:95]
	v_mfma_f32_16x16x32_bf16 v[88:91], v[164:167], v[212:215], v[88:91]
	v_mfma_f32_16x16x32_bf16 v[76:79], v[156:159], v[220:223], v[76:79]
	v_mfma_f32_16x16x32_bf16 v[72:75], v[164:167], v[220:223], v[72:75]
	s_setprio 0
	s_setprio 1
	v_mfma_f32_16x16x32_bf16 v[116:119], v[168:171], v[186:189], 0
	v_mfma_f32_16x16x32_bf16 v[112:115], v[176:179], v[186:189], 0
	v_mfma_f32_16x16x32_bf16 v[100:103], v[168:171], v[194:197], 0
	v_mfma_f32_16x16x32_bf16 v[96:99], v[176:179], v[194:197], 0
	v_mfma_f32_16x16x32_bf16 v[84:87], v[168:171], v[208:211], 0
	v_mfma_f32_16x16x32_bf16 v[80:83], v[176:179], v[208:211], 0
	v_mfma_f32_16x16x32_bf16 v[68:71], v[168:171], v[216:219], 0
	v_mfma_f32_16x16x32_bf16 v[64:67], v[176:179], v[216:219], 0
	v_mfma_f32_16x16x32_bf16 v[116:119], v[172:175], v[190:193], v[116:119]
	v_mfma_f32_16x16x32_bf16 v[112:115], v[182:185], v[190:193], v[112:115]
	v_mfma_f32_16x16x32_bf16 v[100:103], v[172:175], v[198:201], v[100:103]
	v_mfma_f32_16x16x32_bf16 v[96:99], v[182:185], v[198:201], v[96:99]
	v_mfma_f32_16x16x32_bf16 v[84:87], v[172:175], v[212:215], v[84:87]
	v_mfma_f32_16x16x32_bf16 v[80:83], v[182:185], v[212:215], v[80:83]
	v_mfma_f32_16x16x32_bf16 v[68:71], v[172:175], v[220:223], v[68:71]
	v_mfma_f32_16x16x32_bf16 v[64:67], v[182:185], v[220:223], v[64:67]
	s_setprio 0
	s_barrier
	s_add_i32 s3, s74, s14
	v_lshl_add_u64 v[202:203], s[60:61], 0, v[130:131]
	s_mov_b32 m0, s3
	ds_read_b128 v[186:189], v153 offset:16384
	ds_read_b128 v[190:193], v153 offset:17408
	ds_read_b128 v[194:197], v153 offset:18432
	ds_read_b128 v[198:201], v153 offset:19456
	ds_read_b128 v[208:211], v153 offset:20480
	ds_read_b128 v[212:215], v153 offset:21504
	ds_read_b128 v[216:219], v153 offset:22528
	ds_read_b128 v[220:223], v153 offset:23552
	global_load_lds_dwordx4 v[202:203], off
	s_add_i32 m0, s3, 0x2000
	s_add_u32 s78, s60, 0x20000
	v_lshl_add_u64 v[224:225], s[60:61], 0, v[134:135]
	s_addc_u32 s79, s61, 0
	s_add_i32 s3, s75, s14
	global_load_lds_dwordx4 v[224:225], off
	v_lshl_add_u64 v[226:227], s[78:79], 0, v[130:131]
	s_mov_b32 m0, s3
	global_load_lds_dwordx4 v[226:227], off
	v_lshl_add_u64 v[226:227], s[78:79], 0, v[134:135]
	s_add_i32 m0, s3, 0x2000
	s_nop 0
	global_load_lds_dwordx4 v[226:227], off
	s_waitcnt vmcnt(6)
	s_waitcnt lgkmcnt(0)
	s_barrier
; #define PG8_STAGE(bufoff, gbase, voff) do { _Pragma("unroll") for (int _i = 0; _i < 2; ++_i) \
;         __builtin_amdgcn_global_load_lds((const unsigned*)((const char*)(gbase) + (voff)[_i]), (PG8_LAS unsigned*)(lds + (bufoff) + ldsw + _i * 8192), 16, 0, 0); } while (0)
; #define PG8_LDA(dst, b, h) do { _Pragma("unroll") for (int m = 0; m < 4; ++m) _Pragma("unroll") for (int k = 0; k < 2; ++k) dst[m][k] = *(const PG8_LAS bf16x8*)(lds + PG8_SA(b, h) + aoff + m * 2048 + k * 1024); } while (0)
; #define PG8_LDB(dst, b, h) do { _Pragma("unroll") for (int n = 0; n < 2; ++n) _Pragma("unroll") for (int k = 0; k < 2; ++k) dst[n][k] = *(const PG8_LAS bf16x8*)(lds + PG8_SB(b, h) + boff + n * 2048 + k * 1024); } while (0)
; #define PG8_MMA(ai, bj, At, Bt) do { __builtin_amdgcn_s_setprio(1); _Pragma("unroll") for (int m = 0; m < 4; ++m) _Pragma("unroll") for (int n = 0; n < 2; ++n) _Pragma("unroll") for (int k = 0; k < 2; ++k) \
;         acc[ai][bj][m][n] = __builtin_amdgcn_mfma_f32_16x16x32_bf16(Bt[n][k], At[m][k], acc[ai][bj][m][n], 0, 0, 0); __builtin_amdgcn_s_setprio(0); } while (0)
; #define PG8_WAIT_V(n) asm volatile("s_waitcnt vmcnt(" #n ")" ::: "memory")
; #define PG8_WAIT_L(n) asm volatile("s_waitcnt lgkmcnt(" #n ")" ::: "memory")
; #define PG8_BAR __builtin_amdgcn_s_barrier()
; #define PG8_SCHED __builtin_amdgcn_sched_barrier(0)
; template <class Epi, class Sched, bool ALIGN_EPI = false, bool SP2 = false>
; __device__ __forceinline__ void gemm_phase(PG8_LAS unsigned char* lds, const Gemm g, const Sched& S, const Epi& E) {
;     ...
;             PG8_WAIT_V(8); PG8_WAIT_L(0); PG8_BAR; PG8_MMA(0, 0, At, B0); PG8_MMA(0, 1, At, B1); PG8_BAR; PG8_SCHED;
;             PG8_LDA(At, 0, 1); PG8_STAGE(PG8_SB(0, 0), b2, voffB); PG8_STAGE(PG8_SB(0, 1), b2 + hstep, voffB); PG8_STAGE(PG8_SA(0, 0), a2, voffA);
;             PG8_WAIT_V(8); PG8_WAIT_L(0); PG8_BAR; PG8_MMA(1, 0, At, B0); PG8_MMA(1, 1, At, B1); PG8_BAR; PG8_SCHED;
;             PG8_LDB(B0, 1, 0); PG8_LDB(B1, 1, 1); PG8_SCHED; PG8_LDA(At, 1, 0); PG8_STAGE(PG8_SA(0, 1), a2 + hstep, voffA);
;             PG8_WAIT_V(8); PG8_WAIT_L(0); PG8_BAR; PG8_MMA(0, 0, At, B0); PG8_MMA(0, 1, At, B1); PG8_BAR; PG8_SCHED;
	s_setprio 1
	s_waitcnt lgkmcnt(0)
	v_mfma_f32_16x16x32_bf16 v[60:63], v[144:147], v[186:189], 0
	v_mfma_f32_16x16x32_bf16 v[56:59], v[160:163], v[186:189], 0
	v_mfma_f32_16x16x32_bf16 v[44:47], v[144:147], v[194:197], 0
	v_mfma_f32_16x16x32_bf16 v[40:43], v[160:163], v[194:197], 0
	v_mfma_f32_16x16x32_bf16 v[28:31], v[144:147], v[208:211], 0
	v_mfma_f32_16x16x32_bf16 v[24:27], v[160:163], v[208:211], 0
	v_mfma_f32_16x16x32_bf16 v[12:15], v[144:147], v[216:219], 0
	v_mfma_f32_16x16x32_bf16 v[8:11], v[160:163], v[216:219], 0
	v_mfma_f32_16x16x32_bf16 v[60:63], v[156:159], v[190:193], v[60:63]
	v_mfma_f32_16x16x32_bf16 v[56:59], v[164:167], v[190:193], v[56:59]
	v_mfma_f32_16x16x32_bf16 v[44:47], v[156:159], v[198:201], v[44:47]
	v_mfma_f32_16x16x32_bf16 v[40:43], v[164:167], v[198:201], v[40:43]
	v_mfma_f32_16x16x32_bf16 v[28:31], v[156:159], v[212:215], v[28:31]
	v_mfma_f32_16x16x32_bf16 v[24:27], v[164:167], v[212:215], v[24:27]
	v_lshl_add_u64 v[226:227], s[62:63], 0, v[128:129]
	s_mov_b32 m0, s15
	s_nop 0
	global_load_lds_dwordx4 v[226:227], off
	v_mfma_f32_16x16x32_bf16 v[12:15], v[156:159], v[220:223], v[12:15]
	v_mfma_f32_16x16x32_bf16 v[8:11], v[164:167], v[220:223], v[8:11]
	s_setprio 0
	s_setprio 1
	v_mfma_f32_16x16x32_bf16 v[52:55], v[168:171], v[186:189], 0
	v_mfma_f32_16x16x32_bf16 v[48:51], v[176:179], v[186:189], 0
	v_mfma_f32_16x16x32_bf16 v[36:39], v[168:171], v[194:197], 0
	v_mfma_f32_16x16x32_bf16 v[32:35], v[176:179], v[194:197], 0
	v_mfma_f32_16x16x32_bf16 v[20:23], v[168:171], v[208:211], 0
	v_mfma_f32_16x16x32_bf16 v[16:19], v[176:179], v[208:211], 0
	v_mfma_f32_16x16x32_bf16 v[4:7], v[168:171], v[216:219], 0
	v_mfma_f32_16x16x32_bf16 v[0:3], v[176:179], v[216:219], 0
	v_mfma_f32_16x16x32_bf16 v[52:55], v[172:175], v[190:193], v[52:55]
	v_mfma_f32_16x16x32_bf16 v[48:51], v[182:185], v[190:193], v[48:51]
	v_mfma_f32_16x16x32_bf16 v[36:39], v[172:175], v[198:201], v[36:39]
	v_mfma_f32_16x16x32_bf16 v[32:35], v[182:185], v[198:201], v[32:35]
	v_mfma_f32_16x16x32_bf16 v[20:23], v[172:175], v[212:215], v[20:23]
	v_mfma_f32_16x16x32_bf16 v[16:19], v[182:185], v[212:215], v[16:19]
	v_lshl_add_u64 v[228:229], s[62:63], 0, v[132:133]
	s_mov_b32 m0, s34
	s_nop 0
	global_load_lds_dwordx4 v[228:229], off
	v_mfma_f32_16x16x32_bf16 v[4:7], v[172:175], v[220:223], v[4:7]
	v_mfma_f32_16x16x32_bf16 v[0:3], v[182:185], v[220:223], v[0:3]
	s_setprio 0
	s_barrier
	s_add_i32 s3, 0, 0x18000
	v_add_u32_e32 v155, s3, v149
	s_add_i32 s33, 0, 0x1c000
	ds_read_b128 v[144:147], v155
	ds_read_b128 v[156:159], v155 offset:1024
	ds_read_b128 v[160:163], v155 offset:2048
	ds_read_b128 v[164:167], v155 offset:3072
	v_add_u32_e32 v155, s33, v149
	ds_read_b128 v[168:171], v155
	ds_read_b128 v[172:175], v155 offset:1024
	ds_read_b128 v[176:179], v155 offset:2048
	ds_read_b128 v[182:185], v155 offset:3072
	s_add_u32 s62, s62, 0x20000
	s_addc_u32 s63, s63, 0
	s_mov_b32 m0, s57
	v_lshl_add_u64 v[230:231], s[62:63], 0, v[128:129]
	ds_read_b128 v[186:189], v153 offset:32768
	ds_read_b128 v[190:193], v153 offset:33792
	ds_read_b128 v[194:197], v153 offset:34816
	ds_read_b128 v[198:201], v153 offset:35840
	ds_read_b128 v[208:211], v153 offset:36864
	ds_read_b128 v[212:215], v153 offset:37888
	ds_read_b128 v[216:219], v153 offset:38912
	ds_read_b128 v[220:223], v153 offset:39936
	global_load_lds_dwordx4 v[230:231], off
	v_lshl_add_u64 v[230:231], s[62:63], 0, v[132:133]
	s_mov_b32 m0, s64
	s_nop 0
	global_load_lds_dwordx4 v[230:231], off
	s_waitcnt vmcnt(8)
	s_waitcnt lgkmcnt(0)
	s_barrier
	s_setprio 1
	s_waitcnt lgkmcnt(0)
	v_mfma_f32_16x16x32_bf16 v[124:127], v[144:147], v[186:189], v[124:127]
	v_mfma_f32_16x16x32_bf16 v[120:123], v[160:163], v[186:189], v[120:123]
	v_mfma_f32_16x16x32_bf16 v[108:111], v[144:147], v[194:197], v[108:111]
	v_mfma_f32_16x16x32_bf16 v[104:107], v[160:163], v[194:197], v[104:107]
	v_mfma_f32_16x16x32_bf16 v[92:95], v[144:147], v[208:211], v[92:95]
	v_mfma_f32_16x16x32_bf16 v[88:91], v[160:163], v[208:211], v[88:91]
	v_mfma_f32_16x16x32_bf16 v[76:79], v[144:147], v[216:219], v[76:79]
	v_mfma_f32_16x16x32_bf16 v[72:75], v[160:163], v[216:219], v[72:75]
	v_mfma_f32_16x16x32_bf16 v[124:127], v[156:159], v[190:193], v[124:127]
	v_mfma_f32_16x16x32_bf16 v[120:123], v[164:167], v[190:193], v[120:123]
	v_mfma_f32_16x16x32_bf16 v[108:111], v[156:159], v[198:201], v[108:111]
	v_mfma_f32_16x16x32_bf16 v[104:107], v[164:167], v[198:201], v[104:107]
	v_mfma_f32_16x16x32_bf16 v[92:95], v[156:159], v[212:215], v[92:95]
	v_mfma_f32_16x16x32_bf16 v[88:91], v[164:167], v[212:215], v[88:91]
	v_mfma_f32_16x16x32_bf16 v[76:79], v[156:159], v[220:223], v[76:79]
	v_mfma_f32_16x16x32_bf16 v[72:75], v[164:167], v[220:223], v[72:75]
	s_setprio 0
	s_setprio 1
	v_mfma_f32_16x16x32_bf16 v[116:119], v[168:171], v[186:189], v[116:119]
	v_mfma_f32_16x16x32_bf16 v[112:115], v[176:179], v[186:189], v[112:115]
	v_mfma_f32_16x16x32_bf16 v[100:103], v[168:171], v[194:197], v[100:103]
	v_mfma_f32_16x16x32_bf16 v[96:99], v[176:179], v[194:197], v[96:99]
	v_mfma_f32_16x16x32_bf16 v[84:87], v[168:171], v[208:211], v[84:87]
	v_mfma_f32_16x16x32_bf16 v[80:83], v[176:179], v[208:211], v[80:83]
	v_mfma_f32_16x16x32_bf16 v[68:71], v[168:171], v[216:219], v[68:71]
	v_mfma_f32_16x16x32_bf16 v[64:67], v[176:179], v[216:219], v[64:67]
	v_mfma_f32_16x16x32_bf16 v[116:119], v[172:175], v[190:193], v[116:119]
	v_mfma_f32_16x16x32_bf16 v[112:115], v[182:185], v[190:193], v[112:115]
	v_mfma_f32_16x16x32_bf16 v[100:103], v[172:175], v[198:201], v[100:103]
	v_mfma_f32_16x16x32_bf16 v[96:99], v[182:185], v[198:201], v[96:99]
	v_mfma_f32_16x16x32_bf16 v[84:87], v[172:175], v[212:215], v[84:87]
	v_mfma_f32_16x16x32_bf16 v[80:83], v[182:185], v[212:215], v[80:83]
	v_mfma_f32_16x16x32_bf16 v[68:71], v[172:175], v[220:223], v[68:71]
	v_mfma_f32_16x16x32_bf16 v[64:67], v[182:185], v[220:223], v[64:67]
	s_setprio 0
	s_barrier
; #define PG8_STAGE(bufoff, gbase, voff) do { _Pragma("unroll") for (int _i = 0; _i < 2; ++_i) \
;         __builtin_amdgcn_global_load_lds((const unsigned*)((const char*)(gbase) + (voff)[_i]), (PG8_LAS unsigned*)(lds + (bufoff) + ldsw + _i * 8192), 16, 0, 0); } while (0)
; #define PG8_LDA(dst, b, h) do { _Pragma("unroll") for (int m = 0; m < 4; ++m) _Pragma("unroll") for (int k = 0; k < 2; ++k) dst[m][k] = *(const PG8_LAS bf16x8*)(lds + PG8_SA(b, h) + aoff + m * 2048 + k * 1024); } while (0)
; #define PG8_LDB(dst, b, h) do { _Pragma("unroll") for (int n = 0; n < 2; ++n) _Pragma("unroll") for (int k = 0; k < 2; ++k) dst[n][k] = *(const PG8_LAS bf16x8*)(lds + PG8_SB(b, h) + boff + n * 2048 + k * 1024); } while (0)
; #define PG8_MMA(ai, bj, At, Bt) do { __builtin_amdgcn_s_setprio(1); _Pragma("unroll") for (int m = 0; m < 4; ++m) _Pragma("unroll") for (int n = 0; n < 2; ++n) _Pragma("unroll") for (int k = 0; k < 2; ++k) \
;         acc[ai][bj][m][n] = __builtin_amdgcn_mfma_f32_16x16x32_bf16(Bt[n][k], At[m][k], acc[ai][bj][m][n], 0, 0, 0); __builtin_amdgcn_s_setprio(0); } while (0)
; #define PG8_WAIT_V(n) asm volatile("s_waitcnt vmcnt(" #n ")" ::: "memory")
; template <class Epi, class Sched, bool ALIGN_EPI = false, bool SP2 = false>
; __device__ __forceinline__ void gemm_phase(PG8_LAS unsigned char* lds, const Gemm g, const Sched& S, const Epi& E) {
;     ...
;             PG8_LDB(B0, 0, 0); PG8_LDB(B1, 0, 1); PG8_SCHED; PG8_LDA(At, 0, 0); PG8_STAGE(PG8_SA(1, 1), a1 + hstep, voffA);
;             PG8_WAIT_V(8); PG8_WAIT_L(0); PG8_BAR; PG8_MMA(0, 0, At, B0); PG8_MMA(0, 1, At, B1); PG8_BAR; PG8_SCHED;
;             PG8_LDA(At, 0, 1); PG8_STAGE(PG8_SB(0, 0), b2, voffB); PG8_STAGE(PG8_SB(0, 1), b2 + hstep, voffB); PG8_STAGE(PG8_SA(0, 0), a2, voffA);
;             PG8_WAIT_V(8); PG8_WAIT_L(0); PG8_BAR; PG8_MMA(1, 0, At, B0); PG8_MMA(1, 1, At, B1); PG8_BAR; PG8_SCHED;
;             PG8_LDB(B0, 1, 0); PG8_LDB(B1, 1, 1); PG8_SCHED; PG8_LDA(At, 1, 0); PG8_STAGE(PG8_SA(0, 1), a2 + hstep, voffA);
;             PG8_WAIT_V(8); PG8_WAIT_L(0); PG8_BAR; PG8_MMA(0, 0, At, B0); PG8_MMA(0, 1, At, B1); PG8_BAR; PG8_SCHED;
;             PG8_LDA(At, 1, 1); PG8_STAGE(PG8_SB(1, 0), b3, voffB); PG8_STAGE(PG8_SB(1, 1), b3 + hstep, voffB); PG8_STAGE(PG8_SA(1, 0), a3, voffA);
;             PG8_WAIT_V(8); PG8_WAIT_L(0); PG8_BAR; PG8_MMA(1, 0, At, B0); PG8_MMA(1, 1, At, B1); PG8_BAR; PG8_SCHED;
	s_add_i32 s3, s3, s14
	v_lshl_add_u64 v[202:203], v[202:203], 0, s[38:39]
	s_mov_b32 m0, s3
	ds_read_b128 v[186:189], v153 offset:49152
	ds_read_b128 v[190:193], v153 offset:50176
	ds_read_b128 v[194:197], v153 offset:51200
	ds_read_b128 v[198:201], v153 offset:52224
	ds_read_b128 v[208:211], v153 offset:53248
	ds_read_b128 v[212:215], v153 offset:54272
	ds_read_b128 v[216:219], v153 offset:55296
	ds_read_b128 v[220:223], v153 offset:56320
	global_load_lds_dwordx4 v[202:203], off
	s_add_i32 m0, s3, 0x2000
	s_add_u32 s60, s60, 0x20080
	v_lshl_add_u64 v[202:203], v[224:225], 0, s[38:39]
	s_addc_u32 s61, s61, 0
	s_add_i32 s3, s33, s14
	global_load_lds_dwordx4 v[202:203], off
	v_lshl_add_u64 v[202:203], s[60:61], 0, v[130:131]
	s_mov_b32 m0, s3
	s_nop 0
	global_load_lds_dwordx4 v[202:203], off
	v_lshl_add_u64 v[202:203], s[60:61], 0, v[134:135]
	s_add_i32 m0, s3, 0x2000
	s_nop 0
	global_load_lds_dwordx4 v[202:203], off
	s_waitcnt vmcnt(6)
	s_waitcnt lgkmcnt(0)
	s_barrier
	s_setprio 1
	s_waitcnt lgkmcnt(0)
	v_mfma_f32_16x16x32_bf16 v[60:63], v[144:147], v[186:189], v[60:63]
	v_mfma_f32_16x16x32_bf16 v[56:59], v[160:163], v[186:189], v[56:59]
	v_mfma_f32_16x16x32_bf16 v[44:47], v[144:147], v[194:197], v[44:47]
	v_mfma_f32_16x16x32_bf16 v[40:43], v[160:163], v[194:197], v[40:43]
	v_mfma_f32_16x16x32_bf16 v[28:31], v[144:147], v[208:211], v[28:31]
	v_mfma_f32_16x16x32_bf16 v[24:27], v[160:163], v[208:211], v[24:27]
	v_mfma_f32_16x16x32_bf16 v[12:15], v[144:147], v[216:219], v[12:15]
	v_mfma_f32_16x16x32_bf16 v[8:11], v[160:163], v[216:219], v[8:11]
	v_mfma_f32_16x16x32_bf16 v[60:63], v[156:159], v[190:193], v[60:63]
	v_mfma_f32_16x16x32_bf16 v[56:59], v[164:167], v[190:193], v[56:59]
	v_mfma_f32_16x16x32_bf16 v[44:47], v[156:159], v[198:201], v[44:47]
	v_mfma_f32_16x16x32_bf16 v[40:43], v[164:167], v[198:201], v[40:43]
	v_mfma_f32_16x16x32_bf16 v[28:31], v[156:159], v[212:215], v[28:31]
	v_mfma_f32_16x16x32_bf16 v[24:27], v[164:167], v[212:215], v[24:27]
	v_lshl_add_u64 v[202:203], v[226:227], 0, s[38:39]
	s_mov_b32 m0, s66
	s_nop 0
	global_load_lds_dwordx4 v[202:203], off
	v_mfma_f32_16x16x32_bf16 v[12:15], v[156:159], v[220:223], v[12:15]
	v_mfma_f32_16x16x32_bf16 v[8:11], v[164:167], v[220:223], v[8:11]
	s_setprio 0
	s_setprio 1
	v_mfma_f32_16x16x32_bf16 v[52:55], v[168:171], v[186:189], v[52:55]
	v_mfma_f32_16x16x32_bf16 v[48:51], v[176:179], v[186:189], v[48:51]
	v_mfma_f32_16x16x32_bf16 v[36:39], v[168:171], v[194:197], v[36:39]
	v_mfma_f32_16x16x32_bf16 v[32:35], v[176:179], v[194:197], v[32:35]
	v_mfma_f32_16x16x32_bf16 v[20:23], v[168:171], v[208:211], v[20:23]
	v_mfma_f32_16x16x32_bf16 v[16:19], v[176:179], v[208:211], v[16:19]
	v_mfma_f32_16x16x32_bf16 v[4:7], v[168:171], v[216:219], v[4:7]
	v_mfma_f32_16x16x32_bf16 v[0:3], v[176:179], v[216:219], v[0:3]
	v_mfma_f32_16x16x32_bf16 v[52:55], v[172:175], v[190:193], v[52:55]
	v_mfma_f32_16x16x32_bf16 v[48:51], v[182:185], v[190:193], v[48:51]
	v_mfma_f32_16x16x32_bf16 v[36:39], v[172:175], v[198:201], v[36:39]
	v_mfma_f32_16x16x32_bf16 v[32:35], v[182:185], v[198:201], v[32:35]
	v_mfma_f32_16x16x32_bf16 v[20:23], v[172:175], v[212:215], v[20:23]
	v_mfma_f32_16x16x32_bf16 v[16:19], v[182:185], v[212:215], v[16:19]
	v_lshl_add_u64 v[202:203], v[228:229], 0, s[38:39]
	s_mov_b32 m0, s67
	s_nop 0
	global_load_lds_dwordx4 v[202:203], off
	v_mfma_f32_16x16x32_bf16 v[4:7], v[172:175], v[220:223], v[4:7]
	v_mfma_f32_16x16x32_bf16 v[0:3], v[182:185], v[220:223], v[0:3]
	s_setprio 0
	s_barrier
	s_add_i32 s87, s87, 2
	s_add_u32 s58, s58, 0x100
	s_addc_u32 s59, s59, 0
	s_add_u32 s85, s85, 0x100
	s_addc_u32 s86, s86, 0
.LBB0_873:
	ds_read_b128 v[144:147], v151
	ds_read_b128 v[156:159], v151 offset:1024
	ds_read_b128 v[160:163], v151 offset:2048
	ds_read_b128 v[164:167], v151 offset:3072
	ds_read_b128 v[168:171], v152
	ds_read_b128 v[172:175], v152 offset:1024
	ds_read_b128 v[176:179], v152 offset:2048
	ds_read_b128 v[182:185], v152 offset:3072
	s_add_u32 s3, s58, 0xfffe0080
	s_addc_u32 s33, s59, -1
	s_cmp_eq_u32 s87, 4
	s_cselect_b32 s63, s49, s33
	s_cselect_b32 s62, s55, s3
	s_cselect_b32 s61, s45, s86
	s_cselect_b32 s60, s84, s85
	v_lshl_add_u64 v[202:203], s[58:59], 0, v[136:137]
	s_add_i32 m0, s15, 0xc000
	ds_read_b128 v[186:189], v153
	ds_read_b128 v[190:193], v153 offset:1024
	ds_read_b128 v[194:197], v153 offset:2048
	ds_read_b128 v[198:201], v153 offset:3072
	ds_read_b128 v[208:211], v153 offset:4096
	ds_read_b128 v[212:215], v153 offset:5120
	ds_read_b128 v[216:219], v153 offset:6144
	ds_read_b128 v[220:223], v153 offset:7168
	global_load_lds_dwordx4 v[202:203], off
	v_lshl_add_u64 v[202:203], s[58:59], 0, v[138:139]
	s_add_i32 m0, s15, 0xe000
	s_nop 0
	global_load_lds_dwordx4 v[202:203], off
	s_waitcnt vmcnt(8)
	s_waitcnt lgkmcnt(0)
	s_barrier
; #define PG8_STAGE(bufoff, gbase, voff) do { _Pragma("unroll") for (int _i = 0; _i < 2; ++_i) \
;         __builtin_amdgcn_global_load_lds((const unsigned*)((const char*)(gbase) + (voff)[_i]), (PG8_LAS unsigned*)(lds + (bufoff) + ldsw + _i * 8192), 16, 0, 0); } while (0)
; #define PG8_LDA(dst, b, h) do { _Pragma("unroll") for (int m = 0; m < 4; ++m) _Pragma("unroll") for (int k = 0; k < 2; ++k) dst[m][k] = *(const PG8_LAS bf16x8*)(lds + PG8_SA(b, h) + aoff + m * 2048 + k * 1024); } while (0)
; #define PG8_LDB(dst, b, h) do { _Pragma("unroll") for (int n = 0; n < 2; ++n) _Pragma("unroll") for (int k = 0; k < 2; ++k) dst[n][k] = *(const PG8_LAS bf16x8*)(lds + PG8_SB(b, h) + boff + n * 2048 + k * 1024); } while (0)
; #define PG8_MMA(ai, bj, At, Bt) do { __builtin_amdgcn_s_setprio(1); _Pragma("unroll") for (int m = 0; m < 4; ++m) _Pragma("unroll") for (int n = 0; n < 2; ++n) _Pragma("unroll") for (int k = 0; k < 2; ++k) \
;         acc[ai][bj][m][n] = __builtin_amdgcn_mfma_f32_16x16x32_bf16(Bt[n][k], At[m][k], acc[ai][bj][m][n], 0, 0, 0); __builtin_amdgcn_s_setprio(0); } while (0)
; #define PG8_WAIT_V(n) asm volatile("s_waitcnt vmcnt(" #n ")" ::: "memory")
; #define PG8_WAIT_L(n) asm volatile("s_waitcnt lgkmcnt(" #n ")" ::: "memory")
; #define PG8_BAR __builtin_amdgcn_s_barrier()
; #define PG8_SCHED __builtin_amdgcn_sched_barrier(0)
; template <class Epi, class Sched, bool ALIGN_EPI = false, bool SP2 = false>
; __device__ __forceinline__ void gemm_phase(PG8_LAS unsigned char* lds, const Gemm g, const Sched& S, const Epi& E) {
;     ...
;             PG8_WAIT_V(8); PG8_WAIT_L(0); PG8_BAR; PG8_MMA(0, 0, At, B0); PG8_MMA(0, 1, At, B1); PG8_BAR; PG8_SCHED;
;             PG8_LDA(At, 0, 1); PG8_STAGE(PG8_SB(0, 0), b2, voffB); PG8_STAGE(PG8_SB(0, 1), b2 + hstep, voffB); PG8_STAGE(PG8_SA(0, 0), a2, voffA);
;             PG8_WAIT_V(8); PG8_WAIT_L(0); PG8_BAR; PG8_MMA(1, 0, At, B0); PG8_MMA(1, 1, At, B1); PG8_BAR; PG8_SCHED;
;             PG8_LDB(B0, 1, 0); PG8_LDB(B1, 1, 1); PG8_SCHED; PG8_LDA(At, 1, 0); PG8_STAGE(PG8_SA(0, 1), a2 + hstep, voffA);
;             PG8_WAIT_V(8); PG8_WAIT_L(0); PG8_BAR; PG8_MMA(0, 0, At, B0); PG8_MMA(0, 1, At, B1); PG8_BAR; PG8_SCHED;
	s_setprio 1
	s_waitcnt lgkmcnt(0)
	v_mfma_f32_16x16x32_bf16 v[124:127], v[144:147], v[186:189], v[124:127]
	v_mfma_f32_16x16x32_bf16 v[120:123], v[160:163], v[186:189], v[120:123]
	v_mfma_f32_16x16x32_bf16 v[108:111], v[144:147], v[194:197], v[108:111]
	v_mfma_f32_16x16x32_bf16 v[104:107], v[160:163], v[194:197], v[104:107]
	v_mfma_f32_16x16x32_bf16 v[92:95], v[144:147], v[208:211], v[92:95]
	v_mfma_f32_16x16x32_bf16 v[88:91], v[160:163], v[208:211], v[88:91]
	v_mfma_f32_16x16x32_bf16 v[76:79], v[144:147], v[216:219], v[76:79]
	v_mfma_f32_16x16x32_bf16 v[72:75], v[160:163], v[216:219], v[72:75]
	v_mfma_f32_16x16x32_bf16 v[124:127], v[156:159], v[190:193], v[124:127]
	v_mfma_f32_16x16x32_bf16 v[120:123], v[164:167], v[190:193], v[120:123]
	v_mfma_f32_16x16x32_bf16 v[108:111], v[156:159], v[198:201], v[108:111]
	v_mfma_f32_16x16x32_bf16 v[104:107], v[164:167], v[198:201], v[104:107]
	v_mfma_f32_16x16x32_bf16 v[92:95], v[156:159], v[212:215], v[92:95]
	v_mfma_f32_16x16x32_bf16 v[88:91], v[164:167], v[212:215], v[88:91]
	v_mfma_f32_16x16x32_bf16 v[76:79], v[156:159], v[220:223], v[76:79]
	v_mfma_f32_16x16x32_bf16 v[72:75], v[164:167], v[220:223], v[72:75]
	s_setprio 0
	s_setprio 1
	v_mfma_f32_16x16x32_bf16 v[116:119], v[168:171], v[186:189], v[116:119]
	v_mfma_f32_16x16x32_bf16 v[112:115], v[176:179], v[186:189], v[112:115]
	v_mfma_f32_16x16x32_bf16 v[100:103], v[168:171], v[194:197], v[100:103]
	v_mfma_f32_16x16x32_bf16 v[96:99], v[176:179], v[194:197], v[96:99]
	v_mfma_f32_16x16x32_bf16 v[84:87], v[168:171], v[208:211], v[84:87]
	v_mfma_f32_16x16x32_bf16 v[80:83], v[176:179], v[208:211], v[80:83]
	v_mfma_f32_16x16x32_bf16 v[68:71], v[168:171], v[216:219], v[68:71]
	v_mfma_f32_16x16x32_bf16 v[64:67], v[176:179], v[216:219], v[64:67]
	v_mfma_f32_16x16x32_bf16 v[116:119], v[172:175], v[190:193], v[116:119]
	v_mfma_f32_16x16x32_bf16 v[112:115], v[182:185], v[190:193], v[112:115]
	v_mfma_f32_16x16x32_bf16 v[100:103], v[172:175], v[198:201], v[100:103]
	v_mfma_f32_16x16x32_bf16 v[96:99], v[182:185], v[198:201], v[96:99]
	v_mfma_f32_16x16x32_bf16 v[84:87], v[172:175], v[212:215], v[84:87]
	v_mfma_f32_16x16x32_bf16 v[80:83], v[182:185], v[212:215], v[80:83]
	v_mfma_f32_16x16x32_bf16 v[68:71], v[172:175], v[220:223], v[68:71]
	v_mfma_f32_16x16x32_bf16 v[64:67], v[182:185], v[220:223], v[64:67]
	s_setprio 0
	s_barrier
	s_add_i32 s3, s74, s14
	v_lshl_add_u64 v[202:203], s[60:61], 0, v[130:131]
	s_mov_b32 m0, s3
	ds_read_b128 v[186:189], v153 offset:16384
	ds_read_b128 v[190:193], v153 offset:17408
	ds_read_b128 v[194:197], v153 offset:18432
	ds_read_b128 v[198:201], v153 offset:19456
	ds_read_b128 v[208:211], v153 offset:20480
	ds_read_b128 v[212:215], v153 offset:21504
	ds_read_b128 v[216:219], v153 offset:22528
	ds_read_b128 v[220:223], v153 offset:23552
	global_load_lds_dwordx4 v[202:203], off
	s_add_i32 m0, s3, 0x2000
	s_add_u32 s78, s60, 0x20000
	v_lshl_add_u64 v[224:225], s[60:61], 0, v[134:135]
	s_addc_u32 s79, s61, 0
	s_add_i32 s3, s75, s14
	global_load_lds_dwordx4 v[224:225], off
	v_lshl_add_u64 v[226:227], s[78:79], 0, v[130:131]
	s_mov_b32 m0, s3
	global_load_lds_dwordx4 v[226:227], off
	v_lshl_add_u64 v[226:227], s[78:79], 0, v[134:135]
	s_add_i32 m0, s3, 0x2000
	s_nop 0
	global_load_lds_dwordx4 v[226:227], off
	s_waitcnt vmcnt(6)
	s_waitcnt lgkmcnt(0)
	s_barrier
	s_setprio 1
	s_waitcnt lgkmcnt(0)
	v_mfma_f32_16x16x32_bf16 v[60:63], v[144:147], v[186:189], v[60:63]
	v_mfma_f32_16x16x32_bf16 v[56:59], v[160:163], v[186:189], v[56:59]
	v_mfma_f32_16x16x32_bf16 v[44:47], v[144:147], v[194:197], v[44:47]
	v_mfma_f32_16x16x32_bf16 v[40:43], v[160:163], v[194:197], v[40:43]
	v_mfma_f32_16x16x32_bf16 v[28:31], v[144:147], v[208:211], v[28:31]
	v_mfma_f32_16x16x32_bf16 v[24:27], v[160:163], v[208:211], v[24:27]
	v_mfma_f32_16x16x32_bf16 v[12:15], v[144:147], v[216:219], v[12:15]
	v_mfma_f32_16x16x32_bf16 v[8:11], v[160:163], v[216:219], v[8:11]
	v_mfma_f32_16x16x32_bf16 v[60:63], v[156:159], v[190:193], v[60:63]
	v_mfma_f32_16x16x32_bf16 v[56:59], v[164:167], v[190:193], v[56:59]
	v_mfma_f32_16x16x32_bf16 v[44:47], v[156:159], v[198:201], v[44:47]
	v_mfma_f32_16x16x32_bf16 v[40:43], v[164:167], v[198:201], v[40:43]
	v_mfma_f32_16x16x32_bf16 v[28:31], v[156:159], v[212:215], v[28:31]
	v_mfma_f32_16x16x32_bf16 v[24:27], v[164:167], v[212:215], v[24:27]
	v_lshl_add_u64 v[226:227], s[62:63], 0, v[128:129]
	s_mov_b32 m0, s15
	s_nop 0
	global_load_lds_dwordx4 v[226:227], off
	v_mfma_f32_16x16x32_bf16 v[12:15], v[156:159], v[220:223], v[12:15]
	v_mfma_f32_16x16x32_bf16 v[8:11], v[164:167], v[220:223], v[8:11]
	s_setprio 0
	s_setprio 1
	v_mfma_f32_16x16x32_bf16 v[52:55], v[168:171], v[186:189], v[52:55]
	v_mfma_f32_16x16x32_bf16 v[48:51], v[176:179], v[186:189], v[48:51]
	v_mfma_f32_16x16x32_bf16 v[36:39], v[168:171], v[194:197], v[36:39]
	v_mfma_f32_16x16x32_bf16 v[32:35], v[176:179], v[194:197], v[32:35]
	v_mfma_f32_16x16x32_bf16 v[20:23], v[168:171], v[208:211], v[20:23]
	v_mfma_f32_16x16x32_bf16 v[16:19], v[176:179], v[208:211], v[16:19]
	v_mfma_f32_16x16x32_bf16 v[4:7], v[168:171], v[216:219], v[4:7]
	v_mfma_f32_16x16x32_bf16 v[0:3], v[176:179], v[216:219], v[0:3]
	v_mfma_f32_16x16x32_bf16 v[52:55], v[172:175], v[190:193], v[52:55]
	v_mfma_f32_16x16x32_bf16 v[48:51], v[182:185], v[190:193], v[48:51]
	v_mfma_f32_16x16x32_bf16 v[36:39], v[172:175], v[198:201], v[36:39]
	v_mfma_f32_16x16x32_bf16 v[32:35], v[182:185], v[198:201], v[32:35]
	v_mfma_f32_16x16x32_bf16 v[20:23], v[172:175], v[212:215], v[20:23]
	v_mfma_f32_16x16x32_bf16 v[16:19], v[182:185], v[212:215], v[16:19]
	v_lshl_add_u64 v[228:229], s[62:63], 0, v[132:133]
	s_mov_b32 m0, s34
	s_nop 0
	global_load_lds_dwordx4 v[228:229], off
	v_mfma_f32_16x16x32_bf16 v[4:7], v[172:175], v[220:223], v[4:7]
	v_mfma_f32_16x16x32_bf16 v[0:3], v[182:185], v[220:223], v[0:3]
	s_setprio 0
	s_barrier
; #define PG8_STAGE(bufoff, gbase, voff) do { _Pragma("unroll") for (int _i = 0; _i < 2; ++_i) \
;         __builtin_amdgcn_global_load_lds((const unsigned*)((const char*)(gbase) + (voff)[_i]), (PG8_LAS unsigned*)(lds + (bufoff) + ldsw + _i * 8192), 16, 0, 0); } while (0)
; #define PG8_LDA(dst, b, h) do { _Pragma("unroll") for (int m = 0; m < 4; ++m) _Pragma("unroll") for (int k = 0; k < 2; ++k) dst[m][k] = *(const PG8_LAS bf16x8*)(lds + PG8_SA(b, h) + aoff + m * 2048 + k * 1024); } while (0)
; #define PG8_LDB(dst, b, h) do { _Pragma("unroll") for (int n = 0; n < 2; ++n) _Pragma("unroll") for (int k = 0; k < 2; ++k) dst[n][k] = *(const PG8_LAS bf16x8*)(lds + PG8_SB(b, h) + boff + n * 2048 + k * 1024); } while (0)
; #define PG8_MMA(ai, bj, At, Bt) do { __builtin_amdgcn_s_setprio(1); _Pragma("unroll") for (int m = 0; m < 4; ++m) _Pragma("unroll") for (int n = 0; n < 2; ++n) _Pragma("unroll") for (int k = 0; k < 2; ++k) \
;         acc[ai][bj][m][n] = __builtin_amdgcn_mfma_f32_16x16x32_bf16(Bt[n][k], At[m][k], acc[ai][bj][m][n], 0, 0, 0); __builtin_amdgcn_s_setprio(0); } while (0)
; #define PG8_WAIT_V(n) asm volatile("s_waitcnt vmcnt(" #n ")" ::: "memory")
; #define PG8_WAIT_L(n) asm volatile("s_waitcnt lgkmcnt(" #n ")" ::: "memory")
; #define PG8_BAR __builtin_amdgcn_s_barrier()
; #define PG8_SCHED __builtin_amdgcn_sched_barrier(0)
; template <class Epi, class Sched, bool ALIGN_EPI = false, bool SP2 = false>
; __device__ __forceinline__ void gemm_phase(PG8_LAS unsigned char* lds, const Gemm g, const Sched& S, const Epi& E) {
;     ...
;             PG8_LDB(B0, 1, 0); PG8_LDB(B1, 1, 1); PG8_SCHED; PG8_LDA(At, 1, 0); PG8_STAGE(PG8_SA(0, 1), a2 + hstep, voffA);
;             PG8_WAIT_V(8); PG8_WAIT_L(0); PG8_BAR; PG8_MMA(0, 0, At, B0); PG8_MMA(0, 1, At, B1); PG8_BAR; PG8_SCHED;
;             PG8_LDA(At, 1, 1); PG8_STAGE(PG8_SB(1, 0), b3, voffB); PG8_STAGE(PG8_SB(1, 1), b3 + hstep, voffB); PG8_STAGE(PG8_SA(1, 0), a3, voffA);
;             PG8_WAIT_V(8); PG8_WAIT_L(0); PG8_BAR; PG8_MMA(1, 0, At, B0); PG8_MMA(1, 1, At, B1); PG8_BAR; PG8_SCHED;
	s_add_i32 s3, 0, 0x18000
	v_add_u32_e32 v155, s3, v149
	s_add_i32 s33, 0, 0x1c000
	ds_read_b128 v[144:147], v155
	ds_read_b128 v[156:159], v155 offset:1024
	ds_read_b128 v[160:163], v155 offset:2048
	ds_read_b128 v[164:167], v155 offset:3072
	v_add_u32_e32 v155, s33, v149
	ds_read_b128 v[168:171], v155
	ds_read_b128 v[172:175], v155 offset:1024
	ds_read_b128 v[176:179], v155 offset:2048
	ds_read_b128 v[182:185], v155 offset:3072
	s_add_u32 s62, s62, 0x20000
	s_addc_u32 s63, s63, 0
	s_mov_b32 m0, s57
	v_lshl_add_u64 v[230:231], s[62:63], 0, v[128:129]
	ds_read_b128 v[186:189], v153 offset:32768
	ds_read_b128 v[190:193], v153 offset:33792
	ds_read_b128 v[194:197], v153 offset:34816
	ds_read_b128 v[198:201], v153 offset:35840
	ds_read_b128 v[208:211], v153 offset:36864
	ds_read_b128 v[212:215], v153 offset:37888
	ds_read_b128 v[216:219], v153 offset:38912
	ds_read_b128 v[220:223], v153 offset:39936
	global_load_lds_dwordx4 v[230:231], off
	v_lshl_add_u64 v[230:231], s[62:63], 0, v[132:133]
	s_mov_b32 m0, s64
	s_nop 0
	global_load_lds_dwordx4 v[230:231], off
	s_waitcnt vmcnt(8)
	s_waitcnt lgkmcnt(0)
	s_barrier
	s_setprio 1
	s_waitcnt lgkmcnt(0)
	v_mfma_f32_16x16x32_bf16 v[124:127], v[144:147], v[186:189], v[124:127]
	v_mfma_f32_16x16x32_bf16 v[120:123], v[160:163], v[186:189], v[120:123]
	v_mfma_f32_16x16x32_bf16 v[108:111], v[144:147], v[194:197], v[108:111]
	v_mfma_f32_16x16x32_bf16 v[104:107], v[160:163], v[194:197], v[104:107]
	v_mfma_f32_16x16x32_bf16 v[92:95], v[144:147], v[208:211], v[92:95]
	v_mfma_f32_16x16x32_bf16 v[88:91], v[160:163], v[208:211], v[88:91]
	v_mfma_f32_16x16x32_bf16 v[76:79], v[144:147], v[216:219], v[76:79]
	v_mfma_f32_16x16x32_bf16 v[72:75], v[160:163], v[216:219], v[72:75]
	v_mfma_f32_16x16x32_bf16 v[124:127], v[156:159], v[190:193], v[124:127]
	v_mfma_f32_16x16x32_bf16 v[120:123], v[164:167], v[190:193], v[120:123]
	v_mfma_f32_16x16x32_bf16 v[108:111], v[156:159], v[198:201], v[108:111]
	v_mfma_f32_16x16x32_bf16 v[104:107], v[164:167], v[198:201], v[104:107]
	v_mfma_f32_16x16x32_bf16 v[92:95], v[156:159], v[212:215], v[92:95]
	v_mfma_f32_16x16x32_bf16 v[88:91], v[164:167], v[212:215], v[88:91]
	v_mfma_f32_16x16x32_bf16 v[76:79], v[156:159], v[220:223], v[76:79]
	v_mfma_f32_16x16x32_bf16 v[72:75], v[164:167], v[220:223], v[72:75]
	s_setprio 0
	s_setprio 1
	v_mfma_f32_16x16x32_bf16 v[116:119], v[168:171], v[186:189], v[116:119]
	v_mfma_f32_16x16x32_bf16 v[112:115], v[176:179], v[186:189], v[112:115]
	v_mfma_f32_16x16x32_bf16 v[100:103], v[168:171], v[194:197], v[100:103]
	v_mfma_f32_16x16x32_bf16 v[96:99], v[176:179], v[194:197], v[96:99]
	v_mfma_f32_16x16x32_bf16 v[84:87], v[168:171], v[208:211], v[84:87]
	v_mfma_f32_16x16x32_bf16 v[80:83], v[176:179], v[208:211], v[80:83]
	v_mfma_f32_16x16x32_bf16 v[68:71], v[168:171], v[216:219], v[68:71]
	v_mfma_f32_16x16x32_bf16 v[64:67], v[176:179], v[216:219], v[64:67]
	v_mfma_f32_16x16x32_bf16 v[116:119], v[172:175], v[190:193], v[116:119]
	v_mfma_f32_16x16x32_bf16 v[112:115], v[182:185], v[190:193], v[112:115]
	v_mfma_f32_16x16x32_bf16 v[100:103], v[172:175], v[198:201], v[100:103]
	v_mfma_f32_16x16x32_bf16 v[96:99], v[182:185], v[198:201], v[96:99]
	v_mfma_f32_16x16x32_bf16 v[84:87], v[172:175], v[212:215], v[84:87]
	v_mfma_f32_16x16x32_bf16 v[80:83], v[182:185], v[212:215], v[80:83]
	v_mfma_f32_16x16x32_bf16 v[68:71], v[172:175], v[220:223], v[68:71]
	v_mfma_f32_16x16x32_bf16 v[64:67], v[182:185], v[220:223], v[64:67]
	s_setprio 0
	s_barrier
	s_add_i32 s3, s3, s14
	v_lshl_add_u64 v[202:203], v[202:203], 0, s[38:39]
	s_mov_b32 m0, s3
	ds_read_b128 v[186:189], v153 offset:49152
	ds_read_b128 v[190:193], v153 offset:50176
	ds_read_b128 v[194:197], v153 offset:51200
	ds_read_b128 v[198:201], v153 offset:52224
	ds_read_b128 v[208:211], v153 offset:53248
	ds_read_b128 v[212:215], v153 offset:54272
	ds_read_b128 v[216:219], v153 offset:55296
	ds_read_b128 v[220:223], v153 offset:56320
	global_load_lds_dwordx4 v[202:203], off
	s_add_i32 m0, s3, 0x2000
	s_add_u32 s60, s60, 0x20080
	v_lshl_add_u64 v[202:203], v[224:225], 0, s[38:39]
	s_addc_u32 s61, s61, 0
	s_add_i32 s3, s33, s14
	global_load_lds_dwordx4 v[202:203], off
	v_lshl_add_u64 v[202:203], s[60:61], 0, v[130:131]
	s_mov_b32 m0, s3
	s_nop 0
	global_load_lds_dwordx4 v[202:203], off
	v_lshl_add_u64 v[202:203], s[60:61], 0, v[134:135]
	s_add_i32 m0, s3, 0x2000
	s_nop 0
	global_load_lds_dwordx4 v[202:203], off
	s_waitcnt vmcnt(6)
	s_waitcnt lgkmcnt(0)
	s_barrier
; #define PG8_BAR __builtin_amdgcn_s_barrier()
;     __device__ __forceinline__ void operator()(const f32x4 (&acc)[2][2][4][2], const Unit& u, int wr, int wc, int fr, int fq) const {
;         const int row0 = u.pm * BM + wr * 64 + fr, col0 = u.pn * BM + wc * 32 + 8 * fq;
; #pragma unroll
;         for (int ai = 0; ai < 2; ++ai)
; #pragma unroll
;             for (int m = 0; m < 4; ++m) { const int row = row0 + ai * HALF + m * 16; const size_t off = (size_t)row * 1024 + col0; float s = 0.f;
; #pragma unroll
;                 for (int bj = 0; bj < 2; ++bj) { f32x4 a0, a1;
;                     if (xin32) { const float* p = xin32 + off + bj * HALF; a0 = *(const f32x4*)p; a1 = *(const f32x4*)(p + 4); }
; template <class Epi, class Sched, bool ALIGN_EPI = false, bool SP2 = false>
; __device__ __forceinline__ void gemm_phase(PG8_LAS unsigned char* lds, const Gemm g, const Sched& S, const Epi& E) {
;     ...
;             PG8_WAIT_V(8); PG8_WAIT_L(0); PG8_BAR; PG8_MMA(1, 0, At, B0); PG8_MMA(1, 1, At, B1); PG8_BAR; PG8_SCHED;
;             } else {
;             PG8_LDB(B0, 0, 0); PG8_SCHED; PG8_LDA(At, 0, 0); PG8_STAGE(PG8_SA(1, 1), a1 + hstep, voffA);
;             PG8_WAIT_L(8); PG8_BAR; PG8_WAIT_L(0); PG8_MMA(0, 0, At, B0); PG8_BAR; PG8_SCHED;
;             PG8_LDB(B1, 0, 1); PG8_STAGE(PG8_SB(0, 0), b2, voffB);
;             PG8_BAR; PG8_WAIT_L(0); PG8_MMA(0, 1, At, B1); PG8_BAR;
;             PG8_LDA(At, 0, 1); PG8_STAGE(PG8_SA(0, 0), a2, voffA);
;             PG8_BAR; PG8_WAIT_L(0); PG8_MMA(1, 0, At, B0); PG8_BAR; PG8_SCHED;
;             PG8_STAGE(PG8_SB(0, 1), b2 + hstep, voffB);
;             PG8_WAIT_V(6); PG8_BAR; PG8_MMA(1, 1, At, B1); PG8_BAR;
;             PG8_LDB(B0, 1, 0); PG8_SCHED; PG8_LDA(At, 1, 0); PG8_STAGE(PG8_SA(0, 1), a2 + hstep, voffA);
;             PG8_WAIT_L(8); PG8_BAR; PG8_WAIT_L(0); PG8_MMA(0, 0, At, B0); PG8_BAR; PG8_SCHED;
;             PG8_LDB(B1, 1, 1); PG8_STAGE(PG8_SB(1, 0), b3, voffB);
;             PG8_BAR; PG8_WAIT_L(0); PG8_MMA(0, 1, At, B1); PG8_BAR;
;             PG8_LDA(At, 1, 1); PG8_STAGE(PG8_SA(1, 0), a3, voffA);
;             PG8_BAR; PG8_WAIT_L(0); PG8_MMA(1, 0, At, B0); PG8_BAR; PG8_SCHED;
;             PG8_STAGE(PG8_SB(1, 1), b3 + hstep, voffB);
;             PG8_WAIT_V(6); PG8_BAR; PG8_MMA(1, 1, At, B1); PG8_BAR;
;             }
;         }
;         if constexpr (ALIGN_EPI) { if (wr == 0) PG8_BAR; }
	s_setprio 1
	s_waitcnt lgkmcnt(0)
	v_mfma_f32_16x16x32_bf16 v[60:63], v[144:147], v[186:189], v[60:63]
	v_mfma_f32_16x16x32_bf16 v[56:59], v[160:163], v[186:189], v[56:59]
	v_mfma_f32_16x16x32_bf16 v[44:47], v[144:147], v[194:197], v[44:47]
	v_mfma_f32_16x16x32_bf16 v[40:43], v[160:163], v[194:197], v[40:43]
	v_mfma_f32_16x16x32_bf16 v[28:31], v[144:147], v[208:211], v[28:31]
	v_mfma_f32_16x16x32_bf16 v[24:27], v[160:163], v[208:211], v[24:27]
	v_mfma_f32_16x16x32_bf16 v[12:15], v[144:147], v[216:219], v[12:15]
	v_mfma_f32_16x16x32_bf16 v[8:11], v[160:163], v[216:219], v[8:11]
	v_mfma_f32_16x16x32_bf16 v[60:63], v[156:159], v[190:193], v[60:63]
	v_mfma_f32_16x16x32_bf16 v[56:59], v[164:167], v[190:193], v[56:59]
	v_mfma_f32_16x16x32_bf16 v[44:47], v[156:159], v[198:201], v[44:47]
	v_mfma_f32_16x16x32_bf16 v[40:43], v[164:167], v[198:201], v[40:43]
	v_mfma_f32_16x16x32_bf16 v[28:31], v[156:159], v[212:215], v[28:31]
	v_mfma_f32_16x16x32_bf16 v[24:27], v[164:167], v[212:215], v[24:27]
	v_lshl_add_u64 v[202:203], v[226:227], 0, s[38:39]
	s_mov_b32 m0, s66
	s_nop 0
	global_load_lds_dwordx4 v[202:203], off
	v_mfma_f32_16x16x32_bf16 v[12:15], v[156:159], v[220:223], v[12:15]
	v_mfma_f32_16x16x32_bf16 v[8:11], v[164:167], v[220:223], v[8:11]
	s_setprio 0
	s_setprio 1
	v_mfma_f32_16x16x32_bf16 v[52:55], v[168:171], v[186:189], v[52:55]
	v_mfma_f32_16x16x32_bf16 v[48:51], v[176:179], v[186:189], v[48:51]
	v_mfma_f32_16x16x32_bf16 v[36:39], v[168:171], v[194:197], v[36:39]
	v_mfma_f32_16x16x32_bf16 v[32:35], v[176:179], v[194:197], v[32:35]
	v_mfma_f32_16x16x32_bf16 v[20:23], v[168:171], v[208:211], v[20:23]
	v_mfma_f32_16x16x32_bf16 v[16:19], v[176:179], v[208:211], v[16:19]
	v_mfma_f32_16x16x32_bf16 v[4:7], v[168:171], v[216:219], v[4:7]
	v_mfma_f32_16x16x32_bf16 v[0:3], v[176:179], v[216:219], v[0:3]
	v_mfma_f32_16x16x32_bf16 v[52:55], v[172:175], v[190:193], v[52:55]
	v_mfma_f32_16x16x32_bf16 v[48:51], v[182:185], v[190:193], v[48:51]
	v_mfma_f32_16x16x32_bf16 v[36:39], v[172:175], v[198:201], v[36:39]
	v_mfma_f32_16x16x32_bf16 v[32:35], v[182:185], v[198:201], v[32:35]
	v_mfma_f32_16x16x32_bf16 v[20:23], v[172:175], v[212:215], v[20:23]
	v_mfma_f32_16x16x32_bf16 v[16:19], v[182:185], v[212:215], v[16:19]
	v_lshl_add_u64 v[202:203], v[228:229], 0, s[38:39]
	s_mov_b32 m0, s67
	s_nop 0
	global_load_lds_dwordx4 v[202:203], off
	v_mfma_f32_16x16x32_bf16 v[4:7], v[172:175], v[220:223], v[4:7]
	v_mfma_f32_16x16x32_bf16 v[0:3], v[182:185], v[220:223], v[0:3]
	s_setprio 0
	s_barrier
	s_add_i32 s87, s87, 2
	s_add_u32 s58, s58, 0x100
	s_addc_u32 s59, s59, 0
	s_add_u32 s85, s85, 0x100
	s_addc_u32 s86, s86, 0
	s_cmp_gt_u32 s87, 5
	s_cbranch_scc0 .LBB0_873
	s_and_b64 vcc, exec, s[42:43]
	s_cbranch_vccz .LBB0_876
.LBB0_876:
	v_lshl_add_u32 v146, s56, 8, v148
	v_ashrrev_i32_e32 v147, 31, v146
	v_lshl_or_b32 v144, s54, 8, v150
	v_lshlrev_b64 v[156:157], 11, v[146:147]
	v_ashrrev_i32_e32 v145, 31, v144
	v_lshl_add_u64 v[156:157], s[22:23], 0, v[156:157]
	v_lshl_add_u64 v[166:167], v[144:145], 1, v[156:157]
	global_load_dwordx4 v[158:161], v[166:167], off
	global_load_dwordx4 v[162:165], v[166:167], off offset:256
	v_and_b32_e32 v156, 64, v154
	v_xor_b32_e32 v155, 16, v154
	v_add_u32_e32 v156, 64, v156
	v_xor_b32_e32 v157, 32, v154
	v_cmp_lt_i32_e32 vcc, v155, v156
	s_waitcnt vmcnt(0)
	v_lshlrev_b32_e32 v168, 16, v158
	v_cndmask_b32_e32 v155, v154, v155, vcc
	v_cmp_lt_i32_e32 vcc, v157, v156
	v_and_b32_e32 v169, 0xffff0000, v158
	v_lshlrev_b32_e32 v158, 16, v159
	v_and_b32_e32 v159, 0xffff0000, v159
	v_lshlrev_b32_e32 v172, 16, v162
	v_and_b32_e32 v173, 0xffff0000, v162
	v_lshlrev_b32_e32 v162, 16, v163
	v_and_b32_e32 v163, 0xffff0000, v163
	v_cndmask_b32_e32 v157, v154, v157, vcc
	v_lshlrev_b32_e32 v170, 16, v160
	v_and_b32_e32 v171, 0xffff0000, v160
	v_lshlrev_b32_e32 v160, 16, v161
	v_and_b32_e32 v161, 0xffff0000, v161
	v_lshlrev_b32_e32 v174, 16, v164
	v_and_b32_e32 v175, 0xffff0000, v164
	v_lshlrev_b32_e32 v164, 16, v165
	v_and_b32_e32 v165, 0xffff0000, v165
	v_pk_add_f32 v[126:127], v[126:127], v[158:159]
	v_pk_add_f32 v[124:125], v[124:125], v[168:169]
	v_pk_add_f32 v[118:119], v[118:119], v[162:163]
	v_pk_add_f32 v[116:117], v[116:117], v[172:173]
	v_lshlrev_b32_e32 v156, 2, v155
	v_lshlrev_b32_e32 v155, 2, v157
	v_pk_add_f32 v[122:123], v[122:123], v[160:161]
	v_pk_add_f32 v[120:121], v[120:121], v[170:171]
	v_pk_add_f32 v[158:159], v[114:115], v[164:165]
	v_pk_add_f32 v[160:161], v[112:113], v[174:175]
	v_mul_f32_e32 v114, v125, v125
	v_mul_f32_e32 v115, v127, v127
	v_mul_f32_e32 v157, v117, v117
	v_mul_f32_e32 v162, v119, v119
	v_cvt_pk_bf16_f32 v112, v124, v125
	v_mul_f32_e32 v125, v121, v121
	v_mul_f32_e32 v163, v161, v161
	v_fmac_f32_e32 v114, v124, v124
	v_fmac_f32_e32 v115, v126, v126
	v_fmac_f32_e32 v157, v116, v116
	v_fmac_f32_e32 v162, v118, v118
	v_cvt_pk_bf16_f32 v113, v126, v127
	v_mul_f32_e32 v127, v123, v123
	v_mul_f32_e32 v164, v159, v159
	v_fmac_f32_e32 v125, v120, v120
	v_fmac_f32_e32 v163, v160, v160
	v_add_f32_e32 v114, v114, v115
	v_add_f32_e32 v115, v157, v162
	v_fmac_f32_e32 v127, v122, v122
	v_fmac_f32_e32 v164, v158, v158
	v_add_f32_e32 v114, v125, v114
	v_add_f32_e32 v115, v163, v115
	v_add_f32_e32 v114, v127, v114
	v_add_f32_e32 v115, v164, v115
	v_add_f32_e32 v124, v114, v115
	ds_bpermute_b32 v125, v156, v124
	v_cvt_pk_bf16_f32 v114, v120, v121
	v_cvt_pk_bf16_f32 v115, v122, v123
	global_store_dwordx4 v[166:167], v[112:115], off
	s_waitcnt lgkmcnt(0)
	s_nop 0
	v_add_f32_e32 v112, v124, v125
	ds_bpermute_b32 v113, v155, v112
	v_cvt_pk_bf16_f32 v114, v116, v117
	v_cvt_pk_bf16_f32 v115, v118, v119
	v_cvt_pk_bf16_f32 v116, v160, v161
	v_cvt_pk_bf16_f32 v117, v158, v159
	global_store_dwordx4 v[166:167], v[114:117], off offset:256
	s_and_saveexec_b64 s[54:55], s[8:9]
	s_cbranch_execz .LBB0_878
	s_waitcnt lgkmcnt(0)
	v_add_f32_e32 v112, v112, v113
	v_mul_f32_e32 v112, 0x4f800000, v112
	v_trunc_f32_e32 v112, v112
	v_mul_f32_e64 v113, |v112|, s82
	v_floor_f32_e32 v113, v113
	v_fma_f32 v114, v113, s83, |v112|
	v_cvt_u32_f32_e32 v114, v114
	v_cvt_u32_f32_e32 v113, v113
	v_ashrrev_i32_e32 v115, 31, v112
	v_xor_b32_e32 v112, v114, v115
	v_xor_b32_e32 v113, v113, v115
	v_sub_co_u32_e32 v112, vcc, v112, v115
	s_nop 1
	v_subb_co_u32_e32 v113, vcc, v113, v115, vcc
	v_lshl_add_u64 v[114:115], v[146:147], 3, s[0:1]
	global_atomic_add_x2 v[114:115], v[112:113], off

; #define PG8_BAR __builtin_amdgcn_s_barrier()
; template <class Epi, class Sched, bool ALIGN_EPI = false, bool SP2 = false>
; __device__ __forceinline__ void gemm_phase(PG8_LAS unsigned char* lds, const Gemm g, const Sched& S, const Epi& E) {
;     ...
;         if constexpr (ALIGN_EPI) { if (wr == 0) PG8_BAR; }
;         if constexpr (!Epi::AFTER_DRAIN) { E(acc, cur, wr, wc, fr, fq); S.done(cur); }
;         if (!has_next) break;
; #pragma unroll
;         for (int a = 0; a < 2; ++a)
; #pragma unroll
;             for (int b = 0; b < 2; ++b)
; #pragma unroll
;                 for (int m = 0; m < 4; ++m)
; #pragma unroll
;                     for (int n = 0; n < 2; ++n) acc[a][b][m][n] = (f32x4){0.f, 0.f, 0.f, 0.f};
;         cur = nxt; cA = nA; cB = nB; ++ui;
;         if constexpr (ALIGN_EPI) { if (wr == 1) PG8_BAR; }
.LBB0_892:
	s_or_b64 exec, exec, s[54:55]
	s_andn2_b64 vcc, exec, s[10:11]
	s_mov_b64 s[10:11], -1
	s_cmp_eq_u64 s[42:43], 0
	s_cbranch_scc1 .Lxpost_4
	s_barrier

; #define PG8_STAGE(bufoff, gbase, voff) do { _Pragma("unroll") for (int _i = 0; _i < 2; ++_i) \
;         __builtin_amdgcn_global_load_lds((const unsigned*)((const char*)(gbase) + (voff)[_i]), (PG8_LAS unsigned*)(lds + (bufoff) + ldsw + _i * 8192), 16, 0, 0); } while (0)
; #define PG8_LDA(dst, b, h) do { _Pragma("unroll") for (int m = 0; m < 4; ++m) _Pragma("unroll") for (int k = 0; k < 2; ++k) dst[m][k] = *(const PG8_LAS bf16x8*)(lds + PG8_SA(b, h) + aoff + m * 2048 + k * 1024); } while (0)
; #define PG8_LDB(dst, b, h) do { _Pragma("unroll") for (int n = 0; n < 2; ++n) _Pragma("unroll") for (int k = 0; k < 2; ++k) dst[n][k] = *(const PG8_LAS bf16x8*)(lds + PG8_SB(b, h) + boff + n * 2048 + k * 1024); } while (0)
; #define PG8_MMA(ai, bj, At, Bt) do { __builtin_amdgcn_s_setprio(1); _Pragma("unroll") for (int m = 0; m < 4; ++m) _Pragma("unroll") for (int n = 0; n < 2; ++n) _Pragma("unroll") for (int k = 0; k < 2; ++k) \
;         acc[ai][bj][m][n] = __builtin_amdgcn_mfma_f32_16x16x32_bf16(Bt[n][k], At[m][k], acc[ai][bj][m][n], 0, 0, 0); __builtin_amdgcn_s_setprio(0); } while (0)
; #define PG8_BAR __builtin_amdgcn_s_barrier()
; template <class Epi, class Sched, bool ALIGN_EPI = false, bool SP2 = false>
; __device__ __forceinline__ void gemm_phase(PG8_LAS unsigned char* lds, const Gemm g, const Sched& S, const Epi& E) {
;     ...
;         const bool has_next = S.next(ui + 1, nxt);
;         const char* nA = has_next ? (const char*)g.A + (size_t)nxt.pm * tstep : cA; const char* nB = has_next ? (const char*)g.Bt + (size_t)nxt.pn * tstep : cB;
;         for (int t = 0; t < nt; t += 2) {
;             const bool last = (t == nt - 2);
;             const char* a1 = cA + (size_t)(t + 1) * kstep;
;             const char* a2 = last ? nA : cA + (size_t)(t + 2) * kstep; const char* b2 = last ? nB : cB + (size_t)(t + 2) * kstep;
;             const char* a3 = a2 + kstep; const char* b3 = b2 + kstep;
;             if (last && has_next) S.a_ready(nxt);
;             if constexpr (SP2) {
;             PG8_LDB(B0, 0, 0); PG8_LDB(B1, 0, 1); PG8_SCHED; PG8_LDA(At, 0, 0); PG8_STAGE(PG8_SA(1, 1), a1 + hstep, voffA);
;             PG8_WAIT_V(8); PG8_WAIT_L(0); PG8_BAR; PG8_MMA(0, 0, At, B0); PG8_MMA(0, 1, At, B1); PG8_BAR; PG8_SCHED;
;             PG8_LDA(At, 0, 1); PG8_STAGE(PG8_SB(0, 0), b2, voffB); PG8_STAGE(PG8_SB(0, 1), b2 + hstep, voffB); PG8_STAGE(PG8_SA(0, 0), a2, voffA);
.LBB0_956:
	s_ashr_i32 s45, s44, 31
	s_lshl_b64 s[48:49], s[44:45], 19
	s_add_u32 s48, s22, s48
	s_addc_u32 s49, s23, s49
	s_and_b64 s[50:51], s[10:11], exec
	s_cselect_b32 s45, s49, s55
	s_cselect_b32 s75, s48, s54
	s_ashr_i32 s43, s42, 31
	s_lshl_b64 s[50:51], s[42:43], 19
	v_readlane_b32 s3, v250, 18
	s_add_u32 s50, s3, s50
	v_readlane_b32 s3, v250, 19
	s_addc_u32 s51, s3, s51
	s_and_b64 s[58:59], s[10:11], exec
	s_cselect_b32 s43, s51, s57
	s_cselect_b32 s76, s50, s56
	s_add_u32 s54, s54, 0x40080
	s_addc_u32 s55, s55, 0
	s_add_u32 s77, s56, 0x100
	s_addc_u32 s82, s57, 0
	s_mov_b32 s83, -2
	ds_read_b128 v[144:147], v155
	ds_read_b128 v[148:151], v155 offset:1024
	ds_read_b128 v[160:163], v155 offset:2048
	ds_read_b128 v[164:167], v155 offset:3072
	ds_read_b128 v[168:171], v156
	ds_read_b128 v[172:175], v156 offset:1024
	ds_read_b128 v[176:179], v156 offset:2048
	ds_read_b128 v[182:185], v156 offset:3072
	s_add_u32 s3, s54, 0xfffc0080
	s_addc_u32 s33, s55, -1
	s_cmp_eq_u32 s83, 12
	s_cselect_b32 s59, s45, s33
	s_cselect_b32 s58, s75, s3
	s_cselect_b32 s57, s43, s82
	s_cselect_b32 s56, s76, s77
	v_lshl_add_u64 v[202:203], s[54:55], 0, v[136:137]
	s_add_i32 m0, s34, 0xc000
	ds_read_b128 v[186:189], v157
	ds_read_b128 v[190:193], v157 offset:1024
	ds_read_b128 v[194:197], v157 offset:2048
	ds_read_b128 v[198:201], v157 offset:3072
	ds_read_b128 v[208:211], v157 offset:4096
	ds_read_b128 v[212:215], v157 offset:5120
	ds_read_b128 v[216:219], v157 offset:6144
	ds_read_b128 v[220:223], v157 offset:7168
	global_load_lds_dwordx4 v[202:203], off
	v_lshl_add_u64 v[202:203], s[54:55], 0, v[138:139]
	s_add_i32 m0, s34, 0xe000
	s_nop 0
	global_load_lds_dwordx4 v[202:203], off
	s_waitcnt vmcnt(8)
	s_waitcnt lgkmcnt(0)
	s_barrier
	s_setprio 1
	s_waitcnt lgkmcnt(0)
	v_mfma_f32_16x16x32_bf16 v[124:127], v[144:147], v[186:189], 0
	v_mfma_f32_16x16x32_bf16 v[120:123], v[160:163], v[186:189], 0
	v_mfma_f32_16x16x32_bf16 v[108:111], v[144:147], v[194:197], 0
	v_mfma_f32_16x16x32_bf16 v[104:107], v[160:163], v[194:197], 0
	v_mfma_f32_16x16x32_bf16 v[92:95], v[144:147], v[208:211], 0
	v_mfma_f32_16x16x32_bf16 v[88:91], v[160:163], v[208:211], 0
	v_mfma_f32_16x16x32_bf16 v[76:79], v[144:147], v[216:219], 0
	v_mfma_f32_16x16x32_bf16 v[72:75], v[160:163], v[216:219], 0
	v_mfma_f32_16x16x32_bf16 v[124:127], v[148:151], v[190:193], v[124:127]
	v_mfma_f32_16x16x32_bf16 v[120:123], v[164:167], v[190:193], v[120:123]
	v_mfma_f32_16x16x32_bf16 v[108:111], v[148:151], v[198:201], v[108:111]
	v_mfma_f32_16x16x32_bf16 v[104:107], v[164:167], v[198:201], v[104:107]
	v_mfma_f32_16x16x32_bf16 v[92:95], v[148:151], v[212:215], v[92:95]
	v_mfma_f32_16x16x32_bf16 v[88:91], v[164:167], v[212:215], v[88:91]
	v_mfma_f32_16x16x32_bf16 v[76:79], v[148:151], v[220:223], v[76:79]
	v_mfma_f32_16x16x32_bf16 v[72:75], v[164:167], v[220:223], v[72:75]
	s_setprio 0
	s_setprio 1
	v_mfma_f32_16x16x32_bf16 v[116:119], v[168:171], v[186:189], 0
	v_mfma_f32_16x16x32_bf16 v[112:115], v[176:179], v[186:189], 0
	v_mfma_f32_16x16x32_bf16 v[100:103], v[168:171], v[194:197], 0
	v_mfma_f32_16x16x32_bf16 v[96:99], v[176:179], v[194:197], 0
	v_mfma_f32_16x16x32_bf16 v[84:87], v[168:171], v[208:211], 0
	v_mfma_f32_16x16x32_bf16 v[80:83], v[176:179], v[208:211], 0
	v_mfma_f32_16x16x32_bf16 v[68:71], v[168:171], v[216:219], 0
	v_mfma_f32_16x16x32_bf16 v[64:67], v[176:179], v[216:219], 0
	v_mfma_f32_16x16x32_bf16 v[116:119], v[172:175], v[190:193], v[116:119]
	v_mfma_f32_16x16x32_bf16 v[112:115], v[182:185], v[190:193], v[112:115]
	v_mfma_f32_16x16x32_bf16 v[100:103], v[172:175], v[198:201], v[100:103]
	v_mfma_f32_16x16x32_bf16 v[96:99], v[182:185], v[198:201], v[96:99]
	v_mfma_f32_16x16x32_bf16 v[84:87], v[172:175], v[212:215], v[84:87]
	v_mfma_f32_16x16x32_bf16 v[80:83], v[182:185], v[212:215], v[80:83]
	v_mfma_f32_16x16x32_bf16 v[68:71], v[172:175], v[220:223], v[68:71]
	v_mfma_f32_16x16x32_bf16 v[64:67], v[182:185], v[220:223], v[64:67]
	s_setprio 0
	s_barrier
	s_add_i32 s3, s65, s14
	v_lshl_add_u64 v[202:203], s[56:57], 0, v[132:133]
	s_mov_b32 m0, s3
	ds_read_b128 v[186:189], v157 offset:16384
	ds_read_b128 v[190:193], v157 offset:17408
	ds_read_b128 v[194:197], v157 offset:18432
	ds_read_b128 v[198:201], v157 offset:19456
	ds_read_b128 v[208:211], v157 offset:20480
	ds_read_b128 v[212:215], v157 offset:21504
	ds_read_b128 v[216:219], v157 offset:22528
	ds_read_b128 v[220:223], v157 offset:23552
	global_load_lds_dwordx4 v[202:203], off
	s_add_i32 m0, s3, 0x2000
	s_add_u32 s78, s56, 0x40000
	v_lshl_add_u64 v[224:225], s[56:57], 0, v[128:129]
	s_addc_u32 s79, s57, 0
	s_add_i32 s3, s66, s14
	global_load_lds_dwordx4 v[224:225], off
	v_lshl_add_u64 v[226:227], s[78:79], 0, v[132:133]
	s_mov_b32 m0, s3
	global_load_lds_dwordx4 v[226:227], off
	v_lshl_add_u64 v[226:227], s[78:79], 0, v[128:129]
	s_add_i32 m0, s3, 0x2000
	s_nop 0
	global_load_lds_dwordx4 v[226:227], off
	s_waitcnt vmcnt(6)
	s_waitcnt lgkmcnt(0)
	s_barrier
; #define PG8_STAGE(bufoff, gbase, voff) do { _Pragma("unroll") for (int _i = 0; _i < 2; ++_i) \
;         __builtin_amdgcn_global_load_lds((const unsigned*)((const char*)(gbase) + (voff)[_i]), (PG8_LAS unsigned*)(lds + (bufoff) + ldsw + _i * 8192), 16, 0, 0); } while (0)
; #define PG8_LDA(dst, b, h) do { _Pragma("unroll") for (int m = 0; m < 4; ++m) _Pragma("unroll") for (int k = 0; k < 2; ++k) dst[m][k] = *(const PG8_LAS bf16x8*)(lds + PG8_SA(b, h) + aoff + m * 2048 + k * 1024); } while (0)
; #define PG8_LDB(dst, b, h) do { _Pragma("unroll") for (int n = 0; n < 2; ++n) _Pragma("unroll") for (int k = 0; k < 2; ++k) dst[n][k] = *(const PG8_LAS bf16x8*)(lds + PG8_SB(b, h) + boff + n * 2048 + k * 1024); } while (0)
; #define PG8_MMA(ai, bj, At, Bt) do { __builtin_amdgcn_s_setprio(1); _Pragma("unroll") for (int m = 0; m < 4; ++m) _Pragma("unroll") for (int n = 0; n < 2; ++n) _Pragma("unroll") for (int k = 0; k < 2; ++k) \
;         acc[ai][bj][m][n] = __builtin_amdgcn_mfma_f32_16x16x32_bf16(Bt[n][k], At[m][k], acc[ai][bj][m][n], 0, 0, 0); __builtin_amdgcn_s_setprio(0); } while (0)
; #define PG8_WAIT_V(n) asm volatile("s_waitcnt vmcnt(" #n ")" ::: "memory")
; #define PG8_WAIT_L(n) asm volatile("s_waitcnt lgkmcnt(" #n ")" ::: "memory")
; #define PG8_BAR __builtin_amdgcn_s_barrier()
; #define PG8_SCHED __builtin_amdgcn_sched_barrier(0)
; template <class Epi, class Sched, bool ALIGN_EPI = false, bool SP2 = false>
; __device__ __forceinline__ void gemm_phase(PG8_LAS unsigned char* lds, const Gemm g, const Sched& S, const Epi& E) {
;     ...
;             PG8_WAIT_V(8); PG8_WAIT_L(0); PG8_BAR; PG8_MMA(0, 0, At, B0); PG8_MMA(0, 1, At, B1); PG8_BAR; PG8_SCHED;
;             PG8_LDA(At, 0, 1); PG8_STAGE(PG8_SB(0, 0), b2, voffB); PG8_STAGE(PG8_SB(0, 1), b2 + hstep, voffB); PG8_STAGE(PG8_SA(0, 0), a2, voffA);
;             PG8_WAIT_V(8); PG8_WAIT_L(0); PG8_BAR; PG8_MMA(1, 0, At, B0); PG8_MMA(1, 1, At, B1); PG8_BAR; PG8_SCHED;
;             PG8_LDB(B0, 1, 0); PG8_LDB(B1, 1, 1); PG8_SCHED; PG8_LDA(At, 1, 0); PG8_STAGE(PG8_SA(0, 1), a2 + hstep, voffA);
;             PG8_WAIT_V(8); PG8_WAIT_L(0); PG8_BAR; PG8_MMA(0, 0, At, B0); PG8_MMA(0, 1, At, B1); PG8_BAR; PG8_SCHED;
	s_setprio 1
	s_waitcnt lgkmcnt(0)
	v_mfma_f32_16x16x32_bf16 v[60:63], v[144:147], v[186:189], 0
	v_mfma_f32_16x16x32_bf16 v[56:59], v[160:163], v[186:189], 0
	v_mfma_f32_16x16x32_bf16 v[44:47], v[144:147], v[194:197], 0
	v_mfma_f32_16x16x32_bf16 v[40:43], v[160:163], v[194:197], 0
	v_mfma_f32_16x16x32_bf16 v[28:31], v[144:147], v[208:211], 0
	v_mfma_f32_16x16x32_bf16 v[24:27], v[160:163], v[208:211], 0
	v_mfma_f32_16x16x32_bf16 v[12:15], v[144:147], v[216:219], 0
	v_mfma_f32_16x16x32_bf16 v[8:11], v[160:163], v[216:219], 0
	v_mfma_f32_16x16x32_bf16 v[60:63], v[148:151], v[190:193], v[60:63]
	v_mfma_f32_16x16x32_bf16 v[56:59], v[164:167], v[190:193], v[56:59]
	v_mfma_f32_16x16x32_bf16 v[44:47], v[148:151], v[198:201], v[44:47]
	v_mfma_f32_16x16x32_bf16 v[40:43], v[164:167], v[198:201], v[40:43]
	v_mfma_f32_16x16x32_bf16 v[28:31], v[148:151], v[212:215], v[28:31]
	v_mfma_f32_16x16x32_bf16 v[24:27], v[164:167], v[212:215], v[24:27]
	v_lshl_add_u64 v[226:227], s[58:59], 0, v[134:135]
	s_mov_b32 m0, s34
	s_nop 0
	global_load_lds_dwordx4 v[226:227], off
	v_mfma_f32_16x16x32_bf16 v[12:15], v[148:151], v[220:223], v[12:15]
	v_mfma_f32_16x16x32_bf16 v[8:11], v[164:167], v[220:223], v[8:11]
	s_setprio 0
	s_setprio 1
	v_mfma_f32_16x16x32_bf16 v[52:55], v[168:171], v[186:189], 0
	v_mfma_f32_16x16x32_bf16 v[48:51], v[176:179], v[186:189], 0
	v_mfma_f32_16x16x32_bf16 v[36:39], v[168:171], v[194:197], 0
	v_mfma_f32_16x16x32_bf16 v[32:35], v[176:179], v[194:197], 0
	v_mfma_f32_16x16x32_bf16 v[20:23], v[168:171], v[208:211], 0
	v_mfma_f32_16x16x32_bf16 v[16:19], v[176:179], v[208:211], 0
	v_mfma_f32_16x16x32_bf16 v[4:7], v[168:171], v[216:219], 0
	v_mfma_f32_16x16x32_bf16 v[0:3], v[176:179], v[216:219], 0
	v_mfma_f32_16x16x32_bf16 v[52:55], v[172:175], v[190:193], v[52:55]
	v_mfma_f32_16x16x32_bf16 v[48:51], v[182:185], v[190:193], v[48:51]
	v_mfma_f32_16x16x32_bf16 v[36:39], v[172:175], v[198:201], v[36:39]
	v_mfma_f32_16x16x32_bf16 v[32:35], v[182:185], v[198:201], v[32:35]
	v_mfma_f32_16x16x32_bf16 v[20:23], v[172:175], v[212:215], v[20:23]
	v_mfma_f32_16x16x32_bf16 v[16:19], v[182:185], v[212:215], v[16:19]
	v_lshl_add_u64 v[228:229], s[58:59], 0, v[130:131]
	s_mov_b32 m0, s53
	s_nop 0
	global_load_lds_dwordx4 v[228:229], off
	v_mfma_f32_16x16x32_bf16 v[4:7], v[172:175], v[220:223], v[4:7]
	v_mfma_f32_16x16x32_bf16 v[0:3], v[182:185], v[220:223], v[0:3]
	s_setprio 0
	s_barrier
	s_add_i32 s3, 0, 0x18000
	v_add_u32_e32 v159, s3, v153
	s_add_i32 s33, 0, 0x1c000
	ds_read_b128 v[144:147], v159
	ds_read_b128 v[148:151], v159 offset:1024
	ds_read_b128 v[160:163], v159 offset:2048
	ds_read_b128 v[164:167], v159 offset:3072
	v_add_u32_e32 v159, s33, v153
	ds_read_b128 v[168:171], v159
	ds_read_b128 v[172:175], v159 offset:1024
	ds_read_b128 v[176:179], v159 offset:2048
	ds_read_b128 v[182:185], v159 offset:3072
	s_add_u32 s58, s58, 0x40000
	s_addc_u32 s59, s59, 0
	s_mov_b32 m0, s60
	v_lshl_add_u64 v[230:231], s[58:59], 0, v[134:135]
	ds_read_b128 v[186:189], v157 offset:32768
	ds_read_b128 v[190:193], v157 offset:33792
	ds_read_b128 v[194:197], v157 offset:34816
	ds_read_b128 v[198:201], v157 offset:35840
	ds_read_b128 v[208:211], v157 offset:36864
	ds_read_b128 v[212:215], v157 offset:37888
	ds_read_b128 v[216:219], v157 offset:38912
	ds_read_b128 v[220:223], v157 offset:39936
	global_load_lds_dwordx4 v[230:231], off
	v_lshl_add_u64 v[230:231], s[58:59], 0, v[130:131]
	s_mov_b32 m0, s61
	s_nop 0
	global_load_lds_dwordx4 v[230:231], off
	s_waitcnt vmcnt(8)
	s_waitcnt lgkmcnt(0)
	s_barrier
	s_setprio 1
	s_waitcnt lgkmcnt(0)
	v_mfma_f32_16x16x32_bf16 v[124:127], v[144:147], v[186:189], v[124:127]
	v_mfma_f32_16x16x32_bf16 v[120:123], v[160:163], v[186:189], v[120:123]
	v_mfma_f32_16x16x32_bf16 v[108:111], v[144:147], v[194:197], v[108:111]
	v_mfma_f32_16x16x32_bf16 v[104:107], v[160:163], v[194:197], v[104:107]
	v_mfma_f32_16x16x32_bf16 v[92:95], v[144:147], v[208:211], v[92:95]
	v_mfma_f32_16x16x32_bf16 v[88:91], v[160:163], v[208:211], v[88:91]
	v_mfma_f32_16x16x32_bf16 v[76:79], v[144:147], v[216:219], v[76:79]
	v_mfma_f32_16x16x32_bf16 v[72:75], v[160:163], v[216:219], v[72:75]
	v_mfma_f32_16x16x32_bf16 v[124:127], v[148:151], v[190:193], v[124:127]
	v_mfma_f32_16x16x32_bf16 v[120:123], v[164:167], v[190:193], v[120:123]
	v_mfma_f32_16x16x32_bf16 v[108:111], v[148:151], v[198:201], v[108:111]
	v_mfma_f32_16x16x32_bf16 v[104:107], v[164:167], v[198:201], v[104:107]
	v_mfma_f32_16x16x32_bf16 v[92:95], v[148:151], v[212:215], v[92:95]
	v_mfma_f32_16x16x32_bf16 v[88:91], v[164:167], v[212:215], v[88:91]
	v_mfma_f32_16x16x32_bf16 v[76:79], v[148:151], v[220:223], v[76:79]
	v_mfma_f32_16x16x32_bf16 v[72:75], v[164:167], v[220:223], v[72:75]
	s_setprio 0
	s_setprio 1
	v_mfma_f32_16x16x32_bf16 v[116:119], v[168:171], v[186:189], v[116:119]
	v_mfma_f32_16x16x32_bf16 v[112:115], v[176:179], v[186:189], v[112:115]
	v_mfma_f32_16x16x32_bf16 v[100:103], v[168:171], v[194:197], v[100:103]
	v_mfma_f32_16x16x32_bf16 v[96:99], v[176:179], v[194:197], v[96:99]
	v_mfma_f32_16x16x32_bf16 v[84:87], v[168:171], v[208:211], v[84:87]
	v_mfma_f32_16x16x32_bf16 v[80:83], v[176:179], v[208:211], v[80:83]
	v_mfma_f32_16x16x32_bf16 v[68:71], v[168:171], v[216:219], v[68:71]
	v_mfma_f32_16x16x32_bf16 v[64:67], v[176:179], v[216:219], v[64:67]
	v_mfma_f32_16x16x32_bf16 v[116:119], v[172:175], v[190:193], v[116:119]
	v_mfma_f32_16x16x32_bf16 v[112:115], v[182:185], v[190:193], v[112:115]
	v_mfma_f32_16x16x32_bf16 v[100:103], v[172:175], v[198:201], v[100:103]
	v_mfma_f32_16x16x32_bf16 v[96:99], v[182:185], v[198:201], v[96:99]
	v_mfma_f32_16x16x32_bf16 v[84:87], v[172:175], v[212:215], v[84:87]
	v_mfma_f32_16x16x32_bf16 v[80:83], v[182:185], v[212:215], v[80:83]
	v_mfma_f32_16x16x32_bf16 v[68:71], v[172:175], v[220:223], v[68:71]
	v_mfma_f32_16x16x32_bf16 v[64:67], v[182:185], v[220:223], v[64:67]
	s_setprio 0
	s_barrier
; #define PG8_STAGE(bufoff, gbase, voff) do { _Pragma("unroll") for (int _i = 0; _i < 2; ++_i) \
;         __builtin_amdgcn_global_load_lds((const unsigned*)((const char*)(gbase) + (voff)[_i]), (PG8_LAS unsigned*)(lds + (bufoff) + ldsw + _i * 8192), 16, 0, 0); } while (0)
; #define PG8_LDA(dst, b, h) do { _Pragma("unroll") for (int m = 0; m < 4; ++m) _Pragma("unroll") for (int k = 0; k < 2; ++k) dst[m][k] = *(const PG8_LAS bf16x8*)(lds + PG8_SA(b, h) + aoff + m * 2048 + k * 1024); } while (0)
; #define PG8_LDB(dst, b, h) do { _Pragma("unroll") for (int n = 0; n < 2; ++n) _Pragma("unroll") for (int k = 0; k < 2; ++k) dst[n][k] = *(const PG8_LAS bf16x8*)(lds + PG8_SB(b, h) + boff + n * 2048 + k * 1024); } while (0)
; #define PG8_MMA(ai, bj, At, Bt) do { __builtin_amdgcn_s_setprio(1); _Pragma("unroll") for (int m = 0; m < 4; ++m) _Pragma("unroll") for (int n = 0; n < 2; ++n) _Pragma("unroll") for (int k = 0; k < 2; ++k) \
;         acc[ai][bj][m][n] = __builtin_amdgcn_mfma_f32_16x16x32_bf16(Bt[n][k], At[m][k], acc[ai][bj][m][n], 0, 0, 0); __builtin_amdgcn_s_setprio(0); } while (0)
; #define PG8_WAIT_V(n) asm volatile("s_waitcnt vmcnt(" #n ")" ::: "memory")
; template <class Epi, class Sched, bool ALIGN_EPI = false, bool SP2 = false>
; __device__ __forceinline__ void gemm_phase(PG8_LAS unsigned char* lds, const Gemm g, const Sched& S, const Epi& E) {
;     ...
;             PG8_LDB(B0, 0, 0); PG8_LDB(B1, 0, 1); PG8_SCHED; PG8_LDA(At, 0, 0); PG8_STAGE(PG8_SA(1, 1), a1 + hstep, voffA);
;             PG8_WAIT_V(8); PG8_WAIT_L(0); PG8_BAR; PG8_MMA(0, 0, At, B0); PG8_MMA(0, 1, At, B1); PG8_BAR; PG8_SCHED;
;             PG8_LDA(At, 0, 1); PG8_STAGE(PG8_SB(0, 0), b2, voffB); PG8_STAGE(PG8_SB(0, 1), b2 + hstep, voffB); PG8_STAGE(PG8_SA(0, 0), a2, voffA);
;             PG8_WAIT_V(8); PG8_WAIT_L(0); PG8_BAR; PG8_MMA(1, 0, At, B0); PG8_MMA(1, 1, At, B1); PG8_BAR; PG8_SCHED;
;             PG8_LDB(B0, 1, 0); PG8_LDB(B1, 1, 1); PG8_SCHED; PG8_LDA(At, 1, 0); PG8_STAGE(PG8_SA(0, 1), a2 + hstep, voffA);
;             PG8_WAIT_V(8); PG8_WAIT_L(0); PG8_BAR; PG8_MMA(0, 0, At, B0); PG8_MMA(0, 1, At, B1); PG8_BAR; PG8_SCHED;
;             PG8_LDA(At, 1, 1); PG8_STAGE(PG8_SB(1, 0), b3, voffB); PG8_STAGE(PG8_SB(1, 1), b3 + hstep, voffB); PG8_STAGE(PG8_SA(1, 0), a3, voffA);
;             PG8_WAIT_V(8); PG8_WAIT_L(0); PG8_BAR; PG8_MMA(1, 0, At, B0); PG8_MMA(1, 1, At, B1); PG8_BAR; PG8_SCHED;
	s_add_i32 s3, s3, s14
	v_lshl_add_u64 v[202:203], v[202:203], 0, s[36:37]
	s_mov_b32 m0, s3
	ds_read_b128 v[186:189], v157 offset:49152
	ds_read_b128 v[190:193], v157 offset:50176
	ds_read_b128 v[194:197], v157 offset:51200
	ds_read_b128 v[198:201], v157 offset:52224
	ds_read_b128 v[208:211], v157 offset:53248
	ds_read_b128 v[212:215], v157 offset:54272
	ds_read_b128 v[216:219], v157 offset:55296
	ds_read_b128 v[220:223], v157 offset:56320
	global_load_lds_dwordx4 v[202:203], off
	s_add_i32 m0, s3, 0x2000
	s_add_u32 s56, s56, 0x40080
	v_lshl_add_u64 v[202:203], v[224:225], 0, s[36:37]
	s_addc_u32 s57, s57, 0
	s_add_i32 s3, s33, s14
	global_load_lds_dwordx4 v[202:203], off
	v_lshl_add_u64 v[202:203], s[56:57], 0, v[132:133]
	s_mov_b32 m0, s3
	s_nop 0
	global_load_lds_dwordx4 v[202:203], off
	v_lshl_add_u64 v[202:203], s[56:57], 0, v[128:129]
	s_add_i32 m0, s3, 0x2000
	s_nop 0
	global_load_lds_dwordx4 v[202:203], off
	s_waitcnt vmcnt(6)
	s_waitcnt lgkmcnt(0)
	s_barrier
	s_setprio 1
	s_waitcnt lgkmcnt(0)
	v_mfma_f32_16x16x32_bf16 v[60:63], v[144:147], v[186:189], v[60:63]
	v_mfma_f32_16x16x32_bf16 v[56:59], v[160:163], v[186:189], v[56:59]
	v_mfma_f32_16x16x32_bf16 v[44:47], v[144:147], v[194:197], v[44:47]
	v_mfma_f32_16x16x32_bf16 v[40:43], v[160:163], v[194:197], v[40:43]
	v_mfma_f32_16x16x32_bf16 v[28:31], v[144:147], v[208:211], v[28:31]
	v_mfma_f32_16x16x32_bf16 v[24:27], v[160:163], v[208:211], v[24:27]
	v_mfma_f32_16x16x32_bf16 v[12:15], v[144:147], v[216:219], v[12:15]
	v_mfma_f32_16x16x32_bf16 v[8:11], v[160:163], v[216:219], v[8:11]
	v_mfma_f32_16x16x32_bf16 v[60:63], v[148:151], v[190:193], v[60:63]
	v_mfma_f32_16x16x32_bf16 v[56:59], v[164:167], v[190:193], v[56:59]
	v_mfma_f32_16x16x32_bf16 v[44:47], v[148:151], v[198:201], v[44:47]
	v_mfma_f32_16x16x32_bf16 v[40:43], v[164:167], v[198:201], v[40:43]
	v_mfma_f32_16x16x32_bf16 v[28:31], v[148:151], v[212:215], v[28:31]
	v_mfma_f32_16x16x32_bf16 v[24:27], v[164:167], v[212:215], v[24:27]
	v_lshl_add_u64 v[202:203], v[226:227], 0, s[36:37]
	s_mov_b32 m0, s63
	s_nop 0
	global_load_lds_dwordx4 v[202:203], off
	v_mfma_f32_16x16x32_bf16 v[12:15], v[148:151], v[220:223], v[12:15]
	v_mfma_f32_16x16x32_bf16 v[8:11], v[164:167], v[220:223], v[8:11]
	s_setprio 0
	s_setprio 1
	v_mfma_f32_16x16x32_bf16 v[52:55], v[168:171], v[186:189], v[52:55]
	v_mfma_f32_16x16x32_bf16 v[48:51], v[176:179], v[186:189], v[48:51]
	v_mfma_f32_16x16x32_bf16 v[36:39], v[168:171], v[194:197], v[36:39]
	v_mfma_f32_16x16x32_bf16 v[32:35], v[176:179], v[194:197], v[32:35]
	v_mfma_f32_16x16x32_bf16 v[20:23], v[168:171], v[208:211], v[20:23]
	v_mfma_f32_16x16x32_bf16 v[16:19], v[176:179], v[208:211], v[16:19]
	v_mfma_f32_16x16x32_bf16 v[4:7], v[168:171], v[216:219], v[4:7]
	v_mfma_f32_16x16x32_bf16 v[0:3], v[176:179], v[216:219], v[0:3]
	v_mfma_f32_16x16x32_bf16 v[52:55], v[172:175], v[190:193], v[52:55]
	v_mfma_f32_16x16x32_bf16 v[48:51], v[182:185], v[190:193], v[48:51]
	v_mfma_f32_16x16x32_bf16 v[36:39], v[172:175], v[198:201], v[36:39]
	v_mfma_f32_16x16x32_bf16 v[32:35], v[182:185], v[198:201], v[32:35]
	v_mfma_f32_16x16x32_bf16 v[20:23], v[172:175], v[212:215], v[20:23]
	v_mfma_f32_16x16x32_bf16 v[16:19], v[182:185], v[212:215], v[16:19]
	v_lshl_add_u64 v[202:203], v[228:229], 0, s[36:37]
	s_mov_b32 m0, s64
	s_nop 0
	global_load_lds_dwordx4 v[202:203], off
	v_mfma_f32_16x16x32_bf16 v[4:7], v[172:175], v[220:223], v[4:7]
	v_mfma_f32_16x16x32_bf16 v[0:3], v[182:185], v[220:223], v[0:3]
	s_setprio 0
	s_barrier
	s_add_i32 s83, s83, 2
	s_add_u32 s54, s54, 0x100
	s_addc_u32 s55, s55, 0
	s_add_u32 s77, s77, 0x100
	s_addc_u32 s82, s82, 0
.LBB0_957:
	ds_read_b128 v[144:147], v155
	ds_read_b128 v[148:151], v155 offset:1024
	ds_read_b128 v[160:163], v155 offset:2048
	ds_read_b128 v[164:167], v155 offset:3072
	ds_read_b128 v[168:171], v156
	ds_read_b128 v[172:175], v156 offset:1024
	ds_read_b128 v[176:179], v156 offset:2048
	ds_read_b128 v[182:185], v156 offset:3072
	s_add_u32 s3, s54, 0xfffc0080
	s_addc_u32 s33, s55, -1
	s_cmp_eq_u32 s83, 12
	s_cselect_b32 s59, s45, s33
	s_cselect_b32 s58, s75, s3
	s_cselect_b32 s57, s43, s82
	s_cselect_b32 s56, s76, s77
	v_lshl_add_u64 v[202:203], s[54:55], 0, v[136:137]
	s_add_i32 m0, s34, 0xc000
	ds_read_b128 v[186:189], v157
	ds_read_b128 v[190:193], v157 offset:1024
	ds_read_b128 v[194:197], v157 offset:2048
	ds_read_b128 v[198:201], v157 offset:3072
	ds_read_b128 v[208:211], v157 offset:4096
	ds_read_b128 v[212:215], v157 offset:5120
	ds_read_b128 v[216:219], v157 offset:6144
	ds_read_b128 v[220:223], v157 offset:7168
	global_load_lds_dwordx4 v[202:203], off
	v_lshl_add_u64 v[202:203], s[54:55], 0, v[138:139]
	s_add_i32 m0, s34, 0xe000
	s_nop 0
	global_load_lds_dwordx4 v[202:203], off
	s_waitcnt vmcnt(8)
	s_waitcnt lgkmcnt(0)
	s_barrier
; #define PG8_STAGE(bufoff, gbase, voff) do { _Pragma("unroll") for (int _i = 0; _i < 2; ++_i) \
;         __builtin_amdgcn_global_load_lds((const unsigned*)((const char*)(gbase) + (voff)[_i]), (PG8_LAS unsigned*)(lds + (bufoff) + ldsw + _i * 8192), 16, 0, 0); } while (0)
; #define PG8_LDA(dst, b, h) do { _Pragma("unroll") for (int m = 0; m < 4; ++m) _Pragma("unroll") for (int k = 0; k < 2; ++k) dst[m][k] = *(const PG8_LAS bf16x8*)(lds + PG8_SA(b, h) + aoff + m * 2048 + k * 1024); } while (0)
; #define PG8_LDB(dst, b, h) do { _Pragma("unroll") for (int n = 0; n < 2; ++n) _Pragma("unroll") for (int k = 0; k < 2; ++k) dst[n][k] = *(const PG8_LAS bf16x8*)(lds + PG8_SB(b, h) + boff + n * 2048 + k * 1024); } while (0)
; #define PG8_MMA(ai, bj, At, Bt) do { __builtin_amdgcn_s_setprio(1); _Pragma("unroll") for (int m = 0; m < 4; ++m) _Pragma("unroll") for (int n = 0; n < 2; ++n) _Pragma("unroll") for (int k = 0; k < 2; ++k) \
;         acc[ai][bj][m][n] = __builtin_amdgcn_mfma_f32_16x16x32_bf16(Bt[n][k], At[m][k], acc[ai][bj][m][n], 0, 0, 0); __builtin_amdgcn_s_setprio(0); } while (0)
; #define PG8_WAIT_V(n) asm volatile("s_waitcnt vmcnt(" #n ")" ::: "memory")
; #define PG8_WAIT_L(n) asm volatile("s_waitcnt lgkmcnt(" #n ")" ::: "memory")
; #define PG8_BAR __builtin_amdgcn_s_barrier()
; #define PG8_SCHED __builtin_amdgcn_sched_barrier(0)
; template <class Epi, class Sched, bool ALIGN_EPI = false, bool SP2 = false>
; __device__ __forceinline__ void gemm_phase(PG8_LAS unsigned char* lds, const Gemm g, const Sched& S, const Epi& E) {
;     ...
;             PG8_WAIT_V(8); PG8_WAIT_L(0); PG8_BAR; PG8_MMA(0, 0, At, B0); PG8_MMA(0, 1, At, B1); PG8_BAR; PG8_SCHED;
;             PG8_LDA(At, 0, 1); PG8_STAGE(PG8_SB(0, 0), b2, voffB); PG8_STAGE(PG8_SB(0, 1), b2 + hstep, voffB); PG8_STAGE(PG8_SA(0, 0), a2, voffA);
;             PG8_WAIT_V(8); PG8_WAIT_L(0); PG8_BAR; PG8_MMA(1, 0, At, B0); PG8_MMA(1, 1, At, B1); PG8_BAR; PG8_SCHED;
;             PG8_LDB(B0, 1, 0); PG8_LDB(B1, 1, 1); PG8_SCHED; PG8_LDA(At, 1, 0); PG8_STAGE(PG8_SA(0, 1), a2 + hstep, voffA);
;             PG8_WAIT_V(8); PG8_WAIT_L(0); PG8_BAR; PG8_MMA(0, 0, At, B0); PG8_MMA(0, 1, At, B1); PG8_BAR; PG8_SCHED;
	s_setprio 1
	s_waitcnt lgkmcnt(0)
	v_mfma_f32_16x16x32_bf16 v[124:127], v[144:147], v[186:189], v[124:127]
	v_mfma_f32_16x16x32_bf16 v[120:123], v[160:163], v[186:189], v[120:123]
	v_mfma_f32_16x16x32_bf16 v[108:111], v[144:147], v[194:197], v[108:111]
	v_mfma_f32_16x16x32_bf16 v[104:107], v[160:163], v[194:197], v[104:107]
	v_mfma_f32_16x16x32_bf16 v[92:95], v[144:147], v[208:211], v[92:95]
	v_mfma_f32_16x16x32_bf16 v[88:91], v[160:163], v[208:211], v[88:91]
	v_mfma_f32_16x16x32_bf16 v[76:79], v[144:147], v[216:219], v[76:79]
	v_mfma_f32_16x16x32_bf16 v[72:75], v[160:163], v[216:219], v[72:75]
	v_mfma_f32_16x16x32_bf16 v[124:127], v[148:151], v[190:193], v[124:127]
	v_mfma_f32_16x16x32_bf16 v[120:123], v[164:167], v[190:193], v[120:123]
	v_mfma_f32_16x16x32_bf16 v[108:111], v[148:151], v[198:201], v[108:111]
	v_mfma_f32_16x16x32_bf16 v[104:107], v[164:167], v[198:201], v[104:107]
	v_mfma_f32_16x16x32_bf16 v[92:95], v[148:151], v[212:215], v[92:95]
	v_mfma_f32_16x16x32_bf16 v[88:91], v[164:167], v[212:215], v[88:91]
	v_mfma_f32_16x16x32_bf16 v[76:79], v[148:151], v[220:223], v[76:79]
	v_mfma_f32_16x16x32_bf16 v[72:75], v[164:167], v[220:223], v[72:75]
	s_setprio 0
	s_setprio 1
	v_mfma_f32_16x16x32_bf16 v[116:119], v[168:171], v[186:189], v[116:119]
	v_mfma_f32_16x16x32_bf16 v[112:115], v[176:179], v[186:189], v[112:115]
	v_mfma_f32_16x16x32_bf16 v[100:103], v[168:171], v[194:197], v[100:103]
	v_mfma_f32_16x16x32_bf16 v[96:99], v[176:179], v[194:197], v[96:99]
	v_mfma_f32_16x16x32_bf16 v[84:87], v[168:171], v[208:211], v[84:87]
	v_mfma_f32_16x16x32_bf16 v[80:83], v[176:179], v[208:211], v[80:83]
	v_mfma_f32_16x16x32_bf16 v[68:71], v[168:171], v[216:219], v[68:71]
	v_mfma_f32_16x16x32_bf16 v[64:67], v[176:179], v[216:219], v[64:67]
	v_mfma_f32_16x16x32_bf16 v[116:119], v[172:175], v[190:193], v[116:119]
	v_mfma_f32_16x16x32_bf16 v[112:115], v[182:185], v[190:193], v[112:115]
	v_mfma_f32_16x16x32_bf16 v[100:103], v[172:175], v[198:201], v[100:103]
	v_mfma_f32_16x16x32_bf16 v[96:99], v[182:185], v[198:201], v[96:99]
	v_mfma_f32_16x16x32_bf16 v[84:87], v[172:175], v[212:215], v[84:87]
	v_mfma_f32_16x16x32_bf16 v[80:83], v[182:185], v[212:215], v[80:83]
	v_mfma_f32_16x16x32_bf16 v[68:71], v[172:175], v[220:223], v[68:71]
	v_mfma_f32_16x16x32_bf16 v[64:67], v[182:185], v[220:223], v[64:67]
	s_setprio 0
	s_barrier
	s_add_i32 s3, s65, s14
	v_lshl_add_u64 v[202:203], s[56:57], 0, v[132:133]
	s_mov_b32 m0, s3
	ds_read_b128 v[186:189], v157 offset:16384
	ds_read_b128 v[190:193], v157 offset:17408
	ds_read_b128 v[194:197], v157 offset:18432
	ds_read_b128 v[198:201], v157 offset:19456
	ds_read_b128 v[208:211], v157 offset:20480
	ds_read_b128 v[212:215], v157 offset:21504
	ds_read_b128 v[216:219], v157 offset:22528
	ds_read_b128 v[220:223], v157 offset:23552
	global_load_lds_dwordx4 v[202:203], off
	s_add_i32 m0, s3, 0x2000
	s_add_u32 s78, s56, 0x40000
	v_lshl_add_u64 v[224:225], s[56:57], 0, v[128:129]
	s_addc_u32 s79, s57, 0
	s_add_i32 s3, s66, s14
	global_load_lds_dwordx4 v[224:225], off
	v_lshl_add_u64 v[226:227], s[78:79], 0, v[132:133]
	s_mov_b32 m0, s3
	global_load_lds_dwordx4 v[226:227], off
	v_lshl_add_u64 v[226:227], s[78:79], 0, v[128:129]
	s_add_i32 m0, s3, 0x2000
	s_nop 0
	global_load_lds_dwordx4 v[226:227], off
	s_waitcnt vmcnt(6)
	s_waitcnt lgkmcnt(0)
	s_barrier
	s_setprio 1
	s_waitcnt lgkmcnt(0)
	v_mfma_f32_16x16x32_bf16 v[60:63], v[144:147], v[186:189], v[60:63]
	v_mfma_f32_16x16x32_bf16 v[56:59], v[160:163], v[186:189], v[56:59]
	v_mfma_f32_16x16x32_bf16 v[44:47], v[144:147], v[194:197], v[44:47]
	v_mfma_f32_16x16x32_bf16 v[40:43], v[160:163], v[194:197], v[40:43]
	v_mfma_f32_16x16x32_bf16 v[28:31], v[144:147], v[208:211], v[28:31]
	v_mfma_f32_16x16x32_bf16 v[24:27], v[160:163], v[208:211], v[24:27]
	v_mfma_f32_16x16x32_bf16 v[12:15], v[144:147], v[216:219], v[12:15]
	v_mfma_f32_16x16x32_bf16 v[8:11], v[160:163], v[216:219], v[8:11]
	v_mfma_f32_16x16x32_bf16 v[60:63], v[148:151], v[190:193], v[60:63]
	v_mfma_f32_16x16x32_bf16 v[56:59], v[164:167], v[190:193], v[56:59]
	v_mfma_f32_16x16x32_bf16 v[44:47], v[148:151], v[198:201], v[44:47]
	v_mfma_f32_16x16x32_bf16 v[40:43], v[164:167], v[198:201], v[40:43]
	v_mfma_f32_16x16x32_bf16 v[28:31], v[148:151], v[212:215], v[28:31]
	v_mfma_f32_16x16x32_bf16 v[24:27], v[164:167], v[212:215], v[24:27]
	v_lshl_add_u64 v[226:227], s[58:59], 0, v[134:135]
	s_mov_b32 m0, s34
	s_nop 0
	global_load_lds_dwordx4 v[226:227], off
	v_mfma_f32_16x16x32_bf16 v[12:15], v[148:151], v[220:223], v[12:15]
	v_mfma_f32_16x16x32_bf16 v[8:11], v[164:167], v[220:223], v[8:11]
	s_setprio 0
	s_setprio 1
	v_mfma_f32_16x16x32_bf16 v[52:55], v[168:171], v[186:189], v[52:55]
	v_mfma_f32_16x16x32_bf16 v[48:51], v[176:179], v[186:189], v[48:51]
	v_mfma_f32_16x16x32_bf16 v[36:39], v[168:171], v[194:197], v[36:39]
	v_mfma_f32_16x16x32_bf16 v[32:35], v[176:179], v[194:197], v[32:35]
	v_mfma_f32_16x16x32_bf16 v[20:23], v[168:171], v[208:211], v[20:23]
	v_mfma_f32_16x16x32_bf16 v[16:19], v[176:179], v[208:211], v[16:19]
	v_mfma_f32_16x16x32_bf16 v[4:7], v[168:171], v[216:219], v[4:7]
	v_mfma_f32_16x16x32_bf16 v[0:3], v[176:179], v[216:219], v[0:3]
	v_mfma_f32_16x16x32_bf16 v[52:55], v[172:175], v[190:193], v[52:55]
	v_mfma_f32_16x16x32_bf16 v[48:51], v[182:185], v[190:193], v[48:51]
	v_mfma_f32_16x16x32_bf16 v[36:39], v[172:175], v[198:201], v[36:39]
	v_mfma_f32_16x16x32_bf16 v[32:35], v[182:185], v[198:201], v[32:35]
	v_mfma_f32_16x16x32_bf16 v[20:23], v[172:175], v[212:215], v[20:23]
	v_mfma_f32_16x16x32_bf16 v[16:19], v[182:185], v[212:215], v[16:19]
	v_lshl_add_u64 v[228:229], s[58:59], 0, v[130:131]
	s_mov_b32 m0, s53
	s_nop 0
	global_load_lds_dwordx4 v[228:229], off
	v_mfma_f32_16x16x32_bf16 v[4:7], v[172:175], v[220:223], v[4:7]
	v_mfma_f32_16x16x32_bf16 v[0:3], v[182:185], v[220:223], v[0:3]
	s_setprio 0
	s_barrier
; #define PG8_STAGE(bufoff, gbase, voff) do { _Pragma("unroll") for (int _i = 0; _i < 2; ++_i) \
;         __builtin_amdgcn_global_load_lds((const unsigned*)((const char*)(gbase) + (voff)[_i]), (PG8_LAS unsigned*)(lds + (bufoff) + ldsw + _i * 8192), 16, 0, 0); } while (0)
; #define PG8_LDA(dst, b, h) do { _Pragma("unroll") for (int m = 0; m < 4; ++m) _Pragma("unroll") for (int k = 0; k < 2; ++k) dst[m][k] = *(const PG8_LAS bf16x8*)(lds + PG8_SA(b, h) + aoff + m * 2048 + k * 1024); } while (0)
; #define PG8_LDB(dst, b, h) do { _Pragma("unroll") for (int n = 0; n < 2; ++n) _Pragma("unroll") for (int k = 0; k < 2; ++k) dst[n][k] = *(const PG8_LAS bf16x8*)(lds + PG8_SB(b, h) + boff + n * 2048 + k * 1024); } while (0)
; #define PG8_MMA(ai, bj, At, Bt) do { __builtin_amdgcn_s_setprio(1); _Pragma("unroll") for (int m = 0; m < 4; ++m) _Pragma("unroll") for (int n = 0; n < 2; ++n) _Pragma("unroll") for (int k = 0; k < 2; ++k) \
;         acc[ai][bj][m][n] = __builtin_amdgcn_mfma_f32_16x16x32_bf16(Bt[n][k], At[m][k], acc[ai][bj][m][n], 0, 0, 0); __builtin_amdgcn_s_setprio(0); } while (0)
; #define PG8_WAIT_V(n) asm volatile("s_waitcnt vmcnt(" #n ")" ::: "memory")
; #define PG8_WAIT_L(n) asm volatile("s_waitcnt lgkmcnt(" #n ")" ::: "memory")
; #define PG8_BAR __builtin_amdgcn_s_barrier()
; #define PG8_SCHED __builtin_amdgcn_sched_barrier(0)
; template <class Epi, class Sched, bool ALIGN_EPI = false, bool SP2 = false>
; __device__ __forceinline__ void gemm_phase(PG8_LAS unsigned char* lds, const Gemm g, const Sched& S, const Epi& E) {
;     ...
;             PG8_LDB(B0, 1, 0); PG8_LDB(B1, 1, 1); PG8_SCHED; PG8_LDA(At, 1, 0); PG8_STAGE(PG8_SA(0, 1), a2 + hstep, voffA);
;             PG8_WAIT_V(8); PG8_WAIT_L(0); PG8_BAR; PG8_MMA(0, 0, At, B0); PG8_MMA(0, 1, At, B1); PG8_BAR; PG8_SCHED;
;             PG8_LDA(At, 1, 1); PG8_STAGE(PG8_SB(1, 0), b3, voffB); PG8_STAGE(PG8_SB(1, 1), b3 + hstep, voffB); PG8_STAGE(PG8_SA(1, 0), a3, voffA);
;             PG8_WAIT_V(8); PG8_WAIT_L(0); PG8_BAR; PG8_MMA(1, 0, At, B0); PG8_MMA(1, 1, At, B1); PG8_BAR; PG8_SCHED;
	s_add_i32 s3, 0, 0x18000
	v_add_u32_e32 v159, s3, v153
	s_add_i32 s33, 0, 0x1c000
	ds_read_b128 v[144:147], v159
	ds_read_b128 v[148:151], v159 offset:1024
	ds_read_b128 v[160:163], v159 offset:2048
	ds_read_b128 v[164:167], v159 offset:3072
	v_add_u32_e32 v159, s33, v153
	ds_read_b128 v[168:171], v159
	ds_read_b128 v[172:175], v159 offset:1024
	ds_read_b128 v[176:179], v159 offset:2048
	ds_read_b128 v[182:185], v159 offset:3072
	s_add_u32 s58, s58, 0x40000
	s_addc_u32 s59, s59, 0
	s_mov_b32 m0, s60
	v_lshl_add_u64 v[230:231], s[58:59], 0, v[134:135]
	ds_read_b128 v[186:189], v157 offset:32768
	ds_read_b128 v[190:193], v157 offset:33792
	ds_read_b128 v[194:197], v157 offset:34816
	ds_read_b128 v[198:201], v157 offset:35840
	ds_read_b128 v[208:211], v157 offset:36864
	ds_read_b128 v[212:215], v157 offset:37888
	ds_read_b128 v[216:219], v157 offset:38912
	ds_read_b128 v[220:223], v157 offset:39936
	global_load_lds_dwordx4 v[230:231], off
	v_lshl_add_u64 v[230:231], s[58:59], 0, v[130:131]
	s_mov_b32 m0, s61
	s_nop 0
	global_load_lds_dwordx4 v[230:231], off
	s_waitcnt vmcnt(8)
	s_waitcnt lgkmcnt(0)
	s_barrier
	s_setprio 1
	s_waitcnt lgkmcnt(0)
	v_mfma_f32_16x16x32_bf16 v[124:127], v[144:147], v[186:189], v[124:127]
	v_mfma_f32_16x16x32_bf16 v[120:123], v[160:163], v[186:189], v[120:123]
	v_mfma_f32_16x16x32_bf16 v[108:111], v[144:147], v[194:197], v[108:111]
	v_mfma_f32_16x16x32_bf16 v[104:107], v[160:163], v[194:197], v[104:107]
	v_mfma_f32_16x16x32_bf16 v[92:95], v[144:147], v[208:211], v[92:95]
	v_mfma_f32_16x16x32_bf16 v[88:91], v[160:163], v[208:211], v[88:91]
	v_mfma_f32_16x16x32_bf16 v[76:79], v[144:147], v[216:219], v[76:79]
	v_mfma_f32_16x16x32_bf16 v[72:75], v[160:163], v[216:219], v[72:75]
	v_mfma_f32_16x16x32_bf16 v[124:127], v[148:151], v[190:193], v[124:127]
	v_mfma_f32_16x16x32_bf16 v[120:123], v[164:167], v[190:193], v[120:123]
	v_mfma_f32_16x16x32_bf16 v[108:111], v[148:151], v[198:201], v[108:111]
	v_mfma_f32_16x16x32_bf16 v[104:107], v[164:167], v[198:201], v[104:107]
	v_mfma_f32_16x16x32_bf16 v[92:95], v[148:151], v[212:215], v[92:95]
	v_mfma_f32_16x16x32_bf16 v[88:91], v[164:167], v[212:215], v[88:91]
	v_mfma_f32_16x16x32_bf16 v[76:79], v[148:151], v[220:223], v[76:79]
	v_mfma_f32_16x16x32_bf16 v[72:75], v[164:167], v[220:223], v[72:75]
	s_setprio 0
	s_setprio 1
	v_mfma_f32_16x16x32_bf16 v[116:119], v[168:171], v[186:189], v[116:119]
	v_mfma_f32_16x16x32_bf16 v[112:115], v[176:179], v[186:189], v[112:115]
	v_mfma_f32_16x16x32_bf16 v[100:103], v[168:171], v[194:197], v[100:103]
	v_mfma_f32_16x16x32_bf16 v[96:99], v[176:179], v[194:197], v[96:99]
	v_mfma_f32_16x16x32_bf16 v[84:87], v[168:171], v[208:211], v[84:87]
	v_mfma_f32_16x16x32_bf16 v[80:83], v[176:179], v[208:211], v[80:83]
	v_mfma_f32_16x16x32_bf16 v[68:71], v[168:171], v[216:219], v[68:71]
	v_mfma_f32_16x16x32_bf16 v[64:67], v[176:179], v[216:219], v[64:67]
	v_mfma_f32_16x16x32_bf16 v[116:119], v[172:175], v[190:193], v[116:119]
	v_mfma_f32_16x16x32_bf16 v[112:115], v[182:185], v[190:193], v[112:115]
	v_mfma_f32_16x16x32_bf16 v[100:103], v[172:175], v[198:201], v[100:103]
	v_mfma_f32_16x16x32_bf16 v[96:99], v[182:185], v[198:201], v[96:99]
	v_mfma_f32_16x16x32_bf16 v[84:87], v[172:175], v[212:215], v[84:87]
	v_mfma_f32_16x16x32_bf16 v[80:83], v[182:185], v[212:215], v[80:83]
	v_mfma_f32_16x16x32_bf16 v[68:71], v[172:175], v[220:223], v[68:71]
	v_mfma_f32_16x16x32_bf16 v[64:67], v[182:185], v[220:223], v[64:67]
	s_setprio 0
	s_barrier
	s_add_i32 s3, s3, s14
	v_lshl_add_u64 v[202:203], v[202:203], 0, s[36:37]
	s_mov_b32 m0, s3
	ds_read_b128 v[186:189], v157 offset:49152
	ds_read_b128 v[190:193], v157 offset:50176
	ds_read_b128 v[194:197], v157 offset:51200
	ds_read_b128 v[198:201], v157 offset:52224
	ds_read_b128 v[208:211], v157 offset:53248
	ds_read_b128 v[212:215], v157 offset:54272
	ds_read_b128 v[216:219], v157 offset:55296
	ds_read_b128 v[220:223], v157 offset:56320
	global_load_lds_dwordx4 v[202:203], off
	s_add_i32 m0, s3, 0x2000
	s_add_u32 s56, s56, 0x40080
	v_lshl_add_u64 v[202:203], v[224:225], 0, s[36:37]
	s_addc_u32 s57, s57, 0
	s_add_i32 s3, s33, s14
	global_load_lds_dwordx4 v[202:203], off
	v_lshl_add_u64 v[202:203], s[56:57], 0, v[132:133]
	s_mov_b32 m0, s3
	s_nop 0
	global_load_lds_dwordx4 v[202:203], off
	v_lshl_add_u64 v[202:203], s[56:57], 0, v[128:129]
	s_add_i32 m0, s3, 0x2000
	s_nop 0
	global_load_lds_dwordx4 v[202:203], off
	s_waitcnt vmcnt(6)
	s_waitcnt lgkmcnt(0)
	s_barrier
; __device__ __forceinline__ unsigned cvtpk(float lo, float hi) { f32x2v_ v = {lo, hi}; bf16x2v_ b = __builtin_convertvector(v, bf16x2v_); return __builtin_bit_cast(unsigned, b); }
; #define PG8_STAGE(bufoff, gbase, voff) do { _Pragma("unroll") for (int _i = 0; _i < 2; ++_i) \
;         __builtin_amdgcn_global_load_lds((const unsigned*)((const char*)(gbase) + (voff)[_i]), (PG8_LAS unsigned*)(lds + (bufoff) + ldsw + _i * 8192), 16, 0, 0); } while (0)
; #define PG8_LDA(dst, b, h) do { _Pragma("unroll") for (int m = 0; m < 4; ++m) _Pragma("unroll") for (int k = 0; k < 2; ++k) dst[m][k] = *(const PG8_LAS bf16x8*)(lds + PG8_SA(b, h) + aoff + m * 2048 + k * 1024); } while (0)
; #define PG8_MMA(ai, bj, At, Bt) do { __builtin_amdgcn_s_setprio(1); _Pragma("unroll") for (int m = 0; m < 4; ++m) _Pragma("unroll") for (int n = 0; n < 2; ++n) _Pragma("unroll") for (int k = 0; k < 2; ++k) \
;         acc[ai][bj][m][n] = __builtin_amdgcn_mfma_f32_16x16x32_bf16(Bt[n][k], At[m][k], acc[ai][bj][m][n], 0, 0, 0); __builtin_amdgcn_s_setprio(0); } while (0)
; #define PG8_WAIT_V(n) asm volatile("s_waitcnt vmcnt(" #n ")" ::: "memory")
;     __device__ __forceinline__ void operator()(const f32x4 (&acc)[2][2][4][2], const Unit& u, int wr, int wc, int fr, int fq) const {
;     ...
;             for (int m = 0; m < 4; ++m) { const int row = row0 + ai * HALF + m * 16; const float rs = row_rs(ss, row);
;                 float hv[8];
; #pragma unroll
;                 for (int n = 0; n < 2; ++n)
; #pragma unroll
;                     for (int i = 0; i < 4; ++i) { const float g = acc[ai][0][m][n][i] * rs, uu = acc[ai][1][m][n][i] * rs;
;                         hv[n * 4 + i] = g * __builtin_amdgcn_rcpf(1.0f + __expf(-g)) * uu; }
;                 u32x4 w; w.x = cvtpk(hv[0], hv[1]); w.y = cvtpk(hv[2], hv[3]); w.z = cvtpk(hv[4], hv[5]); w.w = cvtpk(hv[6], hv[7]);
;                 *(u32x4*)(H + (size_t)row * ldh + col0) = w; }
; template <class Epi, class Sched, bool ALIGN_EPI = false, bool SP2 = false>
; __device__ __forceinline__ void gemm_phase(PG8_LAS unsigned char* lds, const Gemm g, const Sched& S, const Epi& E) {
;     ...
;             PG8_LDA(At, 1, 1); PG8_STAGE(PG8_SB(1, 0), b3, voffB); PG8_STAGE(PG8_SB(1, 1), b3 + hstep, voffB); PG8_STAGE(PG8_SA(1, 0), a3, voffA);
;             PG8_WAIT_V(8); PG8_WAIT_L(0); PG8_BAR; PG8_MMA(1, 0, At, B0); PG8_MMA(1, 1, At, B1); PG8_BAR; PG8_SCHED;
	s_setprio 1
	s_waitcnt lgkmcnt(0)
	v_mfma_f32_16x16x32_bf16 v[60:63], v[144:147], v[186:189], v[60:63]
	v_mfma_f32_16x16x32_bf16 v[56:59], v[160:163], v[186:189], v[56:59]
	v_mfma_f32_16x16x32_bf16 v[44:47], v[144:147], v[194:197], v[44:47]
	v_mfma_f32_16x16x32_bf16 v[40:43], v[160:163], v[194:197], v[40:43]
	v_mfma_f32_16x16x32_bf16 v[28:31], v[144:147], v[208:211], v[28:31]
	v_mfma_f32_16x16x32_bf16 v[24:27], v[160:163], v[208:211], v[24:27]
	v_mfma_f32_16x16x32_bf16 v[12:15], v[144:147], v[216:219], v[12:15]
	v_mfma_f32_16x16x32_bf16 v[8:11], v[160:163], v[216:219], v[8:11]
	v_mfma_f32_16x16x32_bf16 v[60:63], v[148:151], v[190:193], v[60:63]
	v_mfma_f32_16x16x32_bf16 v[56:59], v[164:167], v[190:193], v[56:59]
	v_mfma_f32_16x16x32_bf16 v[44:47], v[148:151], v[198:201], v[44:47]
	v_mfma_f32_16x16x32_bf16 v[40:43], v[164:167], v[198:201], v[40:43]
	v_mfma_f32_16x16x32_bf16 v[28:31], v[148:151], v[212:215], v[28:31]
	v_mfma_f32_16x16x32_bf16 v[24:27], v[164:167], v[212:215], v[24:27]
	v_lshl_add_u64 v[202:203], v[226:227], 0, s[36:37]
	s_mov_b32 m0, s63
	s_nop 0
	global_load_lds_dwordx4 v[202:203], off
	v_mfma_f32_16x16x32_bf16 v[12:15], v[148:151], v[220:223], v[12:15]
	v_mfma_f32_16x16x32_bf16 v[8:11], v[164:167], v[220:223], v[8:11]
	s_setprio 0
	s_setprio 1
	v_mfma_f32_16x16x32_bf16 v[52:55], v[168:171], v[186:189], v[52:55]
	v_mfma_f32_16x16x32_bf16 v[48:51], v[176:179], v[186:189], v[48:51]
	v_mfma_f32_16x16x32_bf16 v[36:39], v[168:171], v[194:197], v[36:39]
	v_mfma_f32_16x16x32_bf16 v[32:35], v[176:179], v[194:197], v[32:35]
	v_mfma_f32_16x16x32_bf16 v[20:23], v[168:171], v[208:211], v[20:23]
	v_mfma_f32_16x16x32_bf16 v[16:19], v[176:179], v[208:211], v[16:19]
	v_mfma_f32_16x16x32_bf16 v[4:7], v[168:171], v[216:219], v[4:7]
	v_mfma_f32_16x16x32_bf16 v[0:3], v[176:179], v[216:219], v[0:3]
	v_mfma_f32_16x16x32_bf16 v[52:55], v[172:175], v[190:193], v[52:55]
	v_mfma_f32_16x16x32_bf16 v[48:51], v[182:185], v[190:193], v[48:51]
	v_mfma_f32_16x16x32_bf16 v[36:39], v[172:175], v[198:201], v[36:39]
	v_mfma_f32_16x16x32_bf16 v[32:35], v[182:185], v[198:201], v[32:35]
	v_mfma_f32_16x16x32_bf16 v[20:23], v[172:175], v[212:215], v[20:23]
	v_mfma_f32_16x16x32_bf16 v[16:19], v[182:185], v[212:215], v[16:19]
	v_lshl_add_u64 v[202:203], v[228:229], 0, s[36:37]
	s_mov_b32 m0, s64
	s_nop 0
	global_load_lds_dwordx4 v[202:203], off
	v_mfma_f32_16x16x32_bf16 v[4:7], v[172:175], v[220:223], v[4:7]
	v_mfma_f32_16x16x32_bf16 v[0:3], v[182:185], v[220:223], v[0:3]
	s_setprio 0
	s_barrier
	s_add_i32 s83, s83, 2
	s_add_u32 s54, s54, 0x100
	s_addc_u32 s55, s55, 0
	s_add_u32 s77, s77, 0x100
	s_addc_u32 s82, s82, 0
	s_cmp_gt_u32 s83, 13
	s_cbranch_scc0 .LBB0_957
	v_lshl_add_u32 v144, s52, 8, v152
	v_ashrrev_i32_e32 v145, 31, v144
	v_lshl_add_u64 v[150:151], v[144:145], 3, s[0:1]
	global_load_dwordx2 v[182:183], v[150:151], off
	global_load_dwordx2 v[184:185], v[150:151], off offset:128
	global_load_dwordx2 v[186:187], v[150:151], off offset:256
	global_load_dwordx2 v[188:189], v[150:151], off offset:384
	global_load_dwordx2 v[190:191], v[150:151], off offset:1024
	global_load_dwordx2 v[192:193], v[150:151], off offset:1152
	global_load_dwordx2 v[194:195], v[150:151], off offset:1280
	global_load_dwordx2 v[196:197], v[150:151], off offset:1408
	s_and_b64 vcc, exec, s[38:39]
	s_cbranch_vccz .LBB0_960
.LBB0_960:
	v_lshl_or_b32 v160, s74, 7, v154
	v_ashrrev_i32_e32 v161, 31, v160
	v_or_b32_e32 v164, 16, v144
	v_ashrrev_i32_e32 v165, 31, v164
	v_lshl_add_u64 v[166:167], v[164:165], 3, s[0:1]
	v_mov_b64_e32 v[146:147], s[20:21]
	v_mad_i64_i32 v[162:163], s[54:55], v144, s67, v[146:147]
	s_andn2_b64 vcc, exec, s[10:11]
	s_mov_b64 s[10:11], -1
	s_waitcnt vmcnt(7)
	v_cvt_f32_u32_e32 v159, v183
	v_cvt_f32_u32_e32 v145, v182
	v_lshlrev_b64 v[148:149], 1, v[160:161]
	v_lshl_add_u64 v[162:163], v[162:163], 0, v[148:149]
	v_fmamk_f32 v145, v145, 0x2f800000, v159
	v_fmamk_f32 v145, v145, 0x3a800000, v158
	v_rsq_f32_e32 v160, v145
	s_nop 0
	v_mul_f32_e32 v182, 0xbfb8aa3b, v160
	v_mul_f32_e32 v183, v160, v160
	v_pk_mul_f32 v[160:161], v[124:125], v[182:183] op_sel_hi:[1,0]
	v_pk_mul_f32 v[168:169], v[126:127], v[182:183] op_sel_hi:[1,0]
	v_pk_mul_f32 v[170:171], v[120:121], v[182:183] op_sel_hi:[1,0]
	v_pk_mul_f32 v[172:173], v[122:123], v[182:183] op_sel_hi:[1,0]
	v_pk_mul_f32 v[116:117], v[116:117], v[124:125]
	v_pk_mul_f32 v[118:119], v[118:119], v[126:127]
	v_pk_mul_f32 v[120:121], v[112:113], v[120:121]
	v_pk_mul_f32 v[122:123], v[114:115], v[122:123]
	v_exp_f32_e32 v160, v160
	v_exp_f32_e32 v161, v161
	v_exp_f32_e32 v168, v168
	v_exp_f32_e32 v169, v169
	v_exp_f32_e32 v170, v170
	v_exp_f32_e32 v171, v171
	v_exp_f32_e32 v172, v172
	v_exp_f32_e32 v173, v173
	v_pk_mul_f32 v[116:117], v[116:117], v[182:183] op_sel:[0,1] op_sel_hi:[1,1]
	v_pk_mul_f32 v[118:119], v[118:119], v[182:183] op_sel:[0,1] op_sel_hi:[1,1]
	v_pk_mul_f32 v[120:121], v[120:121], v[182:183] op_sel:[0,1] op_sel_hi:[1,1]
	v_pk_mul_f32 v[122:123], v[122:123], v[182:183] op_sel:[0,1] op_sel_hi:[1,1]
	v_pk_add_f32 v[160:161], v[160:161], 1.0 op_sel_hi:[1,0]
	v_pk_add_f32 v[168:169], v[168:169], 1.0 op_sel_hi:[1,0]
	v_pk_add_f32 v[170:171], v[170:171], 1.0 op_sel_hi:[1,0]
	v_pk_add_f32 v[172:173], v[172:173], 1.0 op_sel_hi:[1,0]
	v_rcp_f32_e32 v160, v160
	v_rcp_f32_e32 v161, v161
	v_rcp_f32_e32 v168, v168
	v_rcp_f32_e32 v169, v169
	v_rcp_f32_e32 v170, v170
	v_rcp_f32_e32 v171, v171
	v_rcp_f32_e32 v172, v172
	v_rcp_f32_e32 v173, v173
	v_pk_mul_f32 v[116:117], v[116:117], v[160:161]
	v_pk_mul_f32 v[118:119], v[118:119], v[168:169]
	v_pk_mul_f32 v[120:121], v[120:121], v[170:171]
	v_pk_mul_f32 v[122:123], v[122:123], v[172:173]
	v_cvt_pk_bf16_f32 v112, v116, v117
	v_cvt_pk_bf16_f32 v113, v118, v119
	v_cvt_pk_bf16_f32 v114, v120, v121
	v_cvt_pk_bf16_f32 v115, v122, v123
	global_store_dwordx4 v[162:163], v[112:115], off
	s_nop 0
	s_nop 0
	v_or_b32_e32 v114, 32, v144
	s_waitcnt vmcnt(7)
; __device__ __forceinline__ unsigned cvtpk(float lo, float hi) { f32x2v_ v = {lo, hi}; bf16x2v_ b = __builtin_convertvector(v, bf16x2v_); return __builtin_bit_cast(unsigned, b); }
;     __device__ __forceinline__ void operator()(const f32x4 (&acc)[2][2][4][2], const Unit& u, int wr, int wc, int fr, int fq) const {
;     ...
;             for (int m = 0; m < 4; ++m) { const int row = row0 + ai * HALF + m * 16; const float rs = row_rs(ss, row);
;                 float hv[8];
; #pragma unroll
;                 for (int n = 0; n < 2; ++n)
; #pragma unroll
;                     for (int i = 0; i < 4; ++i) { const float g = acc[ai][0][m][n][i] * rs, uu = acc[ai][1][m][n][i] * rs;
;                         hv[n * 4 + i] = g * __builtin_amdgcn_rcpf(1.0f + __expf(-g)) * uu; }
;                 u32x4 w; w.x = cvtpk(hv[0], hv[1]); w.y = cvtpk(hv[2], hv[3]); w.z = cvtpk(hv[4], hv[5]); w.w = cvtpk(hv[6], hv[7]);
;                 *(u32x4*)(H + (size_t)row * ldh + col0) = w; }
	v_cvt_f32_u32_e32 v116, v185
	v_cvt_f32_u32_e32 v115, v184
	v_mad_i64_i32 v[112:113], s[54:55], v164, s67, v[146:147]
	v_fmamk_f32 v115, v115, 0x2f800000, v116
	v_fmamk_f32 v115, v115, 0x3a800000, v158
	v_rsq_f32_e32 v116, v115
	v_ashrrev_i32_e32 v115, 31, v114
	v_lshl_add_u64 v[118:119], v[114:115], 3, s[0:1]
	v_lshl_add_u64 v[112:113], v[112:113], 0, v[148:149]
	v_mul_f32_e32 v184, 0xbfb8aa3b, v116
	v_mul_f32_e32 v185, v116, v116
	v_pk_mul_f32 v[116:117], v[108:109], v[184:185] op_sel_hi:[1,0]
	v_pk_mul_f32 v[120:121], v[110:111], v[184:185] op_sel_hi:[1,0]
	v_pk_mul_f32 v[122:123], v[104:105], v[184:185] op_sel_hi:[1,0]
	v_pk_mul_f32 v[124:125], v[106:107], v[184:185] op_sel_hi:[1,0]
	v_pk_mul_f32 v[100:101], v[100:101], v[108:109]
	v_pk_mul_f32 v[102:103], v[102:103], v[110:111]
	v_pk_mul_f32 v[104:105], v[96:97], v[104:105]
	v_pk_mul_f32 v[106:107], v[98:99], v[106:107]
	v_exp_f32_e32 v116, v116
	v_exp_f32_e32 v117, v117
	v_exp_f32_e32 v120, v120
	v_exp_f32_e32 v121, v121
	v_exp_f32_e32 v122, v122
	v_exp_f32_e32 v123, v123
	v_exp_f32_e32 v124, v124
	v_exp_f32_e32 v125, v125
	v_pk_mul_f32 v[100:101], v[100:101], v[184:185] op_sel:[0,1] op_sel_hi:[1,1]
	v_pk_mul_f32 v[102:103], v[102:103], v[184:185] op_sel:[0,1] op_sel_hi:[1,1]
	v_pk_mul_f32 v[104:105], v[104:105], v[184:185] op_sel:[0,1] op_sel_hi:[1,1]
	v_pk_mul_f32 v[106:107], v[106:107], v[184:185] op_sel:[0,1] op_sel_hi:[1,1]
	v_pk_add_f32 v[116:117], v[116:117], 1.0 op_sel_hi:[1,0]
	v_pk_add_f32 v[120:121], v[120:121], 1.0 op_sel_hi:[1,0]
	v_pk_add_f32 v[122:123], v[122:123], 1.0 op_sel_hi:[1,0]
	v_pk_add_f32 v[124:125], v[124:125], 1.0 op_sel_hi:[1,0]
	v_rcp_f32_e32 v116, v116
	v_rcp_f32_e32 v117, v117
	v_rcp_f32_e32 v120, v120
	v_rcp_f32_e32 v121, v121
	v_rcp_f32_e32 v122, v122
	v_rcp_f32_e32 v123, v123
	v_rcp_f32_e32 v124, v124
	v_rcp_f32_e32 v125, v125
	v_pk_mul_f32 v[100:101], v[100:101], v[116:117]
	v_pk_mul_f32 v[102:103], v[102:103], v[120:121]
	v_pk_mul_f32 v[104:105], v[104:105], v[122:123]
	v_pk_mul_f32 v[106:107], v[106:107], v[124:125]
	v_cvt_pk_bf16_f32 v96, v100, v101
	v_cvt_pk_bf16_f32 v97, v102, v103
	v_cvt_pk_bf16_f32 v98, v104, v105
	v_cvt_pk_bf16_f32 v99, v106, v107
	global_store_dwordx4 v[112:113], v[96:99], off
	s_nop 0
	s_nop 0
	v_or_b32_e32 v98, 48, v144
	s_waitcnt vmcnt(7)
	v_cvt_f32_u32_e32 v100, v187
	v_cvt_f32_u32_e32 v99, v186
	v_mad_i64_i32 v[96:97], s[54:55], v114, s67, v[146:147]
	v_fmamk_f32 v99, v99, 0x2f800000, v100
	v_fmamk_f32 v99, v99, 0x3a800000, v158
	v_rsq_f32_e32 v100, v99
	v_ashrrev_i32_e32 v99, 31, v98
	v_lshl_add_u64 v[102:103], v[98:99], 3, s[0:1]
	v_lshl_add_u64 v[96:97], v[96:97], 0, v[148:149]
	v_mul_f32_e32 v186, 0xbfb8aa3b, v100
	v_mul_f32_e32 v187, v100, v100
	v_pk_mul_f32 v[100:101], v[92:93], v[186:187] op_sel_hi:[1,0]
	v_pk_mul_f32 v[104:105], v[94:95], v[186:187] op_sel_hi:[1,0]
	v_pk_mul_f32 v[106:107], v[88:89], v[186:187] op_sel_hi:[1,0]
	v_pk_mul_f32 v[108:109], v[90:91], v[186:187] op_sel_hi:[1,0]
	v_pk_mul_f32 v[84:85], v[84:85], v[92:93]
	v_pk_mul_f32 v[86:87], v[86:87], v[94:95]
	v_pk_mul_f32 v[88:89], v[80:81], v[88:89]
	v_pk_mul_f32 v[90:91], v[82:83], v[90:91]
	v_exp_f32_e32 v100, v100
	v_exp_f32_e32 v101, v101
	v_exp_f32_e32 v104, v104
	v_exp_f32_e32 v105, v105
	v_exp_f32_e32 v106, v106
	v_exp_f32_e32 v107, v107
	v_exp_f32_e32 v108, v108
	v_exp_f32_e32 v109, v109
	v_pk_mul_f32 v[84:85], v[84:85], v[186:187] op_sel:[0,1] op_sel_hi:[1,1]
	v_pk_mul_f32 v[86:87], v[86:87], v[186:187] op_sel:[0,1] op_sel_hi:[1,1]
	v_pk_mul_f32 v[88:89], v[88:89], v[186:187] op_sel:[0,1] op_sel_hi:[1,1]
	v_pk_mul_f32 v[90:91], v[90:91], v[186:187] op_sel:[0,1] op_sel_hi:[1,1]
	v_pk_add_f32 v[100:101], v[100:101], 1.0 op_sel_hi:[1,0]
	v_pk_add_f32 v[104:105], v[104:105], 1.0 op_sel_hi:[1,0]
	v_pk_add_f32 v[106:107], v[106:107], 1.0 op_sel_hi:[1,0]
	v_pk_add_f32 v[108:109], v[108:109], 1.0 op_sel_hi:[1,0]
	v_rcp_f32_e32 v100, v100
	v_rcp_f32_e32 v101, v101
	v_rcp_f32_e32 v104, v104
	v_rcp_f32_e32 v105, v105
	v_rcp_f32_e32 v106, v106
	v_rcp_f32_e32 v107, v107
	v_rcp_f32_e32 v108, v108
	v_rcp_f32_e32 v109, v109
	v_pk_mul_f32 v[84:85], v[84:85], v[100:101]
	v_pk_mul_f32 v[86:87], v[86:87], v[104:105]
	v_pk_mul_f32 v[88:89], v[88:89], v[106:107]
	v_pk_mul_f32 v[90:91], v[90:91], v[108:109]
	v_cvt_pk_bf16_f32 v80, v84, v85
	v_cvt_pk_bf16_f32 v81, v86, v87
	v_cvt_pk_bf16_f32 v82, v88, v89
	v_cvt_pk_bf16_f32 v83, v90, v91
	global_store_dwordx4 v[96:97], v[80:83], off
	s_nop 0
	s_waitcnt vmcnt(7)
	v_cvt_f32_u32_e32 v80, v189
	v_cvt_f32_u32_e32 v81, v188
	v_mad_i64_i32 v[82:83], s[54:55], v98, s67, v[146:147]
	v_fmamk_f32 v80, v81, 0x2f800000, v80
	v_fmamk_f32 v80, v80, 0x3a800000, v158
	v_rsq_f32_e32 v80, v80
	v_lshl_add_u64 v[82:83], v[82:83], 0, v[148:149]
	v_mul_f32_e32 v188, 0xbfb8aa3b, v80
	v_mul_f32_e32 v189, v80, v80
	v_pk_mul_f32 v[80:81], v[76:77], v[188:189] op_sel_hi:[1,0]
	v_pk_mul_f32 v[84:85], v[78:79], v[188:189] op_sel_hi:[1,0]
	v_pk_mul_f32 v[86:87], v[72:73], v[188:189] op_sel_hi:[1,0]
	v_pk_mul_f32 v[88:89], v[74:75], v[188:189] op_sel_hi:[1,0]
	v_pk_mul_f32 v[68:69], v[68:69], v[76:77]
	v_pk_mul_f32 v[70:71], v[70:71], v[78:79]
	v_pk_mul_f32 v[72:73], v[64:65], v[72:73]
	v_pk_mul_f32 v[74:75], v[66:67], v[74:75]
	v_exp_f32_e32 v80, v80
	v_exp_f32_e32 v81, v81
	v_exp_f32_e32 v84, v84
	v_exp_f32_e32 v85, v85
	v_exp_f32_e32 v86, v86
	v_exp_f32_e32 v87, v87
	v_exp_f32_e32 v88, v88
	v_exp_f32_e32 v89, v89
	v_pk_mul_f32 v[68:69], v[68:69], v[188:189] op_sel:[0,1] op_sel_hi:[1,1]
	v_pk_mul_f32 v[70:71], v[70:71], v[188:189] op_sel:[0,1] op_sel_hi:[1,1]
	v_pk_mul_f32 v[72:73], v[72:73], v[188:189] op_sel:[0,1] op_sel_hi:[1,1]
	v_pk_mul_f32 v[74:75], v[74:75], v[188:189] op_sel:[0,1] op_sel_hi:[1,1]
	v_pk_add_f32 v[80:81], v[80:81], 1.0 op_sel_hi:[1,0]
	v_pk_add_f32 v[84:85], v[84:85], 1.0 op_sel_hi:[1,0]
	v_pk_add_f32 v[86:87], v[86:87], 1.0 op_sel_hi:[1,0]
	v_pk_add_f32 v[88:89], v[88:89], 1.0 op_sel_hi:[1,0]
	v_rcp_f32_e32 v80, v80
	v_rcp_f32_e32 v81, v81
	v_rcp_f32_e32 v84, v84
	v_rcp_f32_e32 v85, v85
	v_rcp_f32_e32 v86, v86
	v_rcp_f32_e32 v87, v87
	v_rcp_f32_e32 v88, v88
	v_rcp_f32_e32 v89, v89
	v_pk_mul_f32 v[68:69], v[68:69], v[80:81]
	v_pk_mul_f32 v[70:71], v[70:71], v[84:85]
	v_pk_mul_f32 v[72:73], v[72:73], v[86:87]
	v_pk_mul_f32 v[74:75], v[74:75], v[88:89]
	v_cvt_pk_bf16_f32 v64, v68, v69
	v_cvt_pk_bf16_f32 v65, v70, v71
	v_cvt_pk_bf16_f32 v66, v72, v73
	v_cvt_pk_bf16_f32 v67, v74, v75
	global_store_dwordx4 v[82:83], v[64:67], off
	s_nop 0
	s_waitcnt vmcnt(7)
; __device__ __forceinline__ unsigned cvtpk(float lo, float hi) { f32x2v_ v = {lo, hi}; bf16x2v_ b = __builtin_convertvector(v, bf16x2v_); return __builtin_bit_cast(unsigned, b); }
;     __device__ __forceinline__ void operator()(const f32x4 (&acc)[2][2][4][2], const Unit& u, int wr, int wc, int fr, int fq) const {
;     ...
;             for (int m = 0; m < 4; ++m) { const int row = row0 + ai * HALF + m * 16; const float rs = row_rs(ss, row);
;                 float hv[8];
; #pragma unroll
;                 for (int n = 0; n < 2; ++n)
; #pragma unroll
;                     for (int i = 0; i < 4; ++i) { const float g = acc[ai][0][m][n][i] * rs, uu = acc[ai][1][m][n][i] * rs;
;                         hv[n * 4 + i] = g * __builtin_amdgcn_rcpf(1.0f + __expf(-g)) * uu; }
;                 u32x4 w; w.x = cvtpk(hv[0], hv[1]); w.y = cvtpk(hv[2], hv[3]); w.z = cvtpk(hv[4], hv[5]); w.w = cvtpk(hv[6], hv[7]);
;                 *(u32x4*)(H + (size_t)row * ldh + col0) = w; }
	v_cvt_f32_u32_e32 v64, v191
	v_cvt_f32_u32_e32 v66, v190
	v_add_u32_e32 v65, 0x80, v144
	v_fmamk_f32 v64, v66, 0x2f800000, v64
	v_fmamk_f32 v64, v64, 0x3a800000, v158
	v_rsq_f32_e32 v64, v64
	v_mad_i64_i32 v[66:67], s[54:55], v65, s67, v[146:147]
	v_lshl_add_u64 v[66:67], v[66:67], 0, v[148:149]
	v_mul_f32_e32 v190, 0xbfb8aa3b, v64
	v_mul_f32_e32 v191, v64, v64
	v_pk_mul_f32 v[64:65], v[60:61], v[190:191] op_sel_hi:[1,0]
	v_pk_mul_f32 v[68:69], v[62:63], v[190:191] op_sel_hi:[1,0]
	v_pk_mul_f32 v[70:71], v[56:57], v[190:191] op_sel_hi:[1,0]
	v_pk_mul_f32 v[72:73], v[58:59], v[190:191] op_sel_hi:[1,0]
	v_pk_mul_f32 v[52:53], v[52:53], v[60:61]
	v_pk_mul_f32 v[54:55], v[54:55], v[62:63]
	v_pk_mul_f32 v[56:57], v[48:49], v[56:57]
	v_pk_mul_f32 v[58:59], v[50:51], v[58:59]
	v_exp_f32_e32 v64, v64
	v_exp_f32_e32 v65, v65
	v_exp_f32_e32 v68, v68
	v_exp_f32_e32 v69, v69
	v_exp_f32_e32 v70, v70
	v_exp_f32_e32 v71, v71
	v_exp_f32_e32 v72, v72
	v_exp_f32_e32 v73, v73
	v_pk_mul_f32 v[52:53], v[52:53], v[190:191] op_sel:[0,1] op_sel_hi:[1,1]
	v_pk_mul_f32 v[54:55], v[54:55], v[190:191] op_sel:[0,1] op_sel_hi:[1,1]
	v_pk_mul_f32 v[56:57], v[56:57], v[190:191] op_sel:[0,1] op_sel_hi:[1,1]
	v_pk_mul_f32 v[58:59], v[58:59], v[190:191] op_sel:[0,1] op_sel_hi:[1,1]
	v_pk_add_f32 v[64:65], v[64:65], 1.0 op_sel_hi:[1,0]
	v_pk_add_f32 v[68:69], v[68:69], 1.0 op_sel_hi:[1,0]
	v_pk_add_f32 v[70:71], v[70:71], 1.0 op_sel_hi:[1,0]
	v_pk_add_f32 v[72:73], v[72:73], 1.0 op_sel_hi:[1,0]
	v_rcp_f32_e32 v64, v64
	v_rcp_f32_e32 v65, v65
	v_rcp_f32_e32 v68, v68
	v_rcp_f32_e32 v69, v69
	v_rcp_f32_e32 v70, v70
	v_rcp_f32_e32 v71, v71
	v_rcp_f32_e32 v72, v72
	v_rcp_f32_e32 v73, v73
	v_pk_mul_f32 v[52:53], v[52:53], v[64:65]
	v_pk_mul_f32 v[54:55], v[54:55], v[68:69]
	v_pk_mul_f32 v[56:57], v[56:57], v[70:71]
	v_pk_mul_f32 v[58:59], v[58:59], v[72:73]
	v_cvt_pk_bf16_f32 v48, v52, v53
	v_cvt_pk_bf16_f32 v49, v54, v55
	v_cvt_pk_bf16_f32 v50, v56, v57
	v_cvt_pk_bf16_f32 v51, v58, v59
	global_store_dwordx4 v[66:67], v[48:51], off
	s_nop 0
	s_waitcnt vmcnt(7)
	v_cvt_f32_u32_e32 v48, v193
	v_cvt_f32_u32_e32 v50, v192
	v_add_u32_e32 v49, 0x90, v144
	v_fmamk_f32 v48, v50, 0x2f800000, v48
	v_fmamk_f32 v48, v48, 0x3a800000, v158
	v_rsq_f32_e32 v48, v48
	v_mad_i64_i32 v[50:51], s[54:55], v49, s67, v[146:147]
	v_lshl_add_u64 v[50:51], v[50:51], 0, v[148:149]
	v_mul_f32_e32 v192, 0xbfb8aa3b, v48
	v_mul_f32_e32 v193, v48, v48
	v_pk_mul_f32 v[48:49], v[44:45], v[192:193] op_sel_hi:[1,0]
	v_pk_mul_f32 v[52:53], v[46:47], v[192:193] op_sel_hi:[1,0]
	v_pk_mul_f32 v[54:55], v[40:41], v[192:193] op_sel_hi:[1,0]
	v_pk_mul_f32 v[56:57], v[42:43], v[192:193] op_sel_hi:[1,0]
	v_pk_mul_f32 v[36:37], v[36:37], v[44:45]
	v_pk_mul_f32 v[38:39], v[38:39], v[46:47]
	v_pk_mul_f32 v[40:41], v[32:33], v[40:41]
	v_pk_mul_f32 v[42:43], v[34:35], v[42:43]
	v_exp_f32_e32 v48, v48
	v_exp_f32_e32 v49, v49
	v_exp_f32_e32 v52, v52
	v_exp_f32_e32 v53, v53
	v_exp_f32_e32 v54, v54
	v_exp_f32_e32 v55, v55
	v_exp_f32_e32 v56, v56
	v_exp_f32_e32 v57, v57
	v_pk_mul_f32 v[36:37], v[36:37], v[192:193] op_sel:[0,1] op_sel_hi:[1,1]
	v_pk_mul_f32 v[38:39], v[38:39], v[192:193] op_sel:[0,1] op_sel_hi:[1,1]
	v_pk_mul_f32 v[40:41], v[40:41], v[192:193] op_sel:[0,1] op_sel_hi:[1,1]
	v_pk_mul_f32 v[42:43], v[42:43], v[192:193] op_sel:[0,1] op_sel_hi:[1,1]
	v_pk_add_f32 v[48:49], v[48:49], 1.0 op_sel_hi:[1,0]
	v_pk_add_f32 v[52:53], v[52:53], 1.0 op_sel_hi:[1,0]
	v_pk_add_f32 v[54:55], v[54:55], 1.0 op_sel_hi:[1,0]
	v_pk_add_f32 v[56:57], v[56:57], 1.0 op_sel_hi:[1,0]
	v_rcp_f32_e32 v48, v48
	v_rcp_f32_e32 v49, v49
	v_rcp_f32_e32 v52, v52
	v_rcp_f32_e32 v53, v53
	v_rcp_f32_e32 v54, v54
	v_rcp_f32_e32 v55, v55
	v_rcp_f32_e32 v56, v56
	v_rcp_f32_e32 v57, v57
	v_pk_mul_f32 v[36:37], v[36:37], v[48:49]
	v_pk_mul_f32 v[38:39], v[38:39], v[52:53]
	v_pk_mul_f32 v[40:41], v[40:41], v[54:55]
	v_pk_mul_f32 v[42:43], v[42:43], v[56:57]
	v_cvt_pk_bf16_f32 v32, v36, v37
	v_cvt_pk_bf16_f32 v33, v38, v39
	v_cvt_pk_bf16_f32 v34, v40, v41
	v_cvt_pk_bf16_f32 v35, v42, v43
	global_store_dwordx4 v[50:51], v[32:35], off
	s_nop 0
	s_waitcnt vmcnt(7)
; __device__ __forceinline__ unsigned cvtpk(float lo, float hi) { f32x2v_ v = {lo, hi}; bf16x2v_ b = __builtin_convertvector(v, bf16x2v_); return __builtin_bit_cast(unsigned, b); }
; #define PG8_BAR __builtin_amdgcn_s_barrier()
;     __device__ __forceinline__ void operator()(const f32x4 (&acc)[2][2][4][2], const Unit& u, int wr, int wc, int fr, int fq) const {
;     ...
;             for (int m = 0; m < 4; ++m) { const int row = row0 + ai * HALF + m * 16; const float rs = row_rs(ss, row);
;                 float hv[8];
; #pragma unroll
;                 for (int n = 0; n < 2; ++n)
; #pragma unroll
;                     for (int i = 0; i < 4; ++i) { const float g = acc[ai][0][m][n][i] * rs, uu = acc[ai][1][m][n][i] * rs;
;                         hv[n * 4 + i] = g * __builtin_amdgcn_rcpf(1.0f + __expf(-g)) * uu; }
;                 u32x4 w; w.x = cvtpk(hv[0], hv[1]); w.y = cvtpk(hv[2], hv[3]); w.z = cvtpk(hv[4], hv[5]); w.w = cvtpk(hv[6], hv[7]);
;                 *(u32x4*)(H + (size_t)row * ldh + col0) = w; }
; template <class Epi, class Sched, bool ALIGN_EPI = false, bool SP2 = false>
; __device__ __forceinline__ void gemm_phase(PG8_LAS unsigned char* lds, const Gemm g, const Sched& S, const Epi& E) {
;     ...
;         if constexpr (ALIGN_EPI) { if (wr == 0) PG8_BAR; }
;         if constexpr (!Epi::AFTER_DRAIN) { E(acc, cur, wr, wc, fr, fq); S.done(cur); }
;         if (!has_next) break;
	v_cvt_f32_u32_e32 v32, v195
	v_cvt_f32_u32_e32 v34, v194
	v_add_u32_e32 v33, 0xa0, v144
	v_fmamk_f32 v32, v34, 0x2f800000, v32
	v_fmamk_f32 v32, v32, 0x3a800000, v158
	v_rsq_f32_e32 v32, v32
	v_mad_i64_i32 v[34:35], s[54:55], v33, s67, v[146:147]
	v_lshl_add_u64 v[34:35], v[34:35], 0, v[148:149]
	v_mul_f32_e32 v194, 0xbfb8aa3b, v32
	v_mul_f32_e32 v195, v32, v32
	v_pk_mul_f32 v[32:33], v[28:29], v[194:195] op_sel_hi:[1,0]
	v_pk_mul_f32 v[36:37], v[30:31], v[194:195] op_sel_hi:[1,0]
	v_pk_mul_f32 v[38:39], v[24:25], v[194:195] op_sel_hi:[1,0]
	v_pk_mul_f32 v[40:41], v[26:27], v[194:195] op_sel_hi:[1,0]
	v_pk_mul_f32 v[20:21], v[20:21], v[28:29]
	v_pk_mul_f32 v[22:23], v[22:23], v[30:31]
	v_pk_mul_f32 v[24:25], v[16:17], v[24:25]
	v_pk_mul_f32 v[26:27], v[18:19], v[26:27]
	v_exp_f32_e32 v32, v32
	v_exp_f32_e32 v33, v33
	v_exp_f32_e32 v36, v36
	v_exp_f32_e32 v37, v37
	v_exp_f32_e32 v38, v38
	v_exp_f32_e32 v39, v39
	v_exp_f32_e32 v40, v40
	v_exp_f32_e32 v41, v41
	v_pk_mul_f32 v[20:21], v[20:21], v[194:195] op_sel:[0,1] op_sel_hi:[1,1]
	v_pk_mul_f32 v[22:23], v[22:23], v[194:195] op_sel:[0,1] op_sel_hi:[1,1]
	v_pk_mul_f32 v[24:25], v[24:25], v[194:195] op_sel:[0,1] op_sel_hi:[1,1]
	v_pk_mul_f32 v[26:27], v[26:27], v[194:195] op_sel:[0,1] op_sel_hi:[1,1]
	v_pk_add_f32 v[32:33], v[32:33], 1.0 op_sel_hi:[1,0]
	v_pk_add_f32 v[36:37], v[36:37], 1.0 op_sel_hi:[1,0]
	v_pk_add_f32 v[38:39], v[38:39], 1.0 op_sel_hi:[1,0]
	v_pk_add_f32 v[40:41], v[40:41], 1.0 op_sel_hi:[1,0]
	v_rcp_f32_e32 v32, v32
	v_rcp_f32_e32 v33, v33
	v_rcp_f32_e32 v36, v36
	v_rcp_f32_e32 v37, v37
	v_rcp_f32_e32 v38, v38
	v_rcp_f32_e32 v39, v39
	v_rcp_f32_e32 v40, v40
	v_rcp_f32_e32 v41, v41
	v_pk_mul_f32 v[20:21], v[20:21], v[32:33]
	v_pk_mul_f32 v[22:23], v[22:23], v[36:37]
	v_pk_mul_f32 v[24:25], v[24:25], v[38:39]
	v_pk_mul_f32 v[26:27], v[26:27], v[40:41]
	v_cvt_pk_bf16_f32 v16, v20, v21
	v_cvt_pk_bf16_f32 v17, v22, v23
	v_cvt_pk_bf16_f32 v18, v24, v25
	v_cvt_pk_bf16_f32 v19, v26, v27
	global_store_dwordx4 v[34:35], v[16:19], off
	s_nop 0
	s_waitcnt vmcnt(7)
	v_cvt_f32_u32_e32 v16, v197
	v_cvt_f32_u32_e32 v18, v196
	v_add_u32_e32 v17, 0xb0, v144
	v_fmamk_f32 v16, v18, 0x2f800000, v16
	v_fmamk_f32 v16, v16, 0x3a800000, v158
	v_rsq_f32_e32 v16, v16
	v_mad_i64_i32 v[18:19], s[54:55], v17, s67, v[146:147]
	v_lshl_add_u64 v[18:19], v[18:19], 0, v[148:149]
	v_mul_f32_e32 v196, 0xbfb8aa3b, v16
	v_mul_f32_e32 v197, v16, v16
	v_pk_mul_f32 v[16:17], v[12:13], v[196:197] op_sel_hi:[1,0]
	v_pk_mul_f32 v[20:21], v[14:15], v[196:197] op_sel_hi:[1,0]
	v_pk_mul_f32 v[22:23], v[8:9], v[196:197] op_sel_hi:[1,0]
	v_pk_mul_f32 v[24:25], v[10:11], v[196:197] op_sel_hi:[1,0]
	v_pk_mul_f32 v[4:5], v[4:5], v[12:13]
	v_pk_mul_f32 v[6:7], v[6:7], v[14:15]
	v_pk_mul_f32 v[8:9], v[0:1], v[8:9]
	v_pk_mul_f32 v[10:11], v[2:3], v[10:11]
	v_exp_f32_e32 v16, v16
	v_exp_f32_e32 v17, v17
	v_exp_f32_e32 v20, v20
	v_exp_f32_e32 v21, v21
	v_exp_f32_e32 v22, v22
	v_exp_f32_e32 v23, v23
	v_exp_f32_e32 v24, v24
	v_exp_f32_e32 v25, v25
	v_pk_mul_f32 v[4:5], v[4:5], v[196:197] op_sel:[0,1] op_sel_hi:[1,1]
	v_pk_mul_f32 v[6:7], v[6:7], v[196:197] op_sel:[0,1] op_sel_hi:[1,1]
	v_pk_mul_f32 v[8:9], v[8:9], v[196:197] op_sel:[0,1] op_sel_hi:[1,1]
	v_pk_mul_f32 v[10:11], v[10:11], v[196:197] op_sel:[0,1] op_sel_hi:[1,1]
	v_pk_add_f32 v[16:17], v[16:17], 1.0 op_sel_hi:[1,0]
	v_pk_add_f32 v[20:21], v[20:21], 1.0 op_sel_hi:[1,0]
	v_pk_add_f32 v[22:23], v[22:23], 1.0 op_sel_hi:[1,0]
	v_pk_add_f32 v[24:25], v[24:25], 1.0 op_sel_hi:[1,0]
	v_rcp_f32_e32 v16, v16
	v_rcp_f32_e32 v17, v17
	v_rcp_f32_e32 v20, v20
	v_rcp_f32_e32 v21, v21
	v_rcp_f32_e32 v22, v22
	v_rcp_f32_e32 v23, v23
	v_rcp_f32_e32 v24, v24
	v_rcp_f32_e32 v25, v25
	v_pk_mul_f32 v[4:5], v[4:5], v[16:17]
	v_pk_mul_f32 v[6:7], v[6:7], v[20:21]
	v_pk_mul_f32 v[8:9], v[8:9], v[22:23]
	v_pk_mul_f32 v[10:11], v[10:11], v[24:25]
	v_cvt_pk_bf16_f32 v0, v4, v5
	v_cvt_pk_bf16_f32 v1, v6, v7
	v_cvt_pk_bf16_f32 v2, v8, v9
	v_cvt_pk_bf16_f32 v3, v10, v11
	global_store_dwordx4 v[18:19], v[0:3], off
	s_cmp_eq_u64 s[38:39], 0
	s_cbranch_scc1 .Lxpost_5
	s_barrier
.Lxpost_5:
	s_cbranch_vccnz .LBB0_953
	s_andn2_b64 vcc, exec, s[12:13]
	s_cbranch_vccnz .LBB0_952
	s_barrier
	s_branch .LBB0_952

; #define PG8_STAGE(bufoff, gbase, voff) do { _Pragma("unroll") for (int _i = 0; _i < 2; ++_i) \
;         __builtin_amdgcn_global_load_lds((const unsigned*)((const char*)(gbase) + (voff)[_i]), (PG8_LAS unsigned*)(lds + (bufoff) + ldsw + _i * 8192), 16, 0, 0); } while (0)
; #define PG8_LDA(dst, b, h) do { _Pragma("unroll") for (int m = 0; m < 4; ++m) _Pragma("unroll") for (int k = 0; k < 2; ++k) dst[m][k] = *(const PG8_LAS bf16x8*)(lds + PG8_SA(b, h) + aoff + m * 2048 + k * 1024); } while (0)
; #define PG8_LDB(dst, b, h) do { _Pragma("unroll") for (int n = 0; n < 2; ++n) _Pragma("unroll") for (int k = 0; k < 2; ++k) dst[n][k] = *(const PG8_LAS bf16x8*)(lds + PG8_SB(b, h) + boff + n * 2048 + k * 1024); } while (0)
; #define PG8_MMA(ai, bj, At, Bt) do { __builtin_amdgcn_s_setprio(1); _Pragma("unroll") for (int m = 0; m < 4; ++m) _Pragma("unroll") for (int n = 0; n < 2; ++n) _Pragma("unroll") for (int k = 0; k < 2; ++k) \
;         acc[ai][bj][m][n] = __builtin_amdgcn_mfma_f32_16x16x32_bf16(Bt[n][k], At[m][k], acc[ai][bj][m][n], 0, 0, 0); __builtin_amdgcn_s_setprio(0); } while (0)
; #define PG8_WAIT_V(n) asm volatile("s_waitcnt vmcnt(" #n ")" ::: "memory")
; #define PG8_WAIT_L(n) asm volatile("s_waitcnt lgkmcnt(" #n ")" ::: "memory")
; #define PG8_BAR __builtin_amdgcn_s_barrier()
; #define PG8_SCHED __builtin_amdgcn_sched_barrier(0)
; template <class Epi, class Sched, bool ALIGN_EPI = false, bool SP2 = false>
; __device__ __forceinline__ void gemm_phase(PG8_LAS unsigned char* lds, const Gemm g, const Sched& S, const Epi& E) {
;     ...
;             PG8_LDB(B0, 0, 0); PG8_LDB(B1, 0, 1); PG8_SCHED; PG8_LDA(At, 0, 0); PG8_STAGE(PG8_SA(1, 1), a1 + hstep, voffA);
;             PG8_WAIT_V(8); PG8_WAIT_L(0); PG8_BAR; PG8_MMA(0, 0, At, B0); PG8_MMA(0, 1, At, B1); PG8_BAR; PG8_SCHED;
;             PG8_LDA(At, 0, 1); PG8_STAGE(PG8_SB(0, 0), b2, voffB); PG8_STAGE(PG8_SB(0, 1), b2 + hstep, voffB); PG8_STAGE(PG8_SA(0, 0), a2, voffA);
;             PG8_WAIT_V(8); PG8_WAIT_L(0); PG8_BAR; PG8_MMA(1, 0, At, B0); PG8_MMA(1, 1, At, B1); PG8_BAR; PG8_SCHED;
.LBB0_1034:
	s_add_u32 s75, s52, 0x100
	s_addc_u32 s76, s53, 0
	s_mov_b32 s77, -2
	s_waitcnt lgkmcnt(0)
	ds_read_b128 v[144:147], v151
	ds_read_b128 v[156:159], v151 offset:1024
	ds_read_b128 v[160:163], v151 offset:2048
	ds_read_b128 v[164:167], v151 offset:3072
	ds_read_b128 v[168:171], v152
	ds_read_b128 v[172:175], v152 offset:1024
	ds_read_b128 v[176:179], v152 offset:2048
	ds_read_b128 v[182:185], v152 offset:3072
	s_add_u32 s52, s50, 0x100
	s_addc_u32 s53, s51, 0
	s_cmp_eq_u32 s77, 40
	s_cselect_b32 s57, s1, s53
	s_cselect_b32 s56, s0, s52
	s_cselect_b32 s55, s49, s76
	s_cselect_b32 s54, s48, s75
	v_lshl_add_u64 v[202:203], s[50:51], 0, v[136:137]
	s_add_i32 m0, s14, 0xc000
	ds_read_b128 v[186:189], v153
	ds_read_b128 v[190:193], v153 offset:1024
	ds_read_b128 v[194:197], v153 offset:2048
	ds_read_b128 v[198:201], v153 offset:3072
	ds_read_b128 v[208:211], v153 offset:4096
	ds_read_b128 v[212:215], v153 offset:5120
	ds_read_b128 v[216:219], v153 offset:6144
	ds_read_b128 v[220:223], v153 offset:7168
	global_load_lds_dwordx4 v[202:203], off
	v_lshl_add_u64 v[202:203], s[50:51], 0, v[138:139]
	s_add_i32 m0, s14, 0xe000
	s_nop 0
	global_load_lds_dwordx4 v[202:203], off
	s_waitcnt vmcnt(8)
	s_waitcnt lgkmcnt(0)
	s_barrier
	s_setprio 1
	s_waitcnt lgkmcnt(0)
	v_mfma_f32_16x16x32_bf16 v[124:127], v[144:147], v[186:189], 0
	v_mfma_f32_16x16x32_bf16 v[120:123], v[160:163], v[186:189], 0
	v_mfma_f32_16x16x32_bf16 v[108:111], v[144:147], v[194:197], 0
	v_mfma_f32_16x16x32_bf16 v[104:107], v[160:163], v[194:197], 0
	v_mfma_f32_16x16x32_bf16 v[92:95], v[144:147], v[208:211], 0
	v_mfma_f32_16x16x32_bf16 v[88:91], v[160:163], v[208:211], 0
	v_mfma_f32_16x16x32_bf16 v[76:79], v[144:147], v[216:219], 0
	v_mfma_f32_16x16x32_bf16 v[72:75], v[160:163], v[216:219], 0
	v_mfma_f32_16x16x32_bf16 v[124:127], v[156:159], v[190:193], v[124:127]
	v_mfma_f32_16x16x32_bf16 v[120:123], v[164:167], v[190:193], v[120:123]
	v_mfma_f32_16x16x32_bf16 v[108:111], v[156:159], v[198:201], v[108:111]
	v_mfma_f32_16x16x32_bf16 v[104:107], v[164:167], v[198:201], v[104:107]
	v_mfma_f32_16x16x32_bf16 v[92:95], v[156:159], v[212:215], v[92:95]
	v_mfma_f32_16x16x32_bf16 v[88:91], v[164:167], v[212:215], v[88:91]
	v_mfma_f32_16x16x32_bf16 v[76:79], v[156:159], v[220:223], v[76:79]
	v_mfma_f32_16x16x32_bf16 v[72:75], v[164:167], v[220:223], v[72:75]
	s_setprio 0
	s_setprio 1
	v_mfma_f32_16x16x32_bf16 v[116:119], v[168:171], v[186:189], 0
	v_mfma_f32_16x16x32_bf16 v[112:115], v[176:179], v[186:189], 0
	v_mfma_f32_16x16x32_bf16 v[100:103], v[168:171], v[194:197], 0
	v_mfma_f32_16x16x32_bf16 v[96:99], v[176:179], v[194:197], 0
	v_mfma_f32_16x16x32_bf16 v[84:87], v[168:171], v[208:211], 0
	v_mfma_f32_16x16x32_bf16 v[80:83], v[176:179], v[208:211], 0
	v_mfma_f32_16x16x32_bf16 v[68:71], v[168:171], v[216:219], 0
	v_mfma_f32_16x16x32_bf16 v[64:67], v[176:179], v[216:219], 0
	v_mfma_f32_16x16x32_bf16 v[116:119], v[172:175], v[190:193], v[116:119]
	v_mfma_f32_16x16x32_bf16 v[112:115], v[182:185], v[190:193], v[112:115]
	v_mfma_f32_16x16x32_bf16 v[100:103], v[172:175], v[198:201], v[100:103]
	v_mfma_f32_16x16x32_bf16 v[96:99], v[182:185], v[198:201], v[96:99]
	v_mfma_f32_16x16x32_bf16 v[84:87], v[172:175], v[212:215], v[84:87]
	v_mfma_f32_16x16x32_bf16 v[80:83], v[182:185], v[212:215], v[80:83]
	v_mfma_f32_16x16x32_bf16 v[68:71], v[172:175], v[220:223], v[68:71]
	v_mfma_f32_16x16x32_bf16 v[64:67], v[182:185], v[220:223], v[64:67]
	s_setprio 0
	s_barrier
	s_add_i32 s50, s61, s3
	v_lshl_add_u64 v[202:203], s[54:55], 0, v[130:131]
	s_mov_b32 m0, s50
	ds_read_b128 v[186:189], v153 offset:16384
	ds_read_b128 v[190:193], v153 offset:17408
	ds_read_b128 v[194:197], v153 offset:18432
	ds_read_b128 v[198:201], v153 offset:19456
	ds_read_b128 v[208:211], v153 offset:20480
	ds_read_b128 v[212:215], v153 offset:21504
	ds_read_b128 v[216:219], v153 offset:22528
	ds_read_b128 v[220:223], v153 offset:23552
	global_load_lds_dwordx4 v[202:203], off
	s_add_i32 m0, s50, 0x2000
	s_add_u32 s50, s54, 0xb0000
	v_lshl_add_u64 v[224:225], s[54:55], 0, v[134:135]
	s_addc_u32 s51, s55, 0
	s_add_i32 s78, s62, s3
	global_load_lds_dwordx4 v[224:225], off
	v_lshl_add_u64 v[226:227], s[50:51], 0, v[130:131]
	s_mov_b32 m0, s78
	global_load_lds_dwordx4 v[226:227], off
	v_lshl_add_u64 v[226:227], s[50:51], 0, v[134:135]
	s_add_i32 m0, s78, 0x2000
	s_nop 0
	global_load_lds_dwordx4 v[226:227], off
	s_waitcnt vmcnt(6)
	s_waitcnt lgkmcnt(0)
	s_barrier
; #define PG8_STAGE(bufoff, gbase, voff) do { _Pragma("unroll") for (int _i = 0; _i < 2; ++_i) \
;         __builtin_amdgcn_global_load_lds((const unsigned*)((const char*)(gbase) + (voff)[_i]), (PG8_LAS unsigned*)(lds + (bufoff) + ldsw + _i * 8192), 16, 0, 0); } while (0)
; #define PG8_LDA(dst, b, h) do { _Pragma("unroll") for (int m = 0; m < 4; ++m) _Pragma("unroll") for (int k = 0; k < 2; ++k) dst[m][k] = *(const PG8_LAS bf16x8*)(lds + PG8_SA(b, h) + aoff + m * 2048 + k * 1024); } while (0)
; #define PG8_LDB(dst, b, h) do { _Pragma("unroll") for (int n = 0; n < 2; ++n) _Pragma("unroll") for (int k = 0; k < 2; ++k) dst[n][k] = *(const PG8_LAS bf16x8*)(lds + PG8_SB(b, h) + boff + n * 2048 + k * 1024); } while (0)
; #define PG8_MMA(ai, bj, At, Bt) do { __builtin_amdgcn_s_setprio(1); _Pragma("unroll") for (int m = 0; m < 4; ++m) _Pragma("unroll") for (int n = 0; n < 2; ++n) _Pragma("unroll") for (int k = 0; k < 2; ++k) \
;         acc[ai][bj][m][n] = __builtin_amdgcn_mfma_f32_16x16x32_bf16(Bt[n][k], At[m][k], acc[ai][bj][m][n], 0, 0, 0); __builtin_amdgcn_s_setprio(0); } while (0)
; #define PG8_WAIT_V(n) asm volatile("s_waitcnt vmcnt(" #n ")" ::: "memory")
; #define PG8_WAIT_L(n) asm volatile("s_waitcnt lgkmcnt(" #n ")" ::: "memory")
; #define PG8_BAR __builtin_amdgcn_s_barrier()
; #define PG8_SCHED __builtin_amdgcn_sched_barrier(0)
; template <class Epi, class Sched, bool ALIGN_EPI = false, bool SP2 = false>
; __device__ __forceinline__ void gemm_phase(PG8_LAS unsigned char* lds, const Gemm g, const Sched& S, const Epi& E) {
;     ...
;             PG8_WAIT_V(8); PG8_WAIT_L(0); PG8_BAR; PG8_MMA(1, 0, At, B0); PG8_MMA(1, 1, At, B1); PG8_BAR; PG8_SCHED;
;             PG8_LDB(B0, 1, 0); PG8_LDB(B1, 1, 1); PG8_SCHED; PG8_LDA(At, 1, 0); PG8_STAGE(PG8_SA(0, 1), a2 + hstep, voffA);
;             PG8_WAIT_V(8); PG8_WAIT_L(0); PG8_BAR; PG8_MMA(0, 0, At, B0); PG8_MMA(0, 1, At, B1); PG8_BAR; PG8_SCHED;
	s_setprio 1
	s_waitcnt lgkmcnt(0)
	v_mfma_f32_16x16x32_bf16 v[60:63], v[144:147], v[186:189], 0
	v_mfma_f32_16x16x32_bf16 v[56:59], v[160:163], v[186:189], 0
	v_mfma_f32_16x16x32_bf16 v[44:47], v[144:147], v[194:197], 0
	v_mfma_f32_16x16x32_bf16 v[40:43], v[160:163], v[194:197], 0
	v_mfma_f32_16x16x32_bf16 v[28:31], v[144:147], v[208:211], 0
	v_mfma_f32_16x16x32_bf16 v[24:27], v[160:163], v[208:211], 0
	v_mfma_f32_16x16x32_bf16 v[12:15], v[144:147], v[216:219], 0
	v_mfma_f32_16x16x32_bf16 v[8:11], v[160:163], v[216:219], 0
	v_mfma_f32_16x16x32_bf16 v[60:63], v[156:159], v[190:193], v[60:63]
	v_mfma_f32_16x16x32_bf16 v[56:59], v[164:167], v[190:193], v[56:59]
	v_mfma_f32_16x16x32_bf16 v[44:47], v[156:159], v[198:201], v[44:47]
	v_mfma_f32_16x16x32_bf16 v[40:43], v[164:167], v[198:201], v[40:43]
	v_mfma_f32_16x16x32_bf16 v[28:31], v[156:159], v[212:215], v[28:31]
	v_mfma_f32_16x16x32_bf16 v[24:27], v[164:167], v[212:215], v[24:27]
	v_lshl_add_u64 v[226:227], s[56:57], 0, v[128:129]
	s_mov_b32 m0, s14
	s_nop 0
	global_load_lds_dwordx4 v[226:227], off
	v_mfma_f32_16x16x32_bf16 v[12:15], v[156:159], v[220:223], v[12:15]
	v_mfma_f32_16x16x32_bf16 v[8:11], v[164:167], v[220:223], v[8:11]
	s_setprio 0
	s_setprio 1
	v_mfma_f32_16x16x32_bf16 v[52:55], v[168:171], v[186:189], 0
	v_mfma_f32_16x16x32_bf16 v[48:51], v[176:179], v[186:189], 0
	v_mfma_f32_16x16x32_bf16 v[36:39], v[168:171], v[194:197], 0
	v_mfma_f32_16x16x32_bf16 v[32:35], v[176:179], v[194:197], 0
	v_mfma_f32_16x16x32_bf16 v[20:23], v[168:171], v[208:211], 0
	v_mfma_f32_16x16x32_bf16 v[16:19], v[176:179], v[208:211], 0
	v_mfma_f32_16x16x32_bf16 v[4:7], v[168:171], v[216:219], 0
	v_mfma_f32_16x16x32_bf16 v[0:3], v[176:179], v[216:219], 0
	v_mfma_f32_16x16x32_bf16 v[52:55], v[172:175], v[190:193], v[52:55]
	v_mfma_f32_16x16x32_bf16 v[48:51], v[182:185], v[190:193], v[48:51]
	v_mfma_f32_16x16x32_bf16 v[36:39], v[172:175], v[198:201], v[36:39]
	v_mfma_f32_16x16x32_bf16 v[32:35], v[182:185], v[198:201], v[32:35]
	v_mfma_f32_16x16x32_bf16 v[20:23], v[172:175], v[212:215], v[20:23]
	v_mfma_f32_16x16x32_bf16 v[16:19], v[182:185], v[212:215], v[16:19]
	v_lshl_add_u64 v[228:229], s[56:57], 0, v[132:133]
	s_mov_b32 m0, s15
	s_nop 0
	global_load_lds_dwordx4 v[228:229], off
	v_mfma_f32_16x16x32_bf16 v[4:7], v[172:175], v[220:223], v[4:7]
	v_mfma_f32_16x16x32_bf16 v[0:3], v[182:185], v[220:223], v[0:3]
	s_setprio 0
	s_barrier
	s_add_i32 s78, 0, 0x18000
	v_add_u32_e32 v155, s78, v149
	s_add_i32 s79, 0, 0x1c000
	ds_read_b128 v[144:147], v155
	ds_read_b128 v[156:159], v155 offset:1024
	ds_read_b128 v[160:163], v155 offset:2048
	ds_read_b128 v[164:167], v155 offset:3072
	v_add_u32_e32 v155, s79, v149
	ds_read_b128 v[168:171], v155
	ds_read_b128 v[172:175], v155 offset:1024
	ds_read_b128 v[176:179], v155 offset:2048
	ds_read_b128 v[182:185], v155 offset:3072
	s_add_u32 s50, s56, 0xb0000
	s_addc_u32 s51, s57, 0
	s_mov_b32 m0, s33
	v_lshl_add_u64 v[230:231], s[50:51], 0, v[128:129]
	ds_read_b128 v[186:189], v153 offset:32768
	ds_read_b128 v[190:193], v153 offset:33792
	ds_read_b128 v[194:197], v153 offset:34816
	ds_read_b128 v[198:201], v153 offset:35840
	ds_read_b128 v[208:211], v153 offset:36864
	ds_read_b128 v[212:215], v153 offset:37888
	ds_read_b128 v[216:219], v153 offset:38912
	ds_read_b128 v[220:223], v153 offset:39936
	global_load_lds_dwordx4 v[230:231], off
	v_lshl_add_u64 v[230:231], s[50:51], 0, v[132:133]
	s_mov_b32 m0, s34
	s_nop 0
	global_load_lds_dwordx4 v[230:231], off
	s_waitcnt vmcnt(8)
	s_waitcnt lgkmcnt(0)
	s_barrier
	s_setprio 1
	s_waitcnt lgkmcnt(0)
	v_mfma_f32_16x16x32_bf16 v[124:127], v[144:147], v[186:189], v[124:127]
	v_mfma_f32_16x16x32_bf16 v[120:123], v[160:163], v[186:189], v[120:123]
	v_mfma_f32_16x16x32_bf16 v[108:111], v[144:147], v[194:197], v[108:111]
	v_mfma_f32_16x16x32_bf16 v[104:107], v[160:163], v[194:197], v[104:107]
	v_mfma_f32_16x16x32_bf16 v[92:95], v[144:147], v[208:211], v[92:95]
	v_mfma_f32_16x16x32_bf16 v[88:91], v[160:163], v[208:211], v[88:91]
	v_mfma_f32_16x16x32_bf16 v[76:79], v[144:147], v[216:219], v[76:79]
	v_mfma_f32_16x16x32_bf16 v[72:75], v[160:163], v[216:219], v[72:75]
	v_mfma_f32_16x16x32_bf16 v[124:127], v[156:159], v[190:193], v[124:127]
	v_mfma_f32_16x16x32_bf16 v[120:123], v[164:167], v[190:193], v[120:123]
	v_mfma_f32_16x16x32_bf16 v[108:111], v[156:159], v[198:201], v[108:111]
	v_mfma_f32_16x16x32_bf16 v[104:107], v[164:167], v[198:201], v[104:107]
	v_mfma_f32_16x16x32_bf16 v[92:95], v[156:159], v[212:215], v[92:95]
	v_mfma_f32_16x16x32_bf16 v[88:91], v[164:167], v[212:215], v[88:91]
	v_mfma_f32_16x16x32_bf16 v[76:79], v[156:159], v[220:223], v[76:79]
	v_mfma_f32_16x16x32_bf16 v[72:75], v[164:167], v[220:223], v[72:75]
	s_setprio 0
	s_setprio 1
	v_mfma_f32_16x16x32_bf16 v[116:119], v[168:171], v[186:189], v[116:119]
	v_mfma_f32_16x16x32_bf16 v[112:115], v[176:179], v[186:189], v[112:115]
	v_mfma_f32_16x16x32_bf16 v[100:103], v[168:171], v[194:197], v[100:103]
	v_mfma_f32_16x16x32_bf16 v[96:99], v[176:179], v[194:197], v[96:99]
	v_mfma_f32_16x16x32_bf16 v[84:87], v[168:171], v[208:211], v[84:87]
	v_mfma_f32_16x16x32_bf16 v[80:83], v[176:179], v[208:211], v[80:83]
	v_mfma_f32_16x16x32_bf16 v[68:71], v[168:171], v[216:219], v[68:71]
	v_mfma_f32_16x16x32_bf16 v[64:67], v[176:179], v[216:219], v[64:67]
	v_mfma_f32_16x16x32_bf16 v[116:119], v[172:175], v[190:193], v[116:119]
	v_mfma_f32_16x16x32_bf16 v[112:115], v[182:185], v[190:193], v[112:115]
	v_mfma_f32_16x16x32_bf16 v[100:103], v[172:175], v[198:201], v[100:103]
	v_mfma_f32_16x16x32_bf16 v[96:99], v[182:185], v[198:201], v[96:99]
	v_mfma_f32_16x16x32_bf16 v[84:87], v[172:175], v[212:215], v[84:87]
	v_mfma_f32_16x16x32_bf16 v[80:83], v[182:185], v[212:215], v[80:83]
	v_mfma_f32_16x16x32_bf16 v[68:71], v[172:175], v[220:223], v[68:71]
	v_mfma_f32_16x16x32_bf16 v[64:67], v[182:185], v[220:223], v[64:67]
	s_setprio 0
	s_barrier
; #define PG8_STAGE(bufoff, gbase, voff) do { _Pragma("unroll") for (int _i = 0; _i < 2; ++_i) \
;         __builtin_amdgcn_global_load_lds((const unsigned*)((const char*)(gbase) + (voff)[_i]), (PG8_LAS unsigned*)(lds + (bufoff) + ldsw + _i * 8192), 16, 0, 0); } while (0)
; #define PG8_LDA(dst, b, h) do { _Pragma("unroll") for (int m = 0; m < 4; ++m) _Pragma("unroll") for (int k = 0; k < 2; ++k) dst[m][k] = *(const PG8_LAS bf16x8*)(lds + PG8_SA(b, h) + aoff + m * 2048 + k * 1024); } while (0)
; #define PG8_LDB(dst, b, h) do { _Pragma("unroll") for (int n = 0; n < 2; ++n) _Pragma("unroll") for (int k = 0; k < 2; ++k) dst[n][k] = *(const PG8_LAS bf16x8*)(lds + PG8_SB(b, h) + boff + n * 2048 + k * 1024); } while (0)
; #define PG8_MMA(ai, bj, At, Bt) do { __builtin_amdgcn_s_setprio(1); _Pragma("unroll") for (int m = 0; m < 4; ++m) _Pragma("unroll") for (int n = 0; n < 2; ++n) _Pragma("unroll") for (int k = 0; k < 2; ++k) \
;         acc[ai][bj][m][n] = __builtin_amdgcn_mfma_f32_16x16x32_bf16(Bt[n][k], At[m][k], acc[ai][bj][m][n], 0, 0, 0); __builtin_amdgcn_s_setprio(0); } while (0)
; #define PG8_WAIT_V(n) asm volatile("s_waitcnt vmcnt(" #n ")" ::: "memory")
; #define PG8_WAIT_L(n) asm volatile("s_waitcnt lgkmcnt(" #n ")" ::: "memory")
; #define PG8_BAR __builtin_amdgcn_s_barrier()
; #define PG8_SCHED __builtin_amdgcn_sched_barrier(0)
; template <class Epi, class Sched, bool ALIGN_EPI = false, bool SP2 = false>
; __device__ __forceinline__ void gemm_phase(PG8_LAS unsigned char* lds, const Gemm g, const Sched& S, const Epi& E) {
;     ...
;             PG8_LDB(B0, 0, 0); PG8_LDB(B1, 0, 1); PG8_SCHED; PG8_LDA(At, 0, 0); PG8_STAGE(PG8_SA(1, 1), a1 + hstep, voffA);
;             PG8_WAIT_V(8); PG8_WAIT_L(0); PG8_BAR; PG8_MMA(0, 0, At, B0); PG8_MMA(0, 1, At, B1); PG8_BAR; PG8_SCHED;
;     ...
;             PG8_LDA(At, 1, 1); PG8_STAGE(PG8_SB(1, 0), b3, voffB); PG8_STAGE(PG8_SB(1, 1), b3 + hstep, voffB); PG8_STAGE(PG8_SA(1, 0), a3, voffA);
;             PG8_WAIT_V(8); PG8_WAIT_L(0); PG8_BAR; PG8_MMA(1, 0, At, B0); PG8_MMA(1, 1, At, B1); PG8_BAR; PG8_SCHED;
	s_add_i32 s50, s78, s3
	v_lshl_add_u64 v[202:203], v[202:203], 0, s[42:43]
	s_mov_b32 m0, s50
	ds_read_b128 v[186:189], v153 offset:49152
	ds_read_b128 v[190:193], v153 offset:50176
	ds_read_b128 v[194:197], v153 offset:51200
	ds_read_b128 v[198:201], v153 offset:52224
	ds_read_b128 v[208:211], v153 offset:53248
	ds_read_b128 v[212:215], v153 offset:54272
	ds_read_b128 v[216:219], v153 offset:55296
	ds_read_b128 v[220:223], v153 offset:56320
	global_load_lds_dwordx4 v[202:203], off
	s_add_i32 m0, s50, 0x2000
	s_add_u32 s50, s54, 0xb0080
	v_lshl_add_u64 v[202:203], v[224:225], 0, s[42:43]
	s_addc_u32 s51, s55, 0
	s_add_i32 s54, s79, s3
	global_load_lds_dwordx4 v[202:203], off
	v_lshl_add_u64 v[202:203], s[50:51], 0, v[130:131]
	s_mov_b32 m0, s54
	s_nop 0
	global_load_lds_dwordx4 v[202:203], off
	v_lshl_add_u64 v[202:203], s[50:51], 0, v[134:135]
	s_add_i32 m0, s54, 0x2000
	s_nop 0
	global_load_lds_dwordx4 v[202:203], off
	s_waitcnt vmcnt(6)
	s_waitcnt lgkmcnt(0)
	s_barrier
	s_setprio 1
	s_waitcnt lgkmcnt(0)
	v_mfma_f32_16x16x32_bf16 v[60:63], v[144:147], v[186:189], v[60:63]
	v_mfma_f32_16x16x32_bf16 v[56:59], v[160:163], v[186:189], v[56:59]
	v_mfma_f32_16x16x32_bf16 v[44:47], v[144:147], v[194:197], v[44:47]
	v_mfma_f32_16x16x32_bf16 v[40:43], v[160:163], v[194:197], v[40:43]
	v_mfma_f32_16x16x32_bf16 v[28:31], v[144:147], v[208:211], v[28:31]
	v_mfma_f32_16x16x32_bf16 v[24:27], v[160:163], v[208:211], v[24:27]
	v_mfma_f32_16x16x32_bf16 v[12:15], v[144:147], v[216:219], v[12:15]
	v_mfma_f32_16x16x32_bf16 v[8:11], v[160:163], v[216:219], v[8:11]
	v_mfma_f32_16x16x32_bf16 v[60:63], v[156:159], v[190:193], v[60:63]
	v_mfma_f32_16x16x32_bf16 v[56:59], v[164:167], v[190:193], v[56:59]
	v_mfma_f32_16x16x32_bf16 v[44:47], v[156:159], v[198:201], v[44:47]
	v_mfma_f32_16x16x32_bf16 v[40:43], v[164:167], v[198:201], v[40:43]
	v_mfma_f32_16x16x32_bf16 v[28:31], v[156:159], v[212:215], v[28:31]
	v_mfma_f32_16x16x32_bf16 v[24:27], v[164:167], v[212:215], v[24:27]
	v_lshl_add_u64 v[202:203], v[226:227], 0, s[42:43]
	s_mov_b32 m0, s59
	s_nop 0
	global_load_lds_dwordx4 v[202:203], off
	v_mfma_f32_16x16x32_bf16 v[12:15], v[156:159], v[220:223], v[12:15]
	v_mfma_f32_16x16x32_bf16 v[8:11], v[164:167], v[220:223], v[8:11]
	s_setprio 0
	s_setprio 1
	v_mfma_f32_16x16x32_bf16 v[52:55], v[168:171], v[186:189], v[52:55]
	v_mfma_f32_16x16x32_bf16 v[48:51], v[176:179], v[186:189], v[48:51]
	v_mfma_f32_16x16x32_bf16 v[36:39], v[168:171], v[194:197], v[36:39]
	v_mfma_f32_16x16x32_bf16 v[32:35], v[176:179], v[194:197], v[32:35]
	v_mfma_f32_16x16x32_bf16 v[20:23], v[168:171], v[208:211], v[20:23]
	v_mfma_f32_16x16x32_bf16 v[16:19], v[176:179], v[208:211], v[16:19]
	v_mfma_f32_16x16x32_bf16 v[4:7], v[168:171], v[216:219], v[4:7]
	v_mfma_f32_16x16x32_bf16 v[0:3], v[176:179], v[216:219], v[0:3]
	v_mfma_f32_16x16x32_bf16 v[52:55], v[172:175], v[190:193], v[52:55]
	v_mfma_f32_16x16x32_bf16 v[48:51], v[182:185], v[190:193], v[48:51]
	v_mfma_f32_16x16x32_bf16 v[36:39], v[172:175], v[198:201], v[36:39]
	v_mfma_f32_16x16x32_bf16 v[32:35], v[182:185], v[198:201], v[32:35]
	v_mfma_f32_16x16x32_bf16 v[20:23], v[172:175], v[212:215], v[20:23]
	v_mfma_f32_16x16x32_bf16 v[16:19], v[182:185], v[212:215], v[16:19]
	v_lshl_add_u64 v[202:203], v[228:229], 0, s[42:43]
	s_mov_b32 m0, s60
	s_nop 0
	global_load_lds_dwordx4 v[202:203], off
	v_mfma_f32_16x16x32_bf16 v[4:7], v[172:175], v[220:223], v[4:7]
	v_mfma_f32_16x16x32_bf16 v[0:3], v[182:185], v[220:223], v[0:3]
	s_setprio 0
	s_barrier
	s_add_i32 s77, s77, 2
	s_add_u32 s75, s75, 0x100
	s_addc_u32 s76, s76, 0
	s_mov_b64 s[50:51], s[52:53]
.LBB0_1035:
	ds_read_b128 v[144:147], v151
	ds_read_b128 v[156:159], v151 offset:1024
	ds_read_b128 v[160:163], v151 offset:2048
	ds_read_b128 v[164:167], v151 offset:3072
	ds_read_b128 v[168:171], v152
	ds_read_b128 v[172:175], v152 offset:1024
	ds_read_b128 v[176:179], v152 offset:2048
	ds_read_b128 v[182:185], v152 offset:3072
	s_add_u32 s52, s50, 0x100
	s_addc_u32 s53, s51, 0
	s_cmp_eq_u32 s77, 40
	s_cselect_b32 s57, s1, s53
	s_cselect_b32 s56, s0, s52
	s_cselect_b32 s55, s49, s76
	s_cselect_b32 s54, s48, s75
	v_lshl_add_u64 v[202:203], s[50:51], 0, v[136:137]
	s_add_i32 m0, s14, 0xc000
	ds_read_b128 v[186:189], v153
	ds_read_b128 v[190:193], v153 offset:1024
	ds_read_b128 v[194:197], v153 offset:2048
	ds_read_b128 v[198:201], v153 offset:3072
	ds_read_b128 v[208:211], v153 offset:4096
	ds_read_b128 v[212:215], v153 offset:5120
	ds_read_b128 v[216:219], v153 offset:6144
	ds_read_b128 v[220:223], v153 offset:7168
	global_load_lds_dwordx4 v[202:203], off
	v_lshl_add_u64 v[202:203], s[50:51], 0, v[138:139]
	s_add_i32 m0, s14, 0xe000
	s_nop 0
	global_load_lds_dwordx4 v[202:203], off
	s_waitcnt vmcnt(8)
	s_waitcnt lgkmcnt(0)
	s_barrier
; #define PG8_STAGE(bufoff, gbase, voff) do { _Pragma("unroll") for (int _i = 0; _i < 2; ++_i) \
;         __builtin_amdgcn_global_load_lds((const unsigned*)((const char*)(gbase) + (voff)[_i]), (PG8_LAS unsigned*)(lds + (bufoff) + ldsw + _i * 8192), 16, 0, 0); } while (0)
; #define PG8_LDA(dst, b, h) do { _Pragma("unroll") for (int m = 0; m < 4; ++m) _Pragma("unroll") for (int k = 0; k < 2; ++k) dst[m][k] = *(const PG8_LAS bf16x8*)(lds + PG8_SA(b, h) + aoff + m * 2048 + k * 1024); } while (0)
; #define PG8_MMA(ai, bj, At, Bt) do { __builtin_amdgcn_s_setprio(1); _Pragma("unroll") for (int m = 0; m < 4; ++m) _Pragma("unroll") for (int n = 0; n < 2; ++n) _Pragma("unroll") for (int k = 0; k < 2; ++k) \
;         acc[ai][bj][m][n] = __builtin_amdgcn_mfma_f32_16x16x32_bf16(Bt[n][k], At[m][k], acc[ai][bj][m][n], 0, 0, 0); __builtin_amdgcn_s_setprio(0); } while (0)
; #define PG8_WAIT_V(n) asm volatile("s_waitcnt vmcnt(" #n ")" ::: "memory")
; #define PG8_WAIT_L(n) asm volatile("s_waitcnt lgkmcnt(" #n ")" ::: "memory")
; #define PG8_BAR __builtin_amdgcn_s_barrier()
; #define PG8_SCHED __builtin_amdgcn_sched_barrier(0)
; template <class Epi, class Sched, bool ALIGN_EPI = false, bool SP2 = false>
; __device__ __forceinline__ void gemm_phase(PG8_LAS unsigned char* lds, const Gemm g, const Sched& S, const Epi& E) {
;     ...
;             PG8_WAIT_V(8); PG8_WAIT_L(0); PG8_BAR; PG8_MMA(0, 0, At, B0); PG8_MMA(0, 1, At, B1); PG8_BAR; PG8_SCHED;
;             PG8_LDA(At, 0, 1); PG8_STAGE(PG8_SB(0, 0), b2, voffB); PG8_STAGE(PG8_SB(0, 1), b2 + hstep, voffB); PG8_STAGE(PG8_SA(0, 0), a2, voffA);
;             PG8_WAIT_V(8); PG8_WAIT_L(0); PG8_BAR; PG8_MMA(1, 0, At, B0); PG8_MMA(1, 1, At, B1); PG8_BAR; PG8_SCHED;
	s_setprio 1
	s_waitcnt lgkmcnt(0)
	v_mfma_f32_16x16x32_bf16 v[124:127], v[144:147], v[186:189], v[124:127]
	v_mfma_f32_16x16x32_bf16 v[120:123], v[160:163], v[186:189], v[120:123]
	v_mfma_f32_16x16x32_bf16 v[108:111], v[144:147], v[194:197], v[108:111]
	v_mfma_f32_16x16x32_bf16 v[104:107], v[160:163], v[194:197], v[104:107]
	v_mfma_f32_16x16x32_bf16 v[92:95], v[144:147], v[208:211], v[92:95]
	v_mfma_f32_16x16x32_bf16 v[88:91], v[160:163], v[208:211], v[88:91]
	v_mfma_f32_16x16x32_bf16 v[76:79], v[144:147], v[216:219], v[76:79]
	v_mfma_f32_16x16x32_bf16 v[72:75], v[160:163], v[216:219], v[72:75]
	v_mfma_f32_16x16x32_bf16 v[124:127], v[156:159], v[190:193], v[124:127]
	v_mfma_f32_16x16x32_bf16 v[120:123], v[164:167], v[190:193], v[120:123]
	v_mfma_f32_16x16x32_bf16 v[108:111], v[156:159], v[198:201], v[108:111]
	v_mfma_f32_16x16x32_bf16 v[104:107], v[164:167], v[198:201], v[104:107]
	v_mfma_f32_16x16x32_bf16 v[92:95], v[156:159], v[212:215], v[92:95]
	v_mfma_f32_16x16x32_bf16 v[88:91], v[164:167], v[212:215], v[88:91]
	v_mfma_f32_16x16x32_bf16 v[76:79], v[156:159], v[220:223], v[76:79]
	v_mfma_f32_16x16x32_bf16 v[72:75], v[164:167], v[220:223], v[72:75]
	s_setprio 0
	s_setprio 1
	v_mfma_f32_16x16x32_bf16 v[116:119], v[168:171], v[186:189], v[116:119]
	v_mfma_f32_16x16x32_bf16 v[112:115], v[176:179], v[186:189], v[112:115]
	v_mfma_f32_16x16x32_bf16 v[100:103], v[168:171], v[194:197], v[100:103]
	v_mfma_f32_16x16x32_bf16 v[96:99], v[176:179], v[194:197], v[96:99]
	v_mfma_f32_16x16x32_bf16 v[84:87], v[168:171], v[208:211], v[84:87]
	v_mfma_f32_16x16x32_bf16 v[80:83], v[176:179], v[208:211], v[80:83]
	v_mfma_f32_16x16x32_bf16 v[68:71], v[168:171], v[216:219], v[68:71]
	v_mfma_f32_16x16x32_bf16 v[64:67], v[176:179], v[216:219], v[64:67]
	v_mfma_f32_16x16x32_bf16 v[116:119], v[172:175], v[190:193], v[116:119]
	v_mfma_f32_16x16x32_bf16 v[112:115], v[182:185], v[190:193], v[112:115]
	v_mfma_f32_16x16x32_bf16 v[100:103], v[172:175], v[198:201], v[100:103]
	v_mfma_f32_16x16x32_bf16 v[96:99], v[182:185], v[198:201], v[96:99]
	v_mfma_f32_16x16x32_bf16 v[84:87], v[172:175], v[212:215], v[84:87]
	v_mfma_f32_16x16x32_bf16 v[80:83], v[182:185], v[212:215], v[80:83]
	v_mfma_f32_16x16x32_bf16 v[68:71], v[172:175], v[220:223], v[68:71]
	v_mfma_f32_16x16x32_bf16 v[64:67], v[182:185], v[220:223], v[64:67]
	s_setprio 0
	s_barrier
	s_add_i32 s50, s61, s3
	v_lshl_add_u64 v[202:203], s[54:55], 0, v[130:131]
	s_mov_b32 m0, s50
	ds_read_b128 v[186:189], v153 offset:16384
	ds_read_b128 v[190:193], v153 offset:17408
	ds_read_b128 v[194:197], v153 offset:18432
	ds_read_b128 v[198:201], v153 offset:19456
	ds_read_b128 v[208:211], v153 offset:20480
	ds_read_b128 v[212:215], v153 offset:21504
	ds_read_b128 v[216:219], v153 offset:22528
	ds_read_b128 v[220:223], v153 offset:23552
	global_load_lds_dwordx4 v[202:203], off
	s_add_i32 m0, s50, 0x2000
	s_add_u32 s50, s54, 0xb0000
	v_lshl_add_u64 v[224:225], s[54:55], 0, v[134:135]
	s_addc_u32 s51, s55, 0
	s_add_i32 s78, s62, s3
	global_load_lds_dwordx4 v[224:225], off
	v_lshl_add_u64 v[226:227], s[50:51], 0, v[130:131]
	s_mov_b32 m0, s78
	global_load_lds_dwordx4 v[226:227], off
	v_lshl_add_u64 v[226:227], s[50:51], 0, v[134:135]
	s_add_i32 m0, s78, 0x2000
	s_nop 0
	global_load_lds_dwordx4 v[226:227], off
	s_waitcnt vmcnt(6)
	s_waitcnt lgkmcnt(0)
	s_barrier
	s_setprio 1
	s_waitcnt lgkmcnt(0)
	v_mfma_f32_16x16x32_bf16 v[60:63], v[144:147], v[186:189], v[60:63]
	v_mfma_f32_16x16x32_bf16 v[56:59], v[160:163], v[186:189], v[56:59]
	v_mfma_f32_16x16x32_bf16 v[44:47], v[144:147], v[194:197], v[44:47]
	v_mfma_f32_16x16x32_bf16 v[40:43], v[160:163], v[194:197], v[40:43]
	v_mfma_f32_16x16x32_bf16 v[28:31], v[144:147], v[208:211], v[28:31]
	v_mfma_f32_16x16x32_bf16 v[24:27], v[160:163], v[208:211], v[24:27]
	v_mfma_f32_16x16x32_bf16 v[12:15], v[144:147], v[216:219], v[12:15]
	v_mfma_f32_16x16x32_bf16 v[8:11], v[160:163], v[216:219], v[8:11]
	v_mfma_f32_16x16x32_bf16 v[60:63], v[156:159], v[190:193], v[60:63]
	v_mfma_f32_16x16x32_bf16 v[56:59], v[164:167], v[190:193], v[56:59]
	v_mfma_f32_16x16x32_bf16 v[44:47], v[156:159], v[198:201], v[44:47]
	v_mfma_f32_16x16x32_bf16 v[40:43], v[164:167], v[198:201], v[40:43]
	v_mfma_f32_16x16x32_bf16 v[28:31], v[156:159], v[212:215], v[28:31]
	v_mfma_f32_16x16x32_bf16 v[24:27], v[164:167], v[212:215], v[24:27]
	v_lshl_add_u64 v[226:227], s[56:57], 0, v[128:129]
	s_mov_b32 m0, s14
	s_nop 0
	global_load_lds_dwordx4 v[226:227], off
	v_mfma_f32_16x16x32_bf16 v[12:15], v[156:159], v[220:223], v[12:15]
	v_mfma_f32_16x16x32_bf16 v[8:11], v[164:167], v[220:223], v[8:11]
	s_setprio 0
	s_setprio 1
	v_mfma_f32_16x16x32_bf16 v[52:55], v[168:171], v[186:189], v[52:55]
	v_mfma_f32_16x16x32_bf16 v[48:51], v[176:179], v[186:189], v[48:51]
	v_mfma_f32_16x16x32_bf16 v[36:39], v[168:171], v[194:197], v[36:39]
	v_mfma_f32_16x16x32_bf16 v[32:35], v[176:179], v[194:197], v[32:35]
	v_mfma_f32_16x16x32_bf16 v[20:23], v[168:171], v[208:211], v[20:23]
	v_mfma_f32_16x16x32_bf16 v[16:19], v[176:179], v[208:211], v[16:19]
	v_mfma_f32_16x16x32_bf16 v[4:7], v[168:171], v[216:219], v[4:7]
	v_mfma_f32_16x16x32_bf16 v[0:3], v[176:179], v[216:219], v[0:3]
	v_mfma_f32_16x16x32_bf16 v[52:55], v[172:175], v[190:193], v[52:55]
	v_mfma_f32_16x16x32_bf16 v[48:51], v[182:185], v[190:193], v[48:51]
	v_mfma_f32_16x16x32_bf16 v[36:39], v[172:175], v[198:201], v[36:39]
	v_mfma_f32_16x16x32_bf16 v[32:35], v[182:185], v[198:201], v[32:35]
	v_mfma_f32_16x16x32_bf16 v[20:23], v[172:175], v[212:215], v[20:23]
	v_mfma_f32_16x16x32_bf16 v[16:19], v[182:185], v[212:215], v[16:19]
	v_lshl_add_u64 v[228:229], s[56:57], 0, v[132:133]
	s_mov_b32 m0, s15
	s_nop 0
	global_load_lds_dwordx4 v[228:229], off
	v_mfma_f32_16x16x32_bf16 v[4:7], v[172:175], v[220:223], v[4:7]
	v_mfma_f32_16x16x32_bf16 v[0:3], v[182:185], v[220:223], v[0:3]
	s_setprio 0
	s_barrier
; #define PG8_STAGE(bufoff, gbase, voff) do { _Pragma("unroll") for (int _i = 0; _i < 2; ++_i) \
;         __builtin_amdgcn_global_load_lds((const unsigned*)((const char*)(gbase) + (voff)[_i]), (PG8_LAS unsigned*)(lds + (bufoff) + ldsw + _i * 8192), 16, 0, 0); } while (0)
; #define PG8_LDA(dst, b, h) do { _Pragma("unroll") for (int m = 0; m < 4; ++m) _Pragma("unroll") for (int k = 0; k < 2; ++k) dst[m][k] = *(const PG8_LAS bf16x8*)(lds + PG8_SA(b, h) + aoff + m * 2048 + k * 1024); } while (0)
; #define PG8_LDB(dst, b, h) do { _Pragma("unroll") for (int n = 0; n < 2; ++n) _Pragma("unroll") for (int k = 0; k < 2; ++k) dst[n][k] = *(const PG8_LAS bf16x8*)(lds + PG8_SB(b, h) + boff + n * 2048 + k * 1024); } while (0)
; #define PG8_MMA(ai, bj, At, Bt) do { __builtin_amdgcn_s_setprio(1); _Pragma("unroll") for (int m = 0; m < 4; ++m) _Pragma("unroll") for (int n = 0; n < 2; ++n) _Pragma("unroll") for (int k = 0; k < 2; ++k) \
;         acc[ai][bj][m][n] = __builtin_amdgcn_mfma_f32_16x16x32_bf16(Bt[n][k], At[m][k], acc[ai][bj][m][n], 0, 0, 0); __builtin_amdgcn_s_setprio(0); } while (0)
; #define PG8_WAIT_V(n) asm volatile("s_waitcnt vmcnt(" #n ")" ::: "memory")
; #define PG8_WAIT_L(n) asm volatile("s_waitcnt lgkmcnt(" #n ")" ::: "memory")
; #define PG8_BAR __builtin_amdgcn_s_barrier()
; #define PG8_SCHED __builtin_amdgcn_sched_barrier(0)
; template <class Epi, class Sched, bool ALIGN_EPI = false, bool SP2 = false>
; __device__ __forceinline__ void gemm_phase(PG8_LAS unsigned char* lds, const Gemm g, const Sched& S, const Epi& E) {
;     ...
;             PG8_LDB(B0, 1, 0); PG8_LDB(B1, 1, 1); PG8_SCHED; PG8_LDA(At, 1, 0); PG8_STAGE(PG8_SA(0, 1), a2 + hstep, voffA);
;             PG8_WAIT_V(8); PG8_WAIT_L(0); PG8_BAR; PG8_MMA(0, 0, At, B0); PG8_MMA(0, 1, At, B1); PG8_BAR; PG8_SCHED;
;             PG8_LDA(At, 1, 1); PG8_STAGE(PG8_SB(1, 0), b3, voffB); PG8_STAGE(PG8_SB(1, 1), b3 + hstep, voffB); PG8_STAGE(PG8_SA(1, 0), a3, voffA);
	s_add_i32 s78, 0, 0x18000
	v_add_u32_e32 v155, s78, v149
	s_add_i32 s79, 0, 0x1c000
	ds_read_b128 v[144:147], v155
	ds_read_b128 v[156:159], v155 offset:1024
	ds_read_b128 v[160:163], v155 offset:2048
	ds_read_b128 v[164:167], v155 offset:3072
	v_add_u32_e32 v155, s79, v149
	ds_read_b128 v[168:171], v155
	ds_read_b128 v[172:175], v155 offset:1024
	ds_read_b128 v[176:179], v155 offset:2048
	ds_read_b128 v[182:185], v155 offset:3072
	s_add_u32 s50, s56, 0xb0000
	s_addc_u32 s51, s57, 0
	s_mov_b32 m0, s33
	v_lshl_add_u64 v[230:231], s[50:51], 0, v[128:129]
	ds_read_b128 v[186:189], v153 offset:32768
	ds_read_b128 v[190:193], v153 offset:33792
	ds_read_b128 v[194:197], v153 offset:34816
	ds_read_b128 v[198:201], v153 offset:35840
	ds_read_b128 v[208:211], v153 offset:36864
	ds_read_b128 v[212:215], v153 offset:37888
	ds_read_b128 v[216:219], v153 offset:38912
	ds_read_b128 v[220:223], v153 offset:39936
	global_load_lds_dwordx4 v[230:231], off
	v_lshl_add_u64 v[230:231], s[50:51], 0, v[132:133]
	s_mov_b32 m0, s34
	s_nop 0
	global_load_lds_dwordx4 v[230:231], off
	s_waitcnt vmcnt(8)
	s_waitcnt lgkmcnt(0)
	s_barrier
	s_setprio 1
	s_waitcnt lgkmcnt(0)
	v_mfma_f32_16x16x32_bf16 v[124:127], v[144:147], v[186:189], v[124:127]
	v_mfma_f32_16x16x32_bf16 v[120:123], v[160:163], v[186:189], v[120:123]
	v_mfma_f32_16x16x32_bf16 v[108:111], v[144:147], v[194:197], v[108:111]
	v_mfma_f32_16x16x32_bf16 v[104:107], v[160:163], v[194:197], v[104:107]
	v_mfma_f32_16x16x32_bf16 v[92:95], v[144:147], v[208:211], v[92:95]
	v_mfma_f32_16x16x32_bf16 v[88:91], v[160:163], v[208:211], v[88:91]
	v_mfma_f32_16x16x32_bf16 v[76:79], v[144:147], v[216:219], v[76:79]
	v_mfma_f32_16x16x32_bf16 v[72:75], v[160:163], v[216:219], v[72:75]
	v_mfma_f32_16x16x32_bf16 v[124:127], v[156:159], v[190:193], v[124:127]
	v_mfma_f32_16x16x32_bf16 v[120:123], v[164:167], v[190:193], v[120:123]
	v_mfma_f32_16x16x32_bf16 v[108:111], v[156:159], v[198:201], v[108:111]
	v_mfma_f32_16x16x32_bf16 v[104:107], v[164:167], v[198:201], v[104:107]
	v_mfma_f32_16x16x32_bf16 v[92:95], v[156:159], v[212:215], v[92:95]
	v_mfma_f32_16x16x32_bf16 v[88:91], v[164:167], v[212:215], v[88:91]
	v_mfma_f32_16x16x32_bf16 v[76:79], v[156:159], v[220:223], v[76:79]
	v_mfma_f32_16x16x32_bf16 v[72:75], v[164:167], v[220:223], v[72:75]
	s_setprio 0
	s_setprio 1
	v_mfma_f32_16x16x32_bf16 v[116:119], v[168:171], v[186:189], v[116:119]
	v_mfma_f32_16x16x32_bf16 v[112:115], v[176:179], v[186:189], v[112:115]
	v_mfma_f32_16x16x32_bf16 v[100:103], v[168:171], v[194:197], v[100:103]
	v_mfma_f32_16x16x32_bf16 v[96:99], v[176:179], v[194:197], v[96:99]
	v_mfma_f32_16x16x32_bf16 v[84:87], v[168:171], v[208:211], v[84:87]
	v_mfma_f32_16x16x32_bf16 v[80:83], v[176:179], v[208:211], v[80:83]
	v_mfma_f32_16x16x32_bf16 v[68:71], v[168:171], v[216:219], v[68:71]
	v_mfma_f32_16x16x32_bf16 v[64:67], v[176:179], v[216:219], v[64:67]
	v_mfma_f32_16x16x32_bf16 v[116:119], v[172:175], v[190:193], v[116:119]
	v_mfma_f32_16x16x32_bf16 v[112:115], v[182:185], v[190:193], v[112:115]
	v_mfma_f32_16x16x32_bf16 v[100:103], v[172:175], v[198:201], v[100:103]
	v_mfma_f32_16x16x32_bf16 v[96:99], v[182:185], v[198:201], v[96:99]
	v_mfma_f32_16x16x32_bf16 v[84:87], v[172:175], v[212:215], v[84:87]
	v_mfma_f32_16x16x32_bf16 v[80:83], v[182:185], v[212:215], v[80:83]
	v_mfma_f32_16x16x32_bf16 v[68:71], v[172:175], v[220:223], v[68:71]
	v_mfma_f32_16x16x32_bf16 v[64:67], v[182:185], v[220:223], v[64:67]
	s_setprio 0
	s_barrier
	s_add_i32 s50, s78, s3
	v_lshl_add_u64 v[202:203], v[202:203], 0, s[42:43]
	s_mov_b32 m0, s50
	ds_read_b128 v[186:189], v153 offset:49152
	ds_read_b128 v[190:193], v153 offset:50176
	ds_read_b128 v[194:197], v153 offset:51200
	ds_read_b128 v[198:201], v153 offset:52224
	ds_read_b128 v[208:211], v153 offset:53248
	ds_read_b128 v[212:215], v153 offset:54272
	ds_read_b128 v[216:219], v153 offset:55296
	ds_read_b128 v[220:223], v153 offset:56320
	global_load_lds_dwordx4 v[202:203], off
	s_add_i32 m0, s50, 0x2000
	s_add_u32 s50, s54, 0xb0080
	v_lshl_add_u64 v[202:203], v[224:225], 0, s[42:43]
	s_addc_u32 s51, s55, 0
	s_add_i32 s54, s79, s3
	global_load_lds_dwordx4 v[202:203], off
	v_lshl_add_u64 v[202:203], s[50:51], 0, v[130:131]
	s_mov_b32 m0, s54
	s_nop 0
	global_load_lds_dwordx4 v[202:203], off
	v_lshl_add_u64 v[202:203], s[50:51], 0, v[134:135]
	s_add_i32 m0, s54, 0x2000
	s_nop 0
	global_load_lds_dwordx4 v[202:203], off
	s_waitcnt vmcnt(6)
	s_waitcnt lgkmcnt(0)
	s_barrier
; __device__ __forceinline__ void fx_add(float* p, size_t idx, float s) { atomicAdd((unsigned long long*)p + idx, (unsigned long long)(long long)(s * 4294967296.0f)); }
; __device__ __forceinline__ unsigned cvtpk(float lo, float hi) { f32x2v_ v = {lo, hi}; bf16x2v_ b = __builtin_convertvector(v, bf16x2v_); return __builtin_bit_cast(unsigned, b); }
; #define PG8_BAR __builtin_amdgcn_s_barrier()
;     __device__ __forceinline__ void operator()(const f32x4 (&acc)[2][2][4][2], const Unit& u, int wr, int wc, int fr, int fq) const {
;     ...
;             for (int m = 0; m < 4; ++m) { const int row = row0 + ai * HALF + m * 16; const size_t off = (size_t)row * 1024 + col0; float s = 0.f;
; #pragma unroll
;                 for (int bj = 0; bj < 2; ++bj) { f32x4 a0, a1;
;                     if (xin32) { const float* p = xin32 + off + bj * HALF; a0 = *(const f32x4*)p; a1 = *(const f32x4*)(p + 4); }
;                     else { const u32x4 w = *(const u32x4*)(xb + off + bj * HALF);
;                         a0 = (f32x4){__uint_as_float(w.x << 16), __uint_as_float(w.x & 0xffff0000u), __uint_as_float(w.y << 16), __uint_as_float(w.y & 0xffff0000u)};
;                         a1 = (f32x4){__uint_as_float(w.z << 16), __uint_as_float(w.z & 0xffff0000u), __uint_as_float(w.w << 16), __uint_as_float(w.w & 0xffff0000u)}; }
;                     const f32x4 v0 = a0 + acc[ai][bj][m][0] * alpha, v1 = a1 + acc[ai][bj][m][1] * alpha;
;                     u32x4 w; w.x = cvtpk(v0[0], v0[1]); w.y = cvtpk(v0[2], v0[3]); w.z = cvtpk(v1[0], v1[1]); w.w = cvtpk(v1[2], v1[3]);
;                     *(u32x4*)(xb + off + bj * HALF) = w;
;                     s += (v0[0] * v0[0] + v0[1] * v0[1]) + (v0[2] * v0[2] + v0[3] * v0[3]) + (v1[0] * v1[0] + v1[1] * v1[1]) + (v1[2] * v1[2] + v1[3] * v1[3]); }
;                 s += __shfl_xor(s, 16); s += __shfl_xor(s, 32);
;                 if (fq == 0) fx_add(ssout, row, s); }
; template <class Epi, class Sched, bool ALIGN_EPI = false, bool SP2 = false>
; __device__ __forceinline__ void gemm_phase(PG8_LAS unsigned char* lds, const Gemm g, const Sched& S, const Epi& E) {
;     ...
;             PG8_LDA(At, 1, 1); PG8_STAGE(PG8_SB(1, 0), b3, voffB); PG8_STAGE(PG8_SB(1, 1), b3 + hstep, voffB); PG8_STAGE(PG8_SA(1, 0), a3, voffA);
;             PG8_WAIT_V(8); PG8_WAIT_L(0); PG8_BAR; PG8_MMA(1, 0, At, B0); PG8_MMA(1, 1, At, B1); PG8_BAR; PG8_SCHED;
	s_setprio 1
	s_waitcnt lgkmcnt(0)
	v_mfma_f32_16x16x32_bf16 v[60:63], v[144:147], v[186:189], v[60:63]
	v_mfma_f32_16x16x32_bf16 v[56:59], v[160:163], v[186:189], v[56:59]
	v_mfma_f32_16x16x32_bf16 v[44:47], v[144:147], v[194:197], v[44:47]
	v_mfma_f32_16x16x32_bf16 v[40:43], v[160:163], v[194:197], v[40:43]
	v_mfma_f32_16x16x32_bf16 v[28:31], v[144:147], v[208:211], v[28:31]
	v_mfma_f32_16x16x32_bf16 v[24:27], v[160:163], v[208:211], v[24:27]
	v_mfma_f32_16x16x32_bf16 v[12:15], v[144:147], v[216:219], v[12:15]
	v_mfma_f32_16x16x32_bf16 v[8:11], v[160:163], v[216:219], v[8:11]
	v_mfma_f32_16x16x32_bf16 v[60:63], v[156:159], v[190:193], v[60:63]
	v_mfma_f32_16x16x32_bf16 v[56:59], v[164:167], v[190:193], v[56:59]
	v_mfma_f32_16x16x32_bf16 v[44:47], v[156:159], v[198:201], v[44:47]
	v_mfma_f32_16x16x32_bf16 v[40:43], v[164:167], v[198:201], v[40:43]
	v_mfma_f32_16x16x32_bf16 v[28:31], v[156:159], v[212:215], v[28:31]
	v_mfma_f32_16x16x32_bf16 v[24:27], v[164:167], v[212:215], v[24:27]
	v_lshl_add_u64 v[202:203], v[226:227], 0, s[42:43]
	s_mov_b32 m0, s59
	s_nop 0
	global_load_lds_dwordx4 v[202:203], off
	v_mfma_f32_16x16x32_bf16 v[12:15], v[156:159], v[220:223], v[12:15]
	v_mfma_f32_16x16x32_bf16 v[8:11], v[164:167], v[220:223], v[8:11]
	s_setprio 0
	s_setprio 1
	v_mfma_f32_16x16x32_bf16 v[52:55], v[168:171], v[186:189], v[52:55]
	v_mfma_f32_16x16x32_bf16 v[48:51], v[176:179], v[186:189], v[48:51]
	v_mfma_f32_16x16x32_bf16 v[36:39], v[168:171], v[194:197], v[36:39]
	v_mfma_f32_16x16x32_bf16 v[32:35], v[176:179], v[194:197], v[32:35]
	v_mfma_f32_16x16x32_bf16 v[20:23], v[168:171], v[208:211], v[20:23]
	v_mfma_f32_16x16x32_bf16 v[16:19], v[176:179], v[208:211], v[16:19]
	v_mfma_f32_16x16x32_bf16 v[4:7], v[168:171], v[216:219], v[4:7]
	v_mfma_f32_16x16x32_bf16 v[0:3], v[176:179], v[216:219], v[0:3]
	v_mfma_f32_16x16x32_bf16 v[52:55], v[172:175], v[190:193], v[52:55]
	v_mfma_f32_16x16x32_bf16 v[48:51], v[182:185], v[190:193], v[48:51]
	v_mfma_f32_16x16x32_bf16 v[36:39], v[172:175], v[198:201], v[36:39]
	v_mfma_f32_16x16x32_bf16 v[32:35], v[182:185], v[198:201], v[32:35]
	v_mfma_f32_16x16x32_bf16 v[20:23], v[172:175], v[212:215], v[20:23]
	v_mfma_f32_16x16x32_bf16 v[16:19], v[182:185], v[212:215], v[16:19]
	v_lshl_add_u64 v[202:203], v[228:229], 0, s[42:43]
	s_mov_b32 m0, s60
	s_nop 0
	global_load_lds_dwordx4 v[202:203], off
	v_mfma_f32_16x16x32_bf16 v[4:7], v[172:175], v[220:223], v[4:7]
	v_mfma_f32_16x16x32_bf16 v[0:3], v[182:185], v[220:223], v[0:3]
	s_setprio 0
	s_barrier
	s_add_i32 s77, s77, 2
	s_add_u32 s75, s75, 0x100
	s_addc_u32 s76, s76, 0
	s_cmp_gt_u32 s77, 41
	s_mov_b64 s[50:51], s[52:53]
	s_cbranch_scc0 .LBB0_1035
	s_and_b64 vcc, exec, s[44:45]
	s_cbranch_vccz .LBB0_1038
.LBB0_1038:
	v_lshl_add_u32 v146, s74, 8, v148
	v_ashrrev_i32_e32 v147, 31, v146
	v_lshl_or_b32 v144, s67, 8, v150
	v_lshlrev_b64 v[156:157], 11, v[146:147]
	v_ashrrev_i32_e32 v145, 31, v144
	v_lshl_add_u64 v[156:157], s[22:23], 0, v[156:157]
	v_lshl_add_u64 v[166:167], v[144:145], 1, v[156:157]
	global_load_dwordx4 v[158:161], v[166:167], off
	global_load_dwordx4 v[162:165], v[166:167], off offset:256
	v_and_b32_e32 v156, 64, v154
	v_xor_b32_e32 v155, 16, v154
	v_add_u32_e32 v156, 64, v156
	v_xor_b32_e32 v157, 32, v154
	v_cmp_lt_i32_e32 vcc, v155, v156
	s_waitcnt vmcnt(0)
	v_lshlrev_b32_e32 v168, 16, v158
	v_cndmask_b32_e32 v155, v154, v155, vcc
	v_cmp_lt_i32_e32 vcc, v157, v156
	v_and_b32_e32 v169, 0xffff0000, v158
	v_lshlrev_b32_e32 v158, 16, v159
	v_and_b32_e32 v159, 0xffff0000, v159
	v_lshlrev_b32_e32 v172, 16, v162
	v_and_b32_e32 v173, 0xffff0000, v162
	v_lshlrev_b32_e32 v162, 16, v163
	v_and_b32_e32 v163, 0xffff0000, v163
	v_cndmask_b32_e32 v157, v154, v157, vcc
	v_lshlrev_b32_e32 v170, 16, v160
	v_and_b32_e32 v171, 0xffff0000, v160
	v_lshlrev_b32_e32 v160, 16, v161
	v_and_b32_e32 v161, 0xffff0000, v161
	v_lshlrev_b32_e32 v174, 16, v164
	v_and_b32_e32 v175, 0xffff0000, v164
	v_lshlrev_b32_e32 v164, 16, v165
	v_and_b32_e32 v165, 0xffff0000, v165
	v_pk_fma_f32 v[126:127], v[126:127], 0.5, v[158:159] op_sel_hi:[1,0,1]
	v_pk_fma_f32 v[124:125], v[124:125], 0.5, v[168:169] op_sel_hi:[1,0,1]
	v_pk_fma_f32 v[118:119], v[118:119], 0.5, v[162:163] op_sel_hi:[1,0,1]
	v_pk_fma_f32 v[116:117], v[116:117], 0.5, v[172:173] op_sel_hi:[1,0,1]
	v_lshlrev_b32_e32 v156, 2, v155
	v_lshlrev_b32_e32 v155, 2, v157
	v_pk_fma_f32 v[122:123], v[122:123], 0.5, v[160:161] op_sel_hi:[1,0,1]
	v_pk_fma_f32 v[120:121], v[120:121], 0.5, v[170:171] op_sel_hi:[1,0,1]
	v_pk_fma_f32 v[158:159], v[114:115], 0.5, v[164:165] op_sel_hi:[1,0,1]
	v_pk_fma_f32 v[160:161], v[112:113], 0.5, v[174:175] op_sel_hi:[1,0,1]
	v_mul_f32_e32 v114, v125, v125
	v_mul_f32_e32 v115, v127, v127
	v_mul_f32_e32 v157, v117, v117
	v_mul_f32_e32 v162, v119, v119
	v_cvt_pk_bf16_f32 v112, v124, v125
	v_mul_f32_e32 v125, v121, v121
	v_mul_f32_e32 v163, v161, v161
	v_fmac_f32_e32 v114, v124, v124
	v_fmac_f32_e32 v115, v126, v126
	v_fmac_f32_e32 v157, v116, v116
	v_fmac_f32_e32 v162, v118, v118
	v_cvt_pk_bf16_f32 v113, v126, v127
	v_mul_f32_e32 v127, v123, v123
	v_mul_f32_e32 v164, v159, v159
	v_fmac_f32_e32 v125, v120, v120
	v_fmac_f32_e32 v163, v160, v160
	v_add_f32_e32 v114, v114, v115
	v_add_f32_e32 v115, v157, v162
	v_fmac_f32_e32 v127, v122, v122
	v_fmac_f32_e32 v164, v158, v158
	v_add_f32_e32 v114, v125, v114
	v_add_f32_e32 v115, v163, v115
	v_add_f32_e32 v114, v127, v114
	v_add_f32_e32 v115, v164, v115
	v_add_f32_e32 v124, v114, v115
	ds_bpermute_b32 v125, v156, v124
	v_cvt_pk_bf16_f32 v114, v120, v121
	v_cvt_pk_bf16_f32 v115, v122, v123
	global_store_dwordx4 v[166:167], v[112:115], off
	s_waitcnt lgkmcnt(0)
	s_nop 0
	v_add_f32_e32 v112, v124, v125
	ds_bpermute_b32 v113, v155, v112
	v_cvt_pk_bf16_f32 v114, v116, v117
	v_cvt_pk_bf16_f32 v115, v118, v119
	v_cvt_pk_bf16_f32 v116, v160, v161
	v_cvt_pk_bf16_f32 v117, v158, v159
	global_store_dwordx4 v[166:167], v[114:117], off offset:256
	s_and_saveexec_b64 s[50:51], s[10:11]
	s_cbranch_execz .LBB0_1040
	s_waitcnt lgkmcnt(0)
	v_add_f32_e32 v112, v112, v113
	v_mul_f32_e32 v112, 0x4f800000, v112
	v_trunc_f32_e32 v112, v112
	v_mul_f32_e64 v113, |v112|, s63
	v_floor_f32_e32 v113, v113
	v_fma_f32 v114, v113, s64, |v112|
	v_cvt_u32_f32_e32 v114, v114
	v_cvt_u32_f32_e32 v113, v113
	v_ashrrev_i32_e32 v115, 31, v112
	v_xor_b32_e32 v112, v114, v115
	v_xor_b32_e32 v113, v113, v115
	v_sub_co_u32_e32 v112, vcc, v112, v115
	s_nop 1
	v_subb_co_u32_e32 v113, vcc, v113, v115, vcc
	v_lshl_add_u64 v[114:115], v[146:147], 3, s[36:37]
	global_atomic_add_x2 v[114:115], v[112:113], off

; #define PG8_BAR __builtin_amdgcn_s_barrier()
; template <class Epi, class Sched, bool ALIGN_EPI = false, bool SP2 = false>
; __device__ __forceinline__ void gemm_phase(PG8_LAS unsigned char* lds, const Gemm g, const Sched& S, const Epi& E) {
;     ...
;         if constexpr (ALIGN_EPI) { if (wr == 0) PG8_BAR; }
;         if constexpr (!Epi::AFTER_DRAIN) { E(acc, cur, wr, wc, fr, fq); S.done(cur); }
;         if (!has_next) break;
; #pragma unroll
;         for (int a = 0; a < 2; ++a)
; #pragma unroll
;             for (int b = 0; b < 2; ++b)
; #pragma unroll
;                 for (int m = 0; m < 4; ++m)
; #pragma unroll
;                     for (int n = 0; n < 2; ++n) acc[a][b][m][n] = (f32x4){0.f, 0.f, 0.f, 0.f};
;         cur = nxt; cA = nA; cB = nB; ++ui;
;         if constexpr (ALIGN_EPI) { if (wr == 1) PG8_BAR; }
.LBB0_1054:
	s_or_b64 exec, exec, s[50:51]
	s_and_b64 vcc, exec, s[12:13]
	s_mov_b64 s[12:13], -1
	s_cmp_eq_u64 s[44:45], 0
	s_cbranch_scc1 .Lxpost_6
	s_barrier
.Lxpost_6:
	s_cbranch_vccnz .LBB0_1023
	s_andn2_b64 vcc, exec, s[38:39]
	s_cbranch_vccnz .LBB0_1022
	s_barrier
	s_branch .LBB0_1022

; #define PG8_STAGE(bufoff, gbase, voff) do { _Pragma("unroll") for (int _i = 0; _i < 2; ++_i) \
;         __builtin_amdgcn_global_load_lds((const unsigned*)((const char*)(gbase) + (voff)[_i]), (PG8_LAS unsigned*)(lds + (bufoff) + ldsw + _i * 8192), 16, 0, 0); } while (0)
; #define PG8_LDA(dst, b, h) do { _Pragma("unroll") for (int m = 0; m < 4; ++m) _Pragma("unroll") for (int k = 0; k < 2; ++k) dst[m][k] = *(const PG8_LAS bf16x8*)(lds + PG8_SA(b, h) + aoff + m * 2048 + k * 1024); } while (0)
; #define PG8_LDB(dst, b, h) do { _Pragma("unroll") for (int n = 0; n < 2; ++n) _Pragma("unroll") for (int k = 0; k < 2; ++k) dst[n][k] = *(const PG8_LAS bf16x8*)(lds + PG8_SB(b, h) + boff + n * 2048 + k * 1024); } while (0)
; #define PG8_WAIT_V(n) asm volatile("s_waitcnt vmcnt(" #n ")" ::: "memory")
; #define PG8_WAIT_L(n) asm volatile("s_waitcnt lgkmcnt(" #n ")" ::: "memory")
; #define PG8_BAR __builtin_amdgcn_s_barrier()
; #define PG8_SCHED __builtin_amdgcn_sched_barrier(0)
; template <class Epi, class Sched, bool ALIGN_EPI = false, bool SP2 = false>
; __device__ __forceinline__ void gemm_phase(PG8_LAS unsigned char* lds, const Gemm g, const Sched& S, const Epi& E) {
;     ...
;         const char* nA = has_next ? (const char*)g.A + (size_t)nxt.pm * tstep : cA; const char* nB = has_next ? (const char*)g.Bt + (size_t)nxt.pn * tstep : cB;
;         for (int t = 0; t < nt; t += 2) {
;             const bool last = (t == nt - 2);
;             const char* a1 = cA + (size_t)(t + 1) * kstep;
;             const char* a2 = last ? nA : cA + (size_t)(t + 2) * kstep; const char* b2 = last ? nB : cB + (size_t)(t + 2) * kstep;
;             const char* a3 = a2 + kstep; const char* b3 = b2 + kstep;
;             if (last && has_next) S.a_ready(nxt);
;             if constexpr (SP2) {
;             PG8_LDB(B0, 0, 0); PG8_LDB(B1, 0, 1); PG8_SCHED; PG8_LDA(At, 0, 0); PG8_STAGE(PG8_SA(1, 1), a1 + hstep, voffA);
;             PG8_WAIT_V(8); PG8_WAIT_L(0); PG8_BAR; PG8_MMA(0, 0, At, B0); PG8_MMA(0, 1, At, B1); PG8_BAR; PG8_SCHED;
;             PG8_LDA(At, 0, 1); PG8_STAGE(PG8_SB(0, 0), b2, voffB); PG8_STAGE(PG8_SB(0, 1), b2 + hstep, voffB); PG8_STAGE(PG8_SA(0, 0), a2, voffA);
;             PG8_WAIT_V(8); PG8_WAIT_L(0); PG8_BAR; PG8_MMA(1, 0, At, B0); PG8_MMA(1, 1, At, B1); PG8_BAR; PG8_SCHED;
.LBB0_1118:
	s_ashr_i32 s45, s44, 31
	s_lshl_b64 s[48:49], s[44:45], 19
	s_add_u32 s48, s22, s48
	s_addc_u32 s49, s23, s49
	s_and_b64 s[50:51], s[10:11], exec
	s_cselect_b32 s45, s49, s55
	s_cselect_b32 s76, s48, s54
	s_ashr_i32 s43, s42, 31
	s_lshl_b64 s[50:51], s[42:43], 19
	s_add_u32 s50, s14, s50
	s_addc_u32 s51, s15, s51
	s_and_b64 s[58:59], s[10:11], exec
	s_cselect_b32 s43, s51, s57
	s_cselect_b32 s77, s50, s56
	s_add_u32 s54, s54, 0x40080
	s_addc_u32 s55, s55, 0
	s_add_u32 s82, s56, 0x100
	s_addc_u32 s83, s57, 0
	s_mov_b32 s84, -2
	ds_read_b128 v[144:147], v155
	ds_read_b128 v[148:151], v155 offset:1024
	ds_read_b128 v[160:163], v155 offset:2048
	ds_read_b128 v[164:167], v155 offset:3072
	ds_read_b128 v[168:171], v156
	ds_read_b128 v[172:175], v156 offset:1024
	ds_read_b128 v[176:179], v156 offset:2048
	ds_read_b128 v[182:185], v156 offset:3072
	s_add_u32 s56, s54, 0xfffc0080
	s_addc_u32 s57, s55, -1
	s_cmp_eq_u32 s84, 12
	s_cselect_b32 s59, s45, s57
	s_cselect_b32 s58, s76, s56
	s_cselect_b32 s57, s43, s83
	s_cselect_b32 s56, s77, s82
	v_lshl_add_u64 v[224:225], s[54:55], 0, v[136:137]
	s_add_i32 m0, s53, 0xc000
	ds_read_b128 v[186:189], v157
	ds_read_b128 v[190:193], v157 offset:1024
	ds_read_b128 v[194:197], v157 offset:2048
	ds_read_b128 v[198:201], v157 offset:3072
	ds_read_b128 v[208:211], v157 offset:4096
	ds_read_b128 v[212:215], v157 offset:5120
	ds_read_b128 v[216:219], v157 offset:6144
	ds_read_b128 v[220:223], v157 offset:7168
	global_load_lds_dwordx4 v[224:225], off
	v_lshl_add_u64 v[224:225], s[54:55], 0, v[138:139]
	s_add_i32 m0, s53, 0xe000
	s_nop 0
	global_load_lds_dwordx4 v[224:225], off
	s_waitcnt vmcnt(8)
	s_waitcnt lgkmcnt(0)
	s_barrier
	s_setprio 1
	s_waitcnt lgkmcnt(0)
	v_mfma_f32_16x16x32_bf16 v[124:127], v[144:147], v[186:189], 0
	v_mfma_f32_16x16x32_bf16 v[120:123], v[160:163], v[186:189], 0
	v_mfma_f32_16x16x32_bf16 v[108:111], v[144:147], v[194:197], 0
	v_mfma_f32_16x16x32_bf16 v[104:107], v[160:163], v[194:197], 0
	v_mfma_f32_16x16x32_bf16 v[92:95], v[144:147], v[208:211], 0
	v_mfma_f32_16x16x32_bf16 v[88:91], v[160:163], v[208:211], 0
	v_mfma_f32_16x16x32_bf16 v[76:79], v[144:147], v[216:219], 0
	v_mfma_f32_16x16x32_bf16 v[72:75], v[160:163], v[216:219], 0
	v_mfma_f32_16x16x32_bf16 v[124:127], v[148:151], v[190:193], v[124:127]
	v_mfma_f32_16x16x32_bf16 v[120:123], v[164:167], v[190:193], v[120:123]
	v_mfma_f32_16x16x32_bf16 v[108:111], v[148:151], v[198:201], v[108:111]
	v_mfma_f32_16x16x32_bf16 v[104:107], v[164:167], v[198:201], v[104:107]
	v_mfma_f32_16x16x32_bf16 v[92:95], v[148:151], v[212:215], v[92:95]
	v_mfma_f32_16x16x32_bf16 v[88:91], v[164:167], v[212:215], v[88:91]
	v_mfma_f32_16x16x32_bf16 v[76:79], v[148:151], v[220:223], v[76:79]
	v_mfma_f32_16x16x32_bf16 v[72:75], v[164:167], v[220:223], v[72:75]
	s_setprio 0
	s_setprio 1
	v_mfma_f32_16x16x32_bf16 v[116:119], v[168:171], v[186:189], 0
	v_mfma_f32_16x16x32_bf16 v[112:115], v[176:179], v[186:189], 0
	v_mfma_f32_16x16x32_bf16 v[100:103], v[168:171], v[194:197], 0
	v_mfma_f32_16x16x32_bf16 v[96:99], v[176:179], v[194:197], 0
	v_mfma_f32_16x16x32_bf16 v[84:87], v[168:171], v[208:211], 0
	v_mfma_f32_16x16x32_bf16 v[80:83], v[176:179], v[208:211], 0
	v_mfma_f32_16x16x32_bf16 v[68:71], v[168:171], v[216:219], 0
	v_mfma_f32_16x16x32_bf16 v[64:67], v[176:179], v[216:219], 0
	v_mfma_f32_16x16x32_bf16 v[116:119], v[172:175], v[190:193], v[116:119]
	v_mfma_f32_16x16x32_bf16 v[112:115], v[182:185], v[190:193], v[112:115]
	v_mfma_f32_16x16x32_bf16 v[100:103], v[172:175], v[198:201], v[100:103]
	v_mfma_f32_16x16x32_bf16 v[96:99], v[182:185], v[198:201], v[96:99]
	v_mfma_f32_16x16x32_bf16 v[84:87], v[172:175], v[212:215], v[84:87]
	v_mfma_f32_16x16x32_bf16 v[80:83], v[182:185], v[212:215], v[80:83]
	v_mfma_f32_16x16x32_bf16 v[68:71], v[172:175], v[220:223], v[68:71]
	v_mfma_f32_16x16x32_bf16 v[64:67], v[182:185], v[220:223], v[64:67]
	s_setprio 0
	s_barrier
	s_add_i32 s78, s66, s33
	v_lshl_add_u64 v[224:225], s[56:57], 0, v[132:133]
	s_mov_b32 m0, s78
	ds_read_b128 v[186:189], v157 offset:16384
	ds_read_b128 v[190:193], v157 offset:17408
	ds_read_b128 v[194:197], v157 offset:18432
	ds_read_b128 v[198:201], v157 offset:19456
	ds_read_b128 v[208:211], v157 offset:20480
	ds_read_b128 v[212:215], v157 offset:21504
	ds_read_b128 v[216:219], v157 offset:22528
	ds_read_b128 v[220:223], v157 offset:23552
	global_load_lds_dwordx4 v[224:225], off
	s_add_i32 m0, s78, 0x2000
	s_add_u32 s78, s56, 0x40000
	v_lshl_add_u64 v[226:227], s[56:57], 0, v[128:129]
	s_addc_u32 s79, s57, 0
	s_add_i32 s85, s67, s33
	global_load_lds_dwordx4 v[226:227], off
	v_lshl_add_u64 v[228:229], s[78:79], 0, v[132:133]
	s_mov_b32 m0, s85
	global_load_lds_dwordx4 v[228:229], off
	v_lshl_add_u64 v[228:229], s[78:79], 0, v[128:129]
	s_add_i32 m0, s85, 0x2000
	s_nop 0
	global_load_lds_dwordx4 v[228:229], off
	s_waitcnt vmcnt(6)
	s_waitcnt lgkmcnt(0)
	s_barrier
; #define PG8_STAGE(bufoff, gbase, voff) do { _Pragma("unroll") for (int _i = 0; _i < 2; ++_i) \
;         __builtin_amdgcn_global_load_lds((const unsigned*)((const char*)(gbase) + (voff)[_i]), (PG8_LAS unsigned*)(lds + (bufoff) + ldsw + _i * 8192), 16, 0, 0); } while (0)
; #define PG8_LDA(dst, b, h) do { _Pragma("unroll") for (int m = 0; m < 4; ++m) _Pragma("unroll") for (int k = 0; k < 2; ++k) dst[m][k] = *(const PG8_LAS bf16x8*)(lds + PG8_SA(b, h) + aoff + m * 2048 + k * 1024); } while (0)
; #define PG8_LDB(dst, b, h) do { _Pragma("unroll") for (int n = 0; n < 2; ++n) _Pragma("unroll") for (int k = 0; k < 2; ++k) dst[n][k] = *(const PG8_LAS bf16x8*)(lds + PG8_SB(b, h) + boff + n * 2048 + k * 1024); } while (0)
; #define PG8_MMA(ai, bj, At, Bt) do { __builtin_amdgcn_s_setprio(1); _Pragma("unroll") for (int m = 0; m < 4; ++m) _Pragma("unroll") for (int n = 0; n < 2; ++n) _Pragma("unroll") for (int k = 0; k < 2; ++k) \
;         acc[ai][bj][m][n] = __builtin_amdgcn_mfma_f32_16x16x32_bf16(Bt[n][k], At[m][k], acc[ai][bj][m][n], 0, 0, 0); __builtin_amdgcn_s_setprio(0); } while (0)
; #define PG8_WAIT_V(n) asm volatile("s_waitcnt vmcnt(" #n ")" ::: "memory")
; #define PG8_WAIT_L(n) asm volatile("s_waitcnt lgkmcnt(" #n ")" ::: "memory")
; #define PG8_BAR __builtin_amdgcn_s_barrier()
; #define PG8_SCHED __builtin_amdgcn_sched_barrier(0)
; template <class Epi, class Sched, bool ALIGN_EPI = false, bool SP2 = false>
; __device__ __forceinline__ void gemm_phase(PG8_LAS unsigned char* lds, const Gemm g, const Sched& S, const Epi& E) {
;     ...
;             PG8_WAIT_V(8); PG8_WAIT_L(0); PG8_BAR; PG8_MMA(1, 0, At, B0); PG8_MMA(1, 1, At, B1); PG8_BAR; PG8_SCHED;
;             PG8_LDB(B0, 1, 0); PG8_LDB(B1, 1, 1); PG8_SCHED; PG8_LDA(At, 1, 0); PG8_STAGE(PG8_SA(0, 1), a2 + hstep, voffA);
;             PG8_WAIT_V(8); PG8_WAIT_L(0); PG8_BAR; PG8_MMA(0, 0, At, B0); PG8_MMA(0, 1, At, B1); PG8_BAR; PG8_SCHED;
	s_setprio 1
	s_waitcnt lgkmcnt(0)
	v_mfma_f32_16x16x32_bf16 v[60:63], v[144:147], v[186:189], 0
	v_mfma_f32_16x16x32_bf16 v[56:59], v[160:163], v[186:189], 0
	v_mfma_f32_16x16x32_bf16 v[44:47], v[144:147], v[194:197], 0
	v_mfma_f32_16x16x32_bf16 v[40:43], v[160:163], v[194:197], 0
	v_mfma_f32_16x16x32_bf16 v[28:31], v[144:147], v[208:211], 0
	v_mfma_f32_16x16x32_bf16 v[24:27], v[160:163], v[208:211], 0
	v_mfma_f32_16x16x32_bf16 v[12:15], v[144:147], v[216:219], 0
	v_mfma_f32_16x16x32_bf16 v[8:11], v[160:163], v[216:219], 0
	v_mfma_f32_16x16x32_bf16 v[60:63], v[148:151], v[190:193], v[60:63]
	v_mfma_f32_16x16x32_bf16 v[56:59], v[164:167], v[190:193], v[56:59]
	v_mfma_f32_16x16x32_bf16 v[44:47], v[148:151], v[198:201], v[44:47]
	v_mfma_f32_16x16x32_bf16 v[40:43], v[164:167], v[198:201], v[40:43]
	v_mfma_f32_16x16x32_bf16 v[28:31], v[148:151], v[212:215], v[28:31]
	v_mfma_f32_16x16x32_bf16 v[24:27], v[164:167], v[212:215], v[24:27]
	v_lshl_add_u64 v[228:229], s[58:59], 0, v[134:135]
	s_mov_b32 m0, s53
	s_nop 0
	global_load_lds_dwordx4 v[228:229], off
	v_mfma_f32_16x16x32_bf16 v[12:15], v[148:151], v[220:223], v[12:15]
	v_mfma_f32_16x16x32_bf16 v[8:11], v[164:167], v[220:223], v[8:11]
	s_setprio 0
	s_setprio 1
	v_mfma_f32_16x16x32_bf16 v[52:55], v[168:171], v[186:189], 0
	v_mfma_f32_16x16x32_bf16 v[48:51], v[176:179], v[186:189], 0
	v_mfma_f32_16x16x32_bf16 v[36:39], v[168:171], v[194:197], 0
	v_mfma_f32_16x16x32_bf16 v[32:35], v[176:179], v[194:197], 0
	v_mfma_f32_16x16x32_bf16 v[20:23], v[168:171], v[208:211], 0
	v_mfma_f32_16x16x32_bf16 v[16:19], v[176:179], v[208:211], 0
	v_mfma_f32_16x16x32_bf16 v[4:7], v[168:171], v[216:219], 0
	v_mfma_f32_16x16x32_bf16 v[0:3], v[176:179], v[216:219], 0
	v_mfma_f32_16x16x32_bf16 v[52:55], v[172:175], v[190:193], v[52:55]
	v_mfma_f32_16x16x32_bf16 v[48:51], v[182:185], v[190:193], v[48:51]
	v_mfma_f32_16x16x32_bf16 v[36:39], v[172:175], v[198:201], v[36:39]
	v_mfma_f32_16x16x32_bf16 v[32:35], v[182:185], v[198:201], v[32:35]
	v_mfma_f32_16x16x32_bf16 v[20:23], v[172:175], v[212:215], v[20:23]
	v_mfma_f32_16x16x32_bf16 v[16:19], v[182:185], v[212:215], v[16:19]
	v_lshl_add_u64 v[230:231], s[58:59], 0, v[130:131]
	s_mov_b32 m0, s60
	s_nop 0
	global_load_lds_dwordx4 v[230:231], off
	v_mfma_f32_16x16x32_bf16 v[4:7], v[172:175], v[220:223], v[4:7]
	v_mfma_f32_16x16x32_bf16 v[0:3], v[182:185], v[220:223], v[0:3]
	s_setprio 0
	s_barrier
	s_add_i32 s78, 0, 0x18000
	v_add_u32_e32 v159, s78, v153
	s_add_i32 s79, 0, 0x1c000
	ds_read_b128 v[144:147], v159
	ds_read_b128 v[148:151], v159 offset:1024
	ds_read_b128 v[160:163], v159 offset:2048
	ds_read_b128 v[164:167], v159 offset:3072
	v_add_u32_e32 v159, s79, v153
	ds_read_b128 v[168:171], v159
	ds_read_b128 v[172:175], v159 offset:1024
	ds_read_b128 v[176:179], v159 offset:2048
	ds_read_b128 v[182:185], v159 offset:3072
	s_add_u32 s58, s58, 0x40000
	s_addc_u32 s59, s59, 0
	s_mov_b32 m0, s61
	v_lshl_add_u64 v[232:233], s[58:59], 0, v[134:135]
	ds_read_b128 v[186:189], v157 offset:32768
	ds_read_b128 v[190:193], v157 offset:33792
	ds_read_b128 v[194:197], v157 offset:34816
	ds_read_b128 v[198:201], v157 offset:35840
	ds_read_b128 v[208:211], v157 offset:36864
	ds_read_b128 v[212:215], v157 offset:37888
	ds_read_b128 v[216:219], v157 offset:38912
	ds_read_b128 v[220:223], v157 offset:39936
	global_load_lds_dwordx4 v[232:233], off
	v_lshl_add_u64 v[232:233], s[58:59], 0, v[130:131]
	s_mov_b32 m0, s62
	s_nop 0
	global_load_lds_dwordx4 v[232:233], off
	s_waitcnt vmcnt(8)
	s_waitcnt lgkmcnt(0)
	s_barrier
	s_setprio 1
	s_waitcnt lgkmcnt(0)
	v_mfma_f32_16x16x32_bf16 v[124:127], v[144:147], v[186:189], v[124:127]
	v_mfma_f32_16x16x32_bf16 v[120:123], v[160:163], v[186:189], v[120:123]
	v_mfma_f32_16x16x32_bf16 v[108:111], v[144:147], v[194:197], v[108:111]
	v_mfma_f32_16x16x32_bf16 v[104:107], v[160:163], v[194:197], v[104:107]
	v_mfma_f32_16x16x32_bf16 v[92:95], v[144:147], v[208:211], v[92:95]
	v_mfma_f32_16x16x32_bf16 v[88:91], v[160:163], v[208:211], v[88:91]
	v_mfma_f32_16x16x32_bf16 v[76:79], v[144:147], v[216:219], v[76:79]
	v_mfma_f32_16x16x32_bf16 v[72:75], v[160:163], v[216:219], v[72:75]
	v_mfma_f32_16x16x32_bf16 v[124:127], v[148:151], v[190:193], v[124:127]
	v_mfma_f32_16x16x32_bf16 v[120:123], v[164:167], v[190:193], v[120:123]
	v_mfma_f32_16x16x32_bf16 v[108:111], v[148:151], v[198:201], v[108:111]
	v_mfma_f32_16x16x32_bf16 v[104:107], v[164:167], v[198:201], v[104:107]
	v_mfma_f32_16x16x32_bf16 v[92:95], v[148:151], v[212:215], v[92:95]
	v_mfma_f32_16x16x32_bf16 v[88:91], v[164:167], v[212:215], v[88:91]
	v_mfma_f32_16x16x32_bf16 v[76:79], v[148:151], v[220:223], v[76:79]
	v_mfma_f32_16x16x32_bf16 v[72:75], v[164:167], v[220:223], v[72:75]
	s_setprio 0
	s_setprio 1
	v_mfma_f32_16x16x32_bf16 v[116:119], v[168:171], v[186:189], v[116:119]
	v_mfma_f32_16x16x32_bf16 v[112:115], v[176:179], v[186:189], v[112:115]
	v_mfma_f32_16x16x32_bf16 v[100:103], v[168:171], v[194:197], v[100:103]
	v_mfma_f32_16x16x32_bf16 v[96:99], v[176:179], v[194:197], v[96:99]
	v_mfma_f32_16x16x32_bf16 v[84:87], v[168:171], v[208:211], v[84:87]
	v_mfma_f32_16x16x32_bf16 v[80:83], v[176:179], v[208:211], v[80:83]
	v_mfma_f32_16x16x32_bf16 v[68:71], v[168:171], v[216:219], v[68:71]
	v_mfma_f32_16x16x32_bf16 v[64:67], v[176:179], v[216:219], v[64:67]
	v_mfma_f32_16x16x32_bf16 v[116:119], v[172:175], v[190:193], v[116:119]
	v_mfma_f32_16x16x32_bf16 v[112:115], v[182:185], v[190:193], v[112:115]
	v_mfma_f32_16x16x32_bf16 v[100:103], v[172:175], v[198:201], v[100:103]
	v_mfma_f32_16x16x32_bf16 v[96:99], v[182:185], v[198:201], v[96:99]
	v_mfma_f32_16x16x32_bf16 v[84:87], v[172:175], v[212:215], v[84:87]
	v_mfma_f32_16x16x32_bf16 v[80:83], v[182:185], v[212:215], v[80:83]
	v_mfma_f32_16x16x32_bf16 v[68:71], v[172:175], v[220:223], v[68:71]
	v_mfma_f32_16x16x32_bf16 v[64:67], v[182:185], v[220:223], v[64:67]
	s_setprio 0
	s_barrier
; #define PG8_STAGE(bufoff, gbase, voff) do { _Pragma("unroll") for (int _i = 0; _i < 2; ++_i) \
;         __builtin_amdgcn_global_load_lds((const unsigned*)((const char*)(gbase) + (voff)[_i]), (PG8_LAS unsigned*)(lds + (bufoff) + ldsw + _i * 8192), 16, 0, 0); } while (0)
; #define PG8_LDA(dst, b, h) do { _Pragma("unroll") for (int m = 0; m < 4; ++m) _Pragma("unroll") for (int k = 0; k < 2; ++k) dst[m][k] = *(const PG8_LAS bf16x8*)(lds + PG8_SA(b, h) + aoff + m * 2048 + k * 1024); } while (0)
; #define PG8_LDB(dst, b, h) do { _Pragma("unroll") for (int n = 0; n < 2; ++n) _Pragma("unroll") for (int k = 0; k < 2; ++k) dst[n][k] = *(const PG8_LAS bf16x8*)(lds + PG8_SB(b, h) + boff + n * 2048 + k * 1024); } while (0)
; #define PG8_MMA(ai, bj, At, Bt) do { __builtin_amdgcn_s_setprio(1); _Pragma("unroll") for (int m = 0; m < 4; ++m) _Pragma("unroll") for (int n = 0; n < 2; ++n) _Pragma("unroll") for (int k = 0; k < 2; ++k) \
;         acc[ai][bj][m][n] = __builtin_amdgcn_mfma_f32_16x16x32_bf16(Bt[n][k], At[m][k], acc[ai][bj][m][n], 0, 0, 0); __builtin_amdgcn_s_setprio(0); } while (0)
; #define PG8_WAIT_V(n) asm volatile("s_waitcnt vmcnt(" #n ")" ::: "memory")
; #define PG8_WAIT_L(n) asm volatile("s_waitcnt lgkmcnt(" #n ")" ::: "memory")
; #define PG8_BAR __builtin_amdgcn_s_barrier()
; #define PG8_SCHED __builtin_amdgcn_sched_barrier(0)
; template <class Epi, class Sched, bool ALIGN_EPI = false, bool SP2 = false>
; __device__ __forceinline__ void gemm_phase(PG8_LAS unsigned char* lds, const Gemm g, const Sched& S, const Epi& E) {
;     ...
;             PG8_LDB(B0, 0, 0); PG8_LDB(B1, 0, 1); PG8_SCHED; PG8_LDA(At, 0, 0); PG8_STAGE(PG8_SA(1, 1), a1 + hstep, voffA);
;             PG8_WAIT_V(8); PG8_WAIT_L(0); PG8_BAR; PG8_MMA(0, 0, At, B0); PG8_MMA(0, 1, At, B1); PG8_BAR; PG8_SCHED;
;     ...
;             PG8_LDA(At, 1, 1); PG8_STAGE(PG8_SB(1, 0), b3, voffB); PG8_STAGE(PG8_SB(1, 1), b3 + hstep, voffB); PG8_STAGE(PG8_SA(1, 0), a3, voffA);
;             PG8_WAIT_V(8); PG8_WAIT_L(0); PG8_BAR; PG8_MMA(1, 0, At, B0); PG8_MMA(1, 1, At, B1); PG8_BAR; PG8_SCHED;
	s_add_i32 s58, s78, s33
	v_lshl_add_u64 v[224:225], v[224:225], 0, s[12:13]
	s_mov_b32 m0, s58
	ds_read_b128 v[186:189], v157 offset:49152
	ds_read_b128 v[190:193], v157 offset:50176
	ds_read_b128 v[194:197], v157 offset:51200
	ds_read_b128 v[198:201], v157 offset:52224
	ds_read_b128 v[208:211], v157 offset:53248
	ds_read_b128 v[212:215], v157 offset:54272
	ds_read_b128 v[216:219], v157 offset:55296
	ds_read_b128 v[220:223], v157 offset:56320
	global_load_lds_dwordx4 v[224:225], off
	s_add_i32 m0, s58, 0x2000
	s_add_u32 s56, s56, 0x40080
	v_lshl_add_u64 v[224:225], v[226:227], 0, s[12:13]
	s_addc_u32 s57, s57, 0
	s_add_i32 s58, s79, s33
	global_load_lds_dwordx4 v[224:225], off
	v_lshl_add_u64 v[224:225], s[56:57], 0, v[132:133]
	s_mov_b32 m0, s58
	s_nop 0
	global_load_lds_dwordx4 v[224:225], off
	v_lshl_add_u64 v[224:225], s[56:57], 0, v[128:129]
	s_add_i32 m0, s58, 0x2000
	s_nop 0
	global_load_lds_dwordx4 v[224:225], off
	s_waitcnt vmcnt(6)
	s_waitcnt lgkmcnt(0)
	s_barrier
	s_setprio 1
	s_waitcnt lgkmcnt(0)
	v_mfma_f32_16x16x32_bf16 v[60:63], v[144:147], v[186:189], v[60:63]
	v_mfma_f32_16x16x32_bf16 v[56:59], v[160:163], v[186:189], v[56:59]
	v_mfma_f32_16x16x32_bf16 v[44:47], v[144:147], v[194:197], v[44:47]
	v_mfma_f32_16x16x32_bf16 v[40:43], v[160:163], v[194:197], v[40:43]
	v_mfma_f32_16x16x32_bf16 v[28:31], v[144:147], v[208:211], v[28:31]
	v_mfma_f32_16x16x32_bf16 v[24:27], v[160:163], v[208:211], v[24:27]
	v_mfma_f32_16x16x32_bf16 v[12:15], v[144:147], v[216:219], v[12:15]
	v_mfma_f32_16x16x32_bf16 v[8:11], v[160:163], v[216:219], v[8:11]
	v_mfma_f32_16x16x32_bf16 v[60:63], v[148:151], v[190:193], v[60:63]
	v_mfma_f32_16x16x32_bf16 v[56:59], v[164:167], v[190:193], v[56:59]
	v_mfma_f32_16x16x32_bf16 v[44:47], v[148:151], v[198:201], v[44:47]
	v_mfma_f32_16x16x32_bf16 v[40:43], v[164:167], v[198:201], v[40:43]
	v_mfma_f32_16x16x32_bf16 v[28:31], v[148:151], v[212:215], v[28:31]
	v_mfma_f32_16x16x32_bf16 v[24:27], v[164:167], v[212:215], v[24:27]
	v_lshl_add_u64 v[224:225], v[228:229], 0, s[12:13]
	s_mov_b32 m0, s64
	s_nop 0
	global_load_lds_dwordx4 v[224:225], off
	v_mfma_f32_16x16x32_bf16 v[12:15], v[148:151], v[220:223], v[12:15]
	v_mfma_f32_16x16x32_bf16 v[8:11], v[164:167], v[220:223], v[8:11]
	s_setprio 0
	s_setprio 1
	v_mfma_f32_16x16x32_bf16 v[52:55], v[168:171], v[186:189], v[52:55]
	v_mfma_f32_16x16x32_bf16 v[48:51], v[176:179], v[186:189], v[48:51]
	v_mfma_f32_16x16x32_bf16 v[36:39], v[168:171], v[194:197], v[36:39]
	v_mfma_f32_16x16x32_bf16 v[32:35], v[176:179], v[194:197], v[32:35]
	v_mfma_f32_16x16x32_bf16 v[20:23], v[168:171], v[208:211], v[20:23]
	v_mfma_f32_16x16x32_bf16 v[16:19], v[176:179], v[208:211], v[16:19]
	v_mfma_f32_16x16x32_bf16 v[4:7], v[168:171], v[216:219], v[4:7]
	v_mfma_f32_16x16x32_bf16 v[0:3], v[176:179], v[216:219], v[0:3]
	v_mfma_f32_16x16x32_bf16 v[52:55], v[172:175], v[190:193], v[52:55]
	v_mfma_f32_16x16x32_bf16 v[48:51], v[182:185], v[190:193], v[48:51]
	v_mfma_f32_16x16x32_bf16 v[36:39], v[172:175], v[198:201], v[36:39]
	v_mfma_f32_16x16x32_bf16 v[32:35], v[182:185], v[198:201], v[32:35]
	v_mfma_f32_16x16x32_bf16 v[20:23], v[172:175], v[212:215], v[20:23]
	v_mfma_f32_16x16x32_bf16 v[16:19], v[182:185], v[212:215], v[16:19]
	v_lshl_add_u64 v[224:225], v[230:231], 0, s[12:13]
	s_mov_b32 m0, s65
	s_nop 0
	global_load_lds_dwordx4 v[224:225], off
	v_mfma_f32_16x16x32_bf16 v[4:7], v[172:175], v[220:223], v[4:7]
	v_mfma_f32_16x16x32_bf16 v[0:3], v[182:185], v[220:223], v[0:3]
	s_setprio 0
	s_barrier
	s_add_i32 s84, s84, 2
	s_add_u32 s54, s54, 0x100
	s_addc_u32 s55, s55, 0
	s_add_u32 s82, s82, 0x100
	s_addc_u32 s83, s83, 0
.LBB0_1119:
	ds_read_b128 v[144:147], v155
	ds_read_b128 v[148:151], v155 offset:1024
	ds_read_b128 v[160:163], v155 offset:2048
	ds_read_b128 v[164:167], v155 offset:3072
	ds_read_b128 v[168:171], v156
	ds_read_b128 v[172:175], v156 offset:1024
	ds_read_b128 v[176:179], v156 offset:2048
	ds_read_b128 v[182:185], v156 offset:3072
	s_add_u32 s56, s54, 0xfffc0080
	s_addc_u32 s57, s55, -1
	s_cmp_eq_u32 s84, 12
	s_cselect_b32 s59, s45, s57
	s_cselect_b32 s58, s76, s56
	s_cselect_b32 s57, s43, s83
	s_cselect_b32 s56, s77, s82
	v_lshl_add_u64 v[224:225], s[54:55], 0, v[136:137]
	s_add_i32 m0, s53, 0xc000
	ds_read_b128 v[186:189], v157
	ds_read_b128 v[190:193], v157 offset:1024
	ds_read_b128 v[194:197], v157 offset:2048
	ds_read_b128 v[198:201], v157 offset:3072
	ds_read_b128 v[208:211], v157 offset:4096
	ds_read_b128 v[212:215], v157 offset:5120
	ds_read_b128 v[216:219], v157 offset:6144
	ds_read_b128 v[220:223], v157 offset:7168
	global_load_lds_dwordx4 v[224:225], off
	v_lshl_add_u64 v[224:225], s[54:55], 0, v[138:139]
	s_add_i32 m0, s53, 0xe000
	s_nop 0
	global_load_lds_dwordx4 v[224:225], off
	s_waitcnt vmcnt(8)
	s_waitcnt lgkmcnt(0)
	s_barrier
; #define PG8_STAGE(bufoff, gbase, voff) do { _Pragma("unroll") for (int _i = 0; _i < 2; ++_i) \
;         __builtin_amdgcn_global_load_lds((const unsigned*)((const char*)(gbase) + (voff)[_i]), (PG8_LAS unsigned*)(lds + (bufoff) + ldsw + _i * 8192), 16, 0, 0); } while (0)
; #define PG8_LDA(dst, b, h) do { _Pragma("unroll") for (int m = 0; m < 4; ++m) _Pragma("unroll") for (int k = 0; k < 2; ++k) dst[m][k] = *(const PG8_LAS bf16x8*)(lds + PG8_SA(b, h) + aoff + m * 2048 + k * 1024); } while (0)
; #define PG8_MMA(ai, bj, At, Bt) do { __builtin_amdgcn_s_setprio(1); _Pragma("unroll") for (int m = 0; m < 4; ++m) _Pragma("unroll") for (int n = 0; n < 2; ++n) _Pragma("unroll") for (int k = 0; k < 2; ++k) \
;         acc[ai][bj][m][n] = __builtin_amdgcn_mfma_f32_16x16x32_bf16(Bt[n][k], At[m][k], acc[ai][bj][m][n], 0, 0, 0); __builtin_amdgcn_s_setprio(0); } while (0)
; #define PG8_WAIT_V(n) asm volatile("s_waitcnt vmcnt(" #n ")" ::: "memory")
; #define PG8_WAIT_L(n) asm volatile("s_waitcnt lgkmcnt(" #n ")" ::: "memory")
; #define PG8_BAR __builtin_amdgcn_s_barrier()
; #define PG8_SCHED __builtin_amdgcn_sched_barrier(0)
; template <class Epi, class Sched, bool ALIGN_EPI = false, bool SP2 = false>
; __device__ __forceinline__ void gemm_phase(PG8_LAS unsigned char* lds, const Gemm g, const Sched& S, const Epi& E) {
;     ...
;             PG8_WAIT_V(8); PG8_WAIT_L(0); PG8_BAR; PG8_MMA(0, 0, At, B0); PG8_MMA(0, 1, At, B1); PG8_BAR; PG8_SCHED;
;             PG8_LDA(At, 0, 1); PG8_STAGE(PG8_SB(0, 0), b2, voffB); PG8_STAGE(PG8_SB(0, 1), b2 + hstep, voffB); PG8_STAGE(PG8_SA(0, 0), a2, voffA);
;             PG8_WAIT_V(8); PG8_WAIT_L(0); PG8_BAR; PG8_MMA(1, 0, At, B0); PG8_MMA(1, 1, At, B1); PG8_BAR; PG8_SCHED;
	s_setprio 1
	s_waitcnt lgkmcnt(0)
	v_mfma_f32_16x16x32_bf16 v[124:127], v[144:147], v[186:189], v[124:127]
	v_mfma_f32_16x16x32_bf16 v[120:123], v[160:163], v[186:189], v[120:123]
	v_mfma_f32_16x16x32_bf16 v[108:111], v[144:147], v[194:197], v[108:111]
	v_mfma_f32_16x16x32_bf16 v[104:107], v[160:163], v[194:197], v[104:107]
	v_mfma_f32_16x16x32_bf16 v[92:95], v[144:147], v[208:211], v[92:95]
	v_mfma_f32_16x16x32_bf16 v[88:91], v[160:163], v[208:211], v[88:91]
	v_mfma_f32_16x16x32_bf16 v[76:79], v[144:147], v[216:219], v[76:79]
	v_mfma_f32_16x16x32_bf16 v[72:75], v[160:163], v[216:219], v[72:75]
	v_mfma_f32_16x16x32_bf16 v[124:127], v[148:151], v[190:193], v[124:127]
	v_mfma_f32_16x16x32_bf16 v[120:123], v[164:167], v[190:193], v[120:123]
	v_mfma_f32_16x16x32_bf16 v[108:111], v[148:151], v[198:201], v[108:111]
	v_mfma_f32_16x16x32_bf16 v[104:107], v[164:167], v[198:201], v[104:107]
	v_mfma_f32_16x16x32_bf16 v[92:95], v[148:151], v[212:215], v[92:95]
	v_mfma_f32_16x16x32_bf16 v[88:91], v[164:167], v[212:215], v[88:91]
	v_mfma_f32_16x16x32_bf16 v[76:79], v[148:151], v[220:223], v[76:79]
	v_mfma_f32_16x16x32_bf16 v[72:75], v[164:167], v[220:223], v[72:75]
	s_setprio 0
	s_setprio 1
	v_mfma_f32_16x16x32_bf16 v[116:119], v[168:171], v[186:189], v[116:119]
	v_mfma_f32_16x16x32_bf16 v[112:115], v[176:179], v[186:189], v[112:115]
	v_mfma_f32_16x16x32_bf16 v[100:103], v[168:171], v[194:197], v[100:103]
	v_mfma_f32_16x16x32_bf16 v[96:99], v[176:179], v[194:197], v[96:99]
	v_mfma_f32_16x16x32_bf16 v[84:87], v[168:171], v[208:211], v[84:87]
	v_mfma_f32_16x16x32_bf16 v[80:83], v[176:179], v[208:211], v[80:83]
	v_mfma_f32_16x16x32_bf16 v[68:71], v[168:171], v[216:219], v[68:71]
	v_mfma_f32_16x16x32_bf16 v[64:67], v[176:179], v[216:219], v[64:67]
	v_mfma_f32_16x16x32_bf16 v[116:119], v[172:175], v[190:193], v[116:119]
	v_mfma_f32_16x16x32_bf16 v[112:115], v[182:185], v[190:193], v[112:115]
	v_mfma_f32_16x16x32_bf16 v[100:103], v[172:175], v[198:201], v[100:103]
	v_mfma_f32_16x16x32_bf16 v[96:99], v[182:185], v[198:201], v[96:99]
	v_mfma_f32_16x16x32_bf16 v[84:87], v[172:175], v[212:215], v[84:87]
	v_mfma_f32_16x16x32_bf16 v[80:83], v[182:185], v[212:215], v[80:83]
	v_mfma_f32_16x16x32_bf16 v[68:71], v[172:175], v[220:223], v[68:71]
	v_mfma_f32_16x16x32_bf16 v[64:67], v[182:185], v[220:223], v[64:67]
	s_setprio 0
	s_barrier
	s_add_i32 s78, s66, s33
	v_lshl_add_u64 v[224:225], s[56:57], 0, v[132:133]
	s_mov_b32 m0, s78
	ds_read_b128 v[186:189], v157 offset:16384
	ds_read_b128 v[190:193], v157 offset:17408
	ds_read_b128 v[194:197], v157 offset:18432
	ds_read_b128 v[198:201], v157 offset:19456
	ds_read_b128 v[208:211], v157 offset:20480
	ds_read_b128 v[212:215], v157 offset:21504
	ds_read_b128 v[216:219], v157 offset:22528
	ds_read_b128 v[220:223], v157 offset:23552
	global_load_lds_dwordx4 v[224:225], off
	s_add_i32 m0, s78, 0x2000
	s_add_u32 s78, s56, 0x40000
	v_lshl_add_u64 v[226:227], s[56:57], 0, v[128:129]
	s_addc_u32 s79, s57, 0
	s_add_i32 s85, s67, s33
	global_load_lds_dwordx4 v[226:227], off
	v_lshl_add_u64 v[228:229], s[78:79], 0, v[132:133]
	s_mov_b32 m0, s85
	global_load_lds_dwordx4 v[228:229], off
	v_lshl_add_u64 v[228:229], s[78:79], 0, v[128:129]
	s_add_i32 m0, s85, 0x2000
	s_nop 0
	global_load_lds_dwordx4 v[228:229], off
	s_waitcnt vmcnt(6)
	s_waitcnt lgkmcnt(0)
	s_barrier
	s_setprio 1
	s_waitcnt lgkmcnt(0)
	v_mfma_f32_16x16x32_bf16 v[60:63], v[144:147], v[186:189], v[60:63]
	v_mfma_f32_16x16x32_bf16 v[56:59], v[160:163], v[186:189], v[56:59]
	v_mfma_f32_16x16x32_bf16 v[44:47], v[144:147], v[194:197], v[44:47]
	v_mfma_f32_16x16x32_bf16 v[40:43], v[160:163], v[194:197], v[40:43]
	v_mfma_f32_16x16x32_bf16 v[28:31], v[144:147], v[208:211], v[28:31]
	v_mfma_f32_16x16x32_bf16 v[24:27], v[160:163], v[208:211], v[24:27]
	v_mfma_f32_16x16x32_bf16 v[12:15], v[144:147], v[216:219], v[12:15]
	v_mfma_f32_16x16x32_bf16 v[8:11], v[160:163], v[216:219], v[8:11]
	v_mfma_f32_16x16x32_bf16 v[60:63], v[148:151], v[190:193], v[60:63]
	v_mfma_f32_16x16x32_bf16 v[56:59], v[164:167], v[190:193], v[56:59]
	v_mfma_f32_16x16x32_bf16 v[44:47], v[148:151], v[198:201], v[44:47]
	v_mfma_f32_16x16x32_bf16 v[40:43], v[164:167], v[198:201], v[40:43]
	v_mfma_f32_16x16x32_bf16 v[28:31], v[148:151], v[212:215], v[28:31]
	v_mfma_f32_16x16x32_bf16 v[24:27], v[164:167], v[212:215], v[24:27]
	v_lshl_add_u64 v[228:229], s[58:59], 0, v[134:135]
	s_mov_b32 m0, s53
	s_nop 0
	global_load_lds_dwordx4 v[228:229], off
	v_mfma_f32_16x16x32_bf16 v[12:15], v[148:151], v[220:223], v[12:15]
	v_mfma_f32_16x16x32_bf16 v[8:11], v[164:167], v[220:223], v[8:11]
	s_setprio 0
	s_setprio 1
	v_mfma_f32_16x16x32_bf16 v[52:55], v[168:171], v[186:189], v[52:55]
	v_mfma_f32_16x16x32_bf16 v[48:51], v[176:179], v[186:189], v[48:51]
	v_mfma_f32_16x16x32_bf16 v[36:39], v[168:171], v[194:197], v[36:39]
	v_mfma_f32_16x16x32_bf16 v[32:35], v[176:179], v[194:197], v[32:35]
	v_mfma_f32_16x16x32_bf16 v[20:23], v[168:171], v[208:211], v[20:23]
	v_mfma_f32_16x16x32_bf16 v[16:19], v[176:179], v[208:211], v[16:19]
	v_mfma_f32_16x16x32_bf16 v[4:7], v[168:171], v[216:219], v[4:7]
	v_mfma_f32_16x16x32_bf16 v[0:3], v[176:179], v[216:219], v[0:3]
	v_mfma_f32_16x16x32_bf16 v[52:55], v[172:175], v[190:193], v[52:55]
	v_mfma_f32_16x16x32_bf16 v[48:51], v[182:185], v[190:193], v[48:51]
	v_mfma_f32_16x16x32_bf16 v[36:39], v[172:175], v[198:201], v[36:39]
	v_mfma_f32_16x16x32_bf16 v[32:35], v[182:185], v[198:201], v[32:35]
	v_mfma_f32_16x16x32_bf16 v[20:23], v[172:175], v[212:215], v[20:23]
	v_mfma_f32_16x16x32_bf16 v[16:19], v[182:185], v[212:215], v[16:19]
	v_lshl_add_u64 v[230:231], s[58:59], 0, v[130:131]
	s_mov_b32 m0, s60
	s_nop 0
	global_load_lds_dwordx4 v[230:231], off
	v_mfma_f32_16x16x32_bf16 v[4:7], v[172:175], v[220:223], v[4:7]
	v_mfma_f32_16x16x32_bf16 v[0:3], v[182:185], v[220:223], v[0:3]
	s_setprio 0
	s_barrier
; #define PG8_STAGE(bufoff, gbase, voff) do { _Pragma("unroll") for (int _i = 0; _i < 2; ++_i) \
;         __builtin_amdgcn_global_load_lds((const unsigned*)((const char*)(gbase) + (voff)[_i]), (PG8_LAS unsigned*)(lds + (bufoff) + ldsw + _i * 8192), 16, 0, 0); } while (0)
; #define PG8_LDA(dst, b, h) do { _Pragma("unroll") for (int m = 0; m < 4; ++m) _Pragma("unroll") for (int k = 0; k < 2; ++k) dst[m][k] = *(const PG8_LAS bf16x8*)(lds + PG8_SA(b, h) + aoff + m * 2048 + k * 1024); } while (0)
; #define PG8_LDB(dst, b, h) do { _Pragma("unroll") for (int n = 0; n < 2; ++n) _Pragma("unroll") for (int k = 0; k < 2; ++k) dst[n][k] = *(const PG8_LAS bf16x8*)(lds + PG8_SB(b, h) + boff + n * 2048 + k * 1024); } while (0)
; #define PG8_MMA(ai, bj, At, Bt) do { __builtin_amdgcn_s_setprio(1); _Pragma("unroll") for (int m = 0; m < 4; ++m) _Pragma("unroll") for (int n = 0; n < 2; ++n) _Pragma("unroll") for (int k = 0; k < 2; ++k) \
;         acc[ai][bj][m][n] = __builtin_amdgcn_mfma_f32_16x16x32_bf16(Bt[n][k], At[m][k], acc[ai][bj][m][n], 0, 0, 0); __builtin_amdgcn_s_setprio(0); } while (0)
; #define PG8_WAIT_V(n) asm volatile("s_waitcnt vmcnt(" #n ")" ::: "memory")
; #define PG8_WAIT_L(n) asm volatile("s_waitcnt lgkmcnt(" #n ")" ::: "memory")
; #define PG8_BAR __builtin_amdgcn_s_barrier()
; #define PG8_SCHED __builtin_amdgcn_sched_barrier(0)
; template <class Epi, class Sched, bool ALIGN_EPI = false, bool SP2 = false>
; __device__ __forceinline__ void gemm_phase(PG8_LAS unsigned char* lds, const Gemm g, const Sched& S, const Epi& E) {
;     ...
;             PG8_LDB(B0, 1, 0); PG8_LDB(B1, 1, 1); PG8_SCHED; PG8_LDA(At, 1, 0); PG8_STAGE(PG8_SA(0, 1), a2 + hstep, voffA);
;             PG8_WAIT_V(8); PG8_WAIT_L(0); PG8_BAR; PG8_MMA(0, 0, At, B0); PG8_MMA(0, 1, At, B1); PG8_BAR; PG8_SCHED;
;             PG8_LDA(At, 1, 1); PG8_STAGE(PG8_SB(1, 0), b3, voffB); PG8_STAGE(PG8_SB(1, 1), b3 + hstep, voffB); PG8_STAGE(PG8_SA(1, 0), a3, voffA);
	s_add_i32 s78, 0, 0x18000
	v_add_u32_e32 v159, s78, v153
	s_add_i32 s79, 0, 0x1c000
	ds_read_b128 v[144:147], v159
	ds_read_b128 v[148:151], v159 offset:1024
	ds_read_b128 v[160:163], v159 offset:2048
	ds_read_b128 v[164:167], v159 offset:3072
	v_add_u32_e32 v159, s79, v153
	ds_read_b128 v[168:171], v159
	ds_read_b128 v[172:175], v159 offset:1024
	ds_read_b128 v[176:179], v159 offset:2048
	ds_read_b128 v[182:185], v159 offset:3072
	s_add_u32 s58, s58, 0x40000
	s_addc_u32 s59, s59, 0
	s_mov_b32 m0, s61
	v_lshl_add_u64 v[232:233], s[58:59], 0, v[134:135]
	ds_read_b128 v[186:189], v157 offset:32768
	ds_read_b128 v[190:193], v157 offset:33792
	ds_read_b128 v[194:197], v157 offset:34816
	ds_read_b128 v[198:201], v157 offset:35840
	ds_read_b128 v[208:211], v157 offset:36864
	ds_read_b128 v[212:215], v157 offset:37888
	ds_read_b128 v[216:219], v157 offset:38912
	ds_read_b128 v[220:223], v157 offset:39936
	global_load_lds_dwordx4 v[232:233], off
	v_lshl_add_u64 v[232:233], s[58:59], 0, v[130:131]
	s_mov_b32 m0, s62
	s_nop 0
	global_load_lds_dwordx4 v[232:233], off
	s_waitcnt vmcnt(8)
	s_waitcnt lgkmcnt(0)
	s_barrier
	s_setprio 1
	s_waitcnt lgkmcnt(0)
	v_mfma_f32_16x16x32_bf16 v[124:127], v[144:147], v[186:189], v[124:127]
	v_mfma_f32_16x16x32_bf16 v[120:123], v[160:163], v[186:189], v[120:123]
	v_mfma_f32_16x16x32_bf16 v[108:111], v[144:147], v[194:197], v[108:111]
	v_mfma_f32_16x16x32_bf16 v[104:107], v[160:163], v[194:197], v[104:107]
	v_mfma_f32_16x16x32_bf16 v[92:95], v[144:147], v[208:211], v[92:95]
	v_mfma_f32_16x16x32_bf16 v[88:91], v[160:163], v[208:211], v[88:91]
	v_mfma_f32_16x16x32_bf16 v[76:79], v[144:147], v[216:219], v[76:79]
	v_mfma_f32_16x16x32_bf16 v[72:75], v[160:163], v[216:219], v[72:75]
	v_mfma_f32_16x16x32_bf16 v[124:127], v[148:151], v[190:193], v[124:127]
	v_mfma_f32_16x16x32_bf16 v[120:123], v[164:167], v[190:193], v[120:123]
	v_mfma_f32_16x16x32_bf16 v[108:111], v[148:151], v[198:201], v[108:111]
	v_mfma_f32_16x16x32_bf16 v[104:107], v[164:167], v[198:201], v[104:107]
	v_mfma_f32_16x16x32_bf16 v[92:95], v[148:151], v[212:215], v[92:95]
	v_mfma_f32_16x16x32_bf16 v[88:91], v[164:167], v[212:215], v[88:91]
	v_mfma_f32_16x16x32_bf16 v[76:79], v[148:151], v[220:223], v[76:79]
	v_mfma_f32_16x16x32_bf16 v[72:75], v[164:167], v[220:223], v[72:75]
	s_setprio 0
	s_setprio 1
	v_mfma_f32_16x16x32_bf16 v[116:119], v[168:171], v[186:189], v[116:119]
	v_mfma_f32_16x16x32_bf16 v[112:115], v[176:179], v[186:189], v[112:115]
	v_mfma_f32_16x16x32_bf16 v[100:103], v[168:171], v[194:197], v[100:103]
	v_mfma_f32_16x16x32_bf16 v[96:99], v[176:179], v[194:197], v[96:99]
	v_mfma_f32_16x16x32_bf16 v[84:87], v[168:171], v[208:211], v[84:87]
	v_mfma_f32_16x16x32_bf16 v[80:83], v[176:179], v[208:211], v[80:83]
	v_mfma_f32_16x16x32_bf16 v[68:71], v[168:171], v[216:219], v[68:71]
	v_mfma_f32_16x16x32_bf16 v[64:67], v[176:179], v[216:219], v[64:67]
	v_mfma_f32_16x16x32_bf16 v[116:119], v[172:175], v[190:193], v[116:119]
	v_mfma_f32_16x16x32_bf16 v[112:115], v[182:185], v[190:193], v[112:115]
	v_mfma_f32_16x16x32_bf16 v[100:103], v[172:175], v[198:201], v[100:103]
	v_mfma_f32_16x16x32_bf16 v[96:99], v[182:185], v[198:201], v[96:99]
	v_mfma_f32_16x16x32_bf16 v[84:87], v[172:175], v[212:215], v[84:87]
	v_mfma_f32_16x16x32_bf16 v[80:83], v[182:185], v[212:215], v[80:83]
	v_mfma_f32_16x16x32_bf16 v[68:71], v[172:175], v[220:223], v[68:71]
	v_mfma_f32_16x16x32_bf16 v[64:67], v[182:185], v[220:223], v[64:67]
	s_setprio 0
	s_barrier
	s_add_i32 s58, s78, s33
	v_lshl_add_u64 v[224:225], v[224:225], 0, s[12:13]
	s_mov_b32 m0, s58
	ds_read_b128 v[186:189], v157 offset:49152
	ds_read_b128 v[190:193], v157 offset:50176
	ds_read_b128 v[194:197], v157 offset:51200
	ds_read_b128 v[198:201], v157 offset:52224
	ds_read_b128 v[208:211], v157 offset:53248
	ds_read_b128 v[212:215], v157 offset:54272
	ds_read_b128 v[216:219], v157 offset:55296
	ds_read_b128 v[220:223], v157 offset:56320
	global_load_lds_dwordx4 v[224:225], off
	s_add_i32 m0, s58, 0x2000
	s_add_u32 s56, s56, 0x40080
	v_lshl_add_u64 v[224:225], v[226:227], 0, s[12:13]
	s_addc_u32 s57, s57, 0
	s_add_i32 s58, s79, s33
	global_load_lds_dwordx4 v[224:225], off
	v_lshl_add_u64 v[224:225], s[56:57], 0, v[132:133]
	s_mov_b32 m0, s58
	s_nop 0
	global_load_lds_dwordx4 v[224:225], off
	v_lshl_add_u64 v[224:225], s[56:57], 0, v[128:129]
	s_add_i32 m0, s58, 0x2000
	s_nop 0
	global_load_lds_dwordx4 v[224:225], off
	s_waitcnt vmcnt(6)
	s_waitcnt lgkmcnt(0)
	s_barrier
; __device__ __forceinline__ unsigned cvtpk(float lo, float hi) { f32x2v_ v = {lo, hi}; bf16x2v_ b = __builtin_convertvector(v, bf16x2v_); return __builtin_bit_cast(unsigned, b); }
; #define PG8_STAGE(bufoff, gbase, voff) do { _Pragma("unroll") for (int _i = 0; _i < 2; ++_i) \
;         __builtin_amdgcn_global_load_lds((const unsigned*)((const char*)(gbase) + (voff)[_i]), (PG8_LAS unsigned*)(lds + (bufoff) + ldsw + _i * 8192), 16, 0, 0); } while (0)
; #define PG8_LDA(dst, b, h) do { _Pragma("unroll") for (int m = 0; m < 4; ++m) _Pragma("unroll") for (int k = 0; k < 2; ++k) dst[m][k] = *(const PG8_LAS bf16x8*)(lds + PG8_SA(b, h) + aoff + m * 2048 + k * 1024); } while (0)
; #define PG8_MMA(ai, bj, At, Bt) do { __builtin_amdgcn_s_setprio(1); _Pragma("unroll") for (int m = 0; m < 4; ++m) _Pragma("unroll") for (int n = 0; n < 2; ++n) _Pragma("unroll") for (int k = 0; k < 2; ++k) \
;         acc[ai][bj][m][n] = __builtin_amdgcn_mfma_f32_16x16x32_bf16(Bt[n][k], At[m][k], acc[ai][bj][m][n], 0, 0, 0); __builtin_amdgcn_s_setprio(0); } while (0)
; #define PG8_WAIT_V(n) asm volatile("s_waitcnt vmcnt(" #n ")" ::: "memory")
;     __device__ __forceinline__ void operator()(const f32x4 (&acc)[2][2][4][2], const Unit& u, int wr, int wc, int fr, int fq) const {
;     ...
;             for (int m = 0; m < 4; ++m) { const int row = row0 + ai * HALF + m * 16; const float rs = row_rs(ss, row);
;                 float hv[8];
; #pragma unroll
;                 for (int n = 0; n < 2; ++n)
; #pragma unroll
;                     for (int i = 0; i < 4; ++i) { const float g = acc[ai][0][m][n][i] * rs, uu = acc[ai][1][m][n][i] * rs;
;                         hv[n * 4 + i] = g * __builtin_amdgcn_rcpf(1.0f + __expf(-g)) * uu; }
;                 u32x4 w; w.x = cvtpk(hv[0], hv[1]); w.y = cvtpk(hv[2], hv[3]); w.z = cvtpk(hv[4], hv[5]); w.w = cvtpk(hv[6], hv[7]);
;                 *(u32x4*)(H + (size_t)row * ldh + col0) = w; }
; template <class Epi, class Sched, bool ALIGN_EPI = false, bool SP2 = false>
; __device__ __forceinline__ void gemm_phase(PG8_LAS unsigned char* lds, const Gemm g, const Sched& S, const Epi& E) {
;     ...
;             PG8_LDA(At, 1, 1); PG8_STAGE(PG8_SB(1, 0), b3, voffB); PG8_STAGE(PG8_SB(1, 1), b3 + hstep, voffB); PG8_STAGE(PG8_SA(1, 0), a3, voffA);
;             PG8_WAIT_V(8); PG8_WAIT_L(0); PG8_BAR; PG8_MMA(1, 0, At, B0); PG8_MMA(1, 1, At, B1); PG8_BAR; PG8_SCHED;
	s_setprio 1
	s_waitcnt lgkmcnt(0)
	v_mfma_f32_16x16x32_bf16 v[60:63], v[144:147], v[186:189], v[60:63]
	v_mfma_f32_16x16x32_bf16 v[56:59], v[160:163], v[186:189], v[56:59]
	v_mfma_f32_16x16x32_bf16 v[44:47], v[144:147], v[194:197], v[44:47]
	v_mfma_f32_16x16x32_bf16 v[40:43], v[160:163], v[194:197], v[40:43]
	v_mfma_f32_16x16x32_bf16 v[28:31], v[144:147], v[208:211], v[28:31]
	v_mfma_f32_16x16x32_bf16 v[24:27], v[160:163], v[208:211], v[24:27]
	v_mfma_f32_16x16x32_bf16 v[12:15], v[144:147], v[216:219], v[12:15]
	v_mfma_f32_16x16x32_bf16 v[8:11], v[160:163], v[216:219], v[8:11]
	v_mfma_f32_16x16x32_bf16 v[60:63], v[148:151], v[190:193], v[60:63]
	v_mfma_f32_16x16x32_bf16 v[56:59], v[164:167], v[190:193], v[56:59]
	v_mfma_f32_16x16x32_bf16 v[44:47], v[148:151], v[198:201], v[44:47]
	v_mfma_f32_16x16x32_bf16 v[40:43], v[164:167], v[198:201], v[40:43]
	v_mfma_f32_16x16x32_bf16 v[28:31], v[148:151], v[212:215], v[28:31]
	v_mfma_f32_16x16x32_bf16 v[24:27], v[164:167], v[212:215], v[24:27]
	v_lshl_add_u64 v[224:225], v[228:229], 0, s[12:13]
	s_mov_b32 m0, s64
	s_nop 0
	global_load_lds_dwordx4 v[224:225], off
	v_mfma_f32_16x16x32_bf16 v[12:15], v[148:151], v[220:223], v[12:15]
	v_mfma_f32_16x16x32_bf16 v[8:11], v[164:167], v[220:223], v[8:11]
	s_setprio 0
	s_setprio 1
	v_mfma_f32_16x16x32_bf16 v[52:55], v[168:171], v[186:189], v[52:55]
	v_mfma_f32_16x16x32_bf16 v[48:51], v[176:179], v[186:189], v[48:51]
	v_mfma_f32_16x16x32_bf16 v[36:39], v[168:171], v[194:197], v[36:39]
	v_mfma_f32_16x16x32_bf16 v[32:35], v[176:179], v[194:197], v[32:35]
	v_mfma_f32_16x16x32_bf16 v[20:23], v[168:171], v[208:211], v[20:23]
	v_mfma_f32_16x16x32_bf16 v[16:19], v[176:179], v[208:211], v[16:19]
	v_mfma_f32_16x16x32_bf16 v[4:7], v[168:171], v[216:219], v[4:7]
	v_mfma_f32_16x16x32_bf16 v[0:3], v[176:179], v[216:219], v[0:3]
	v_mfma_f32_16x16x32_bf16 v[52:55], v[172:175], v[190:193], v[52:55]
	v_mfma_f32_16x16x32_bf16 v[48:51], v[182:185], v[190:193], v[48:51]
	v_mfma_f32_16x16x32_bf16 v[36:39], v[172:175], v[198:201], v[36:39]
	v_mfma_f32_16x16x32_bf16 v[32:35], v[182:185], v[198:201], v[32:35]
	v_mfma_f32_16x16x32_bf16 v[20:23], v[172:175], v[212:215], v[20:23]
	v_mfma_f32_16x16x32_bf16 v[16:19], v[182:185], v[212:215], v[16:19]
	v_lshl_add_u64 v[224:225], v[230:231], 0, s[12:13]
	s_mov_b32 m0, s65
	s_nop 0
	global_load_lds_dwordx4 v[224:225], off
	v_mfma_f32_16x16x32_bf16 v[4:7], v[172:175], v[220:223], v[4:7]
	v_mfma_f32_16x16x32_bf16 v[0:3], v[182:185], v[220:223], v[0:3]
	s_setprio 0
	s_barrier
	s_add_i32 s84, s84, 2
	s_add_u32 s54, s54, 0x100
	s_addc_u32 s55, s55, 0
	s_add_u32 s82, s82, 0x100
	s_addc_u32 s83, s83, 0
	s_cmp_gt_u32 s84, 13
	s_cbranch_scc0 .LBB0_1119
	v_lshl_add_u32 v144, s52, 8, v152
	v_ashrrev_i32_e32 v145, 31, v144
	v_lshl_add_u64 v[150:151], v[144:145], 3, s[36:37]
	global_load_dwordx2 v[182:183], v[150:151], off
	global_load_dwordx2 v[184:185], v[150:151], off offset:128
	global_load_dwordx2 v[186:187], v[150:151], off offset:256
	global_load_dwordx2 v[188:189], v[150:151], off offset:384
	global_load_dwordx2 v[190:191], v[150:151], off offset:1024
	global_load_dwordx2 v[192:193], v[150:151], off offset:1152
	global_load_dwordx2 v[194:195], v[150:151], off offset:1280
	global_load_dwordx2 v[196:197], v[150:151], off offset:1408
	s_and_b64 vcc, exec, s[38:39]
	s_cbranch_vccz .LBB0_1122
.LBB0_1122:
	v_lshl_or_b32 v160, s75, 7, v154
	v_ashrrev_i32_e32 v161, 31, v160
	v_or_b32_e32 v164, 16, v144
	v_ashrrev_i32_e32 v165, 31, v164
	v_lshl_add_u64 v[166:167], v[164:165], 3, s[36:37]
	v_mov_b64_e32 v[146:147], s[20:21]
	v_mad_i64_i32 v[162:163], s[54:55], v144, s74, v[146:147]
	s_andn2_b64 vcc, exec, s[10:11]
	s_mov_b64 s[10:11], -1
	s_waitcnt vmcnt(7)
	v_cvt_f32_u32_e32 v159, v183
	v_cvt_f32_u32_e32 v145, v182
	v_lshlrev_b64 v[148:149], 1, v[160:161]
	v_lshl_add_u64 v[162:163], v[162:163], 0, v[148:149]
	v_fmamk_f32 v145, v145, 0x2f800000, v159
	v_fmamk_f32 v145, v145, 0x3a800000, v158
	v_rsq_f32_e32 v160, v145
	s_nop 0
	v_mul_f32_e32 v182, 0xbfb8aa3b, v160
	v_mul_f32_e32 v183, v160, v160
	v_pk_mul_f32 v[160:161], v[124:125], v[182:183] op_sel_hi:[1,0]
	v_pk_mul_f32 v[168:169], v[126:127], v[182:183] op_sel_hi:[1,0]
	v_pk_mul_f32 v[170:171], v[120:121], v[182:183] op_sel_hi:[1,0]
	v_pk_mul_f32 v[172:173], v[122:123], v[182:183] op_sel_hi:[1,0]
	v_pk_mul_f32 v[116:117], v[116:117], v[124:125]
	v_pk_mul_f32 v[118:119], v[118:119], v[126:127]
	v_pk_mul_f32 v[120:121], v[112:113], v[120:121]
	v_pk_mul_f32 v[122:123], v[114:115], v[122:123]
	v_exp_f32_e32 v160, v160
	v_exp_f32_e32 v161, v161
	v_exp_f32_e32 v168, v168
	v_exp_f32_e32 v169, v169
	v_exp_f32_e32 v170, v170
	v_exp_f32_e32 v171, v171
	v_exp_f32_e32 v172, v172
	v_exp_f32_e32 v173, v173
	v_pk_mul_f32 v[116:117], v[116:117], v[182:183] op_sel:[0,1] op_sel_hi:[1,1]
	v_pk_mul_f32 v[118:119], v[118:119], v[182:183] op_sel:[0,1] op_sel_hi:[1,1]
	v_pk_mul_f32 v[120:121], v[120:121], v[182:183] op_sel:[0,1] op_sel_hi:[1,1]
	v_pk_mul_f32 v[122:123], v[122:123], v[182:183] op_sel:[0,1] op_sel_hi:[1,1]
	v_pk_add_f32 v[160:161], v[160:161], 1.0 op_sel_hi:[1,0]
	v_pk_add_f32 v[168:169], v[168:169], 1.0 op_sel_hi:[1,0]
	v_pk_add_f32 v[170:171], v[170:171], 1.0 op_sel_hi:[1,0]
	v_pk_add_f32 v[172:173], v[172:173], 1.0 op_sel_hi:[1,0]
	v_rcp_f32_e32 v160, v160
	v_rcp_f32_e32 v161, v161
	v_rcp_f32_e32 v168, v168
	v_rcp_f32_e32 v169, v169
	v_rcp_f32_e32 v170, v170
	v_rcp_f32_e32 v171, v171
	v_rcp_f32_e32 v172, v172
	v_rcp_f32_e32 v173, v173
	v_pk_mul_f32 v[116:117], v[116:117], v[160:161]
	v_pk_mul_f32 v[118:119], v[118:119], v[168:169]
	v_pk_mul_f32 v[120:121], v[120:121], v[170:171]
	v_pk_mul_f32 v[122:123], v[122:123], v[172:173]
	v_cvt_pk_bf16_f32 v112, v116, v117
	v_cvt_pk_bf16_f32 v113, v118, v119
	v_cvt_pk_bf16_f32 v114, v120, v121
	v_cvt_pk_bf16_f32 v115, v122, v123
	global_store_dwordx4 v[162:163], v[112:115], off
	s_nop 0
	s_nop 0
	v_or_b32_e32 v114, 32, v144
	s_waitcnt vmcnt(7)
; __device__ __forceinline__ unsigned cvtpk(float lo, float hi) { f32x2v_ v = {lo, hi}; bf16x2v_ b = __builtin_convertvector(v, bf16x2v_); return __builtin_bit_cast(unsigned, b); }
;     __device__ __forceinline__ void operator()(const f32x4 (&acc)[2][2][4][2], const Unit& u, int wr, int wc, int fr, int fq) const {
;     ...
;             for (int m = 0; m < 4; ++m) { const int row = row0 + ai * HALF + m * 16; const float rs = row_rs(ss, row);
;                 float hv[8];
; #pragma unroll
;                 for (int n = 0; n < 2; ++n)
; #pragma unroll
;                     for (int i = 0; i < 4; ++i) { const float g = acc[ai][0][m][n][i] * rs, uu = acc[ai][1][m][n][i] * rs;
;                         hv[n * 4 + i] = g * __builtin_amdgcn_rcpf(1.0f + __expf(-g)) * uu; }
;                 u32x4 w; w.x = cvtpk(hv[0], hv[1]); w.y = cvtpk(hv[2], hv[3]); w.z = cvtpk(hv[4], hv[5]); w.w = cvtpk(hv[6], hv[7]);
;                 *(u32x4*)(H + (size_t)row * ldh + col0) = w; }
	v_cvt_f32_u32_e32 v116, v185
	v_cvt_f32_u32_e32 v115, v184
	v_mad_i64_i32 v[112:113], s[54:55], v164, s74, v[146:147]
	v_fmamk_f32 v115, v115, 0x2f800000, v116
	v_fmamk_f32 v115, v115, 0x3a800000, v158
	v_rsq_f32_e32 v116, v115
	v_ashrrev_i32_e32 v115, 31, v114
	v_lshl_add_u64 v[118:119], v[114:115], 3, s[36:37]
	v_lshl_add_u64 v[112:113], v[112:113], 0, v[148:149]
	v_mul_f32_e32 v184, 0xbfb8aa3b, v116
	v_mul_f32_e32 v185, v116, v116
	v_pk_mul_f32 v[116:117], v[108:109], v[184:185] op_sel_hi:[1,0]
	v_pk_mul_f32 v[120:121], v[110:111], v[184:185] op_sel_hi:[1,0]
	v_pk_mul_f32 v[122:123], v[104:105], v[184:185] op_sel_hi:[1,0]
	v_pk_mul_f32 v[124:125], v[106:107], v[184:185] op_sel_hi:[1,0]
	v_pk_mul_f32 v[100:101], v[100:101], v[108:109]
	v_pk_mul_f32 v[102:103], v[102:103], v[110:111]
	v_pk_mul_f32 v[104:105], v[96:97], v[104:105]
	v_pk_mul_f32 v[106:107], v[98:99], v[106:107]
	v_exp_f32_e32 v116, v116
	v_exp_f32_e32 v117, v117
	v_exp_f32_e32 v120, v120
	v_exp_f32_e32 v121, v121
	v_exp_f32_e32 v122, v122
	v_exp_f32_e32 v123, v123
	v_exp_f32_e32 v124, v124
	v_exp_f32_e32 v125, v125
	v_pk_mul_f32 v[100:101], v[100:101], v[184:185] op_sel:[0,1] op_sel_hi:[1,1]
	v_pk_mul_f32 v[102:103], v[102:103], v[184:185] op_sel:[0,1] op_sel_hi:[1,1]
	v_pk_mul_f32 v[104:105], v[104:105], v[184:185] op_sel:[0,1] op_sel_hi:[1,1]
	v_pk_mul_f32 v[106:107], v[106:107], v[184:185] op_sel:[0,1] op_sel_hi:[1,1]
	v_pk_add_f32 v[116:117], v[116:117], 1.0 op_sel_hi:[1,0]
	v_pk_add_f32 v[120:121], v[120:121], 1.0 op_sel_hi:[1,0]
	v_pk_add_f32 v[122:123], v[122:123], 1.0 op_sel_hi:[1,0]
	v_pk_add_f32 v[124:125], v[124:125], 1.0 op_sel_hi:[1,0]
	v_rcp_f32_e32 v116, v116
	v_rcp_f32_e32 v117, v117
	v_rcp_f32_e32 v120, v120
	v_rcp_f32_e32 v121, v121
	v_rcp_f32_e32 v122, v122
	v_rcp_f32_e32 v123, v123
	v_rcp_f32_e32 v124, v124
	v_rcp_f32_e32 v125, v125
	v_pk_mul_f32 v[100:101], v[100:101], v[116:117]
	v_pk_mul_f32 v[102:103], v[102:103], v[120:121]
	v_pk_mul_f32 v[104:105], v[104:105], v[122:123]
	v_pk_mul_f32 v[106:107], v[106:107], v[124:125]
	v_cvt_pk_bf16_f32 v96, v100, v101
	v_cvt_pk_bf16_f32 v97, v102, v103
	v_cvt_pk_bf16_f32 v98, v104, v105
	v_cvt_pk_bf16_f32 v99, v106, v107
	global_store_dwordx4 v[112:113], v[96:99], off
	s_nop 0
	s_nop 0
	v_or_b32_e32 v98, 48, v144
	s_waitcnt vmcnt(7)
	v_cvt_f32_u32_e32 v100, v187
	v_cvt_f32_u32_e32 v99, v186
	v_mad_i64_i32 v[96:97], s[54:55], v114, s74, v[146:147]
	v_fmamk_f32 v99, v99, 0x2f800000, v100
	v_fmamk_f32 v99, v99, 0x3a800000, v158
	v_rsq_f32_e32 v100, v99
	v_ashrrev_i32_e32 v99, 31, v98
	v_lshl_add_u64 v[102:103], v[98:99], 3, s[36:37]
	v_lshl_add_u64 v[96:97], v[96:97], 0, v[148:149]
	v_mul_f32_e32 v186, 0xbfb8aa3b, v100
	v_mul_f32_e32 v187, v100, v100
	v_pk_mul_f32 v[100:101], v[92:93], v[186:187] op_sel_hi:[1,0]
	v_pk_mul_f32 v[104:105], v[94:95], v[186:187] op_sel_hi:[1,0]
	v_pk_mul_f32 v[106:107], v[88:89], v[186:187] op_sel_hi:[1,0]
	v_pk_mul_f32 v[108:109], v[90:91], v[186:187] op_sel_hi:[1,0]
	v_pk_mul_f32 v[84:85], v[84:85], v[92:93]
	v_pk_mul_f32 v[86:87], v[86:87], v[94:95]
	v_pk_mul_f32 v[88:89], v[80:81], v[88:89]
	v_pk_mul_f32 v[90:91], v[82:83], v[90:91]
	v_exp_f32_e32 v100, v100
	v_exp_f32_e32 v101, v101
	v_exp_f32_e32 v104, v104
	v_exp_f32_e32 v105, v105
	v_exp_f32_e32 v106, v106
	v_exp_f32_e32 v107, v107
	v_exp_f32_e32 v108, v108
	v_exp_f32_e32 v109, v109
	v_pk_mul_f32 v[84:85], v[84:85], v[186:187] op_sel:[0,1] op_sel_hi:[1,1]
	v_pk_mul_f32 v[86:87], v[86:87], v[186:187] op_sel:[0,1] op_sel_hi:[1,1]
	v_pk_mul_f32 v[88:89], v[88:89], v[186:187] op_sel:[0,1] op_sel_hi:[1,1]
	v_pk_mul_f32 v[90:91], v[90:91], v[186:187] op_sel:[0,1] op_sel_hi:[1,1]
	v_pk_add_f32 v[100:101], v[100:101], 1.0 op_sel_hi:[1,0]
	v_pk_add_f32 v[104:105], v[104:105], 1.0 op_sel_hi:[1,0]
	v_pk_add_f32 v[106:107], v[106:107], 1.0 op_sel_hi:[1,0]
	v_pk_add_f32 v[108:109], v[108:109], 1.0 op_sel_hi:[1,0]
	v_rcp_f32_e32 v100, v100
	v_rcp_f32_e32 v101, v101
	v_rcp_f32_e32 v104, v104
	v_rcp_f32_e32 v105, v105
	v_rcp_f32_e32 v106, v106
	v_rcp_f32_e32 v107, v107
	v_rcp_f32_e32 v108, v108
	v_rcp_f32_e32 v109, v109
	v_pk_mul_f32 v[84:85], v[84:85], v[100:101]
	v_pk_mul_f32 v[86:87], v[86:87], v[104:105]
	v_pk_mul_f32 v[88:89], v[88:89], v[106:107]
	v_pk_mul_f32 v[90:91], v[90:91], v[108:109]
	v_cvt_pk_bf16_f32 v80, v84, v85
	v_cvt_pk_bf16_f32 v81, v86, v87
	v_cvt_pk_bf16_f32 v82, v88, v89
	v_cvt_pk_bf16_f32 v83, v90, v91
	global_store_dwordx4 v[96:97], v[80:83], off
	s_nop 0
	s_waitcnt vmcnt(7)
	v_cvt_f32_u32_e32 v80, v189
	v_cvt_f32_u32_e32 v81, v188
	v_mad_i64_i32 v[82:83], s[54:55], v98, s74, v[146:147]
	v_fmamk_f32 v80, v81, 0x2f800000, v80
	v_fmamk_f32 v80, v80, 0x3a800000, v158
	v_rsq_f32_e32 v80, v80
	v_lshl_add_u64 v[82:83], v[82:83], 0, v[148:149]
	v_mul_f32_e32 v188, 0xbfb8aa3b, v80
	v_mul_f32_e32 v189, v80, v80
	v_pk_mul_f32 v[80:81], v[76:77], v[188:189] op_sel_hi:[1,0]
	v_pk_mul_f32 v[84:85], v[78:79], v[188:189] op_sel_hi:[1,0]
	v_pk_mul_f32 v[86:87], v[72:73], v[188:189] op_sel_hi:[1,0]
	v_pk_mul_f32 v[88:89], v[74:75], v[188:189] op_sel_hi:[1,0]
	v_pk_mul_f32 v[68:69], v[68:69], v[76:77]
	v_pk_mul_f32 v[70:71], v[70:71], v[78:79]
	v_pk_mul_f32 v[72:73], v[64:65], v[72:73]
	v_pk_mul_f32 v[74:75], v[66:67], v[74:75]
	v_exp_f32_e32 v80, v80
	v_exp_f32_e32 v81, v81
	v_exp_f32_e32 v84, v84
	v_exp_f32_e32 v85, v85
	v_exp_f32_e32 v86, v86
	v_exp_f32_e32 v87, v87
	v_exp_f32_e32 v88, v88
	v_exp_f32_e32 v89, v89
	v_pk_mul_f32 v[68:69], v[68:69], v[188:189] op_sel:[0,1] op_sel_hi:[1,1]
	v_pk_mul_f32 v[70:71], v[70:71], v[188:189] op_sel:[0,1] op_sel_hi:[1,1]
	v_pk_mul_f32 v[72:73], v[72:73], v[188:189] op_sel:[0,1] op_sel_hi:[1,1]
	v_pk_mul_f32 v[74:75], v[74:75], v[188:189] op_sel:[0,1] op_sel_hi:[1,1]
	v_pk_add_f32 v[80:81], v[80:81], 1.0 op_sel_hi:[1,0]
	v_pk_add_f32 v[84:85], v[84:85], 1.0 op_sel_hi:[1,0]
	v_pk_add_f32 v[86:87], v[86:87], 1.0 op_sel_hi:[1,0]
	v_pk_add_f32 v[88:89], v[88:89], 1.0 op_sel_hi:[1,0]
	v_rcp_f32_e32 v80, v80
	v_rcp_f32_e32 v81, v81
	v_rcp_f32_e32 v84, v84
	v_rcp_f32_e32 v85, v85
	v_rcp_f32_e32 v86, v86
	v_rcp_f32_e32 v87, v87
	v_rcp_f32_e32 v88, v88
	v_rcp_f32_e32 v89, v89
	v_pk_mul_f32 v[68:69], v[68:69], v[80:81]
	v_pk_mul_f32 v[70:71], v[70:71], v[84:85]
	v_pk_mul_f32 v[72:73], v[72:73], v[86:87]
	v_pk_mul_f32 v[74:75], v[74:75], v[88:89]
	v_cvt_pk_bf16_f32 v64, v68, v69
	v_cvt_pk_bf16_f32 v65, v70, v71
	v_cvt_pk_bf16_f32 v66, v72, v73
	v_cvt_pk_bf16_f32 v67, v74, v75
	global_store_dwordx4 v[82:83], v[64:67], off
	s_nop 0
	s_waitcnt vmcnt(7)
; __device__ __forceinline__ unsigned cvtpk(float lo, float hi) { f32x2v_ v = {lo, hi}; bf16x2v_ b = __builtin_convertvector(v, bf16x2v_); return __builtin_bit_cast(unsigned, b); }
;     __device__ __forceinline__ void operator()(const f32x4 (&acc)[2][2][4][2], const Unit& u, int wr, int wc, int fr, int fq) const {
;     ...
;             for (int m = 0; m < 4; ++m) { const int row = row0 + ai * HALF + m * 16; const float rs = row_rs(ss, row);
;                 float hv[8];
; #pragma unroll
;                 for (int n = 0; n < 2; ++n)
; #pragma unroll
;                     for (int i = 0; i < 4; ++i) { const float g = acc[ai][0][m][n][i] * rs, uu = acc[ai][1][m][n][i] * rs;
;                         hv[n * 4 + i] = g * __builtin_amdgcn_rcpf(1.0f + __expf(-g)) * uu; }
;                 u32x4 w; w.x = cvtpk(hv[0], hv[1]); w.y = cvtpk(hv[2], hv[3]); w.z = cvtpk(hv[4], hv[5]); w.w = cvtpk(hv[6], hv[7]);
;                 *(u32x4*)(H + (size_t)row * ldh + col0) = w; }
	v_cvt_f32_u32_e32 v64, v191
	v_cvt_f32_u32_e32 v66, v190
	v_add_u32_e32 v65, 0x80, v144
	v_fmamk_f32 v64, v66, 0x2f800000, v64
	v_fmamk_f32 v64, v64, 0x3a800000, v158
	v_rsq_f32_e32 v64, v64
	v_mad_i64_i32 v[66:67], s[54:55], v65, s74, v[146:147]
	v_lshl_add_u64 v[66:67], v[66:67], 0, v[148:149]
	v_mul_f32_e32 v190, 0xbfb8aa3b, v64
	v_mul_f32_e32 v191, v64, v64
	v_pk_mul_f32 v[64:65], v[60:61], v[190:191] op_sel_hi:[1,0]
	v_pk_mul_f32 v[68:69], v[62:63], v[190:191] op_sel_hi:[1,0]
	v_pk_mul_f32 v[70:71], v[56:57], v[190:191] op_sel_hi:[1,0]
	v_pk_mul_f32 v[72:73], v[58:59], v[190:191] op_sel_hi:[1,0]
	v_pk_mul_f32 v[52:53], v[52:53], v[60:61]
	v_pk_mul_f32 v[54:55], v[54:55], v[62:63]
	v_pk_mul_f32 v[56:57], v[48:49], v[56:57]
	v_pk_mul_f32 v[58:59], v[50:51], v[58:59]
	v_exp_f32_e32 v64, v64
	v_exp_f32_e32 v65, v65
	v_exp_f32_e32 v68, v68
	v_exp_f32_e32 v69, v69
	v_exp_f32_e32 v70, v70
	v_exp_f32_e32 v71, v71
	v_exp_f32_e32 v72, v72
	v_exp_f32_e32 v73, v73
	v_pk_mul_f32 v[52:53], v[52:53], v[190:191] op_sel:[0,1] op_sel_hi:[1,1]
	v_pk_mul_f32 v[54:55], v[54:55], v[190:191] op_sel:[0,1] op_sel_hi:[1,1]
	v_pk_mul_f32 v[56:57], v[56:57], v[190:191] op_sel:[0,1] op_sel_hi:[1,1]
	v_pk_mul_f32 v[58:59], v[58:59], v[190:191] op_sel:[0,1] op_sel_hi:[1,1]
	v_pk_add_f32 v[64:65], v[64:65], 1.0 op_sel_hi:[1,0]
	v_pk_add_f32 v[68:69], v[68:69], 1.0 op_sel_hi:[1,0]
	v_pk_add_f32 v[70:71], v[70:71], 1.0 op_sel_hi:[1,0]
	v_pk_add_f32 v[72:73], v[72:73], 1.0 op_sel_hi:[1,0]
	v_rcp_f32_e32 v64, v64
	v_rcp_f32_e32 v65, v65
	v_rcp_f32_e32 v68, v68
	v_rcp_f32_e32 v69, v69
	v_rcp_f32_e32 v70, v70
	v_rcp_f32_e32 v71, v71
	v_rcp_f32_e32 v72, v72
	v_rcp_f32_e32 v73, v73
	v_pk_mul_f32 v[52:53], v[52:53], v[64:65]
	v_pk_mul_f32 v[54:55], v[54:55], v[68:69]
	v_pk_mul_f32 v[56:57], v[56:57], v[70:71]
	v_pk_mul_f32 v[58:59], v[58:59], v[72:73]
	v_cvt_pk_bf16_f32 v48, v52, v53
	v_cvt_pk_bf16_f32 v49, v54, v55
	v_cvt_pk_bf16_f32 v50, v56, v57
	v_cvt_pk_bf16_f32 v51, v58, v59
	global_store_dwordx4 v[66:67], v[48:51], off
	s_nop 0
	s_waitcnt vmcnt(7)
	v_cvt_f32_u32_e32 v48, v193
	v_cvt_f32_u32_e32 v50, v192
	v_add_u32_e32 v49, 0x90, v144
	v_fmamk_f32 v48, v50, 0x2f800000, v48
	v_fmamk_f32 v48, v48, 0x3a800000, v158
	v_rsq_f32_e32 v48, v48
	v_mad_i64_i32 v[50:51], s[54:55], v49, s74, v[146:147]
	v_lshl_add_u64 v[50:51], v[50:51], 0, v[148:149]
	v_mul_f32_e32 v192, 0xbfb8aa3b, v48
	v_mul_f32_e32 v193, v48, v48
	v_pk_mul_f32 v[48:49], v[44:45], v[192:193] op_sel_hi:[1,0]
	v_pk_mul_f32 v[52:53], v[46:47], v[192:193] op_sel_hi:[1,0]
	v_pk_mul_f32 v[54:55], v[40:41], v[192:193] op_sel_hi:[1,0]
	v_pk_mul_f32 v[56:57], v[42:43], v[192:193] op_sel_hi:[1,0]
	v_pk_mul_f32 v[36:37], v[36:37], v[44:45]
	v_pk_mul_f32 v[38:39], v[38:39], v[46:47]
	v_pk_mul_f32 v[40:41], v[32:33], v[40:41]
	v_pk_mul_f32 v[42:43], v[34:35], v[42:43]
	v_exp_f32_e32 v48, v48
	v_exp_f32_e32 v49, v49
	v_exp_f32_e32 v52, v52
	v_exp_f32_e32 v53, v53
	v_exp_f32_e32 v54, v54
	v_exp_f32_e32 v55, v55
	v_exp_f32_e32 v56, v56
	v_exp_f32_e32 v57, v57
	v_pk_mul_f32 v[36:37], v[36:37], v[192:193] op_sel:[0,1] op_sel_hi:[1,1]
	v_pk_mul_f32 v[38:39], v[38:39], v[192:193] op_sel:[0,1] op_sel_hi:[1,1]
	v_pk_mul_f32 v[40:41], v[40:41], v[192:193] op_sel:[0,1] op_sel_hi:[1,1]
	v_pk_mul_f32 v[42:43], v[42:43], v[192:193] op_sel:[0,1] op_sel_hi:[1,1]
	v_pk_add_f32 v[48:49], v[48:49], 1.0 op_sel_hi:[1,0]
	v_pk_add_f32 v[52:53], v[52:53], 1.0 op_sel_hi:[1,0]
	v_pk_add_f32 v[54:55], v[54:55], 1.0 op_sel_hi:[1,0]
	v_pk_add_f32 v[56:57], v[56:57], 1.0 op_sel_hi:[1,0]
	v_rcp_f32_e32 v48, v48
	v_rcp_f32_e32 v49, v49
	v_rcp_f32_e32 v52, v52
	v_rcp_f32_e32 v53, v53
	v_rcp_f32_e32 v54, v54
	v_rcp_f32_e32 v55, v55
	v_rcp_f32_e32 v56, v56
	v_rcp_f32_e32 v57, v57
	v_pk_mul_f32 v[36:37], v[36:37], v[48:49]
	v_pk_mul_f32 v[38:39], v[38:39], v[52:53]
	v_pk_mul_f32 v[40:41], v[40:41], v[54:55]
	v_pk_mul_f32 v[42:43], v[42:43], v[56:57]
	v_cvt_pk_bf16_f32 v32, v36, v37
	v_cvt_pk_bf16_f32 v33, v38, v39
	v_cvt_pk_bf16_f32 v34, v40, v41
	v_cvt_pk_bf16_f32 v35, v42, v43
	global_store_dwordx4 v[50:51], v[32:35], off
	s_nop 0
	s_waitcnt vmcnt(7)
; __device__ __forceinline__ unsigned cvtpk(float lo, float hi) { f32x2v_ v = {lo, hi}; bf16x2v_ b = __builtin_convertvector(v, bf16x2v_); return __builtin_bit_cast(unsigned, b); }
; #define PG8_BAR __builtin_amdgcn_s_barrier()
;     __device__ __forceinline__ void operator()(const f32x4 (&acc)[2][2][4][2], const Unit& u, int wr, int wc, int fr, int fq) const {
;     ...
;             for (int m = 0; m < 4; ++m) { const int row = row0 + ai * HALF + m * 16; const float rs = row_rs(ss, row);
;                 float hv[8];
; #pragma unroll
;                 for (int n = 0; n < 2; ++n)
; #pragma unroll
;                     for (int i = 0; i < 4; ++i) { const float g = acc[ai][0][m][n][i] * rs, uu = acc[ai][1][m][n][i] * rs;
;                         hv[n * 4 + i] = g * __builtin_amdgcn_rcpf(1.0f + __expf(-g)) * uu; }
;                 u32x4 w; w.x = cvtpk(hv[0], hv[1]); w.y = cvtpk(hv[2], hv[3]); w.z = cvtpk(hv[4], hv[5]); w.w = cvtpk(hv[6], hv[7]);
;                 *(u32x4*)(H + (size_t)row * ldh + col0) = w; }
; template <class Epi, class Sched, bool ALIGN_EPI = false, bool SP2 = false>
; __device__ __forceinline__ void gemm_phase(PG8_LAS unsigned char* lds, const Gemm g, const Sched& S, const Epi& E) {
;     ...
;         if constexpr (ALIGN_EPI) { if (wr == 0) PG8_BAR; }
;         if constexpr (!Epi::AFTER_DRAIN) { E(acc, cur, wr, wc, fr, fq); S.done(cur); }
	v_cvt_f32_u32_e32 v32, v195
	v_cvt_f32_u32_e32 v34, v194
	v_add_u32_e32 v33, 0xa0, v144
	v_fmamk_f32 v32, v34, 0x2f800000, v32
	v_fmamk_f32 v32, v32, 0x3a800000, v158
	v_rsq_f32_e32 v32, v32
	v_mad_i64_i32 v[34:35], s[54:55], v33, s74, v[146:147]
	v_lshl_add_u64 v[34:35], v[34:35], 0, v[148:149]
	v_mul_f32_e32 v194, 0xbfb8aa3b, v32
	v_mul_f32_e32 v195, v32, v32
	v_pk_mul_f32 v[32:33], v[28:29], v[194:195] op_sel_hi:[1,0]
	v_pk_mul_f32 v[36:37], v[30:31], v[194:195] op_sel_hi:[1,0]
	v_pk_mul_f32 v[38:39], v[24:25], v[194:195] op_sel_hi:[1,0]
	v_pk_mul_f32 v[40:41], v[26:27], v[194:195] op_sel_hi:[1,0]
	v_pk_mul_f32 v[20:21], v[20:21], v[28:29]
	v_pk_mul_f32 v[22:23], v[22:23], v[30:31]
	v_pk_mul_f32 v[24:25], v[16:17], v[24:25]
	v_pk_mul_f32 v[26:27], v[18:19], v[26:27]
	v_exp_f32_e32 v32, v32
	v_exp_f32_e32 v33, v33
	v_exp_f32_e32 v36, v36
	v_exp_f32_e32 v37, v37
	v_exp_f32_e32 v38, v38
	v_exp_f32_e32 v39, v39
	v_exp_f32_e32 v40, v40
	v_exp_f32_e32 v41, v41
	v_pk_mul_f32 v[20:21], v[20:21], v[194:195] op_sel:[0,1] op_sel_hi:[1,1]
	v_pk_mul_f32 v[22:23], v[22:23], v[194:195] op_sel:[0,1] op_sel_hi:[1,1]
	v_pk_mul_f32 v[24:25], v[24:25], v[194:195] op_sel:[0,1] op_sel_hi:[1,1]
	v_pk_mul_f32 v[26:27], v[26:27], v[194:195] op_sel:[0,1] op_sel_hi:[1,1]
	v_pk_add_f32 v[32:33], v[32:33], 1.0 op_sel_hi:[1,0]
	v_pk_add_f32 v[36:37], v[36:37], 1.0 op_sel_hi:[1,0]
	v_pk_add_f32 v[38:39], v[38:39], 1.0 op_sel_hi:[1,0]
	v_pk_add_f32 v[40:41], v[40:41], 1.0 op_sel_hi:[1,0]
	v_rcp_f32_e32 v32, v32
	v_rcp_f32_e32 v33, v33
	v_rcp_f32_e32 v36, v36
	v_rcp_f32_e32 v37, v37
	v_rcp_f32_e32 v38, v38
	v_rcp_f32_e32 v39, v39
	v_rcp_f32_e32 v40, v40
	v_rcp_f32_e32 v41, v41
	v_pk_mul_f32 v[20:21], v[20:21], v[32:33]
	v_pk_mul_f32 v[22:23], v[22:23], v[36:37]
	v_pk_mul_f32 v[24:25], v[24:25], v[38:39]
	v_pk_mul_f32 v[26:27], v[26:27], v[40:41]
	v_cvt_pk_bf16_f32 v16, v20, v21
	v_cvt_pk_bf16_f32 v17, v22, v23
	v_cvt_pk_bf16_f32 v18, v24, v25
	v_cvt_pk_bf16_f32 v19, v26, v27
	global_store_dwordx4 v[34:35], v[16:19], off
	s_nop 0
	s_waitcnt vmcnt(7)
	v_cvt_f32_u32_e32 v16, v197
	v_cvt_f32_u32_e32 v18, v196
	v_add_u32_e32 v17, 0xb0, v144
	v_fmamk_f32 v16, v18, 0x2f800000, v16
	v_fmamk_f32 v16, v16, 0x3a800000, v158
	v_rsq_f32_e32 v16, v16
	v_mad_i64_i32 v[18:19], s[54:55], v17, s74, v[146:147]
	v_lshl_add_u64 v[18:19], v[18:19], 0, v[148:149]
	v_mul_f32_e32 v196, 0xbfb8aa3b, v16
	v_mul_f32_e32 v197, v16, v16
	v_pk_mul_f32 v[16:17], v[12:13], v[196:197] op_sel_hi:[1,0]
	v_pk_mul_f32 v[20:21], v[14:15], v[196:197] op_sel_hi:[1,0]
	v_pk_mul_f32 v[22:23], v[8:9], v[196:197] op_sel_hi:[1,0]
	v_pk_mul_f32 v[24:25], v[10:11], v[196:197] op_sel_hi:[1,0]
	v_pk_mul_f32 v[4:5], v[4:5], v[12:13]
	v_pk_mul_f32 v[6:7], v[6:7], v[14:15]
	v_pk_mul_f32 v[8:9], v[0:1], v[8:9]
	v_pk_mul_f32 v[10:11], v[2:3], v[10:11]
	v_exp_f32_e32 v16, v16
	v_exp_f32_e32 v17, v17
	v_exp_f32_e32 v20, v20
	v_exp_f32_e32 v21, v21
	v_exp_f32_e32 v22, v22
	v_exp_f32_e32 v23, v23
	v_exp_f32_e32 v24, v24
	v_exp_f32_e32 v25, v25
	v_pk_mul_f32 v[4:5], v[4:5], v[196:197] op_sel:[0,1] op_sel_hi:[1,1]
	v_pk_mul_f32 v[6:7], v[6:7], v[196:197] op_sel:[0,1] op_sel_hi:[1,1]
	v_pk_mul_f32 v[8:9], v[8:9], v[196:197] op_sel:[0,1] op_sel_hi:[1,1]
	v_pk_mul_f32 v[10:11], v[10:11], v[196:197] op_sel:[0,1] op_sel_hi:[1,1]
	v_pk_add_f32 v[16:17], v[16:17], 1.0 op_sel_hi:[1,0]
	v_pk_add_f32 v[20:21], v[20:21], 1.0 op_sel_hi:[1,0]
	v_pk_add_f32 v[22:23], v[22:23], 1.0 op_sel_hi:[1,0]
	v_pk_add_f32 v[24:25], v[24:25], 1.0 op_sel_hi:[1,0]
	v_rcp_f32_e32 v16, v16
	v_rcp_f32_e32 v17, v17
	v_rcp_f32_e32 v20, v20
	v_rcp_f32_e32 v21, v21
	v_rcp_f32_e32 v22, v22
	v_rcp_f32_e32 v23, v23
	v_rcp_f32_e32 v24, v24
	v_rcp_f32_e32 v25, v25
	v_pk_mul_f32 v[4:5], v[4:5], v[16:17]
	v_pk_mul_f32 v[6:7], v[6:7], v[20:21]
	v_pk_mul_f32 v[8:9], v[8:9], v[22:23]
	v_pk_mul_f32 v[10:11], v[10:11], v[24:25]
	v_cvt_pk_bf16_f32 v0, v4, v5
	v_cvt_pk_bf16_f32 v1, v6, v7
	v_cvt_pk_bf16_f32 v2, v8, v9
	v_cvt_pk_bf16_f32 v3, v10, v11
	global_store_dwordx4 v[18:19], v[0:3], off
	s_cmp_eq_u64 s[38:39], 0
	s_cbranch_scc1 .Lxpost_7
	s_barrier

; #define PG8_STAGE(bufoff, gbase, voff) do { _Pragma("unroll") for (int _i = 0; _i < 2; ++_i) \
;         __builtin_amdgcn_global_load_lds((const unsigned*)((const char*)(gbase) + (voff)[_i]), (PG8_LAS unsigned*)(lds + (bufoff) + ldsw + _i * 8192), 16, 0, 0); } while (0)
; #define PG8_LDA(dst, b, h) do { _Pragma("unroll") for (int m = 0; m < 4; ++m) _Pragma("unroll") for (int k = 0; k < 2; ++k) dst[m][k] = *(const PG8_LAS bf16x8*)(lds + PG8_SA(b, h) + aoff + m * 2048 + k * 1024); } while (0)
; #define PG8_LDB(dst, b, h) do { _Pragma("unroll") for (int n = 0; n < 2; ++n) _Pragma("unroll") for (int k = 0; k < 2; ++k) dst[n][k] = *(const PG8_LAS bf16x8*)(lds + PG8_SB(b, h) + boff + n * 2048 + k * 1024); } while (0)
; #define PG8_MMA(ai, bj, At, Bt) do { __builtin_amdgcn_s_setprio(1); _Pragma("unroll") for (int m = 0; m < 4; ++m) _Pragma("unroll") for (int n = 0; n < 2; ++n) _Pragma("unroll") for (int k = 0; k < 2; ++k) \
;         acc[ai][bj][m][n] = __builtin_amdgcn_mfma_f32_16x16x32_bf16(Bt[n][k], At[m][k], acc[ai][bj][m][n], 0, 0, 0); __builtin_amdgcn_s_setprio(0); } while (0)
; #define PG8_WAIT_V(n) asm volatile("s_waitcnt vmcnt(" #n ")" ::: "memory")
; #define PG8_WAIT_L(n) asm volatile("s_waitcnt lgkmcnt(" #n ")" ::: "memory")
; #define PG8_BAR __builtin_amdgcn_s_barrier()
; #define PG8_SCHED __builtin_amdgcn_sched_barrier(0)
; template <class Epi, class Sched, bool ALIGN_EPI = false, bool SP2 = false>
; __device__ __forceinline__ void gemm_phase(PG8_LAS unsigned char* lds, const Gemm g, const Sched& S, const Epi& E) {
;     ...
;             PG8_LDB(B0, 0, 0); PG8_LDB(B1, 0, 1); PG8_SCHED; PG8_LDA(At, 0, 0); PG8_STAGE(PG8_SA(1, 1), a1 + hstep, voffA);
;             PG8_WAIT_V(8); PG8_WAIT_L(0); PG8_BAR; PG8_MMA(0, 0, At, B0); PG8_MMA(0, 1, At, B1); PG8_BAR; PG8_SCHED;
;             PG8_LDA(At, 0, 1); PG8_STAGE(PG8_SB(0, 0), b2, voffB); PG8_STAGE(PG8_SB(0, 1), b2 + hstep, voffB); PG8_STAGE(PG8_SA(0, 0), a2, voffA);
;             PG8_WAIT_V(8); PG8_WAIT_L(0); PG8_BAR; PG8_MMA(1, 0, At, B0); PG8_MMA(1, 1, At, B1); PG8_BAR; PG8_SCHED;
.LBB0_1196:
	s_add_u32 s82, s52, 0x100
	s_addc_u32 s83, s53, 0
	s_mov_b32 s84, -2
	s_waitcnt lgkmcnt(0)
	ds_read_b128 v[144:147], v151
	ds_read_b128 v[156:159], v151 offset:1024
	ds_read_b128 v[160:163], v151 offset:2048
	ds_read_b128 v[164:167], v151 offset:3072
	ds_read_b128 v[168:171], v152
	ds_read_b128 v[172:175], v152 offset:1024
	ds_read_b128 v[176:179], v152 offset:2048
	ds_read_b128 v[182:185], v152 offset:3072
	s_add_u32 s52, s50, 0x100
	s_addc_u32 s53, s51, 0
	s_cmp_eq_u32 s84, 40
	s_cselect_b32 s57, s1, s53
	s_cselect_b32 s56, s0, s52
	s_cselect_b32 s55, s49, s83
	s_cselect_b32 s54, s48, s82
	v_lshl_add_u64 v[224:225], s[50:51], 0, v[136:137]
	s_add_i32 m0, s34, 0xc000
	ds_read_b128 v[186:189], v153
	ds_read_b128 v[190:193], v153 offset:1024
	ds_read_b128 v[194:197], v153 offset:2048
	ds_read_b128 v[198:201], v153 offset:3072
	ds_read_b128 v[208:211], v153 offset:4096
	ds_read_b128 v[212:215], v153 offset:5120
	ds_read_b128 v[216:219], v153 offset:6144
	ds_read_b128 v[220:223], v153 offset:7168
	global_load_lds_dwordx4 v[224:225], off
	v_lshl_add_u64 v[224:225], s[50:51], 0, v[138:139]
	s_add_i32 m0, s34, 0xe000
	s_nop 0
	global_load_lds_dwordx4 v[224:225], off
	s_waitcnt vmcnt(8)
	s_waitcnt lgkmcnt(0)
	s_barrier
	s_setprio 1
	s_waitcnt lgkmcnt(0)
	v_mfma_f32_16x16x32_bf16 v[124:127], v[144:147], v[186:189], 0
	v_mfma_f32_16x16x32_bf16 v[120:123], v[160:163], v[186:189], 0
	v_mfma_f32_16x16x32_bf16 v[108:111], v[144:147], v[194:197], 0
	v_mfma_f32_16x16x32_bf16 v[104:107], v[160:163], v[194:197], 0
	v_mfma_f32_16x16x32_bf16 v[92:95], v[144:147], v[208:211], 0
	v_mfma_f32_16x16x32_bf16 v[88:91], v[160:163], v[208:211], 0
	v_mfma_f32_16x16x32_bf16 v[76:79], v[144:147], v[216:219], 0
	v_mfma_f32_16x16x32_bf16 v[72:75], v[160:163], v[216:219], 0
	v_mfma_f32_16x16x32_bf16 v[124:127], v[156:159], v[190:193], v[124:127]
	v_mfma_f32_16x16x32_bf16 v[120:123], v[164:167], v[190:193], v[120:123]
	v_mfma_f32_16x16x32_bf16 v[108:111], v[156:159], v[198:201], v[108:111]
	v_mfma_f32_16x16x32_bf16 v[104:107], v[164:167], v[198:201], v[104:107]
	v_mfma_f32_16x16x32_bf16 v[92:95], v[156:159], v[212:215], v[92:95]
	v_mfma_f32_16x16x32_bf16 v[88:91], v[164:167], v[212:215], v[88:91]
	v_mfma_f32_16x16x32_bf16 v[76:79], v[156:159], v[220:223], v[76:79]
	v_mfma_f32_16x16x32_bf16 v[72:75], v[164:167], v[220:223], v[72:75]
	s_setprio 0
	s_setprio 1
	v_mfma_f32_16x16x32_bf16 v[116:119], v[168:171], v[186:189], 0
	v_mfma_f32_16x16x32_bf16 v[112:115], v[176:179], v[186:189], 0
	v_mfma_f32_16x16x32_bf16 v[100:103], v[168:171], v[194:197], 0
	v_mfma_f32_16x16x32_bf16 v[96:99], v[176:179], v[194:197], 0
	v_mfma_f32_16x16x32_bf16 v[84:87], v[168:171], v[208:211], 0
	v_mfma_f32_16x16x32_bf16 v[80:83], v[176:179], v[208:211], 0
	v_mfma_f32_16x16x32_bf16 v[68:71], v[168:171], v[216:219], 0
	v_mfma_f32_16x16x32_bf16 v[64:67], v[176:179], v[216:219], 0
	v_mfma_f32_16x16x32_bf16 v[116:119], v[172:175], v[190:193], v[116:119]
	v_mfma_f32_16x16x32_bf16 v[112:115], v[182:185], v[190:193], v[112:115]
	v_mfma_f32_16x16x32_bf16 v[100:103], v[172:175], v[198:201], v[100:103]
	v_mfma_f32_16x16x32_bf16 v[96:99], v[182:185], v[198:201], v[96:99]
	v_mfma_f32_16x16x32_bf16 v[84:87], v[172:175], v[212:215], v[84:87]
	v_mfma_f32_16x16x32_bf16 v[80:83], v[182:185], v[212:215], v[80:83]
	v_mfma_f32_16x16x32_bf16 v[68:71], v[172:175], v[220:223], v[68:71]
	v_mfma_f32_16x16x32_bf16 v[64:67], v[182:185], v[220:223], v[64:67]
	s_setprio 0
	s_barrier
	s_add_i32 s50, s64, s33
	v_lshl_add_u64 v[224:225], s[54:55], 0, v[130:131]
	s_mov_b32 m0, s50
	ds_read_b128 v[186:189], v153 offset:16384
	ds_read_b128 v[190:193], v153 offset:17408
	ds_read_b128 v[194:197], v153 offset:18432
	ds_read_b128 v[198:201], v153 offset:19456
	ds_read_b128 v[208:211], v153 offset:20480
	ds_read_b128 v[212:215], v153 offset:21504
	ds_read_b128 v[216:219], v153 offset:22528
	ds_read_b128 v[220:223], v153 offset:23552
	global_load_lds_dwordx4 v[224:225], off
	s_add_i32 m0, s50, 0x2000
	s_add_u32 s50, s54, 0xb0000
	v_lshl_add_u64 v[226:227], s[54:55], 0, v[134:135]
	s_addc_u32 s51, s55, 0
	s_add_i32 s78, s65, s33
	global_load_lds_dwordx4 v[226:227], off
	v_lshl_add_u64 v[228:229], s[50:51], 0, v[130:131]
	s_mov_b32 m0, s78
	global_load_lds_dwordx4 v[228:229], off
	v_lshl_add_u64 v[228:229], s[50:51], 0, v[134:135]
	s_add_i32 m0, s78, 0x2000
	s_nop 0
	global_load_lds_dwordx4 v[228:229], off
	s_waitcnt vmcnt(6)
	s_waitcnt lgkmcnt(0)
	s_barrier
; #define PG8_STAGE(bufoff, gbase, voff) do { _Pragma("unroll") for (int _i = 0; _i < 2; ++_i) \
;         __builtin_amdgcn_global_load_lds((const unsigned*)((const char*)(gbase) + (voff)[_i]), (PG8_LAS unsigned*)(lds + (bufoff) + ldsw + _i * 8192), 16, 0, 0); } while (0)
; #define PG8_LDA(dst, b, h) do { _Pragma("unroll") for (int m = 0; m < 4; ++m) _Pragma("unroll") for (int k = 0; k < 2; ++k) dst[m][k] = *(const PG8_LAS bf16x8*)(lds + PG8_SA(b, h) + aoff + m * 2048 + k * 1024); } while (0)
; #define PG8_LDB(dst, b, h) do { _Pragma("unroll") for (int n = 0; n < 2; ++n) _Pragma("unroll") for (int k = 0; k < 2; ++k) dst[n][k] = *(const PG8_LAS bf16x8*)(lds + PG8_SB(b, h) + boff + n * 2048 + k * 1024); } while (0)
; #define PG8_MMA(ai, bj, At, Bt) do { __builtin_amdgcn_s_setprio(1); _Pragma("unroll") for (int m = 0; m < 4; ++m) _Pragma("unroll") for (int n = 0; n < 2; ++n) _Pragma("unroll") for (int k = 0; k < 2; ++k) \
;         acc[ai][bj][m][n] = __builtin_amdgcn_mfma_f32_16x16x32_bf16(Bt[n][k], At[m][k], acc[ai][bj][m][n], 0, 0, 0); __builtin_amdgcn_s_setprio(0); } while (0)
; #define PG8_WAIT_V(n) asm volatile("s_waitcnt vmcnt(" #n ")" ::: "memory")
; #define PG8_WAIT_L(n) asm volatile("s_waitcnt lgkmcnt(" #n ")" ::: "memory")
; #define PG8_BAR __builtin_amdgcn_s_barrier()
; #define PG8_SCHED __builtin_amdgcn_sched_barrier(0)
; template <class Epi, class Sched, bool ALIGN_EPI = false, bool SP2 = false>
; __device__ __forceinline__ void gemm_phase(PG8_LAS unsigned char* lds, const Gemm g, const Sched& S, const Epi& E) {
;     ...
;             PG8_WAIT_V(8); PG8_WAIT_L(0); PG8_BAR; PG8_MMA(1, 0, At, B0); PG8_MMA(1, 1, At, B1); PG8_BAR; PG8_SCHED;
;             PG8_LDB(B0, 1, 0); PG8_LDB(B1, 1, 1); PG8_SCHED; PG8_LDA(At, 1, 0); PG8_STAGE(PG8_SA(0, 1), a2 + hstep, voffA);
;             PG8_WAIT_V(8); PG8_WAIT_L(0); PG8_BAR; PG8_MMA(0, 0, At, B0); PG8_MMA(0, 1, At, B1); PG8_BAR; PG8_SCHED;
	s_setprio 1
	s_waitcnt lgkmcnt(0)
	v_mfma_f32_16x16x32_bf16 v[60:63], v[144:147], v[186:189], 0
	v_mfma_f32_16x16x32_bf16 v[56:59], v[160:163], v[186:189], 0
	v_mfma_f32_16x16x32_bf16 v[44:47], v[144:147], v[194:197], 0
	v_mfma_f32_16x16x32_bf16 v[40:43], v[160:163], v[194:197], 0
	v_mfma_f32_16x16x32_bf16 v[28:31], v[144:147], v[208:211], 0
	v_mfma_f32_16x16x32_bf16 v[24:27], v[160:163], v[208:211], 0
	v_mfma_f32_16x16x32_bf16 v[12:15], v[144:147], v[216:219], 0
	v_mfma_f32_16x16x32_bf16 v[8:11], v[160:163], v[216:219], 0
	v_mfma_f32_16x16x32_bf16 v[60:63], v[156:159], v[190:193], v[60:63]
	v_mfma_f32_16x16x32_bf16 v[56:59], v[164:167], v[190:193], v[56:59]
	v_mfma_f32_16x16x32_bf16 v[44:47], v[156:159], v[198:201], v[44:47]
	v_mfma_f32_16x16x32_bf16 v[40:43], v[164:167], v[198:201], v[40:43]
	v_mfma_f32_16x16x32_bf16 v[28:31], v[156:159], v[212:215], v[28:31]
	v_mfma_f32_16x16x32_bf16 v[24:27], v[164:167], v[212:215], v[24:27]
	v_lshl_add_u64 v[228:229], s[56:57], 0, v[128:129]
	s_mov_b32 m0, s34
	s_nop 0
	global_load_lds_dwordx4 v[228:229], off
	v_mfma_f32_16x16x32_bf16 v[12:15], v[156:159], v[220:223], v[12:15]
	v_mfma_f32_16x16x32_bf16 v[8:11], v[164:167], v[220:223], v[8:11]
	s_setprio 0
	s_setprio 1
	v_mfma_f32_16x16x32_bf16 v[52:55], v[168:171], v[186:189], 0
	v_mfma_f32_16x16x32_bf16 v[48:51], v[176:179], v[186:189], 0
	v_mfma_f32_16x16x32_bf16 v[36:39], v[168:171], v[194:197], 0
	v_mfma_f32_16x16x32_bf16 v[32:35], v[176:179], v[194:197], 0
	v_mfma_f32_16x16x32_bf16 v[20:23], v[168:171], v[208:211], 0
	v_mfma_f32_16x16x32_bf16 v[16:19], v[176:179], v[208:211], 0
	v_mfma_f32_16x16x32_bf16 v[4:7], v[168:171], v[216:219], 0
	v_mfma_f32_16x16x32_bf16 v[0:3], v[176:179], v[216:219], 0
	v_mfma_f32_16x16x32_bf16 v[52:55], v[172:175], v[190:193], v[52:55]
	v_mfma_f32_16x16x32_bf16 v[48:51], v[182:185], v[190:193], v[48:51]
	v_mfma_f32_16x16x32_bf16 v[36:39], v[172:175], v[198:201], v[36:39]
	v_mfma_f32_16x16x32_bf16 v[32:35], v[182:185], v[198:201], v[32:35]
	v_mfma_f32_16x16x32_bf16 v[20:23], v[172:175], v[212:215], v[20:23]
	v_mfma_f32_16x16x32_bf16 v[16:19], v[182:185], v[212:215], v[16:19]
	v_lshl_add_u64 v[230:231], s[56:57], 0, v[132:133]
	s_mov_b32 m0, s58
	s_nop 0
	global_load_lds_dwordx4 v[230:231], off
	v_mfma_f32_16x16x32_bf16 v[4:7], v[172:175], v[220:223], v[4:7]
	v_mfma_f32_16x16x32_bf16 v[0:3], v[182:185], v[220:223], v[0:3]
	s_setprio 0
	s_barrier
	s_add_i32 s78, 0, 0x18000
	v_add_u32_e32 v155, s78, v149
	s_add_i32 s79, 0, 0x1c000
	ds_read_b128 v[144:147], v155
	ds_read_b128 v[156:159], v155 offset:1024
	ds_read_b128 v[160:163], v155 offset:2048
	ds_read_b128 v[164:167], v155 offset:3072
	v_add_u32_e32 v155, s79, v149
	ds_read_b128 v[168:171], v155
	ds_read_b128 v[172:175], v155 offset:1024
	ds_read_b128 v[176:179], v155 offset:2048
	ds_read_b128 v[182:185], v155 offset:3072
	s_add_u32 s50, s56, 0xb0000
	s_addc_u32 s51, s57, 0
	s_mov_b32 m0, s59
	v_lshl_add_u64 v[232:233], s[50:51], 0, v[128:129]
	ds_read_b128 v[186:189], v153 offset:32768
	ds_read_b128 v[190:193], v153 offset:33792
	ds_read_b128 v[194:197], v153 offset:34816
	ds_read_b128 v[198:201], v153 offset:35840
	ds_read_b128 v[208:211], v153 offset:36864
	ds_read_b128 v[212:215], v153 offset:37888
	ds_read_b128 v[216:219], v153 offset:38912
	ds_read_b128 v[220:223], v153 offset:39936
	global_load_lds_dwordx4 v[232:233], off
	v_lshl_add_u64 v[232:233], s[50:51], 0, v[132:133]
	s_mov_b32 m0, s60
	s_nop 0
	global_load_lds_dwordx4 v[232:233], off
	s_waitcnt vmcnt(8)
	s_waitcnt lgkmcnt(0)
	s_barrier
	s_setprio 1
	s_waitcnt lgkmcnt(0)
	v_mfma_f32_16x16x32_bf16 v[124:127], v[144:147], v[186:189], v[124:127]
	v_mfma_f32_16x16x32_bf16 v[120:123], v[160:163], v[186:189], v[120:123]
	v_mfma_f32_16x16x32_bf16 v[108:111], v[144:147], v[194:197], v[108:111]
	v_mfma_f32_16x16x32_bf16 v[104:107], v[160:163], v[194:197], v[104:107]
	v_mfma_f32_16x16x32_bf16 v[92:95], v[144:147], v[208:211], v[92:95]
	v_mfma_f32_16x16x32_bf16 v[88:91], v[160:163], v[208:211], v[88:91]
	v_mfma_f32_16x16x32_bf16 v[76:79], v[144:147], v[216:219], v[76:79]
	v_mfma_f32_16x16x32_bf16 v[72:75], v[160:163], v[216:219], v[72:75]
	v_mfma_f32_16x16x32_bf16 v[124:127], v[156:159], v[190:193], v[124:127]
	v_mfma_f32_16x16x32_bf16 v[120:123], v[164:167], v[190:193], v[120:123]
	v_mfma_f32_16x16x32_bf16 v[108:111], v[156:159], v[198:201], v[108:111]
	v_mfma_f32_16x16x32_bf16 v[104:107], v[164:167], v[198:201], v[104:107]
	v_mfma_f32_16x16x32_bf16 v[92:95], v[156:159], v[212:215], v[92:95]
	v_mfma_f32_16x16x32_bf16 v[88:91], v[164:167], v[212:215], v[88:91]
	v_mfma_f32_16x16x32_bf16 v[76:79], v[156:159], v[220:223], v[76:79]
	v_mfma_f32_16x16x32_bf16 v[72:75], v[164:167], v[220:223], v[72:75]
	s_setprio 0
	s_setprio 1
	v_mfma_f32_16x16x32_bf16 v[116:119], v[168:171], v[186:189], v[116:119]
	v_mfma_f32_16x16x32_bf16 v[112:115], v[176:179], v[186:189], v[112:115]
	v_mfma_f32_16x16x32_bf16 v[100:103], v[168:171], v[194:197], v[100:103]
	v_mfma_f32_16x16x32_bf16 v[96:99], v[176:179], v[194:197], v[96:99]
	v_mfma_f32_16x16x32_bf16 v[84:87], v[168:171], v[208:211], v[84:87]
	v_mfma_f32_16x16x32_bf16 v[80:83], v[176:179], v[208:211], v[80:83]
	v_mfma_f32_16x16x32_bf16 v[68:71], v[168:171], v[216:219], v[68:71]
	v_mfma_f32_16x16x32_bf16 v[64:67], v[176:179], v[216:219], v[64:67]
	v_mfma_f32_16x16x32_bf16 v[116:119], v[172:175], v[190:193], v[116:119]
	v_mfma_f32_16x16x32_bf16 v[112:115], v[182:185], v[190:193], v[112:115]
	v_mfma_f32_16x16x32_bf16 v[100:103], v[172:175], v[198:201], v[100:103]
	v_mfma_f32_16x16x32_bf16 v[96:99], v[182:185], v[198:201], v[96:99]
	v_mfma_f32_16x16x32_bf16 v[84:87], v[172:175], v[212:215], v[84:87]
	v_mfma_f32_16x16x32_bf16 v[80:83], v[182:185], v[212:215], v[80:83]
	v_mfma_f32_16x16x32_bf16 v[68:71], v[172:175], v[220:223], v[68:71]
	v_mfma_f32_16x16x32_bf16 v[64:67], v[182:185], v[220:223], v[64:67]
	s_setprio 0
	s_barrier
; #define PG8_STAGE(bufoff, gbase, voff) do { _Pragma("unroll") for (int _i = 0; _i < 2; ++_i) \
;         __builtin_amdgcn_global_load_lds((const unsigned*)((const char*)(gbase) + (voff)[_i]), (PG8_LAS unsigned*)(lds + (bufoff) + ldsw + _i * 8192), 16, 0, 0); } while (0)
; #define PG8_LDA(dst, b, h) do { _Pragma("unroll") for (int m = 0; m < 4; ++m) _Pragma("unroll") for (int k = 0; k < 2; ++k) dst[m][k] = *(const PG8_LAS bf16x8*)(lds + PG8_SA(b, h) + aoff + m * 2048 + k * 1024); } while (0)
; #define PG8_LDB(dst, b, h) do { _Pragma("unroll") for (int n = 0; n < 2; ++n) _Pragma("unroll") for (int k = 0; k < 2; ++k) dst[n][k] = *(const PG8_LAS bf16x8*)(lds + PG8_SB(b, h) + boff + n * 2048 + k * 1024); } while (0)
; #define PG8_MMA(ai, bj, At, Bt) do { __builtin_amdgcn_s_setprio(1); _Pragma("unroll") for (int m = 0; m < 4; ++m) _Pragma("unroll") for (int n = 0; n < 2; ++n) _Pragma("unroll") for (int k = 0; k < 2; ++k) \
;         acc[ai][bj][m][n] = __builtin_amdgcn_mfma_f32_16x16x32_bf16(Bt[n][k], At[m][k], acc[ai][bj][m][n], 0, 0, 0); __builtin_amdgcn_s_setprio(0); } while (0)
; #define PG8_WAIT_V(n) asm volatile("s_waitcnt vmcnt(" #n ")" ::: "memory")
; #define PG8_WAIT_L(n) asm volatile("s_waitcnt lgkmcnt(" #n ")" ::: "memory")
; #define PG8_BAR __builtin_amdgcn_s_barrier()
; #define PG8_SCHED __builtin_amdgcn_sched_barrier(0)
; template <class Epi, class Sched, bool ALIGN_EPI = false, bool SP2 = false>
; __device__ __forceinline__ void gemm_phase(PG8_LAS unsigned char* lds, const Gemm g, const Sched& S, const Epi& E) {
;     ...
;             PG8_LDB(B0, 0, 0); PG8_LDB(B1, 0, 1); PG8_SCHED; PG8_LDA(At, 0, 0); PG8_STAGE(PG8_SA(1, 1), a1 + hstep, voffA);
;             PG8_WAIT_V(8); PG8_WAIT_L(0); PG8_BAR; PG8_MMA(0, 0, At, B0); PG8_MMA(0, 1, At, B1); PG8_BAR; PG8_SCHED;
;     ...
;             PG8_LDA(At, 1, 1); PG8_STAGE(PG8_SB(1, 0), b3, voffB); PG8_STAGE(PG8_SB(1, 1), b3 + hstep, voffB); PG8_STAGE(PG8_SA(1, 0), a3, voffA);
;             PG8_WAIT_V(8); PG8_WAIT_L(0); PG8_BAR; PG8_MMA(1, 0, At, B0); PG8_MMA(1, 1, At, B1); PG8_BAR; PG8_SCHED;
	s_add_i32 s50, s78, s33
	v_lshl_add_u64 v[224:225], v[224:225], 0, s[42:43]
	s_mov_b32 m0, s50
	ds_read_b128 v[186:189], v153 offset:49152
	ds_read_b128 v[190:193], v153 offset:50176
	ds_read_b128 v[194:197], v153 offset:51200
	ds_read_b128 v[198:201], v153 offset:52224
	ds_read_b128 v[208:211], v153 offset:53248
	ds_read_b128 v[212:215], v153 offset:54272
	ds_read_b128 v[216:219], v153 offset:55296
	ds_read_b128 v[220:223], v153 offset:56320
	global_load_lds_dwordx4 v[224:225], off
	s_add_i32 m0, s50, 0x2000
	s_add_u32 s50, s54, 0xb0080
	v_lshl_add_u64 v[224:225], v[226:227], 0, s[42:43]
	s_addc_u32 s51, s55, 0
	s_add_i32 s54, s79, s33
	global_load_lds_dwordx4 v[224:225], off
	v_lshl_add_u64 v[224:225], s[50:51], 0, v[130:131]
	s_mov_b32 m0, s54
	s_nop 0
	global_load_lds_dwordx4 v[224:225], off
	v_lshl_add_u64 v[224:225], s[50:51], 0, v[134:135]
	s_add_i32 m0, s54, 0x2000
	s_nop 0
	global_load_lds_dwordx4 v[224:225], off
	s_waitcnt vmcnt(6)
	s_waitcnt lgkmcnt(0)
	s_barrier
	s_setprio 1
	s_waitcnt lgkmcnt(0)
	v_mfma_f32_16x16x32_bf16 v[60:63], v[144:147], v[186:189], v[60:63]
	v_mfma_f32_16x16x32_bf16 v[56:59], v[160:163], v[186:189], v[56:59]
	v_mfma_f32_16x16x32_bf16 v[44:47], v[144:147], v[194:197], v[44:47]
	v_mfma_f32_16x16x32_bf16 v[40:43], v[160:163], v[194:197], v[40:43]
	v_mfma_f32_16x16x32_bf16 v[28:31], v[144:147], v[208:211], v[28:31]
	v_mfma_f32_16x16x32_bf16 v[24:27], v[160:163], v[208:211], v[24:27]
	v_mfma_f32_16x16x32_bf16 v[12:15], v[144:147], v[216:219], v[12:15]
	v_mfma_f32_16x16x32_bf16 v[8:11], v[160:163], v[216:219], v[8:11]
	v_mfma_f32_16x16x32_bf16 v[60:63], v[156:159], v[190:193], v[60:63]
	v_mfma_f32_16x16x32_bf16 v[56:59], v[164:167], v[190:193], v[56:59]
	v_mfma_f32_16x16x32_bf16 v[44:47], v[156:159], v[198:201], v[44:47]
	v_mfma_f32_16x16x32_bf16 v[40:43], v[164:167], v[198:201], v[40:43]
	v_mfma_f32_16x16x32_bf16 v[28:31], v[156:159], v[212:215], v[28:31]
	v_mfma_f32_16x16x32_bf16 v[24:27], v[164:167], v[212:215], v[24:27]
	v_lshl_add_u64 v[224:225], v[228:229], 0, s[42:43]
	s_mov_b32 m0, s62
	s_nop 0
	global_load_lds_dwordx4 v[224:225], off
	v_mfma_f32_16x16x32_bf16 v[12:15], v[156:159], v[220:223], v[12:15]
	v_mfma_f32_16x16x32_bf16 v[8:11], v[164:167], v[220:223], v[8:11]
	s_setprio 0
	s_setprio 1
	v_mfma_f32_16x16x32_bf16 v[52:55], v[168:171], v[186:189], v[52:55]
	v_mfma_f32_16x16x32_bf16 v[48:51], v[176:179], v[186:189], v[48:51]
	v_mfma_f32_16x16x32_bf16 v[36:39], v[168:171], v[194:197], v[36:39]
	v_mfma_f32_16x16x32_bf16 v[32:35], v[176:179], v[194:197], v[32:35]
	v_mfma_f32_16x16x32_bf16 v[20:23], v[168:171], v[208:211], v[20:23]
	v_mfma_f32_16x16x32_bf16 v[16:19], v[176:179], v[208:211], v[16:19]
	v_mfma_f32_16x16x32_bf16 v[4:7], v[168:171], v[216:219], v[4:7]
	v_mfma_f32_16x16x32_bf16 v[0:3], v[176:179], v[216:219], v[0:3]
	v_mfma_f32_16x16x32_bf16 v[52:55], v[172:175], v[190:193], v[52:55]
	v_mfma_f32_16x16x32_bf16 v[48:51], v[182:185], v[190:193], v[48:51]
	v_mfma_f32_16x16x32_bf16 v[36:39], v[172:175], v[198:201], v[36:39]
	v_mfma_f32_16x16x32_bf16 v[32:35], v[182:185], v[198:201], v[32:35]
	v_mfma_f32_16x16x32_bf16 v[20:23], v[172:175], v[212:215], v[20:23]
	v_mfma_f32_16x16x32_bf16 v[16:19], v[182:185], v[212:215], v[16:19]
	v_lshl_add_u64 v[224:225], v[230:231], 0, s[42:43]
	s_mov_b32 m0, s63
	s_nop 0
	global_load_lds_dwordx4 v[224:225], off
	v_mfma_f32_16x16x32_bf16 v[4:7], v[172:175], v[220:223], v[4:7]
	v_mfma_f32_16x16x32_bf16 v[0:3], v[182:185], v[220:223], v[0:3]
	s_setprio 0
	s_barrier
	s_add_i32 s84, s84, 2
	s_add_u32 s82, s82, 0x100
	s_addc_u32 s83, s83, 0
	s_mov_b64 s[50:51], s[52:53]
.LBB0_1197:
	ds_read_b128 v[144:147], v151
	ds_read_b128 v[156:159], v151 offset:1024
	ds_read_b128 v[160:163], v151 offset:2048
	ds_read_b128 v[164:167], v151 offset:3072
	ds_read_b128 v[168:171], v152
	ds_read_b128 v[172:175], v152 offset:1024
	ds_read_b128 v[176:179], v152 offset:2048
	ds_read_b128 v[182:185], v152 offset:3072
	s_add_u32 s52, s50, 0x100
	s_addc_u32 s53, s51, 0
	s_cmp_eq_u32 s84, 40
	s_cselect_b32 s57, s1, s53
	s_cselect_b32 s56, s0, s52
	s_cselect_b32 s55, s49, s83
	s_cselect_b32 s54, s48, s82
	v_lshl_add_u64 v[224:225], s[50:51], 0, v[136:137]
	s_add_i32 m0, s34, 0xc000
	ds_read_b128 v[186:189], v153
	ds_read_b128 v[190:193], v153 offset:1024
	ds_read_b128 v[194:197], v153 offset:2048
	ds_read_b128 v[198:201], v153 offset:3072
	ds_read_b128 v[208:211], v153 offset:4096
	ds_read_b128 v[212:215], v153 offset:5120
	ds_read_b128 v[216:219], v153 offset:6144
	ds_read_b128 v[220:223], v153 offset:7168
	global_load_lds_dwordx4 v[224:225], off
	v_lshl_add_u64 v[224:225], s[50:51], 0, v[138:139]
	s_add_i32 m0, s34, 0xe000
	s_nop 0
	global_load_lds_dwordx4 v[224:225], off
	s_waitcnt vmcnt(8)
	s_waitcnt lgkmcnt(0)
	s_barrier
; #define PG8_STAGE(bufoff, gbase, voff) do { _Pragma("unroll") for (int _i = 0; _i < 2; ++_i) \
;         __builtin_amdgcn_global_load_lds((const unsigned*)((const char*)(gbase) + (voff)[_i]), (PG8_LAS unsigned*)(lds + (bufoff) + ldsw + _i * 8192), 16, 0, 0); } while (0)
; #define PG8_LDA(dst, b, h) do { _Pragma("unroll") for (int m = 0; m < 4; ++m) _Pragma("unroll") for (int k = 0; k < 2; ++k) dst[m][k] = *(const PG8_LAS bf16x8*)(lds + PG8_SA(b, h) + aoff + m * 2048 + k * 1024); } while (0)
; #define PG8_MMA(ai, bj, At, Bt) do { __builtin_amdgcn_s_setprio(1); _Pragma("unroll") for (int m = 0; m < 4; ++m) _Pragma("unroll") for (int n = 0; n < 2; ++n) _Pragma("unroll") for (int k = 0; k < 2; ++k) \
;         acc[ai][bj][m][n] = __builtin_amdgcn_mfma_f32_16x16x32_bf16(Bt[n][k], At[m][k], acc[ai][bj][m][n], 0, 0, 0); __builtin_amdgcn_s_setprio(0); } while (0)
; #define PG8_WAIT_V(n) asm volatile("s_waitcnt vmcnt(" #n ")" ::: "memory")
; #define PG8_WAIT_L(n) asm volatile("s_waitcnt lgkmcnt(" #n ")" ::: "memory")
; #define PG8_BAR __builtin_amdgcn_s_barrier()
; #define PG8_SCHED __builtin_amdgcn_sched_barrier(0)
; template <class Epi, class Sched, bool ALIGN_EPI = false, bool SP2 = false>
; __device__ __forceinline__ void gemm_phase(PG8_LAS unsigned char* lds, const Gemm g, const Sched& S, const Epi& E) {
;     ...
;             PG8_WAIT_V(8); PG8_WAIT_L(0); PG8_BAR; PG8_MMA(0, 0, At, B0); PG8_MMA(0, 1, At, B1); PG8_BAR; PG8_SCHED;
;             PG8_LDA(At, 0, 1); PG8_STAGE(PG8_SB(0, 0), b2, voffB); PG8_STAGE(PG8_SB(0, 1), b2 + hstep, voffB); PG8_STAGE(PG8_SA(0, 0), a2, voffA);
;             PG8_WAIT_V(8); PG8_WAIT_L(0); PG8_BAR; PG8_MMA(1, 0, At, B0); PG8_MMA(1, 1, At, B1); PG8_BAR; PG8_SCHED;
	s_setprio 1
	s_waitcnt lgkmcnt(0)
	v_mfma_f32_16x16x32_bf16 v[124:127], v[144:147], v[186:189], v[124:127]
	v_mfma_f32_16x16x32_bf16 v[120:123], v[160:163], v[186:189], v[120:123]
	v_mfma_f32_16x16x32_bf16 v[108:111], v[144:147], v[194:197], v[108:111]
	v_mfma_f32_16x16x32_bf16 v[104:107], v[160:163], v[194:197], v[104:107]
	v_mfma_f32_16x16x32_bf16 v[92:95], v[144:147], v[208:211], v[92:95]
	v_mfma_f32_16x16x32_bf16 v[88:91], v[160:163], v[208:211], v[88:91]
	v_mfma_f32_16x16x32_bf16 v[76:79], v[144:147], v[216:219], v[76:79]
	v_mfma_f32_16x16x32_bf16 v[72:75], v[160:163], v[216:219], v[72:75]
	v_mfma_f32_16x16x32_bf16 v[124:127], v[156:159], v[190:193], v[124:127]
	v_mfma_f32_16x16x32_bf16 v[120:123], v[164:167], v[190:193], v[120:123]
	v_mfma_f32_16x16x32_bf16 v[108:111], v[156:159], v[198:201], v[108:111]
	v_mfma_f32_16x16x32_bf16 v[104:107], v[164:167], v[198:201], v[104:107]
	v_mfma_f32_16x16x32_bf16 v[92:95], v[156:159], v[212:215], v[92:95]
	v_mfma_f32_16x16x32_bf16 v[88:91], v[164:167], v[212:215], v[88:91]
	v_mfma_f32_16x16x32_bf16 v[76:79], v[156:159], v[220:223], v[76:79]
	v_mfma_f32_16x16x32_bf16 v[72:75], v[164:167], v[220:223], v[72:75]
	s_setprio 0
	s_setprio 1
	v_mfma_f32_16x16x32_bf16 v[116:119], v[168:171], v[186:189], v[116:119]
	v_mfma_f32_16x16x32_bf16 v[112:115], v[176:179], v[186:189], v[112:115]
	v_mfma_f32_16x16x32_bf16 v[100:103], v[168:171], v[194:197], v[100:103]
	v_mfma_f32_16x16x32_bf16 v[96:99], v[176:179], v[194:197], v[96:99]
	v_mfma_f32_16x16x32_bf16 v[84:87], v[168:171], v[208:211], v[84:87]
	v_mfma_f32_16x16x32_bf16 v[80:83], v[176:179], v[208:211], v[80:83]
	v_mfma_f32_16x16x32_bf16 v[68:71], v[168:171], v[216:219], v[68:71]
	v_mfma_f32_16x16x32_bf16 v[64:67], v[176:179], v[216:219], v[64:67]
	v_mfma_f32_16x16x32_bf16 v[116:119], v[172:175], v[190:193], v[116:119]
	v_mfma_f32_16x16x32_bf16 v[112:115], v[182:185], v[190:193], v[112:115]
	v_mfma_f32_16x16x32_bf16 v[100:103], v[172:175], v[198:201], v[100:103]
	v_mfma_f32_16x16x32_bf16 v[96:99], v[182:185], v[198:201], v[96:99]
	v_mfma_f32_16x16x32_bf16 v[84:87], v[172:175], v[212:215], v[84:87]
	v_mfma_f32_16x16x32_bf16 v[80:83], v[182:185], v[212:215], v[80:83]
	v_mfma_f32_16x16x32_bf16 v[68:71], v[172:175], v[220:223], v[68:71]
	v_mfma_f32_16x16x32_bf16 v[64:67], v[182:185], v[220:223], v[64:67]
	s_setprio 0
	s_barrier
	s_add_i32 s50, s64, s33
	v_lshl_add_u64 v[224:225], s[54:55], 0, v[130:131]
	s_mov_b32 m0, s50
	ds_read_b128 v[186:189], v153 offset:16384
	ds_read_b128 v[190:193], v153 offset:17408
	ds_read_b128 v[194:197], v153 offset:18432
	ds_read_b128 v[198:201], v153 offset:19456
	ds_read_b128 v[208:211], v153 offset:20480
	ds_read_b128 v[212:215], v153 offset:21504
	ds_read_b128 v[216:219], v153 offset:22528
	ds_read_b128 v[220:223], v153 offset:23552
	global_load_lds_dwordx4 v[224:225], off
	s_add_i32 m0, s50, 0x2000
	s_add_u32 s50, s54, 0xb0000
	v_lshl_add_u64 v[226:227], s[54:55], 0, v[134:135]
	s_addc_u32 s51, s55, 0
	s_add_i32 s78, s65, s33
	global_load_lds_dwordx4 v[226:227], off
	v_lshl_add_u64 v[228:229], s[50:51], 0, v[130:131]
	s_mov_b32 m0, s78
	global_load_lds_dwordx4 v[228:229], off
	v_lshl_add_u64 v[228:229], s[50:51], 0, v[134:135]
	s_add_i32 m0, s78, 0x2000
	s_nop 0
	global_load_lds_dwordx4 v[228:229], off
	s_waitcnt vmcnt(6)
	s_waitcnt lgkmcnt(0)
	s_barrier
	s_setprio 1
	s_waitcnt lgkmcnt(0)
	v_mfma_f32_16x16x32_bf16 v[60:63], v[144:147], v[186:189], v[60:63]
	v_mfma_f32_16x16x32_bf16 v[56:59], v[160:163], v[186:189], v[56:59]
	v_mfma_f32_16x16x32_bf16 v[44:47], v[144:147], v[194:197], v[44:47]
	v_mfma_f32_16x16x32_bf16 v[40:43], v[160:163], v[194:197], v[40:43]
	v_mfma_f32_16x16x32_bf16 v[28:31], v[144:147], v[208:211], v[28:31]
	v_mfma_f32_16x16x32_bf16 v[24:27], v[160:163], v[208:211], v[24:27]
	v_mfma_f32_16x16x32_bf16 v[12:15], v[144:147], v[216:219], v[12:15]
	v_mfma_f32_16x16x32_bf16 v[8:11], v[160:163], v[216:219], v[8:11]
	v_mfma_f32_16x16x32_bf16 v[60:63], v[156:159], v[190:193], v[60:63]
	v_mfma_f32_16x16x32_bf16 v[56:59], v[164:167], v[190:193], v[56:59]
	v_mfma_f32_16x16x32_bf16 v[44:47], v[156:159], v[198:201], v[44:47]
	v_mfma_f32_16x16x32_bf16 v[40:43], v[164:167], v[198:201], v[40:43]
	v_mfma_f32_16x16x32_bf16 v[28:31], v[156:159], v[212:215], v[28:31]
	v_mfma_f32_16x16x32_bf16 v[24:27], v[164:167], v[212:215], v[24:27]
	v_lshl_add_u64 v[228:229], s[56:57], 0, v[128:129]
	s_mov_b32 m0, s34
	s_nop 0
	global_load_lds_dwordx4 v[228:229], off
	v_mfma_f32_16x16x32_bf16 v[12:15], v[156:159], v[220:223], v[12:15]
	v_mfma_f32_16x16x32_bf16 v[8:11], v[164:167], v[220:223], v[8:11]
	s_setprio 0
	s_setprio 1
	v_mfma_f32_16x16x32_bf16 v[52:55], v[168:171], v[186:189], v[52:55]
	v_mfma_f32_16x16x32_bf16 v[48:51], v[176:179], v[186:189], v[48:51]
	v_mfma_f32_16x16x32_bf16 v[36:39], v[168:171], v[194:197], v[36:39]
	v_mfma_f32_16x16x32_bf16 v[32:35], v[176:179], v[194:197], v[32:35]
	v_mfma_f32_16x16x32_bf16 v[20:23], v[168:171], v[208:211], v[20:23]
	v_mfma_f32_16x16x32_bf16 v[16:19], v[176:179], v[208:211], v[16:19]
	v_mfma_f32_16x16x32_bf16 v[4:7], v[168:171], v[216:219], v[4:7]
	v_mfma_f32_16x16x32_bf16 v[0:3], v[176:179], v[216:219], v[0:3]
	v_mfma_f32_16x16x32_bf16 v[52:55], v[172:175], v[190:193], v[52:55]
	v_mfma_f32_16x16x32_bf16 v[48:51], v[182:185], v[190:193], v[48:51]
	v_mfma_f32_16x16x32_bf16 v[36:39], v[172:175], v[198:201], v[36:39]
	v_mfma_f32_16x16x32_bf16 v[32:35], v[182:185], v[198:201], v[32:35]
	v_mfma_f32_16x16x32_bf16 v[20:23], v[172:175], v[212:215], v[20:23]
	v_mfma_f32_16x16x32_bf16 v[16:19], v[182:185], v[212:215], v[16:19]
	v_lshl_add_u64 v[230:231], s[56:57], 0, v[132:133]
	s_mov_b32 m0, s58
	s_nop 0
	global_load_lds_dwordx4 v[230:231], off
	v_mfma_f32_16x16x32_bf16 v[4:7], v[172:175], v[220:223], v[4:7]
	v_mfma_f32_16x16x32_bf16 v[0:3], v[182:185], v[220:223], v[0:3]
	s_setprio 0
	s_barrier
; #define PG8_STAGE(bufoff, gbase, voff) do { _Pragma("unroll") for (int _i = 0; _i < 2; ++_i) \
;         __builtin_amdgcn_global_load_lds((const unsigned*)((const char*)(gbase) + (voff)[_i]), (PG8_LAS unsigned*)(lds + (bufoff) + ldsw + _i * 8192), 16, 0, 0); } while (0)
; #define PG8_LDA(dst, b, h) do { _Pragma("unroll") for (int m = 0; m < 4; ++m) _Pragma("unroll") for (int k = 0; k < 2; ++k) dst[m][k] = *(const PG8_LAS bf16x8*)(lds + PG8_SA(b, h) + aoff + m * 2048 + k * 1024); } while (0)
; #define PG8_LDB(dst, b, h) do { _Pragma("unroll") for (int n = 0; n < 2; ++n) _Pragma("unroll") for (int k = 0; k < 2; ++k) dst[n][k] = *(const PG8_LAS bf16x8*)(lds + PG8_SB(b, h) + boff + n * 2048 + k * 1024); } while (0)
; #define PG8_MMA(ai, bj, At, Bt) do { __builtin_amdgcn_s_setprio(1); _Pragma("unroll") for (int m = 0; m < 4; ++m) _Pragma("unroll") for (int n = 0; n < 2; ++n) _Pragma("unroll") for (int k = 0; k < 2; ++k) \
;         acc[ai][bj][m][n] = __builtin_amdgcn_mfma_f32_16x16x32_bf16(Bt[n][k], At[m][k], acc[ai][bj][m][n], 0, 0, 0); __builtin_amdgcn_s_setprio(0); } while (0)
; #define PG8_WAIT_V(n) asm volatile("s_waitcnt vmcnt(" #n ")" ::: "memory")
; template <class Epi, class Sched, bool ALIGN_EPI = false, bool SP2 = false>
; __device__ __forceinline__ void gemm_phase(PG8_LAS unsigned char* lds, const Gemm g, const Sched& S, const Epi& E) {
;     ...
;             PG8_LDB(B0, 0, 0); PG8_LDB(B1, 0, 1); PG8_SCHED; PG8_LDA(At, 0, 0); PG8_STAGE(PG8_SA(1, 1), a1 + hstep, voffA);
;             PG8_WAIT_V(8); PG8_WAIT_L(0); PG8_BAR; PG8_MMA(0, 0, At, B0); PG8_MMA(0, 1, At, B1); PG8_BAR; PG8_SCHED;
;             PG8_LDA(At, 0, 1); PG8_STAGE(PG8_SB(0, 0), b2, voffB); PG8_STAGE(PG8_SB(0, 1), b2 + hstep, voffB); PG8_STAGE(PG8_SA(0, 0), a2, voffA);
;             PG8_WAIT_V(8); PG8_WAIT_L(0); PG8_BAR; PG8_MMA(1, 0, At, B0); PG8_MMA(1, 1, At, B1); PG8_BAR; PG8_SCHED;
;             PG8_LDB(B0, 1, 0); PG8_LDB(B1, 1, 1); PG8_SCHED; PG8_LDA(At, 1, 0); PG8_STAGE(PG8_SA(0, 1), a2 + hstep, voffA);
;             PG8_WAIT_V(8); PG8_WAIT_L(0); PG8_BAR; PG8_MMA(0, 0, At, B0); PG8_MMA(0, 1, At, B1); PG8_BAR; PG8_SCHED;
;             PG8_LDA(At, 1, 1); PG8_STAGE(PG8_SB(1, 0), b3, voffB); PG8_STAGE(PG8_SB(1, 1), b3 + hstep, voffB); PG8_STAGE(PG8_SA(1, 0), a3, voffA);
;             PG8_WAIT_V(8); PG8_WAIT_L(0); PG8_BAR; PG8_MMA(1, 0, At, B0); PG8_MMA(1, 1, At, B1); PG8_BAR; PG8_SCHED;
	s_add_i32 s78, 0, 0x18000
	v_add_u32_e32 v155, s78, v149
	s_add_i32 s79, 0, 0x1c000
	ds_read_b128 v[144:147], v155
	ds_read_b128 v[156:159], v155 offset:1024
	ds_read_b128 v[160:163], v155 offset:2048
	ds_read_b128 v[164:167], v155 offset:3072
	v_add_u32_e32 v155, s79, v149
	ds_read_b128 v[168:171], v155
	ds_read_b128 v[172:175], v155 offset:1024
	ds_read_b128 v[176:179], v155 offset:2048
	ds_read_b128 v[182:185], v155 offset:3072
	s_add_u32 s50, s56, 0xb0000
	s_addc_u32 s51, s57, 0
	s_mov_b32 m0, s59
	v_lshl_add_u64 v[232:233], s[50:51], 0, v[128:129]
	ds_read_b128 v[186:189], v153 offset:32768
	ds_read_b128 v[190:193], v153 offset:33792
	ds_read_b128 v[194:197], v153 offset:34816
	ds_read_b128 v[198:201], v153 offset:35840
	ds_read_b128 v[208:211], v153 offset:36864
	ds_read_b128 v[212:215], v153 offset:37888
	ds_read_b128 v[216:219], v153 offset:38912
	ds_read_b128 v[220:223], v153 offset:39936
	global_load_lds_dwordx4 v[232:233], off
	v_lshl_add_u64 v[232:233], s[50:51], 0, v[132:133]
	s_mov_b32 m0, s60
	s_nop 0
	global_load_lds_dwordx4 v[232:233], off
	s_waitcnt vmcnt(8)
	s_waitcnt lgkmcnt(0)
	s_barrier
	s_setprio 1
	s_waitcnt lgkmcnt(0)
	v_mfma_f32_16x16x32_bf16 v[124:127], v[144:147], v[186:189], v[124:127]
	v_mfma_f32_16x16x32_bf16 v[120:123], v[160:163], v[186:189], v[120:123]
	v_mfma_f32_16x16x32_bf16 v[108:111], v[144:147], v[194:197], v[108:111]
	v_mfma_f32_16x16x32_bf16 v[104:107], v[160:163], v[194:197], v[104:107]
	v_mfma_f32_16x16x32_bf16 v[92:95], v[144:147], v[208:211], v[92:95]
	v_mfma_f32_16x16x32_bf16 v[88:91], v[160:163], v[208:211], v[88:91]
	v_mfma_f32_16x16x32_bf16 v[76:79], v[144:147], v[216:219], v[76:79]
	v_mfma_f32_16x16x32_bf16 v[72:75], v[160:163], v[216:219], v[72:75]
	v_mfma_f32_16x16x32_bf16 v[124:127], v[156:159], v[190:193], v[124:127]
	v_mfma_f32_16x16x32_bf16 v[120:123], v[164:167], v[190:193], v[120:123]
	v_mfma_f32_16x16x32_bf16 v[108:111], v[156:159], v[198:201], v[108:111]
	v_mfma_f32_16x16x32_bf16 v[104:107], v[164:167], v[198:201], v[104:107]
	v_mfma_f32_16x16x32_bf16 v[92:95], v[156:159], v[212:215], v[92:95]
	v_mfma_f32_16x16x32_bf16 v[88:91], v[164:167], v[212:215], v[88:91]
	v_mfma_f32_16x16x32_bf16 v[76:79], v[156:159], v[220:223], v[76:79]
	v_mfma_f32_16x16x32_bf16 v[72:75], v[164:167], v[220:223], v[72:75]
	s_setprio 0
	s_setprio 1
	v_mfma_f32_16x16x32_bf16 v[116:119], v[168:171], v[186:189], v[116:119]
	v_mfma_f32_16x16x32_bf16 v[112:115], v[176:179], v[186:189], v[112:115]
	v_mfma_f32_16x16x32_bf16 v[100:103], v[168:171], v[194:197], v[100:103]
	v_mfma_f32_16x16x32_bf16 v[96:99], v[176:179], v[194:197], v[96:99]
	v_mfma_f32_16x16x32_bf16 v[84:87], v[168:171], v[208:211], v[84:87]
	v_mfma_f32_16x16x32_bf16 v[80:83], v[176:179], v[208:211], v[80:83]
	v_mfma_f32_16x16x32_bf16 v[68:71], v[168:171], v[216:219], v[68:71]
	v_mfma_f32_16x16x32_bf16 v[64:67], v[176:179], v[216:219], v[64:67]
	v_mfma_f32_16x16x32_bf16 v[116:119], v[172:175], v[190:193], v[116:119]
	v_mfma_f32_16x16x32_bf16 v[112:115], v[182:185], v[190:193], v[112:115]
	v_mfma_f32_16x16x32_bf16 v[100:103], v[172:175], v[198:201], v[100:103]
	v_mfma_f32_16x16x32_bf16 v[96:99], v[182:185], v[198:201], v[96:99]
	v_mfma_f32_16x16x32_bf16 v[84:87], v[172:175], v[212:215], v[84:87]
	v_mfma_f32_16x16x32_bf16 v[80:83], v[182:185], v[212:215], v[80:83]
	v_mfma_f32_16x16x32_bf16 v[68:71], v[172:175], v[220:223], v[68:71]
	v_mfma_f32_16x16x32_bf16 v[64:67], v[182:185], v[220:223], v[64:67]
	s_setprio 0
	s_barrier
	s_add_i32 s50, s78, s33
	v_lshl_add_u64 v[224:225], v[224:225], 0, s[42:43]
	s_mov_b32 m0, s50
	ds_read_b128 v[186:189], v153 offset:49152
	ds_read_b128 v[190:193], v153 offset:50176
	ds_read_b128 v[194:197], v153 offset:51200
	ds_read_b128 v[198:201], v153 offset:52224
	ds_read_b128 v[208:211], v153 offset:53248
	ds_read_b128 v[212:215], v153 offset:54272
	ds_read_b128 v[216:219], v153 offset:55296
	ds_read_b128 v[220:223], v153 offset:56320
	global_load_lds_dwordx4 v[224:225], off
	s_add_i32 m0, s50, 0x2000
	s_add_u32 s50, s54, 0xb0080
	v_lshl_add_u64 v[224:225], v[226:227], 0, s[42:43]
	s_addc_u32 s51, s55, 0
	s_add_i32 s54, s79, s33
	global_load_lds_dwordx4 v[224:225], off
	v_lshl_add_u64 v[224:225], s[50:51], 0, v[130:131]
	s_mov_b32 m0, s54
	s_nop 0
	global_load_lds_dwordx4 v[224:225], off
	v_lshl_add_u64 v[224:225], s[50:51], 0, v[134:135]
	s_add_i32 m0, s54, 0x2000
	s_nop 0
	global_load_lds_dwordx4 v[224:225], off
	s_waitcnt vmcnt(6)
	s_waitcnt lgkmcnt(0)
	s_barrier
; #define PG8_BAR __builtin_amdgcn_s_barrier()
;     __device__ __forceinline__ void operator()(const f32x4 (&acc)[2][2][4][2], const Unit& u, int wr, int wc, int fr, int fq) const {
;     ...
;             for (int m = 0; m < 4; ++m) { const int row = row0 + ai * HALF + m * 16; const size_t off = (size_t)row * 1024 + col0; float s = 0.f;
; #pragma unroll
;                 for (int bj = 0; bj < 2; ++bj) { f32x4 a0, a1;
;                     if (xin32) { const float* p = xin32 + off + bj * HALF; a0 = *(const f32x4*)p; a1 = *(const f32x4*)(p + 4); }
;                     else { const u32x4 w = *(const u32x4*)(xb + off + bj * HALF);
; template <class Epi, class Sched, bool ALIGN_EPI = false, bool SP2 = false>
; __device__ __forceinline__ void gemm_phase(PG8_LAS unsigned char* lds, const Gemm g, const Sched& S, const Epi& E) {
;     ...
;             PG8_WAIT_V(8); PG8_WAIT_L(0); PG8_BAR; PG8_MMA(1, 0, At, B0); PG8_MMA(1, 1, At, B1); PG8_BAR; PG8_SCHED;
;             } else {
;             PG8_LDB(B0, 0, 0); PG8_SCHED; PG8_LDA(At, 0, 0); PG8_STAGE(PG8_SA(1, 1), a1 + hstep, voffA);
;             PG8_WAIT_L(8); PG8_BAR; PG8_WAIT_L(0); PG8_MMA(0, 0, At, B0); PG8_BAR; PG8_SCHED;
;             PG8_LDB(B1, 0, 1); PG8_STAGE(PG8_SB(0, 0), b2, voffB);
;             PG8_BAR; PG8_WAIT_L(0); PG8_MMA(0, 1, At, B1); PG8_BAR;
;             PG8_LDA(At, 0, 1); PG8_STAGE(PG8_SA(0, 0), a2, voffA);
;             PG8_BAR; PG8_WAIT_L(0); PG8_MMA(1, 0, At, B0); PG8_BAR; PG8_SCHED;
;             PG8_STAGE(PG8_SB(0, 1), b2 + hstep, voffB);
;             PG8_WAIT_V(6); PG8_BAR; PG8_MMA(1, 1, At, B1); PG8_BAR;
;             PG8_LDB(B0, 1, 0); PG8_SCHED; PG8_LDA(At, 1, 0); PG8_STAGE(PG8_SA(0, 1), a2 + hstep, voffA);
;             PG8_WAIT_L(8); PG8_BAR; PG8_WAIT_L(0); PG8_MMA(0, 0, At, B0); PG8_BAR; PG8_SCHED;
;             PG8_LDB(B1, 1, 1); PG8_STAGE(PG8_SB(1, 0), b3, voffB);
;             PG8_BAR; PG8_WAIT_L(0); PG8_MMA(0, 1, At, B1); PG8_BAR;
;             PG8_LDA(At, 1, 1); PG8_STAGE(PG8_SA(1, 0), a3, voffA);
;             PG8_BAR; PG8_WAIT_L(0); PG8_MMA(1, 0, At, B0); PG8_BAR; PG8_SCHED;
;             PG8_STAGE(PG8_SB(1, 1), b3 + hstep, voffB);
;             PG8_WAIT_V(6); PG8_BAR; PG8_MMA(1, 1, At, B1); PG8_BAR;
;             }
;         }
;         if constexpr (ALIGN_EPI) { if (wr == 0) PG8_BAR; }
;         if constexpr (!Epi::AFTER_DRAIN) { E(acc, cur, wr, wc, fr, fq); S.done(cur); }
	s_setprio 1
	s_waitcnt lgkmcnt(0)
	v_mfma_f32_16x16x32_bf16 v[60:63], v[144:147], v[186:189], v[60:63]
	v_mfma_f32_16x16x32_bf16 v[56:59], v[160:163], v[186:189], v[56:59]
	v_mfma_f32_16x16x32_bf16 v[44:47], v[144:147], v[194:197], v[44:47]
	v_mfma_f32_16x16x32_bf16 v[40:43], v[160:163], v[194:197], v[40:43]
	v_mfma_f32_16x16x32_bf16 v[28:31], v[144:147], v[208:211], v[28:31]
	v_mfma_f32_16x16x32_bf16 v[24:27], v[160:163], v[208:211], v[24:27]
	v_mfma_f32_16x16x32_bf16 v[12:15], v[144:147], v[216:219], v[12:15]
	v_mfma_f32_16x16x32_bf16 v[8:11], v[160:163], v[216:219], v[8:11]
	v_mfma_f32_16x16x32_bf16 v[60:63], v[156:159], v[190:193], v[60:63]
	v_mfma_f32_16x16x32_bf16 v[56:59], v[164:167], v[190:193], v[56:59]
	v_mfma_f32_16x16x32_bf16 v[44:47], v[156:159], v[198:201], v[44:47]
	v_mfma_f32_16x16x32_bf16 v[40:43], v[164:167], v[198:201], v[40:43]
	v_mfma_f32_16x16x32_bf16 v[28:31], v[156:159], v[212:215], v[28:31]
	v_mfma_f32_16x16x32_bf16 v[24:27], v[164:167], v[212:215], v[24:27]
	v_lshl_add_u64 v[224:225], v[228:229], 0, s[42:43]
	s_mov_b32 m0, s62
	s_nop 0
	global_load_lds_dwordx4 v[224:225], off
	v_mfma_f32_16x16x32_bf16 v[12:15], v[156:159], v[220:223], v[12:15]
	v_mfma_f32_16x16x32_bf16 v[8:11], v[164:167], v[220:223], v[8:11]
	s_setprio 0
	s_setprio 1
	v_mfma_f32_16x16x32_bf16 v[52:55], v[168:171], v[186:189], v[52:55]
	v_mfma_f32_16x16x32_bf16 v[48:51], v[176:179], v[186:189], v[48:51]
	v_mfma_f32_16x16x32_bf16 v[36:39], v[168:171], v[194:197], v[36:39]
	v_mfma_f32_16x16x32_bf16 v[32:35], v[176:179], v[194:197], v[32:35]
	v_mfma_f32_16x16x32_bf16 v[20:23], v[168:171], v[208:211], v[20:23]
	v_mfma_f32_16x16x32_bf16 v[16:19], v[176:179], v[208:211], v[16:19]
	v_mfma_f32_16x16x32_bf16 v[4:7], v[168:171], v[216:219], v[4:7]
	v_mfma_f32_16x16x32_bf16 v[0:3], v[176:179], v[216:219], v[0:3]
	v_mfma_f32_16x16x32_bf16 v[52:55], v[172:175], v[190:193], v[52:55]
	v_mfma_f32_16x16x32_bf16 v[48:51], v[182:185], v[190:193], v[48:51]
	v_mfma_f32_16x16x32_bf16 v[36:39], v[172:175], v[198:201], v[36:39]
	v_mfma_f32_16x16x32_bf16 v[32:35], v[182:185], v[198:201], v[32:35]
	v_mfma_f32_16x16x32_bf16 v[20:23], v[172:175], v[212:215], v[20:23]
	v_mfma_f32_16x16x32_bf16 v[16:19], v[182:185], v[212:215], v[16:19]
	v_lshl_add_u64 v[224:225], v[230:231], 0, s[42:43]
	s_mov_b32 m0, s63
	s_nop 0
	global_load_lds_dwordx4 v[224:225], off
	v_mfma_f32_16x16x32_bf16 v[4:7], v[172:175], v[220:223], v[4:7]
	v_mfma_f32_16x16x32_bf16 v[0:3], v[182:185], v[220:223], v[0:3]
	s_setprio 0
	s_barrier
	s_add_i32 s84, s84, 2
	s_add_u32 s82, s82, 0x100
	s_addc_u32 s83, s83, 0
	s_cmp_gt_u32 s84, 41
	s_mov_b64 s[50:51], s[52:53]
	s_cbranch_scc0 .LBB0_1197
	s_and_b64 vcc, exec, s[44:45]
	s_cbranch_vccz .LBB0_1200
.LBB0_1200:
	v_lshl_add_u32 v146, s77, 8, v148
	v_ashrrev_i32_e32 v147, 31, v146
	v_lshl_or_b32 v144, s76, 8, v150
	v_lshlrev_b64 v[156:157], 11, v[146:147]
	v_ashrrev_i32_e32 v145, 31, v144
	v_lshl_add_u64 v[156:157], s[22:23], 0, v[156:157]
	v_lshl_add_u64 v[166:167], v[144:145], 1, v[156:157]
	global_load_dwordx4 v[158:161], v[166:167], off
	global_load_dwordx4 v[162:165], v[166:167], off offset:256
	v_and_b32_e32 v156, 64, v154
	v_xor_b32_e32 v155, 16, v154
	v_add_u32_e32 v156, 64, v156
	v_xor_b32_e32 v157, 32, v154
	v_cmp_lt_i32_e32 vcc, v155, v156
	s_waitcnt vmcnt(0)
	v_lshlrev_b32_e32 v168, 16, v158
	v_cndmask_b32_e32 v155, v154, v155, vcc
	v_cmp_lt_i32_e32 vcc, v157, v156
	v_and_b32_e32 v169, 0xffff0000, v158
	v_lshlrev_b32_e32 v158, 16, v159
	v_and_b32_e32 v159, 0xffff0000, v159
	v_lshlrev_b32_e32 v172, 16, v162
	v_and_b32_e32 v173, 0xffff0000, v162
	v_lshlrev_b32_e32 v162, 16, v163
	v_and_b32_e32 v163, 0xffff0000, v163
	v_cndmask_b32_e32 v157, v154, v157, vcc
	v_lshlrev_b32_e32 v170, 16, v160
	v_and_b32_e32 v171, 0xffff0000, v160
	v_lshlrev_b32_e32 v160, 16, v161
	v_and_b32_e32 v161, 0xffff0000, v161
	v_lshlrev_b32_e32 v174, 16, v164
	v_and_b32_e32 v175, 0xffff0000, v164
	v_lshlrev_b32_e32 v164, 16, v165
	v_and_b32_e32 v165, 0xffff0000, v165
	v_pk_fma_f32 v[126:127], v[126:127], 0.5, v[158:159] op_sel_hi:[1,0,1]
	v_pk_fma_f32 v[124:125], v[124:125], 0.5, v[168:169] op_sel_hi:[1,0,1]
	v_pk_fma_f32 v[118:119], v[118:119], 0.5, v[162:163] op_sel_hi:[1,0,1]
	v_pk_fma_f32 v[116:117], v[116:117], 0.5, v[172:173] op_sel_hi:[1,0,1]
	v_lshlrev_b32_e32 v156, 2, v155
	v_lshlrev_b32_e32 v155, 2, v157
	v_pk_fma_f32 v[122:123], v[122:123], 0.5, v[160:161] op_sel_hi:[1,0,1]
	v_pk_fma_f32 v[120:121], v[120:121], 0.5, v[170:171] op_sel_hi:[1,0,1]
	v_pk_fma_f32 v[158:159], v[114:115], 0.5, v[164:165] op_sel_hi:[1,0,1]
	v_pk_fma_f32 v[160:161], v[112:113], 0.5, v[174:175] op_sel_hi:[1,0,1]
	v_mul_f32_e32 v114, v125, v125
	v_mul_f32_e32 v115, v127, v127
	v_mul_f32_e32 v157, v117, v117
	v_mul_f32_e32 v162, v119, v119
	v_cvt_pk_bf16_f32 v112, v124, v125
	v_mul_f32_e32 v125, v121, v121
	v_mul_f32_e32 v163, v161, v161
	v_fmac_f32_e32 v114, v124, v124
	v_fmac_f32_e32 v115, v126, v126
	v_fmac_f32_e32 v157, v116, v116
	v_fmac_f32_e32 v162, v118, v118
	v_cvt_pk_bf16_f32 v113, v126, v127
	v_mul_f32_e32 v127, v123, v123
	v_mul_f32_e32 v164, v159, v159
	v_fmac_f32_e32 v125, v120, v120
	v_fmac_f32_e32 v163, v160, v160
	v_add_f32_e32 v114, v114, v115
	v_add_f32_e32 v115, v157, v162
	v_fmac_f32_e32 v127, v122, v122
	v_fmac_f32_e32 v164, v158, v158
	v_add_f32_e32 v114, v125, v114
	v_add_f32_e32 v115, v163, v115
	v_add_f32_e32 v114, v127, v114
	v_add_f32_e32 v115, v164, v115
	v_add_f32_e32 v124, v114, v115
	ds_bpermute_b32 v125, v156, v124
	v_cvt_pk_bf16_f32 v114, v120, v121
	v_cvt_pk_bf16_f32 v115, v122, v123
	global_store_dwordx4 v[166:167], v[112:115], off
	s_waitcnt lgkmcnt(0)
	s_nop 0
	v_add_f32_e32 v112, v124, v125
	ds_bpermute_b32 v113, v155, v112
	v_cvt_pk_bf16_f32 v114, v116, v117
	v_cvt_pk_bf16_f32 v115, v118, v119
	v_cvt_pk_bf16_f32 v116, v160, v161
	v_cvt_pk_bf16_f32 v117, v158, v159
	global_store_dwordx4 v[166:167], v[114:117], off offset:256
	s_and_saveexec_b64 s[50:51], s[10:11]
	s_cbranch_execz .LBB0_1202
	s_waitcnt lgkmcnt(0)
	v_add_f32_e32 v112, v112, v113
	v_mul_f32_e32 v112, 0x4f800000, v112
	v_trunc_f32_e32 v112, v112
	v_mul_f32_e64 v113, |v112|, s66
	v_floor_f32_e32 v113, v113
	v_fma_f32 v114, v113, s67, |v112|
	v_cvt_u32_f32_e32 v114, v114
	v_cvt_u32_f32_e32 v113, v113
	v_ashrrev_i32_e32 v115, 31, v112
	v_xor_b32_e32 v112, v114, v115
	v_xor_b32_e32 v113, v113, v115
	v_sub_co_u32_e32 v112, vcc, v112, v115
	s_nop 1
	v_subb_co_u32_e32 v113, vcc, v113, v115, vcc
	v_lshl_add_u64 v[114:115], v[146:147], 3, s[36:37]
	global_atomic_add_x2 v[114:115], v[112:113], off

; #define PG8_STAGE(bufoff, gbase, voff) do { _Pragma("unroll") for (int _i = 0; _i < 2; ++_i) \
;         __builtin_amdgcn_global_load_lds((const unsigned*)((const char*)(gbase) + (voff)[_i]), (PG8_LAS unsigned*)(lds + (bufoff) + ldsw + _i * 8192), 16, 0, 0); } while (0)
; #define PG8_LDA(dst, b, h) do { _Pragma("unroll") for (int m = 0; m < 4; ++m) _Pragma("unroll") for (int k = 0; k < 2; ++k) dst[m][k] = *(const PG8_LAS bf16x8*)(lds + PG8_SA(b, h) + aoff + m * 2048 + k * 1024); } while (0)
; #define PG8_LDB(dst, b, h) do { _Pragma("unroll") for (int n = 0; n < 2; ++n) _Pragma("unroll") for (int k = 0; k < 2; ++k) dst[n][k] = *(const PG8_LAS bf16x8*)(lds + PG8_SB(b, h) + boff + n * 2048 + k * 1024); } while (0)
; #define PG8_WAIT_V(n) asm volatile("s_waitcnt vmcnt(" #n ")" ::: "memory")
; #define PG8_WAIT_L(n) asm volatile("s_waitcnt lgkmcnt(" #n ")" ::: "memory")
; #define PG8_BAR __builtin_amdgcn_s_barrier()
; #define PG8_SCHED __builtin_amdgcn_sched_barrier(0)
; template <class Epi, class Sched, bool ALIGN_EPI = false, bool SP2 = false>
; __device__ __forceinline__ void gemm_phase(PG8_LAS unsigned char* lds, const Gemm g, const Sched& S, const Epi& E) {
;     ...
;         const bool has_next = S.next(ui + 1, nxt);
;         const char* nA = has_next ? (const char*)g.A + (size_t)nxt.pm * tstep : cA; const char* nB = has_next ? (const char*)g.Bt + (size_t)nxt.pn * tstep : cB;
;         for (int t = 0; t < nt; t += 2) {
;             const bool last = (t == nt - 2);
;             const char* a1 = cA + (size_t)(t + 1) * kstep;
;             const char* a2 = last ? nA : cA + (size_t)(t + 2) * kstep; const char* b2 = last ? nB : cB + (size_t)(t + 2) * kstep;
;             const char* a3 = a2 + kstep; const char* b3 = b2 + kstep;
;             if (last && has_next) S.a_ready(nxt);
;             if constexpr (SP2) {
;             PG8_LDB(B0, 0, 0); PG8_LDB(B1, 0, 1); PG8_SCHED; PG8_LDA(At, 0, 0); PG8_STAGE(PG8_SA(1, 1), a1 + hstep, voffA);
;             PG8_WAIT_V(8); PG8_WAIT_L(0); PG8_BAR; PG8_MMA(0, 0, At, B0); PG8_MMA(0, 1, At, B1); PG8_BAR; PG8_SCHED;
;             PG8_LDA(At, 0, 1); PG8_STAGE(PG8_SB(0, 0), b2, voffB); PG8_STAGE(PG8_SB(0, 1), b2 + hstep, voffB); PG8_STAGE(PG8_SA(0, 0), a2, voffA);
;             PG8_WAIT_V(8); PG8_WAIT_L(0); PG8_BAR; PG8_MMA(1, 0, At, B0); PG8_MMA(1, 1, At, B1); PG8_BAR; PG8_SCHED;
.LBB0_1592:
	s_ashr_i32 s39, s38, 31
	s_lshl_b64 s[42:43], s[38:39], 19
	s_add_u32 s42, s40, s42
	s_addc_u32 s43, s41, s43
	s_and_b64 s[44:45], s[10:11], exec
	s_cselect_b32 s39, s43, s51
	s_cselect_b32 s47, s42, s50
	s_ashr_i32 s37, s36, 31
	s_lshl_b64 s[44:45], s[36:37], 19
	v_readlane_b32 s54, v250, 11
	v_readlane_b32 s55, v250, 12
	s_add_u32 s44, s54, s44
	s_addc_u32 s45, s55, s45
	s_and_b64 s[54:55], s[10:11], exec
	s_cselect_b32 s37, s45, s53
	s_cselect_b32 s64, s44, s52
	s_add_u32 s50, s50, 0x40080
	s_addc_u32 s51, s51, 0
	s_add_u32 s65, s52, 0x100
	s_addc_u32 s66, s53, 0
	s_mov_b32 s67, -2
	s_waitcnt lgkmcnt(0)
	ds_read_b128 v[146:149], v152
	ds_read_b128 v[156:159], v152 offset:1024
	ds_read_b128 v[160:163], v152 offset:2048
	ds_read_b128 v[164:167], v152 offset:3072
	ds_read_b128 v[168:171], v153
	ds_read_b128 v[172:175], v153 offset:1024
	ds_read_b128 v[180:183], v153 offset:2048
	ds_read_b128 v[184:187], v153 offset:3072
	s_add_u32 s52, s50, 0xfffc0080
	s_addc_u32 s53, s51, -1
	s_cmp_eq_u32 s67, 12
	s_cselect_b32 s55, s39, s53
	s_cselect_b32 s54, s47, s52
	s_cselect_b32 s53, s37, s66
	s_cselect_b32 s52, s64, s65
	v_lshl_add_u64 v[200:201], s[50:51], 0, v[136:137]
	s_add_i32 m0, s33, 0xc000
	ds_read_b128 v[188:191], v154
	ds_read_b128 v[192:195], v154 offset:1024
	ds_read_b128 v[196:199], v154 offset:2048
	ds_read_b128 v[206:209], v154 offset:3072
	ds_read_b128 v[210:213], v154 offset:4096
	ds_read_b128 v[214:217], v154 offset:5120
	ds_read_b128 v[218:221], v154 offset:6144
	ds_read_b128 v[222:225], v154 offset:7168
	global_load_lds_dwordx4 v[200:201], off
	v_lshl_add_u64 v[200:201], s[50:51], 0, v[138:139]
	s_add_i32 m0, s33, 0xe000
	s_nop 0
	global_load_lds_dwordx4 v[200:201], off
	s_waitcnt vmcnt(8)
	s_waitcnt lgkmcnt(0)
	s_barrier
	s_setprio 1
	s_waitcnt lgkmcnt(0)
	v_mfma_f32_16x16x32_bf16 v[124:127], v[146:149], v[188:191], 0
	v_mfma_f32_16x16x32_bf16 v[120:123], v[160:163], v[188:191], 0
	v_mfma_f32_16x16x32_bf16 v[108:111], v[146:149], v[196:199], 0
	v_mfma_f32_16x16x32_bf16 v[104:107], v[160:163], v[196:199], 0
	v_mfma_f32_16x16x32_bf16 v[92:95], v[146:149], v[210:213], 0
	v_mfma_f32_16x16x32_bf16 v[88:91], v[160:163], v[210:213], 0
	v_mfma_f32_16x16x32_bf16 v[76:79], v[146:149], v[218:221], 0
	v_mfma_f32_16x16x32_bf16 v[72:75], v[160:163], v[218:221], 0
	v_mfma_f32_16x16x32_bf16 v[124:127], v[156:159], v[192:195], v[124:127]
	v_mfma_f32_16x16x32_bf16 v[120:123], v[164:167], v[192:195], v[120:123]
	v_mfma_f32_16x16x32_bf16 v[108:111], v[156:159], v[206:209], v[108:111]
	v_mfma_f32_16x16x32_bf16 v[104:107], v[164:167], v[206:209], v[104:107]
	v_mfma_f32_16x16x32_bf16 v[92:95], v[156:159], v[214:217], v[92:95]
	v_mfma_f32_16x16x32_bf16 v[88:91], v[164:167], v[214:217], v[88:91]
	v_mfma_f32_16x16x32_bf16 v[76:79], v[156:159], v[222:225], v[76:79]
	v_mfma_f32_16x16x32_bf16 v[72:75], v[164:167], v[222:225], v[72:75]
	s_setprio 0
	s_setprio 1
	v_mfma_f32_16x16x32_bf16 v[116:119], v[168:171], v[188:191], 0
	v_mfma_f32_16x16x32_bf16 v[112:115], v[180:183], v[188:191], 0
	v_mfma_f32_16x16x32_bf16 v[100:103], v[168:171], v[196:199], 0
	v_mfma_f32_16x16x32_bf16 v[96:99], v[180:183], v[196:199], 0
	v_mfma_f32_16x16x32_bf16 v[84:87], v[168:171], v[210:213], 0
	v_mfma_f32_16x16x32_bf16 v[80:83], v[180:183], v[210:213], 0
	v_mfma_f32_16x16x32_bf16 v[68:71], v[168:171], v[218:221], 0
	v_mfma_f32_16x16x32_bf16 v[64:67], v[180:183], v[218:221], 0
	v_mfma_f32_16x16x32_bf16 v[116:119], v[172:175], v[192:195], v[116:119]
	v_mfma_f32_16x16x32_bf16 v[112:115], v[184:187], v[192:195], v[112:115]
	v_mfma_f32_16x16x32_bf16 v[100:103], v[172:175], v[206:209], v[100:103]
	v_mfma_f32_16x16x32_bf16 v[96:99], v[184:187], v[206:209], v[96:99]
	v_mfma_f32_16x16x32_bf16 v[84:87], v[172:175], v[214:217], v[84:87]
	v_mfma_f32_16x16x32_bf16 v[80:83], v[184:187], v[214:217], v[80:83]
	v_mfma_f32_16x16x32_bf16 v[68:71], v[172:175], v[222:225], v[68:71]
	v_mfma_f32_16x16x32_bf16 v[64:67], v[184:187], v[222:225], v[64:67]
	s_setprio 0
	s_barrier
	s_add_i32 s74, s60, s15
	v_lshl_add_u64 v[200:201], s[52:53], 0, v[130:131]
	s_mov_b32 m0, s74
	ds_read_b128 v[188:191], v154 offset:16384
	ds_read_b128 v[192:195], v154 offset:17408
	ds_read_b128 v[196:199], v154 offset:18432
	ds_read_b128 v[206:209], v154 offset:19456
	ds_read_b128 v[210:213], v154 offset:20480
	ds_read_b128 v[214:217], v154 offset:21504
	ds_read_b128 v[218:221], v154 offset:22528
	ds_read_b128 v[222:225], v154 offset:23552
	global_load_lds_dwordx4 v[200:201], off
	s_add_i32 m0, s74, 0x2000
	s_add_u32 s74, s52, 0x40000
	v_lshl_add_u64 v[226:227], s[52:53], 0, v[134:135]
	s_addc_u32 s75, s53, 0
	s_add_i32 s76, s61, s15
	global_load_lds_dwordx4 v[226:227], off
	v_lshl_add_u64 v[228:229], s[74:75], 0, v[130:131]
	s_mov_b32 m0, s76
	global_load_lds_dwordx4 v[228:229], off
	v_lshl_add_u64 v[228:229], s[74:75], 0, v[134:135]
	s_add_i32 m0, s76, 0x2000
	s_nop 0
	global_load_lds_dwordx4 v[228:229], off
	s_waitcnt vmcnt(6)
	s_waitcnt lgkmcnt(0)
	s_barrier
; #define PG8_STAGE(bufoff, gbase, voff) do { _Pragma("unroll") for (int _i = 0; _i < 2; ++_i) \
;         __builtin_amdgcn_global_load_lds((const unsigned*)((const char*)(gbase) + (voff)[_i]), (PG8_LAS unsigned*)(lds + (bufoff) + ldsw + _i * 8192), 16, 0, 0); } while (0)
; #define PG8_LDA(dst, b, h) do { _Pragma("unroll") for (int m = 0; m < 4; ++m) _Pragma("unroll") for (int k = 0; k < 2; ++k) dst[m][k] = *(const PG8_LAS bf16x8*)(lds + PG8_SA(b, h) + aoff + m * 2048 + k * 1024); } while (0)
; #define PG8_LDB(dst, b, h) do { _Pragma("unroll") for (int n = 0; n < 2; ++n) _Pragma("unroll") for (int k = 0; k < 2; ++k) dst[n][k] = *(const PG8_LAS bf16x8*)(lds + PG8_SB(b, h) + boff + n * 2048 + k * 1024); } while (0)
; #define PG8_MMA(ai, bj, At, Bt) do { __builtin_amdgcn_s_setprio(1); _Pragma("unroll") for (int m = 0; m < 4; ++m) _Pragma("unroll") for (int n = 0; n < 2; ++n) _Pragma("unroll") for (int k = 0; k < 2; ++k) \
;         acc[ai][bj][m][n] = __builtin_amdgcn_mfma_f32_16x16x32_bf16(Bt[n][k], At[m][k], acc[ai][bj][m][n], 0, 0, 0); __builtin_amdgcn_s_setprio(0); } while (0)
; #define PG8_WAIT_V(n) asm volatile("s_waitcnt vmcnt(" #n ")" ::: "memory")
; #define PG8_WAIT_L(n) asm volatile("s_waitcnt lgkmcnt(" #n ")" ::: "memory")
; #define PG8_BAR __builtin_amdgcn_s_barrier()
; #define PG8_SCHED __builtin_amdgcn_sched_barrier(0)
; template <class Epi, class Sched, bool ALIGN_EPI = false, bool SP2 = false>
; __device__ __forceinline__ void gemm_phase(PG8_LAS unsigned char* lds, const Gemm g, const Sched& S, const Epi& E) {
;     ...
;             PG8_LDA(At, 0, 1); PG8_STAGE(PG8_SB(0, 0), b2, voffB); PG8_STAGE(PG8_SB(0, 1), b2 + hstep, voffB); PG8_STAGE(PG8_SA(0, 0), a2, voffA);
;             PG8_WAIT_V(8); PG8_WAIT_L(0); PG8_BAR; PG8_MMA(1, 0, At, B0); PG8_MMA(1, 1, At, B1); PG8_BAR; PG8_SCHED;
;             PG8_LDB(B0, 1, 0); PG8_LDB(B1, 1, 1); PG8_SCHED; PG8_LDA(At, 1, 0); PG8_STAGE(PG8_SA(0, 1), a2 + hstep, voffA);
;             PG8_WAIT_V(8); PG8_WAIT_L(0); PG8_BAR; PG8_MMA(0, 0, At, B0); PG8_MMA(0, 1, At, B1); PG8_BAR; PG8_SCHED;
;             PG8_LDA(At, 1, 1); PG8_STAGE(PG8_SB(1, 0), b3, voffB); PG8_STAGE(PG8_SB(1, 1), b3 + hstep, voffB); PG8_STAGE(PG8_SA(1, 0), a3, voffA);
;             PG8_WAIT_V(8); PG8_WAIT_L(0); PG8_BAR; PG8_MMA(1, 0, At, B0); PG8_MMA(1, 1, At, B1); PG8_BAR; PG8_SCHED;
	s_setprio 1
	s_waitcnt lgkmcnt(0)
	v_mfma_f32_16x16x32_bf16 v[60:63], v[146:149], v[188:191], 0
	v_mfma_f32_16x16x32_bf16 v[56:59], v[160:163], v[188:191], 0
	v_mfma_f32_16x16x32_bf16 v[44:47], v[146:149], v[196:199], 0
	v_mfma_f32_16x16x32_bf16 v[40:43], v[160:163], v[196:199], 0
	v_mfma_f32_16x16x32_bf16 v[28:31], v[146:149], v[210:213], 0
	v_mfma_f32_16x16x32_bf16 v[24:27], v[160:163], v[210:213], 0
	v_mfma_f32_16x16x32_bf16 v[12:15], v[146:149], v[218:221], 0
	v_mfma_f32_16x16x32_bf16 v[8:11], v[160:163], v[218:221], 0
	v_mfma_f32_16x16x32_bf16 v[60:63], v[156:159], v[192:195], v[60:63]
	v_mfma_f32_16x16x32_bf16 v[56:59], v[164:167], v[192:195], v[56:59]
	v_mfma_f32_16x16x32_bf16 v[44:47], v[156:159], v[206:209], v[44:47]
	v_mfma_f32_16x16x32_bf16 v[40:43], v[164:167], v[206:209], v[40:43]
	v_mfma_f32_16x16x32_bf16 v[28:31], v[156:159], v[214:217], v[28:31]
	v_mfma_f32_16x16x32_bf16 v[24:27], v[164:167], v[214:217], v[24:27]
	v_lshl_add_u64 v[228:229], s[54:55], 0, v[128:129]
	s_mov_b32 m0, s33
	s_nop 0
	global_load_lds_dwordx4 v[228:229], off
	v_mfma_f32_16x16x32_bf16 v[12:15], v[156:159], v[222:225], v[12:15]
	v_mfma_f32_16x16x32_bf16 v[8:11], v[164:167], v[222:225], v[8:11]
	s_setprio 0
	s_setprio 1
	v_mfma_f32_16x16x32_bf16 v[52:55], v[168:171], v[188:191], 0
	v_mfma_f32_16x16x32_bf16 v[48:51], v[180:183], v[188:191], 0
	v_mfma_f32_16x16x32_bf16 v[36:39], v[168:171], v[196:199], 0
	v_mfma_f32_16x16x32_bf16 v[32:35], v[180:183], v[196:199], 0
	v_mfma_f32_16x16x32_bf16 v[20:23], v[168:171], v[210:213], 0
	v_mfma_f32_16x16x32_bf16 v[16:19], v[180:183], v[210:213], 0
	v_mfma_f32_16x16x32_bf16 v[4:7], v[168:171], v[218:221], 0
	v_mfma_f32_16x16x32_bf16 v[0:3], v[180:183], v[218:221], 0
	v_mfma_f32_16x16x32_bf16 v[52:55], v[172:175], v[192:195], v[52:55]
	v_mfma_f32_16x16x32_bf16 v[48:51], v[184:187], v[192:195], v[48:51]
	v_mfma_f32_16x16x32_bf16 v[36:39], v[172:175], v[206:209], v[36:39]
	v_mfma_f32_16x16x32_bf16 v[32:35], v[184:187], v[206:209], v[32:35]
	v_mfma_f32_16x16x32_bf16 v[20:23], v[172:175], v[214:217], v[20:23]
	v_mfma_f32_16x16x32_bf16 v[16:19], v[184:187], v[214:217], v[16:19]
	v_lshl_add_u64 v[230:231], s[54:55], 0, v[132:133]
	s_mov_b32 m0, s34
	s_nop 0
	global_load_lds_dwordx4 v[230:231], off
	v_mfma_f32_16x16x32_bf16 v[4:7], v[172:175], v[222:225], v[4:7]
	v_mfma_f32_16x16x32_bf16 v[0:3], v[184:187], v[222:225], v[0:3]
	s_setprio 0
	s_barrier
	s_add_i32 s74, 0, 0x18000
	s_add_i32 s75, 0, 0x1c000
	v_add_u32_e32 v164, s74, v150
	v_add_u32_e32 v179, s75, v150
	ds_read_b128 v[146:149], v164
	ds_read_b128 v[156:159], v164 offset:1024
	ds_read_b128 v[160:163], v164 offset:2048
	ds_read_b128 v[164:167], v164 offset:3072
	ds_read_b128 v[168:171], v179
	ds_read_b128 v[172:175], v179 offset:1024
	ds_read_b128 v[180:183], v179 offset:2048
	ds_read_b128 v[184:187], v179 offset:3072
	s_add_u32 s54, s54, 0x40000
	s_addc_u32 s55, s55, 0
	s_mov_b32 m0, s49
	v_lshl_add_u64 v[232:233], s[54:55], 0, v[128:129]
	ds_read_b128 v[188:191], v154 offset:32768
	ds_read_b128 v[192:195], v154 offset:33792
	ds_read_b128 v[196:199], v154 offset:34816
	ds_read_b128 v[206:209], v154 offset:35840
	ds_read_b128 v[210:213], v154 offset:36864
	ds_read_b128 v[214:217], v154 offset:37888
	ds_read_b128 v[218:221], v154 offset:38912
	ds_read_b128 v[222:225], v154 offset:39936
	global_load_lds_dwordx4 v[232:233], off
	v_lshl_add_u64 v[232:233], s[54:55], 0, v[132:133]
	s_mov_b32 m0, s56
	s_nop 0
	global_load_lds_dwordx4 v[232:233], off
	s_waitcnt vmcnt(8)
	s_waitcnt lgkmcnt(0)
	s_barrier
	s_setprio 1
	s_waitcnt lgkmcnt(0)
	v_mfma_f32_16x16x32_bf16 v[124:127], v[146:149], v[188:191], v[124:127]
	v_mfma_f32_16x16x32_bf16 v[120:123], v[160:163], v[188:191], v[120:123]
	v_mfma_f32_16x16x32_bf16 v[108:111], v[146:149], v[196:199], v[108:111]
	v_mfma_f32_16x16x32_bf16 v[104:107], v[160:163], v[196:199], v[104:107]
	v_mfma_f32_16x16x32_bf16 v[92:95], v[146:149], v[210:213], v[92:95]
	v_mfma_f32_16x16x32_bf16 v[88:91], v[160:163], v[210:213], v[88:91]
	v_mfma_f32_16x16x32_bf16 v[76:79], v[146:149], v[218:221], v[76:79]
	v_mfma_f32_16x16x32_bf16 v[72:75], v[160:163], v[218:221], v[72:75]
	v_mfma_f32_16x16x32_bf16 v[124:127], v[156:159], v[192:195], v[124:127]
	v_mfma_f32_16x16x32_bf16 v[120:123], v[164:167], v[192:195], v[120:123]
	v_mfma_f32_16x16x32_bf16 v[108:111], v[156:159], v[206:209], v[108:111]
	v_mfma_f32_16x16x32_bf16 v[104:107], v[164:167], v[206:209], v[104:107]
	v_mfma_f32_16x16x32_bf16 v[92:95], v[156:159], v[214:217], v[92:95]
	v_mfma_f32_16x16x32_bf16 v[88:91], v[164:167], v[214:217], v[88:91]
	v_mfma_f32_16x16x32_bf16 v[76:79], v[156:159], v[222:225], v[76:79]
	v_mfma_f32_16x16x32_bf16 v[72:75], v[164:167], v[222:225], v[72:75]
	s_setprio 0
	s_setprio 1
	v_mfma_f32_16x16x32_bf16 v[116:119], v[168:171], v[188:191], v[116:119]
	v_mfma_f32_16x16x32_bf16 v[112:115], v[180:183], v[188:191], v[112:115]
	v_mfma_f32_16x16x32_bf16 v[100:103], v[168:171], v[196:199], v[100:103]
	v_mfma_f32_16x16x32_bf16 v[96:99], v[180:183], v[196:199], v[96:99]
	v_mfma_f32_16x16x32_bf16 v[84:87], v[168:171], v[210:213], v[84:87]
	v_mfma_f32_16x16x32_bf16 v[80:83], v[180:183], v[210:213], v[80:83]
	v_mfma_f32_16x16x32_bf16 v[68:71], v[168:171], v[218:221], v[68:71]
	v_mfma_f32_16x16x32_bf16 v[64:67], v[180:183], v[218:221], v[64:67]
	v_mfma_f32_16x16x32_bf16 v[116:119], v[172:175], v[192:195], v[116:119]
	v_mfma_f32_16x16x32_bf16 v[112:115], v[184:187], v[192:195], v[112:115]
	v_mfma_f32_16x16x32_bf16 v[100:103], v[172:175], v[206:209], v[100:103]
	v_mfma_f32_16x16x32_bf16 v[96:99], v[184:187], v[206:209], v[96:99]
	v_mfma_f32_16x16x32_bf16 v[84:87], v[172:175], v[214:217], v[84:87]
	v_mfma_f32_16x16x32_bf16 v[80:83], v[184:187], v[214:217], v[80:83]
	v_mfma_f32_16x16x32_bf16 v[68:71], v[172:175], v[222:225], v[68:71]
	v_mfma_f32_16x16x32_bf16 v[64:67], v[184:187], v[222:225], v[64:67]
	s_setprio 0
	s_barrier
; #define PG8_STAGE(bufoff, gbase, voff) do { _Pragma("unroll") for (int _i = 0; _i < 2; ++_i) \
;         __builtin_amdgcn_global_load_lds((const unsigned*)((const char*)(gbase) + (voff)[_i]), (PG8_LAS unsigned*)(lds + (bufoff) + ldsw + _i * 8192), 16, 0, 0); } while (0)
; #define PG8_LDA(dst, b, h) do { _Pragma("unroll") for (int m = 0; m < 4; ++m) _Pragma("unroll") for (int k = 0; k < 2; ++k) dst[m][k] = *(const PG8_LAS bf16x8*)(lds + PG8_SA(b, h) + aoff + m * 2048 + k * 1024); } while (0)
; #define PG8_LDB(dst, b, h) do { _Pragma("unroll") for (int n = 0; n < 2; ++n) _Pragma("unroll") for (int k = 0; k < 2; ++k) dst[n][k] = *(const PG8_LAS bf16x8*)(lds + PG8_SB(b, h) + boff + n * 2048 + k * 1024); } while (0)
; #define PG8_MMA(ai, bj, At, Bt) do { __builtin_amdgcn_s_setprio(1); _Pragma("unroll") for (int m = 0; m < 4; ++m) _Pragma("unroll") for (int n = 0; n < 2; ++n) _Pragma("unroll") for (int k = 0; k < 2; ++k) \
;         acc[ai][bj][m][n] = __builtin_amdgcn_mfma_f32_16x16x32_bf16(Bt[n][k], At[m][k], acc[ai][bj][m][n], 0, 0, 0); __builtin_amdgcn_s_setprio(0); } while (0)
; #define PG8_WAIT_V(n) asm volatile("s_waitcnt vmcnt(" #n ")" ::: "memory")
; template <class Epi, class Sched, bool ALIGN_EPI = false, bool SP2 = false>
; __device__ __forceinline__ void gemm_phase(PG8_LAS unsigned char* lds, const Gemm g, const Sched& S, const Epi& E) {
;     ...
;             PG8_LDB(B0, 0, 0); PG8_LDB(B1, 0, 1); PG8_SCHED; PG8_LDA(At, 0, 0); PG8_STAGE(PG8_SA(1, 1), a1 + hstep, voffA);
;             PG8_WAIT_V(8); PG8_WAIT_L(0); PG8_BAR; PG8_MMA(0, 0, At, B0); PG8_MMA(0, 1, At, B1); PG8_BAR; PG8_SCHED;
;             PG8_LDA(At, 0, 1); PG8_STAGE(PG8_SB(0, 0), b2, voffB); PG8_STAGE(PG8_SB(0, 1), b2 + hstep, voffB); PG8_STAGE(PG8_SA(0, 0), a2, voffA);
;             PG8_WAIT_V(8); PG8_WAIT_L(0); PG8_BAR; PG8_MMA(1, 0, At, B0); PG8_MMA(1, 1, At, B1); PG8_BAR; PG8_SCHED;
;             PG8_LDB(B0, 1, 0); PG8_LDB(B1, 1, 1); PG8_SCHED; PG8_LDA(At, 1, 0); PG8_STAGE(PG8_SA(0, 1), a2 + hstep, voffA);
;             PG8_WAIT_V(8); PG8_WAIT_L(0); PG8_BAR; PG8_MMA(0, 0, At, B0); PG8_MMA(0, 1, At, B1); PG8_BAR; PG8_SCHED;
;             PG8_LDA(At, 1, 1); PG8_STAGE(PG8_SB(1, 0), b3, voffB); PG8_STAGE(PG8_SB(1, 1), b3 + hstep, voffB); PG8_STAGE(PG8_SA(1, 0), a3, voffA);
;             PG8_WAIT_V(8); PG8_WAIT_L(0); PG8_BAR; PG8_MMA(1, 0, At, B0); PG8_MMA(1, 1, At, B1); PG8_BAR; PG8_SCHED;
	s_add_i32 s54, s74, s15
	v_lshl_add_u64 v[200:201], v[200:201], 0, s[26:27]
	s_mov_b32 m0, s54
	ds_read_b128 v[188:191], v154 offset:49152
	ds_read_b128 v[192:195], v154 offset:50176
	ds_read_b128 v[196:199], v154 offset:51200
	ds_read_b128 v[206:209], v154 offset:52224
	ds_read_b128 v[210:213], v154 offset:53248
	ds_read_b128 v[214:217], v154 offset:54272
	ds_read_b128 v[218:221], v154 offset:55296
	ds_read_b128 v[222:225], v154 offset:56320
	global_load_lds_dwordx4 v[200:201], off
	s_add_i32 m0, s54, 0x2000
	s_add_u32 s52, s52, 0x40080
	v_lshl_add_u64 v[200:201], v[226:227], 0, s[26:27]
	s_addc_u32 s53, s53, 0
	s_add_i32 s54, s75, s15
	global_load_lds_dwordx4 v[200:201], off
	v_lshl_add_u64 v[200:201], s[52:53], 0, v[130:131]
	s_mov_b32 m0, s54
	s_nop 0
	global_load_lds_dwordx4 v[200:201], off
	v_lshl_add_u64 v[200:201], s[52:53], 0, v[134:135]
	s_add_i32 m0, s54, 0x2000
	s_nop 0
	global_load_lds_dwordx4 v[200:201], off
	s_waitcnt vmcnt(6)
	s_waitcnt lgkmcnt(0)
	s_barrier
	s_setprio 1
	s_waitcnt lgkmcnt(0)
	v_mfma_f32_16x16x32_bf16 v[60:63], v[146:149], v[188:191], v[60:63]
	v_mfma_f32_16x16x32_bf16 v[56:59], v[160:163], v[188:191], v[56:59]
	v_mfma_f32_16x16x32_bf16 v[44:47], v[146:149], v[196:199], v[44:47]
	v_mfma_f32_16x16x32_bf16 v[40:43], v[160:163], v[196:199], v[40:43]
	v_mfma_f32_16x16x32_bf16 v[28:31], v[146:149], v[210:213], v[28:31]
	v_mfma_f32_16x16x32_bf16 v[24:27], v[160:163], v[210:213], v[24:27]
	v_mfma_f32_16x16x32_bf16 v[12:15], v[146:149], v[218:221], v[12:15]
	v_mfma_f32_16x16x32_bf16 v[8:11], v[160:163], v[218:221], v[8:11]
	v_mfma_f32_16x16x32_bf16 v[60:63], v[156:159], v[192:195], v[60:63]
	v_mfma_f32_16x16x32_bf16 v[56:59], v[164:167], v[192:195], v[56:59]
	v_mfma_f32_16x16x32_bf16 v[44:47], v[156:159], v[206:209], v[44:47]
	v_mfma_f32_16x16x32_bf16 v[40:43], v[164:167], v[206:209], v[40:43]
	v_mfma_f32_16x16x32_bf16 v[28:31], v[156:159], v[214:217], v[28:31]
	v_mfma_f32_16x16x32_bf16 v[24:27], v[164:167], v[214:217], v[24:27]
	v_lshl_add_u64 v[200:201], v[228:229], 0, s[26:27]
	s_mov_b32 m0, s58
	s_nop 0
	global_load_lds_dwordx4 v[200:201], off
	v_mfma_f32_16x16x32_bf16 v[12:15], v[156:159], v[222:225], v[12:15]
	v_mfma_f32_16x16x32_bf16 v[8:11], v[164:167], v[222:225], v[8:11]
	s_setprio 0
	s_setprio 1
	v_mfma_f32_16x16x32_bf16 v[52:55], v[168:171], v[188:191], v[52:55]
	v_mfma_f32_16x16x32_bf16 v[48:51], v[180:183], v[188:191], v[48:51]
	v_mfma_f32_16x16x32_bf16 v[36:39], v[168:171], v[196:199], v[36:39]
	v_mfma_f32_16x16x32_bf16 v[32:35], v[180:183], v[196:199], v[32:35]
	v_mfma_f32_16x16x32_bf16 v[20:23], v[168:171], v[210:213], v[20:23]
	v_mfma_f32_16x16x32_bf16 v[16:19], v[180:183], v[210:213], v[16:19]
	v_mfma_f32_16x16x32_bf16 v[4:7], v[168:171], v[218:221], v[4:7]
	v_mfma_f32_16x16x32_bf16 v[0:3], v[180:183], v[218:221], v[0:3]
	v_mfma_f32_16x16x32_bf16 v[52:55], v[172:175], v[192:195], v[52:55]
	v_mfma_f32_16x16x32_bf16 v[48:51], v[184:187], v[192:195], v[48:51]
	v_mfma_f32_16x16x32_bf16 v[36:39], v[172:175], v[206:209], v[36:39]
	v_mfma_f32_16x16x32_bf16 v[32:35], v[184:187], v[206:209], v[32:35]
	v_mfma_f32_16x16x32_bf16 v[20:23], v[172:175], v[214:217], v[20:23]
	v_mfma_f32_16x16x32_bf16 v[16:19], v[184:187], v[214:217], v[16:19]
	v_lshl_add_u64 v[200:201], v[230:231], 0, s[26:27]
	s_mov_b32 m0, s59
	s_nop 0
	global_load_lds_dwordx4 v[200:201], off
	v_mfma_f32_16x16x32_bf16 v[4:7], v[172:175], v[222:225], v[4:7]
	v_mfma_f32_16x16x32_bf16 v[0:3], v[184:187], v[222:225], v[0:3]
	s_setprio 0
	s_barrier
	s_add_i32 s67, s67, 2
	s_add_u32 s50, s50, 0x100
	s_addc_u32 s51, s51, 0
	s_add_u32 s65, s65, 0x100
	s_addc_u32 s66, s66, 0
.LBB0_1593:
	ds_read_b128 v[146:149], v152
	ds_read_b128 v[156:159], v152 offset:1024
	ds_read_b128 v[160:163], v152 offset:2048
	ds_read_b128 v[164:167], v152 offset:3072
	ds_read_b128 v[168:171], v153
	ds_read_b128 v[172:175], v153 offset:1024
	ds_read_b128 v[180:183], v153 offset:2048
	ds_read_b128 v[184:187], v153 offset:3072
	s_add_u32 s52, s50, 0xfffc0080
	s_addc_u32 s53, s51, -1
	s_cmp_eq_u32 s67, 12
	s_cselect_b32 s55, s39, s53
	s_cselect_b32 s54, s47, s52
	s_cselect_b32 s53, s37, s66
	s_cselect_b32 s52, s64, s65
	v_lshl_add_u64 v[200:201], s[50:51], 0, v[136:137]
	s_add_i32 m0, s33, 0xc000
	ds_read_b128 v[188:191], v154
	ds_read_b128 v[192:195], v154 offset:1024
	ds_read_b128 v[196:199], v154 offset:2048
	ds_read_b128 v[206:209], v154 offset:3072
	ds_read_b128 v[210:213], v154 offset:4096
	ds_read_b128 v[214:217], v154 offset:5120
	ds_read_b128 v[218:221], v154 offset:6144
	ds_read_b128 v[222:225], v154 offset:7168
	global_load_lds_dwordx4 v[200:201], off
	v_lshl_add_u64 v[200:201], s[50:51], 0, v[138:139]
	s_add_i32 m0, s33, 0xe000
	s_nop 0
	global_load_lds_dwordx4 v[200:201], off
	s_waitcnt vmcnt(8)
	s_waitcnt lgkmcnt(0)
	s_barrier
; #define PG8_STAGE(bufoff, gbase, voff) do { _Pragma("unroll") for (int _i = 0; _i < 2; ++_i) \
;         __builtin_amdgcn_global_load_lds((const unsigned*)((const char*)(gbase) + (voff)[_i]), (PG8_LAS unsigned*)(lds + (bufoff) + ldsw + _i * 8192), 16, 0, 0); } while (0)
; #define PG8_LDA(dst, b, h) do { _Pragma("unroll") for (int m = 0; m < 4; ++m) _Pragma("unroll") for (int k = 0; k < 2; ++k) dst[m][k] = *(const PG8_LAS bf16x8*)(lds + PG8_SA(b, h) + aoff + m * 2048 + k * 1024); } while (0)
; #define PG8_LDB(dst, b, h) do { _Pragma("unroll") for (int n = 0; n < 2; ++n) _Pragma("unroll") for (int k = 0; k < 2; ++k) dst[n][k] = *(const PG8_LAS bf16x8*)(lds + PG8_SB(b, h) + boff + n * 2048 + k * 1024); } while (0)
; #define PG8_MMA(ai, bj, At, Bt) do { __builtin_amdgcn_s_setprio(1); _Pragma("unroll") for (int m = 0; m < 4; ++m) _Pragma("unroll") for (int n = 0; n < 2; ++n) _Pragma("unroll") for (int k = 0; k < 2; ++k) \
;         acc[ai][bj][m][n] = __builtin_amdgcn_mfma_f32_16x16x32_bf16(Bt[n][k], At[m][k], acc[ai][bj][m][n], 0, 0, 0); __builtin_amdgcn_s_setprio(0); } while (0)
; #define PG8_WAIT_V(n) asm volatile("s_waitcnt vmcnt(" #n ")" ::: "memory")
; #define PG8_WAIT_L(n) asm volatile("s_waitcnt lgkmcnt(" #n ")" ::: "memory")
; #define PG8_BAR __builtin_amdgcn_s_barrier()
; #define PG8_SCHED __builtin_amdgcn_sched_barrier(0)
; template <class Epi, class Sched, bool ALIGN_EPI = false, bool SP2 = false>
; __device__ __forceinline__ void gemm_phase(PG8_LAS unsigned char* lds, const Gemm g, const Sched& S, const Epi& E) {
;     ...
;             PG8_LDB(B0, 0, 0); PG8_LDB(B1, 0, 1); PG8_SCHED; PG8_LDA(At, 0, 0); PG8_STAGE(PG8_SA(1, 1), a1 + hstep, voffA);
;             PG8_WAIT_V(8); PG8_WAIT_L(0); PG8_BAR; PG8_MMA(0, 0, At, B0); PG8_MMA(0, 1, At, B1); PG8_BAR; PG8_SCHED;
;             PG8_LDA(At, 0, 1); PG8_STAGE(PG8_SB(0, 0), b2, voffB); PG8_STAGE(PG8_SB(0, 1), b2 + hstep, voffB); PG8_STAGE(PG8_SA(0, 0), a2, voffA);
;             PG8_WAIT_V(8); PG8_WAIT_L(0); PG8_BAR; PG8_MMA(1, 0, At, B0); PG8_MMA(1, 1, At, B1); PG8_BAR; PG8_SCHED;
;             PG8_LDB(B0, 1, 0); PG8_LDB(B1, 1, 1); PG8_SCHED; PG8_LDA(At, 1, 0); PG8_STAGE(PG8_SA(0, 1), a2 + hstep, voffA);
;             PG8_WAIT_V(8); PG8_WAIT_L(0); PG8_BAR; PG8_MMA(0, 0, At, B0); PG8_MMA(0, 1, At, B1); PG8_BAR; PG8_SCHED;
	s_setprio 1
	s_waitcnt lgkmcnt(0)
	v_mfma_f32_16x16x32_bf16 v[124:127], v[146:149], v[188:191], v[124:127]
	v_mfma_f32_16x16x32_bf16 v[120:123], v[160:163], v[188:191], v[120:123]
	v_mfma_f32_16x16x32_bf16 v[108:111], v[146:149], v[196:199], v[108:111]
	v_mfma_f32_16x16x32_bf16 v[104:107], v[160:163], v[196:199], v[104:107]
	v_mfma_f32_16x16x32_bf16 v[92:95], v[146:149], v[210:213], v[92:95]
	v_mfma_f32_16x16x32_bf16 v[88:91], v[160:163], v[210:213], v[88:91]
	v_mfma_f32_16x16x32_bf16 v[76:79], v[146:149], v[218:221], v[76:79]
	v_mfma_f32_16x16x32_bf16 v[72:75], v[160:163], v[218:221], v[72:75]
	v_mfma_f32_16x16x32_bf16 v[124:127], v[156:159], v[192:195], v[124:127]
	v_mfma_f32_16x16x32_bf16 v[120:123], v[164:167], v[192:195], v[120:123]
	v_mfma_f32_16x16x32_bf16 v[108:111], v[156:159], v[206:209], v[108:111]
	v_mfma_f32_16x16x32_bf16 v[104:107], v[164:167], v[206:209], v[104:107]
	v_mfma_f32_16x16x32_bf16 v[92:95], v[156:159], v[214:217], v[92:95]
	v_mfma_f32_16x16x32_bf16 v[88:91], v[164:167], v[214:217], v[88:91]
	v_mfma_f32_16x16x32_bf16 v[76:79], v[156:159], v[222:225], v[76:79]
	v_mfma_f32_16x16x32_bf16 v[72:75], v[164:167], v[222:225], v[72:75]
	s_setprio 0
	s_setprio 1
	v_mfma_f32_16x16x32_bf16 v[116:119], v[168:171], v[188:191], v[116:119]
	v_mfma_f32_16x16x32_bf16 v[112:115], v[180:183], v[188:191], v[112:115]
	v_mfma_f32_16x16x32_bf16 v[100:103], v[168:171], v[196:199], v[100:103]
	v_mfma_f32_16x16x32_bf16 v[96:99], v[180:183], v[196:199], v[96:99]
	v_mfma_f32_16x16x32_bf16 v[84:87], v[168:171], v[210:213], v[84:87]
	v_mfma_f32_16x16x32_bf16 v[80:83], v[180:183], v[210:213], v[80:83]
	v_mfma_f32_16x16x32_bf16 v[68:71], v[168:171], v[218:221], v[68:71]
	v_mfma_f32_16x16x32_bf16 v[64:67], v[180:183], v[218:221], v[64:67]
	v_mfma_f32_16x16x32_bf16 v[116:119], v[172:175], v[192:195], v[116:119]
	v_mfma_f32_16x16x32_bf16 v[112:115], v[184:187], v[192:195], v[112:115]
	v_mfma_f32_16x16x32_bf16 v[100:103], v[172:175], v[206:209], v[100:103]
	v_mfma_f32_16x16x32_bf16 v[96:99], v[184:187], v[206:209], v[96:99]
	v_mfma_f32_16x16x32_bf16 v[84:87], v[172:175], v[214:217], v[84:87]
	v_mfma_f32_16x16x32_bf16 v[80:83], v[184:187], v[214:217], v[80:83]
	v_mfma_f32_16x16x32_bf16 v[68:71], v[172:175], v[222:225], v[68:71]
	v_mfma_f32_16x16x32_bf16 v[64:67], v[184:187], v[222:225], v[64:67]
	s_setprio 0
	s_barrier
	s_add_i32 s74, s60, s15
	v_lshl_add_u64 v[200:201], s[52:53], 0, v[130:131]
	s_mov_b32 m0, s74
	ds_read_b128 v[188:191], v154 offset:16384
	ds_read_b128 v[192:195], v154 offset:17408
	ds_read_b128 v[196:199], v154 offset:18432
	ds_read_b128 v[206:209], v154 offset:19456
	ds_read_b128 v[210:213], v154 offset:20480
	ds_read_b128 v[214:217], v154 offset:21504
	ds_read_b128 v[218:221], v154 offset:22528
	ds_read_b128 v[222:225], v154 offset:23552
	global_load_lds_dwordx4 v[200:201], off
	s_add_i32 m0, s74, 0x2000
	s_add_u32 s74, s52, 0x40000
	v_lshl_add_u64 v[226:227], s[52:53], 0, v[134:135]
	s_addc_u32 s75, s53, 0
	s_add_i32 s76, s61, s15
	global_load_lds_dwordx4 v[226:227], off
	v_lshl_add_u64 v[228:229], s[74:75], 0, v[130:131]
	s_mov_b32 m0, s76
	global_load_lds_dwordx4 v[228:229], off
	v_lshl_add_u64 v[228:229], s[74:75], 0, v[134:135]
	s_add_i32 m0, s76, 0x2000
	s_nop 0
	global_load_lds_dwordx4 v[228:229], off
	s_waitcnt vmcnt(6)
	s_waitcnt lgkmcnt(0)
	s_barrier
	s_setprio 1
	s_waitcnt lgkmcnt(0)
	v_mfma_f32_16x16x32_bf16 v[60:63], v[146:149], v[188:191], v[60:63]
	v_mfma_f32_16x16x32_bf16 v[56:59], v[160:163], v[188:191], v[56:59]
	v_mfma_f32_16x16x32_bf16 v[44:47], v[146:149], v[196:199], v[44:47]
	v_mfma_f32_16x16x32_bf16 v[40:43], v[160:163], v[196:199], v[40:43]
	v_mfma_f32_16x16x32_bf16 v[28:31], v[146:149], v[210:213], v[28:31]
	v_mfma_f32_16x16x32_bf16 v[24:27], v[160:163], v[210:213], v[24:27]
	v_mfma_f32_16x16x32_bf16 v[12:15], v[146:149], v[218:221], v[12:15]
	v_mfma_f32_16x16x32_bf16 v[8:11], v[160:163], v[218:221], v[8:11]
	v_mfma_f32_16x16x32_bf16 v[60:63], v[156:159], v[192:195], v[60:63]
	v_mfma_f32_16x16x32_bf16 v[56:59], v[164:167], v[192:195], v[56:59]
	v_mfma_f32_16x16x32_bf16 v[44:47], v[156:159], v[206:209], v[44:47]
	v_mfma_f32_16x16x32_bf16 v[40:43], v[164:167], v[206:209], v[40:43]
	v_mfma_f32_16x16x32_bf16 v[28:31], v[156:159], v[214:217], v[28:31]
	v_mfma_f32_16x16x32_bf16 v[24:27], v[164:167], v[214:217], v[24:27]
	v_lshl_add_u64 v[228:229], s[54:55], 0, v[128:129]
	s_mov_b32 m0, s33
	s_nop 0
	global_load_lds_dwordx4 v[228:229], off
	v_mfma_f32_16x16x32_bf16 v[12:15], v[156:159], v[222:225], v[12:15]
	v_mfma_f32_16x16x32_bf16 v[8:11], v[164:167], v[222:225], v[8:11]
	s_setprio 0
	s_setprio 1
	v_mfma_f32_16x16x32_bf16 v[52:55], v[168:171], v[188:191], v[52:55]
	v_mfma_f32_16x16x32_bf16 v[48:51], v[180:183], v[188:191], v[48:51]
	v_mfma_f32_16x16x32_bf16 v[36:39], v[168:171], v[196:199], v[36:39]
	v_mfma_f32_16x16x32_bf16 v[32:35], v[180:183], v[196:199], v[32:35]
	v_mfma_f32_16x16x32_bf16 v[20:23], v[168:171], v[210:213], v[20:23]
	v_mfma_f32_16x16x32_bf16 v[16:19], v[180:183], v[210:213], v[16:19]
	v_mfma_f32_16x16x32_bf16 v[4:7], v[168:171], v[218:221], v[4:7]
	v_mfma_f32_16x16x32_bf16 v[0:3], v[180:183], v[218:221], v[0:3]
	v_mfma_f32_16x16x32_bf16 v[52:55], v[172:175], v[192:195], v[52:55]
	v_mfma_f32_16x16x32_bf16 v[48:51], v[184:187], v[192:195], v[48:51]
	v_mfma_f32_16x16x32_bf16 v[36:39], v[172:175], v[206:209], v[36:39]
	v_mfma_f32_16x16x32_bf16 v[32:35], v[184:187], v[206:209], v[32:35]
	v_mfma_f32_16x16x32_bf16 v[20:23], v[172:175], v[214:217], v[20:23]
	v_mfma_f32_16x16x32_bf16 v[16:19], v[184:187], v[214:217], v[16:19]
	v_lshl_add_u64 v[230:231], s[54:55], 0, v[132:133]
	s_mov_b32 m0, s34
	s_nop 0
	global_load_lds_dwordx4 v[230:231], off
	v_mfma_f32_16x16x32_bf16 v[4:7], v[172:175], v[222:225], v[4:7]
	v_mfma_f32_16x16x32_bf16 v[0:3], v[184:187], v[222:225], v[0:3]
	s_setprio 0
	s_barrier
; #define PG8_STAGE(bufoff, gbase, voff) do { _Pragma("unroll") for (int _i = 0; _i < 2; ++_i) \
;         __builtin_amdgcn_global_load_lds((const unsigned*)((const char*)(gbase) + (voff)[_i]), (PG8_LAS unsigned*)(lds + (bufoff) + ldsw + _i * 8192), 16, 0, 0); } while (0)
; #define PG8_LDA(dst, b, h) do { _Pragma("unroll") for (int m = 0; m < 4; ++m) _Pragma("unroll") for (int k = 0; k < 2; ++k) dst[m][k] = *(const PG8_LAS bf16x8*)(lds + PG8_SA(b, h) + aoff + m * 2048 + k * 1024); } while (0)
; #define PG8_LDB(dst, b, h) do { _Pragma("unroll") for (int n = 0; n < 2; ++n) _Pragma("unroll") for (int k = 0; k < 2; ++k) dst[n][k] = *(const PG8_LAS bf16x8*)(lds + PG8_SB(b, h) + boff + n * 2048 + k * 1024); } while (0)
; #define PG8_MMA(ai, bj, At, Bt) do { __builtin_amdgcn_s_setprio(1); _Pragma("unroll") for (int m = 0; m < 4; ++m) _Pragma("unroll") for (int n = 0; n < 2; ++n) _Pragma("unroll") for (int k = 0; k < 2; ++k) \
;         acc[ai][bj][m][n] = __builtin_amdgcn_mfma_f32_16x16x32_bf16(Bt[n][k], At[m][k], acc[ai][bj][m][n], 0, 0, 0); __builtin_amdgcn_s_setprio(0); } while (0)
; #define PG8_WAIT_V(n) asm volatile("s_waitcnt vmcnt(" #n ")" ::: "memory")
; #define PG8_WAIT_L(n) asm volatile("s_waitcnt lgkmcnt(" #n ")" ::: "memory")
; #define PG8_BAR __builtin_amdgcn_s_barrier()
; #define PG8_SCHED __builtin_amdgcn_sched_barrier(0)
; template <class Epi, class Sched, bool ALIGN_EPI = false, bool SP2 = false>
; __device__ __forceinline__ void gemm_phase(PG8_LAS unsigned char* lds, const Gemm g, const Sched& S, const Epi& E) {
;     ...
;             PG8_LDB(B0, 1, 0); PG8_LDB(B1, 1, 1); PG8_SCHED; PG8_LDA(At, 1, 0); PG8_STAGE(PG8_SA(0, 1), a2 + hstep, voffA);
;             PG8_WAIT_V(8); PG8_WAIT_L(0); PG8_BAR; PG8_MMA(0, 0, At, B0); PG8_MMA(0, 1, At, B1); PG8_BAR; PG8_SCHED;
;             PG8_LDA(At, 1, 1); PG8_STAGE(PG8_SB(1, 0), b3, voffB); PG8_STAGE(PG8_SB(1, 1), b3 + hstep, voffB); PG8_STAGE(PG8_SA(1, 0), a3, voffA);
;             PG8_WAIT_V(8); PG8_WAIT_L(0); PG8_BAR; PG8_MMA(1, 0, At, B0); PG8_MMA(1, 1, At, B1); PG8_BAR; PG8_SCHED;
	s_add_i32 s74, 0, 0x18000
	s_add_i32 s75, 0, 0x1c000
	v_add_u32_e32 v164, s74, v150
	v_add_u32_e32 v179, s75, v150
	ds_read_b128 v[146:149], v164
	ds_read_b128 v[156:159], v164 offset:1024
	ds_read_b128 v[160:163], v164 offset:2048
	ds_read_b128 v[164:167], v164 offset:3072
	ds_read_b128 v[168:171], v179
	ds_read_b128 v[172:175], v179 offset:1024
	ds_read_b128 v[180:183], v179 offset:2048
	ds_read_b128 v[184:187], v179 offset:3072
	s_add_u32 s54, s54, 0x40000
	s_addc_u32 s55, s55, 0
	s_mov_b32 m0, s49
	v_lshl_add_u64 v[232:233], s[54:55], 0, v[128:129]
	ds_read_b128 v[188:191], v154 offset:32768
	ds_read_b128 v[192:195], v154 offset:33792
	ds_read_b128 v[196:199], v154 offset:34816
	ds_read_b128 v[206:209], v154 offset:35840
	ds_read_b128 v[210:213], v154 offset:36864
	ds_read_b128 v[214:217], v154 offset:37888
	ds_read_b128 v[218:221], v154 offset:38912
	ds_read_b128 v[222:225], v154 offset:39936
	global_load_lds_dwordx4 v[232:233], off
	v_lshl_add_u64 v[232:233], s[54:55], 0, v[132:133]
	s_mov_b32 m0, s56
	s_nop 0
	global_load_lds_dwordx4 v[232:233], off
	s_waitcnt vmcnt(8)
	s_waitcnt lgkmcnt(0)
	s_barrier
	s_setprio 1
	s_waitcnt lgkmcnt(0)
	v_mfma_f32_16x16x32_bf16 v[124:127], v[146:149], v[188:191], v[124:127]
	v_mfma_f32_16x16x32_bf16 v[120:123], v[160:163], v[188:191], v[120:123]
	v_mfma_f32_16x16x32_bf16 v[108:111], v[146:149], v[196:199], v[108:111]
	v_mfma_f32_16x16x32_bf16 v[104:107], v[160:163], v[196:199], v[104:107]
	v_mfma_f32_16x16x32_bf16 v[92:95], v[146:149], v[210:213], v[92:95]
	v_mfma_f32_16x16x32_bf16 v[88:91], v[160:163], v[210:213], v[88:91]
	v_mfma_f32_16x16x32_bf16 v[76:79], v[146:149], v[218:221], v[76:79]
	v_mfma_f32_16x16x32_bf16 v[72:75], v[160:163], v[218:221], v[72:75]
	v_mfma_f32_16x16x32_bf16 v[124:127], v[156:159], v[192:195], v[124:127]
	v_mfma_f32_16x16x32_bf16 v[120:123], v[164:167], v[192:195], v[120:123]
	v_mfma_f32_16x16x32_bf16 v[108:111], v[156:159], v[206:209], v[108:111]
	v_mfma_f32_16x16x32_bf16 v[104:107], v[164:167], v[206:209], v[104:107]
	v_mfma_f32_16x16x32_bf16 v[92:95], v[156:159], v[214:217], v[92:95]
	v_mfma_f32_16x16x32_bf16 v[88:91], v[164:167], v[214:217], v[88:91]
	v_mfma_f32_16x16x32_bf16 v[76:79], v[156:159], v[222:225], v[76:79]
	v_mfma_f32_16x16x32_bf16 v[72:75], v[164:167], v[222:225], v[72:75]
	s_setprio 0
	s_setprio 1
	v_mfma_f32_16x16x32_bf16 v[116:119], v[168:171], v[188:191], v[116:119]
	v_mfma_f32_16x16x32_bf16 v[112:115], v[180:183], v[188:191], v[112:115]
	v_mfma_f32_16x16x32_bf16 v[100:103], v[168:171], v[196:199], v[100:103]
	v_mfma_f32_16x16x32_bf16 v[96:99], v[180:183], v[196:199], v[96:99]
	v_mfma_f32_16x16x32_bf16 v[84:87], v[168:171], v[210:213], v[84:87]
	v_mfma_f32_16x16x32_bf16 v[80:83], v[180:183], v[210:213], v[80:83]
	v_mfma_f32_16x16x32_bf16 v[68:71], v[168:171], v[218:221], v[68:71]
	v_mfma_f32_16x16x32_bf16 v[64:67], v[180:183], v[218:221], v[64:67]
	v_mfma_f32_16x16x32_bf16 v[116:119], v[172:175], v[192:195], v[116:119]
	v_mfma_f32_16x16x32_bf16 v[112:115], v[184:187], v[192:195], v[112:115]
	v_mfma_f32_16x16x32_bf16 v[100:103], v[172:175], v[206:209], v[100:103]
	v_mfma_f32_16x16x32_bf16 v[96:99], v[184:187], v[206:209], v[96:99]
	v_mfma_f32_16x16x32_bf16 v[84:87], v[172:175], v[214:217], v[84:87]
	v_mfma_f32_16x16x32_bf16 v[80:83], v[184:187], v[214:217], v[80:83]
	v_mfma_f32_16x16x32_bf16 v[68:71], v[172:175], v[222:225], v[68:71]
	v_mfma_f32_16x16x32_bf16 v[64:67], v[184:187], v[222:225], v[64:67]
	s_setprio 0
	s_barrier
	s_add_i32 s54, s74, s15
	v_lshl_add_u64 v[200:201], v[200:201], 0, s[26:27]
	s_mov_b32 m0, s54
	ds_read_b128 v[188:191], v154 offset:49152
	ds_read_b128 v[192:195], v154 offset:50176
	ds_read_b128 v[196:199], v154 offset:51200
	ds_read_b128 v[206:209], v154 offset:52224
	ds_read_b128 v[210:213], v154 offset:53248
	ds_read_b128 v[214:217], v154 offset:54272
	ds_read_b128 v[218:221], v154 offset:55296
	ds_read_b128 v[222:225], v154 offset:56320
	global_load_lds_dwordx4 v[200:201], off
	s_add_i32 m0, s54, 0x2000
	s_add_u32 s52, s52, 0x40080
	v_lshl_add_u64 v[200:201], v[226:227], 0, s[26:27]
	s_addc_u32 s53, s53, 0
	s_add_i32 s54, s75, s15
	global_load_lds_dwordx4 v[200:201], off
	v_lshl_add_u64 v[200:201], s[52:53], 0, v[130:131]
	s_mov_b32 m0, s54
	s_nop 0
	global_load_lds_dwordx4 v[200:201], off
	v_lshl_add_u64 v[200:201], s[52:53], 0, v[134:135]
	s_add_i32 m0, s54, 0x2000
	s_nop 0
	global_load_lds_dwordx4 v[200:201], off
	s_waitcnt vmcnt(6)
	s_waitcnt lgkmcnt(0)
	s_barrier
; #define PG8_BAR __builtin_amdgcn_s_barrier()
;     __device__ __forceinline__ void operator()(const f32x4 (&acc)[2][2][4][2], const Unit& u, int wr, int wc, int fr, int fq) const {
;     ...
;             for (int m = 0; m < 4; ++m) { const int row = row0 + ai * HALF + m * 16; const size_t off = (size_t)row * 1024 + col0; float s = 0.f;
; #pragma unroll
;                 for (int bj = 0; bj < 2; ++bj) { f32x4 a0, a1;
;                     if (xin32) { const float* p = xin32 + off + bj * HALF; a0 = *(const f32x4*)p; a1 = *(const f32x4*)(p + 4); }
;                     else { const u32x4 w = *(const u32x4*)(xb + off + bj * HALF);
; template <class Epi, class Sched, bool ALIGN_EPI = false, bool SP2 = false>
; __device__ __forceinline__ void gemm_phase(PG8_LAS unsigned char* lds, const Gemm g, const Sched& S, const Epi& E) {
;     ...
;             PG8_WAIT_V(8); PG8_WAIT_L(0); PG8_BAR; PG8_MMA(1, 0, At, B0); PG8_MMA(1, 1, At, B1); PG8_BAR; PG8_SCHED;
;             } else {
;             PG8_LDB(B0, 0, 0); PG8_SCHED; PG8_LDA(At, 0, 0); PG8_STAGE(PG8_SA(1, 1), a1 + hstep, voffA);
;             PG8_WAIT_L(8); PG8_BAR; PG8_WAIT_L(0); PG8_MMA(0, 0, At, B0); PG8_BAR; PG8_SCHED;
;             PG8_LDB(B1, 0, 1); PG8_STAGE(PG8_SB(0, 0), b2, voffB);
;             PG8_BAR; PG8_WAIT_L(0); PG8_MMA(0, 1, At, B1); PG8_BAR;
;             PG8_LDA(At, 0, 1); PG8_STAGE(PG8_SA(0, 0), a2, voffA);
;             PG8_BAR; PG8_WAIT_L(0); PG8_MMA(1, 0, At, B0); PG8_BAR; PG8_SCHED;
;             PG8_STAGE(PG8_SB(0, 1), b2 + hstep, voffB);
;             PG8_WAIT_V(6); PG8_BAR; PG8_MMA(1, 1, At, B1); PG8_BAR;
;             PG8_LDB(B0, 1, 0); PG8_SCHED; PG8_LDA(At, 1, 0); PG8_STAGE(PG8_SA(0, 1), a2 + hstep, voffA);
;             PG8_WAIT_L(8); PG8_BAR; PG8_WAIT_L(0); PG8_MMA(0, 0, At, B0); PG8_BAR; PG8_SCHED;
;             PG8_LDB(B1, 1, 1); PG8_STAGE(PG8_SB(1, 0), b3, voffB);
;             PG8_BAR; PG8_WAIT_L(0); PG8_MMA(0, 1, At, B1); PG8_BAR;
;             PG8_LDA(At, 1, 1); PG8_STAGE(PG8_SA(1, 0), a3, voffA);
;             PG8_BAR; PG8_WAIT_L(0); PG8_MMA(1, 0, At, B0); PG8_BAR; PG8_SCHED;
;             PG8_STAGE(PG8_SB(1, 1), b3 + hstep, voffB);
;             PG8_WAIT_V(6); PG8_BAR; PG8_MMA(1, 1, At, B1); PG8_BAR;
;             }
;         }
;         if constexpr (ALIGN_EPI) { if (wr == 0) PG8_BAR; }
;         if constexpr (!Epi::AFTER_DRAIN) { E(acc, cur, wr, wc, fr, fq); S.done(cur); }
	s_setprio 1
	s_waitcnt lgkmcnt(0)
	v_mfma_f32_16x16x32_bf16 v[60:63], v[146:149], v[188:191], v[60:63]
	v_mfma_f32_16x16x32_bf16 v[56:59], v[160:163], v[188:191], v[56:59]
	v_mfma_f32_16x16x32_bf16 v[44:47], v[146:149], v[196:199], v[44:47]
	v_mfma_f32_16x16x32_bf16 v[40:43], v[160:163], v[196:199], v[40:43]
	v_mfma_f32_16x16x32_bf16 v[28:31], v[146:149], v[210:213], v[28:31]
	v_mfma_f32_16x16x32_bf16 v[24:27], v[160:163], v[210:213], v[24:27]
	v_mfma_f32_16x16x32_bf16 v[12:15], v[146:149], v[218:221], v[12:15]
	v_mfma_f32_16x16x32_bf16 v[8:11], v[160:163], v[218:221], v[8:11]
	v_mfma_f32_16x16x32_bf16 v[60:63], v[156:159], v[192:195], v[60:63]
	v_mfma_f32_16x16x32_bf16 v[56:59], v[164:167], v[192:195], v[56:59]
	v_mfma_f32_16x16x32_bf16 v[44:47], v[156:159], v[206:209], v[44:47]
	v_mfma_f32_16x16x32_bf16 v[40:43], v[164:167], v[206:209], v[40:43]
	v_mfma_f32_16x16x32_bf16 v[28:31], v[156:159], v[214:217], v[28:31]
	v_mfma_f32_16x16x32_bf16 v[24:27], v[164:167], v[214:217], v[24:27]
	v_lshl_add_u64 v[200:201], v[228:229], 0, s[26:27]
	s_mov_b32 m0, s58
	s_nop 0
	global_load_lds_dwordx4 v[200:201], off
	v_mfma_f32_16x16x32_bf16 v[12:15], v[156:159], v[222:225], v[12:15]
	v_mfma_f32_16x16x32_bf16 v[8:11], v[164:167], v[222:225], v[8:11]
	s_setprio 0
	s_setprio 1
	v_mfma_f32_16x16x32_bf16 v[52:55], v[168:171], v[188:191], v[52:55]
	v_mfma_f32_16x16x32_bf16 v[48:51], v[180:183], v[188:191], v[48:51]
	v_mfma_f32_16x16x32_bf16 v[36:39], v[168:171], v[196:199], v[36:39]
	v_mfma_f32_16x16x32_bf16 v[32:35], v[180:183], v[196:199], v[32:35]
	v_mfma_f32_16x16x32_bf16 v[20:23], v[168:171], v[210:213], v[20:23]
	v_mfma_f32_16x16x32_bf16 v[16:19], v[180:183], v[210:213], v[16:19]
	v_mfma_f32_16x16x32_bf16 v[4:7], v[168:171], v[218:221], v[4:7]
	v_mfma_f32_16x16x32_bf16 v[0:3], v[180:183], v[218:221], v[0:3]
	v_mfma_f32_16x16x32_bf16 v[52:55], v[172:175], v[192:195], v[52:55]
	v_mfma_f32_16x16x32_bf16 v[48:51], v[184:187], v[192:195], v[48:51]
	v_mfma_f32_16x16x32_bf16 v[36:39], v[172:175], v[206:209], v[36:39]
	v_mfma_f32_16x16x32_bf16 v[32:35], v[184:187], v[206:209], v[32:35]
	v_mfma_f32_16x16x32_bf16 v[20:23], v[172:175], v[214:217], v[20:23]
	v_mfma_f32_16x16x32_bf16 v[16:19], v[184:187], v[214:217], v[16:19]
	v_lshl_add_u64 v[200:201], v[230:231], 0, s[26:27]
	s_mov_b32 m0, s59
	s_nop 0
	global_load_lds_dwordx4 v[200:201], off
	v_mfma_f32_16x16x32_bf16 v[4:7], v[172:175], v[222:225], v[4:7]
	v_mfma_f32_16x16x32_bf16 v[0:3], v[184:187], v[222:225], v[0:3]
	s_setprio 0
	s_barrier
	s_add_i32 s67, s67, 2
	s_add_u32 s50, s50, 0x100
	s_addc_u32 s51, s51, 0
	s_add_u32 s65, s65, 0x100
	s_addc_u32 s66, s66, 0
	s_cmp_gt_u32 s67, 13
	s_cbranch_scc0 .LBB0_1593
	s_and_b64 vcc, exec, s[28:29]
	s_cbranch_vccz .LBB0_1596
.LBB0_1596:
	v_lshl_add_u32 v148, s48, 8, v145
	v_ashrrev_i32_e32 v149, 31, v148
	v_lshl_or_b32 v146, s46, 8, v151
	v_lshlrev_b64 v[156:157], 11, v[148:149]
	v_ashrrev_i32_e32 v147, 31, v146
	v_lshl_add_u64 v[156:157], s[22:23], 0, v[156:157]
	v_lshl_add_u64 v[166:167], v[146:147], 1, v[156:157]
	global_load_dwordx4 v[158:161], v[166:167], off
	global_load_dwordx4 v[162:165], v[166:167], off offset:256
	v_and_b32_e32 v157, 64, v155
	v_xor_b32_e32 v156, 16, v155
	v_add_u32_e32 v157, 64, v157
	v_xor_b32_e32 v168, 32, v155
	v_cmp_lt_i32_e32 vcc, v156, v157
	s_waitcnt vmcnt(0)
	v_and_b32_e32 v169, 0xffff0000, v158
	v_cndmask_b32_e32 v156, v155, v156, vcc
	v_cmp_lt_i32_e32 vcc, v168, v157
	v_lshlrev_b32_e32 v157, 2, v156
	v_lshlrev_b32_e32 v172, 16, v162
	v_cndmask_b32_e32 v168, v155, v168, vcc
	v_lshlrev_b32_e32 v156, 2, v168
	v_lshlrev_b32_e32 v168, 16, v158
	v_lshlrev_b32_e32 v158, 16, v159
	v_and_b32_e32 v159, 0xffff0000, v159
	v_and_b32_e32 v173, 0xffff0000, v162
	v_lshlrev_b32_e32 v162, 16, v163
	v_and_b32_e32 v163, 0xffff0000, v163
	v_lshlrev_b32_e32 v170, 16, v160
	v_and_b32_e32 v171, 0xffff0000, v160
	v_lshlrev_b32_e32 v160, 16, v161
	v_and_b32_e32 v161, 0xffff0000, v161
	v_lshlrev_b32_e32 v174, 16, v164
	v_and_b32_e32 v175, 0xffff0000, v164
	v_lshlrev_b32_e32 v164, 16, v165
	v_and_b32_e32 v165, 0xffff0000, v165
	v_pk_add_f32 v[126:127], v[126:127], v[158:159]
	v_pk_add_f32 v[124:125], v[124:125], v[168:169]
	v_pk_add_f32 v[118:119], v[118:119], v[162:163]
	v_pk_add_f32 v[116:117], v[116:117], v[172:173]
	v_pk_add_f32 v[122:123], v[122:123], v[160:161]
	v_pk_add_f32 v[120:121], v[120:121], v[170:171]
	v_pk_add_f32 v[158:159], v[114:115], v[164:165]
	v_pk_add_f32 v[160:161], v[112:113], v[174:175]
	v_mul_f32_e32 v114, v125, v125
	v_mul_f32_e32 v115, v127, v127
	v_mul_f32_e32 v162, v117, v117
	v_mul_f32_e32 v163, v119, v119
	v_cvt_pk_bf16_f32 v112, v124, v125
	v_mul_f32_e32 v125, v121, v121
	v_mul_f32_e32 v164, v161, v161
	v_fmac_f32_e32 v114, v124, v124
	v_fmac_f32_e32 v115, v126, v126
	v_fmac_f32_e32 v162, v116, v116
	v_fmac_f32_e32 v163, v118, v118
	v_cvt_pk_bf16_f32 v113, v126, v127
	v_mul_f32_e32 v127, v123, v123
	v_mul_f32_e32 v165, v159, v159
	v_fmac_f32_e32 v125, v120, v120
	v_fmac_f32_e32 v164, v160, v160
	v_add_f32_e32 v114, v114, v115
	v_add_f32_e32 v115, v162, v163
	v_fmac_f32_e32 v127, v122, v122
	v_fmac_f32_e32 v165, v158, v158
	v_add_f32_e32 v114, v125, v114
	v_add_f32_e32 v115, v164, v115
	v_add_f32_e32 v114, v127, v114
	v_add_f32_e32 v115, v165, v115
	v_add_f32_e32 v124, v114, v115
	ds_bpermute_b32 v125, v157, v124
	v_cvt_pk_bf16_f32 v114, v120, v121
	v_cvt_pk_bf16_f32 v115, v122, v123
	global_store_dwordx4 v[166:167], v[112:115], off
	s_waitcnt lgkmcnt(0)
	s_nop 0
	v_add_f32_e32 v112, v124, v125
	ds_bpermute_b32 v113, v156, v112
	v_cvt_pk_bf16_f32 v114, v116, v117
	v_cvt_pk_bf16_f32 v115, v118, v119
	v_cvt_pk_bf16_f32 v116, v160, v161
	v_cvt_pk_bf16_f32 v117, v158, v159
	global_store_dwordx4 v[166:167], v[114:117], off offset:256
	s_and_saveexec_b64 s[46:47], s[4:5]
	s_cbranch_execz .LBB0_1598
	s_waitcnt lgkmcnt(0)
	v_add_f32_e32 v112, v112, v113
	v_mul_f32_e32 v112, 0x4f800000, v112
	v_trunc_f32_e32 v112, v112
	v_mul_f32_e64 v113, |v112|, s62
	v_floor_f32_e32 v113, v113
	v_fma_f32 v114, v113, s63, |v112|
	v_cvt_u32_f32_e32 v114, v114
	v_cvt_u32_f32_e32 v113, v113
	v_ashrrev_i32_e32 v115, 31, v112
	v_xor_b32_e32 v112, v114, v115
	v_xor_b32_e32 v113, v113, v115
	v_sub_co_u32_e32 v112, vcc, v112, v115
	s_nop 1
	v_subb_co_u32_e32 v113, vcc, v113, v115, vcc
	v_lshl_add_u64 v[114:115], v[148:149], 3, s[12:13]
	global_atomic_add_x2 v[114:115], v[112:113], off

; #define PG8_BAR __builtin_amdgcn_s_barrier()
; template <class Epi, class Sched, bool ALIGN_EPI = false, bool SP2 = false>
; __device__ __forceinline__ void gemm_phase(PG8_LAS unsigned char* lds, const Gemm g, const Sched& S, const Epi& E) {
;     ...
;         if constexpr (ALIGN_EPI) { if (wr == 0) PG8_BAR; }
;         if constexpr (!Epi::AFTER_DRAIN) { E(acc, cur, wr, wc, fr, fq); S.done(cur); }
;         if (!has_next) break;
.LBB0_1612:
	s_or_b64 exec, exec, s[46:47]
	s_andn2_b64 vcc, exec, s[10:11]
	s_mov_b64 s[10:11], -1
	s_cmp_eq_u64 s[28:29], 0
	s_cbranch_scc1 .Lxpost_9
	s_barrier

; #define PG8_STAGE(bufoff, gbase, voff) do { _Pragma("unroll") for (int _i = 0; _i < 2; ++_i) \
;         __builtin_amdgcn_global_load_lds((const unsigned*)((const char*)(gbase) + (voff)[_i]), (PG8_LAS unsigned*)(lds + (bufoff) + ldsw + _i * 8192), 16, 0, 0); } while (0)
; #define PG8_LDA(dst, b, h) do { _Pragma("unroll") for (int m = 0; m < 4; ++m) _Pragma("unroll") for (int k = 0; k < 2; ++k) dst[m][k] = *(const PG8_LAS bf16x8*)(lds + PG8_SA(b, h) + aoff + m * 2048 + k * 1024); } while (0)
; #define PG8_LDB(dst, b, h) do { _Pragma("unroll") for (int n = 0; n < 2; ++n) _Pragma("unroll") for (int k = 0; k < 2; ++k) dst[n][k] = *(const PG8_LAS bf16x8*)(lds + PG8_SB(b, h) + boff + n * 2048 + k * 1024); } while (0)
; #define PG8_WAIT_V(n) asm volatile("s_waitcnt vmcnt(" #n ")" ::: "memory")
; #define PG8_WAIT_L(n) asm volatile("s_waitcnt lgkmcnt(" #n ")" ::: "memory")
; #define PG8_BAR __builtin_amdgcn_s_barrier()
; #define PG8_SCHED __builtin_amdgcn_sched_barrier(0)
; template <class Epi, class Sched, bool ALIGN_EPI = false, bool SP2 = false>
; __device__ __forceinline__ void gemm_phase(PG8_LAS unsigned char* lds, const Gemm g, const Sched& S, const Epi& E) {
;     ...
;         const bool has_next = S.next(ui + 1, nxt);
;         const char* nA = has_next ? (const char*)g.A + (size_t)nxt.pm * tstep : cA; const char* nB = has_next ? (const char*)g.Bt + (size_t)nxt.pn * tstep : cB;
;         for (int t = 0; t < nt; t += 2) {
;             const bool last = (t == nt - 2);
;             const char* a1 = cA + (size_t)(t + 1) * kstep;
;             const char* a2 = last ? nA : cA + (size_t)(t + 2) * kstep; const char* b2 = last ? nB : cB + (size_t)(t + 2) * kstep;
;             const char* a3 = a2 + kstep; const char* b3 = b2 + kstep;
;             if (last && has_next) S.a_ready(nxt);
;             if constexpr (SP2) {
;             PG8_LDB(B0, 0, 0); PG8_LDB(B1, 0, 1); PG8_SCHED; PG8_LDA(At, 0, 0); PG8_STAGE(PG8_SA(1, 1), a1 + hstep, voffA);
;             PG8_WAIT_V(8); PG8_WAIT_L(0); PG8_BAR; PG8_MMA(0, 0, At, B0); PG8_MMA(0, 1, At, B1); PG8_BAR; PG8_SCHED;
;             PG8_LDA(At, 0, 1); PG8_STAGE(PG8_SB(0, 0), b2, voffB); PG8_STAGE(PG8_SB(0, 1), b2 + hstep, voffB); PG8_STAGE(PG8_SA(0, 0), a2, voffA);
;             PG8_WAIT_V(8); PG8_WAIT_L(0); PG8_BAR; PG8_MMA(1, 0, At, B0); PG8_MMA(1, 1, At, B1); PG8_BAR; PG8_SCHED;
.LBB0_1680:
	s_ashr_i32 s47, s46, 31
	s_lshl_b64 s[48:49], s[46:47], 19
	s_add_u32 s48, s22, s48
	s_addc_u32 s49, s23, s49
	s_and_b64 s[50:51], s[4:5], exec
	s_cselect_b32 s47, s49, s53
	s_cselect_b32 s77, s48, s52
	s_ashr_i32 s45, s44, 31
	s_lshl_b64 s[50:51], s[44:45], 19
	s_add_u32 s50, s15, s50
	s_addc_u32 s51, s33, s51
	s_and_b64 s[56:57], s[4:5], exec
	s_cselect_b32 s45, s51, s55
	s_cselect_b32 s78, s50, s54
	s_add_u32 s52, s52, 0x40080
	s_addc_u32 s53, s53, 0
	s_add_u32 s79, s54, 0x100
	s_addc_u32 s80, s55, 0
	s_mov_b32 s81, -2
	ds_read_b128 v[146:149], v152
	ds_read_b128 v[156:159], v152 offset:1024
	ds_read_b128 v[160:163], v152 offset:2048
	ds_read_b128 v[164:167], v152 offset:3072
	ds_read_b128 v[168:171], v153
	ds_read_b128 v[172:175], v153 offset:1024
	ds_read_b128 v[180:183], v153 offset:2048
	ds_read_b128 v[184:187], v153 offset:3072
	s_add_u32 s54, s52, 0xfffc0080
	s_addc_u32 s55, s53, -1
	s_cmp_eq_u32 s81, 12
	s_cselect_b32 s57, s47, s55
	s_cselect_b32 s56, s77, s54
	s_cselect_b32 s55, s45, s80
	s_cselect_b32 s54, s78, s79
	v_lshl_add_u64 v[200:201], s[52:53], 0, v[136:137]
	s_add_i32 m0, s58, 0xc000
	ds_read_b128 v[188:191], v154
	ds_read_b128 v[192:195], v154 offset:1024
	ds_read_b128 v[196:199], v154 offset:2048
	ds_read_b128 v[206:209], v154 offset:3072
	ds_read_b128 v[210:213], v154 offset:4096
	ds_read_b128 v[214:217], v154 offset:5120
	ds_read_b128 v[218:221], v154 offset:6144
	ds_read_b128 v[222:225], v154 offset:7168
	global_load_lds_dwordx4 v[200:201], off
	v_lshl_add_u64 v[200:201], s[52:53], 0, v[138:139]
	s_add_i32 m0, s58, 0xe000
	s_nop 0
	global_load_lds_dwordx4 v[200:201], off
	s_waitcnt vmcnt(8)
	s_waitcnt lgkmcnt(0)
	s_barrier
	s_setprio 1
	s_waitcnt lgkmcnt(0)
	v_mfma_f32_16x16x32_bf16 v[124:127], v[146:149], v[188:191], 0
	v_mfma_f32_16x16x32_bf16 v[120:123], v[160:163], v[188:191], 0
	v_mfma_f32_16x16x32_bf16 v[108:111], v[146:149], v[196:199], 0
	v_mfma_f32_16x16x32_bf16 v[104:107], v[160:163], v[196:199], 0
	v_mfma_f32_16x16x32_bf16 v[92:95], v[146:149], v[210:213], 0
	v_mfma_f32_16x16x32_bf16 v[88:91], v[160:163], v[210:213], 0
	v_mfma_f32_16x16x32_bf16 v[76:79], v[146:149], v[218:221], 0
	v_mfma_f32_16x16x32_bf16 v[72:75], v[160:163], v[218:221], 0
	v_mfma_f32_16x16x32_bf16 v[124:127], v[156:159], v[192:195], v[124:127]
	v_mfma_f32_16x16x32_bf16 v[120:123], v[164:167], v[192:195], v[120:123]
	v_mfma_f32_16x16x32_bf16 v[108:111], v[156:159], v[206:209], v[108:111]
	v_mfma_f32_16x16x32_bf16 v[104:107], v[164:167], v[206:209], v[104:107]
	v_mfma_f32_16x16x32_bf16 v[92:95], v[156:159], v[214:217], v[92:95]
	v_mfma_f32_16x16x32_bf16 v[88:91], v[164:167], v[214:217], v[88:91]
	v_mfma_f32_16x16x32_bf16 v[76:79], v[156:159], v[222:225], v[76:79]
	v_mfma_f32_16x16x32_bf16 v[72:75], v[164:167], v[222:225], v[72:75]
	s_setprio 0
	s_setprio 1
	v_mfma_f32_16x16x32_bf16 v[116:119], v[168:171], v[188:191], 0
	v_mfma_f32_16x16x32_bf16 v[112:115], v[180:183], v[188:191], 0
	v_mfma_f32_16x16x32_bf16 v[100:103], v[168:171], v[196:199], 0
	v_mfma_f32_16x16x32_bf16 v[96:99], v[180:183], v[196:199], 0
	v_mfma_f32_16x16x32_bf16 v[84:87], v[168:171], v[210:213], 0
	v_mfma_f32_16x16x32_bf16 v[80:83], v[180:183], v[210:213], 0
	v_mfma_f32_16x16x32_bf16 v[68:71], v[168:171], v[218:221], 0
	v_mfma_f32_16x16x32_bf16 v[64:67], v[180:183], v[218:221], 0
	v_mfma_f32_16x16x32_bf16 v[116:119], v[172:175], v[192:195], v[116:119]
	v_mfma_f32_16x16x32_bf16 v[112:115], v[184:187], v[192:195], v[112:115]
	v_mfma_f32_16x16x32_bf16 v[100:103], v[172:175], v[206:209], v[100:103]
	v_mfma_f32_16x16x32_bf16 v[96:99], v[184:187], v[206:209], v[96:99]
	v_mfma_f32_16x16x32_bf16 v[84:87], v[172:175], v[214:217], v[84:87]
	v_mfma_f32_16x16x32_bf16 v[80:83], v[184:187], v[214:217], v[80:83]
	v_mfma_f32_16x16x32_bf16 v[68:71], v[172:175], v[222:225], v[68:71]
	v_mfma_f32_16x16x32_bf16 v[64:67], v[184:187], v[222:225], v[64:67]
	s_setprio 0
	s_barrier
	s_add_i32 s82, s65, s34
	v_lshl_add_u64 v[200:201], s[54:55], 0, v[132:133]
	s_mov_b32 m0, s82
	ds_read_b128 v[188:191], v154 offset:16384
	ds_read_b128 v[192:195], v154 offset:17408
	ds_read_b128 v[196:199], v154 offset:18432
	ds_read_b128 v[206:209], v154 offset:19456
	ds_read_b128 v[210:213], v154 offset:20480
	ds_read_b128 v[214:217], v154 offset:21504
	ds_read_b128 v[218:221], v154 offset:22528
	ds_read_b128 v[222:225], v154 offset:23552
	global_load_lds_dwordx4 v[200:201], off
	s_add_i32 m0, s82, 0x2000
	s_add_u32 s82, s54, 0x40000
	v_lshl_add_u64 v[226:227], s[54:55], 0, v[128:129]
	s_addc_u32 s83, s55, 0
	s_add_i32 s84, s66, s34
	global_load_lds_dwordx4 v[226:227], off
	v_lshl_add_u64 v[228:229], s[82:83], 0, v[132:133]
	s_mov_b32 m0, s84
	global_load_lds_dwordx4 v[228:229], off
	v_lshl_add_u64 v[228:229], s[82:83], 0, v[128:129]
	s_add_i32 m0, s84, 0x2000
	s_nop 0
	global_load_lds_dwordx4 v[228:229], off
	s_waitcnt vmcnt(6)
	s_waitcnt lgkmcnt(0)
	s_barrier
; #define PG8_STAGE(bufoff, gbase, voff) do { _Pragma("unroll") for (int _i = 0; _i < 2; ++_i) \
;         __builtin_amdgcn_global_load_lds((const unsigned*)((const char*)(gbase) + (voff)[_i]), (PG8_LAS unsigned*)(lds + (bufoff) + ldsw + _i * 8192), 16, 0, 0); } while (0)
; #define PG8_LDA(dst, b, h) do { _Pragma("unroll") for (int m = 0; m < 4; ++m) _Pragma("unroll") for (int k = 0; k < 2; ++k) dst[m][k] = *(const PG8_LAS bf16x8*)(lds + PG8_SA(b, h) + aoff + m * 2048 + k * 1024); } while (0)
; #define PG8_LDB(dst, b, h) do { _Pragma("unroll") for (int n = 0; n < 2; ++n) _Pragma("unroll") for (int k = 0; k < 2; ++k) dst[n][k] = *(const PG8_LAS bf16x8*)(lds + PG8_SB(b, h) + boff + n * 2048 + k * 1024); } while (0)
; #define PG8_MMA(ai, bj, At, Bt) do { __builtin_amdgcn_s_setprio(1); _Pragma("unroll") for (int m = 0; m < 4; ++m) _Pragma("unroll") for (int n = 0; n < 2; ++n) _Pragma("unroll") for (int k = 0; k < 2; ++k) \
;         acc[ai][bj][m][n] = __builtin_amdgcn_mfma_f32_16x16x32_bf16(Bt[n][k], At[m][k], acc[ai][bj][m][n], 0, 0, 0); __builtin_amdgcn_s_setprio(0); } while (0)
; #define PG8_WAIT_V(n) asm volatile("s_waitcnt vmcnt(" #n ")" ::: "memory")
; #define PG8_WAIT_L(n) asm volatile("s_waitcnt lgkmcnt(" #n ")" ::: "memory")
; #define PG8_BAR __builtin_amdgcn_s_barrier()
; #define PG8_SCHED __builtin_amdgcn_sched_barrier(0)
; template <class Epi, class Sched, bool ALIGN_EPI = false, bool SP2 = false>
; __device__ __forceinline__ void gemm_phase(PG8_LAS unsigned char* lds, const Gemm g, const Sched& S, const Epi& E) {
;     ...
;             PG8_LDA(At, 0, 1); PG8_STAGE(PG8_SB(0, 0), b2, voffB); PG8_STAGE(PG8_SB(0, 1), b2 + hstep, voffB); PG8_STAGE(PG8_SA(0, 0), a2, voffA);
;             PG8_WAIT_V(8); PG8_WAIT_L(0); PG8_BAR; PG8_MMA(1, 0, At, B0); PG8_MMA(1, 1, At, B1); PG8_BAR; PG8_SCHED;
;             PG8_LDB(B0, 1, 0); PG8_LDB(B1, 1, 1); PG8_SCHED; PG8_LDA(At, 1, 0); PG8_STAGE(PG8_SA(0, 1), a2 + hstep, voffA);
;             PG8_WAIT_V(8); PG8_WAIT_L(0); PG8_BAR; PG8_MMA(0, 0, At, B0); PG8_MMA(0, 1, At, B1); PG8_BAR; PG8_SCHED;
;             PG8_LDA(At, 1, 1); PG8_STAGE(PG8_SB(1, 0), b3, voffB); PG8_STAGE(PG8_SB(1, 1), b3 + hstep, voffB); PG8_STAGE(PG8_SA(1, 0), a3, voffA);
;             PG8_WAIT_V(8); PG8_WAIT_L(0); PG8_BAR; PG8_MMA(1, 0, At, B0); PG8_MMA(1, 1, At, B1); PG8_BAR; PG8_SCHED;
	s_setprio 1
	s_waitcnt lgkmcnt(0)
	v_mfma_f32_16x16x32_bf16 v[60:63], v[146:149], v[188:191], 0
	v_mfma_f32_16x16x32_bf16 v[56:59], v[160:163], v[188:191], 0
	v_mfma_f32_16x16x32_bf16 v[44:47], v[146:149], v[196:199], 0
	v_mfma_f32_16x16x32_bf16 v[40:43], v[160:163], v[196:199], 0
	v_mfma_f32_16x16x32_bf16 v[28:31], v[146:149], v[210:213], 0
	v_mfma_f32_16x16x32_bf16 v[24:27], v[160:163], v[210:213], 0
	v_mfma_f32_16x16x32_bf16 v[12:15], v[146:149], v[218:221], 0
	v_mfma_f32_16x16x32_bf16 v[8:11], v[160:163], v[218:221], 0
	v_mfma_f32_16x16x32_bf16 v[60:63], v[156:159], v[192:195], v[60:63]
	v_mfma_f32_16x16x32_bf16 v[56:59], v[164:167], v[192:195], v[56:59]
	v_mfma_f32_16x16x32_bf16 v[44:47], v[156:159], v[206:209], v[44:47]
	v_mfma_f32_16x16x32_bf16 v[40:43], v[164:167], v[206:209], v[40:43]
	v_mfma_f32_16x16x32_bf16 v[28:31], v[156:159], v[214:217], v[28:31]
	v_mfma_f32_16x16x32_bf16 v[24:27], v[164:167], v[214:217], v[24:27]
	v_lshl_add_u64 v[228:229], s[56:57], 0, v[134:135]
	s_mov_b32 m0, s58
	s_nop 0
	global_load_lds_dwordx4 v[228:229], off
	v_mfma_f32_16x16x32_bf16 v[12:15], v[156:159], v[222:225], v[12:15]
	v_mfma_f32_16x16x32_bf16 v[8:11], v[164:167], v[222:225], v[8:11]
	s_setprio 0
	s_setprio 1
	v_mfma_f32_16x16x32_bf16 v[52:55], v[168:171], v[188:191], 0
	v_mfma_f32_16x16x32_bf16 v[48:51], v[180:183], v[188:191], 0
	v_mfma_f32_16x16x32_bf16 v[36:39], v[168:171], v[196:199], 0
	v_mfma_f32_16x16x32_bf16 v[32:35], v[180:183], v[196:199], 0
	v_mfma_f32_16x16x32_bf16 v[20:23], v[168:171], v[210:213], 0
	v_mfma_f32_16x16x32_bf16 v[16:19], v[180:183], v[210:213], 0
	v_mfma_f32_16x16x32_bf16 v[4:7], v[168:171], v[218:221], 0
	v_mfma_f32_16x16x32_bf16 v[0:3], v[180:183], v[218:221], 0
	v_mfma_f32_16x16x32_bf16 v[52:55], v[172:175], v[192:195], v[52:55]
	v_mfma_f32_16x16x32_bf16 v[48:51], v[184:187], v[192:195], v[48:51]
	v_mfma_f32_16x16x32_bf16 v[36:39], v[172:175], v[206:209], v[36:39]
	v_mfma_f32_16x16x32_bf16 v[32:35], v[184:187], v[206:209], v[32:35]
	v_mfma_f32_16x16x32_bf16 v[20:23], v[172:175], v[214:217], v[20:23]
	v_mfma_f32_16x16x32_bf16 v[16:19], v[184:187], v[214:217], v[16:19]
	v_lshl_add_u64 v[230:231], s[56:57], 0, v[130:131]
	s_mov_b32 m0, s59
	s_nop 0
	global_load_lds_dwordx4 v[230:231], off
	v_mfma_f32_16x16x32_bf16 v[4:7], v[172:175], v[222:225], v[4:7]
	v_mfma_f32_16x16x32_bf16 v[0:3], v[184:187], v[222:225], v[0:3]
	s_setprio 0
	s_barrier
	s_add_i32 s82, 0, 0x18000
	s_add_i32 s83, 0, 0x1c000
	v_add_u32_e32 v164, s82, v150
	v_add_u32_e32 v179, s83, v150
	ds_read_b128 v[146:149], v164
	ds_read_b128 v[156:159], v164 offset:1024
	ds_read_b128 v[160:163], v164 offset:2048
	ds_read_b128 v[164:167], v164 offset:3072
	ds_read_b128 v[168:171], v179
	ds_read_b128 v[172:175], v179 offset:1024
	ds_read_b128 v[180:183], v179 offset:2048
	ds_read_b128 v[184:187], v179 offset:3072
	s_add_u32 s56, s56, 0x40000
	s_addc_u32 s57, s57, 0
	s_mov_b32 m0, s60
	v_lshl_add_u64 v[232:233], s[56:57], 0, v[134:135]
	ds_read_b128 v[188:191], v154 offset:32768
	ds_read_b128 v[192:195], v154 offset:33792
	ds_read_b128 v[196:199], v154 offset:34816
	ds_read_b128 v[206:209], v154 offset:35840
	ds_read_b128 v[210:213], v154 offset:36864
	ds_read_b128 v[214:217], v154 offset:37888
	ds_read_b128 v[218:221], v154 offset:38912
	ds_read_b128 v[222:225], v154 offset:39936
	global_load_lds_dwordx4 v[232:233], off
	v_lshl_add_u64 v[232:233], s[56:57], 0, v[130:131]
	s_mov_b32 m0, s61
	s_nop 0
	global_load_lds_dwordx4 v[232:233], off
	s_waitcnt vmcnt(8)
	s_waitcnt lgkmcnt(0)
	s_barrier
	s_setprio 1
	s_waitcnt lgkmcnt(0)
	v_mfma_f32_16x16x32_bf16 v[124:127], v[146:149], v[188:191], v[124:127]
	v_mfma_f32_16x16x32_bf16 v[120:123], v[160:163], v[188:191], v[120:123]
	v_mfma_f32_16x16x32_bf16 v[108:111], v[146:149], v[196:199], v[108:111]
	v_mfma_f32_16x16x32_bf16 v[104:107], v[160:163], v[196:199], v[104:107]
	v_mfma_f32_16x16x32_bf16 v[92:95], v[146:149], v[210:213], v[92:95]
	v_mfma_f32_16x16x32_bf16 v[88:91], v[160:163], v[210:213], v[88:91]
	v_mfma_f32_16x16x32_bf16 v[76:79], v[146:149], v[218:221], v[76:79]
	v_mfma_f32_16x16x32_bf16 v[72:75], v[160:163], v[218:221], v[72:75]
	v_mfma_f32_16x16x32_bf16 v[124:127], v[156:159], v[192:195], v[124:127]
	v_mfma_f32_16x16x32_bf16 v[120:123], v[164:167], v[192:195], v[120:123]
	v_mfma_f32_16x16x32_bf16 v[108:111], v[156:159], v[206:209], v[108:111]
	v_mfma_f32_16x16x32_bf16 v[104:107], v[164:167], v[206:209], v[104:107]
	v_mfma_f32_16x16x32_bf16 v[92:95], v[156:159], v[214:217], v[92:95]
	v_mfma_f32_16x16x32_bf16 v[88:91], v[164:167], v[214:217], v[88:91]
	v_mfma_f32_16x16x32_bf16 v[76:79], v[156:159], v[222:225], v[76:79]
	v_mfma_f32_16x16x32_bf16 v[72:75], v[164:167], v[222:225], v[72:75]
	s_setprio 0
	s_setprio 1
	v_mfma_f32_16x16x32_bf16 v[116:119], v[168:171], v[188:191], v[116:119]
	v_mfma_f32_16x16x32_bf16 v[112:115], v[180:183], v[188:191], v[112:115]
	v_mfma_f32_16x16x32_bf16 v[100:103], v[168:171], v[196:199], v[100:103]
	v_mfma_f32_16x16x32_bf16 v[96:99], v[180:183], v[196:199], v[96:99]
	v_mfma_f32_16x16x32_bf16 v[84:87], v[168:171], v[210:213], v[84:87]
	v_mfma_f32_16x16x32_bf16 v[80:83], v[180:183], v[210:213], v[80:83]
	v_mfma_f32_16x16x32_bf16 v[68:71], v[168:171], v[218:221], v[68:71]
	v_mfma_f32_16x16x32_bf16 v[64:67], v[180:183], v[218:221], v[64:67]
	v_mfma_f32_16x16x32_bf16 v[116:119], v[172:175], v[192:195], v[116:119]
	v_mfma_f32_16x16x32_bf16 v[112:115], v[184:187], v[192:195], v[112:115]
	v_mfma_f32_16x16x32_bf16 v[100:103], v[172:175], v[206:209], v[100:103]
	v_mfma_f32_16x16x32_bf16 v[96:99], v[184:187], v[206:209], v[96:99]
	v_mfma_f32_16x16x32_bf16 v[84:87], v[172:175], v[214:217], v[84:87]
	v_mfma_f32_16x16x32_bf16 v[80:83], v[184:187], v[214:217], v[80:83]
	v_mfma_f32_16x16x32_bf16 v[68:71], v[172:175], v[222:225], v[68:71]
	v_mfma_f32_16x16x32_bf16 v[64:67], v[184:187], v[222:225], v[64:67]
	s_setprio 0
	s_barrier
; #define PG8_STAGE(bufoff, gbase, voff) do { _Pragma("unroll") for (int _i = 0; _i < 2; ++_i) \
;         __builtin_amdgcn_global_load_lds((const unsigned*)((const char*)(gbase) + (voff)[_i]), (PG8_LAS unsigned*)(lds + (bufoff) + ldsw + _i * 8192), 16, 0, 0); } while (0)
; #define PG8_LDA(dst, b, h) do { _Pragma("unroll") for (int m = 0; m < 4; ++m) _Pragma("unroll") for (int k = 0; k < 2; ++k) dst[m][k] = *(const PG8_LAS bf16x8*)(lds + PG8_SA(b, h) + aoff + m * 2048 + k * 1024); } while (0)
; #define PG8_LDB(dst, b, h) do { _Pragma("unroll") for (int n = 0; n < 2; ++n) _Pragma("unroll") for (int k = 0; k < 2; ++k) dst[n][k] = *(const PG8_LAS bf16x8*)(lds + PG8_SB(b, h) + boff + n * 2048 + k * 1024); } while (0)
; #define PG8_MMA(ai, bj, At, Bt) do { __builtin_amdgcn_s_setprio(1); _Pragma("unroll") for (int m = 0; m < 4; ++m) _Pragma("unroll") for (int n = 0; n < 2; ++n) _Pragma("unroll") for (int k = 0; k < 2; ++k) \
;         acc[ai][bj][m][n] = __builtin_amdgcn_mfma_f32_16x16x32_bf16(Bt[n][k], At[m][k], acc[ai][bj][m][n], 0, 0, 0); __builtin_amdgcn_s_setprio(0); } while (0)
; #define PG8_WAIT_V(n) asm volatile("s_waitcnt vmcnt(" #n ")" ::: "memory")
; template <class Epi, class Sched, bool ALIGN_EPI = false, bool SP2 = false>
; __device__ __forceinline__ void gemm_phase(PG8_LAS unsigned char* lds, const Gemm g, const Sched& S, const Epi& E) {
;     ...
;             PG8_LDB(B0, 0, 0); PG8_LDB(B1, 0, 1); PG8_SCHED; PG8_LDA(At, 0, 0); PG8_STAGE(PG8_SA(1, 1), a1 + hstep, voffA);
;             PG8_WAIT_V(8); PG8_WAIT_L(0); PG8_BAR; PG8_MMA(0, 0, At, B0); PG8_MMA(0, 1, At, B1); PG8_BAR; PG8_SCHED;
;             PG8_LDA(At, 0, 1); PG8_STAGE(PG8_SB(0, 0), b2, voffB); PG8_STAGE(PG8_SB(0, 1), b2 + hstep, voffB); PG8_STAGE(PG8_SA(0, 0), a2, voffA);
;             PG8_WAIT_V(8); PG8_WAIT_L(0); PG8_BAR; PG8_MMA(1, 0, At, B0); PG8_MMA(1, 1, At, B1); PG8_BAR; PG8_SCHED;
;             PG8_LDB(B0, 1, 0); PG8_LDB(B1, 1, 1); PG8_SCHED; PG8_LDA(At, 1, 0); PG8_STAGE(PG8_SA(0, 1), a2 + hstep, voffA);
;             PG8_WAIT_V(8); PG8_WAIT_L(0); PG8_BAR; PG8_MMA(0, 0, At, B0); PG8_MMA(0, 1, At, B1); PG8_BAR; PG8_SCHED;
;             PG8_LDA(At, 1, 1); PG8_STAGE(PG8_SB(1, 0), b3, voffB); PG8_STAGE(PG8_SB(1, 1), b3 + hstep, voffB); PG8_STAGE(PG8_SA(1, 0), a3, voffA);
;             PG8_WAIT_V(8); PG8_WAIT_L(0); PG8_BAR; PG8_MMA(1, 0, At, B0); PG8_MMA(1, 1, At, B1); PG8_BAR; PG8_SCHED;
	s_add_i32 s56, s82, s34
	v_lshl_add_u64 v[200:201], v[200:201], 0, s[26:27]
	s_mov_b32 m0, s56
	ds_read_b128 v[188:191], v154 offset:49152
	ds_read_b128 v[192:195], v154 offset:50176
	ds_read_b128 v[196:199], v154 offset:51200
	ds_read_b128 v[206:209], v154 offset:52224
	ds_read_b128 v[210:213], v154 offset:53248
	ds_read_b128 v[214:217], v154 offset:54272
	ds_read_b128 v[218:221], v154 offset:55296
	ds_read_b128 v[222:225], v154 offset:56320
	global_load_lds_dwordx4 v[200:201], off
	s_add_i32 m0, s56, 0x2000
	s_add_u32 s54, s54, 0x40080
	v_lshl_add_u64 v[200:201], v[226:227], 0, s[26:27]
	s_addc_u32 s55, s55, 0
	s_add_i32 s56, s83, s34
	global_load_lds_dwordx4 v[200:201], off
	v_lshl_add_u64 v[200:201], s[54:55], 0, v[132:133]
	s_mov_b32 m0, s56
	s_nop 0
	global_load_lds_dwordx4 v[200:201], off
	v_lshl_add_u64 v[200:201], s[54:55], 0, v[128:129]
	s_add_i32 m0, s56, 0x2000
	s_nop 0
	global_load_lds_dwordx4 v[200:201], off
	s_waitcnt vmcnt(6)
	s_waitcnt lgkmcnt(0)
	s_barrier
	s_setprio 1
	s_waitcnt lgkmcnt(0)
	v_mfma_f32_16x16x32_bf16 v[60:63], v[146:149], v[188:191], v[60:63]
	v_mfma_f32_16x16x32_bf16 v[56:59], v[160:163], v[188:191], v[56:59]
	v_mfma_f32_16x16x32_bf16 v[44:47], v[146:149], v[196:199], v[44:47]
	v_mfma_f32_16x16x32_bf16 v[40:43], v[160:163], v[196:199], v[40:43]
	v_mfma_f32_16x16x32_bf16 v[28:31], v[146:149], v[210:213], v[28:31]
	v_mfma_f32_16x16x32_bf16 v[24:27], v[160:163], v[210:213], v[24:27]
	v_mfma_f32_16x16x32_bf16 v[12:15], v[146:149], v[218:221], v[12:15]
	v_mfma_f32_16x16x32_bf16 v[8:11], v[160:163], v[218:221], v[8:11]
	v_mfma_f32_16x16x32_bf16 v[60:63], v[156:159], v[192:195], v[60:63]
	v_mfma_f32_16x16x32_bf16 v[56:59], v[164:167], v[192:195], v[56:59]
	v_mfma_f32_16x16x32_bf16 v[44:47], v[156:159], v[206:209], v[44:47]
	v_mfma_f32_16x16x32_bf16 v[40:43], v[164:167], v[206:209], v[40:43]
	v_mfma_f32_16x16x32_bf16 v[28:31], v[156:159], v[214:217], v[28:31]
	v_mfma_f32_16x16x32_bf16 v[24:27], v[164:167], v[214:217], v[24:27]
	v_lshl_add_u64 v[200:201], v[228:229], 0, s[26:27]
	s_mov_b32 m0, s63
	s_nop 0
	global_load_lds_dwordx4 v[200:201], off
	v_mfma_f32_16x16x32_bf16 v[12:15], v[156:159], v[222:225], v[12:15]
	v_mfma_f32_16x16x32_bf16 v[8:11], v[164:167], v[222:225], v[8:11]
	s_setprio 0
	s_setprio 1
	v_mfma_f32_16x16x32_bf16 v[52:55], v[168:171], v[188:191], v[52:55]
	v_mfma_f32_16x16x32_bf16 v[48:51], v[180:183], v[188:191], v[48:51]
	v_mfma_f32_16x16x32_bf16 v[36:39], v[168:171], v[196:199], v[36:39]
	v_mfma_f32_16x16x32_bf16 v[32:35], v[180:183], v[196:199], v[32:35]
	v_mfma_f32_16x16x32_bf16 v[20:23], v[168:171], v[210:213], v[20:23]
	v_mfma_f32_16x16x32_bf16 v[16:19], v[180:183], v[210:213], v[16:19]
	v_mfma_f32_16x16x32_bf16 v[4:7], v[168:171], v[218:221], v[4:7]
	v_mfma_f32_16x16x32_bf16 v[0:3], v[180:183], v[218:221], v[0:3]
	v_mfma_f32_16x16x32_bf16 v[52:55], v[172:175], v[192:195], v[52:55]
	v_mfma_f32_16x16x32_bf16 v[48:51], v[184:187], v[192:195], v[48:51]
	v_mfma_f32_16x16x32_bf16 v[36:39], v[172:175], v[206:209], v[36:39]
	v_mfma_f32_16x16x32_bf16 v[32:35], v[184:187], v[206:209], v[32:35]
	v_mfma_f32_16x16x32_bf16 v[20:23], v[172:175], v[214:217], v[20:23]
	v_mfma_f32_16x16x32_bf16 v[16:19], v[184:187], v[214:217], v[16:19]
	v_lshl_add_u64 v[200:201], v[230:231], 0, s[26:27]
	s_mov_b32 m0, s64
	s_nop 0
	global_load_lds_dwordx4 v[200:201], off
	v_mfma_f32_16x16x32_bf16 v[4:7], v[172:175], v[222:225], v[4:7]
	v_mfma_f32_16x16x32_bf16 v[0:3], v[184:187], v[222:225], v[0:3]
	s_setprio 0
	s_barrier
	s_add_i32 s81, s81, 2
	s_add_u32 s52, s52, 0x100
	s_addc_u32 s53, s53, 0
	s_add_u32 s79, s79, 0x100
	s_addc_u32 s80, s80, 0
.LBB0_1681:
	ds_read_b128 v[146:149], v152
	ds_read_b128 v[156:159], v152 offset:1024
	ds_read_b128 v[160:163], v152 offset:2048
	ds_read_b128 v[164:167], v152 offset:3072
	ds_read_b128 v[168:171], v153
	ds_read_b128 v[172:175], v153 offset:1024
	ds_read_b128 v[180:183], v153 offset:2048
	ds_read_b128 v[184:187], v153 offset:3072
	s_add_u32 s54, s52, 0xfffc0080
	s_addc_u32 s55, s53, -1
	s_cmp_eq_u32 s81, 12
	s_cselect_b32 s57, s47, s55
	s_cselect_b32 s56, s77, s54
	s_cselect_b32 s55, s45, s80
	s_cselect_b32 s54, s78, s79
	v_lshl_add_u64 v[200:201], s[52:53], 0, v[136:137]
	s_add_i32 m0, s58, 0xc000
	ds_read_b128 v[188:191], v154
	ds_read_b128 v[192:195], v154 offset:1024
	ds_read_b128 v[196:199], v154 offset:2048
	ds_read_b128 v[206:209], v154 offset:3072
	ds_read_b128 v[210:213], v154 offset:4096
	ds_read_b128 v[214:217], v154 offset:5120
	ds_read_b128 v[218:221], v154 offset:6144
	ds_read_b128 v[222:225], v154 offset:7168
	global_load_lds_dwordx4 v[200:201], off
	v_lshl_add_u64 v[200:201], s[52:53], 0, v[138:139]
	s_add_i32 m0, s58, 0xe000
	s_nop 0
	global_load_lds_dwordx4 v[200:201], off
	s_waitcnt vmcnt(8)
	s_waitcnt lgkmcnt(0)
	s_barrier
; #define PG8_STAGE(bufoff, gbase, voff) do { _Pragma("unroll") for (int _i = 0; _i < 2; ++_i) \
;         __builtin_amdgcn_global_load_lds((const unsigned*)((const char*)(gbase) + (voff)[_i]), (PG8_LAS unsigned*)(lds + (bufoff) + ldsw + _i * 8192), 16, 0, 0); } while (0)
; #define PG8_LDA(dst, b, h) do { _Pragma("unroll") for (int m = 0; m < 4; ++m) _Pragma("unroll") for (int k = 0; k < 2; ++k) dst[m][k] = *(const PG8_LAS bf16x8*)(lds + PG8_SA(b, h) + aoff + m * 2048 + k * 1024); } while (0)
; #define PG8_LDB(dst, b, h) do { _Pragma("unroll") for (int n = 0; n < 2; ++n) _Pragma("unroll") for (int k = 0; k < 2; ++k) dst[n][k] = *(const PG8_LAS bf16x8*)(lds + PG8_SB(b, h) + boff + n * 2048 + k * 1024); } while (0)
; #define PG8_MMA(ai, bj, At, Bt) do { __builtin_amdgcn_s_setprio(1); _Pragma("unroll") for (int m = 0; m < 4; ++m) _Pragma("unroll") for (int n = 0; n < 2; ++n) _Pragma("unroll") for (int k = 0; k < 2; ++k) \
;         acc[ai][bj][m][n] = __builtin_amdgcn_mfma_f32_16x16x32_bf16(Bt[n][k], At[m][k], acc[ai][bj][m][n], 0, 0, 0); __builtin_amdgcn_s_setprio(0); } while (0)
; #define PG8_WAIT_V(n) asm volatile("s_waitcnt vmcnt(" #n ")" ::: "memory")
; #define PG8_WAIT_L(n) asm volatile("s_waitcnt lgkmcnt(" #n ")" ::: "memory")
; #define PG8_BAR __builtin_amdgcn_s_barrier()
; #define PG8_SCHED __builtin_amdgcn_sched_barrier(0)
; template <class Epi, class Sched, bool ALIGN_EPI = false, bool SP2 = false>
; __device__ __forceinline__ void gemm_phase(PG8_LAS unsigned char* lds, const Gemm g, const Sched& S, const Epi& E) {
;     ...
;             PG8_LDB(B0, 0, 0); PG8_LDB(B1, 0, 1); PG8_SCHED; PG8_LDA(At, 0, 0); PG8_STAGE(PG8_SA(1, 1), a1 + hstep, voffA);
;             PG8_WAIT_V(8); PG8_WAIT_L(0); PG8_BAR; PG8_MMA(0, 0, At, B0); PG8_MMA(0, 1, At, B1); PG8_BAR; PG8_SCHED;
;             PG8_LDA(At, 0, 1); PG8_STAGE(PG8_SB(0, 0), b2, voffB); PG8_STAGE(PG8_SB(0, 1), b2 + hstep, voffB); PG8_STAGE(PG8_SA(0, 0), a2, voffA);
;             PG8_WAIT_V(8); PG8_WAIT_L(0); PG8_BAR; PG8_MMA(1, 0, At, B0); PG8_MMA(1, 1, At, B1); PG8_BAR; PG8_SCHED;
;             PG8_LDB(B0, 1, 0); PG8_LDB(B1, 1, 1); PG8_SCHED; PG8_LDA(At, 1, 0); PG8_STAGE(PG8_SA(0, 1), a2 + hstep, voffA);
;             PG8_WAIT_V(8); PG8_WAIT_L(0); PG8_BAR; PG8_MMA(0, 0, At, B0); PG8_MMA(0, 1, At, B1); PG8_BAR; PG8_SCHED;
	s_setprio 1
	s_waitcnt lgkmcnt(0)
	v_mfma_f32_16x16x32_bf16 v[124:127], v[146:149], v[188:191], v[124:127]
	v_mfma_f32_16x16x32_bf16 v[120:123], v[160:163], v[188:191], v[120:123]
	v_mfma_f32_16x16x32_bf16 v[108:111], v[146:149], v[196:199], v[108:111]
	v_mfma_f32_16x16x32_bf16 v[104:107], v[160:163], v[196:199], v[104:107]
	v_mfma_f32_16x16x32_bf16 v[92:95], v[146:149], v[210:213], v[92:95]
	v_mfma_f32_16x16x32_bf16 v[88:91], v[160:163], v[210:213], v[88:91]
	v_mfma_f32_16x16x32_bf16 v[76:79], v[146:149], v[218:221], v[76:79]
	v_mfma_f32_16x16x32_bf16 v[72:75], v[160:163], v[218:221], v[72:75]
	v_mfma_f32_16x16x32_bf16 v[124:127], v[156:159], v[192:195], v[124:127]
	v_mfma_f32_16x16x32_bf16 v[120:123], v[164:167], v[192:195], v[120:123]
	v_mfma_f32_16x16x32_bf16 v[108:111], v[156:159], v[206:209], v[108:111]
	v_mfma_f32_16x16x32_bf16 v[104:107], v[164:167], v[206:209], v[104:107]
	v_mfma_f32_16x16x32_bf16 v[92:95], v[156:159], v[214:217], v[92:95]
	v_mfma_f32_16x16x32_bf16 v[88:91], v[164:167], v[214:217], v[88:91]
	v_mfma_f32_16x16x32_bf16 v[76:79], v[156:159], v[222:225], v[76:79]
	v_mfma_f32_16x16x32_bf16 v[72:75], v[164:167], v[222:225], v[72:75]
	s_setprio 0
	s_setprio 1
	v_mfma_f32_16x16x32_bf16 v[116:119], v[168:171], v[188:191], v[116:119]
	v_mfma_f32_16x16x32_bf16 v[112:115], v[180:183], v[188:191], v[112:115]
	v_mfma_f32_16x16x32_bf16 v[100:103], v[168:171], v[196:199], v[100:103]
	v_mfma_f32_16x16x32_bf16 v[96:99], v[180:183], v[196:199], v[96:99]
	v_mfma_f32_16x16x32_bf16 v[84:87], v[168:171], v[210:213], v[84:87]
	v_mfma_f32_16x16x32_bf16 v[80:83], v[180:183], v[210:213], v[80:83]
	v_mfma_f32_16x16x32_bf16 v[68:71], v[168:171], v[218:221], v[68:71]
	v_mfma_f32_16x16x32_bf16 v[64:67], v[180:183], v[218:221], v[64:67]
	v_mfma_f32_16x16x32_bf16 v[116:119], v[172:175], v[192:195], v[116:119]
	v_mfma_f32_16x16x32_bf16 v[112:115], v[184:187], v[192:195], v[112:115]
	v_mfma_f32_16x16x32_bf16 v[100:103], v[172:175], v[206:209], v[100:103]
	v_mfma_f32_16x16x32_bf16 v[96:99], v[184:187], v[206:209], v[96:99]
	v_mfma_f32_16x16x32_bf16 v[84:87], v[172:175], v[214:217], v[84:87]
	v_mfma_f32_16x16x32_bf16 v[80:83], v[184:187], v[214:217], v[80:83]
	v_mfma_f32_16x16x32_bf16 v[68:71], v[172:175], v[222:225], v[68:71]
	v_mfma_f32_16x16x32_bf16 v[64:67], v[184:187], v[222:225], v[64:67]
	s_setprio 0
	s_barrier
	s_add_i32 s82, s65, s34
	v_lshl_add_u64 v[200:201], s[54:55], 0, v[132:133]
	s_mov_b32 m0, s82
	ds_read_b128 v[188:191], v154 offset:16384
	ds_read_b128 v[192:195], v154 offset:17408
	ds_read_b128 v[196:199], v154 offset:18432
	ds_read_b128 v[206:209], v154 offset:19456
	ds_read_b128 v[210:213], v154 offset:20480
	ds_read_b128 v[214:217], v154 offset:21504
	ds_read_b128 v[218:221], v154 offset:22528
	ds_read_b128 v[222:225], v154 offset:23552
	global_load_lds_dwordx4 v[200:201], off
	s_add_i32 m0, s82, 0x2000
	s_add_u32 s82, s54, 0x40000
	v_lshl_add_u64 v[226:227], s[54:55], 0, v[128:129]
	s_addc_u32 s83, s55, 0
	s_add_i32 s84, s66, s34
	global_load_lds_dwordx4 v[226:227], off
	v_lshl_add_u64 v[228:229], s[82:83], 0, v[132:133]
	s_mov_b32 m0, s84
	global_load_lds_dwordx4 v[228:229], off
	v_lshl_add_u64 v[228:229], s[82:83], 0, v[128:129]
	s_add_i32 m0, s84, 0x2000
	s_nop 0
	global_load_lds_dwordx4 v[228:229], off
	s_waitcnt vmcnt(6)
	s_waitcnt lgkmcnt(0)
	s_barrier
	s_setprio 1
	s_waitcnt lgkmcnt(0)
	v_mfma_f32_16x16x32_bf16 v[60:63], v[146:149], v[188:191], v[60:63]
	v_mfma_f32_16x16x32_bf16 v[56:59], v[160:163], v[188:191], v[56:59]
	v_mfma_f32_16x16x32_bf16 v[44:47], v[146:149], v[196:199], v[44:47]
	v_mfma_f32_16x16x32_bf16 v[40:43], v[160:163], v[196:199], v[40:43]
	v_mfma_f32_16x16x32_bf16 v[28:31], v[146:149], v[210:213], v[28:31]
	v_mfma_f32_16x16x32_bf16 v[24:27], v[160:163], v[210:213], v[24:27]
	v_mfma_f32_16x16x32_bf16 v[12:15], v[146:149], v[218:221], v[12:15]
	v_mfma_f32_16x16x32_bf16 v[8:11], v[160:163], v[218:221], v[8:11]
	v_mfma_f32_16x16x32_bf16 v[60:63], v[156:159], v[192:195], v[60:63]
	v_mfma_f32_16x16x32_bf16 v[56:59], v[164:167], v[192:195], v[56:59]
	v_mfma_f32_16x16x32_bf16 v[44:47], v[156:159], v[206:209], v[44:47]
	v_mfma_f32_16x16x32_bf16 v[40:43], v[164:167], v[206:209], v[40:43]
	v_mfma_f32_16x16x32_bf16 v[28:31], v[156:159], v[214:217], v[28:31]
	v_mfma_f32_16x16x32_bf16 v[24:27], v[164:167], v[214:217], v[24:27]
	v_lshl_add_u64 v[228:229], s[56:57], 0, v[134:135]
	s_mov_b32 m0, s58
	s_nop 0
	global_load_lds_dwordx4 v[228:229], off
	v_mfma_f32_16x16x32_bf16 v[12:15], v[156:159], v[222:225], v[12:15]
	v_mfma_f32_16x16x32_bf16 v[8:11], v[164:167], v[222:225], v[8:11]
	s_setprio 0
	s_setprio 1
	v_mfma_f32_16x16x32_bf16 v[52:55], v[168:171], v[188:191], v[52:55]
	v_mfma_f32_16x16x32_bf16 v[48:51], v[180:183], v[188:191], v[48:51]
	v_mfma_f32_16x16x32_bf16 v[36:39], v[168:171], v[196:199], v[36:39]
	v_mfma_f32_16x16x32_bf16 v[32:35], v[180:183], v[196:199], v[32:35]
	v_mfma_f32_16x16x32_bf16 v[20:23], v[168:171], v[210:213], v[20:23]
	v_mfma_f32_16x16x32_bf16 v[16:19], v[180:183], v[210:213], v[16:19]
	v_mfma_f32_16x16x32_bf16 v[4:7], v[168:171], v[218:221], v[4:7]
	v_mfma_f32_16x16x32_bf16 v[0:3], v[180:183], v[218:221], v[0:3]
	v_mfma_f32_16x16x32_bf16 v[52:55], v[172:175], v[192:195], v[52:55]
	v_mfma_f32_16x16x32_bf16 v[48:51], v[184:187], v[192:195], v[48:51]
	v_mfma_f32_16x16x32_bf16 v[36:39], v[172:175], v[206:209], v[36:39]
	v_mfma_f32_16x16x32_bf16 v[32:35], v[184:187], v[206:209], v[32:35]
	v_mfma_f32_16x16x32_bf16 v[20:23], v[172:175], v[214:217], v[20:23]
	v_mfma_f32_16x16x32_bf16 v[16:19], v[184:187], v[214:217], v[16:19]
	v_lshl_add_u64 v[230:231], s[56:57], 0, v[130:131]
	s_mov_b32 m0, s59
	s_nop 0
	global_load_lds_dwordx4 v[230:231], off
	v_mfma_f32_16x16x32_bf16 v[4:7], v[172:175], v[222:225], v[4:7]
	v_mfma_f32_16x16x32_bf16 v[0:3], v[184:187], v[222:225], v[0:3]
	s_setprio 0
	s_barrier
; #define PG8_STAGE(bufoff, gbase, voff) do { _Pragma("unroll") for (int _i = 0; _i < 2; ++_i) \
;         __builtin_amdgcn_global_load_lds((const unsigned*)((const char*)(gbase) + (voff)[_i]), (PG8_LAS unsigned*)(lds + (bufoff) + ldsw + _i * 8192), 16, 0, 0); } while (0)
; #define PG8_LDA(dst, b, h) do { _Pragma("unroll") for (int m = 0; m < 4; ++m) _Pragma("unroll") for (int k = 0; k < 2; ++k) dst[m][k] = *(const PG8_LAS bf16x8*)(lds + PG8_SA(b, h) + aoff + m * 2048 + k * 1024); } while (0)
; #define PG8_LDB(dst, b, h) do { _Pragma("unroll") for (int n = 0; n < 2; ++n) _Pragma("unroll") for (int k = 0; k < 2; ++k) dst[n][k] = *(const PG8_LAS bf16x8*)(lds + PG8_SB(b, h) + boff + n * 2048 + k * 1024); } while (0)
; #define PG8_MMA(ai, bj, At, Bt) do { __builtin_amdgcn_s_setprio(1); _Pragma("unroll") for (int m = 0; m < 4; ++m) _Pragma("unroll") for (int n = 0; n < 2; ++n) _Pragma("unroll") for (int k = 0; k < 2; ++k) \
;         acc[ai][bj][m][n] = __builtin_amdgcn_mfma_f32_16x16x32_bf16(Bt[n][k], At[m][k], acc[ai][bj][m][n], 0, 0, 0); __builtin_amdgcn_s_setprio(0); } while (0)
; #define PG8_WAIT_V(n) asm volatile("s_waitcnt vmcnt(" #n ")" ::: "memory")
; #define PG8_WAIT_L(n) asm volatile("s_waitcnt lgkmcnt(" #n ")" ::: "memory")
; #define PG8_BAR __builtin_amdgcn_s_barrier()
; #define PG8_SCHED __builtin_amdgcn_sched_barrier(0)
; template <class Epi, class Sched, bool ALIGN_EPI = false, bool SP2 = false>
; __device__ __forceinline__ void gemm_phase(PG8_LAS unsigned char* lds, const Gemm g, const Sched& S, const Epi& E) {
;     ...
;             PG8_LDB(B0, 1, 0); PG8_LDB(B1, 1, 1); PG8_SCHED; PG8_LDA(At, 1, 0); PG8_STAGE(PG8_SA(0, 1), a2 + hstep, voffA);
;             PG8_WAIT_V(8); PG8_WAIT_L(0); PG8_BAR; PG8_MMA(0, 0, At, B0); PG8_MMA(0, 1, At, B1); PG8_BAR; PG8_SCHED;
;             PG8_LDA(At, 1, 1); PG8_STAGE(PG8_SB(1, 0), b3, voffB); PG8_STAGE(PG8_SB(1, 1), b3 + hstep, voffB); PG8_STAGE(PG8_SA(1, 0), a3, voffA);
;             PG8_WAIT_V(8); PG8_WAIT_L(0); PG8_BAR; PG8_MMA(1, 0, At, B0); PG8_MMA(1, 1, At, B1); PG8_BAR; PG8_SCHED;
	s_add_i32 s82, 0, 0x18000
	s_add_i32 s83, 0, 0x1c000
	v_add_u32_e32 v164, s82, v150
	v_add_u32_e32 v179, s83, v150
	ds_read_b128 v[146:149], v164
	ds_read_b128 v[156:159], v164 offset:1024
	ds_read_b128 v[160:163], v164 offset:2048
	ds_read_b128 v[164:167], v164 offset:3072
	ds_read_b128 v[168:171], v179
	ds_read_b128 v[172:175], v179 offset:1024
	ds_read_b128 v[180:183], v179 offset:2048
	ds_read_b128 v[184:187], v179 offset:3072
	s_add_u32 s56, s56, 0x40000
	s_addc_u32 s57, s57, 0
	s_mov_b32 m0, s60
	v_lshl_add_u64 v[232:233], s[56:57], 0, v[134:135]
	ds_read_b128 v[188:191], v154 offset:32768
	ds_read_b128 v[192:195], v154 offset:33792
	ds_read_b128 v[196:199], v154 offset:34816
	ds_read_b128 v[206:209], v154 offset:35840
	ds_read_b128 v[210:213], v154 offset:36864
	ds_read_b128 v[214:217], v154 offset:37888
	ds_read_b128 v[218:221], v154 offset:38912
	ds_read_b128 v[222:225], v154 offset:39936
	global_load_lds_dwordx4 v[232:233], off
	v_lshl_add_u64 v[232:233], s[56:57], 0, v[130:131]
	s_mov_b32 m0, s61
	s_nop 0
	global_load_lds_dwordx4 v[232:233], off
	s_waitcnt vmcnt(8)
	s_waitcnt lgkmcnt(0)
	s_barrier
	s_setprio 1
	s_waitcnt lgkmcnt(0)
	v_mfma_f32_16x16x32_bf16 v[124:127], v[146:149], v[188:191], v[124:127]
	v_mfma_f32_16x16x32_bf16 v[120:123], v[160:163], v[188:191], v[120:123]
	v_mfma_f32_16x16x32_bf16 v[108:111], v[146:149], v[196:199], v[108:111]
	v_mfma_f32_16x16x32_bf16 v[104:107], v[160:163], v[196:199], v[104:107]
	v_mfma_f32_16x16x32_bf16 v[92:95], v[146:149], v[210:213], v[92:95]
	v_mfma_f32_16x16x32_bf16 v[88:91], v[160:163], v[210:213], v[88:91]
	v_mfma_f32_16x16x32_bf16 v[76:79], v[146:149], v[218:221], v[76:79]
	v_mfma_f32_16x16x32_bf16 v[72:75], v[160:163], v[218:221], v[72:75]
	v_mfma_f32_16x16x32_bf16 v[124:127], v[156:159], v[192:195], v[124:127]
	v_mfma_f32_16x16x32_bf16 v[120:123], v[164:167], v[192:195], v[120:123]
	v_mfma_f32_16x16x32_bf16 v[108:111], v[156:159], v[206:209], v[108:111]
	v_mfma_f32_16x16x32_bf16 v[104:107], v[164:167], v[206:209], v[104:107]
	v_mfma_f32_16x16x32_bf16 v[92:95], v[156:159], v[214:217], v[92:95]
	v_mfma_f32_16x16x32_bf16 v[88:91], v[164:167], v[214:217], v[88:91]
	v_mfma_f32_16x16x32_bf16 v[76:79], v[156:159], v[222:225], v[76:79]
	v_mfma_f32_16x16x32_bf16 v[72:75], v[164:167], v[222:225], v[72:75]
	s_setprio 0
	s_setprio 1
	v_mfma_f32_16x16x32_bf16 v[116:119], v[168:171], v[188:191], v[116:119]
	v_mfma_f32_16x16x32_bf16 v[112:115], v[180:183], v[188:191], v[112:115]
	v_mfma_f32_16x16x32_bf16 v[100:103], v[168:171], v[196:199], v[100:103]
	v_mfma_f32_16x16x32_bf16 v[96:99], v[180:183], v[196:199], v[96:99]
	v_mfma_f32_16x16x32_bf16 v[84:87], v[168:171], v[210:213], v[84:87]
	v_mfma_f32_16x16x32_bf16 v[80:83], v[180:183], v[210:213], v[80:83]
	v_mfma_f32_16x16x32_bf16 v[68:71], v[168:171], v[218:221], v[68:71]
	v_mfma_f32_16x16x32_bf16 v[64:67], v[180:183], v[218:221], v[64:67]
	v_mfma_f32_16x16x32_bf16 v[116:119], v[172:175], v[192:195], v[116:119]
	v_mfma_f32_16x16x32_bf16 v[112:115], v[184:187], v[192:195], v[112:115]
	v_mfma_f32_16x16x32_bf16 v[100:103], v[172:175], v[206:209], v[100:103]
	v_mfma_f32_16x16x32_bf16 v[96:99], v[184:187], v[206:209], v[96:99]
	v_mfma_f32_16x16x32_bf16 v[84:87], v[172:175], v[214:217], v[84:87]
	v_mfma_f32_16x16x32_bf16 v[80:83], v[184:187], v[214:217], v[80:83]
	v_mfma_f32_16x16x32_bf16 v[68:71], v[172:175], v[222:225], v[68:71]
	v_mfma_f32_16x16x32_bf16 v[64:67], v[184:187], v[222:225], v[64:67]
	s_setprio 0
	s_barrier
	s_add_i32 s56, s82, s34
	v_lshl_add_u64 v[200:201], v[200:201], 0, s[26:27]
	s_mov_b32 m0, s56
	ds_read_b128 v[188:191], v154 offset:49152
	ds_read_b128 v[192:195], v154 offset:50176
	ds_read_b128 v[196:199], v154 offset:51200
	ds_read_b128 v[206:209], v154 offset:52224
	ds_read_b128 v[210:213], v154 offset:53248
	ds_read_b128 v[214:217], v154 offset:54272
	ds_read_b128 v[218:221], v154 offset:55296
	ds_read_b128 v[222:225], v154 offset:56320
	global_load_lds_dwordx4 v[200:201], off
	s_add_i32 m0, s56, 0x2000
	s_add_u32 s54, s54, 0x40080
	v_lshl_add_u64 v[200:201], v[226:227], 0, s[26:27]
	s_addc_u32 s55, s55, 0
	s_add_i32 s56, s83, s34
	global_load_lds_dwordx4 v[200:201], off
	v_lshl_add_u64 v[200:201], s[54:55], 0, v[132:133]
	s_mov_b32 m0, s56
	s_nop 0
	global_load_lds_dwordx4 v[200:201], off
	v_lshl_add_u64 v[200:201], s[54:55], 0, v[128:129]
	s_add_i32 m0, s56, 0x2000
	s_nop 0
	global_load_lds_dwordx4 v[200:201], off
	s_waitcnt vmcnt(6)
	s_waitcnt lgkmcnt(0)
	s_barrier
; #define PG8_BAR __builtin_amdgcn_s_barrier()
;     __device__ __forceinline__ void operator()(const f32x4 (&acc)[2][2][4][2], const Unit& u, int wr, int wc, int fr, int fq) const {
;         const int row0 = u.pm * BM + wr * 64 + fr, col0 = u.pn * BM + wc * 32 + 8 * fq;
; #pragma unroll
;         for (int ai = 0; ai < 2; ++ai)
; #pragma unroll
;             for (int m = 0; m < 4; ++m) { const int row = row0 + ai * HALF + m * 16; const float rs = ss ? row_rs(ss, row) : 1.0f;
; #pragma unroll
;                 for (int bj = 0; bj < 2; ++bj) { const f32x4 v0 = acc[ai][bj][m][0] * rs, v1 = acc[ai][bj][m][1] * rs;
; template <class Epi, class Sched, bool ALIGN_EPI = false, bool SP2 = false>
; __device__ __forceinline__ void gemm_phase(PG8_LAS unsigned char* lds, const Gemm g, const Sched& S, const Epi& E) {
;     ...
;             PG8_WAIT_V(8); PG8_WAIT_L(0); PG8_BAR; PG8_MMA(1, 0, At, B0); PG8_MMA(1, 1, At, B1); PG8_BAR; PG8_SCHED;
;             } else {
;             PG8_LDB(B0, 0, 0); PG8_SCHED; PG8_LDA(At, 0, 0); PG8_STAGE(PG8_SA(1, 1), a1 + hstep, voffA);
;             PG8_WAIT_L(8); PG8_BAR; PG8_WAIT_L(0); PG8_MMA(0, 0, At, B0); PG8_BAR; PG8_SCHED;
;             PG8_LDB(B1, 0, 1); PG8_STAGE(PG8_SB(0, 0), b2, voffB);
;             PG8_BAR; PG8_WAIT_L(0); PG8_MMA(0, 1, At, B1); PG8_BAR;
;             PG8_LDA(At, 0, 1); PG8_STAGE(PG8_SA(0, 0), a2, voffA);
;             PG8_BAR; PG8_WAIT_L(0); PG8_MMA(1, 0, At, B0); PG8_BAR; PG8_SCHED;
;             PG8_STAGE(PG8_SB(0, 1), b2 + hstep, voffB);
;             PG8_WAIT_V(6); PG8_BAR; PG8_MMA(1, 1, At, B1); PG8_BAR;
;             PG8_LDB(B0, 1, 0); PG8_SCHED; PG8_LDA(At, 1, 0); PG8_STAGE(PG8_SA(0, 1), a2 + hstep, voffA);
;             PG8_WAIT_L(8); PG8_BAR; PG8_WAIT_L(0); PG8_MMA(0, 0, At, B0); PG8_BAR; PG8_SCHED;
;             PG8_LDB(B1, 1, 1); PG8_STAGE(PG8_SB(1, 0), b3, voffB);
;             PG8_BAR; PG8_WAIT_L(0); PG8_MMA(0, 1, At, B1); PG8_BAR;
;             PG8_LDA(At, 1, 1); PG8_STAGE(PG8_SA(1, 0), a3, voffA);
;             PG8_BAR; PG8_WAIT_L(0); PG8_MMA(1, 0, At, B0); PG8_BAR; PG8_SCHED;
;             PG8_STAGE(PG8_SB(1, 1), b3 + hstep, voffB);
;             PG8_WAIT_V(6); PG8_BAR; PG8_MMA(1, 1, At, B1); PG8_BAR;
;             }
;         }
;         if constexpr (ALIGN_EPI) { if (wr == 0) PG8_BAR; }
;         if constexpr (!Epi::AFTER_DRAIN) { E(acc, cur, wr, wc, fr, fq); S.done(cur); }
	s_setprio 1
	s_waitcnt lgkmcnt(0)
	v_mfma_f32_16x16x32_bf16 v[60:63], v[146:149], v[188:191], v[60:63]
	v_mfma_f32_16x16x32_bf16 v[56:59], v[160:163], v[188:191], v[56:59]
	v_mfma_f32_16x16x32_bf16 v[44:47], v[146:149], v[196:199], v[44:47]
	v_mfma_f32_16x16x32_bf16 v[40:43], v[160:163], v[196:199], v[40:43]
	v_mfma_f32_16x16x32_bf16 v[28:31], v[146:149], v[210:213], v[28:31]
	v_mfma_f32_16x16x32_bf16 v[24:27], v[160:163], v[210:213], v[24:27]
	v_mfma_f32_16x16x32_bf16 v[12:15], v[146:149], v[218:221], v[12:15]
	v_mfma_f32_16x16x32_bf16 v[8:11], v[160:163], v[218:221], v[8:11]
	v_mfma_f32_16x16x32_bf16 v[60:63], v[156:159], v[192:195], v[60:63]
	v_mfma_f32_16x16x32_bf16 v[56:59], v[164:167], v[192:195], v[56:59]
	v_mfma_f32_16x16x32_bf16 v[44:47], v[156:159], v[206:209], v[44:47]
	v_mfma_f32_16x16x32_bf16 v[40:43], v[164:167], v[206:209], v[40:43]
	v_mfma_f32_16x16x32_bf16 v[28:31], v[156:159], v[214:217], v[28:31]
	v_mfma_f32_16x16x32_bf16 v[24:27], v[164:167], v[214:217], v[24:27]
	v_lshl_add_u64 v[200:201], v[228:229], 0, s[26:27]
	s_mov_b32 m0, s63
	s_nop 0
	global_load_lds_dwordx4 v[200:201], off
	v_mfma_f32_16x16x32_bf16 v[12:15], v[156:159], v[222:225], v[12:15]
	v_mfma_f32_16x16x32_bf16 v[8:11], v[164:167], v[222:225], v[8:11]
	s_setprio 0
	s_setprio 1
	v_mfma_f32_16x16x32_bf16 v[52:55], v[168:171], v[188:191], v[52:55]
	v_mfma_f32_16x16x32_bf16 v[48:51], v[180:183], v[188:191], v[48:51]
	v_mfma_f32_16x16x32_bf16 v[36:39], v[168:171], v[196:199], v[36:39]
	v_mfma_f32_16x16x32_bf16 v[32:35], v[180:183], v[196:199], v[32:35]
	v_mfma_f32_16x16x32_bf16 v[20:23], v[168:171], v[210:213], v[20:23]
	v_mfma_f32_16x16x32_bf16 v[16:19], v[180:183], v[210:213], v[16:19]
	v_mfma_f32_16x16x32_bf16 v[4:7], v[168:171], v[218:221], v[4:7]
	v_mfma_f32_16x16x32_bf16 v[0:3], v[180:183], v[218:221], v[0:3]
	v_mfma_f32_16x16x32_bf16 v[52:55], v[172:175], v[192:195], v[52:55]
	v_mfma_f32_16x16x32_bf16 v[48:51], v[184:187], v[192:195], v[48:51]
	v_mfma_f32_16x16x32_bf16 v[36:39], v[172:175], v[206:209], v[36:39]
	v_mfma_f32_16x16x32_bf16 v[32:35], v[184:187], v[206:209], v[32:35]
	v_mfma_f32_16x16x32_bf16 v[20:23], v[172:175], v[214:217], v[20:23]
	v_mfma_f32_16x16x32_bf16 v[16:19], v[184:187], v[214:217], v[16:19]
	v_lshl_add_u64 v[200:201], v[230:231], 0, s[26:27]
	s_mov_b32 m0, s64
	s_nop 0
	global_load_lds_dwordx4 v[200:201], off
	v_mfma_f32_16x16x32_bf16 v[4:7], v[172:175], v[222:225], v[4:7]
	v_mfma_f32_16x16x32_bf16 v[0:3], v[184:187], v[222:225], v[0:3]
	s_setprio 0
	s_barrier
	s_add_i32 s81, s81, 2
	s_add_u32 s52, s52, 0x100
	s_addc_u32 s53, s53, 0
	s_add_u32 s79, s79, 0x100
	s_addc_u32 s80, s80, 0
	s_cmp_gt_u32 s81, 13
	s_cbranch_scc0 .LBB0_1681
	s_and_b64 vcc, exec, s[28:29]
	s_cbranch_vccz .LBB0_1684
.LBB0_1684:
	v_lshl_add_u32 v156, s0, 8, v145
	v_ashrrev_i32_e32 v157, 31, v156
	v_lshl_add_u64 v[146:147], v[156:157], 3, s[12:13]
	global_load_dwordx2 v[148:149], v[146:147], off
	v_lshlrev_b64 v[162:163], 10, v[156:157]
	v_lshl_or_b32 v158, s1, 8, v151
	v_ashrrev_i32_e32 v159, 31, v158
	v_or_b32_e32 v160, 16, v156
	v_lshlrev_b64 v[158:159], 1, v[158:159]
	v_ashrrev_i32_e32 v161, 31, v160
	s_waitcnt vmcnt(0)
	v_ffbh_u32_e32 v157, v149
	v_min_u32_e32 v157, 32, v157
	v_lshlrev_b64 v[148:149], v157, v[148:149]
	v_min_u32_e32 v148, 1, v148
	v_or_b32_e32 v148, v149, v148
	v_cvt_f32_u32_e32 v148, v148
	v_sub_u32_e32 v149, 32, v157
	v_ldexp_f32 v148, v148, v149
	v_mul_f32_e32 v148, 0x2f800000, v148
	v_fmamk_f32 v148, v148, 0x3a800000, v155
	v_rsq_f32_e32 v164, v148
	v_lshl_add_u64 v[148:149], s[20:21], 0, v[162:163]
	v_lshl_add_u64 v[148:149], v[148:149], 0, v[158:159]
	v_lshl_add_u64 v[162:163], v[160:161], 3, s[12:13]
	v_pk_mul_f32 v[126:127], v[126:127], v[164:165] op_sel_hi:[1,0]
	v_pk_mul_f32 v[124:125], v[124:125], v[164:165] op_sel_hi:[1,0]
	v_pk_mul_f32 v[122:123], v[122:123], v[164:165] op_sel_hi:[1,0]
	v_pk_mul_f32 v[120:121], v[120:121], v[164:165] op_sel_hi:[1,0]
	v_pk_mul_f32 v[118:119], v[118:119], v[164:165] op_sel_hi:[1,0]
	v_pk_mul_f32 v[116:117], v[116:117], v[164:165] op_sel_hi:[1,0]
	v_pk_mul_f32 v[166:167], v[114:115], v[164:165] op_sel_hi:[1,0]
	v_pk_mul_f32 v[164:165], v[112:113], v[164:165] op_sel_hi:[1,0]
	v_cvt_pk_bf16_f32 v112, v124, v125
	v_cvt_pk_bf16_f32 v113, v126, v127
	v_cvt_pk_bf16_f32 v114, v120, v121
	v_cvt_pk_bf16_f32 v115, v122, v123
	v_cvt_pk_bf16_f32 v116, v116, v117
	v_cvt_pk_bf16_f32 v117, v118, v119
	v_cvt_pk_bf16_f32 v118, v164, v165
	v_cvt_pk_bf16_f32 v119, v166, v167
	global_store_dwordx4 v[148:149], v[112:115], off
	global_store_dwordx4 v[148:149], v[116:119], off offset:256
	global_load_dwordx2 v[112:113], v[162:163], off
	v_or_b32_e32 v114, 32, v156
	s_waitcnt vmcnt(0)
	v_ffbh_u32_e32 v115, v113
	v_min_u32_e32 v116, 32, v115
	v_lshlrev_b64 v[112:113], v116, v[112:113]
	v_min_u32_e32 v112, 1, v112
	v_or_b32_e32 v112, v113, v112
	v_cvt_f32_u32_e32 v117, v112
	v_sub_u32_e32 v116, 32, v116
	v_lshlrev_b64 v[112:113], 10, v[160:161]
	v_lshl_add_u64 v[112:113], s[20:21], 0, v[112:113]
	v_ldexp_f32 v116, v117, v116
	v_mul_f32_e32 v116, 0x2f800000, v116
	v_fmamk_f32 v116, v116, 0x3a800000, v155
	v_rsq_f32_e32 v116, v116
	v_ashrrev_i32_e32 v115, 31, v114
	v_lshl_add_u64 v[112:113], v[112:113], 0, v[158:159]
	v_lshl_add_u64 v[118:119], v[114:115], 3, s[12:13]
	v_pk_mul_f32 v[110:111], v[110:111], v[116:117] op_sel_hi:[1,0]
	v_pk_mul_f32 v[108:109], v[108:109], v[116:117] op_sel_hi:[1,0]
	v_pk_mul_f32 v[106:107], v[106:107], v[116:117] op_sel_hi:[1,0]
	v_pk_mul_f32 v[104:105], v[104:105], v[116:117] op_sel_hi:[1,0]
	v_pk_mul_f32 v[102:103], v[102:103], v[116:117] op_sel_hi:[1,0]
	v_pk_mul_f32 v[100:101], v[100:101], v[116:117] op_sel_hi:[1,0]
	v_pk_mul_f32 v[120:121], v[98:99], v[116:117] op_sel_hi:[1,0]
	v_pk_mul_f32 v[116:117], v[96:97], v[116:117] op_sel_hi:[1,0]
	v_cvt_pk_bf16_f32 v96, v108, v109
	v_cvt_pk_bf16_f32 v97, v110, v111
	v_cvt_pk_bf16_f32 v98, v104, v105
	v_cvt_pk_bf16_f32 v99, v106, v107
	v_cvt_pk_bf16_f32 v100, v100, v101
	v_cvt_pk_bf16_f32 v101, v102, v103
	v_cvt_pk_bf16_f32 v102, v116, v117
	v_cvt_pk_bf16_f32 v103, v120, v121
	global_store_dwordx4 v[112:113], v[96:99], off
	global_store_dwordx4 v[112:113], v[100:103], off offset:256
	global_load_dwordx2 v[96:97], v[118:119], off
	v_or_b32_e32 v98, 48, v156
	s_waitcnt vmcnt(0)
; __device__ __forceinline__ unsigned cvtpk(float lo, float hi) { f32x2v_ v = {lo, hi}; bf16x2v_ b = __builtin_convertvector(v, bf16x2v_); return __builtin_bit_cast(unsigned, b); }
;     __device__ __forceinline__ void operator()(const f32x4 (&acc)[2][2][4][2], const Unit& u, int wr, int wc, int fr, int fq) const {
;         const int row0 = u.pm * BM + wr * 64 + fr, col0 = u.pn * BM + wc * 32 + 8 * fq;
; #pragma unroll
;         for (int ai = 0; ai < 2; ++ai)
; #pragma unroll
;             for (int m = 0; m < 4; ++m) { const int row = row0 + ai * HALF + m * 16; const float rs = ss ? row_rs(ss, row) : 1.0f;
; #pragma unroll
;                 for (int bj = 0; bj < 2; ++bj) { const f32x4 v0 = acc[ai][bj][m][0] * rs, v1 = acc[ai][bj][m][1] * rs;
;                     u32x4 w; w.x = cvtpk(v0[0], v0[1]); w.y = cvtpk(v0[2], v0[3]); w.z = cvtpk(v1[0], v1[1]); w.w = cvtpk(v1[2], v1[3]);
;                     *(u32x4*)(O + (size_t)row * ldc + col0 + bj * HALF) = w; } }
	v_ffbh_u32_e32 v99, v97
	v_min_u32_e32 v100, 32, v99
	v_lshlrev_b64 v[96:97], v100, v[96:97]
	v_min_u32_e32 v96, 1, v96
	v_or_b32_e32 v96, v97, v96
	v_cvt_f32_u32_e32 v101, v96
	v_sub_u32_e32 v100, 32, v100
	v_lshlrev_b64 v[96:97], 10, v[114:115]
	v_lshl_add_u64 v[96:97], s[20:21], 0, v[96:97]
	v_ldexp_f32 v100, v101, v100
	v_mul_f32_e32 v100, 0x2f800000, v100
	v_fmamk_f32 v100, v100, 0x3a800000, v155
	v_rsq_f32_e32 v100, v100
	v_ashrrev_i32_e32 v99, 31, v98
	v_lshl_add_u64 v[96:97], v[96:97], 0, v[158:159]
	v_lshl_add_u64 v[102:103], v[98:99], 3, s[12:13]
	v_pk_mul_f32 v[94:95], v[94:95], v[100:101] op_sel_hi:[1,0]
	v_pk_mul_f32 v[92:93], v[92:93], v[100:101] op_sel_hi:[1,0]
	v_pk_mul_f32 v[90:91], v[90:91], v[100:101] op_sel_hi:[1,0]
	v_pk_mul_f32 v[88:89], v[88:89], v[100:101] op_sel_hi:[1,0]
	v_pk_mul_f32 v[86:87], v[86:87], v[100:101] op_sel_hi:[1,0]
	v_pk_mul_f32 v[84:85], v[84:85], v[100:101] op_sel_hi:[1,0]
	v_pk_mul_f32 v[104:105], v[82:83], v[100:101] op_sel_hi:[1,0]
	v_pk_mul_f32 v[100:101], v[80:81], v[100:101] op_sel_hi:[1,0]
	v_cvt_pk_bf16_f32 v80, v92, v93
	v_cvt_pk_bf16_f32 v81, v94, v95
	v_cvt_pk_bf16_f32 v82, v88, v89
	v_cvt_pk_bf16_f32 v83, v90, v91
	v_cvt_pk_bf16_f32 v84, v84, v85
	v_cvt_pk_bf16_f32 v85, v86, v87
	v_cvt_pk_bf16_f32 v86, v100, v101
	v_cvt_pk_bf16_f32 v87, v104, v105
	global_store_dwordx4 v[96:97], v[80:83], off
	global_store_dwordx4 v[96:97], v[84:87], off offset:256
	global_load_dwordx2 v[80:81], v[102:103], off
	s_waitcnt vmcnt(0)
	v_ffbh_u32_e32 v82, v81
	v_min_u32_e32 v82, 32, v82
	v_lshlrev_b64 v[80:81], v82, v[80:81]
	v_min_u32_e32 v80, 1, v80
	v_or_b32_e32 v80, v81, v80
	v_cvt_f32_u32_e32 v80, v80
	v_sub_u32_e32 v81, 32, v82
	v_lshlrev_b64 v[82:83], 10, v[98:99]
	v_lshl_add_u64 v[82:83], s[20:21], 0, v[82:83]
	v_ldexp_f32 v80, v80, v81
	v_mul_f32_e32 v80, 0x2f800000, v80
	v_fmamk_f32 v80, v80, 0x3a800000, v155
	v_rsq_f32_e32 v80, v80
	v_lshl_add_u64 v[82:83], v[82:83], 0, v[158:159]
	v_pk_mul_f32 v[78:79], v[78:79], v[80:81] op_sel_hi:[1,0]
	v_pk_mul_f32 v[76:77], v[76:77], v[80:81] op_sel_hi:[1,0]
	v_pk_mul_f32 v[74:75], v[74:75], v[80:81] op_sel_hi:[1,0]
	v_pk_mul_f32 v[72:73], v[72:73], v[80:81] op_sel_hi:[1,0]
	v_pk_mul_f32 v[70:71], v[70:71], v[80:81] op_sel_hi:[1,0]
	v_pk_mul_f32 v[68:69], v[68:69], v[80:81] op_sel_hi:[1,0]
	v_pk_mul_f32 v[84:85], v[66:67], v[80:81] op_sel_hi:[1,0]
	v_pk_mul_f32 v[80:81], v[64:65], v[80:81] op_sel_hi:[1,0]
	v_cvt_pk_bf16_f32 v64, v76, v77
	v_cvt_pk_bf16_f32 v65, v78, v79
	v_cvt_pk_bf16_f32 v66, v72, v73
	v_cvt_pk_bf16_f32 v67, v74, v75
	v_cvt_pk_bf16_f32 v68, v68, v69
	v_cvt_pk_bf16_f32 v69, v70, v71
	v_cvt_pk_bf16_f32 v70, v80, v81
	v_cvt_pk_bf16_f32 v71, v84, v85
	global_store_dwordx4 v[82:83], v[64:67], off
	global_store_dwordx4 v[82:83], v[68:71], off offset:256
	global_load_dwordx2 v[64:65], v[146:147], off offset:1024
	s_waitcnt vmcnt(0)
	v_ffbh_u32_e32 v66, v65
	v_min_u32_e32 v66, 32, v66
	v_lshlrev_b64 v[64:65], v66, v[64:65]
	v_min_u32_e32 v64, 1, v64
	v_or_b32_e32 v64, v65, v64
	v_cvt_f32_u32_e32 v67, v64
	v_sub_u32_e32 v66, 32, v66
	v_add_co_u32_e32 v68, vcc, s67, v148
	v_ldexp_f32 v66, v67, v66
	v_mul_f32_e32 v66, 0x2f800000, v66
	v_fmamk_f32 v66, v66, 0x3a800000, v155
	v_rsq_f32_e32 v66, v66
	v_addc_co_u32_e32 v69, vcc, 0, v149, vcc
	v_lshl_add_u64 v[64:65], v[148:149], 0, s[36:37]
	v_pk_mul_f32 v[62:63], v[62:63], v[66:67] op_sel_hi:[1,0]
	v_pk_mul_f32 v[60:61], v[60:61], v[66:67] op_sel_hi:[1,0]
	v_pk_mul_f32 v[58:59], v[58:59], v[66:67] op_sel_hi:[1,0]
	v_pk_mul_f32 v[56:57], v[56:57], v[66:67] op_sel_hi:[1,0]
	v_pk_mul_f32 v[54:55], v[54:55], v[66:67] op_sel_hi:[1,0]
	v_pk_mul_f32 v[52:53], v[52:53], v[66:67] op_sel_hi:[1,0]
	v_pk_mul_f32 v[70:71], v[50:51], v[66:67] op_sel_hi:[1,0]
	v_pk_mul_f32 v[66:67], v[48:49], v[66:67] op_sel_hi:[1,0]
	v_cvt_pk_bf16_f32 v48, v60, v61
	v_cvt_pk_bf16_f32 v49, v62, v63
	v_cvt_pk_bf16_f32 v50, v56, v57
	v_cvt_pk_bf16_f32 v51, v58, v59
	v_cvt_pk_bf16_f32 v52, v52, v53
	v_cvt_pk_bf16_f32 v53, v54, v55
	v_cvt_pk_bf16_f32 v54, v66, v67
	v_cvt_pk_bf16_f32 v55, v70, v71
	global_store_dwordx4 v[68:69], v[48:51], off
	global_store_dwordx4 v[64:65], v[52:55], off offset:256
	global_load_dwordx2 v[48:49], v[146:147], off offset:1152
	s_waitcnt vmcnt(0)
; __device__ __forceinline__ unsigned cvtpk(float lo, float hi) { f32x2v_ v = {lo, hi}; bf16x2v_ b = __builtin_convertvector(v, bf16x2v_); return __builtin_bit_cast(unsigned, b); }
; #define PG8_BAR __builtin_amdgcn_s_barrier()
;     __device__ __forceinline__ void operator()(const f32x4 (&acc)[2][2][4][2], const Unit& u, int wr, int wc, int fr, int fq) const {
;         const int row0 = u.pm * BM + wr * 64 + fr, col0 = u.pn * BM + wc * 32 + 8 * fq;
; #pragma unroll
;         for (int ai = 0; ai < 2; ++ai)
; #pragma unroll
;             for (int m = 0; m < 4; ++m) { const int row = row0 + ai * HALF + m * 16; const float rs = ss ? row_rs(ss, row) : 1.0f;
; #pragma unroll
;                 for (int bj = 0; bj < 2; ++bj) { const f32x4 v0 = acc[ai][bj][m][0] * rs, v1 = acc[ai][bj][m][1] * rs;
;                     u32x4 w; w.x = cvtpk(v0[0], v0[1]); w.y = cvtpk(v0[2], v0[3]); w.z = cvtpk(v1[0], v1[1]); w.w = cvtpk(v1[2], v1[3]);
;                     *(u32x4*)(O + (size_t)row * ldc + col0 + bj * HALF) = w; } }
; template <class Epi, class Sched, bool ALIGN_EPI = false, bool SP2 = false>
; __device__ __forceinline__ void gemm_phase(PG8_LAS unsigned char* lds, const Gemm g, const Sched& S, const Epi& E) {
;     ...
;         if constexpr (ALIGN_EPI) { if (wr == 0) PG8_BAR; }
;         if constexpr (!Epi::AFTER_DRAIN) { E(acc, cur, wr, wc, fr, fq); S.done(cur); }
;         if (!has_next) break;
; #pragma unroll
;         for (int a = 0; a < 2; ++a)
; #pragma unroll
;             for (int b = 0; b < 2; ++b)
; #pragma unroll
;                 for (int m = 0; m < 4; ++m)
; #pragma unroll
;                     for (int n = 0; n < 2; ++n) acc[a][b][m][n] = (f32x4){0.f, 0.f, 0.f, 0.f};
;         cur = nxt; cA = nA; cB = nB; ++ui;
;         if constexpr (ALIGN_EPI) { if (wr == 1) PG8_BAR; }
	v_ffbh_u32_e32 v50, v49
	v_min_u32_e32 v50, 32, v50
	v_lshlrev_b64 v[48:49], v50, v[48:49]
	v_min_u32_e32 v48, 1, v48
	v_or_b32_e32 v48, v49, v48
	v_cvt_f32_u32_e32 v51, v48
	v_sub_u32_e32 v50, 32, v50
	v_add_co_u32_e32 v52, vcc, s74, v148
	v_ldexp_f32 v50, v51, v50
	v_mul_f32_e32 v50, 0x2f800000, v50
	v_fmamk_f32 v50, v50, 0x3a800000, v155
	v_rsq_f32_e32 v50, v50
	v_addc_co_u32_e32 v53, vcc, 0, v149, vcc
	v_lshl_add_u64 v[48:49], v[148:149], 0, s[38:39]
	v_pk_mul_f32 v[46:47], v[46:47], v[50:51] op_sel_hi:[1,0]
	v_pk_mul_f32 v[44:45], v[44:45], v[50:51] op_sel_hi:[1,0]
	v_pk_mul_f32 v[42:43], v[42:43], v[50:51] op_sel_hi:[1,0]
	v_pk_mul_f32 v[40:41], v[40:41], v[50:51] op_sel_hi:[1,0]
	v_pk_mul_f32 v[38:39], v[38:39], v[50:51] op_sel_hi:[1,0]
	v_pk_mul_f32 v[36:37], v[36:37], v[50:51] op_sel_hi:[1,0]
	v_pk_mul_f32 v[54:55], v[34:35], v[50:51] op_sel_hi:[1,0]
	v_pk_mul_f32 v[50:51], v[32:33], v[50:51] op_sel_hi:[1,0]
	v_cvt_pk_bf16_f32 v32, v44, v45
	v_cvt_pk_bf16_f32 v33, v46, v47
	v_cvt_pk_bf16_f32 v34, v40, v41
	v_cvt_pk_bf16_f32 v35, v42, v43
	v_cvt_pk_bf16_f32 v36, v36, v37
	v_cvt_pk_bf16_f32 v37, v38, v39
	v_cvt_pk_bf16_f32 v38, v50, v51
	v_cvt_pk_bf16_f32 v39, v54, v55
	global_store_dwordx4 v[52:53], v[32:35], off
	global_store_dwordx4 v[48:49], v[36:39], off offset:256
	global_load_dwordx2 v[32:33], v[146:147], off offset:1280
	s_waitcnt vmcnt(0)
	v_ffbh_u32_e32 v34, v33
	v_min_u32_e32 v34, 32, v34
	v_lshlrev_b64 v[32:33], v34, v[32:33]
	v_min_u32_e32 v32, 1, v32
	v_or_b32_e32 v32, v33, v32
	v_cvt_f32_u32_e32 v35, v32
	v_sub_u32_e32 v34, 32, v34
	v_add_co_u32_e32 v36, vcc, s75, v148
	v_ldexp_f32 v34, v35, v34
	v_mul_f32_e32 v34, 0x2f800000, v34
	v_fmamk_f32 v34, v34, 0x3a800000, v155
	v_rsq_f32_e32 v34, v34
	v_addc_co_u32_e32 v37, vcc, 0, v149, vcc
	v_lshl_add_u64 v[32:33], v[148:149], 0, s[40:41]
	v_pk_mul_f32 v[30:31], v[30:31], v[34:35] op_sel_hi:[1,0]
	v_pk_mul_f32 v[28:29], v[28:29], v[34:35] op_sel_hi:[1,0]
	v_pk_mul_f32 v[26:27], v[26:27], v[34:35] op_sel_hi:[1,0]
	v_pk_mul_f32 v[24:25], v[24:25], v[34:35] op_sel_hi:[1,0]
	v_pk_mul_f32 v[22:23], v[22:23], v[34:35] op_sel_hi:[1,0]
	v_pk_mul_f32 v[20:21], v[20:21], v[34:35] op_sel_hi:[1,0]
	v_pk_mul_f32 v[38:39], v[18:19], v[34:35] op_sel_hi:[1,0]
	v_pk_mul_f32 v[34:35], v[16:17], v[34:35] op_sel_hi:[1,0]
	v_cvt_pk_bf16_f32 v16, v28, v29
	v_cvt_pk_bf16_f32 v17, v30, v31
	v_cvt_pk_bf16_f32 v18, v24, v25
	v_cvt_pk_bf16_f32 v19, v26, v27
	v_cvt_pk_bf16_f32 v20, v20, v21
	v_cvt_pk_bf16_f32 v21, v22, v23
	v_cvt_pk_bf16_f32 v22, v34, v35
	v_cvt_pk_bf16_f32 v23, v38, v39
	global_store_dwordx4 v[36:37], v[16:19], off
	global_store_dwordx4 v[32:33], v[20:23], off offset:256
	global_load_dwordx2 v[16:17], v[146:147], off offset:1408
	s_andn2_b64 vcc, exec, s[4:5]
	v_add_co_u32_e64 v20, s[0:1], s76, v148
	s_waitcnt vmcnt(0)
	v_ffbh_u32_e32 v18, v17
	v_min_u32_e32 v18, 32, v18
	v_lshlrev_b64 v[16:17], v18, v[16:17]
	v_min_u32_e32 v16, 1, v16
	v_or_b32_e32 v16, v17, v16
	v_cvt_f32_u32_e32 v19, v16
	v_sub_u32_e32 v18, 32, v18
	v_addc_co_u32_e64 v21, s[0:1], 0, v149, s[0:1]
	v_ldexp_f32 v18, v19, v18
	v_mul_f32_e32 v18, 0x2f800000, v18
	v_fmamk_f32 v18, v18, 0x3a800000, v155
	v_rsq_f32_e32 v18, v18
	s_mov_b64 s[0:1], -1
	v_lshl_add_u64 v[16:17], v[148:149], 0, s[42:43]
	v_pk_mul_f32 v[14:15], v[14:15], v[18:19] op_sel_hi:[1,0]
	v_pk_mul_f32 v[12:13], v[12:13], v[18:19] op_sel_hi:[1,0]
	v_pk_mul_f32 v[10:11], v[10:11], v[18:19] op_sel_hi:[1,0]
	v_pk_mul_f32 v[8:9], v[8:9], v[18:19] op_sel_hi:[1,0]
	v_pk_mul_f32 v[6:7], v[6:7], v[18:19] op_sel_hi:[1,0]
	v_pk_mul_f32 v[4:5], v[4:5], v[18:19] op_sel_hi:[1,0]
	v_pk_mul_f32 v[22:23], v[2:3], v[18:19] op_sel_hi:[1,0]
	v_pk_mul_f32 v[18:19], v[0:1], v[18:19] op_sel_hi:[1,0]
	v_cvt_pk_bf16_f32 v0, v12, v13
	v_cvt_pk_bf16_f32 v1, v14, v15
	v_cvt_pk_bf16_f32 v2, v8, v9
	v_cvt_pk_bf16_f32 v3, v10, v11
	v_cvt_pk_bf16_f32 v4, v4, v5
	v_cvt_pk_bf16_f32 v5, v6, v7
	v_cvt_pk_bf16_f32 v6, v18, v19
	v_cvt_pk_bf16_f32 v7, v22, v23
	global_store_dwordx4 v[20:21], v[0:3], off
	global_store_dwordx4 v[16:17], v[4:7], off offset:256
	s_cmp_eq_u64 s[28:29], 0
	s_cbranch_scc1 .Lxpost_10
	s_barrier
.Lxpost_10:
	s_cbranch_vccnz .LBB0_1673
	s_andn2_b64 vcc, exec, s[10:11]
	s_cbranch_vccnz .LBB0_1672
	s_barrier
	s_branch .LBB0_1672

; #define PG8_STAGE(bufoff, gbase, voff) do { _Pragma("unroll") for (int _i = 0; _i < 2; ++_i) \
;         __builtin_amdgcn_global_load_lds((const unsigned*)((const char*)(gbase) + (voff)[_i]), (PG8_LAS unsigned*)(lds + (bufoff) + ldsw + _i * 8192), 16, 0, 0); } while (0)
; #define PG8_LDA(dst, b, h) do { _Pragma("unroll") for (int m = 0; m < 4; ++m) _Pragma("unroll") for (int k = 0; k < 2; ++k) dst[m][k] = *(const PG8_LAS bf16x8*)(lds + PG8_SA(b, h) + aoff + m * 2048 + k * 1024); } while (0)
; #define PG8_LDB(dst, b, h) do { _Pragma("unroll") for (int n = 0; n < 2; ++n) _Pragma("unroll") for (int k = 0; k < 2; ++k) dst[n][k] = *(const PG8_LAS bf16x8*)(lds + PG8_SB(b, h) + boff + n * 2048 + k * 1024); } while (0)
; #define PG8_WAIT_V(n) asm volatile("s_waitcnt vmcnt(" #n ")" ::: "memory")
; #define PG8_WAIT_L(n) asm volatile("s_waitcnt lgkmcnt(" #n ")" ::: "memory")
; #define PG8_BAR __builtin_amdgcn_s_barrier()
; #define PG8_SCHED __builtin_amdgcn_sched_barrier(0)
; template <class Epi, class Sched, bool ALIGN_EPI = false, bool SP2 = false>
; __device__ __forceinline__ void gemm_phase(PG8_LAS unsigned char* lds, const Gemm g, const Sched& S, const Epi& E) {
;     ...
;         const bool has_next = S.next(ui + 1, nxt);
;         const char* nA = has_next ? (const char*)g.A + (size_t)nxt.pm * tstep : cA; const char* nB = has_next ? (const char*)g.Bt + (size_t)nxt.pn * tstep : cB;
;         for (int t = 0; t < nt; t += 2) {
;             const bool last = (t == nt - 2);
;             const char* a1 = cA + (size_t)(t + 1) * kstep;
;             const char* a2 = last ? nA : cA + (size_t)(t + 2) * kstep; const char* b2 = last ? nB : cB + (size_t)(t + 2) * kstep;
;             const char* a3 = a2 + kstep; const char* b3 = b2 + kstep;
;             if (last && has_next) S.a_ready(nxt);
;             if constexpr (SP2) {
;             PG8_LDB(B0, 0, 0); PG8_LDB(B1, 0, 1); PG8_SCHED; PG8_LDA(At, 0, 0); PG8_STAGE(PG8_SA(1, 1), a1 + hstep, voffA);
;             PG8_WAIT_V(8); PG8_WAIT_L(0); PG8_BAR; PG8_MMA(0, 0, At, B0); PG8_MMA(0, 1, At, B1); PG8_BAR; PG8_SCHED;
;             PG8_LDA(At, 0, 1); PG8_STAGE(PG8_SB(0, 0), b2, voffB); PG8_STAGE(PG8_SB(0, 1), b2 + hstep, voffB); PG8_STAGE(PG8_SA(0, 0), a2, voffA);
;             PG8_WAIT_V(8); PG8_WAIT_L(0); PG8_BAR; PG8_MMA(1, 0, At, B0); PG8_MMA(1, 1, At, B1); PG8_BAR; PG8_SCHED;
.LBB0_1815:
	s_ashr_i32 s29, s28, 31
	s_lshl_b64 s[36:37], s[28:29], 18
	s_add_u32 s36, s92, s36
	s_addc_u32 s37, s93, s37
	s_and_b64 s[38:39], s[6:7], exec
	s_cselect_b32 s29, s37, s45
	s_cselect_b32 s41, s36, s44
	s_ashr_i32 s27, s26, 31
	s_lshl_b64 s[38:39], s[26:27], 18
	s_add_u32 s38, s3, s38
	s_addc_u32 s39, s14, s39
	s_and_b64 s[48:49], s[6:7], exec
	s_cselect_b32 s27, s39, s47
	s_cselect_b32 s58, s38, s46
	s_add_u32 s44, s44, 0x20080
	s_addc_u32 s45, s45, 0
	s_add_u32 s59, s46, 0x100
	s_addc_u32 s60, s47, 0
	s_mov_b32 s61, -2
	s_waitcnt lgkmcnt(0)
	ds_read_b128 v[144:147], v151
	ds_read_b128 v[156:159], v151 offset:1024
	ds_read_b128 v[160:163], v151 offset:2048
	ds_read_b128 v[164:167], v151 offset:3072
	ds_read_b128 v[168:171], v152
	ds_read_b128 v[172:175], v152 offset:1024
	ds_read_b128 v[176:179], v152 offset:2048
	ds_read_b128 v[180:183], v152 offset:3072
	s_add_u32 s46, s44, 0xfffe0080
	s_addc_u32 s47, s45, -1
	s_cmp_eq_u32 s61, 4
	s_cselect_b32 s49, s29, s47
	s_cselect_b32 s48, s41, s46
	s_cselect_b32 s47, s27, s60
	s_cselect_b32 s46, s58, s59
	v_lshl_add_u64 v[218:219], s[44:45], 0, v[136:137]
	s_add_i32 m0, s33, 0xc000
	ds_read_b128 v[184:187], v153
	ds_read_b128 v[188:191], v153 offset:1024
	ds_read_b128 v[192:195], v153 offset:2048
	ds_read_b128 v[196:199], v153 offset:3072
	ds_read_b128 v[200:203], v153 offset:4096
	ds_read_b128 v[206:209], v153 offset:5120
	ds_read_b128 v[210:213], v153 offset:6144
	ds_read_b128 v[214:217], v153 offset:7168
	global_load_lds_dwordx4 v[218:219], off
	v_lshl_add_u64 v[218:219], s[44:45], 0, v[138:139]
	s_add_i32 m0, s33, 0xe000
	s_nop 0
	global_load_lds_dwordx4 v[218:219], off
	s_waitcnt vmcnt(8)
	s_waitcnt lgkmcnt(0)
	s_barrier
	s_setprio 1
	s_waitcnt lgkmcnt(0)
	v_mfma_f32_16x16x32_bf16 v[124:127], v[144:147], v[184:187], 0
	v_mfma_f32_16x16x32_bf16 v[120:123], v[160:163], v[184:187], 0
	v_mfma_f32_16x16x32_bf16 v[108:111], v[144:147], v[192:195], 0
	v_mfma_f32_16x16x32_bf16 v[104:107], v[160:163], v[192:195], 0
	v_mfma_f32_16x16x32_bf16 v[92:95], v[144:147], v[200:203], 0
	v_mfma_f32_16x16x32_bf16 v[88:91], v[160:163], v[200:203], 0
	v_mfma_f32_16x16x32_bf16 v[76:79], v[144:147], v[210:213], 0
	v_mfma_f32_16x16x32_bf16 v[72:75], v[160:163], v[210:213], 0
	v_mfma_f32_16x16x32_bf16 v[124:127], v[156:159], v[188:191], v[124:127]
	v_mfma_f32_16x16x32_bf16 v[120:123], v[164:167], v[188:191], v[120:123]
	v_mfma_f32_16x16x32_bf16 v[108:111], v[156:159], v[196:199], v[108:111]
	v_mfma_f32_16x16x32_bf16 v[104:107], v[164:167], v[196:199], v[104:107]
	v_mfma_f32_16x16x32_bf16 v[92:95], v[156:159], v[206:209], v[92:95]
	v_mfma_f32_16x16x32_bf16 v[88:91], v[164:167], v[206:209], v[88:91]
	v_mfma_f32_16x16x32_bf16 v[76:79], v[156:159], v[214:217], v[76:79]
	v_mfma_f32_16x16x32_bf16 v[72:75], v[164:167], v[214:217], v[72:75]
	s_setprio 0
	s_setprio 1
	v_mfma_f32_16x16x32_bf16 v[116:119], v[168:171], v[184:187], 0
	v_mfma_f32_16x16x32_bf16 v[112:115], v[176:179], v[184:187], 0
	v_mfma_f32_16x16x32_bf16 v[100:103], v[168:171], v[192:195], 0
	v_mfma_f32_16x16x32_bf16 v[96:99], v[176:179], v[192:195], 0
	v_mfma_f32_16x16x32_bf16 v[84:87], v[168:171], v[200:203], 0
	v_mfma_f32_16x16x32_bf16 v[80:83], v[176:179], v[200:203], 0
	v_mfma_f32_16x16x32_bf16 v[68:71], v[168:171], v[210:213], 0
	v_mfma_f32_16x16x32_bf16 v[64:67], v[176:179], v[210:213], 0
	v_mfma_f32_16x16x32_bf16 v[116:119], v[172:175], v[188:191], v[116:119]
	v_mfma_f32_16x16x32_bf16 v[112:115], v[180:183], v[188:191], v[112:115]
	v_mfma_f32_16x16x32_bf16 v[100:103], v[172:175], v[196:199], v[100:103]
	v_mfma_f32_16x16x32_bf16 v[96:99], v[180:183], v[196:199], v[96:99]
	v_mfma_f32_16x16x32_bf16 v[84:87], v[172:175], v[206:209], v[84:87]
	v_mfma_f32_16x16x32_bf16 v[80:83], v[180:183], v[206:209], v[80:83]
	v_mfma_f32_16x16x32_bf16 v[68:71], v[172:175], v[214:217], v[68:71]
	v_mfma_f32_16x16x32_bf16 v[64:67], v[180:183], v[214:217], v[64:67]
	s_setprio 0
	s_barrier
	s_add_i32 s62, s54, s15
	v_lshl_add_u64 v[218:219], s[46:47], 0, v[130:131]
	s_mov_b32 m0, s62
	ds_read_b128 v[184:187], v153 offset:16384
	ds_read_b128 v[188:191], v153 offset:17408
	ds_read_b128 v[192:195], v153 offset:18432
	ds_read_b128 v[196:199], v153 offset:19456
	ds_read_b128 v[200:203], v153 offset:20480
	ds_read_b128 v[206:209], v153 offset:21504
	ds_read_b128 v[210:213], v153 offset:22528
	ds_read_b128 v[214:217], v153 offset:23552
	global_load_lds_dwordx4 v[218:219], off
	s_add_i32 m0, s62, 0x2000
	s_add_u32 s62, s46, 0x20000
	v_lshl_add_u64 v[220:221], s[46:47], 0, v[134:135]
	s_addc_u32 s63, s47, 0
	s_add_i32 s64, s55, s15
	global_load_lds_dwordx4 v[220:221], off
	v_lshl_add_u64 v[222:223], s[62:63], 0, v[130:131]
	s_mov_b32 m0, s64
	global_load_lds_dwordx4 v[222:223], off
	v_lshl_add_u64 v[222:223], s[62:63], 0, v[134:135]
	s_add_i32 m0, s64, 0x2000
	s_nop 0
	global_load_lds_dwordx4 v[222:223], off
	s_waitcnt vmcnt(6)
	s_waitcnt lgkmcnt(0)
	s_barrier
; #define PG8_STAGE(bufoff, gbase, voff) do { _Pragma("unroll") for (int _i = 0; _i < 2; ++_i) \
;         __builtin_amdgcn_global_load_lds((const unsigned*)((const char*)(gbase) + (voff)[_i]), (PG8_LAS unsigned*)(lds + (bufoff) + ldsw + _i * 8192), 16, 0, 0); } while (0)
; #define PG8_LDA(dst, b, h) do { _Pragma("unroll") for (int m = 0; m < 4; ++m) _Pragma("unroll") for (int k = 0; k < 2; ++k) dst[m][k] = *(const PG8_LAS bf16x8*)(lds + PG8_SA(b, h) + aoff + m * 2048 + k * 1024); } while (0)
; #define PG8_LDB(dst, b, h) do { _Pragma("unroll") for (int n = 0; n < 2; ++n) _Pragma("unroll") for (int k = 0; k < 2; ++k) dst[n][k] = *(const PG8_LAS bf16x8*)(lds + PG8_SB(b, h) + boff + n * 2048 + k * 1024); } while (0)
; #define PG8_MMA(ai, bj, At, Bt) do { __builtin_amdgcn_s_setprio(1); _Pragma("unroll") for (int m = 0; m < 4; ++m) _Pragma("unroll") for (int n = 0; n < 2; ++n) _Pragma("unroll") for (int k = 0; k < 2; ++k) \
;         acc[ai][bj][m][n] = __builtin_amdgcn_mfma_f32_16x16x32_bf16(Bt[n][k], At[m][k], acc[ai][bj][m][n], 0, 0, 0); __builtin_amdgcn_s_setprio(0); } while (0)
; #define PG8_WAIT_V(n) asm volatile("s_waitcnt vmcnt(" #n ")" ::: "memory")
; #define PG8_WAIT_L(n) asm volatile("s_waitcnt lgkmcnt(" #n ")" ::: "memory")
; #define PG8_BAR __builtin_amdgcn_s_barrier()
; #define PG8_SCHED __builtin_amdgcn_sched_barrier(0)
; template <class Epi, class Sched, bool ALIGN_EPI = false, bool SP2 = false>
; __device__ __forceinline__ void gemm_phase(PG8_LAS unsigned char* lds, const Gemm g, const Sched& S, const Epi& E) {
;     ...
;             PG8_LDA(At, 0, 1); PG8_STAGE(PG8_SB(0, 0), b2, voffB); PG8_STAGE(PG8_SB(0, 1), b2 + hstep, voffB); PG8_STAGE(PG8_SA(0, 0), a2, voffA);
;             PG8_WAIT_V(8); PG8_WAIT_L(0); PG8_BAR; PG8_MMA(1, 0, At, B0); PG8_MMA(1, 1, At, B1); PG8_BAR; PG8_SCHED;
;             PG8_LDB(B0, 1, 0); PG8_LDB(B1, 1, 1); PG8_SCHED; PG8_LDA(At, 1, 0); PG8_STAGE(PG8_SA(0, 1), a2 + hstep, voffA);
;             PG8_WAIT_V(8); PG8_WAIT_L(0); PG8_BAR; PG8_MMA(0, 0, At, B0); PG8_MMA(0, 1, At, B1); PG8_BAR; PG8_SCHED;
;             PG8_LDA(At, 1, 1); PG8_STAGE(PG8_SB(1, 0), b3, voffB); PG8_STAGE(PG8_SB(1, 1), b3 + hstep, voffB); PG8_STAGE(PG8_SA(1, 0), a3, voffA);
;             PG8_WAIT_V(8); PG8_WAIT_L(0); PG8_BAR; PG8_MMA(1, 0, At, B0); PG8_MMA(1, 1, At, B1); PG8_BAR; PG8_SCHED;
	s_setprio 1
	s_waitcnt lgkmcnt(0)
	v_mfma_f32_16x16x32_bf16 v[60:63], v[144:147], v[184:187], 0
	v_mfma_f32_16x16x32_bf16 v[56:59], v[160:163], v[184:187], 0
	v_mfma_f32_16x16x32_bf16 v[44:47], v[144:147], v[192:195], 0
	v_mfma_f32_16x16x32_bf16 v[40:43], v[160:163], v[192:195], 0
	v_mfma_f32_16x16x32_bf16 v[28:31], v[144:147], v[200:203], 0
	v_mfma_f32_16x16x32_bf16 v[24:27], v[160:163], v[200:203], 0
	v_mfma_f32_16x16x32_bf16 v[12:15], v[144:147], v[210:213], 0
	v_mfma_f32_16x16x32_bf16 v[8:11], v[160:163], v[210:213], 0
	v_mfma_f32_16x16x32_bf16 v[60:63], v[156:159], v[188:191], v[60:63]
	v_mfma_f32_16x16x32_bf16 v[56:59], v[164:167], v[188:191], v[56:59]
	v_mfma_f32_16x16x32_bf16 v[44:47], v[156:159], v[196:199], v[44:47]
	v_mfma_f32_16x16x32_bf16 v[40:43], v[164:167], v[196:199], v[40:43]
	v_mfma_f32_16x16x32_bf16 v[28:31], v[156:159], v[206:209], v[28:31]
	v_mfma_f32_16x16x32_bf16 v[24:27], v[164:167], v[206:209], v[24:27]
	v_lshl_add_u64 v[222:223], s[48:49], 0, v[128:129]
	s_mov_b32 m0, s33
	s_nop 0
	global_load_lds_dwordx4 v[222:223], off
	v_mfma_f32_16x16x32_bf16 v[12:15], v[156:159], v[214:217], v[12:15]
	v_mfma_f32_16x16x32_bf16 v[8:11], v[164:167], v[214:217], v[8:11]
	s_setprio 0
	s_setprio 1
	v_mfma_f32_16x16x32_bf16 v[52:55], v[168:171], v[184:187], 0
	v_mfma_f32_16x16x32_bf16 v[48:51], v[176:179], v[184:187], 0
	v_mfma_f32_16x16x32_bf16 v[36:39], v[168:171], v[192:195], 0
	v_mfma_f32_16x16x32_bf16 v[32:35], v[176:179], v[192:195], 0
	v_mfma_f32_16x16x32_bf16 v[20:23], v[168:171], v[200:203], 0
	v_mfma_f32_16x16x32_bf16 v[16:19], v[176:179], v[200:203], 0
	v_mfma_f32_16x16x32_bf16 v[4:7], v[168:171], v[210:213], 0
	v_mfma_f32_16x16x32_bf16 v[0:3], v[176:179], v[210:213], 0
	v_mfma_f32_16x16x32_bf16 v[52:55], v[172:175], v[188:191], v[52:55]
	v_mfma_f32_16x16x32_bf16 v[48:51], v[180:183], v[188:191], v[48:51]
	v_mfma_f32_16x16x32_bf16 v[36:39], v[172:175], v[196:199], v[36:39]
	v_mfma_f32_16x16x32_bf16 v[32:35], v[180:183], v[196:199], v[32:35]
	v_mfma_f32_16x16x32_bf16 v[20:23], v[172:175], v[206:209], v[20:23]
	v_mfma_f32_16x16x32_bf16 v[16:19], v[180:183], v[206:209], v[16:19]
	v_lshl_add_u64 v[224:225], s[48:49], 0, v[132:133]
	s_mov_b32 m0, s34
	s_nop 0
	global_load_lds_dwordx4 v[224:225], off
	v_mfma_f32_16x16x32_bf16 v[4:7], v[172:175], v[214:217], v[4:7]
	v_mfma_f32_16x16x32_bf16 v[0:3], v[180:183], v[214:217], v[0:3]
	s_setprio 0
	s_barrier
	s_add_i32 s62, 0, 0x18000
	v_add_u32_e32 v155, s62, v149
	s_add_i32 s63, 0, 0x1c000
	ds_read_b128 v[144:147], v155
	ds_read_b128 v[156:159], v155 offset:1024
	ds_read_b128 v[160:163], v155 offset:2048
	ds_read_b128 v[164:167], v155 offset:3072
	v_add_u32_e32 v155, s63, v149
	ds_read_b128 v[168:171], v155
	ds_read_b128 v[172:175], v155 offset:1024
	ds_read_b128 v[176:179], v155 offset:2048
	ds_read_b128 v[180:183], v155 offset:3072
	s_add_u32 s48, s48, 0x20000
	s_addc_u32 s49, s49, 0
	s_mov_b32 m0, s43
	v_lshl_add_u64 v[226:227], s[48:49], 0, v[128:129]
	ds_read_b128 v[184:187], v153 offset:32768
	ds_read_b128 v[188:191], v153 offset:33792
	ds_read_b128 v[192:195], v153 offset:34816
	ds_read_b128 v[196:199], v153 offset:35840
	ds_read_b128 v[200:203], v153 offset:36864
	ds_read_b128 v[206:209], v153 offset:37888
	ds_read_b128 v[210:213], v153 offset:38912
	ds_read_b128 v[214:217], v153 offset:39936
	global_load_lds_dwordx4 v[226:227], off
	v_lshl_add_u64 v[226:227], s[48:49], 0, v[132:133]
	s_mov_b32 m0, s50
	s_nop 0
	global_load_lds_dwordx4 v[226:227], off
	s_waitcnt vmcnt(8)
	s_waitcnt lgkmcnt(0)
	s_barrier
	s_setprio 1
	s_waitcnt lgkmcnt(0)
	v_mfma_f32_16x16x32_bf16 v[124:127], v[144:147], v[184:187], v[124:127]
	v_mfma_f32_16x16x32_bf16 v[120:123], v[160:163], v[184:187], v[120:123]
	v_mfma_f32_16x16x32_bf16 v[108:111], v[144:147], v[192:195], v[108:111]
	v_mfma_f32_16x16x32_bf16 v[104:107], v[160:163], v[192:195], v[104:107]
	v_mfma_f32_16x16x32_bf16 v[92:95], v[144:147], v[200:203], v[92:95]
	v_mfma_f32_16x16x32_bf16 v[88:91], v[160:163], v[200:203], v[88:91]
	v_mfma_f32_16x16x32_bf16 v[76:79], v[144:147], v[210:213], v[76:79]
	v_mfma_f32_16x16x32_bf16 v[72:75], v[160:163], v[210:213], v[72:75]
	v_mfma_f32_16x16x32_bf16 v[124:127], v[156:159], v[188:191], v[124:127]
	v_mfma_f32_16x16x32_bf16 v[120:123], v[164:167], v[188:191], v[120:123]
	v_mfma_f32_16x16x32_bf16 v[108:111], v[156:159], v[196:199], v[108:111]
	v_mfma_f32_16x16x32_bf16 v[104:107], v[164:167], v[196:199], v[104:107]
	v_mfma_f32_16x16x32_bf16 v[92:95], v[156:159], v[206:209], v[92:95]
	v_mfma_f32_16x16x32_bf16 v[88:91], v[164:167], v[206:209], v[88:91]
	v_mfma_f32_16x16x32_bf16 v[76:79], v[156:159], v[214:217], v[76:79]
	v_mfma_f32_16x16x32_bf16 v[72:75], v[164:167], v[214:217], v[72:75]
	s_setprio 0
	s_setprio 1
	v_mfma_f32_16x16x32_bf16 v[116:119], v[168:171], v[184:187], v[116:119]
	v_mfma_f32_16x16x32_bf16 v[112:115], v[176:179], v[184:187], v[112:115]
	v_mfma_f32_16x16x32_bf16 v[100:103], v[168:171], v[192:195], v[100:103]
	v_mfma_f32_16x16x32_bf16 v[96:99], v[176:179], v[192:195], v[96:99]
	v_mfma_f32_16x16x32_bf16 v[84:87], v[168:171], v[200:203], v[84:87]
	v_mfma_f32_16x16x32_bf16 v[80:83], v[176:179], v[200:203], v[80:83]
	v_mfma_f32_16x16x32_bf16 v[68:71], v[168:171], v[210:213], v[68:71]
	v_mfma_f32_16x16x32_bf16 v[64:67], v[176:179], v[210:213], v[64:67]
	v_mfma_f32_16x16x32_bf16 v[116:119], v[172:175], v[188:191], v[116:119]
	v_mfma_f32_16x16x32_bf16 v[112:115], v[180:183], v[188:191], v[112:115]
	v_mfma_f32_16x16x32_bf16 v[100:103], v[172:175], v[196:199], v[100:103]
	v_mfma_f32_16x16x32_bf16 v[96:99], v[180:183], v[196:199], v[96:99]
	v_mfma_f32_16x16x32_bf16 v[84:87], v[172:175], v[206:209], v[84:87]
	v_mfma_f32_16x16x32_bf16 v[80:83], v[180:183], v[206:209], v[80:83]
	v_mfma_f32_16x16x32_bf16 v[68:71], v[172:175], v[214:217], v[68:71]
	v_mfma_f32_16x16x32_bf16 v[64:67], v[180:183], v[214:217], v[64:67]
	s_setprio 0
	s_barrier
; #define PG8_STAGE(bufoff, gbase, voff) do { _Pragma("unroll") for (int _i = 0; _i < 2; ++_i) \
;         __builtin_amdgcn_global_load_lds((const unsigned*)((const char*)(gbase) + (voff)[_i]), (PG8_LAS unsigned*)(lds + (bufoff) + ldsw + _i * 8192), 16, 0, 0); } while (0)
; #define PG8_LDA(dst, b, h) do { _Pragma("unroll") for (int m = 0; m < 4; ++m) _Pragma("unroll") for (int k = 0; k < 2; ++k) dst[m][k] = *(const PG8_LAS bf16x8*)(lds + PG8_SA(b, h) + aoff + m * 2048 + k * 1024); } while (0)
; #define PG8_LDB(dst, b, h) do { _Pragma("unroll") for (int n = 0; n < 2; ++n) _Pragma("unroll") for (int k = 0; k < 2; ++k) dst[n][k] = *(const PG8_LAS bf16x8*)(lds + PG8_SB(b, h) + boff + n * 2048 + k * 1024); } while (0)
; #define PG8_MMA(ai, bj, At, Bt) do { __builtin_amdgcn_s_setprio(1); _Pragma("unroll") for (int m = 0; m < 4; ++m) _Pragma("unroll") for (int n = 0; n < 2; ++n) _Pragma("unroll") for (int k = 0; k < 2; ++k) \
;         acc[ai][bj][m][n] = __builtin_amdgcn_mfma_f32_16x16x32_bf16(Bt[n][k], At[m][k], acc[ai][bj][m][n], 0, 0, 0); __builtin_amdgcn_s_setprio(0); } while (0)
; #define PG8_WAIT_V(n) asm volatile("s_waitcnt vmcnt(" #n ")" ::: "memory")
; template <class Epi, class Sched, bool ALIGN_EPI = false, bool SP2 = false>
; __device__ __forceinline__ void gemm_phase(PG8_LAS unsigned char* lds, const Gemm g, const Sched& S, const Epi& E) {
;     ...
;             PG8_LDB(B0, 0, 0); PG8_LDB(B1, 0, 1); PG8_SCHED; PG8_LDA(At, 0, 0); PG8_STAGE(PG8_SA(1, 1), a1 + hstep, voffA);
;             PG8_WAIT_V(8); PG8_WAIT_L(0); PG8_BAR; PG8_MMA(0, 0, At, B0); PG8_MMA(0, 1, At, B1); PG8_BAR; PG8_SCHED;
;             PG8_LDA(At, 0, 1); PG8_STAGE(PG8_SB(0, 0), b2, voffB); PG8_STAGE(PG8_SB(0, 1), b2 + hstep, voffB); PG8_STAGE(PG8_SA(0, 0), a2, voffA);
;             PG8_WAIT_V(8); PG8_WAIT_L(0); PG8_BAR; PG8_MMA(1, 0, At, B0); PG8_MMA(1, 1, At, B1); PG8_BAR; PG8_SCHED;
;             PG8_LDB(B0, 1, 0); PG8_LDB(B1, 1, 1); PG8_SCHED; PG8_LDA(At, 1, 0); PG8_STAGE(PG8_SA(0, 1), a2 + hstep, voffA);
;             PG8_WAIT_V(8); PG8_WAIT_L(0); PG8_BAR; PG8_MMA(0, 0, At, B0); PG8_MMA(0, 1, At, B1); PG8_BAR; PG8_SCHED;
;             PG8_LDA(At, 1, 1); PG8_STAGE(PG8_SB(1, 0), b3, voffB); PG8_STAGE(PG8_SB(1, 1), b3 + hstep, voffB); PG8_STAGE(PG8_SA(1, 0), a3, voffA);
;             PG8_WAIT_V(8); PG8_WAIT_L(0); PG8_BAR; PG8_MMA(1, 0, At, B0); PG8_MMA(1, 1, At, B1); PG8_BAR; PG8_SCHED;
	s_add_i32 s48, s62, s15
	v_lshl_add_u64 v[218:219], v[218:219], 0, s[12:13]
	s_mov_b32 m0, s48
	ds_read_b128 v[184:187], v153 offset:49152
	ds_read_b128 v[188:191], v153 offset:50176
	ds_read_b128 v[192:195], v153 offset:51200
	ds_read_b128 v[196:199], v153 offset:52224
	ds_read_b128 v[200:203], v153 offset:53248
	ds_read_b128 v[206:209], v153 offset:54272
	ds_read_b128 v[210:213], v153 offset:55296
	ds_read_b128 v[214:217], v153 offset:56320
	global_load_lds_dwordx4 v[218:219], off
	s_add_i32 m0, s48, 0x2000
	s_add_u32 s46, s46, 0x20080
	v_lshl_add_u64 v[218:219], v[220:221], 0, s[12:13]
	s_addc_u32 s47, s47, 0
	s_add_i32 s48, s63, s15
	global_load_lds_dwordx4 v[218:219], off
	v_lshl_add_u64 v[218:219], s[46:47], 0, v[130:131]
	s_mov_b32 m0, s48
	s_nop 0
	global_load_lds_dwordx4 v[218:219], off
	v_lshl_add_u64 v[218:219], s[46:47], 0, v[134:135]
	s_add_i32 m0, s48, 0x2000
	s_nop 0
	global_load_lds_dwordx4 v[218:219], off
	s_waitcnt vmcnt(6)
	s_waitcnt lgkmcnt(0)
	s_barrier
	s_setprio 1
	s_waitcnt lgkmcnt(0)
	v_mfma_f32_16x16x32_bf16 v[60:63], v[144:147], v[184:187], v[60:63]
	v_mfma_f32_16x16x32_bf16 v[56:59], v[160:163], v[184:187], v[56:59]
	v_mfma_f32_16x16x32_bf16 v[44:47], v[144:147], v[192:195], v[44:47]
	v_mfma_f32_16x16x32_bf16 v[40:43], v[160:163], v[192:195], v[40:43]
	v_mfma_f32_16x16x32_bf16 v[28:31], v[144:147], v[200:203], v[28:31]
	v_mfma_f32_16x16x32_bf16 v[24:27], v[160:163], v[200:203], v[24:27]
	v_mfma_f32_16x16x32_bf16 v[12:15], v[144:147], v[210:213], v[12:15]
	v_mfma_f32_16x16x32_bf16 v[8:11], v[160:163], v[210:213], v[8:11]
	v_mfma_f32_16x16x32_bf16 v[60:63], v[156:159], v[188:191], v[60:63]
	v_mfma_f32_16x16x32_bf16 v[56:59], v[164:167], v[188:191], v[56:59]
	v_mfma_f32_16x16x32_bf16 v[44:47], v[156:159], v[196:199], v[44:47]
	v_mfma_f32_16x16x32_bf16 v[40:43], v[164:167], v[196:199], v[40:43]
	v_mfma_f32_16x16x32_bf16 v[28:31], v[156:159], v[206:209], v[28:31]
	v_mfma_f32_16x16x32_bf16 v[24:27], v[164:167], v[206:209], v[24:27]
	v_lshl_add_u64 v[218:219], v[222:223], 0, s[12:13]
	s_mov_b32 m0, s52
	s_nop 0
	global_load_lds_dwordx4 v[218:219], off
	v_mfma_f32_16x16x32_bf16 v[12:15], v[156:159], v[214:217], v[12:15]
	v_mfma_f32_16x16x32_bf16 v[8:11], v[164:167], v[214:217], v[8:11]
	s_setprio 0
	s_setprio 1
	v_mfma_f32_16x16x32_bf16 v[52:55], v[168:171], v[184:187], v[52:55]
	v_mfma_f32_16x16x32_bf16 v[48:51], v[176:179], v[184:187], v[48:51]
	v_mfma_f32_16x16x32_bf16 v[36:39], v[168:171], v[192:195], v[36:39]
	v_mfma_f32_16x16x32_bf16 v[32:35], v[176:179], v[192:195], v[32:35]
	v_mfma_f32_16x16x32_bf16 v[20:23], v[168:171], v[200:203], v[20:23]
	v_mfma_f32_16x16x32_bf16 v[16:19], v[176:179], v[200:203], v[16:19]
	v_mfma_f32_16x16x32_bf16 v[4:7], v[168:171], v[210:213], v[4:7]
	v_mfma_f32_16x16x32_bf16 v[0:3], v[176:179], v[210:213], v[0:3]
	v_mfma_f32_16x16x32_bf16 v[52:55], v[172:175], v[188:191], v[52:55]
	v_mfma_f32_16x16x32_bf16 v[48:51], v[180:183], v[188:191], v[48:51]
	v_mfma_f32_16x16x32_bf16 v[36:39], v[172:175], v[196:199], v[36:39]
	v_mfma_f32_16x16x32_bf16 v[32:35], v[180:183], v[196:199], v[32:35]
	v_mfma_f32_16x16x32_bf16 v[20:23], v[172:175], v[206:209], v[20:23]
	v_mfma_f32_16x16x32_bf16 v[16:19], v[180:183], v[206:209], v[16:19]
	v_lshl_add_u64 v[218:219], v[224:225], 0, s[12:13]
	s_mov_b32 m0, s53
	s_nop 0
	global_load_lds_dwordx4 v[218:219], off
	v_mfma_f32_16x16x32_bf16 v[4:7], v[172:175], v[214:217], v[4:7]
	v_mfma_f32_16x16x32_bf16 v[0:3], v[180:183], v[214:217], v[0:3]
	s_setprio 0
	s_barrier
	s_add_i32 s61, s61, 2
	s_add_u32 s44, s44, 0x100
	s_addc_u32 s45, s45, 0
	s_add_u32 s59, s59, 0x100
	s_addc_u32 s60, s60, 0
.LBB0_1816:
	ds_read_b128 v[144:147], v151
	ds_read_b128 v[156:159], v151 offset:1024
	ds_read_b128 v[160:163], v151 offset:2048
	ds_read_b128 v[164:167], v151 offset:3072
	ds_read_b128 v[168:171], v152
	ds_read_b128 v[172:175], v152 offset:1024
	ds_read_b128 v[176:179], v152 offset:2048
	ds_read_b128 v[180:183], v152 offset:3072
	s_add_u32 s46, s44, 0xfffe0080
	s_addc_u32 s47, s45, -1
	s_cmp_eq_u32 s61, 4
	s_cselect_b32 s49, s29, s47
	s_cselect_b32 s48, s41, s46
	s_cselect_b32 s47, s27, s60
	s_cselect_b32 s46, s58, s59
	v_lshl_add_u64 v[218:219], s[44:45], 0, v[136:137]
	s_add_i32 m0, s33, 0xc000
	ds_read_b128 v[184:187], v153
	ds_read_b128 v[188:191], v153 offset:1024
	ds_read_b128 v[192:195], v153 offset:2048
	ds_read_b128 v[196:199], v153 offset:3072
	ds_read_b128 v[200:203], v153 offset:4096
	ds_read_b128 v[206:209], v153 offset:5120
	ds_read_b128 v[210:213], v153 offset:6144
	ds_read_b128 v[214:217], v153 offset:7168
	global_load_lds_dwordx4 v[218:219], off
	v_lshl_add_u64 v[218:219], s[44:45], 0, v[138:139]
	s_add_i32 m0, s33, 0xe000
	s_nop 0
	global_load_lds_dwordx4 v[218:219], off
	s_waitcnt vmcnt(8)
	s_waitcnt lgkmcnt(0)
	s_barrier
; #define PG8_STAGE(bufoff, gbase, voff) do { _Pragma("unroll") for (int _i = 0; _i < 2; ++_i) \
;         __builtin_amdgcn_global_load_lds((const unsigned*)((const char*)(gbase) + (voff)[_i]), (PG8_LAS unsigned*)(lds + (bufoff) + ldsw + _i * 8192), 16, 0, 0); } while (0)
; #define PG8_LDA(dst, b, h) do { _Pragma("unroll") for (int m = 0; m < 4; ++m) _Pragma("unroll") for (int k = 0; k < 2; ++k) dst[m][k] = *(const PG8_LAS bf16x8*)(lds + PG8_SA(b, h) + aoff + m * 2048 + k * 1024); } while (0)
; #define PG8_LDB(dst, b, h) do { _Pragma("unroll") for (int n = 0; n < 2; ++n) _Pragma("unroll") for (int k = 0; k < 2; ++k) dst[n][k] = *(const PG8_LAS bf16x8*)(lds + PG8_SB(b, h) + boff + n * 2048 + k * 1024); } while (0)
; #define PG8_MMA(ai, bj, At, Bt) do { __builtin_amdgcn_s_setprio(1); _Pragma("unroll") for (int m = 0; m < 4; ++m) _Pragma("unroll") for (int n = 0; n < 2; ++n) _Pragma("unroll") for (int k = 0; k < 2; ++k) \
;         acc[ai][bj][m][n] = __builtin_amdgcn_mfma_f32_16x16x32_bf16(Bt[n][k], At[m][k], acc[ai][bj][m][n], 0, 0, 0); __builtin_amdgcn_s_setprio(0); } while (0)
; #define PG8_WAIT_V(n) asm volatile("s_waitcnt vmcnt(" #n ")" ::: "memory")
; #define PG8_WAIT_L(n) asm volatile("s_waitcnt lgkmcnt(" #n ")" ::: "memory")
; #define PG8_BAR __builtin_amdgcn_s_barrier()
; #define PG8_SCHED __builtin_amdgcn_sched_barrier(0)
; template <class Epi, class Sched, bool ALIGN_EPI = false, bool SP2 = false>
; __device__ __forceinline__ void gemm_phase(PG8_LAS unsigned char* lds, const Gemm g, const Sched& S, const Epi& E) {
;     ...
;             PG8_LDB(B0, 0, 0); PG8_LDB(B1, 0, 1); PG8_SCHED; PG8_LDA(At, 0, 0); PG8_STAGE(PG8_SA(1, 1), a1 + hstep, voffA);
;             PG8_WAIT_V(8); PG8_WAIT_L(0); PG8_BAR; PG8_MMA(0, 0, At, B0); PG8_MMA(0, 1, At, B1); PG8_BAR; PG8_SCHED;
;             PG8_LDA(At, 0, 1); PG8_STAGE(PG8_SB(0, 0), b2, voffB); PG8_STAGE(PG8_SB(0, 1), b2 + hstep, voffB); PG8_STAGE(PG8_SA(0, 0), a2, voffA);
;             PG8_WAIT_V(8); PG8_WAIT_L(0); PG8_BAR; PG8_MMA(1, 0, At, B0); PG8_MMA(1, 1, At, B1); PG8_BAR; PG8_SCHED;
;             PG8_LDB(B0, 1, 0); PG8_LDB(B1, 1, 1); PG8_SCHED; PG8_LDA(At, 1, 0); PG8_STAGE(PG8_SA(0, 1), a2 + hstep, voffA);
;             PG8_WAIT_V(8); PG8_WAIT_L(0); PG8_BAR; PG8_MMA(0, 0, At, B0); PG8_MMA(0, 1, At, B1); PG8_BAR; PG8_SCHED;
	s_setprio 1
	s_waitcnt lgkmcnt(0)
	v_mfma_f32_16x16x32_bf16 v[124:127], v[144:147], v[184:187], v[124:127]
	v_mfma_f32_16x16x32_bf16 v[120:123], v[160:163], v[184:187], v[120:123]
	v_mfma_f32_16x16x32_bf16 v[108:111], v[144:147], v[192:195], v[108:111]
	v_mfma_f32_16x16x32_bf16 v[104:107], v[160:163], v[192:195], v[104:107]
	v_mfma_f32_16x16x32_bf16 v[92:95], v[144:147], v[200:203], v[92:95]
	v_mfma_f32_16x16x32_bf16 v[88:91], v[160:163], v[200:203], v[88:91]
	v_mfma_f32_16x16x32_bf16 v[76:79], v[144:147], v[210:213], v[76:79]
	v_mfma_f32_16x16x32_bf16 v[72:75], v[160:163], v[210:213], v[72:75]
	v_mfma_f32_16x16x32_bf16 v[124:127], v[156:159], v[188:191], v[124:127]
	v_mfma_f32_16x16x32_bf16 v[120:123], v[164:167], v[188:191], v[120:123]
	v_mfma_f32_16x16x32_bf16 v[108:111], v[156:159], v[196:199], v[108:111]
	v_mfma_f32_16x16x32_bf16 v[104:107], v[164:167], v[196:199], v[104:107]
	v_mfma_f32_16x16x32_bf16 v[92:95], v[156:159], v[206:209], v[92:95]
	v_mfma_f32_16x16x32_bf16 v[88:91], v[164:167], v[206:209], v[88:91]
	v_mfma_f32_16x16x32_bf16 v[76:79], v[156:159], v[214:217], v[76:79]
	v_mfma_f32_16x16x32_bf16 v[72:75], v[164:167], v[214:217], v[72:75]
	s_setprio 0
	s_setprio 1
	v_mfma_f32_16x16x32_bf16 v[116:119], v[168:171], v[184:187], v[116:119]
	v_mfma_f32_16x16x32_bf16 v[112:115], v[176:179], v[184:187], v[112:115]
	v_mfma_f32_16x16x32_bf16 v[100:103], v[168:171], v[192:195], v[100:103]
	v_mfma_f32_16x16x32_bf16 v[96:99], v[176:179], v[192:195], v[96:99]
	v_mfma_f32_16x16x32_bf16 v[84:87], v[168:171], v[200:203], v[84:87]
	v_mfma_f32_16x16x32_bf16 v[80:83], v[176:179], v[200:203], v[80:83]
	v_mfma_f32_16x16x32_bf16 v[68:71], v[168:171], v[210:213], v[68:71]
	v_mfma_f32_16x16x32_bf16 v[64:67], v[176:179], v[210:213], v[64:67]
	v_mfma_f32_16x16x32_bf16 v[116:119], v[172:175], v[188:191], v[116:119]
	v_mfma_f32_16x16x32_bf16 v[112:115], v[180:183], v[188:191], v[112:115]
	v_mfma_f32_16x16x32_bf16 v[100:103], v[172:175], v[196:199], v[100:103]
	v_mfma_f32_16x16x32_bf16 v[96:99], v[180:183], v[196:199], v[96:99]
	v_mfma_f32_16x16x32_bf16 v[84:87], v[172:175], v[206:209], v[84:87]
	v_mfma_f32_16x16x32_bf16 v[80:83], v[180:183], v[206:209], v[80:83]
	v_mfma_f32_16x16x32_bf16 v[68:71], v[172:175], v[214:217], v[68:71]
	v_mfma_f32_16x16x32_bf16 v[64:67], v[180:183], v[214:217], v[64:67]
	s_setprio 0
	s_barrier
	s_add_i32 s62, s54, s15
	v_lshl_add_u64 v[218:219], s[46:47], 0, v[130:131]
	s_mov_b32 m0, s62
	ds_read_b128 v[184:187], v153 offset:16384
	ds_read_b128 v[188:191], v153 offset:17408
	ds_read_b128 v[192:195], v153 offset:18432
	ds_read_b128 v[196:199], v153 offset:19456
	ds_read_b128 v[200:203], v153 offset:20480
	ds_read_b128 v[206:209], v153 offset:21504
	ds_read_b128 v[210:213], v153 offset:22528
	ds_read_b128 v[214:217], v153 offset:23552
	global_load_lds_dwordx4 v[218:219], off
	s_add_i32 m0, s62, 0x2000
	s_add_u32 s62, s46, 0x20000
	v_lshl_add_u64 v[220:221], s[46:47], 0, v[134:135]
	s_addc_u32 s63, s47, 0
	s_add_i32 s64, s55, s15
	global_load_lds_dwordx4 v[220:221], off
	v_lshl_add_u64 v[222:223], s[62:63], 0, v[130:131]
	s_mov_b32 m0, s64
	global_load_lds_dwordx4 v[222:223], off
	v_lshl_add_u64 v[222:223], s[62:63], 0, v[134:135]
	s_add_i32 m0, s64, 0x2000
	s_nop 0
	global_load_lds_dwordx4 v[222:223], off
	s_waitcnt vmcnt(6)
	s_waitcnt lgkmcnt(0)
	s_barrier
	s_setprio 1
	s_waitcnt lgkmcnt(0)
	v_mfma_f32_16x16x32_bf16 v[60:63], v[144:147], v[184:187], v[60:63]
	v_mfma_f32_16x16x32_bf16 v[56:59], v[160:163], v[184:187], v[56:59]
	v_mfma_f32_16x16x32_bf16 v[44:47], v[144:147], v[192:195], v[44:47]
	v_mfma_f32_16x16x32_bf16 v[40:43], v[160:163], v[192:195], v[40:43]
	v_mfma_f32_16x16x32_bf16 v[28:31], v[144:147], v[200:203], v[28:31]
	v_mfma_f32_16x16x32_bf16 v[24:27], v[160:163], v[200:203], v[24:27]
	v_mfma_f32_16x16x32_bf16 v[12:15], v[144:147], v[210:213], v[12:15]
	v_mfma_f32_16x16x32_bf16 v[8:11], v[160:163], v[210:213], v[8:11]
	v_mfma_f32_16x16x32_bf16 v[60:63], v[156:159], v[188:191], v[60:63]
	v_mfma_f32_16x16x32_bf16 v[56:59], v[164:167], v[188:191], v[56:59]
	v_mfma_f32_16x16x32_bf16 v[44:47], v[156:159], v[196:199], v[44:47]
	v_mfma_f32_16x16x32_bf16 v[40:43], v[164:167], v[196:199], v[40:43]
	v_mfma_f32_16x16x32_bf16 v[28:31], v[156:159], v[206:209], v[28:31]
	v_mfma_f32_16x16x32_bf16 v[24:27], v[164:167], v[206:209], v[24:27]
	v_lshl_add_u64 v[222:223], s[48:49], 0, v[128:129]
	s_mov_b32 m0, s33
	s_nop 0
	global_load_lds_dwordx4 v[222:223], off
	v_mfma_f32_16x16x32_bf16 v[12:15], v[156:159], v[214:217], v[12:15]
	v_mfma_f32_16x16x32_bf16 v[8:11], v[164:167], v[214:217], v[8:11]
	s_setprio 0
	s_setprio 1
	v_mfma_f32_16x16x32_bf16 v[52:55], v[168:171], v[184:187], v[52:55]
	v_mfma_f32_16x16x32_bf16 v[48:51], v[176:179], v[184:187], v[48:51]
	v_mfma_f32_16x16x32_bf16 v[36:39], v[168:171], v[192:195], v[36:39]
	v_mfma_f32_16x16x32_bf16 v[32:35], v[176:179], v[192:195], v[32:35]
	v_mfma_f32_16x16x32_bf16 v[20:23], v[168:171], v[200:203], v[20:23]
	v_mfma_f32_16x16x32_bf16 v[16:19], v[176:179], v[200:203], v[16:19]
	v_mfma_f32_16x16x32_bf16 v[4:7], v[168:171], v[210:213], v[4:7]
	v_mfma_f32_16x16x32_bf16 v[0:3], v[176:179], v[210:213], v[0:3]
	v_mfma_f32_16x16x32_bf16 v[52:55], v[172:175], v[188:191], v[52:55]
	v_mfma_f32_16x16x32_bf16 v[48:51], v[180:183], v[188:191], v[48:51]
	v_mfma_f32_16x16x32_bf16 v[36:39], v[172:175], v[196:199], v[36:39]
	v_mfma_f32_16x16x32_bf16 v[32:35], v[180:183], v[196:199], v[32:35]
	v_mfma_f32_16x16x32_bf16 v[20:23], v[172:175], v[206:209], v[20:23]
	v_mfma_f32_16x16x32_bf16 v[16:19], v[180:183], v[206:209], v[16:19]
	v_lshl_add_u64 v[224:225], s[48:49], 0, v[132:133]
	s_mov_b32 m0, s34
	s_nop 0
	global_load_lds_dwordx4 v[224:225], off
	v_mfma_f32_16x16x32_bf16 v[4:7], v[172:175], v[214:217], v[4:7]
	v_mfma_f32_16x16x32_bf16 v[0:3], v[180:183], v[214:217], v[0:3]
	s_setprio 0
	s_barrier
; #define PG8_STAGE(bufoff, gbase, voff) do { _Pragma("unroll") for (int _i = 0; _i < 2; ++_i) \
;         __builtin_amdgcn_global_load_lds((const unsigned*)((const char*)(gbase) + (voff)[_i]), (PG8_LAS unsigned*)(lds + (bufoff) + ldsw + _i * 8192), 16, 0, 0); } while (0)
; #define PG8_LDA(dst, b, h) do { _Pragma("unroll") for (int m = 0; m < 4; ++m) _Pragma("unroll") for (int k = 0; k < 2; ++k) dst[m][k] = *(const PG8_LAS bf16x8*)(lds + PG8_SA(b, h) + aoff + m * 2048 + k * 1024); } while (0)
; #define PG8_LDB(dst, b, h) do { _Pragma("unroll") for (int n = 0; n < 2; ++n) _Pragma("unroll") for (int k = 0; k < 2; ++k) dst[n][k] = *(const PG8_LAS bf16x8*)(lds + PG8_SB(b, h) + boff + n * 2048 + k * 1024); } while (0)
; #define PG8_MMA(ai, bj, At, Bt) do { __builtin_amdgcn_s_setprio(1); _Pragma("unroll") for (int m = 0; m < 4; ++m) _Pragma("unroll") for (int n = 0; n < 2; ++n) _Pragma("unroll") for (int k = 0; k < 2; ++k) \
;         acc[ai][bj][m][n] = __builtin_amdgcn_mfma_f32_16x16x32_bf16(Bt[n][k], At[m][k], acc[ai][bj][m][n], 0, 0, 0); __builtin_amdgcn_s_setprio(0); } while (0)
; #define PG8_WAIT_V(n) asm volatile("s_waitcnt vmcnt(" #n ")" ::: "memory")
; #define PG8_WAIT_L(n) asm volatile("s_waitcnt lgkmcnt(" #n ")" ::: "memory")
; #define PG8_BAR __builtin_amdgcn_s_barrier()
; #define PG8_SCHED __builtin_amdgcn_sched_barrier(0)
; template <class Epi, class Sched, bool ALIGN_EPI = false, bool SP2 = false>
; __device__ __forceinline__ void gemm_phase(PG8_LAS unsigned char* lds, const Gemm g, const Sched& S, const Epi& E) {
;     ...
;             PG8_LDB(B0, 1, 0); PG8_LDB(B1, 1, 1); PG8_SCHED; PG8_LDA(At, 1, 0); PG8_STAGE(PG8_SA(0, 1), a2 + hstep, voffA);
;             PG8_WAIT_V(8); PG8_WAIT_L(0); PG8_BAR; PG8_MMA(0, 0, At, B0); PG8_MMA(0, 1, At, B1); PG8_BAR; PG8_SCHED;
;             PG8_LDA(At, 1, 1); PG8_STAGE(PG8_SB(1, 0), b3, voffB); PG8_STAGE(PG8_SB(1, 1), b3 + hstep, voffB); PG8_STAGE(PG8_SA(1, 0), a3, voffA);
;             PG8_WAIT_V(8); PG8_WAIT_L(0); PG8_BAR; PG8_MMA(1, 0, At, B0); PG8_MMA(1, 1, At, B1); PG8_BAR; PG8_SCHED;
	s_add_i32 s62, 0, 0x18000
	v_add_u32_e32 v155, s62, v149
	s_add_i32 s63, 0, 0x1c000
	ds_read_b128 v[144:147], v155
	ds_read_b128 v[156:159], v155 offset:1024
	ds_read_b128 v[160:163], v155 offset:2048
	ds_read_b128 v[164:167], v155 offset:3072
	v_add_u32_e32 v155, s63, v149
	ds_read_b128 v[168:171], v155
	ds_read_b128 v[172:175], v155 offset:1024
	ds_read_b128 v[176:179], v155 offset:2048
	ds_read_b128 v[180:183], v155 offset:3072
	s_add_u32 s48, s48, 0x20000
	s_addc_u32 s49, s49, 0
	s_mov_b32 m0, s43
	v_lshl_add_u64 v[226:227], s[48:49], 0, v[128:129]
	ds_read_b128 v[184:187], v153 offset:32768
	ds_read_b128 v[188:191], v153 offset:33792
	ds_read_b128 v[192:195], v153 offset:34816
	ds_read_b128 v[196:199], v153 offset:35840
	ds_read_b128 v[200:203], v153 offset:36864
	ds_read_b128 v[206:209], v153 offset:37888
	ds_read_b128 v[210:213], v153 offset:38912
	ds_read_b128 v[214:217], v153 offset:39936
	global_load_lds_dwordx4 v[226:227], off
	v_lshl_add_u64 v[226:227], s[48:49], 0, v[132:133]
	s_mov_b32 m0, s50
	s_nop 0
	global_load_lds_dwordx4 v[226:227], off
	s_waitcnt vmcnt(8)
	s_waitcnt lgkmcnt(0)
	s_barrier
	s_setprio 1
	s_waitcnt lgkmcnt(0)
	v_mfma_f32_16x16x32_bf16 v[124:127], v[144:147], v[184:187], v[124:127]
	v_mfma_f32_16x16x32_bf16 v[120:123], v[160:163], v[184:187], v[120:123]
	v_mfma_f32_16x16x32_bf16 v[108:111], v[144:147], v[192:195], v[108:111]
	v_mfma_f32_16x16x32_bf16 v[104:107], v[160:163], v[192:195], v[104:107]
	v_mfma_f32_16x16x32_bf16 v[92:95], v[144:147], v[200:203], v[92:95]
	v_mfma_f32_16x16x32_bf16 v[88:91], v[160:163], v[200:203], v[88:91]
	v_mfma_f32_16x16x32_bf16 v[76:79], v[144:147], v[210:213], v[76:79]
	v_mfma_f32_16x16x32_bf16 v[72:75], v[160:163], v[210:213], v[72:75]
	v_mfma_f32_16x16x32_bf16 v[124:127], v[156:159], v[188:191], v[124:127]
	v_mfma_f32_16x16x32_bf16 v[120:123], v[164:167], v[188:191], v[120:123]
	v_mfma_f32_16x16x32_bf16 v[108:111], v[156:159], v[196:199], v[108:111]
	v_mfma_f32_16x16x32_bf16 v[104:107], v[164:167], v[196:199], v[104:107]
	v_mfma_f32_16x16x32_bf16 v[92:95], v[156:159], v[206:209], v[92:95]
	v_mfma_f32_16x16x32_bf16 v[88:91], v[164:167], v[206:209], v[88:91]
	v_mfma_f32_16x16x32_bf16 v[76:79], v[156:159], v[214:217], v[76:79]
	v_mfma_f32_16x16x32_bf16 v[72:75], v[164:167], v[214:217], v[72:75]
	s_setprio 0
	s_setprio 1
	v_mfma_f32_16x16x32_bf16 v[116:119], v[168:171], v[184:187], v[116:119]
	v_mfma_f32_16x16x32_bf16 v[112:115], v[176:179], v[184:187], v[112:115]
	v_mfma_f32_16x16x32_bf16 v[100:103], v[168:171], v[192:195], v[100:103]
	v_mfma_f32_16x16x32_bf16 v[96:99], v[176:179], v[192:195], v[96:99]
	v_mfma_f32_16x16x32_bf16 v[84:87], v[168:171], v[200:203], v[84:87]
	v_mfma_f32_16x16x32_bf16 v[80:83], v[176:179], v[200:203], v[80:83]
	v_mfma_f32_16x16x32_bf16 v[68:71], v[168:171], v[210:213], v[68:71]
	v_mfma_f32_16x16x32_bf16 v[64:67], v[176:179], v[210:213], v[64:67]
	v_mfma_f32_16x16x32_bf16 v[116:119], v[172:175], v[188:191], v[116:119]
	v_mfma_f32_16x16x32_bf16 v[112:115], v[180:183], v[188:191], v[112:115]
	v_mfma_f32_16x16x32_bf16 v[100:103], v[172:175], v[196:199], v[100:103]
	v_mfma_f32_16x16x32_bf16 v[96:99], v[180:183], v[196:199], v[96:99]
	v_mfma_f32_16x16x32_bf16 v[84:87], v[172:175], v[206:209], v[84:87]
	v_mfma_f32_16x16x32_bf16 v[80:83], v[180:183], v[206:209], v[80:83]
	v_mfma_f32_16x16x32_bf16 v[68:71], v[172:175], v[214:217], v[68:71]
	v_mfma_f32_16x16x32_bf16 v[64:67], v[180:183], v[214:217], v[64:67]
	s_setprio 0
	s_barrier
	s_add_i32 s48, s62, s15
	v_lshl_add_u64 v[218:219], v[218:219], 0, s[12:13]
	s_mov_b32 m0, s48
	ds_read_b128 v[184:187], v153 offset:49152
	ds_read_b128 v[188:191], v153 offset:50176
	ds_read_b128 v[192:195], v153 offset:51200
	ds_read_b128 v[196:199], v153 offset:52224
	ds_read_b128 v[200:203], v153 offset:53248
	ds_read_b128 v[206:209], v153 offset:54272
	ds_read_b128 v[210:213], v153 offset:55296
	ds_read_b128 v[214:217], v153 offset:56320
	global_load_lds_dwordx4 v[218:219], off
	s_add_i32 m0, s48, 0x2000
	s_add_u32 s46, s46, 0x20080
	v_lshl_add_u64 v[218:219], v[220:221], 0, s[12:13]
	s_addc_u32 s47, s47, 0
	s_add_i32 s48, s63, s15
	global_load_lds_dwordx4 v[218:219], off
	v_lshl_add_u64 v[218:219], s[46:47], 0, v[130:131]
	s_mov_b32 m0, s48
	s_nop 0
	global_load_lds_dwordx4 v[218:219], off
	v_lshl_add_u64 v[218:219], s[46:47], 0, v[134:135]
	s_add_i32 m0, s48, 0x2000
	s_nop 0
	global_load_lds_dwordx4 v[218:219], off
	s_waitcnt vmcnt(6)
	s_waitcnt lgkmcnt(0)
	s_barrier
; #define PG8_BAR __builtin_amdgcn_s_barrier()
;     __device__ __forceinline__ void operator()(const f32x4 (&acc)[2][2][4][2], const Unit& u, int wr, int wc, int fr, int fq) const {
;     ...
;             for (int m = 0; m < 4; ++m) { const int row = row0 + ai * HALF + m * 16; const size_t off = (size_t)row * 1024 + col0; float s = 0.f;
; #pragma unroll
;                 for (int bj = 0; bj < 2; ++bj) { f32x4 a0, a1;
;                     if (xin32) { const float* p = xin32 + off + bj * HALF; a0 = *(const f32x4*)p; a1 = *(const f32x4*)(p + 4); }
;                     else { const u32x4 w = *(const u32x4*)(xb + off + bj * HALF);
; template <class Epi, class Sched, bool ALIGN_EPI = false, bool SP2 = false>
; __device__ __forceinline__ void gemm_phase(PG8_LAS unsigned char* lds, const Gemm g, const Sched& S, const Epi& E) {
;     ...
;             PG8_WAIT_V(8); PG8_WAIT_L(0); PG8_BAR; PG8_MMA(1, 0, At, B0); PG8_MMA(1, 1, At, B1); PG8_BAR; PG8_SCHED;
;             } else {
;             PG8_LDB(B0, 0, 0); PG8_SCHED; PG8_LDA(At, 0, 0); PG8_STAGE(PG8_SA(1, 1), a1 + hstep, voffA);
;             PG8_WAIT_L(8); PG8_BAR; PG8_WAIT_L(0); PG8_MMA(0, 0, At, B0); PG8_BAR; PG8_SCHED;
;             PG8_LDB(B1, 0, 1); PG8_STAGE(PG8_SB(0, 0), b2, voffB);
;             PG8_BAR; PG8_WAIT_L(0); PG8_MMA(0, 1, At, B1); PG8_BAR;
;             PG8_LDA(At, 0, 1); PG8_STAGE(PG8_SA(0, 0), a2, voffA);
;             PG8_BAR; PG8_WAIT_L(0); PG8_MMA(1, 0, At, B0); PG8_BAR; PG8_SCHED;
;             PG8_STAGE(PG8_SB(0, 1), b2 + hstep, voffB);
;             PG8_WAIT_V(6); PG8_BAR; PG8_MMA(1, 1, At, B1); PG8_BAR;
;             PG8_LDB(B0, 1, 0); PG8_SCHED; PG8_LDA(At, 1, 0); PG8_STAGE(PG8_SA(0, 1), a2 + hstep, voffA);
;             PG8_WAIT_L(8); PG8_BAR; PG8_WAIT_L(0); PG8_MMA(0, 0, At, B0); PG8_BAR; PG8_SCHED;
;             PG8_LDB(B1, 1, 1); PG8_STAGE(PG8_SB(1, 0), b3, voffB);
;             PG8_BAR; PG8_WAIT_L(0); PG8_MMA(0, 1, At, B1); PG8_BAR;
;             PG8_LDA(At, 1, 1); PG8_STAGE(PG8_SA(1, 0), a3, voffA);
;             PG8_BAR; PG8_WAIT_L(0); PG8_MMA(1, 0, At, B0); PG8_BAR; PG8_SCHED;
;             PG8_STAGE(PG8_SB(1, 1), b3 + hstep, voffB);
;             PG8_WAIT_V(6); PG8_BAR; PG8_MMA(1, 1, At, B1); PG8_BAR;
;             }
;         }
;         if constexpr (ALIGN_EPI) { if (wr == 0) PG8_BAR; }
;         if constexpr (!Epi::AFTER_DRAIN) { E(acc, cur, wr, wc, fr, fq); S.done(cur); }
	s_setprio 1
	s_waitcnt lgkmcnt(0)
	v_mfma_f32_16x16x32_bf16 v[60:63], v[144:147], v[184:187], v[60:63]
	v_mfma_f32_16x16x32_bf16 v[56:59], v[160:163], v[184:187], v[56:59]
	v_mfma_f32_16x16x32_bf16 v[44:47], v[144:147], v[192:195], v[44:47]
	v_mfma_f32_16x16x32_bf16 v[40:43], v[160:163], v[192:195], v[40:43]
	v_mfma_f32_16x16x32_bf16 v[28:31], v[144:147], v[200:203], v[28:31]
	v_mfma_f32_16x16x32_bf16 v[24:27], v[160:163], v[200:203], v[24:27]
	v_mfma_f32_16x16x32_bf16 v[12:15], v[144:147], v[210:213], v[12:15]
	v_mfma_f32_16x16x32_bf16 v[8:11], v[160:163], v[210:213], v[8:11]
	v_mfma_f32_16x16x32_bf16 v[60:63], v[156:159], v[188:191], v[60:63]
	v_mfma_f32_16x16x32_bf16 v[56:59], v[164:167], v[188:191], v[56:59]
	v_mfma_f32_16x16x32_bf16 v[44:47], v[156:159], v[196:199], v[44:47]
	v_mfma_f32_16x16x32_bf16 v[40:43], v[164:167], v[196:199], v[40:43]
	v_mfma_f32_16x16x32_bf16 v[28:31], v[156:159], v[206:209], v[28:31]
	v_mfma_f32_16x16x32_bf16 v[24:27], v[164:167], v[206:209], v[24:27]
	v_lshl_add_u64 v[218:219], v[222:223], 0, s[12:13]
	s_mov_b32 m0, s52
	s_nop 0
	global_load_lds_dwordx4 v[218:219], off
	v_mfma_f32_16x16x32_bf16 v[12:15], v[156:159], v[214:217], v[12:15]
	v_mfma_f32_16x16x32_bf16 v[8:11], v[164:167], v[214:217], v[8:11]
	s_setprio 0
	s_setprio 1
	v_mfma_f32_16x16x32_bf16 v[52:55], v[168:171], v[184:187], v[52:55]
	v_mfma_f32_16x16x32_bf16 v[48:51], v[176:179], v[184:187], v[48:51]
	v_mfma_f32_16x16x32_bf16 v[36:39], v[168:171], v[192:195], v[36:39]
	v_mfma_f32_16x16x32_bf16 v[32:35], v[176:179], v[192:195], v[32:35]
	v_mfma_f32_16x16x32_bf16 v[20:23], v[168:171], v[200:203], v[20:23]
	v_mfma_f32_16x16x32_bf16 v[16:19], v[176:179], v[200:203], v[16:19]
	v_mfma_f32_16x16x32_bf16 v[4:7], v[168:171], v[210:213], v[4:7]
	v_mfma_f32_16x16x32_bf16 v[0:3], v[176:179], v[210:213], v[0:3]
	v_mfma_f32_16x16x32_bf16 v[52:55], v[172:175], v[188:191], v[52:55]
	v_mfma_f32_16x16x32_bf16 v[48:51], v[180:183], v[188:191], v[48:51]
	v_mfma_f32_16x16x32_bf16 v[36:39], v[172:175], v[196:199], v[36:39]
	v_mfma_f32_16x16x32_bf16 v[32:35], v[180:183], v[196:199], v[32:35]
	v_mfma_f32_16x16x32_bf16 v[20:23], v[172:175], v[206:209], v[20:23]
	v_mfma_f32_16x16x32_bf16 v[16:19], v[180:183], v[206:209], v[16:19]
	v_lshl_add_u64 v[218:219], v[224:225], 0, s[12:13]
	s_mov_b32 m0, s53
	s_nop 0
	global_load_lds_dwordx4 v[218:219], off
	v_mfma_f32_16x16x32_bf16 v[4:7], v[172:175], v[214:217], v[4:7]
	v_mfma_f32_16x16x32_bf16 v[0:3], v[180:183], v[214:217], v[0:3]
	s_setprio 0
	s_barrier
	s_add_i32 s61, s61, 2
	s_add_u32 s44, s44, 0x100
	s_addc_u32 s45, s45, 0
	s_add_u32 s59, s59, 0x100
	s_addc_u32 s60, s60, 0
	s_cmp_gt_u32 s61, 5
	s_cbranch_scc0 .LBB0_1816
	s_and_b64 vcc, exec, s[24:25]
	s_cbranch_vccz .LBB0_1819
.LBB0_1819:
	v_lshl_add_u32 v146, s42, 8, v148
	v_ashrrev_i32_e32 v147, 31, v146
	v_lshl_or_b32 v144, s40, 8, v150
	v_lshlrev_b64 v[156:157], 11, v[146:147]
	v_ashrrev_i32_e32 v145, 31, v144
	v_lshl_add_u64 v[156:157], s[22:23], 0, v[156:157]
	v_lshl_add_u64 v[166:167], v[144:145], 1, v[156:157]
	global_load_dwordx4 v[158:161], v[166:167], off
	global_load_dwordx4 v[162:165], v[166:167], off offset:256
	v_and_b32_e32 v156, 64, v154
	v_xor_b32_e32 v155, 16, v154
	v_add_u32_e32 v156, 64, v156
	v_xor_b32_e32 v157, 32, v154
	v_cmp_lt_i32_e32 vcc, v155, v156
	s_waitcnt vmcnt(0)
	v_lshlrev_b32_e32 v168, 16, v158
	v_cndmask_b32_e32 v155, v154, v155, vcc
	v_cmp_lt_i32_e32 vcc, v157, v156
	v_and_b32_e32 v169, 0xffff0000, v158
	v_lshlrev_b32_e32 v158, 16, v159
	v_and_b32_e32 v159, 0xffff0000, v159
	v_lshlrev_b32_e32 v172, 16, v162
	v_and_b32_e32 v173, 0xffff0000, v162
	v_lshlrev_b32_e32 v162, 16, v163
	v_and_b32_e32 v163, 0xffff0000, v163
	v_cndmask_b32_e32 v157, v154, v157, vcc
	v_lshlrev_b32_e32 v170, 16, v160
	v_and_b32_e32 v171, 0xffff0000, v160
	v_lshlrev_b32_e32 v160, 16, v161
	v_and_b32_e32 v161, 0xffff0000, v161
	v_lshlrev_b32_e32 v174, 16, v164
	v_and_b32_e32 v175, 0xffff0000, v164
	v_lshlrev_b32_e32 v164, 16, v165
	v_and_b32_e32 v165, 0xffff0000, v165
	v_pk_add_f32 v[126:127], v[126:127], v[158:159]
	v_pk_add_f32 v[124:125], v[124:125], v[168:169]
	v_pk_add_f32 v[118:119], v[118:119], v[162:163]
	v_pk_add_f32 v[116:117], v[116:117], v[172:173]
	v_lshlrev_b32_e32 v156, 2, v155
	v_lshlrev_b32_e32 v155, 2, v157
	v_pk_add_f32 v[122:123], v[122:123], v[160:161]
	v_pk_add_f32 v[120:121], v[120:121], v[170:171]
	v_pk_add_f32 v[158:159], v[114:115], v[164:165]
	v_pk_add_f32 v[160:161], v[112:113], v[174:175]
	v_mul_f32_e32 v114, v125, v125
	v_mul_f32_e32 v115, v127, v127
	v_mul_f32_e32 v157, v117, v117
	v_mul_f32_e32 v162, v119, v119
	v_cvt_pk_bf16_f32 v112, v124, v125
	v_mul_f32_e32 v125, v121, v121
	v_mul_f32_e32 v163, v161, v161
	v_fmac_f32_e32 v114, v124, v124
	v_fmac_f32_e32 v115, v126, v126
	v_fmac_f32_e32 v157, v116, v116
	v_fmac_f32_e32 v162, v118, v118
	v_cvt_pk_bf16_f32 v113, v126, v127
	v_mul_f32_e32 v127, v123, v123
	v_mul_f32_e32 v164, v159, v159
	v_fmac_f32_e32 v125, v120, v120
	v_fmac_f32_e32 v163, v160, v160
	v_add_f32_e32 v114, v114, v115
	v_add_f32_e32 v115, v157, v162
	v_fmac_f32_e32 v127, v122, v122
	v_fmac_f32_e32 v164, v158, v158
	v_add_f32_e32 v114, v125, v114
	v_add_f32_e32 v115, v163, v115
	v_add_f32_e32 v114, v127, v114
	v_add_f32_e32 v115, v164, v115
	v_add_f32_e32 v124, v114, v115
	ds_bpermute_b32 v125, v156, v124
	v_cvt_pk_bf16_f32 v114, v120, v121
	v_cvt_pk_bf16_f32 v115, v122, v123
	global_store_dwordx4 v[166:167], v[112:115], off
	s_waitcnt lgkmcnt(0)
	s_nop 0
	v_add_f32_e32 v112, v124, v125
	ds_bpermute_b32 v113, v155, v112
	v_cvt_pk_bf16_f32 v114, v116, v117
	v_cvt_pk_bf16_f32 v115, v118, v119
	v_cvt_pk_bf16_f32 v116, v160, v161
	v_cvt_pk_bf16_f32 v117, v158, v159
	global_store_dwordx4 v[166:167], v[114:117], off offset:256
	s_and_saveexec_b64 s[40:41], s[4:5]
	s_cbranch_execz .LBB0_1821
	s_waitcnt lgkmcnt(0)
	v_add_f32_e32 v112, v112, v113
	v_mul_f32_e32 v112, 0x4f800000, v112
	v_trunc_f32_e32 v112, v112
	v_mul_f32_e64 v113, |v112|, s56
	v_floor_f32_e32 v113, v113
	v_fma_f32 v114, v113, s57, |v112|
	v_cvt_u32_f32_e32 v114, v114
	v_cvt_u32_f32_e32 v113, v113
	v_ashrrev_i32_e32 v115, 31, v112
	v_xor_b32_e32 v112, v114, v115
	v_xor_b32_e32 v113, v113, v115
	v_sub_co_u32_e32 v112, vcc, v112, v115
	s_nop 1
	v_subb_co_u32_e32 v113, vcc, v113, v115, vcc
	v_lshl_add_u64 v[114:115], v[146:147], 3, s[0:1]
	global_atomic_add_x2 v[114:115], v[112:113], off

; #define PG8_BAR __builtin_amdgcn_s_barrier()
; template <class Epi, class Sched, bool ALIGN_EPI = false, bool SP2 = false>
; __device__ __forceinline__ void gemm_phase(PG8_LAS unsigned char* lds, const Gemm g, const Sched& S, const Epi& E) {
;     ...
;         if constexpr (ALIGN_EPI) { if (wr == 0) PG8_BAR; }
;         if constexpr (!Epi::AFTER_DRAIN) { E(acc, cur, wr, wc, fr, fq); S.done(cur); }
;         if (!has_next) break;
.LBB0_1835:
	s_or_b64 exec, exec, s[40:41]
	s_andn2_b64 vcc, exec, s[6:7]
	s_mov_b64 s[6:7], -1
	s_cmp_eq_u64 s[24:25], 0
	s_cbranch_scc1 .Lxpost_11
	s_barrier

; #define PG8_STAGE(bufoff, gbase, voff) do { _Pragma("unroll") for (int _i = 0; _i < 2; ++_i) \
;         __builtin_amdgcn_global_load_lds((const unsigned*)((const char*)(gbase) + (voff)[_i]), (PG8_LAS unsigned*)(lds + (bufoff) + ldsw + _i * 8192), 16, 0, 0); } while (0)
; #define PG8_LDA(dst, b, h) do { _Pragma("unroll") for (int m = 0; m < 4; ++m) _Pragma("unroll") for (int k = 0; k < 2; ++k) dst[m][k] = *(const PG8_LAS bf16x8*)(lds + PG8_SA(b, h) + aoff + m * 2048 + k * 1024); } while (0)
; #define PG8_LDB(dst, b, h) do { _Pragma("unroll") for (int n = 0; n < 2; ++n) _Pragma("unroll") for (int k = 0; k < 2; ++k) dst[n][k] = *(const PG8_LAS bf16x8*)(lds + PG8_SB(b, h) + boff + n * 2048 + k * 1024); } while (0)
; #define PG8_WAIT_V(n) asm volatile("s_waitcnt vmcnt(" #n ")" ::: "memory")
; #define PG8_WAIT_L(n) asm volatile("s_waitcnt lgkmcnt(" #n ")" ::: "memory")
; #define PG8_BAR __builtin_amdgcn_s_barrier()
; #define PG8_SCHED __builtin_amdgcn_sched_barrier(0)
; template <class Epi, class Sched, bool ALIGN_EPI = false, bool SP2 = false>
; __device__ __forceinline__ void gemm_phase(PG8_LAS unsigned char* lds, const Gemm g, const Sched& S, const Epi& E) {
;     ...
;         const bool has_next = S.next(ui + 1, nxt);
;         const char* nA = has_next ? (const char*)g.A + (size_t)nxt.pm * tstep : cA; const char* nB = has_next ? (const char*)g.Bt + (size_t)nxt.pn * tstep : cB;
;         for (int t = 0; t < nt; t += 2) {
;             const bool last = (t == nt - 2);
;             const char* a1 = cA + (size_t)(t + 1) * kstep;
;             const char* a2 = last ? nA : cA + (size_t)(t + 2) * kstep; const char* b2 = last ? nB : cB + (size_t)(t + 2) * kstep;
;             const char* a3 = a2 + kstep; const char* b3 = b2 + kstep;
;             if (last && has_next) S.a_ready(nxt);
;             if constexpr (SP2) {
;             PG8_LDB(B0, 0, 0); PG8_LDB(B1, 0, 1); PG8_SCHED; PG8_LDA(At, 0, 0); PG8_STAGE(PG8_SA(1, 1), a1 + hstep, voffA);
;             PG8_WAIT_V(8); PG8_WAIT_L(0); PG8_BAR; PG8_MMA(0, 0, At, B0); PG8_MMA(0, 1, At, B1); PG8_BAR; PG8_SCHED;
;             PG8_LDA(At, 0, 1); PG8_STAGE(PG8_SB(0, 0), b2, voffB); PG8_STAGE(PG8_SB(0, 1), b2 + hstep, voffB); PG8_STAGE(PG8_SA(0, 0), a2, voffA);
;             PG8_WAIT_V(8); PG8_WAIT_L(0); PG8_BAR; PG8_MMA(1, 0, At, B0); PG8_MMA(1, 1, At, B1); PG8_BAR; PG8_SCHED;
.LBB0_1899:
	s_ashr_i32 s25, s24, 31
	s_lshl_b64 s[26:27], s[24:25], 19
	s_add_u32 s26, s22, s26
	s_addc_u32 s27, s23, s27
	s_and_b64 s[28:29], s[4:5], exec
	s_cselect_b32 s25, s27, s39
	s_cselect_b32 s53, s26, s38
	s_ashr_i32 s13, s12, 31
	s_lshl_b64 s[28:29], s[12:13], 19
	s_add_u32 s28, s3, s28
	s_addc_u32 s29, s14, s29
	s_and_b64 s[42:43], s[4:5], exec
	s_cselect_b32 s13, s29, s41
	s_cselect_b32 s54, s28, s40
	s_add_u32 s38, s38, 0x40080
	s_addc_u32 s39, s39, 0
	s_add_u32 s55, s40, 0x100
	s_addc_u32 s56, s41, 0
	s_mov_b32 s57, -2
	ds_read_b128 v[144:147], v155
	ds_read_b128 v[148:151], v155 offset:1024
	ds_read_b128 v[160:163], v155 offset:2048
	ds_read_b128 v[164:167], v155 offset:3072
	ds_read_b128 v[168:171], v156
	ds_read_b128 v[172:175], v156 offset:1024
	ds_read_b128 v[176:179], v156 offset:2048
	ds_read_b128 v[180:183], v156 offset:3072
	s_add_u32 s40, s38, 0xfffc0080
	s_addc_u32 s41, s39, -1
	s_cmp_eq_u32 s57, 12
	s_cselect_b32 s43, s25, s41
	s_cselect_b32 s42, s53, s40
	s_cselect_b32 s41, s13, s56
	s_cselect_b32 s40, s54, s55
	v_lshl_add_u64 v[218:219], s[38:39], 0, v[136:137]
	s_add_i32 m0, s34, 0xc000
	ds_read_b128 v[184:187], v157
	ds_read_b128 v[188:191], v157 offset:1024
	ds_read_b128 v[192:195], v157 offset:2048
	ds_read_b128 v[196:199], v157 offset:3072
	ds_read_b128 v[200:203], v157 offset:4096
	ds_read_b128 v[206:209], v157 offset:5120
	ds_read_b128 v[210:213], v157 offset:6144
	ds_read_b128 v[214:217], v157 offset:7168
	global_load_lds_dwordx4 v[218:219], off
	v_lshl_add_u64 v[218:219], s[38:39], 0, v[138:139]
	s_add_i32 m0, s34, 0xe000
	s_nop 0
	global_load_lds_dwordx4 v[218:219], off
	s_waitcnt vmcnt(8)
	s_waitcnt lgkmcnt(0)
	s_barrier
	s_setprio 1
	s_waitcnt lgkmcnt(0)
	v_mfma_f32_16x16x32_bf16 v[124:127], v[144:147], v[184:187], 0
	v_mfma_f32_16x16x32_bf16 v[120:123], v[160:163], v[184:187], 0
	v_mfma_f32_16x16x32_bf16 v[108:111], v[144:147], v[192:195], 0
	v_mfma_f32_16x16x32_bf16 v[104:107], v[160:163], v[192:195], 0
	v_mfma_f32_16x16x32_bf16 v[92:95], v[144:147], v[200:203], 0
	v_mfma_f32_16x16x32_bf16 v[88:91], v[160:163], v[200:203], 0
	v_mfma_f32_16x16x32_bf16 v[76:79], v[144:147], v[210:213], 0
	v_mfma_f32_16x16x32_bf16 v[72:75], v[160:163], v[210:213], 0
	v_mfma_f32_16x16x32_bf16 v[124:127], v[148:151], v[188:191], v[124:127]
	v_mfma_f32_16x16x32_bf16 v[120:123], v[164:167], v[188:191], v[120:123]
	v_mfma_f32_16x16x32_bf16 v[108:111], v[148:151], v[196:199], v[108:111]
	v_mfma_f32_16x16x32_bf16 v[104:107], v[164:167], v[196:199], v[104:107]
	v_mfma_f32_16x16x32_bf16 v[92:95], v[148:151], v[206:209], v[92:95]
	v_mfma_f32_16x16x32_bf16 v[88:91], v[164:167], v[206:209], v[88:91]
	v_mfma_f32_16x16x32_bf16 v[76:79], v[148:151], v[214:217], v[76:79]
	v_mfma_f32_16x16x32_bf16 v[72:75], v[164:167], v[214:217], v[72:75]
	s_setprio 0
	s_setprio 1
	v_mfma_f32_16x16x32_bf16 v[116:119], v[168:171], v[184:187], 0
	v_mfma_f32_16x16x32_bf16 v[112:115], v[176:179], v[184:187], 0
	v_mfma_f32_16x16x32_bf16 v[100:103], v[168:171], v[192:195], 0
	v_mfma_f32_16x16x32_bf16 v[96:99], v[176:179], v[192:195], 0
	v_mfma_f32_16x16x32_bf16 v[84:87], v[168:171], v[200:203], 0
	v_mfma_f32_16x16x32_bf16 v[80:83], v[176:179], v[200:203], 0
	v_mfma_f32_16x16x32_bf16 v[68:71], v[168:171], v[210:213], 0
	v_mfma_f32_16x16x32_bf16 v[64:67], v[176:179], v[210:213], 0
	v_mfma_f32_16x16x32_bf16 v[116:119], v[172:175], v[188:191], v[116:119]
	v_mfma_f32_16x16x32_bf16 v[112:115], v[180:183], v[188:191], v[112:115]
	v_mfma_f32_16x16x32_bf16 v[100:103], v[172:175], v[196:199], v[100:103]
	v_mfma_f32_16x16x32_bf16 v[96:99], v[180:183], v[196:199], v[96:99]
	v_mfma_f32_16x16x32_bf16 v[84:87], v[172:175], v[206:209], v[84:87]
	v_mfma_f32_16x16x32_bf16 v[80:83], v[180:183], v[206:209], v[80:83]
	v_mfma_f32_16x16x32_bf16 v[68:71], v[172:175], v[214:217], v[68:71]
	v_mfma_f32_16x16x32_bf16 v[64:67], v[180:183], v[214:217], v[64:67]
	s_setprio 0
	s_barrier
	s_add_i32 s58, s49, s15
	v_lshl_add_u64 v[218:219], s[40:41], 0, v[132:133]
	s_mov_b32 m0, s58
	ds_read_b128 v[184:187], v157 offset:16384
	ds_read_b128 v[188:191], v157 offset:17408
	ds_read_b128 v[192:195], v157 offset:18432
	ds_read_b128 v[196:199], v157 offset:19456
	ds_read_b128 v[200:203], v157 offset:20480
	ds_read_b128 v[206:209], v157 offset:21504
	ds_read_b128 v[210:213], v157 offset:22528
	ds_read_b128 v[214:217], v157 offset:23552
	global_load_lds_dwordx4 v[218:219], off
	s_add_i32 m0, s58, 0x2000
	s_add_u32 s58, s40, 0x40000
	v_lshl_add_u64 v[220:221], s[40:41], 0, v[128:129]
	s_addc_u32 s59, s41, 0
	s_add_i32 s60, s50, s15
	global_load_lds_dwordx4 v[220:221], off
	v_lshl_add_u64 v[222:223], s[58:59], 0, v[132:133]
	s_mov_b32 m0, s60
	global_load_lds_dwordx4 v[222:223], off
	v_lshl_add_u64 v[222:223], s[58:59], 0, v[128:129]
	s_add_i32 m0, s60, 0x2000
	s_nop 0
	global_load_lds_dwordx4 v[222:223], off
	s_waitcnt vmcnt(6)
	s_waitcnt lgkmcnt(0)
	s_barrier
; #define PG8_STAGE(bufoff, gbase, voff) do { _Pragma("unroll") for (int _i = 0; _i < 2; ++_i) \
;         __builtin_amdgcn_global_load_lds((const unsigned*)((const char*)(gbase) + (voff)[_i]), (PG8_LAS unsigned*)(lds + (bufoff) + ldsw + _i * 8192), 16, 0, 0); } while (0)
; #define PG8_LDA(dst, b, h) do { _Pragma("unroll") for (int m = 0; m < 4; ++m) _Pragma("unroll") for (int k = 0; k < 2; ++k) dst[m][k] = *(const PG8_LAS bf16x8*)(lds + PG8_SA(b, h) + aoff + m * 2048 + k * 1024); } while (0)
; #define PG8_LDB(dst, b, h) do { _Pragma("unroll") for (int n = 0; n < 2; ++n) _Pragma("unroll") for (int k = 0; k < 2; ++k) dst[n][k] = *(const PG8_LAS bf16x8*)(lds + PG8_SB(b, h) + boff + n * 2048 + k * 1024); } while (0)
; #define PG8_MMA(ai, bj, At, Bt) do { __builtin_amdgcn_s_setprio(1); _Pragma("unroll") for (int m = 0; m < 4; ++m) _Pragma("unroll") for (int n = 0; n < 2; ++n) _Pragma("unroll") for (int k = 0; k < 2; ++k) \
;         acc[ai][bj][m][n] = __builtin_amdgcn_mfma_f32_16x16x32_bf16(Bt[n][k], At[m][k], acc[ai][bj][m][n], 0, 0, 0); __builtin_amdgcn_s_setprio(0); } while (0)
; #define PG8_WAIT_V(n) asm volatile("s_waitcnt vmcnt(" #n ")" ::: "memory")
; template <class Epi, class Sched, bool ALIGN_EPI = false, bool SP2 = false>
; __device__ __forceinline__ void gemm_phase(PG8_LAS unsigned char* lds, const Gemm g, const Sched& S, const Epi& E) {
;     ...
;             PG8_LDB(B0, 0, 0); PG8_LDB(B1, 0, 1); PG8_SCHED; PG8_LDA(At, 0, 0); PG8_STAGE(PG8_SA(1, 1), a1 + hstep, voffA);
;             PG8_WAIT_V(8); PG8_WAIT_L(0); PG8_BAR; PG8_MMA(0, 0, At, B0); PG8_MMA(0, 1, At, B1); PG8_BAR; PG8_SCHED;
;             PG8_LDA(At, 0, 1); PG8_STAGE(PG8_SB(0, 0), b2, voffB); PG8_STAGE(PG8_SB(0, 1), b2 + hstep, voffB); PG8_STAGE(PG8_SA(0, 0), a2, voffA);
;             PG8_WAIT_V(8); PG8_WAIT_L(0); PG8_BAR; PG8_MMA(1, 0, At, B0); PG8_MMA(1, 1, At, B1); PG8_BAR; PG8_SCHED;
;             PG8_LDB(B0, 1, 0); PG8_LDB(B1, 1, 1); PG8_SCHED; PG8_LDA(At, 1, 0); PG8_STAGE(PG8_SA(0, 1), a2 + hstep, voffA);
;             PG8_WAIT_V(8); PG8_WAIT_L(0); PG8_BAR; PG8_MMA(0, 0, At, B0); PG8_MMA(0, 1, At, B1); PG8_BAR; PG8_SCHED;
;             PG8_LDA(At, 1, 1); PG8_STAGE(PG8_SB(1, 0), b3, voffB); PG8_STAGE(PG8_SB(1, 1), b3 + hstep, voffB); PG8_STAGE(PG8_SA(1, 0), a3, voffA);
;             PG8_WAIT_V(8); PG8_WAIT_L(0); PG8_BAR; PG8_MMA(1, 0, At, B0); PG8_MMA(1, 1, At, B1); PG8_BAR; PG8_SCHED;
	s_setprio 1
	s_waitcnt lgkmcnt(0)
	v_mfma_f32_16x16x32_bf16 v[60:63], v[144:147], v[184:187], 0
	v_mfma_f32_16x16x32_bf16 v[56:59], v[160:163], v[184:187], 0
	v_mfma_f32_16x16x32_bf16 v[44:47], v[144:147], v[192:195], 0
	v_mfma_f32_16x16x32_bf16 v[40:43], v[160:163], v[192:195], 0
	v_mfma_f32_16x16x32_bf16 v[28:31], v[144:147], v[200:203], 0
	v_mfma_f32_16x16x32_bf16 v[24:27], v[160:163], v[200:203], 0
	v_mfma_f32_16x16x32_bf16 v[12:15], v[144:147], v[210:213], 0
	v_mfma_f32_16x16x32_bf16 v[8:11], v[160:163], v[210:213], 0
	v_mfma_f32_16x16x32_bf16 v[60:63], v[148:151], v[188:191], v[60:63]
	v_mfma_f32_16x16x32_bf16 v[56:59], v[164:167], v[188:191], v[56:59]
	v_mfma_f32_16x16x32_bf16 v[44:47], v[148:151], v[196:199], v[44:47]
	v_mfma_f32_16x16x32_bf16 v[40:43], v[164:167], v[196:199], v[40:43]
	v_mfma_f32_16x16x32_bf16 v[28:31], v[148:151], v[206:209], v[28:31]
	v_mfma_f32_16x16x32_bf16 v[24:27], v[164:167], v[206:209], v[24:27]
	v_lshl_add_u64 v[222:223], s[42:43], 0, v[134:135]
	s_mov_b32 m0, s34
	s_nop 0
	global_load_lds_dwordx4 v[222:223], off
	v_mfma_f32_16x16x32_bf16 v[12:15], v[148:151], v[214:217], v[12:15]
	v_mfma_f32_16x16x32_bf16 v[8:11], v[164:167], v[214:217], v[8:11]
	s_setprio 0
	s_setprio 1
	v_mfma_f32_16x16x32_bf16 v[52:55], v[168:171], v[184:187], 0
	v_mfma_f32_16x16x32_bf16 v[48:51], v[176:179], v[184:187], 0
	v_mfma_f32_16x16x32_bf16 v[36:39], v[168:171], v[192:195], 0
	v_mfma_f32_16x16x32_bf16 v[32:35], v[176:179], v[192:195], 0
	v_mfma_f32_16x16x32_bf16 v[20:23], v[168:171], v[200:203], 0
	v_mfma_f32_16x16x32_bf16 v[16:19], v[176:179], v[200:203], 0
	v_mfma_f32_16x16x32_bf16 v[4:7], v[168:171], v[210:213], 0
	v_mfma_f32_16x16x32_bf16 v[0:3], v[176:179], v[210:213], 0
	v_mfma_f32_16x16x32_bf16 v[52:55], v[172:175], v[188:191], v[52:55]
	v_mfma_f32_16x16x32_bf16 v[48:51], v[180:183], v[188:191], v[48:51]
	v_mfma_f32_16x16x32_bf16 v[36:39], v[172:175], v[196:199], v[36:39]
	v_mfma_f32_16x16x32_bf16 v[32:35], v[180:183], v[196:199], v[32:35]
	v_mfma_f32_16x16x32_bf16 v[20:23], v[172:175], v[206:209], v[20:23]
	v_mfma_f32_16x16x32_bf16 v[16:19], v[180:183], v[206:209], v[16:19]
	v_lshl_add_u64 v[224:225], s[42:43], 0, v[130:131]
	s_mov_b32 m0, s37
	s_nop 0
	global_load_lds_dwordx4 v[224:225], off
	v_mfma_f32_16x16x32_bf16 v[4:7], v[172:175], v[214:217], v[4:7]
	v_mfma_f32_16x16x32_bf16 v[0:3], v[180:183], v[214:217], v[0:3]
	s_setprio 0
	s_barrier
	s_add_i32 s58, 0, 0x18000
	v_add_u32_e32 v159, s58, v153
	s_add_i32 s59, 0, 0x1c000
	ds_read_b128 v[144:147], v159
	ds_read_b128 v[148:151], v159 offset:1024
	ds_read_b128 v[160:163], v159 offset:2048
	ds_read_b128 v[164:167], v159 offset:3072
	v_add_u32_e32 v159, s59, v153
	ds_read_b128 v[168:171], v159
	ds_read_b128 v[172:175], v159 offset:1024
	ds_read_b128 v[176:179], v159 offset:2048
	ds_read_b128 v[180:183], v159 offset:3072
	s_add_u32 s42, s42, 0x40000
	s_addc_u32 s43, s43, 0
	s_mov_b32 m0, s44
	v_lshl_add_u64 v[226:227], s[42:43], 0, v[134:135]
	ds_read_b128 v[184:187], v157 offset:32768
	ds_read_b128 v[188:191], v157 offset:33792
	ds_read_b128 v[192:195], v157 offset:34816
	ds_read_b128 v[196:199], v157 offset:35840
	ds_read_b128 v[200:203], v157 offset:36864
	ds_read_b128 v[206:209], v157 offset:37888
	ds_read_b128 v[210:213], v157 offset:38912
	ds_read_b128 v[214:217], v157 offset:39936
	global_load_lds_dwordx4 v[226:227], off
	v_lshl_add_u64 v[226:227], s[42:43], 0, v[130:131]
	s_mov_b32 m0, s45
	s_nop 0
	global_load_lds_dwordx4 v[226:227], off
	s_waitcnt vmcnt(8)
	s_waitcnt lgkmcnt(0)
	s_barrier
	s_setprio 1
	s_waitcnt lgkmcnt(0)
	v_mfma_f32_16x16x32_bf16 v[124:127], v[144:147], v[184:187], v[124:127]
	v_mfma_f32_16x16x32_bf16 v[120:123], v[160:163], v[184:187], v[120:123]
	v_mfma_f32_16x16x32_bf16 v[108:111], v[144:147], v[192:195], v[108:111]
	v_mfma_f32_16x16x32_bf16 v[104:107], v[160:163], v[192:195], v[104:107]
	v_mfma_f32_16x16x32_bf16 v[92:95], v[144:147], v[200:203], v[92:95]
	v_mfma_f32_16x16x32_bf16 v[88:91], v[160:163], v[200:203], v[88:91]
	v_mfma_f32_16x16x32_bf16 v[76:79], v[144:147], v[210:213], v[76:79]
	v_mfma_f32_16x16x32_bf16 v[72:75], v[160:163], v[210:213], v[72:75]
	v_mfma_f32_16x16x32_bf16 v[124:127], v[148:151], v[188:191], v[124:127]
	v_mfma_f32_16x16x32_bf16 v[120:123], v[164:167], v[188:191], v[120:123]
	v_mfma_f32_16x16x32_bf16 v[108:111], v[148:151], v[196:199], v[108:111]
	v_mfma_f32_16x16x32_bf16 v[104:107], v[164:167], v[196:199], v[104:107]
	v_mfma_f32_16x16x32_bf16 v[92:95], v[148:151], v[206:209], v[92:95]
	v_mfma_f32_16x16x32_bf16 v[88:91], v[164:167], v[206:209], v[88:91]
	v_mfma_f32_16x16x32_bf16 v[76:79], v[148:151], v[214:217], v[76:79]
	v_mfma_f32_16x16x32_bf16 v[72:75], v[164:167], v[214:217], v[72:75]
	s_setprio 0
	s_setprio 1
	v_mfma_f32_16x16x32_bf16 v[116:119], v[168:171], v[184:187], v[116:119]
	v_mfma_f32_16x16x32_bf16 v[112:115], v[176:179], v[184:187], v[112:115]
	v_mfma_f32_16x16x32_bf16 v[100:103], v[168:171], v[192:195], v[100:103]
	v_mfma_f32_16x16x32_bf16 v[96:99], v[176:179], v[192:195], v[96:99]
	v_mfma_f32_16x16x32_bf16 v[84:87], v[168:171], v[200:203], v[84:87]
	v_mfma_f32_16x16x32_bf16 v[80:83], v[176:179], v[200:203], v[80:83]
	v_mfma_f32_16x16x32_bf16 v[68:71], v[168:171], v[210:213], v[68:71]
	v_mfma_f32_16x16x32_bf16 v[64:67], v[176:179], v[210:213], v[64:67]
	v_mfma_f32_16x16x32_bf16 v[116:119], v[172:175], v[188:191], v[116:119]
	v_mfma_f32_16x16x32_bf16 v[112:115], v[180:183], v[188:191], v[112:115]
	v_mfma_f32_16x16x32_bf16 v[100:103], v[172:175], v[196:199], v[100:103]
	v_mfma_f32_16x16x32_bf16 v[96:99], v[180:183], v[196:199], v[96:99]
	v_mfma_f32_16x16x32_bf16 v[84:87], v[172:175], v[206:209], v[84:87]
	v_mfma_f32_16x16x32_bf16 v[80:83], v[180:183], v[206:209], v[80:83]
	v_mfma_f32_16x16x32_bf16 v[68:71], v[172:175], v[214:217], v[68:71]
	v_mfma_f32_16x16x32_bf16 v[64:67], v[180:183], v[214:217], v[64:67]
	s_setprio 0
	s_barrier
; #define PG8_STAGE(bufoff, gbase, voff) do { _Pragma("unroll") for (int _i = 0; _i < 2; ++_i) \
;         __builtin_amdgcn_global_load_lds((const unsigned*)((const char*)(gbase) + (voff)[_i]), (PG8_LAS unsigned*)(lds + (bufoff) + ldsw + _i * 8192), 16, 0, 0); } while (0)
; #define PG8_LDA(dst, b, h) do { _Pragma("unroll") for (int m = 0; m < 4; ++m) _Pragma("unroll") for (int k = 0; k < 2; ++k) dst[m][k] = *(const PG8_LAS bf16x8*)(lds + PG8_SA(b, h) + aoff + m * 2048 + k * 1024); } while (0)
; #define PG8_LDB(dst, b, h) do { _Pragma("unroll") for (int n = 0; n < 2; ++n) _Pragma("unroll") for (int k = 0; k < 2; ++k) dst[n][k] = *(const PG8_LAS bf16x8*)(lds + PG8_SB(b, h) + boff + n * 2048 + k * 1024); } while (0)
; #define PG8_MMA(ai, bj, At, Bt) do { __builtin_amdgcn_s_setprio(1); _Pragma("unroll") for (int m = 0; m < 4; ++m) _Pragma("unroll") for (int n = 0; n < 2; ++n) _Pragma("unroll") for (int k = 0; k < 2; ++k) \
;         acc[ai][bj][m][n] = __builtin_amdgcn_mfma_f32_16x16x32_bf16(Bt[n][k], At[m][k], acc[ai][bj][m][n], 0, 0, 0); __builtin_amdgcn_s_setprio(0); } while (0)
; #define PG8_WAIT_V(n) asm volatile("s_waitcnt vmcnt(" #n ")" ::: "memory")
; template <class Epi, class Sched, bool ALIGN_EPI = false, bool SP2 = false>
; __device__ __forceinline__ void gemm_phase(PG8_LAS unsigned char* lds, const Gemm g, const Sched& S, const Epi& E) {
;     ...
;             PG8_LDB(B0, 0, 0); PG8_LDB(B1, 0, 1); PG8_SCHED; PG8_LDA(At, 0, 0); PG8_STAGE(PG8_SA(1, 1), a1 + hstep, voffA);
;             PG8_WAIT_V(8); PG8_WAIT_L(0); PG8_BAR; PG8_MMA(0, 0, At, B0); PG8_MMA(0, 1, At, B1); PG8_BAR; PG8_SCHED;
;             PG8_LDA(At, 0, 1); PG8_STAGE(PG8_SB(0, 0), b2, voffB); PG8_STAGE(PG8_SB(0, 1), b2 + hstep, voffB); PG8_STAGE(PG8_SA(0, 0), a2, voffA);
;             PG8_WAIT_V(8); PG8_WAIT_L(0); PG8_BAR; PG8_MMA(1, 0, At, B0); PG8_MMA(1, 1, At, B1); PG8_BAR; PG8_SCHED;
;             PG8_LDB(B0, 1, 0); PG8_LDB(B1, 1, 1); PG8_SCHED; PG8_LDA(At, 1, 0); PG8_STAGE(PG8_SA(0, 1), a2 + hstep, voffA);
;             PG8_WAIT_V(8); PG8_WAIT_L(0); PG8_BAR; PG8_MMA(0, 0, At, B0); PG8_MMA(0, 1, At, B1); PG8_BAR; PG8_SCHED;
;             PG8_LDA(At, 1, 1); PG8_STAGE(PG8_SB(1, 0), b3, voffB); PG8_STAGE(PG8_SB(1, 1), b3 + hstep, voffB); PG8_STAGE(PG8_SA(1, 0), a3, voffA);
;             PG8_WAIT_V(8); PG8_WAIT_L(0); PG8_BAR; PG8_MMA(1, 0, At, B0); PG8_MMA(1, 1, At, B1); PG8_BAR; PG8_SCHED;
	s_add_i32 s42, s58, s15
	v_lshl_add_u64 v[218:219], v[218:219], 0, s[8:9]
	s_mov_b32 m0, s42
	ds_read_b128 v[184:187], v157 offset:49152
	ds_read_b128 v[188:191], v157 offset:50176
	ds_read_b128 v[192:195], v157 offset:51200
	ds_read_b128 v[196:199], v157 offset:52224
	ds_read_b128 v[200:203], v157 offset:53248
	ds_read_b128 v[206:209], v157 offset:54272
	ds_read_b128 v[210:213], v157 offset:55296
	ds_read_b128 v[214:217], v157 offset:56320
	global_load_lds_dwordx4 v[218:219], off
	s_add_i32 m0, s42, 0x2000
	s_add_u32 s40, s40, 0x40080
	v_lshl_add_u64 v[218:219], v[220:221], 0, s[8:9]
	s_addc_u32 s41, s41, 0
	s_add_i32 s42, s59, s15
	global_load_lds_dwordx4 v[218:219], off
	v_lshl_add_u64 v[218:219], s[40:41], 0, v[132:133]
	s_mov_b32 m0, s42
	s_nop 0
	global_load_lds_dwordx4 v[218:219], off
	v_lshl_add_u64 v[218:219], s[40:41], 0, v[128:129]
	s_add_i32 m0, s42, 0x2000
	s_nop 0
	global_load_lds_dwordx4 v[218:219], off
	s_waitcnt vmcnt(6)
	s_waitcnt lgkmcnt(0)
	s_barrier
	s_setprio 1
	s_waitcnt lgkmcnt(0)
	v_mfma_f32_16x16x32_bf16 v[60:63], v[144:147], v[184:187], v[60:63]
	v_mfma_f32_16x16x32_bf16 v[56:59], v[160:163], v[184:187], v[56:59]
	v_mfma_f32_16x16x32_bf16 v[44:47], v[144:147], v[192:195], v[44:47]
	v_mfma_f32_16x16x32_bf16 v[40:43], v[160:163], v[192:195], v[40:43]
	v_mfma_f32_16x16x32_bf16 v[28:31], v[144:147], v[200:203], v[28:31]
	v_mfma_f32_16x16x32_bf16 v[24:27], v[160:163], v[200:203], v[24:27]
	v_mfma_f32_16x16x32_bf16 v[12:15], v[144:147], v[210:213], v[12:15]
	v_mfma_f32_16x16x32_bf16 v[8:11], v[160:163], v[210:213], v[8:11]
	v_mfma_f32_16x16x32_bf16 v[60:63], v[148:151], v[188:191], v[60:63]
	v_mfma_f32_16x16x32_bf16 v[56:59], v[164:167], v[188:191], v[56:59]
	v_mfma_f32_16x16x32_bf16 v[44:47], v[148:151], v[196:199], v[44:47]
	v_mfma_f32_16x16x32_bf16 v[40:43], v[164:167], v[196:199], v[40:43]
	v_mfma_f32_16x16x32_bf16 v[28:31], v[148:151], v[206:209], v[28:31]
	v_mfma_f32_16x16x32_bf16 v[24:27], v[164:167], v[206:209], v[24:27]
	v_lshl_add_u64 v[218:219], v[222:223], 0, s[8:9]
	s_mov_b32 m0, s47
	s_nop 0
	global_load_lds_dwordx4 v[218:219], off
	v_mfma_f32_16x16x32_bf16 v[12:15], v[148:151], v[214:217], v[12:15]
	v_mfma_f32_16x16x32_bf16 v[8:11], v[164:167], v[214:217], v[8:11]
	s_setprio 0
	s_setprio 1
	v_mfma_f32_16x16x32_bf16 v[52:55], v[168:171], v[184:187], v[52:55]
	v_mfma_f32_16x16x32_bf16 v[48:51], v[176:179], v[184:187], v[48:51]
	v_mfma_f32_16x16x32_bf16 v[36:39], v[168:171], v[192:195], v[36:39]
	v_mfma_f32_16x16x32_bf16 v[32:35], v[176:179], v[192:195], v[32:35]
	v_mfma_f32_16x16x32_bf16 v[20:23], v[168:171], v[200:203], v[20:23]
	v_mfma_f32_16x16x32_bf16 v[16:19], v[176:179], v[200:203], v[16:19]
	v_mfma_f32_16x16x32_bf16 v[4:7], v[168:171], v[210:213], v[4:7]
	v_mfma_f32_16x16x32_bf16 v[0:3], v[176:179], v[210:213], v[0:3]
	v_mfma_f32_16x16x32_bf16 v[52:55], v[172:175], v[188:191], v[52:55]
	v_mfma_f32_16x16x32_bf16 v[48:51], v[180:183], v[188:191], v[48:51]
	v_mfma_f32_16x16x32_bf16 v[36:39], v[172:175], v[196:199], v[36:39]
	v_mfma_f32_16x16x32_bf16 v[32:35], v[180:183], v[196:199], v[32:35]
	v_mfma_f32_16x16x32_bf16 v[20:23], v[172:175], v[206:209], v[20:23]
	v_mfma_f32_16x16x32_bf16 v[16:19], v[180:183], v[206:209], v[16:19]
	v_lshl_add_u64 v[218:219], v[224:225], 0, s[8:9]
	s_mov_b32 m0, s48
	s_nop 0
	global_load_lds_dwordx4 v[218:219], off
	v_mfma_f32_16x16x32_bf16 v[4:7], v[172:175], v[214:217], v[4:7]
	v_mfma_f32_16x16x32_bf16 v[0:3], v[180:183], v[214:217], v[0:3]
	s_setprio 0
	s_barrier
	s_add_i32 s57, s57, 2
	s_add_u32 s38, s38, 0x100
	s_addc_u32 s39, s39, 0
	s_add_u32 s55, s55, 0x100
	s_addc_u32 s56, s56, 0
.LBB0_1900:
	ds_read_b128 v[144:147], v155
	ds_read_b128 v[148:151], v155 offset:1024
	ds_read_b128 v[160:163], v155 offset:2048
	ds_read_b128 v[164:167], v155 offset:3072
	ds_read_b128 v[168:171], v156
	ds_read_b128 v[172:175], v156 offset:1024
	ds_read_b128 v[176:179], v156 offset:2048
	ds_read_b128 v[180:183], v156 offset:3072
	s_add_u32 s40, s38, 0xfffc0080
	s_addc_u32 s41, s39, -1
	s_cmp_eq_u32 s57, 12
	s_cselect_b32 s43, s25, s41
	s_cselect_b32 s42, s53, s40
	s_cselect_b32 s41, s13, s56
	s_cselect_b32 s40, s54, s55
	v_lshl_add_u64 v[218:219], s[38:39], 0, v[136:137]
	s_add_i32 m0, s34, 0xc000
	ds_read_b128 v[184:187], v157
	ds_read_b128 v[188:191], v157 offset:1024
	ds_read_b128 v[192:195], v157 offset:2048
	ds_read_b128 v[196:199], v157 offset:3072
	ds_read_b128 v[200:203], v157 offset:4096
	ds_read_b128 v[206:209], v157 offset:5120
	ds_read_b128 v[210:213], v157 offset:6144
	ds_read_b128 v[214:217], v157 offset:7168
	global_load_lds_dwordx4 v[218:219], off
	v_lshl_add_u64 v[218:219], s[38:39], 0, v[138:139]
	s_add_i32 m0, s34, 0xe000
	s_nop 0
	global_load_lds_dwordx4 v[218:219], off
	s_waitcnt vmcnt(8)
	s_waitcnt lgkmcnt(0)
	s_barrier
; #define PG8_STAGE(bufoff, gbase, voff) do { _Pragma("unroll") for (int _i = 0; _i < 2; ++_i) \
;         __builtin_amdgcn_global_load_lds((const unsigned*)((const char*)(gbase) + (voff)[_i]), (PG8_LAS unsigned*)(lds + (bufoff) + ldsw + _i * 8192), 16, 0, 0); } while (0)
; #define PG8_LDA(dst, b, h) do { _Pragma("unroll") for (int m = 0; m < 4; ++m) _Pragma("unroll") for (int k = 0; k < 2; ++k) dst[m][k] = *(const PG8_LAS bf16x8*)(lds + PG8_SA(b, h) + aoff + m * 2048 + k * 1024); } while (0)
; #define PG8_LDB(dst, b, h) do { _Pragma("unroll") for (int n = 0; n < 2; ++n) _Pragma("unroll") for (int k = 0; k < 2; ++k) dst[n][k] = *(const PG8_LAS bf16x8*)(lds + PG8_SB(b, h) + boff + n * 2048 + k * 1024); } while (0)
; #define PG8_MMA(ai, bj, At, Bt) do { __builtin_amdgcn_s_setprio(1); _Pragma("unroll") for (int m = 0; m < 4; ++m) _Pragma("unroll") for (int n = 0; n < 2; ++n) _Pragma("unroll") for (int k = 0; k < 2; ++k) \
;         acc[ai][bj][m][n] = __builtin_amdgcn_mfma_f32_16x16x32_bf16(Bt[n][k], At[m][k], acc[ai][bj][m][n], 0, 0, 0); __builtin_amdgcn_s_setprio(0); } while (0)
; #define PG8_WAIT_V(n) asm volatile("s_waitcnt vmcnt(" #n ")" ::: "memory")
; template <class Epi, class Sched, bool ALIGN_EPI = false, bool SP2 = false>
; __device__ __forceinline__ void gemm_phase(PG8_LAS unsigned char* lds, const Gemm g, const Sched& S, const Epi& E) {
;     ...
;             PG8_LDB(B0, 0, 0); PG8_LDB(B1, 0, 1); PG8_SCHED; PG8_LDA(At, 0, 0); PG8_STAGE(PG8_SA(1, 1), a1 + hstep, voffA);
;             PG8_WAIT_V(8); PG8_WAIT_L(0); PG8_BAR; PG8_MMA(0, 0, At, B0); PG8_MMA(0, 1, At, B1); PG8_BAR; PG8_SCHED;
;             PG8_LDA(At, 0, 1); PG8_STAGE(PG8_SB(0, 0), b2, voffB); PG8_STAGE(PG8_SB(0, 1), b2 + hstep, voffB); PG8_STAGE(PG8_SA(0, 0), a2, voffA);
;             PG8_WAIT_V(8); PG8_WAIT_L(0); PG8_BAR; PG8_MMA(1, 0, At, B0); PG8_MMA(1, 1, At, B1); PG8_BAR; PG8_SCHED;
;             PG8_LDB(B0, 1, 0); PG8_LDB(B1, 1, 1); PG8_SCHED; PG8_LDA(At, 1, 0); PG8_STAGE(PG8_SA(0, 1), a2 + hstep, voffA);
;             PG8_WAIT_V(8); PG8_WAIT_L(0); PG8_BAR; PG8_MMA(0, 0, At, B0); PG8_MMA(0, 1, At, B1); PG8_BAR; PG8_SCHED;
;             PG8_LDA(At, 1, 1); PG8_STAGE(PG8_SB(1, 0), b3, voffB); PG8_STAGE(PG8_SB(1, 1), b3 + hstep, voffB); PG8_STAGE(PG8_SA(1, 0), a3, voffA);
;             PG8_WAIT_V(8); PG8_WAIT_L(0); PG8_BAR; PG8_MMA(1, 0, At, B0); PG8_MMA(1, 1, At, B1); PG8_BAR; PG8_SCHED;
	s_setprio 1
	s_waitcnt lgkmcnt(0)
	v_mfma_f32_16x16x32_bf16 v[124:127], v[144:147], v[184:187], v[124:127]
	v_mfma_f32_16x16x32_bf16 v[120:123], v[160:163], v[184:187], v[120:123]
	v_mfma_f32_16x16x32_bf16 v[108:111], v[144:147], v[192:195], v[108:111]
	v_mfma_f32_16x16x32_bf16 v[104:107], v[160:163], v[192:195], v[104:107]
	v_mfma_f32_16x16x32_bf16 v[92:95], v[144:147], v[200:203], v[92:95]
	v_mfma_f32_16x16x32_bf16 v[88:91], v[160:163], v[200:203], v[88:91]
	v_mfma_f32_16x16x32_bf16 v[76:79], v[144:147], v[210:213], v[76:79]
	v_mfma_f32_16x16x32_bf16 v[72:75], v[160:163], v[210:213], v[72:75]
	v_mfma_f32_16x16x32_bf16 v[124:127], v[148:151], v[188:191], v[124:127]
	v_mfma_f32_16x16x32_bf16 v[120:123], v[164:167], v[188:191], v[120:123]
	v_mfma_f32_16x16x32_bf16 v[108:111], v[148:151], v[196:199], v[108:111]
	v_mfma_f32_16x16x32_bf16 v[104:107], v[164:167], v[196:199], v[104:107]
	v_mfma_f32_16x16x32_bf16 v[92:95], v[148:151], v[206:209], v[92:95]
	v_mfma_f32_16x16x32_bf16 v[88:91], v[164:167], v[206:209], v[88:91]
	v_mfma_f32_16x16x32_bf16 v[76:79], v[148:151], v[214:217], v[76:79]
	v_mfma_f32_16x16x32_bf16 v[72:75], v[164:167], v[214:217], v[72:75]
	s_setprio 0
	s_setprio 1
	v_mfma_f32_16x16x32_bf16 v[116:119], v[168:171], v[184:187], v[116:119]
	v_mfma_f32_16x16x32_bf16 v[112:115], v[176:179], v[184:187], v[112:115]
	v_mfma_f32_16x16x32_bf16 v[100:103], v[168:171], v[192:195], v[100:103]
	v_mfma_f32_16x16x32_bf16 v[96:99], v[176:179], v[192:195], v[96:99]
	v_mfma_f32_16x16x32_bf16 v[84:87], v[168:171], v[200:203], v[84:87]
	v_mfma_f32_16x16x32_bf16 v[80:83], v[176:179], v[200:203], v[80:83]
	v_mfma_f32_16x16x32_bf16 v[68:71], v[168:171], v[210:213], v[68:71]
	v_mfma_f32_16x16x32_bf16 v[64:67], v[176:179], v[210:213], v[64:67]
	v_mfma_f32_16x16x32_bf16 v[116:119], v[172:175], v[188:191], v[116:119]
	v_mfma_f32_16x16x32_bf16 v[112:115], v[180:183], v[188:191], v[112:115]
	v_mfma_f32_16x16x32_bf16 v[100:103], v[172:175], v[196:199], v[100:103]
	v_mfma_f32_16x16x32_bf16 v[96:99], v[180:183], v[196:199], v[96:99]
	v_mfma_f32_16x16x32_bf16 v[84:87], v[172:175], v[206:209], v[84:87]
	v_mfma_f32_16x16x32_bf16 v[80:83], v[180:183], v[206:209], v[80:83]
	v_mfma_f32_16x16x32_bf16 v[68:71], v[172:175], v[214:217], v[68:71]
	v_mfma_f32_16x16x32_bf16 v[64:67], v[180:183], v[214:217], v[64:67]
	s_setprio 0
	s_barrier
	s_add_i32 s58, s49, s15
	v_lshl_add_u64 v[218:219], s[40:41], 0, v[132:133]
	s_mov_b32 m0, s58
	ds_read_b128 v[184:187], v157 offset:16384
	ds_read_b128 v[188:191], v157 offset:17408
	ds_read_b128 v[192:195], v157 offset:18432
	ds_read_b128 v[196:199], v157 offset:19456
	ds_read_b128 v[200:203], v157 offset:20480
	ds_read_b128 v[206:209], v157 offset:21504
	ds_read_b128 v[210:213], v157 offset:22528
	ds_read_b128 v[214:217], v157 offset:23552
	global_load_lds_dwordx4 v[218:219], off
	s_add_i32 m0, s58, 0x2000
	s_add_u32 s58, s40, 0x40000
	v_lshl_add_u64 v[220:221], s[40:41], 0, v[128:129]
	s_addc_u32 s59, s41, 0
	s_add_i32 s60, s50, s15
	global_load_lds_dwordx4 v[220:221], off
	v_lshl_add_u64 v[222:223], s[58:59], 0, v[132:133]
	s_mov_b32 m0, s60
	global_load_lds_dwordx4 v[222:223], off
	v_lshl_add_u64 v[222:223], s[58:59], 0, v[128:129]
	s_add_i32 m0, s60, 0x2000
	s_nop 0
	global_load_lds_dwordx4 v[222:223], off
	s_waitcnt vmcnt(6)
	s_waitcnt lgkmcnt(0)
	s_barrier
	s_setprio 1
	s_waitcnt lgkmcnt(0)
	v_mfma_f32_16x16x32_bf16 v[60:63], v[144:147], v[184:187], v[60:63]
	v_mfma_f32_16x16x32_bf16 v[56:59], v[160:163], v[184:187], v[56:59]
	v_mfma_f32_16x16x32_bf16 v[44:47], v[144:147], v[192:195], v[44:47]
	v_mfma_f32_16x16x32_bf16 v[40:43], v[160:163], v[192:195], v[40:43]
	v_mfma_f32_16x16x32_bf16 v[28:31], v[144:147], v[200:203], v[28:31]
	v_mfma_f32_16x16x32_bf16 v[24:27], v[160:163], v[200:203], v[24:27]
	v_mfma_f32_16x16x32_bf16 v[12:15], v[144:147], v[210:213], v[12:15]
	v_mfma_f32_16x16x32_bf16 v[8:11], v[160:163], v[210:213], v[8:11]
	v_mfma_f32_16x16x32_bf16 v[60:63], v[148:151], v[188:191], v[60:63]
	v_mfma_f32_16x16x32_bf16 v[56:59], v[164:167], v[188:191], v[56:59]
	v_mfma_f32_16x16x32_bf16 v[44:47], v[148:151], v[196:199], v[44:47]
	v_mfma_f32_16x16x32_bf16 v[40:43], v[164:167], v[196:199], v[40:43]
	v_mfma_f32_16x16x32_bf16 v[28:31], v[148:151], v[206:209], v[28:31]
	v_mfma_f32_16x16x32_bf16 v[24:27], v[164:167], v[206:209], v[24:27]
	v_lshl_add_u64 v[222:223], s[42:43], 0, v[134:135]
	s_mov_b32 m0, s34
	s_nop 0
	global_load_lds_dwordx4 v[222:223], off
	v_mfma_f32_16x16x32_bf16 v[12:15], v[148:151], v[214:217], v[12:15]
	v_mfma_f32_16x16x32_bf16 v[8:11], v[164:167], v[214:217], v[8:11]
	s_setprio 0
	s_setprio 1
	v_mfma_f32_16x16x32_bf16 v[52:55], v[168:171], v[184:187], v[52:55]
	v_mfma_f32_16x16x32_bf16 v[48:51], v[176:179], v[184:187], v[48:51]
	v_mfma_f32_16x16x32_bf16 v[36:39], v[168:171], v[192:195], v[36:39]
	v_mfma_f32_16x16x32_bf16 v[32:35], v[176:179], v[192:195], v[32:35]
	v_mfma_f32_16x16x32_bf16 v[20:23], v[168:171], v[200:203], v[20:23]
	v_mfma_f32_16x16x32_bf16 v[16:19], v[176:179], v[200:203], v[16:19]
	v_mfma_f32_16x16x32_bf16 v[4:7], v[168:171], v[210:213], v[4:7]
	v_mfma_f32_16x16x32_bf16 v[0:3], v[176:179], v[210:213], v[0:3]
	v_mfma_f32_16x16x32_bf16 v[52:55], v[172:175], v[188:191], v[52:55]
	v_mfma_f32_16x16x32_bf16 v[48:51], v[180:183], v[188:191], v[48:51]
	v_mfma_f32_16x16x32_bf16 v[36:39], v[172:175], v[196:199], v[36:39]
	v_mfma_f32_16x16x32_bf16 v[32:35], v[180:183], v[196:199], v[32:35]
	v_mfma_f32_16x16x32_bf16 v[20:23], v[172:175], v[206:209], v[20:23]
	v_mfma_f32_16x16x32_bf16 v[16:19], v[180:183], v[206:209], v[16:19]
	v_lshl_add_u64 v[224:225], s[42:43], 0, v[130:131]
	s_mov_b32 m0, s37
	s_nop 0
	global_load_lds_dwordx4 v[224:225], off
	v_mfma_f32_16x16x32_bf16 v[4:7], v[172:175], v[214:217], v[4:7]
	v_mfma_f32_16x16x32_bf16 v[0:3], v[180:183], v[214:217], v[0:3]
	s_setprio 0
	s_barrier
; #define PG8_STAGE(bufoff, gbase, voff) do { _Pragma("unroll") for (int _i = 0; _i < 2; ++_i) \
;         __builtin_amdgcn_global_load_lds((const unsigned*)((const char*)(gbase) + (voff)[_i]), (PG8_LAS unsigned*)(lds + (bufoff) + ldsw + _i * 8192), 16, 0, 0); } while (0)
; #define PG8_LDA(dst, b, h) do { _Pragma("unroll") for (int m = 0; m < 4; ++m) _Pragma("unroll") for (int k = 0; k < 2; ++k) dst[m][k] = *(const PG8_LAS bf16x8*)(lds + PG8_SA(b, h) + aoff + m * 2048 + k * 1024); } while (0)
; #define PG8_LDB(dst, b, h) do { _Pragma("unroll") for (int n = 0; n < 2; ++n) _Pragma("unroll") for (int k = 0; k < 2; ++k) dst[n][k] = *(const PG8_LAS bf16x8*)(lds + PG8_SB(b, h) + boff + n * 2048 + k * 1024); } while (0)
; #define PG8_MMA(ai, bj, At, Bt) do { __builtin_amdgcn_s_setprio(1); _Pragma("unroll") for (int m = 0; m < 4; ++m) _Pragma("unroll") for (int n = 0; n < 2; ++n) _Pragma("unroll") for (int k = 0; k < 2; ++k) \
;         acc[ai][bj][m][n] = __builtin_amdgcn_mfma_f32_16x16x32_bf16(Bt[n][k], At[m][k], acc[ai][bj][m][n], 0, 0, 0); __builtin_amdgcn_s_setprio(0); } while (0)
; #define PG8_WAIT_V(n) asm volatile("s_waitcnt vmcnt(" #n ")" ::: "memory")
; template <class Epi, class Sched, bool ALIGN_EPI = false, bool SP2 = false>
; __device__ __forceinline__ void gemm_phase(PG8_LAS unsigned char* lds, const Gemm g, const Sched& S, const Epi& E) {
;     ...
;             PG8_LDB(B0, 0, 0); PG8_LDB(B1, 0, 1); PG8_SCHED; PG8_LDA(At, 0, 0); PG8_STAGE(PG8_SA(1, 1), a1 + hstep, voffA);
;             PG8_WAIT_V(8); PG8_WAIT_L(0); PG8_BAR; PG8_MMA(0, 0, At, B0); PG8_MMA(0, 1, At, B1); PG8_BAR; PG8_SCHED;
;             PG8_LDA(At, 0, 1); PG8_STAGE(PG8_SB(0, 0), b2, voffB); PG8_STAGE(PG8_SB(0, 1), b2 + hstep, voffB); PG8_STAGE(PG8_SA(0, 0), a2, voffA);
;             PG8_WAIT_V(8); PG8_WAIT_L(0); PG8_BAR; PG8_MMA(1, 0, At, B0); PG8_MMA(1, 1, At, B1); PG8_BAR; PG8_SCHED;
;             PG8_LDB(B0, 1, 0); PG8_LDB(B1, 1, 1); PG8_SCHED; PG8_LDA(At, 1, 0); PG8_STAGE(PG8_SA(0, 1), a2 + hstep, voffA);
;             PG8_WAIT_V(8); PG8_WAIT_L(0); PG8_BAR; PG8_MMA(0, 0, At, B0); PG8_MMA(0, 1, At, B1); PG8_BAR; PG8_SCHED;
;             PG8_LDA(At, 1, 1); PG8_STAGE(PG8_SB(1, 0), b3, voffB); PG8_STAGE(PG8_SB(1, 1), b3 + hstep, voffB); PG8_STAGE(PG8_SA(1, 0), a3, voffA);
;             PG8_WAIT_V(8); PG8_WAIT_L(0); PG8_BAR; PG8_MMA(1, 0, At, B0); PG8_MMA(1, 1, At, B1); PG8_BAR; PG8_SCHED;
	s_add_i32 s58, 0, 0x18000
	v_add_u32_e32 v159, s58, v153
	s_add_i32 s59, 0, 0x1c000
	ds_read_b128 v[144:147], v159
	ds_read_b128 v[148:151], v159 offset:1024
	ds_read_b128 v[160:163], v159 offset:2048
	ds_read_b128 v[164:167], v159 offset:3072
	v_add_u32_e32 v159, s59, v153
	ds_read_b128 v[168:171], v159
	ds_read_b128 v[172:175], v159 offset:1024
	ds_read_b128 v[176:179], v159 offset:2048
	ds_read_b128 v[180:183], v159 offset:3072
	s_add_u32 s42, s42, 0x40000
	s_addc_u32 s43, s43, 0
	s_mov_b32 m0, s44
	v_lshl_add_u64 v[226:227], s[42:43], 0, v[134:135]
	ds_read_b128 v[184:187], v157 offset:32768
	ds_read_b128 v[188:191], v157 offset:33792
	ds_read_b128 v[192:195], v157 offset:34816
	ds_read_b128 v[196:199], v157 offset:35840
	ds_read_b128 v[200:203], v157 offset:36864
	ds_read_b128 v[206:209], v157 offset:37888
	ds_read_b128 v[210:213], v157 offset:38912
	ds_read_b128 v[214:217], v157 offset:39936
	global_load_lds_dwordx4 v[226:227], off
	v_lshl_add_u64 v[226:227], s[42:43], 0, v[130:131]
	s_mov_b32 m0, s45
	s_nop 0
	global_load_lds_dwordx4 v[226:227], off
	s_waitcnt vmcnt(8)
	s_waitcnt lgkmcnt(0)
	s_barrier
	s_setprio 1
	s_waitcnt lgkmcnt(0)
	v_mfma_f32_16x16x32_bf16 v[124:127], v[144:147], v[184:187], v[124:127]
	v_mfma_f32_16x16x32_bf16 v[120:123], v[160:163], v[184:187], v[120:123]
	v_mfma_f32_16x16x32_bf16 v[108:111], v[144:147], v[192:195], v[108:111]
	v_mfma_f32_16x16x32_bf16 v[104:107], v[160:163], v[192:195], v[104:107]
	v_mfma_f32_16x16x32_bf16 v[92:95], v[144:147], v[200:203], v[92:95]
	v_mfma_f32_16x16x32_bf16 v[88:91], v[160:163], v[200:203], v[88:91]
	v_mfma_f32_16x16x32_bf16 v[76:79], v[144:147], v[210:213], v[76:79]
	v_mfma_f32_16x16x32_bf16 v[72:75], v[160:163], v[210:213], v[72:75]
	v_mfma_f32_16x16x32_bf16 v[124:127], v[148:151], v[188:191], v[124:127]
	v_mfma_f32_16x16x32_bf16 v[120:123], v[164:167], v[188:191], v[120:123]
	v_mfma_f32_16x16x32_bf16 v[108:111], v[148:151], v[196:199], v[108:111]
	v_mfma_f32_16x16x32_bf16 v[104:107], v[164:167], v[196:199], v[104:107]
	v_mfma_f32_16x16x32_bf16 v[92:95], v[148:151], v[206:209], v[92:95]
	v_mfma_f32_16x16x32_bf16 v[88:91], v[164:167], v[206:209], v[88:91]
	v_mfma_f32_16x16x32_bf16 v[76:79], v[148:151], v[214:217], v[76:79]
	v_mfma_f32_16x16x32_bf16 v[72:75], v[164:167], v[214:217], v[72:75]
	s_setprio 0
	s_setprio 1
	v_mfma_f32_16x16x32_bf16 v[116:119], v[168:171], v[184:187], v[116:119]
	v_mfma_f32_16x16x32_bf16 v[112:115], v[176:179], v[184:187], v[112:115]
	v_mfma_f32_16x16x32_bf16 v[100:103], v[168:171], v[192:195], v[100:103]
	v_mfma_f32_16x16x32_bf16 v[96:99], v[176:179], v[192:195], v[96:99]
	v_mfma_f32_16x16x32_bf16 v[84:87], v[168:171], v[200:203], v[84:87]
	v_mfma_f32_16x16x32_bf16 v[80:83], v[176:179], v[200:203], v[80:83]
	v_mfma_f32_16x16x32_bf16 v[68:71], v[168:171], v[210:213], v[68:71]
	v_mfma_f32_16x16x32_bf16 v[64:67], v[176:179], v[210:213], v[64:67]
	v_mfma_f32_16x16x32_bf16 v[116:119], v[172:175], v[188:191], v[116:119]
	v_mfma_f32_16x16x32_bf16 v[112:115], v[180:183], v[188:191], v[112:115]
	v_mfma_f32_16x16x32_bf16 v[100:103], v[172:175], v[196:199], v[100:103]
	v_mfma_f32_16x16x32_bf16 v[96:99], v[180:183], v[196:199], v[96:99]
	v_mfma_f32_16x16x32_bf16 v[84:87], v[172:175], v[206:209], v[84:87]
	v_mfma_f32_16x16x32_bf16 v[80:83], v[180:183], v[206:209], v[80:83]
	v_mfma_f32_16x16x32_bf16 v[68:71], v[172:175], v[214:217], v[68:71]
	v_mfma_f32_16x16x32_bf16 v[64:67], v[180:183], v[214:217], v[64:67]
	s_setprio 0
	s_barrier
	s_add_i32 s42, s58, s15
	v_lshl_add_u64 v[218:219], v[218:219], 0, s[8:9]
	s_mov_b32 m0, s42
	ds_read_b128 v[184:187], v157 offset:49152
	ds_read_b128 v[188:191], v157 offset:50176
	ds_read_b128 v[192:195], v157 offset:51200
	ds_read_b128 v[196:199], v157 offset:52224
	ds_read_b128 v[200:203], v157 offset:53248
	ds_read_b128 v[206:209], v157 offset:54272
	ds_read_b128 v[210:213], v157 offset:55296
	ds_read_b128 v[214:217], v157 offset:56320
	global_load_lds_dwordx4 v[218:219], off
	s_add_i32 m0, s42, 0x2000
	s_add_u32 s40, s40, 0x40080
	v_lshl_add_u64 v[218:219], v[220:221], 0, s[8:9]
	s_addc_u32 s41, s41, 0
	s_add_i32 s42, s59, s15
	global_load_lds_dwordx4 v[218:219], off
	v_lshl_add_u64 v[218:219], s[40:41], 0, v[132:133]
	s_mov_b32 m0, s42
	s_nop 0
	global_load_lds_dwordx4 v[218:219], off
	v_lshl_add_u64 v[218:219], s[40:41], 0, v[128:129]
	s_add_i32 m0, s42, 0x2000
	s_nop 0
	global_load_lds_dwordx4 v[218:219], off
	s_waitcnt vmcnt(6)
	s_waitcnt lgkmcnt(0)
	s_barrier
; __device__ __forceinline__ unsigned cvtpk(float lo, float hi) { f32x2v_ v = {lo, hi}; bf16x2v_ b = __builtin_convertvector(v, bf16x2v_); return __builtin_bit_cast(unsigned, b); }
; #define PG8_BAR __builtin_amdgcn_s_barrier()
;     __device__ __forceinline__ void operator()(const f32x4 (&acc)[2][2][4][2], const Unit& u, int wr, int wc, int fr, int fq) const {
;         const int row0 = u.pm * BM + wr * 64 + fr, col0 = u.pn * HALF + wc * 32 + 8 * fq;
; #pragma unroll
;         for (int ai = 0; ai < 2; ++ai)
; #pragma unroll
;             for (int m = 0; m < 4; ++m) { const int row = row0 + ai * HALF + m * 16; const float rs = row_rs(ss, row);
;                 float hv[8];
; #pragma unroll
;                 for (int n = 0; n < 2; ++n)
; #pragma unroll
;                     for (int i = 0; i < 4; ++i) { const float g = acc[ai][0][m][n][i] * rs, uu = acc[ai][1][m][n][i] * rs;
;                         hv[n * 4 + i] = g * __builtin_amdgcn_rcpf(1.0f + __expf(-g)) * uu; }
;                 u32x4 w; w.x = cvtpk(hv[0], hv[1]); w.y = cvtpk(hv[2], hv[3]); w.z = cvtpk(hv[4], hv[5]); w.w = cvtpk(hv[6], hv[7]);
;                 *(u32x4*)(H + (size_t)row * ldh + col0) = w; }
; template <class Epi, class Sched, bool ALIGN_EPI = false, bool SP2 = false>
; __device__ __forceinline__ void gemm_phase(PG8_LAS unsigned char* lds, const Gemm g, const Sched& S, const Epi& E) {
;     ...
;         if constexpr (ALIGN_EPI) { if (wr == 0) PG8_BAR; }
	s_setprio 1
	s_waitcnt lgkmcnt(0)
	v_mfma_f32_16x16x32_bf16 v[60:63], v[144:147], v[184:187], v[60:63]
	v_mfma_f32_16x16x32_bf16 v[56:59], v[160:163], v[184:187], v[56:59]
	v_mfma_f32_16x16x32_bf16 v[44:47], v[144:147], v[192:195], v[44:47]
	v_mfma_f32_16x16x32_bf16 v[40:43], v[160:163], v[192:195], v[40:43]
	v_mfma_f32_16x16x32_bf16 v[28:31], v[144:147], v[200:203], v[28:31]
	v_mfma_f32_16x16x32_bf16 v[24:27], v[160:163], v[200:203], v[24:27]
	v_mfma_f32_16x16x32_bf16 v[12:15], v[144:147], v[210:213], v[12:15]
	v_mfma_f32_16x16x32_bf16 v[8:11], v[160:163], v[210:213], v[8:11]
	v_mfma_f32_16x16x32_bf16 v[60:63], v[148:151], v[188:191], v[60:63]
	v_mfma_f32_16x16x32_bf16 v[56:59], v[164:167], v[188:191], v[56:59]
	v_mfma_f32_16x16x32_bf16 v[44:47], v[148:151], v[196:199], v[44:47]
	v_mfma_f32_16x16x32_bf16 v[40:43], v[164:167], v[196:199], v[40:43]
	v_mfma_f32_16x16x32_bf16 v[28:31], v[148:151], v[206:209], v[28:31]
	v_mfma_f32_16x16x32_bf16 v[24:27], v[164:167], v[206:209], v[24:27]
	v_lshl_add_u64 v[218:219], v[222:223], 0, s[8:9]
	s_mov_b32 m0, s47
	s_nop 0
	global_load_lds_dwordx4 v[218:219], off
	v_mfma_f32_16x16x32_bf16 v[12:15], v[148:151], v[214:217], v[12:15]
	v_mfma_f32_16x16x32_bf16 v[8:11], v[164:167], v[214:217], v[8:11]
	s_setprio 0
	s_setprio 1
	v_mfma_f32_16x16x32_bf16 v[52:55], v[168:171], v[184:187], v[52:55]
	v_mfma_f32_16x16x32_bf16 v[48:51], v[176:179], v[184:187], v[48:51]
	v_mfma_f32_16x16x32_bf16 v[36:39], v[168:171], v[192:195], v[36:39]
	v_mfma_f32_16x16x32_bf16 v[32:35], v[176:179], v[192:195], v[32:35]
	v_mfma_f32_16x16x32_bf16 v[20:23], v[168:171], v[200:203], v[20:23]
	v_mfma_f32_16x16x32_bf16 v[16:19], v[176:179], v[200:203], v[16:19]
	v_mfma_f32_16x16x32_bf16 v[4:7], v[168:171], v[210:213], v[4:7]
	v_mfma_f32_16x16x32_bf16 v[0:3], v[176:179], v[210:213], v[0:3]
	v_mfma_f32_16x16x32_bf16 v[52:55], v[172:175], v[188:191], v[52:55]
	v_mfma_f32_16x16x32_bf16 v[48:51], v[180:183], v[188:191], v[48:51]
	v_mfma_f32_16x16x32_bf16 v[36:39], v[172:175], v[196:199], v[36:39]
	v_mfma_f32_16x16x32_bf16 v[32:35], v[180:183], v[196:199], v[32:35]
	v_mfma_f32_16x16x32_bf16 v[20:23], v[172:175], v[206:209], v[20:23]
	v_mfma_f32_16x16x32_bf16 v[16:19], v[180:183], v[206:209], v[16:19]
	v_lshl_add_u64 v[218:219], v[224:225], 0, s[8:9]
	s_mov_b32 m0, s48
	s_nop 0
	global_load_lds_dwordx4 v[218:219], off
	v_mfma_f32_16x16x32_bf16 v[4:7], v[172:175], v[214:217], v[4:7]
	v_mfma_f32_16x16x32_bf16 v[0:3], v[180:183], v[214:217], v[0:3]
	s_setprio 0
	s_barrier
	s_add_i32 s57, s57, 2
	s_add_u32 s38, s38, 0x100
	s_addc_u32 s39, s39, 0
	s_add_u32 s55, s55, 0x100
	s_addc_u32 s56, s56, 0
	s_cmp_gt_u32 s57, 13
	s_cbranch_scc0 .LBB0_1900
	v_lshl_add_u32 v144, s36, 8, v152
	v_ashrrev_i32_e32 v145, 31, v144
	v_lshl_add_u64 v[150:151], v[144:145], 3, s[0:1]
	global_load_dwordx2 v[182:183], v[150:151], off
	global_load_dwordx2 v[184:185], v[150:151], off offset:128
	global_load_dwordx2 v[186:187], v[150:151], off offset:256
	global_load_dwordx2 v[188:189], v[150:151], off offset:384
	global_load_dwordx2 v[190:191], v[150:151], off offset:1024
	global_load_dwordx2 v[192:193], v[150:151], off offset:1152
	global_load_dwordx2 v[194:195], v[150:151], off offset:1280
	global_load_dwordx2 v[196:197], v[150:151], off offset:1408
	s_and_b64 vcc, exec, s[10:11]
	s_cbranch_vccz .LBB0_1903
.LBB0_1903:
	v_lshl_or_b32 v160, s52, 7, v154
	v_ashrrev_i32_e32 v161, 31, v160
	v_or_b32_e32 v164, 16, v144
	v_ashrrev_i32_e32 v165, 31, v164
	v_lshl_add_u64 v[166:167], v[164:165], 3, s[0:1]
	v_mov_b64_e32 v[146:147], s[20:21]
	v_mad_i64_i32 v[162:163], s[38:39], v144, s51, v[146:147]
	s_andn2_b64 vcc, exec, s[4:5]
	s_mov_b64 s[4:5], -1
	s_waitcnt vmcnt(7)
	v_cvt_f32_u32_e32 v159, v183
	v_cvt_f32_u32_e32 v145, v182
	v_lshlrev_b64 v[148:149], 1, v[160:161]
	v_lshl_add_u64 v[162:163], v[162:163], 0, v[148:149]
	v_fmamk_f32 v145, v145, 0x2f800000, v159
	v_fmamk_f32 v145, v145, 0x3a800000, v158
	v_rsq_f32_e32 v160, v145
	s_nop 0
	v_mul_f32_e32 v182, 0xbfb8aa3b, v160
	v_mul_f32_e32 v183, v160, v160
	v_pk_mul_f32 v[160:161], v[124:125], v[182:183] op_sel_hi:[1,0]
	v_pk_mul_f32 v[168:169], v[126:127], v[182:183] op_sel_hi:[1,0]
	v_pk_mul_f32 v[170:171], v[120:121], v[182:183] op_sel_hi:[1,0]
	v_pk_mul_f32 v[172:173], v[122:123], v[182:183] op_sel_hi:[1,0]
	v_pk_mul_f32 v[116:117], v[116:117], v[124:125]
	v_pk_mul_f32 v[118:119], v[118:119], v[126:127]
	v_pk_mul_f32 v[120:121], v[112:113], v[120:121]
	v_pk_mul_f32 v[122:123], v[114:115], v[122:123]
	v_exp_f32_e32 v160, v160
	v_exp_f32_e32 v161, v161
	v_exp_f32_e32 v168, v168
	v_exp_f32_e32 v169, v169
	v_exp_f32_e32 v170, v170
	v_exp_f32_e32 v171, v171
	v_exp_f32_e32 v172, v172
	v_exp_f32_e32 v173, v173
	v_pk_mul_f32 v[116:117], v[116:117], v[182:183] op_sel:[0,1] op_sel_hi:[1,1]
	v_pk_mul_f32 v[118:119], v[118:119], v[182:183] op_sel:[0,1] op_sel_hi:[1,1]
	v_pk_mul_f32 v[120:121], v[120:121], v[182:183] op_sel:[0,1] op_sel_hi:[1,1]
	v_pk_mul_f32 v[122:123], v[122:123], v[182:183] op_sel:[0,1] op_sel_hi:[1,1]
	v_pk_add_f32 v[160:161], v[160:161], 1.0 op_sel_hi:[1,0]
	v_pk_add_f32 v[168:169], v[168:169], 1.0 op_sel_hi:[1,0]
	v_pk_add_f32 v[170:171], v[170:171], 1.0 op_sel_hi:[1,0]
	v_pk_add_f32 v[172:173], v[172:173], 1.0 op_sel_hi:[1,0]
	v_rcp_f32_e32 v160, v160
	v_rcp_f32_e32 v161, v161
	v_rcp_f32_e32 v168, v168
	v_rcp_f32_e32 v169, v169
	v_rcp_f32_e32 v170, v170
	v_rcp_f32_e32 v171, v171
	v_rcp_f32_e32 v172, v172
	v_rcp_f32_e32 v173, v173
	v_pk_mul_f32 v[116:117], v[116:117], v[160:161]
	v_pk_mul_f32 v[118:119], v[118:119], v[168:169]
	v_pk_mul_f32 v[120:121], v[120:121], v[170:171]
	v_pk_mul_f32 v[122:123], v[122:123], v[172:173]
	v_cvt_pk_bf16_f32 v112, v116, v117
	v_cvt_pk_bf16_f32 v113, v118, v119
	v_cvt_pk_bf16_f32 v114, v120, v121
	v_cvt_pk_bf16_f32 v115, v122, v123
	global_store_dwordx4 v[162:163], v[112:115], off
	s_nop 0
	s_nop 0
	v_or_b32_e32 v114, 32, v144
	s_waitcnt vmcnt(7)
; __device__ __forceinline__ unsigned cvtpk(float lo, float hi) { f32x2v_ v = {lo, hi}; bf16x2v_ b = __builtin_convertvector(v, bf16x2v_); return __builtin_bit_cast(unsigned, b); }
;     __device__ __forceinline__ void operator()(const f32x4 (&acc)[2][2][4][2], const Unit& u, int wr, int wc, int fr, int fq) const {
;     ...
;             for (int m = 0; m < 4; ++m) { const int row = row0 + ai * HALF + m * 16; const float rs = row_rs(ss, row);
;                 float hv[8];
; #pragma unroll
;                 for (int n = 0; n < 2; ++n)
; #pragma unroll
;                     for (int i = 0; i < 4; ++i) { const float g = acc[ai][0][m][n][i] * rs, uu = acc[ai][1][m][n][i] * rs;
;                         hv[n * 4 + i] = g * __builtin_amdgcn_rcpf(1.0f + __expf(-g)) * uu; }
;                 u32x4 w; w.x = cvtpk(hv[0], hv[1]); w.y = cvtpk(hv[2], hv[3]); w.z = cvtpk(hv[4], hv[5]); w.w = cvtpk(hv[6], hv[7]);
;                 *(u32x4*)(H + (size_t)row * ldh + col0) = w; }
	v_cvt_f32_u32_e32 v116, v185
	v_cvt_f32_u32_e32 v115, v184
	v_mad_i64_i32 v[112:113], s[38:39], v164, s51, v[146:147]
	v_fmamk_f32 v115, v115, 0x2f800000, v116
	v_fmamk_f32 v115, v115, 0x3a800000, v158
	v_rsq_f32_e32 v116, v115
	v_ashrrev_i32_e32 v115, 31, v114
	v_lshl_add_u64 v[118:119], v[114:115], 3, s[0:1]
	v_lshl_add_u64 v[112:113], v[112:113], 0, v[148:149]
	v_mul_f32_e32 v184, 0xbfb8aa3b, v116
	v_mul_f32_e32 v185, v116, v116
	v_pk_mul_f32 v[116:117], v[108:109], v[184:185] op_sel_hi:[1,0]
	v_pk_mul_f32 v[120:121], v[110:111], v[184:185] op_sel_hi:[1,0]
	v_pk_mul_f32 v[122:123], v[104:105], v[184:185] op_sel_hi:[1,0]
	v_pk_mul_f32 v[124:125], v[106:107], v[184:185] op_sel_hi:[1,0]
	v_pk_mul_f32 v[100:101], v[100:101], v[108:109]
	v_pk_mul_f32 v[102:103], v[102:103], v[110:111]
	v_pk_mul_f32 v[104:105], v[96:97], v[104:105]
	v_pk_mul_f32 v[106:107], v[98:99], v[106:107]
	v_exp_f32_e32 v116, v116
	v_exp_f32_e32 v117, v117
	v_exp_f32_e32 v120, v120
	v_exp_f32_e32 v121, v121
	v_exp_f32_e32 v122, v122
	v_exp_f32_e32 v123, v123
	v_exp_f32_e32 v124, v124
	v_exp_f32_e32 v125, v125
	v_pk_mul_f32 v[100:101], v[100:101], v[184:185] op_sel:[0,1] op_sel_hi:[1,1]
	v_pk_mul_f32 v[102:103], v[102:103], v[184:185] op_sel:[0,1] op_sel_hi:[1,1]
	v_pk_mul_f32 v[104:105], v[104:105], v[184:185] op_sel:[0,1] op_sel_hi:[1,1]
	v_pk_mul_f32 v[106:107], v[106:107], v[184:185] op_sel:[0,1] op_sel_hi:[1,1]
	v_pk_add_f32 v[116:117], v[116:117], 1.0 op_sel_hi:[1,0]
	v_pk_add_f32 v[120:121], v[120:121], 1.0 op_sel_hi:[1,0]
	v_pk_add_f32 v[122:123], v[122:123], 1.0 op_sel_hi:[1,0]
	v_pk_add_f32 v[124:125], v[124:125], 1.0 op_sel_hi:[1,0]
	v_rcp_f32_e32 v116, v116
	v_rcp_f32_e32 v117, v117
	v_rcp_f32_e32 v120, v120
	v_rcp_f32_e32 v121, v121
	v_rcp_f32_e32 v122, v122
	v_rcp_f32_e32 v123, v123
	v_rcp_f32_e32 v124, v124
	v_rcp_f32_e32 v125, v125
	v_pk_mul_f32 v[100:101], v[100:101], v[116:117]
	v_pk_mul_f32 v[102:103], v[102:103], v[120:121]
	v_pk_mul_f32 v[104:105], v[104:105], v[122:123]
	v_pk_mul_f32 v[106:107], v[106:107], v[124:125]
	v_cvt_pk_bf16_f32 v96, v100, v101
	v_cvt_pk_bf16_f32 v97, v102, v103
	v_cvt_pk_bf16_f32 v98, v104, v105
	v_cvt_pk_bf16_f32 v99, v106, v107
	global_store_dwordx4 v[112:113], v[96:99], off
	s_nop 0
	s_nop 0
	v_or_b32_e32 v98, 48, v144
	s_waitcnt vmcnt(7)
	v_cvt_f32_u32_e32 v100, v187
	v_cvt_f32_u32_e32 v99, v186
	v_mad_i64_i32 v[96:97], s[38:39], v114, s51, v[146:147]
	v_fmamk_f32 v99, v99, 0x2f800000, v100
	v_fmamk_f32 v99, v99, 0x3a800000, v158
	v_rsq_f32_e32 v100, v99
	v_ashrrev_i32_e32 v99, 31, v98
	v_lshl_add_u64 v[102:103], v[98:99], 3, s[0:1]
	v_lshl_add_u64 v[96:97], v[96:97], 0, v[148:149]
	v_mul_f32_e32 v186, 0xbfb8aa3b, v100
	v_mul_f32_e32 v187, v100, v100
	v_pk_mul_f32 v[100:101], v[92:93], v[186:187] op_sel_hi:[1,0]
	v_pk_mul_f32 v[104:105], v[94:95], v[186:187] op_sel_hi:[1,0]
	v_pk_mul_f32 v[106:107], v[88:89], v[186:187] op_sel_hi:[1,0]
	v_pk_mul_f32 v[108:109], v[90:91], v[186:187] op_sel_hi:[1,0]
	v_pk_mul_f32 v[84:85], v[84:85], v[92:93]
	v_pk_mul_f32 v[86:87], v[86:87], v[94:95]
	v_pk_mul_f32 v[88:89], v[80:81], v[88:89]
	v_pk_mul_f32 v[90:91], v[82:83], v[90:91]
	v_exp_f32_e32 v100, v100
	v_exp_f32_e32 v101, v101
	v_exp_f32_e32 v104, v104
	v_exp_f32_e32 v105, v105
	v_exp_f32_e32 v106, v106
	v_exp_f32_e32 v107, v107
	v_exp_f32_e32 v108, v108
	v_exp_f32_e32 v109, v109
	v_pk_mul_f32 v[84:85], v[84:85], v[186:187] op_sel:[0,1] op_sel_hi:[1,1]
	v_pk_mul_f32 v[86:87], v[86:87], v[186:187] op_sel:[0,1] op_sel_hi:[1,1]
	v_pk_mul_f32 v[88:89], v[88:89], v[186:187] op_sel:[0,1] op_sel_hi:[1,1]
	v_pk_mul_f32 v[90:91], v[90:91], v[186:187] op_sel:[0,1] op_sel_hi:[1,1]
	v_pk_add_f32 v[100:101], v[100:101], 1.0 op_sel_hi:[1,0]
	v_pk_add_f32 v[104:105], v[104:105], 1.0 op_sel_hi:[1,0]
	v_pk_add_f32 v[106:107], v[106:107], 1.0 op_sel_hi:[1,0]
	v_pk_add_f32 v[108:109], v[108:109], 1.0 op_sel_hi:[1,0]
	v_rcp_f32_e32 v100, v100
	v_rcp_f32_e32 v101, v101
	v_rcp_f32_e32 v104, v104
	v_rcp_f32_e32 v105, v105
	v_rcp_f32_e32 v106, v106
	v_rcp_f32_e32 v107, v107
	v_rcp_f32_e32 v108, v108
	v_rcp_f32_e32 v109, v109
	v_pk_mul_f32 v[84:85], v[84:85], v[100:101]
	v_pk_mul_f32 v[86:87], v[86:87], v[104:105]
	v_pk_mul_f32 v[88:89], v[88:89], v[106:107]
	v_pk_mul_f32 v[90:91], v[90:91], v[108:109]
	v_cvt_pk_bf16_f32 v80, v84, v85
	v_cvt_pk_bf16_f32 v81, v86, v87
	v_cvt_pk_bf16_f32 v82, v88, v89
	v_cvt_pk_bf16_f32 v83, v90, v91
	global_store_dwordx4 v[96:97], v[80:83], off
	s_nop 0
	s_waitcnt vmcnt(7)
	v_cvt_f32_u32_e32 v80, v189
	v_cvt_f32_u32_e32 v81, v188
	v_mad_i64_i32 v[82:83], s[38:39], v98, s51, v[146:147]
	v_fmamk_f32 v80, v81, 0x2f800000, v80
	v_fmamk_f32 v80, v80, 0x3a800000, v158
	v_rsq_f32_e32 v80, v80
	v_lshl_add_u64 v[82:83], v[82:83], 0, v[148:149]
	v_mul_f32_e32 v188, 0xbfb8aa3b, v80
	v_mul_f32_e32 v189, v80, v80
	v_pk_mul_f32 v[80:81], v[76:77], v[188:189] op_sel_hi:[1,0]
	v_pk_mul_f32 v[84:85], v[78:79], v[188:189] op_sel_hi:[1,0]
	v_pk_mul_f32 v[86:87], v[72:73], v[188:189] op_sel_hi:[1,0]
	v_pk_mul_f32 v[88:89], v[74:75], v[188:189] op_sel_hi:[1,0]
	v_pk_mul_f32 v[68:69], v[68:69], v[76:77]
	v_pk_mul_f32 v[70:71], v[70:71], v[78:79]
	v_pk_mul_f32 v[72:73], v[64:65], v[72:73]
	v_pk_mul_f32 v[74:75], v[66:67], v[74:75]
	v_exp_f32_e32 v80, v80
	v_exp_f32_e32 v81, v81
	v_exp_f32_e32 v84, v84
	v_exp_f32_e32 v85, v85
	v_exp_f32_e32 v86, v86
	v_exp_f32_e32 v87, v87
	v_exp_f32_e32 v88, v88
	v_exp_f32_e32 v89, v89
	v_pk_mul_f32 v[68:69], v[68:69], v[188:189] op_sel:[0,1] op_sel_hi:[1,1]
	v_pk_mul_f32 v[70:71], v[70:71], v[188:189] op_sel:[0,1] op_sel_hi:[1,1]
	v_pk_mul_f32 v[72:73], v[72:73], v[188:189] op_sel:[0,1] op_sel_hi:[1,1]
	v_pk_mul_f32 v[74:75], v[74:75], v[188:189] op_sel:[0,1] op_sel_hi:[1,1]
	v_pk_add_f32 v[80:81], v[80:81], 1.0 op_sel_hi:[1,0]
	v_pk_add_f32 v[84:85], v[84:85], 1.0 op_sel_hi:[1,0]
	v_pk_add_f32 v[86:87], v[86:87], 1.0 op_sel_hi:[1,0]
	v_pk_add_f32 v[88:89], v[88:89], 1.0 op_sel_hi:[1,0]
	v_rcp_f32_e32 v80, v80
	v_rcp_f32_e32 v81, v81
	v_rcp_f32_e32 v84, v84
	v_rcp_f32_e32 v85, v85
	v_rcp_f32_e32 v86, v86
	v_rcp_f32_e32 v87, v87
	v_rcp_f32_e32 v88, v88
	v_rcp_f32_e32 v89, v89
	v_pk_mul_f32 v[68:69], v[68:69], v[80:81]
	v_pk_mul_f32 v[70:71], v[70:71], v[84:85]
	v_pk_mul_f32 v[72:73], v[72:73], v[86:87]
	v_pk_mul_f32 v[74:75], v[74:75], v[88:89]
	v_cvt_pk_bf16_f32 v64, v68, v69
	v_cvt_pk_bf16_f32 v65, v70, v71
	v_cvt_pk_bf16_f32 v66, v72, v73
	v_cvt_pk_bf16_f32 v67, v74, v75
	global_store_dwordx4 v[82:83], v[64:67], off
	s_nop 0
	s_waitcnt vmcnt(7)
; __device__ __forceinline__ unsigned cvtpk(float lo, float hi) { f32x2v_ v = {lo, hi}; bf16x2v_ b = __builtin_convertvector(v, bf16x2v_); return __builtin_bit_cast(unsigned, b); }
;     __device__ __forceinline__ void operator()(const f32x4 (&acc)[2][2][4][2], const Unit& u, int wr, int wc, int fr, int fq) const {
;     ...
;             for (int m = 0; m < 4; ++m) { const int row = row0 + ai * HALF + m * 16; const float rs = row_rs(ss, row);
;                 float hv[8];
; #pragma unroll
;                 for (int n = 0; n < 2; ++n)
; #pragma unroll
;                     for (int i = 0; i < 4; ++i) { const float g = acc[ai][0][m][n][i] * rs, uu = acc[ai][1][m][n][i] * rs;
;                         hv[n * 4 + i] = g * __builtin_amdgcn_rcpf(1.0f + __expf(-g)) * uu; }
;                 u32x4 w; w.x = cvtpk(hv[0], hv[1]); w.y = cvtpk(hv[2], hv[3]); w.z = cvtpk(hv[4], hv[5]); w.w = cvtpk(hv[6], hv[7]);
;                 *(u32x4*)(H + (size_t)row * ldh + col0) = w; }
	v_cvt_f32_u32_e32 v64, v191
	v_cvt_f32_u32_e32 v66, v190
	v_add_u32_e32 v65, 0x80, v144
	v_fmamk_f32 v64, v66, 0x2f800000, v64
	v_fmamk_f32 v64, v64, 0x3a800000, v158
	v_rsq_f32_e32 v64, v64
	v_mad_i64_i32 v[66:67], s[38:39], v65, s51, v[146:147]
	v_lshl_add_u64 v[66:67], v[66:67], 0, v[148:149]
	v_mul_f32_e32 v190, 0xbfb8aa3b, v64
	v_mul_f32_e32 v191, v64, v64
	v_pk_mul_f32 v[64:65], v[60:61], v[190:191] op_sel_hi:[1,0]
	v_pk_mul_f32 v[68:69], v[62:63], v[190:191] op_sel_hi:[1,0]
	v_pk_mul_f32 v[70:71], v[56:57], v[190:191] op_sel_hi:[1,0]
	v_pk_mul_f32 v[72:73], v[58:59], v[190:191] op_sel_hi:[1,0]
	v_pk_mul_f32 v[52:53], v[52:53], v[60:61]
	v_pk_mul_f32 v[54:55], v[54:55], v[62:63]
	v_pk_mul_f32 v[56:57], v[48:49], v[56:57]
	v_pk_mul_f32 v[58:59], v[50:51], v[58:59]
	v_exp_f32_e32 v64, v64
	v_exp_f32_e32 v65, v65
	v_exp_f32_e32 v68, v68
	v_exp_f32_e32 v69, v69
	v_exp_f32_e32 v70, v70
	v_exp_f32_e32 v71, v71
	v_exp_f32_e32 v72, v72
	v_exp_f32_e32 v73, v73
	v_pk_mul_f32 v[52:53], v[52:53], v[190:191] op_sel:[0,1] op_sel_hi:[1,1]
	v_pk_mul_f32 v[54:55], v[54:55], v[190:191] op_sel:[0,1] op_sel_hi:[1,1]
	v_pk_mul_f32 v[56:57], v[56:57], v[190:191] op_sel:[0,1] op_sel_hi:[1,1]
	v_pk_mul_f32 v[58:59], v[58:59], v[190:191] op_sel:[0,1] op_sel_hi:[1,1]
	v_pk_add_f32 v[64:65], v[64:65], 1.0 op_sel_hi:[1,0]
	v_pk_add_f32 v[68:69], v[68:69], 1.0 op_sel_hi:[1,0]
	v_pk_add_f32 v[70:71], v[70:71], 1.0 op_sel_hi:[1,0]
	v_pk_add_f32 v[72:73], v[72:73], 1.0 op_sel_hi:[1,0]
	v_rcp_f32_e32 v64, v64
	v_rcp_f32_e32 v65, v65
	v_rcp_f32_e32 v68, v68
	v_rcp_f32_e32 v69, v69
	v_rcp_f32_e32 v70, v70
	v_rcp_f32_e32 v71, v71
	v_rcp_f32_e32 v72, v72
	v_rcp_f32_e32 v73, v73
	v_pk_mul_f32 v[52:53], v[52:53], v[64:65]
	v_pk_mul_f32 v[54:55], v[54:55], v[68:69]
	v_pk_mul_f32 v[56:57], v[56:57], v[70:71]
	v_pk_mul_f32 v[58:59], v[58:59], v[72:73]
	v_cvt_pk_bf16_f32 v48, v52, v53
	v_cvt_pk_bf16_f32 v49, v54, v55
	v_cvt_pk_bf16_f32 v50, v56, v57
	v_cvt_pk_bf16_f32 v51, v58, v59
	global_store_dwordx4 v[66:67], v[48:51], off
	s_nop 0
	s_waitcnt vmcnt(7)
	v_cvt_f32_u32_e32 v48, v193
	v_cvt_f32_u32_e32 v50, v192
	v_add_u32_e32 v49, 0x90, v144
	v_fmamk_f32 v48, v50, 0x2f800000, v48
	v_fmamk_f32 v48, v48, 0x3a800000, v158
	v_rsq_f32_e32 v48, v48
	v_mad_i64_i32 v[50:51], s[38:39], v49, s51, v[146:147]
	v_lshl_add_u64 v[50:51], v[50:51], 0, v[148:149]
	v_mul_f32_e32 v192, 0xbfb8aa3b, v48
	v_mul_f32_e32 v193, v48, v48
	v_pk_mul_f32 v[48:49], v[44:45], v[192:193] op_sel_hi:[1,0]
	v_pk_mul_f32 v[52:53], v[46:47], v[192:193] op_sel_hi:[1,0]
	v_pk_mul_f32 v[54:55], v[40:41], v[192:193] op_sel_hi:[1,0]
	v_pk_mul_f32 v[56:57], v[42:43], v[192:193] op_sel_hi:[1,0]
	v_pk_mul_f32 v[36:37], v[36:37], v[44:45]
	v_pk_mul_f32 v[38:39], v[38:39], v[46:47]
	v_pk_mul_f32 v[40:41], v[32:33], v[40:41]
	v_pk_mul_f32 v[42:43], v[34:35], v[42:43]
	v_exp_f32_e32 v48, v48
	v_exp_f32_e32 v49, v49
	v_exp_f32_e32 v52, v52
	v_exp_f32_e32 v53, v53
	v_exp_f32_e32 v54, v54
	v_exp_f32_e32 v55, v55
	v_exp_f32_e32 v56, v56
	v_exp_f32_e32 v57, v57
	v_pk_mul_f32 v[36:37], v[36:37], v[192:193] op_sel:[0,1] op_sel_hi:[1,1]
	v_pk_mul_f32 v[38:39], v[38:39], v[192:193] op_sel:[0,1] op_sel_hi:[1,1]
	v_pk_mul_f32 v[40:41], v[40:41], v[192:193] op_sel:[0,1] op_sel_hi:[1,1]
	v_pk_mul_f32 v[42:43], v[42:43], v[192:193] op_sel:[0,1] op_sel_hi:[1,1]
	v_pk_add_f32 v[48:49], v[48:49], 1.0 op_sel_hi:[1,0]
	v_pk_add_f32 v[52:53], v[52:53], 1.0 op_sel_hi:[1,0]
	v_pk_add_f32 v[54:55], v[54:55], 1.0 op_sel_hi:[1,0]
	v_pk_add_f32 v[56:57], v[56:57], 1.0 op_sel_hi:[1,0]
	v_rcp_f32_e32 v48, v48
	v_rcp_f32_e32 v49, v49
	v_rcp_f32_e32 v52, v52
	v_rcp_f32_e32 v53, v53
	v_rcp_f32_e32 v54, v54
	v_rcp_f32_e32 v55, v55
	v_rcp_f32_e32 v56, v56
	v_rcp_f32_e32 v57, v57
	v_pk_mul_f32 v[36:37], v[36:37], v[48:49]
	v_pk_mul_f32 v[38:39], v[38:39], v[52:53]
	v_pk_mul_f32 v[40:41], v[40:41], v[54:55]
	v_pk_mul_f32 v[42:43], v[42:43], v[56:57]
	v_cvt_pk_bf16_f32 v32, v36, v37
	v_cvt_pk_bf16_f32 v33, v38, v39
	v_cvt_pk_bf16_f32 v34, v40, v41
	v_cvt_pk_bf16_f32 v35, v42, v43
	global_store_dwordx4 v[50:51], v[32:35], off
	s_nop 0
	s_waitcnt vmcnt(7)
; __device__ __forceinline__ unsigned cvtpk(float lo, float hi) { f32x2v_ v = {lo, hi}; bf16x2v_ b = __builtin_convertvector(v, bf16x2v_); return __builtin_bit_cast(unsigned, b); }
; #define PG8_BAR __builtin_amdgcn_s_barrier()
;     __device__ __forceinline__ void operator()(const f32x4 (&acc)[2][2][4][2], const Unit& u, int wr, int wc, int fr, int fq) const {
;     ...
;             for (int m = 0; m < 4; ++m) { const int row = row0 + ai * HALF + m * 16; const float rs = row_rs(ss, row);
;                 float hv[8];
; #pragma unroll
;                 for (int n = 0; n < 2; ++n)
; #pragma unroll
;                     for (int i = 0; i < 4; ++i) { const float g = acc[ai][0][m][n][i] * rs, uu = acc[ai][1][m][n][i] * rs;
;                         hv[n * 4 + i] = g * __builtin_amdgcn_rcpf(1.0f + __expf(-g)) * uu; }
;                 u32x4 w; w.x = cvtpk(hv[0], hv[1]); w.y = cvtpk(hv[2], hv[3]); w.z = cvtpk(hv[4], hv[5]); w.w = cvtpk(hv[6], hv[7]);
;                 *(u32x4*)(H + (size_t)row * ldh + col0) = w; }
; template <class Epi, class Sched, bool ALIGN_EPI = false, bool SP2 = false>
; __device__ __forceinline__ void gemm_phase(PG8_LAS unsigned char* lds, const Gemm g, const Sched& S, const Epi& E) {
;     ...
;         if constexpr (ALIGN_EPI) { if (wr == 0) PG8_BAR; }
;         if constexpr (!Epi::AFTER_DRAIN) { E(acc, cur, wr, wc, fr, fq); S.done(cur); }
;         if (!has_next) break;
	v_cvt_f32_u32_e32 v32, v195
	v_cvt_f32_u32_e32 v34, v194
	v_add_u32_e32 v33, 0xa0, v144
	v_fmamk_f32 v32, v34, 0x2f800000, v32
	v_fmamk_f32 v32, v32, 0x3a800000, v158
	v_rsq_f32_e32 v32, v32
	v_mad_i64_i32 v[34:35], s[38:39], v33, s51, v[146:147]
	v_lshl_add_u64 v[34:35], v[34:35], 0, v[148:149]
	v_mul_f32_e32 v194, 0xbfb8aa3b, v32
	v_mul_f32_e32 v195, v32, v32
	v_pk_mul_f32 v[32:33], v[28:29], v[194:195] op_sel_hi:[1,0]
	v_pk_mul_f32 v[36:37], v[30:31], v[194:195] op_sel_hi:[1,0]
	v_pk_mul_f32 v[38:39], v[24:25], v[194:195] op_sel_hi:[1,0]
	v_pk_mul_f32 v[40:41], v[26:27], v[194:195] op_sel_hi:[1,0]
	v_pk_mul_f32 v[20:21], v[20:21], v[28:29]
	v_pk_mul_f32 v[22:23], v[22:23], v[30:31]
	v_pk_mul_f32 v[24:25], v[16:17], v[24:25]
	v_pk_mul_f32 v[26:27], v[18:19], v[26:27]
	v_exp_f32_e32 v32, v32
	v_exp_f32_e32 v33, v33
	v_exp_f32_e32 v36, v36
	v_exp_f32_e32 v37, v37
	v_exp_f32_e32 v38, v38
	v_exp_f32_e32 v39, v39
	v_exp_f32_e32 v40, v40
	v_exp_f32_e32 v41, v41
	v_pk_mul_f32 v[20:21], v[20:21], v[194:195] op_sel:[0,1] op_sel_hi:[1,1]
	v_pk_mul_f32 v[22:23], v[22:23], v[194:195] op_sel:[0,1] op_sel_hi:[1,1]
	v_pk_mul_f32 v[24:25], v[24:25], v[194:195] op_sel:[0,1] op_sel_hi:[1,1]
	v_pk_mul_f32 v[26:27], v[26:27], v[194:195] op_sel:[0,1] op_sel_hi:[1,1]
	v_pk_add_f32 v[32:33], v[32:33], 1.0 op_sel_hi:[1,0]
	v_pk_add_f32 v[36:37], v[36:37], 1.0 op_sel_hi:[1,0]
	v_pk_add_f32 v[38:39], v[38:39], 1.0 op_sel_hi:[1,0]
	v_pk_add_f32 v[40:41], v[40:41], 1.0 op_sel_hi:[1,0]
	v_rcp_f32_e32 v32, v32
	v_rcp_f32_e32 v33, v33
	v_rcp_f32_e32 v36, v36
	v_rcp_f32_e32 v37, v37
	v_rcp_f32_e32 v38, v38
	v_rcp_f32_e32 v39, v39
	v_rcp_f32_e32 v40, v40
	v_rcp_f32_e32 v41, v41
	v_pk_mul_f32 v[20:21], v[20:21], v[32:33]
	v_pk_mul_f32 v[22:23], v[22:23], v[36:37]
	v_pk_mul_f32 v[24:25], v[24:25], v[38:39]
	v_pk_mul_f32 v[26:27], v[26:27], v[40:41]
	v_cvt_pk_bf16_f32 v16, v20, v21
	v_cvt_pk_bf16_f32 v17, v22, v23
	v_cvt_pk_bf16_f32 v18, v24, v25
	v_cvt_pk_bf16_f32 v19, v26, v27
	global_store_dwordx4 v[34:35], v[16:19], off
	s_nop 0
	s_waitcnt vmcnt(7)
	v_cvt_f32_u32_e32 v16, v197
	v_cvt_f32_u32_e32 v18, v196
	v_add_u32_e32 v17, 0xb0, v144
	v_fmamk_f32 v16, v18, 0x2f800000, v16
	v_fmamk_f32 v16, v16, 0x3a800000, v158
	v_rsq_f32_e32 v16, v16
	v_mad_i64_i32 v[18:19], s[38:39], v17, s51, v[146:147]
	v_lshl_add_u64 v[18:19], v[18:19], 0, v[148:149]
	v_mul_f32_e32 v196, 0xbfb8aa3b, v16
	v_mul_f32_e32 v197, v16, v16
	v_pk_mul_f32 v[16:17], v[12:13], v[196:197] op_sel_hi:[1,0]
	v_pk_mul_f32 v[20:21], v[14:15], v[196:197] op_sel_hi:[1,0]
	v_pk_mul_f32 v[22:23], v[8:9], v[196:197] op_sel_hi:[1,0]
	v_pk_mul_f32 v[24:25], v[10:11], v[196:197] op_sel_hi:[1,0]
	v_pk_mul_f32 v[4:5], v[4:5], v[12:13]
	v_pk_mul_f32 v[6:7], v[6:7], v[14:15]
	v_pk_mul_f32 v[8:9], v[0:1], v[8:9]
	v_pk_mul_f32 v[10:11], v[2:3], v[10:11]
	v_exp_f32_e32 v16, v16
	v_exp_f32_e32 v17, v17
	v_exp_f32_e32 v20, v20
	v_exp_f32_e32 v21, v21
	v_exp_f32_e32 v22, v22
	v_exp_f32_e32 v23, v23
	v_exp_f32_e32 v24, v24
	v_exp_f32_e32 v25, v25
	v_pk_mul_f32 v[4:5], v[4:5], v[196:197] op_sel:[0,1] op_sel_hi:[1,1]
	v_pk_mul_f32 v[6:7], v[6:7], v[196:197] op_sel:[0,1] op_sel_hi:[1,1]
	v_pk_mul_f32 v[8:9], v[8:9], v[196:197] op_sel:[0,1] op_sel_hi:[1,1]
	v_pk_mul_f32 v[10:11], v[10:11], v[196:197] op_sel:[0,1] op_sel_hi:[1,1]
	v_pk_add_f32 v[16:17], v[16:17], 1.0 op_sel_hi:[1,0]
	v_pk_add_f32 v[20:21], v[20:21], 1.0 op_sel_hi:[1,0]
	v_pk_add_f32 v[22:23], v[22:23], 1.0 op_sel_hi:[1,0]
	v_pk_add_f32 v[24:25], v[24:25], 1.0 op_sel_hi:[1,0]
	v_rcp_f32_e32 v16, v16
	v_rcp_f32_e32 v17, v17
	v_rcp_f32_e32 v20, v20
	v_rcp_f32_e32 v21, v21
	v_rcp_f32_e32 v22, v22
	v_rcp_f32_e32 v23, v23
	v_rcp_f32_e32 v24, v24
	v_rcp_f32_e32 v25, v25
	v_pk_mul_f32 v[4:5], v[4:5], v[16:17]
	v_pk_mul_f32 v[6:7], v[6:7], v[20:21]
	v_pk_mul_f32 v[8:9], v[8:9], v[22:23]
	v_pk_mul_f32 v[10:11], v[10:11], v[24:25]
	v_cvt_pk_bf16_f32 v0, v4, v5
	v_cvt_pk_bf16_f32 v1, v6, v7
	v_cvt_pk_bf16_f32 v2, v8, v9
	v_cvt_pk_bf16_f32 v3, v10, v11
	global_store_dwordx4 v[18:19], v[0:3], off
	s_cmp_eq_u64 s[10:11], 0
	s_cbranch_scc1 .Lxpost_12
	s_barrier
.Lxpost_12:
	s_cbranch_vccnz .LBB0_1896
	s_andn2_b64 vcc, exec, s[6:7]
	s_cbranch_vccnz .LBB0_1895
	s_barrier
	s_branch .LBB0_1895

; #define PG8_STAGE(bufoff, gbase, voff) do { _Pragma("unroll") for (int _i = 0; _i < 2; ++_i) \
;         __builtin_amdgcn_global_load_lds((const unsigned*)((const char*)(gbase) + (voff)[_i]), (PG8_LAS unsigned*)(lds + (bufoff) + ldsw + _i * 8192), 16, 0, 0); } while (0)
; #define PG8_LDA(dst, b, h) do { _Pragma("unroll") for (int m = 0; m < 4; ++m) _Pragma("unroll") for (int k = 0; k < 2; ++k) dst[m][k] = *(const PG8_LAS bf16x8*)(lds + PG8_SA(b, h) + aoff + m * 2048 + k * 1024); } while (0)
; #define PG8_LDB(dst, b, h) do { _Pragma("unroll") for (int n = 0; n < 2; ++n) _Pragma("unroll") for (int k = 0; k < 2; ++k) dst[n][k] = *(const PG8_LAS bf16x8*)(lds + PG8_SB(b, h) + boff + n * 2048 + k * 1024); } while (0)
; #define PG8_MMA(ai, bj, At, Bt) do { __builtin_amdgcn_s_setprio(1); _Pragma("unroll") for (int m = 0; m < 4; ++m) _Pragma("unroll") for (int n = 0; n < 2; ++n) _Pragma("unroll") for (int k = 0; k < 2; ++k) \
;         acc[ai][bj][m][n] = __builtin_amdgcn_mfma_f32_16x16x32_bf16(Bt[n][k], At[m][k], acc[ai][bj][m][n], 0, 0, 0); __builtin_amdgcn_s_setprio(0); } while (0)
; #define PG8_WAIT_V(n) asm volatile("s_waitcnt vmcnt(" #n ")" ::: "memory")
; template <class Epi, class Sched, bool ALIGN_EPI = false, bool SP2 = false>
; __device__ __forceinline__ void gemm_phase(PG8_LAS unsigned char* lds, const Gemm g, const Sched& S, const Epi& E) {
;     ...
;             PG8_LDB(B0, 0, 0); PG8_LDB(B1, 0, 1); PG8_SCHED; PG8_LDA(At, 0, 0); PG8_STAGE(PG8_SA(1, 1), a1 + hstep, voffA);
;             PG8_WAIT_V(8); PG8_WAIT_L(0); PG8_BAR; PG8_MMA(0, 0, At, B0); PG8_MMA(0, 1, At, B1); PG8_BAR; PG8_SCHED;
;             PG8_LDA(At, 0, 1); PG8_STAGE(PG8_SB(0, 0), b2, voffB); PG8_STAGE(PG8_SB(0, 1), b2 + hstep, voffB); PG8_STAGE(PG8_SA(0, 0), a2, voffA);
;             PG8_WAIT_V(8); PG8_WAIT_L(0); PG8_BAR; PG8_MMA(1, 0, At, B0); PG8_MMA(1, 1, At, B1); PG8_BAR; PG8_SCHED;
;             PG8_LDB(B0, 1, 0); PG8_LDB(B1, 1, 1); PG8_SCHED; PG8_LDA(At, 1, 0); PG8_STAGE(PG8_SA(0, 1), a2 + hstep, voffA);
;             PG8_WAIT_V(8); PG8_WAIT_L(0); PG8_BAR; PG8_MMA(0, 0, At, B0); PG8_MMA(0, 1, At, B1); PG8_BAR; PG8_SCHED;
;             PG8_LDA(At, 1, 1); PG8_STAGE(PG8_SB(1, 0), b3, voffB); PG8_STAGE(PG8_SB(1, 1), b3 + hstep, voffB); PG8_STAGE(PG8_SA(1, 0), a3, voffA);
;             PG8_WAIT_V(8); PG8_WAIT_L(0); PG8_BAR; PG8_MMA(1, 0, At, B0); PG8_MMA(1, 1, At, B1); PG8_BAR; PG8_SCHED;
.LBB0_1977:
	s_add_u32 s53, s28, 0x100
	s_addc_u32 s54, s29, 0
	s_mov_b32 s55, -2
	s_waitcnt lgkmcnt(0)
	ds_read_b128 v[144:147], v151
	ds_read_b128 v[156:159], v151 offset:1024
	ds_read_b128 v[160:163], v151 offset:2048
	ds_read_b128 v[164:167], v151 offset:3072
	ds_read_b128 v[168:171], v152
	ds_read_b128 v[172:175], v152 offset:1024
	ds_read_b128 v[176:179], v152 offset:2048
	ds_read_b128 v[180:183], v152 offset:3072
	s_add_u32 s28, s26, 0x100
	s_addc_u32 s29, s27, 0
	s_cmp_eq_u32 s55, 40
	s_cselect_b32 s39, s1, s29
	s_cselect_b32 s38, s0, s28
	s_cselect_b32 s37, s25, s54
	s_cselect_b32 s36, s24, s53
	v_lshl_add_u64 v[218:219], s[26:27], 0, v[136:137]
	s_add_i32 m0, s33, 0xc000
	ds_read_b128 v[184:187], v153
	ds_read_b128 v[188:191], v153 offset:1024
	ds_read_b128 v[192:195], v153 offset:2048
	ds_read_b128 v[196:199], v153 offset:3072
	ds_read_b128 v[200:203], v153 offset:4096
	ds_read_b128 v[206:209], v153 offset:5120
	ds_read_b128 v[210:213], v153 offset:6144
	ds_read_b128 v[214:217], v153 offset:7168
	global_load_lds_dwordx4 v[218:219], off
	v_lshl_add_u64 v[218:219], s[26:27], 0, v[138:139]
	s_add_i32 m0, s33, 0xe000
	s_nop 0
	global_load_lds_dwordx4 v[218:219], off
	s_waitcnt vmcnt(8)
	s_waitcnt lgkmcnt(0)
	s_barrier
	s_setprio 1
	s_waitcnt lgkmcnt(0)
	v_mfma_f32_16x16x32_bf16 v[124:127], v[144:147], v[184:187], 0
	v_mfma_f32_16x16x32_bf16 v[120:123], v[160:163], v[184:187], 0
	v_mfma_f32_16x16x32_bf16 v[108:111], v[144:147], v[192:195], 0
	v_mfma_f32_16x16x32_bf16 v[104:107], v[160:163], v[192:195], 0
	v_mfma_f32_16x16x32_bf16 v[92:95], v[144:147], v[200:203], 0
	v_mfma_f32_16x16x32_bf16 v[88:91], v[160:163], v[200:203], 0
	v_mfma_f32_16x16x32_bf16 v[76:79], v[144:147], v[210:213], 0
	v_mfma_f32_16x16x32_bf16 v[72:75], v[160:163], v[210:213], 0
	v_mfma_f32_16x16x32_bf16 v[124:127], v[156:159], v[188:191], v[124:127]
	v_mfma_f32_16x16x32_bf16 v[120:123], v[164:167], v[188:191], v[120:123]
	v_mfma_f32_16x16x32_bf16 v[108:111], v[156:159], v[196:199], v[108:111]
	v_mfma_f32_16x16x32_bf16 v[104:107], v[164:167], v[196:199], v[104:107]
	v_mfma_f32_16x16x32_bf16 v[92:95], v[156:159], v[206:209], v[92:95]
	v_mfma_f32_16x16x32_bf16 v[88:91], v[164:167], v[206:209], v[88:91]
	v_mfma_f32_16x16x32_bf16 v[76:79], v[156:159], v[214:217], v[76:79]
	v_mfma_f32_16x16x32_bf16 v[72:75], v[164:167], v[214:217], v[72:75]
	s_setprio 0
	s_setprio 1
	v_mfma_f32_16x16x32_bf16 v[116:119], v[168:171], v[184:187], 0
	v_mfma_f32_16x16x32_bf16 v[112:115], v[176:179], v[184:187], 0
	v_mfma_f32_16x16x32_bf16 v[100:103], v[168:171], v[192:195], 0
	v_mfma_f32_16x16x32_bf16 v[96:99], v[176:179], v[192:195], 0
	v_mfma_f32_16x16x32_bf16 v[84:87], v[168:171], v[200:203], 0
	v_mfma_f32_16x16x32_bf16 v[80:83], v[176:179], v[200:203], 0
	v_mfma_f32_16x16x32_bf16 v[68:71], v[168:171], v[210:213], 0
	v_mfma_f32_16x16x32_bf16 v[64:67], v[176:179], v[210:213], 0
	v_mfma_f32_16x16x32_bf16 v[116:119], v[172:175], v[188:191], v[116:119]
	v_mfma_f32_16x16x32_bf16 v[112:115], v[180:183], v[188:191], v[112:115]
	v_mfma_f32_16x16x32_bf16 v[100:103], v[172:175], v[196:199], v[100:103]
	v_mfma_f32_16x16x32_bf16 v[96:99], v[180:183], v[196:199], v[96:99]
	v_mfma_f32_16x16x32_bf16 v[84:87], v[172:175], v[206:209], v[84:87]
	v_mfma_f32_16x16x32_bf16 v[80:83], v[180:183], v[206:209], v[80:83]
	v_mfma_f32_16x16x32_bf16 v[68:71], v[172:175], v[214:217], v[68:71]
	v_mfma_f32_16x16x32_bf16 v[64:67], v[180:183], v[214:217], v[64:67]
	s_setprio 0
	s_barrier
	s_add_i32 s26, s45, s15
	v_lshl_add_u64 v[218:219], s[36:37], 0, v[130:131]
	s_mov_b32 m0, s26
	ds_read_b128 v[184:187], v153 offset:16384
	ds_read_b128 v[188:191], v153 offset:17408
	ds_read_b128 v[192:195], v153 offset:18432
	ds_read_b128 v[196:199], v153 offset:19456
	ds_read_b128 v[200:203], v153 offset:20480
	ds_read_b128 v[206:209], v153 offset:21504
	ds_read_b128 v[210:213], v153 offset:22528
	ds_read_b128 v[214:217], v153 offset:23552
	global_load_lds_dwordx4 v[218:219], off
	s_add_i32 m0, s26, 0x2000
	s_add_u32 s26, s36, 0xb0000
	v_lshl_add_u64 v[220:221], s[36:37], 0, v[134:135]
	s_addc_u32 s27, s37, 0
	s_add_i32 s56, s46, s15
	global_load_lds_dwordx4 v[220:221], off
	v_lshl_add_u64 v[222:223], s[26:27], 0, v[130:131]
	s_mov_b32 m0, s56
	global_load_lds_dwordx4 v[222:223], off
	v_lshl_add_u64 v[222:223], s[26:27], 0, v[134:135]
	s_add_i32 m0, s56, 0x2000
	s_nop 0
	global_load_lds_dwordx4 v[222:223], off
	s_waitcnt vmcnt(6)
	s_waitcnt lgkmcnt(0)
	s_barrier
; #define PG8_STAGE(bufoff, gbase, voff) do { _Pragma("unroll") for (int _i = 0; _i < 2; ++_i) \
;         __builtin_amdgcn_global_load_lds((const unsigned*)((const char*)(gbase) + (voff)[_i]), (PG8_LAS unsigned*)(lds + (bufoff) + ldsw + _i * 8192), 16, 0, 0); } while (0)
; #define PG8_LDA(dst, b, h) do { _Pragma("unroll") for (int m = 0; m < 4; ++m) _Pragma("unroll") for (int k = 0; k < 2; ++k) dst[m][k] = *(const PG8_LAS bf16x8*)(lds + PG8_SA(b, h) + aoff + m * 2048 + k * 1024); } while (0)
; #define PG8_LDB(dst, b, h) do { _Pragma("unroll") for (int n = 0; n < 2; ++n) _Pragma("unroll") for (int k = 0; k < 2; ++k) dst[n][k] = *(const PG8_LAS bf16x8*)(lds + PG8_SB(b, h) + boff + n * 2048 + k * 1024); } while (0)
; #define PG8_MMA(ai, bj, At, Bt) do { __builtin_amdgcn_s_setprio(1); _Pragma("unroll") for (int m = 0; m < 4; ++m) _Pragma("unroll") for (int n = 0; n < 2; ++n) _Pragma("unroll") for (int k = 0; k < 2; ++k) \
;         acc[ai][bj][m][n] = __builtin_amdgcn_mfma_f32_16x16x32_bf16(Bt[n][k], At[m][k], acc[ai][bj][m][n], 0, 0, 0); __builtin_amdgcn_s_setprio(0); } while (0)
; #define PG8_WAIT_V(n) asm volatile("s_waitcnt vmcnt(" #n ")" ::: "memory")
; template <class Epi, class Sched, bool ALIGN_EPI = false, bool SP2 = false>
; __device__ __forceinline__ void gemm_phase(PG8_LAS unsigned char* lds, const Gemm g, const Sched& S, const Epi& E) {
;     ...
;             PG8_LDB(B0, 0, 0); PG8_LDB(B1, 0, 1); PG8_SCHED; PG8_LDA(At, 0, 0); PG8_STAGE(PG8_SA(1, 1), a1 + hstep, voffA);
;             PG8_WAIT_V(8); PG8_WAIT_L(0); PG8_BAR; PG8_MMA(0, 0, At, B0); PG8_MMA(0, 1, At, B1); PG8_BAR; PG8_SCHED;
;             PG8_LDA(At, 0, 1); PG8_STAGE(PG8_SB(0, 0), b2, voffB); PG8_STAGE(PG8_SB(0, 1), b2 + hstep, voffB); PG8_STAGE(PG8_SA(0, 0), a2, voffA);
;             PG8_WAIT_V(8); PG8_WAIT_L(0); PG8_BAR; PG8_MMA(1, 0, At, B0); PG8_MMA(1, 1, At, B1); PG8_BAR; PG8_SCHED;
;             PG8_LDB(B0, 1, 0); PG8_LDB(B1, 1, 1); PG8_SCHED; PG8_LDA(At, 1, 0); PG8_STAGE(PG8_SA(0, 1), a2 + hstep, voffA);
;             PG8_WAIT_V(8); PG8_WAIT_L(0); PG8_BAR; PG8_MMA(0, 0, At, B0); PG8_MMA(0, 1, At, B1); PG8_BAR; PG8_SCHED;
;             PG8_LDA(At, 1, 1); PG8_STAGE(PG8_SB(1, 0), b3, voffB); PG8_STAGE(PG8_SB(1, 1), b3 + hstep, voffB); PG8_STAGE(PG8_SA(1, 0), a3, voffA);
;             PG8_WAIT_V(8); PG8_WAIT_L(0); PG8_BAR; PG8_MMA(1, 0, At, B0); PG8_MMA(1, 1, At, B1); PG8_BAR; PG8_SCHED;
	s_setprio 1
	s_waitcnt lgkmcnt(0)
	v_mfma_f32_16x16x32_bf16 v[60:63], v[144:147], v[184:187], 0
	v_mfma_f32_16x16x32_bf16 v[56:59], v[160:163], v[184:187], 0
	v_mfma_f32_16x16x32_bf16 v[44:47], v[144:147], v[192:195], 0
	v_mfma_f32_16x16x32_bf16 v[40:43], v[160:163], v[192:195], 0
	v_mfma_f32_16x16x32_bf16 v[28:31], v[144:147], v[200:203], 0
	v_mfma_f32_16x16x32_bf16 v[24:27], v[160:163], v[200:203], 0
	v_mfma_f32_16x16x32_bf16 v[12:15], v[144:147], v[210:213], 0
	v_mfma_f32_16x16x32_bf16 v[8:11], v[160:163], v[210:213], 0
	v_mfma_f32_16x16x32_bf16 v[60:63], v[156:159], v[188:191], v[60:63]
	v_mfma_f32_16x16x32_bf16 v[56:59], v[164:167], v[188:191], v[56:59]
	v_mfma_f32_16x16x32_bf16 v[44:47], v[156:159], v[196:199], v[44:47]
	v_mfma_f32_16x16x32_bf16 v[40:43], v[164:167], v[196:199], v[40:43]
	v_mfma_f32_16x16x32_bf16 v[28:31], v[156:159], v[206:209], v[28:31]
	v_mfma_f32_16x16x32_bf16 v[24:27], v[164:167], v[206:209], v[24:27]
	v_lshl_add_u64 v[222:223], s[38:39], 0, v[128:129]
	s_mov_b32 m0, s33
	s_nop 0
	global_load_lds_dwordx4 v[222:223], off
	v_mfma_f32_16x16x32_bf16 v[12:15], v[156:159], v[214:217], v[12:15]
	v_mfma_f32_16x16x32_bf16 v[8:11], v[164:167], v[214:217], v[8:11]
	s_setprio 0
	s_setprio 1
	v_mfma_f32_16x16x32_bf16 v[52:55], v[168:171], v[184:187], 0
	v_mfma_f32_16x16x32_bf16 v[48:51], v[176:179], v[184:187], 0
	v_mfma_f32_16x16x32_bf16 v[36:39], v[168:171], v[192:195], 0
	v_mfma_f32_16x16x32_bf16 v[32:35], v[176:179], v[192:195], 0
	v_mfma_f32_16x16x32_bf16 v[20:23], v[168:171], v[200:203], 0
	v_mfma_f32_16x16x32_bf16 v[16:19], v[176:179], v[200:203], 0
	v_mfma_f32_16x16x32_bf16 v[4:7], v[168:171], v[210:213], 0
	v_mfma_f32_16x16x32_bf16 v[0:3], v[176:179], v[210:213], 0
	v_mfma_f32_16x16x32_bf16 v[52:55], v[172:175], v[188:191], v[52:55]
	v_mfma_f32_16x16x32_bf16 v[48:51], v[180:183], v[188:191], v[48:51]
	v_mfma_f32_16x16x32_bf16 v[36:39], v[172:175], v[196:199], v[36:39]
	v_mfma_f32_16x16x32_bf16 v[32:35], v[180:183], v[196:199], v[32:35]
	v_mfma_f32_16x16x32_bf16 v[20:23], v[172:175], v[206:209], v[20:23]
	v_mfma_f32_16x16x32_bf16 v[16:19], v[180:183], v[206:209], v[16:19]
	v_lshl_add_u64 v[224:225], s[38:39], 0, v[132:133]
	s_mov_b32 m0, s34
	s_nop 0
	global_load_lds_dwordx4 v[224:225], off
	v_mfma_f32_16x16x32_bf16 v[4:7], v[172:175], v[214:217], v[4:7]
	v_mfma_f32_16x16x32_bf16 v[0:3], v[180:183], v[214:217], v[0:3]
	s_setprio 0
	s_barrier
	s_add_i32 s56, 0, 0x18000
	v_add_u32_e32 v155, s56, v149
	s_add_i32 s57, 0, 0x1c000
	ds_read_b128 v[144:147], v155
	ds_read_b128 v[156:159], v155 offset:1024
	ds_read_b128 v[160:163], v155 offset:2048
	ds_read_b128 v[164:167], v155 offset:3072
	v_add_u32_e32 v155, s57, v149
	ds_read_b128 v[168:171], v155
	ds_read_b128 v[172:175], v155 offset:1024
	ds_read_b128 v[176:179], v155 offset:2048
	ds_read_b128 v[180:183], v155 offset:3072
	s_add_u32 s26, s38, 0xb0000
	s_addc_u32 s27, s39, 0
	s_mov_b32 m0, s40
	v_lshl_add_u64 v[226:227], s[26:27], 0, v[128:129]
	ds_read_b128 v[184:187], v153 offset:32768
	ds_read_b128 v[188:191], v153 offset:33792
	ds_read_b128 v[192:195], v153 offset:34816
	ds_read_b128 v[196:199], v153 offset:35840
	ds_read_b128 v[200:203], v153 offset:36864
	ds_read_b128 v[206:209], v153 offset:37888
	ds_read_b128 v[210:213], v153 offset:38912
	ds_read_b128 v[214:217], v153 offset:39936
	global_load_lds_dwordx4 v[226:227], off
	v_lshl_add_u64 v[226:227], s[26:27], 0, v[132:133]
	s_mov_b32 m0, s41
	s_nop 0
	global_load_lds_dwordx4 v[226:227], off
	s_waitcnt vmcnt(8)
	s_waitcnt lgkmcnt(0)
	s_barrier
	s_setprio 1
	s_waitcnt lgkmcnt(0)
	v_mfma_f32_16x16x32_bf16 v[124:127], v[144:147], v[184:187], v[124:127]
	v_mfma_f32_16x16x32_bf16 v[120:123], v[160:163], v[184:187], v[120:123]
	v_mfma_f32_16x16x32_bf16 v[108:111], v[144:147], v[192:195], v[108:111]
	v_mfma_f32_16x16x32_bf16 v[104:107], v[160:163], v[192:195], v[104:107]
	v_mfma_f32_16x16x32_bf16 v[92:95], v[144:147], v[200:203], v[92:95]
	v_mfma_f32_16x16x32_bf16 v[88:91], v[160:163], v[200:203], v[88:91]
	v_mfma_f32_16x16x32_bf16 v[76:79], v[144:147], v[210:213], v[76:79]
	v_mfma_f32_16x16x32_bf16 v[72:75], v[160:163], v[210:213], v[72:75]
	v_mfma_f32_16x16x32_bf16 v[124:127], v[156:159], v[188:191], v[124:127]
	v_mfma_f32_16x16x32_bf16 v[120:123], v[164:167], v[188:191], v[120:123]
	v_mfma_f32_16x16x32_bf16 v[108:111], v[156:159], v[196:199], v[108:111]
	v_mfma_f32_16x16x32_bf16 v[104:107], v[164:167], v[196:199], v[104:107]
	v_mfma_f32_16x16x32_bf16 v[92:95], v[156:159], v[206:209], v[92:95]
	v_mfma_f32_16x16x32_bf16 v[88:91], v[164:167], v[206:209], v[88:91]
	v_mfma_f32_16x16x32_bf16 v[76:79], v[156:159], v[214:217], v[76:79]
	v_mfma_f32_16x16x32_bf16 v[72:75], v[164:167], v[214:217], v[72:75]
	s_setprio 0
	s_setprio 1
	v_mfma_f32_16x16x32_bf16 v[116:119], v[168:171], v[184:187], v[116:119]
	v_mfma_f32_16x16x32_bf16 v[112:115], v[176:179], v[184:187], v[112:115]
	v_mfma_f32_16x16x32_bf16 v[100:103], v[168:171], v[192:195], v[100:103]
	v_mfma_f32_16x16x32_bf16 v[96:99], v[176:179], v[192:195], v[96:99]
	v_mfma_f32_16x16x32_bf16 v[84:87], v[168:171], v[200:203], v[84:87]
	v_mfma_f32_16x16x32_bf16 v[80:83], v[176:179], v[200:203], v[80:83]
	v_mfma_f32_16x16x32_bf16 v[68:71], v[168:171], v[210:213], v[68:71]
	v_mfma_f32_16x16x32_bf16 v[64:67], v[176:179], v[210:213], v[64:67]
	v_mfma_f32_16x16x32_bf16 v[116:119], v[172:175], v[188:191], v[116:119]
	v_mfma_f32_16x16x32_bf16 v[112:115], v[180:183], v[188:191], v[112:115]
	v_mfma_f32_16x16x32_bf16 v[100:103], v[172:175], v[196:199], v[100:103]
	v_mfma_f32_16x16x32_bf16 v[96:99], v[180:183], v[196:199], v[96:99]
	v_mfma_f32_16x16x32_bf16 v[84:87], v[172:175], v[206:209], v[84:87]
	v_mfma_f32_16x16x32_bf16 v[80:83], v[180:183], v[206:209], v[80:83]
	v_mfma_f32_16x16x32_bf16 v[68:71], v[172:175], v[214:217], v[68:71]
	v_mfma_f32_16x16x32_bf16 v[64:67], v[180:183], v[214:217], v[64:67]
	s_setprio 0
	s_barrier
; #define PG8_STAGE(bufoff, gbase, voff) do { _Pragma("unroll") for (int _i = 0; _i < 2; ++_i) \
;         __builtin_amdgcn_global_load_lds((const unsigned*)((const char*)(gbase) + (voff)[_i]), (PG8_LAS unsigned*)(lds + (bufoff) + ldsw + _i * 8192), 16, 0, 0); } while (0)
; #define PG8_LDA(dst, b, h) do { _Pragma("unroll") for (int m = 0; m < 4; ++m) _Pragma("unroll") for (int k = 0; k < 2; ++k) dst[m][k] = *(const PG8_LAS bf16x8*)(lds + PG8_SA(b, h) + aoff + m * 2048 + k * 1024); } while (0)
; #define PG8_LDB(dst, b, h) do { _Pragma("unroll") for (int n = 0; n < 2; ++n) _Pragma("unroll") for (int k = 0; k < 2; ++k) dst[n][k] = *(const PG8_LAS bf16x8*)(lds + PG8_SB(b, h) + boff + n * 2048 + k * 1024); } while (0)
; #define PG8_MMA(ai, bj, At, Bt) do { __builtin_amdgcn_s_setprio(1); _Pragma("unroll") for (int m = 0; m < 4; ++m) _Pragma("unroll") for (int n = 0; n < 2; ++n) _Pragma("unroll") for (int k = 0; k < 2; ++k) \
;         acc[ai][bj][m][n] = __builtin_amdgcn_mfma_f32_16x16x32_bf16(Bt[n][k], At[m][k], acc[ai][bj][m][n], 0, 0, 0); __builtin_amdgcn_s_setprio(0); } while (0)
; #define PG8_WAIT_V(n) asm volatile("s_waitcnt vmcnt(" #n ")" ::: "memory")
; template <class Epi, class Sched, bool ALIGN_EPI = false, bool SP2 = false>
; __device__ __forceinline__ void gemm_phase(PG8_LAS unsigned char* lds, const Gemm g, const Sched& S, const Epi& E) {
;     ...
;             PG8_LDB(B0, 0, 0); PG8_LDB(B1, 0, 1); PG8_SCHED; PG8_LDA(At, 0, 0); PG8_STAGE(PG8_SA(1, 1), a1 + hstep, voffA);
;             PG8_WAIT_V(8); PG8_WAIT_L(0); PG8_BAR; PG8_MMA(0, 0, At, B0); PG8_MMA(0, 1, At, B1); PG8_BAR; PG8_SCHED;
;             PG8_LDA(At, 0, 1); PG8_STAGE(PG8_SB(0, 0), b2, voffB); PG8_STAGE(PG8_SB(0, 1), b2 + hstep, voffB); PG8_STAGE(PG8_SA(0, 0), a2, voffA);
;             PG8_WAIT_V(8); PG8_WAIT_L(0); PG8_BAR; PG8_MMA(1, 0, At, B0); PG8_MMA(1, 1, At, B1); PG8_BAR; PG8_SCHED;
;             PG8_LDB(B0, 1, 0); PG8_LDB(B1, 1, 1); PG8_SCHED; PG8_LDA(At, 1, 0); PG8_STAGE(PG8_SA(0, 1), a2 + hstep, voffA);
;             PG8_WAIT_V(8); PG8_WAIT_L(0); PG8_BAR; PG8_MMA(0, 0, At, B0); PG8_MMA(0, 1, At, B1); PG8_BAR; PG8_SCHED;
;             PG8_LDA(At, 1, 1); PG8_STAGE(PG8_SB(1, 0), b3, voffB); PG8_STAGE(PG8_SB(1, 1), b3 + hstep, voffB); PG8_STAGE(PG8_SA(1, 0), a3, voffA);
;             PG8_WAIT_V(8); PG8_WAIT_L(0); PG8_BAR; PG8_MMA(1, 0, At, B0); PG8_MMA(1, 1, At, B1); PG8_BAR; PG8_SCHED;
	s_add_i32 s26, s56, s15
	v_lshl_add_u64 v[218:219], v[218:219], 0, s[12:13]
	s_mov_b32 m0, s26
	ds_read_b128 v[184:187], v153 offset:49152
	ds_read_b128 v[188:191], v153 offset:50176
	ds_read_b128 v[192:195], v153 offset:51200
	ds_read_b128 v[196:199], v153 offset:52224
	ds_read_b128 v[200:203], v153 offset:53248
	ds_read_b128 v[206:209], v153 offset:54272
	ds_read_b128 v[210:213], v153 offset:55296
	ds_read_b128 v[214:217], v153 offset:56320
	global_load_lds_dwordx4 v[218:219], off
	s_add_i32 m0, s26, 0x2000
	s_add_u32 s26, s36, 0xb0080
	v_lshl_add_u64 v[218:219], v[220:221], 0, s[12:13]
	s_addc_u32 s27, s37, 0
	s_add_i32 s36, s57, s15
	global_load_lds_dwordx4 v[218:219], off
	v_lshl_add_u64 v[218:219], s[26:27], 0, v[130:131]
	s_mov_b32 m0, s36
	s_nop 0
	global_load_lds_dwordx4 v[218:219], off
	v_lshl_add_u64 v[218:219], s[26:27], 0, v[134:135]
	s_add_i32 m0, s36, 0x2000
	s_nop 0
	global_load_lds_dwordx4 v[218:219], off
	s_waitcnt vmcnt(6)
	s_waitcnt lgkmcnt(0)
	s_barrier
	s_setprio 1
	s_waitcnt lgkmcnt(0)
	v_mfma_f32_16x16x32_bf16 v[60:63], v[144:147], v[184:187], v[60:63]
	v_mfma_f32_16x16x32_bf16 v[56:59], v[160:163], v[184:187], v[56:59]
	v_mfma_f32_16x16x32_bf16 v[44:47], v[144:147], v[192:195], v[44:47]
	v_mfma_f32_16x16x32_bf16 v[40:43], v[160:163], v[192:195], v[40:43]
	v_mfma_f32_16x16x32_bf16 v[28:31], v[144:147], v[200:203], v[28:31]
	v_mfma_f32_16x16x32_bf16 v[24:27], v[160:163], v[200:203], v[24:27]
	v_mfma_f32_16x16x32_bf16 v[12:15], v[144:147], v[210:213], v[12:15]
	v_mfma_f32_16x16x32_bf16 v[8:11], v[160:163], v[210:213], v[8:11]
	v_mfma_f32_16x16x32_bf16 v[60:63], v[156:159], v[188:191], v[60:63]
	v_mfma_f32_16x16x32_bf16 v[56:59], v[164:167], v[188:191], v[56:59]
	v_mfma_f32_16x16x32_bf16 v[44:47], v[156:159], v[196:199], v[44:47]
	v_mfma_f32_16x16x32_bf16 v[40:43], v[164:167], v[196:199], v[40:43]
	v_mfma_f32_16x16x32_bf16 v[28:31], v[156:159], v[206:209], v[28:31]
	v_mfma_f32_16x16x32_bf16 v[24:27], v[164:167], v[206:209], v[24:27]
	v_lshl_add_u64 v[218:219], v[222:223], 0, s[12:13]
	s_mov_b32 m0, s43
	s_nop 0
	global_load_lds_dwordx4 v[218:219], off
	v_mfma_f32_16x16x32_bf16 v[12:15], v[156:159], v[214:217], v[12:15]
	v_mfma_f32_16x16x32_bf16 v[8:11], v[164:167], v[214:217], v[8:11]
	s_setprio 0
	s_setprio 1
	v_mfma_f32_16x16x32_bf16 v[52:55], v[168:171], v[184:187], v[52:55]
	v_mfma_f32_16x16x32_bf16 v[48:51], v[176:179], v[184:187], v[48:51]
	v_mfma_f32_16x16x32_bf16 v[36:39], v[168:171], v[192:195], v[36:39]
	v_mfma_f32_16x16x32_bf16 v[32:35], v[176:179], v[192:195], v[32:35]
	v_mfma_f32_16x16x32_bf16 v[20:23], v[168:171], v[200:203], v[20:23]
	v_mfma_f32_16x16x32_bf16 v[16:19], v[176:179], v[200:203], v[16:19]
	v_mfma_f32_16x16x32_bf16 v[4:7], v[168:171], v[210:213], v[4:7]
	v_mfma_f32_16x16x32_bf16 v[0:3], v[176:179], v[210:213], v[0:3]
	v_mfma_f32_16x16x32_bf16 v[52:55], v[172:175], v[188:191], v[52:55]
	v_mfma_f32_16x16x32_bf16 v[48:51], v[180:183], v[188:191], v[48:51]
	v_mfma_f32_16x16x32_bf16 v[36:39], v[172:175], v[196:199], v[36:39]
	v_mfma_f32_16x16x32_bf16 v[32:35], v[180:183], v[196:199], v[32:35]
	v_mfma_f32_16x16x32_bf16 v[20:23], v[172:175], v[206:209], v[20:23]
	v_mfma_f32_16x16x32_bf16 v[16:19], v[180:183], v[206:209], v[16:19]
	v_lshl_add_u64 v[218:219], v[224:225], 0, s[12:13]
	s_mov_b32 m0, s44
	s_nop 0
	global_load_lds_dwordx4 v[218:219], off
	v_mfma_f32_16x16x32_bf16 v[4:7], v[172:175], v[214:217], v[4:7]
	v_mfma_f32_16x16x32_bf16 v[0:3], v[180:183], v[214:217], v[0:3]
	s_setprio 0
	s_barrier
	s_add_i32 s55, s55, 2
	s_add_u32 s53, s53, 0x100
	s_addc_u32 s54, s54, 0
	s_mov_b64 s[26:27], s[28:29]
.LBB0_1978:
	ds_read_b128 v[144:147], v151
	ds_read_b128 v[156:159], v151 offset:1024
	ds_read_b128 v[160:163], v151 offset:2048
	ds_read_b128 v[164:167], v151 offset:3072
	ds_read_b128 v[168:171], v152
	ds_read_b128 v[172:175], v152 offset:1024
	ds_read_b128 v[176:179], v152 offset:2048
	ds_read_b128 v[180:183], v152 offset:3072
	s_add_u32 s28, s26, 0x100
	s_addc_u32 s29, s27, 0
	s_cmp_eq_u32 s55, 40
	s_cselect_b32 s39, s1, s29
	s_cselect_b32 s38, s0, s28
	s_cselect_b32 s37, s25, s54
	s_cselect_b32 s36, s24, s53
	v_lshl_add_u64 v[218:219], s[26:27], 0, v[136:137]
	s_add_i32 m0, s33, 0xc000
	ds_read_b128 v[184:187], v153
	ds_read_b128 v[188:191], v153 offset:1024
	ds_read_b128 v[192:195], v153 offset:2048
	ds_read_b128 v[196:199], v153 offset:3072
	ds_read_b128 v[200:203], v153 offset:4096
	ds_read_b128 v[206:209], v153 offset:5120
	ds_read_b128 v[210:213], v153 offset:6144
	ds_read_b128 v[214:217], v153 offset:7168
	global_load_lds_dwordx4 v[218:219], off
	v_lshl_add_u64 v[218:219], s[26:27], 0, v[138:139]
	s_add_i32 m0, s33, 0xe000
	s_nop 0
	global_load_lds_dwordx4 v[218:219], off
	s_waitcnt vmcnt(8)
	s_waitcnt lgkmcnt(0)
	s_barrier
; #define PG8_STAGE(bufoff, gbase, voff) do { _Pragma("unroll") for (int _i = 0; _i < 2; ++_i) \
;         __builtin_amdgcn_global_load_lds((const unsigned*)((const char*)(gbase) + (voff)[_i]), (PG8_LAS unsigned*)(lds + (bufoff) + ldsw + _i * 8192), 16, 0, 0); } while (0)
; #define PG8_LDA(dst, b, h) do { _Pragma("unroll") for (int m = 0; m < 4; ++m) _Pragma("unroll") for (int k = 0; k < 2; ++k) dst[m][k] = *(const PG8_LAS bf16x8*)(lds + PG8_SA(b, h) + aoff + m * 2048 + k * 1024); } while (0)
; #define PG8_LDB(dst, b, h) do { _Pragma("unroll") for (int n = 0; n < 2; ++n) _Pragma("unroll") for (int k = 0; k < 2; ++k) dst[n][k] = *(const PG8_LAS bf16x8*)(lds + PG8_SB(b, h) + boff + n * 2048 + k * 1024); } while (0)
; #define PG8_MMA(ai, bj, At, Bt) do { __builtin_amdgcn_s_setprio(1); _Pragma("unroll") for (int m = 0; m < 4; ++m) _Pragma("unroll") for (int n = 0; n < 2; ++n) _Pragma("unroll") for (int k = 0; k < 2; ++k) \
;         acc[ai][bj][m][n] = __builtin_amdgcn_mfma_f32_16x16x32_bf16(Bt[n][k], At[m][k], acc[ai][bj][m][n], 0, 0, 0); __builtin_amdgcn_s_setprio(0); } while (0)
; #define PG8_WAIT_V(n) asm volatile("s_waitcnt vmcnt(" #n ")" ::: "memory")
; template <class Epi, class Sched, bool ALIGN_EPI = false, bool SP2 = false>
; __device__ __forceinline__ void gemm_phase(PG8_LAS unsigned char* lds, const Gemm g, const Sched& S, const Epi& E) {
;     ...
;             PG8_LDB(B0, 0, 0); PG8_LDB(B1, 0, 1); PG8_SCHED; PG8_LDA(At, 0, 0); PG8_STAGE(PG8_SA(1, 1), a1 + hstep, voffA);
;             PG8_WAIT_V(8); PG8_WAIT_L(0); PG8_BAR; PG8_MMA(0, 0, At, B0); PG8_MMA(0, 1, At, B1); PG8_BAR; PG8_SCHED;
;             PG8_LDA(At, 0, 1); PG8_STAGE(PG8_SB(0, 0), b2, voffB); PG8_STAGE(PG8_SB(0, 1), b2 + hstep, voffB); PG8_STAGE(PG8_SA(0, 0), a2, voffA);
;             PG8_WAIT_V(8); PG8_WAIT_L(0); PG8_BAR; PG8_MMA(1, 0, At, B0); PG8_MMA(1, 1, At, B1); PG8_BAR; PG8_SCHED;
;             PG8_LDB(B0, 1, 0); PG8_LDB(B1, 1, 1); PG8_SCHED; PG8_LDA(At, 1, 0); PG8_STAGE(PG8_SA(0, 1), a2 + hstep, voffA);
;             PG8_WAIT_V(8); PG8_WAIT_L(0); PG8_BAR; PG8_MMA(0, 0, At, B0); PG8_MMA(0, 1, At, B1); PG8_BAR; PG8_SCHED;
;             PG8_LDA(At, 1, 1); PG8_STAGE(PG8_SB(1, 0), b3, voffB); PG8_STAGE(PG8_SB(1, 1), b3 + hstep, voffB); PG8_STAGE(PG8_SA(1, 0), a3, voffA);
;             PG8_WAIT_V(8); PG8_WAIT_L(0); PG8_BAR; PG8_MMA(1, 0, At, B0); PG8_MMA(1, 1, At, B1); PG8_BAR; PG8_SCHED;
	s_setprio 1
	s_waitcnt lgkmcnt(0)
	v_mfma_f32_16x16x32_bf16 v[124:127], v[144:147], v[184:187], v[124:127]
	v_mfma_f32_16x16x32_bf16 v[120:123], v[160:163], v[184:187], v[120:123]
	v_mfma_f32_16x16x32_bf16 v[108:111], v[144:147], v[192:195], v[108:111]
	v_mfma_f32_16x16x32_bf16 v[104:107], v[160:163], v[192:195], v[104:107]
	v_mfma_f32_16x16x32_bf16 v[92:95], v[144:147], v[200:203], v[92:95]
	v_mfma_f32_16x16x32_bf16 v[88:91], v[160:163], v[200:203], v[88:91]
	v_mfma_f32_16x16x32_bf16 v[76:79], v[144:147], v[210:213], v[76:79]
	v_mfma_f32_16x16x32_bf16 v[72:75], v[160:163], v[210:213], v[72:75]
	v_mfma_f32_16x16x32_bf16 v[124:127], v[156:159], v[188:191], v[124:127]
	v_mfma_f32_16x16x32_bf16 v[120:123], v[164:167], v[188:191], v[120:123]
	v_mfma_f32_16x16x32_bf16 v[108:111], v[156:159], v[196:199], v[108:111]
	v_mfma_f32_16x16x32_bf16 v[104:107], v[164:167], v[196:199], v[104:107]
	v_mfma_f32_16x16x32_bf16 v[92:95], v[156:159], v[206:209], v[92:95]
	v_mfma_f32_16x16x32_bf16 v[88:91], v[164:167], v[206:209], v[88:91]
	v_mfma_f32_16x16x32_bf16 v[76:79], v[156:159], v[214:217], v[76:79]
	v_mfma_f32_16x16x32_bf16 v[72:75], v[164:167], v[214:217], v[72:75]
	s_setprio 0
	s_setprio 1
	v_mfma_f32_16x16x32_bf16 v[116:119], v[168:171], v[184:187], v[116:119]
	v_mfma_f32_16x16x32_bf16 v[112:115], v[176:179], v[184:187], v[112:115]
	v_mfma_f32_16x16x32_bf16 v[100:103], v[168:171], v[192:195], v[100:103]
	v_mfma_f32_16x16x32_bf16 v[96:99], v[176:179], v[192:195], v[96:99]
	v_mfma_f32_16x16x32_bf16 v[84:87], v[168:171], v[200:203], v[84:87]
	v_mfma_f32_16x16x32_bf16 v[80:83], v[176:179], v[200:203], v[80:83]
	v_mfma_f32_16x16x32_bf16 v[68:71], v[168:171], v[210:213], v[68:71]
	v_mfma_f32_16x16x32_bf16 v[64:67], v[176:179], v[210:213], v[64:67]
	v_mfma_f32_16x16x32_bf16 v[116:119], v[172:175], v[188:191], v[116:119]
	v_mfma_f32_16x16x32_bf16 v[112:115], v[180:183], v[188:191], v[112:115]
	v_mfma_f32_16x16x32_bf16 v[100:103], v[172:175], v[196:199], v[100:103]
	v_mfma_f32_16x16x32_bf16 v[96:99], v[180:183], v[196:199], v[96:99]
	v_mfma_f32_16x16x32_bf16 v[84:87], v[172:175], v[206:209], v[84:87]
	v_mfma_f32_16x16x32_bf16 v[80:83], v[180:183], v[206:209], v[80:83]
	v_mfma_f32_16x16x32_bf16 v[68:71], v[172:175], v[214:217], v[68:71]
	v_mfma_f32_16x16x32_bf16 v[64:67], v[180:183], v[214:217], v[64:67]
	s_setprio 0
	s_barrier
	s_add_i32 s26, s45, s15
	v_lshl_add_u64 v[218:219], s[36:37], 0, v[130:131]
	s_mov_b32 m0, s26
	ds_read_b128 v[184:187], v153 offset:16384
	ds_read_b128 v[188:191], v153 offset:17408
	ds_read_b128 v[192:195], v153 offset:18432
	ds_read_b128 v[196:199], v153 offset:19456
	ds_read_b128 v[200:203], v153 offset:20480
	ds_read_b128 v[206:209], v153 offset:21504
	ds_read_b128 v[210:213], v153 offset:22528
	ds_read_b128 v[214:217], v153 offset:23552
	global_load_lds_dwordx4 v[218:219], off
	s_add_i32 m0, s26, 0x2000
	s_add_u32 s26, s36, 0xb0000
	v_lshl_add_u64 v[220:221], s[36:37], 0, v[134:135]
	s_addc_u32 s27, s37, 0
	s_add_i32 s56, s46, s15
	global_load_lds_dwordx4 v[220:221], off
	v_lshl_add_u64 v[222:223], s[26:27], 0, v[130:131]
	s_mov_b32 m0, s56
	global_load_lds_dwordx4 v[222:223], off
	v_lshl_add_u64 v[222:223], s[26:27], 0, v[134:135]
	s_add_i32 m0, s56, 0x2000
	s_nop 0
	global_load_lds_dwordx4 v[222:223], off
	s_waitcnt vmcnt(6)
	s_waitcnt lgkmcnt(0)
	s_barrier
	s_setprio 1
	s_waitcnt lgkmcnt(0)
	v_mfma_f32_16x16x32_bf16 v[60:63], v[144:147], v[184:187], v[60:63]
	v_mfma_f32_16x16x32_bf16 v[56:59], v[160:163], v[184:187], v[56:59]
	v_mfma_f32_16x16x32_bf16 v[44:47], v[144:147], v[192:195], v[44:47]
	v_mfma_f32_16x16x32_bf16 v[40:43], v[160:163], v[192:195], v[40:43]
	v_mfma_f32_16x16x32_bf16 v[28:31], v[144:147], v[200:203], v[28:31]
	v_mfma_f32_16x16x32_bf16 v[24:27], v[160:163], v[200:203], v[24:27]
	v_mfma_f32_16x16x32_bf16 v[12:15], v[144:147], v[210:213], v[12:15]
	v_mfma_f32_16x16x32_bf16 v[8:11], v[160:163], v[210:213], v[8:11]
	v_mfma_f32_16x16x32_bf16 v[60:63], v[156:159], v[188:191], v[60:63]
	v_mfma_f32_16x16x32_bf16 v[56:59], v[164:167], v[188:191], v[56:59]
	v_mfma_f32_16x16x32_bf16 v[44:47], v[156:159], v[196:199], v[44:47]
	v_mfma_f32_16x16x32_bf16 v[40:43], v[164:167], v[196:199], v[40:43]
	v_mfma_f32_16x16x32_bf16 v[28:31], v[156:159], v[206:209], v[28:31]
	v_mfma_f32_16x16x32_bf16 v[24:27], v[164:167], v[206:209], v[24:27]
	v_lshl_add_u64 v[222:223], s[38:39], 0, v[128:129]
	s_mov_b32 m0, s33
	s_nop 0
	global_load_lds_dwordx4 v[222:223], off
	v_mfma_f32_16x16x32_bf16 v[12:15], v[156:159], v[214:217], v[12:15]
	v_mfma_f32_16x16x32_bf16 v[8:11], v[164:167], v[214:217], v[8:11]
	s_setprio 0
	s_setprio 1
	v_mfma_f32_16x16x32_bf16 v[52:55], v[168:171], v[184:187], v[52:55]
	v_mfma_f32_16x16x32_bf16 v[48:51], v[176:179], v[184:187], v[48:51]
	v_mfma_f32_16x16x32_bf16 v[36:39], v[168:171], v[192:195], v[36:39]
	v_mfma_f32_16x16x32_bf16 v[32:35], v[176:179], v[192:195], v[32:35]
	v_mfma_f32_16x16x32_bf16 v[20:23], v[168:171], v[200:203], v[20:23]
	v_mfma_f32_16x16x32_bf16 v[16:19], v[176:179], v[200:203], v[16:19]
	v_mfma_f32_16x16x32_bf16 v[4:7], v[168:171], v[210:213], v[4:7]
	v_mfma_f32_16x16x32_bf16 v[0:3], v[176:179], v[210:213], v[0:3]
	v_mfma_f32_16x16x32_bf16 v[52:55], v[172:175], v[188:191], v[52:55]
	v_mfma_f32_16x16x32_bf16 v[48:51], v[180:183], v[188:191], v[48:51]
	v_mfma_f32_16x16x32_bf16 v[36:39], v[172:175], v[196:199], v[36:39]
	v_mfma_f32_16x16x32_bf16 v[32:35], v[180:183], v[196:199], v[32:35]
	v_mfma_f32_16x16x32_bf16 v[20:23], v[172:175], v[206:209], v[20:23]
	v_mfma_f32_16x16x32_bf16 v[16:19], v[180:183], v[206:209], v[16:19]
	v_lshl_add_u64 v[224:225], s[38:39], 0, v[132:133]
	s_mov_b32 m0, s34
	s_nop 0
	global_load_lds_dwordx4 v[224:225], off
	v_mfma_f32_16x16x32_bf16 v[4:7], v[172:175], v[214:217], v[4:7]
	v_mfma_f32_16x16x32_bf16 v[0:3], v[180:183], v[214:217], v[0:3]
	s_setprio 0
	s_barrier
; #define PG8_STAGE(bufoff, gbase, voff) do { _Pragma("unroll") for (int _i = 0; _i < 2; ++_i) \
;         __builtin_amdgcn_global_load_lds((const unsigned*)((const char*)(gbase) + (voff)[_i]), (PG8_LAS unsigned*)(lds + (bufoff) + ldsw + _i * 8192), 16, 0, 0); } while (0)
; #define PG8_LDA(dst, b, h) do { _Pragma("unroll") for (int m = 0; m < 4; ++m) _Pragma("unroll") for (int k = 0; k < 2; ++k) dst[m][k] = *(const PG8_LAS bf16x8*)(lds + PG8_SA(b, h) + aoff + m * 2048 + k * 1024); } while (0)
; #define PG8_LDB(dst, b, h) do { _Pragma("unroll") for (int n = 0; n < 2; ++n) _Pragma("unroll") for (int k = 0; k < 2; ++k) dst[n][k] = *(const PG8_LAS bf16x8*)(lds + PG8_SB(b, h) + boff + n * 2048 + k * 1024); } while (0)
; #define PG8_MMA(ai, bj, At, Bt) do { __builtin_amdgcn_s_setprio(1); _Pragma("unroll") for (int m = 0; m < 4; ++m) _Pragma("unroll") for (int n = 0; n < 2; ++n) _Pragma("unroll") for (int k = 0; k < 2; ++k) \
;         acc[ai][bj][m][n] = __builtin_amdgcn_mfma_f32_16x16x32_bf16(Bt[n][k], At[m][k], acc[ai][bj][m][n], 0, 0, 0); __builtin_amdgcn_s_setprio(0); } while (0)
; #define PG8_WAIT_V(n) asm volatile("s_waitcnt vmcnt(" #n ")" ::: "memory")
; template <class Epi, class Sched, bool ALIGN_EPI = false, bool SP2 = false>
; __device__ __forceinline__ void gemm_phase(PG8_LAS unsigned char* lds, const Gemm g, const Sched& S, const Epi& E) {
;     ...
;             PG8_LDB(B0, 0, 0); PG8_LDB(B1, 0, 1); PG8_SCHED; PG8_LDA(At, 0, 0); PG8_STAGE(PG8_SA(1, 1), a1 + hstep, voffA);
;             PG8_WAIT_V(8); PG8_WAIT_L(0); PG8_BAR; PG8_MMA(0, 0, At, B0); PG8_MMA(0, 1, At, B1); PG8_BAR; PG8_SCHED;
;             PG8_LDA(At, 0, 1); PG8_STAGE(PG8_SB(0, 0), b2, voffB); PG8_STAGE(PG8_SB(0, 1), b2 + hstep, voffB); PG8_STAGE(PG8_SA(0, 0), a2, voffA);
;             PG8_WAIT_V(8); PG8_WAIT_L(0); PG8_BAR; PG8_MMA(1, 0, At, B0); PG8_MMA(1, 1, At, B1); PG8_BAR; PG8_SCHED;
;             PG8_LDB(B0, 1, 0); PG8_LDB(B1, 1, 1); PG8_SCHED; PG8_LDA(At, 1, 0); PG8_STAGE(PG8_SA(0, 1), a2 + hstep, voffA);
;             PG8_WAIT_V(8); PG8_WAIT_L(0); PG8_BAR; PG8_MMA(0, 0, At, B0); PG8_MMA(0, 1, At, B1); PG8_BAR; PG8_SCHED;
;             PG8_LDA(At, 1, 1); PG8_STAGE(PG8_SB(1, 0), b3, voffB); PG8_STAGE(PG8_SB(1, 1), b3 + hstep, voffB); PG8_STAGE(PG8_SA(1, 0), a3, voffA);
;             PG8_WAIT_V(8); PG8_WAIT_L(0); PG8_BAR; PG8_MMA(1, 0, At, B0); PG8_MMA(1, 1, At, B1); PG8_BAR; PG8_SCHED;
	s_add_i32 s56, 0, 0x18000
	v_add_u32_e32 v155, s56, v149
	s_add_i32 s57, 0, 0x1c000
	ds_read_b128 v[144:147], v155
	ds_read_b128 v[156:159], v155 offset:1024
	ds_read_b128 v[160:163], v155 offset:2048
	ds_read_b128 v[164:167], v155 offset:3072
	v_add_u32_e32 v155, s57, v149
	ds_read_b128 v[168:171], v155
	ds_read_b128 v[172:175], v155 offset:1024
	ds_read_b128 v[176:179], v155 offset:2048
	ds_read_b128 v[180:183], v155 offset:3072
	s_add_u32 s26, s38, 0xb0000
	s_addc_u32 s27, s39, 0
	s_mov_b32 m0, s40
	v_lshl_add_u64 v[226:227], s[26:27], 0, v[128:129]
	ds_read_b128 v[184:187], v153 offset:32768
	ds_read_b128 v[188:191], v153 offset:33792
	ds_read_b128 v[192:195], v153 offset:34816
	ds_read_b128 v[196:199], v153 offset:35840
	ds_read_b128 v[200:203], v153 offset:36864
	ds_read_b128 v[206:209], v153 offset:37888
	ds_read_b128 v[210:213], v153 offset:38912
	ds_read_b128 v[214:217], v153 offset:39936
	global_load_lds_dwordx4 v[226:227], off
	v_lshl_add_u64 v[226:227], s[26:27], 0, v[132:133]
	s_mov_b32 m0, s41
	s_nop 0
	global_load_lds_dwordx4 v[226:227], off
	s_waitcnt vmcnt(8)
	s_waitcnt lgkmcnt(0)
	s_barrier
	s_setprio 1
	s_waitcnt lgkmcnt(0)
	v_mfma_f32_16x16x32_bf16 v[124:127], v[144:147], v[184:187], v[124:127]
	v_mfma_f32_16x16x32_bf16 v[120:123], v[160:163], v[184:187], v[120:123]
	v_mfma_f32_16x16x32_bf16 v[108:111], v[144:147], v[192:195], v[108:111]
	v_mfma_f32_16x16x32_bf16 v[104:107], v[160:163], v[192:195], v[104:107]
	v_mfma_f32_16x16x32_bf16 v[92:95], v[144:147], v[200:203], v[92:95]
	v_mfma_f32_16x16x32_bf16 v[88:91], v[160:163], v[200:203], v[88:91]
	v_mfma_f32_16x16x32_bf16 v[76:79], v[144:147], v[210:213], v[76:79]
	v_mfma_f32_16x16x32_bf16 v[72:75], v[160:163], v[210:213], v[72:75]
	v_mfma_f32_16x16x32_bf16 v[124:127], v[156:159], v[188:191], v[124:127]
	v_mfma_f32_16x16x32_bf16 v[120:123], v[164:167], v[188:191], v[120:123]
	v_mfma_f32_16x16x32_bf16 v[108:111], v[156:159], v[196:199], v[108:111]
	v_mfma_f32_16x16x32_bf16 v[104:107], v[164:167], v[196:199], v[104:107]
	v_mfma_f32_16x16x32_bf16 v[92:95], v[156:159], v[206:209], v[92:95]
	v_mfma_f32_16x16x32_bf16 v[88:91], v[164:167], v[206:209], v[88:91]
	v_mfma_f32_16x16x32_bf16 v[76:79], v[156:159], v[214:217], v[76:79]
	v_mfma_f32_16x16x32_bf16 v[72:75], v[164:167], v[214:217], v[72:75]
	s_setprio 0
	s_setprio 1
	v_mfma_f32_16x16x32_bf16 v[116:119], v[168:171], v[184:187], v[116:119]
	v_mfma_f32_16x16x32_bf16 v[112:115], v[176:179], v[184:187], v[112:115]
	v_mfma_f32_16x16x32_bf16 v[100:103], v[168:171], v[192:195], v[100:103]
	v_mfma_f32_16x16x32_bf16 v[96:99], v[176:179], v[192:195], v[96:99]
	v_mfma_f32_16x16x32_bf16 v[84:87], v[168:171], v[200:203], v[84:87]
	v_mfma_f32_16x16x32_bf16 v[80:83], v[176:179], v[200:203], v[80:83]
	v_mfma_f32_16x16x32_bf16 v[68:71], v[168:171], v[210:213], v[68:71]
	v_mfma_f32_16x16x32_bf16 v[64:67], v[176:179], v[210:213], v[64:67]
	v_mfma_f32_16x16x32_bf16 v[116:119], v[172:175], v[188:191], v[116:119]
	v_mfma_f32_16x16x32_bf16 v[112:115], v[180:183], v[188:191], v[112:115]
	v_mfma_f32_16x16x32_bf16 v[100:103], v[172:175], v[196:199], v[100:103]
	v_mfma_f32_16x16x32_bf16 v[96:99], v[180:183], v[196:199], v[96:99]
	v_mfma_f32_16x16x32_bf16 v[84:87], v[172:175], v[206:209], v[84:87]
	v_mfma_f32_16x16x32_bf16 v[80:83], v[180:183], v[206:209], v[80:83]
	v_mfma_f32_16x16x32_bf16 v[68:71], v[172:175], v[214:217], v[68:71]
	v_mfma_f32_16x16x32_bf16 v[64:67], v[180:183], v[214:217], v[64:67]
	s_setprio 0
	s_barrier
	s_add_i32 s26, s56, s15
	v_lshl_add_u64 v[218:219], v[218:219], 0, s[12:13]
	s_mov_b32 m0, s26
	ds_read_b128 v[184:187], v153 offset:49152
	ds_read_b128 v[188:191], v153 offset:50176
	ds_read_b128 v[192:195], v153 offset:51200
	ds_read_b128 v[196:199], v153 offset:52224
	ds_read_b128 v[200:203], v153 offset:53248
	ds_read_b128 v[206:209], v153 offset:54272
	ds_read_b128 v[210:213], v153 offset:55296
	ds_read_b128 v[214:217], v153 offset:56320
	global_load_lds_dwordx4 v[218:219], off
	s_add_i32 m0, s26, 0x2000
	s_add_u32 s26, s36, 0xb0080
	v_lshl_add_u64 v[218:219], v[220:221], 0, s[12:13]
	s_addc_u32 s27, s37, 0
	s_add_i32 s36, s57, s15
	global_load_lds_dwordx4 v[218:219], off
	v_lshl_add_u64 v[218:219], s[26:27], 0, v[130:131]
	s_mov_b32 m0, s36
	s_nop 0
	global_load_lds_dwordx4 v[218:219], off
	v_lshl_add_u64 v[218:219], s[26:27], 0, v[134:135]
	s_add_i32 m0, s36, 0x2000
	s_nop 0
	global_load_lds_dwordx4 v[218:219], off
	s_waitcnt vmcnt(6)
	s_waitcnt lgkmcnt(0)
	s_barrier
; __device__ __forceinline__ void fx_add(float* p, size_t idx, float s) { atomicAdd((unsigned long long*)p + idx, (unsigned long long)(long long)(s * 4294967296.0f)); }
; __device__ __forceinline__ unsigned cvtpk(float lo, float hi) { f32x2v_ v = {lo, hi}; bf16x2v_ b = __builtin_convertvector(v, bf16x2v_); return __builtin_bit_cast(unsigned, b); }
; #define PG8_BAR __builtin_amdgcn_s_barrier()
;     __device__ __forceinline__ void operator()(const f32x4 (&acc)[2][2][4][2], const Unit& u, int wr, int wc, int fr, int fq) const {
;     ...
;             for (int m = 0; m < 4; ++m) { const int row = row0 + ai * HALF + m * 16; const size_t off = (size_t)row * 1024 + col0; float s = 0.f;
; #pragma unroll
;                 for (int bj = 0; bj < 2; ++bj) { f32x4 a0, a1;
;                     if (xin32) { const float* p = xin32 + off + bj * HALF; a0 = *(const f32x4*)p; a1 = *(const f32x4*)(p + 4); }
;                     else { const u32x4 w = *(const u32x4*)(xb + off + bj * HALF);
;                         a0 = (f32x4){__uint_as_float(w.x << 16), __uint_as_float(w.x & 0xffff0000u), __uint_as_float(w.y << 16), __uint_as_float(w.y & 0xffff0000u)};
;                         a1 = (f32x4){__uint_as_float(w.z << 16), __uint_as_float(w.z & 0xffff0000u), __uint_as_float(w.w << 16), __uint_as_float(w.w & 0xffff0000u)}; }
;                     const f32x4 v0 = a0 + acc[ai][bj][m][0] * alpha, v1 = a1 + acc[ai][bj][m][1] * alpha;
;                     u32x4 w; w.x = cvtpk(v0[0], v0[1]); w.y = cvtpk(v0[2], v0[3]); w.z = cvtpk(v1[0], v1[1]); w.w = cvtpk(v1[2], v1[3]);
;                     *(u32x4*)(xb + off + bj * HALF) = w;
;                     s += (v0[0] * v0[0] + v0[1] * v0[1]) + (v0[2] * v0[2] + v0[3] * v0[3]) + (v1[0] * v1[0] + v1[1] * v1[1]) + (v1[2] * v1[2] + v1[3] * v1[3]); }
;                 s += __shfl_xor(s, 16); s += __shfl_xor(s, 32);
;                 if (fq == 0) fx_add(ssout, row, s); }
; template <class Epi, class Sched, bool ALIGN_EPI = false, bool SP2 = false>
; __device__ __forceinline__ void gemm_phase(PG8_LAS unsigned char* lds, const Gemm g, const Sched& S, const Epi& E) {
;     ...
;         if constexpr (ALIGN_EPI) { if (wr == 0) PG8_BAR; }
	s_setprio 1
	s_waitcnt lgkmcnt(0)
	v_mfma_f32_16x16x32_bf16 v[60:63], v[144:147], v[184:187], v[60:63]
	v_mfma_f32_16x16x32_bf16 v[56:59], v[160:163], v[184:187], v[56:59]
	v_mfma_f32_16x16x32_bf16 v[44:47], v[144:147], v[192:195], v[44:47]
	v_mfma_f32_16x16x32_bf16 v[40:43], v[160:163], v[192:195], v[40:43]
	v_mfma_f32_16x16x32_bf16 v[28:31], v[144:147], v[200:203], v[28:31]
	v_mfma_f32_16x16x32_bf16 v[24:27], v[160:163], v[200:203], v[24:27]
	v_mfma_f32_16x16x32_bf16 v[12:15], v[144:147], v[210:213], v[12:15]
	v_mfma_f32_16x16x32_bf16 v[8:11], v[160:163], v[210:213], v[8:11]
	v_mfma_f32_16x16x32_bf16 v[60:63], v[156:159], v[188:191], v[60:63]
	v_mfma_f32_16x16x32_bf16 v[56:59], v[164:167], v[188:191], v[56:59]
	v_mfma_f32_16x16x32_bf16 v[44:47], v[156:159], v[196:199], v[44:47]
	v_mfma_f32_16x16x32_bf16 v[40:43], v[164:167], v[196:199], v[40:43]
	v_mfma_f32_16x16x32_bf16 v[28:31], v[156:159], v[206:209], v[28:31]
	v_mfma_f32_16x16x32_bf16 v[24:27], v[164:167], v[206:209], v[24:27]
	v_lshl_add_u64 v[218:219], v[222:223], 0, s[12:13]
	s_mov_b32 m0, s43
	s_nop 0
	global_load_lds_dwordx4 v[218:219], off
	v_mfma_f32_16x16x32_bf16 v[12:15], v[156:159], v[214:217], v[12:15]
	v_mfma_f32_16x16x32_bf16 v[8:11], v[164:167], v[214:217], v[8:11]
	s_setprio 0
	s_setprio 1
	v_mfma_f32_16x16x32_bf16 v[52:55], v[168:171], v[184:187], v[52:55]
	v_mfma_f32_16x16x32_bf16 v[48:51], v[176:179], v[184:187], v[48:51]
	v_mfma_f32_16x16x32_bf16 v[36:39], v[168:171], v[192:195], v[36:39]
	v_mfma_f32_16x16x32_bf16 v[32:35], v[176:179], v[192:195], v[32:35]
	v_mfma_f32_16x16x32_bf16 v[20:23], v[168:171], v[200:203], v[20:23]
	v_mfma_f32_16x16x32_bf16 v[16:19], v[176:179], v[200:203], v[16:19]
	v_mfma_f32_16x16x32_bf16 v[4:7], v[168:171], v[210:213], v[4:7]
	v_mfma_f32_16x16x32_bf16 v[0:3], v[176:179], v[210:213], v[0:3]
	v_mfma_f32_16x16x32_bf16 v[52:55], v[172:175], v[188:191], v[52:55]
	v_mfma_f32_16x16x32_bf16 v[48:51], v[180:183], v[188:191], v[48:51]
	v_mfma_f32_16x16x32_bf16 v[36:39], v[172:175], v[196:199], v[36:39]
	v_mfma_f32_16x16x32_bf16 v[32:35], v[180:183], v[196:199], v[32:35]
	v_mfma_f32_16x16x32_bf16 v[20:23], v[172:175], v[206:209], v[20:23]
	v_mfma_f32_16x16x32_bf16 v[16:19], v[180:183], v[206:209], v[16:19]
	v_lshl_add_u64 v[218:219], v[224:225], 0, s[12:13]
	s_mov_b32 m0, s44
	s_nop 0
	global_load_lds_dwordx4 v[218:219], off
	v_mfma_f32_16x16x32_bf16 v[4:7], v[172:175], v[214:217], v[4:7]
	v_mfma_f32_16x16x32_bf16 v[0:3], v[180:183], v[214:217], v[0:3]
	s_setprio 0
	s_barrier
	s_add_i32 s55, s55, 2
	s_add_u32 s53, s53, 0x100
	s_addc_u32 s54, s54, 0
	s_cmp_gt_u32 s55, 41
	s_mov_b64 s[26:27], s[28:29]
	s_cbranch_scc0 .LBB0_1978
	s_and_b64 vcc, exec, s[16:17]
	s_cbranch_vccz .LBB0_1981
.LBB0_1981:
	v_lshl_add_u32 v146, s52, 8, v148
	v_ashrrev_i32_e32 v147, 31, v146
	v_lshl_or_b32 v144, s51, 8, v150
	v_lshlrev_b64 v[156:157], 11, v[146:147]
	v_ashrrev_i32_e32 v145, 31, v144
	v_lshl_add_u64 v[156:157], s[22:23], 0, v[156:157]
	v_lshl_add_u64 v[166:167], v[144:145], 1, v[156:157]
	global_load_dwordx4 v[158:161], v[166:167], off
	global_load_dwordx4 v[162:165], v[166:167], off offset:256
	v_and_b32_e32 v156, 64, v154
	v_xor_b32_e32 v155, 16, v154
	v_add_u32_e32 v156, 64, v156
	v_xor_b32_e32 v157, 32, v154
	v_cmp_lt_i32_e32 vcc, v155, v156
	s_waitcnt vmcnt(0)
	v_lshlrev_b32_e32 v168, 16, v158
	v_cndmask_b32_e32 v155, v154, v155, vcc
	v_cmp_lt_i32_e32 vcc, v157, v156
	v_and_b32_e32 v169, 0xffff0000, v158
	v_lshlrev_b32_e32 v158, 16, v159
	v_and_b32_e32 v159, 0xffff0000, v159
	v_lshlrev_b32_e32 v172, 16, v162
	v_and_b32_e32 v173, 0xffff0000, v162
	v_lshlrev_b32_e32 v162, 16, v163
	v_and_b32_e32 v163, 0xffff0000, v163
	v_cndmask_b32_e32 v157, v154, v157, vcc
	v_lshlrev_b32_e32 v170, 16, v160
	v_and_b32_e32 v171, 0xffff0000, v160
	v_lshlrev_b32_e32 v160, 16, v161
	v_and_b32_e32 v161, 0xffff0000, v161
	v_lshlrev_b32_e32 v174, 16, v164
	v_and_b32_e32 v175, 0xffff0000, v164
	v_lshlrev_b32_e32 v164, 16, v165
	v_and_b32_e32 v165, 0xffff0000, v165
	v_pk_fma_f32 v[126:127], v[126:127], 0.5, v[158:159] op_sel_hi:[1,0,1]
	v_pk_fma_f32 v[124:125], v[124:125], 0.5, v[168:169] op_sel_hi:[1,0,1]
	v_pk_fma_f32 v[118:119], v[118:119], 0.5, v[162:163] op_sel_hi:[1,0,1]
	v_pk_fma_f32 v[116:117], v[116:117], 0.5, v[172:173] op_sel_hi:[1,0,1]
	v_lshlrev_b32_e32 v156, 2, v155
	v_lshlrev_b32_e32 v155, 2, v157
	v_pk_fma_f32 v[122:123], v[122:123], 0.5, v[160:161] op_sel_hi:[1,0,1]
	v_pk_fma_f32 v[120:121], v[120:121], 0.5, v[170:171] op_sel_hi:[1,0,1]
	v_pk_fma_f32 v[158:159], v[114:115], 0.5, v[164:165] op_sel_hi:[1,0,1]
	v_pk_fma_f32 v[160:161], v[112:113], 0.5, v[174:175] op_sel_hi:[1,0,1]
	v_mul_f32_e32 v114, v125, v125
	v_mul_f32_e32 v115, v127, v127
	v_mul_f32_e32 v157, v117, v117
	v_mul_f32_e32 v162, v119, v119
	v_cvt_pk_bf16_f32 v112, v124, v125
	v_mul_f32_e32 v125, v121, v121
	v_mul_f32_e32 v163, v161, v161
	v_fmac_f32_e32 v114, v124, v124
	v_fmac_f32_e32 v115, v126, v126
	v_fmac_f32_e32 v157, v116, v116
	v_fmac_f32_e32 v162, v118, v118
	v_cvt_pk_bf16_f32 v113, v126, v127
	v_mul_f32_e32 v127, v123, v123
	v_mul_f32_e32 v164, v159, v159
	v_fmac_f32_e32 v125, v120, v120
	v_fmac_f32_e32 v163, v160, v160
	v_add_f32_e32 v114, v114, v115
	v_add_f32_e32 v115, v157, v162
	v_fmac_f32_e32 v127, v122, v122
	v_fmac_f32_e32 v164, v158, v158
	v_add_f32_e32 v114, v125, v114
	v_add_f32_e32 v115, v163, v115
	v_add_f32_e32 v114, v127, v114
	v_add_f32_e32 v115, v164, v115
	v_add_f32_e32 v124, v114, v115
	ds_bpermute_b32 v125, v156, v124
	v_cvt_pk_bf16_f32 v114, v120, v121
	v_cvt_pk_bf16_f32 v115, v122, v123
	global_store_dwordx4 v[166:167], v[112:115], off
	s_waitcnt lgkmcnt(0)
	s_nop 0
	v_add_f32_e32 v112, v124, v125
	ds_bpermute_b32 v113, v155, v112
	v_cvt_pk_bf16_f32 v114, v116, v117
	v_cvt_pk_bf16_f32 v115, v118, v119
	v_cvt_pk_bf16_f32 v116, v160, v161
	v_cvt_pk_bf16_f32 v117, v158, v159
	global_store_dwordx4 v[166:167], v[114:117], off offset:256
	s_and_saveexec_b64 s[26:27], s[6:7]
	s_cbranch_execz .LBB0_1983
	s_waitcnt lgkmcnt(0)
	v_add_f32_e32 v112, v112, v113
	v_mul_f32_e32 v112, 0x4f800000, v112
	v_trunc_f32_e32 v112, v112
	v_mul_f32_e64 v113, |v112|, s47
	v_floor_f32_e32 v113, v113
	v_fma_f32 v114, v113, s48, |v112|
	v_cvt_u32_f32_e32 v114, v114
	v_cvt_u32_f32_e32 v113, v113
	v_ashrrev_i32_e32 v115, 31, v112
	v_xor_b32_e32 v112, v114, v115
	v_xor_b32_e32 v113, v113, v115
	v_sub_co_u32_e32 v112, vcc, v112, v115
	s_nop 1
	v_subb_co_u32_e32 v113, vcc, v113, v115, vcc
	v_lshl_add_u64 v[114:115], v[146:147], 3, s[10:11]
	global_atomic_add_x2 v[114:115], v[112:113], off

; __device__ __forceinline__ void fx_add(float* p, size_t idx, float s) { atomicAdd((unsigned long long*)p + idx, (unsigned long long)(long long)(s * 4294967296.0f)); }
; #define PG8_BAR __builtin_amdgcn_s_barrier()
;     __device__ __forceinline__ void operator()(const f32x4 (&acc)[2][2][4][2], const Unit& u, int wr, int wc, int fr, int fq) const {
;     ...
;                 if (fq == 0) fx_add(ssout, row, s); }
; template <class Epi, class Sched, bool ALIGN_EPI = false, bool SP2 = false>
; __device__ __forceinline__ void gemm_phase(PG8_LAS unsigned char* lds, const Gemm g, const Sched& S, const Epi& E) {
;     ...
;         if constexpr (ALIGN_EPI) { if (wr == 0) PG8_BAR; }
;         if constexpr (!Epi::AFTER_DRAIN) { E(acc, cur, wr, wc, fr, fq); S.done(cur); }
;         if (!has_next) break;
.LBB0_1997:
	s_or_b64 exec, exec, s[26:27]
	s_and_b64 vcc, exec, s[4:5]
	s_mov_b64 s[4:5], -1
	s_cmp_eq_u64 s[16:17], 0
	s_cbranch_scc1 .Lxpost_13
	s_barrier
